# GEMM tile epilogues of the two wave-halves run concurrently: one extra barrier per half per tile (wr0 after the K-loop, wr1 at the tile latch)
# speedup vs baseline: 1.0101x; 1.0101x over previous
; #define PG8_STAGE(bufoff, gbase, voff) do { _Pragma("unroll") for (int _i = 0; _i < 2; ++_i) \
;         __builtin_amdgcn_global_load_lds((const unsigned*)((const char*)(gbase) + (voff)[_i]), (LAS unsigned*)(lds + (bufoff) + ldsw + _i * 8192), 16, 0, 0); } while (0)
; #define PG8_LDA(dst, b, h) do { _Pragma("unroll") for (int m = 0; m < 4; ++m) _Pragma("unroll") for (int k = 0; k < 2; ++k) dst[m][k] = *(const LAS h16x8*)(lds + PG8_SA(b, h) + aoff + m * 2048 + k * 1024); } while (0)
; #define PG8_LDB(dst, b, h) do { _Pragma("unroll") for (int n = 0; n < 2; ++n) _Pragma("unroll") for (int k = 0; k < 2; ++k) dst[n][k] = *(const LAS h16x8*)(lds + PG8_SB(b, h) + boff + n * 2048 + k * 1024); } while (0)
; #define PG8_MMA(ai, bj, At, Bt_) do { __builtin_amdgcn_s_setprio(1); _Pragma("unroll") for (int m = 0; m < 4; ++m) _Pragma("unroll") for (int n = 0; n < 2; ++n) _Pragma("unroll") for (int k = 0; k < 2; ++k) \
;         acc[ai][bj][m][n] = __builtin_amdgcn_mfma_f32_16x16x32_f16(Bt_[n][k], At[m][k], acc[ai][bj][m][n], 0, 0, 0); __builtin_amdgcn_s_setprio(0); } while (0)
; #define PG8_WAIT_V(n) asm volatile("s_waitcnt vmcnt(" #n ")" ::: "memory")
; template <class Epi, class AMap>
; __device__ __forceinline__ void gemm_phase(LAS unsigned char* lds, const AMap am, const int lda, const h16* Bt, const int ldb, const int M, const int N, const int K, const Epi& E) {
;     ...
;         for (int t = 0; t < nt; t += 2) {
;             const bool last = (t == nt - 2);
;             const char* a1 = cA + (size_t)(t + 1) * kstep;
;             const char* a2 = last ? nA : cA + (size_t)(t + 2) * kstep; const char* b2 = last ? nB : cB + (size_t)(t + 2) * kstep;
;             const char* a3 = a2 + kstep; const char* b3 = b2 + kstep;
;             PG8_LDB(B0, 0, 0); PG8_SCHED; PG8_LDA(At, 0, 0); PG8_STAGE(PG8_SA(1, 1), a1 + hstepA, voffA);
;             PG8_WAIT_L(8); PG8_BAR; PG8_WAIT_L(0); PG8_MMA(0, 0, At, B0); PG8_BAR; PG8_SCHED;
;             PG8_LDB(B1, 0, 1); PG8_STAGE(PG8_SB(0, 0), b2, voffB);
;             PG8_BAR; PG8_WAIT_L(0); PG8_MMA(0, 1, At, B1); PG8_BAR;
;             PG8_LDA(At, 0, 1); PG8_STAGE(PG8_SA(0, 0), a2, voffA);
;             PG8_BAR; PG8_WAIT_L(0); PG8_MMA(1, 0, At, B0); PG8_BAR; PG8_SCHED;
;             PG8_STAGE(PG8_SB(0, 1), b2 + hstepB, voffB);
;             PG8_WAIT_V(6); PG8_BAR; PG8_MMA(1, 1, At, B1); PG8_BAR;
.LBB0_61:
	s_add_u32 s26, s22, 0x100
	s_addc_u32 s27, s23, 0
	s_add_i32 s51, 0, 0x10000
	v_add_u32_e32 v144, s51, v147
	ds_read_b128 v[140:143], v144
	ds_read_b128 v[150:153], v144 offset:1024
	ds_read_b128 v[154:157], v144 offset:2048
	ds_read_b128 v[158:161], v144 offset:3072
	s_cmpk_eq_i32 s29, 0x52
	s_cselect_b32 s45, s1, s27
	s_cselect_b32 s44, s0, s26
	s_cselect_b32 s43, s41, s21
	s_cselect_b32 s42, s40, s20
	v_lshl_add_u64 v[144:145], s[22:23], 0, v[136:137]
	s_add_i32 m0, s63, 0xc000
	ds_read_b128 v[162:165], v149
	ds_read_b128 v[166:169], v149 offset:1024
	ds_read_b128 v[170:173], v149 offset:2048
	ds_read_b128 v[174:177], v149 offset:3072
	ds_read_b128 v[178:181], v149 offset:4096
	ds_read_b128 v[182:185], v149 offset:5120
	ds_read_b128 v[186:189], v149 offset:6144
	ds_read_b128 v[190:193], v149 offset:7168
	global_load_lds_dwordx4 v[144:145], off
	v_lshl_add_u64 v[144:145], s[22:23], 0, v[138:139]
	s_add_i32 m0, s63, 0xe000
	s_nop 0
	global_load_lds_dwordx4 v[144:145], off
	s_waitcnt lgkmcnt(11)
	s_add_i32 s60, 0, 0x14000
	v_add_u32_e32 v144, s60, v147
	s_add_i32 s22, s51, s48
	ds_read_b128 v[194:197], v144
	ds_read_b128 v[198:201], v144 offset:1024
	ds_read_b128 v[202:205], v144 offset:2048
	ds_read_b128 v[220:223], v144 offset:3072
	s_waitcnt vmcnt(8) lgkmcnt(0)
	s_barrier
	v_mfma_f32_16x16x32_f16 v[126:129], v[140:143], v[162:165], v[126:129]
	v_mfma_f32_16x16x32_f16 v[122:125], v[154:157], v[162:165], v[122:125]
	v_mfma_f32_16x16x32_f16 v[110:113], v[140:143], v[170:173], v[110:113]
	v_mfma_f32_16x16x32_f16 v[106:109], v[154:157], v[170:173], v[106:109]
	v_mfma_f32_16x16x32_f16 v[94:97], v[140:143], v[178:181], v[94:97]
	v_mfma_f32_16x16x32_f16 v[90:93], v[154:157], v[178:181], v[90:93]
	v_mfma_f32_16x16x32_f16 v[78:81], v[140:143], v[186:189], v[78:81]
	v_mfma_f32_16x16x32_f16 v[74:77], v[154:157], v[186:189], v[74:77]
	v_mfma_f32_16x16x32_f16 v[126:129], v[150:153], v[166:169], v[126:129]
	v_mfma_f32_16x16x32_f16 v[122:125], v[158:161], v[166:169], v[122:125]
	v_mfma_f32_16x16x32_f16 v[110:113], v[150:153], v[174:177], v[110:113]
	v_mfma_f32_16x16x32_f16 v[106:109], v[158:161], v[174:177], v[106:109]
	v_mfma_f32_16x16x32_f16 v[94:97], v[150:153], v[182:185], v[94:97]
	v_mfma_f32_16x16x32_f16 v[90:93], v[158:161], v[182:185], v[90:93]
	v_mfma_f32_16x16x32_f16 v[78:81], v[150:153], v[190:193], v[78:81]
	v_mfma_f32_16x16x32_f16 v[74:77], v[158:161], v[190:193], v[74:77]
	v_mfma_f32_16x16x32_f16 v[118:121], v[194:197], v[162:165], v[118:121]
	v_mfma_f32_16x16x32_f16 v[114:117], v[202:205], v[162:165], v[114:117]
	v_mfma_f32_16x16x32_f16 v[102:105], v[194:197], v[170:173], v[102:105]
	v_mfma_f32_16x16x32_f16 v[98:101], v[202:205], v[170:173], v[98:101]
	v_mfma_f32_16x16x32_f16 v[86:89], v[194:197], v[178:181], v[86:89]
	v_mfma_f32_16x16x32_f16 v[82:85], v[202:205], v[178:181], v[82:85]
	v_mfma_f32_16x16x32_f16 v[70:73], v[194:197], v[186:189], v[70:73]
	v_mfma_f32_16x16x32_f16 v[66:69], v[202:205], v[186:189], v[66:69]
	v_mfma_f32_16x16x32_f16 v[118:121], v[198:201], v[166:169], v[118:121]
	v_mfma_f32_16x16x32_f16 v[114:117], v[220:223], v[166:169], v[114:117]
	v_mfma_f32_16x16x32_f16 v[102:105], v[198:201], v[174:177], v[102:105]
	v_mfma_f32_16x16x32_f16 v[98:101], v[220:223], v[174:177], v[98:101]
	v_mfma_f32_16x16x32_f16 v[86:89], v[198:201], v[182:185], v[86:89]
	v_mfma_f32_16x16x32_f16 v[82:85], v[220:223], v[182:185], v[82:85]
	v_mfma_f32_16x16x32_f16 v[70:73], v[198:201], v[190:193], v[70:73]
	v_mfma_f32_16x16x32_f16 v[66:69], v[220:223], v[190:193], v[66:69]
	s_barrier
	v_lshl_add_u64 v[144:145], s[42:43], 0, v[0:1]
	s_mov_b32 m0, s22
	v_lshl_add_u64 v[206:207], s[42:43], 0, v[134:135]
	global_load_lds_dwordx4 v[144:145], off
	s_add_i32 m0, s22, 0x2000
	s_nop 0
	global_load_lds_dwordx4 v[206:207], off
	s_mov_b32 m0, s63
	v_lshl_add_u64 v[212:213], s[44:45], 0, v[130:131]
	ds_read_b128 v[162:165], v149 offset:16384
	ds_read_b128 v[166:169], v149 offset:17408
	ds_read_b128 v[170:173], v149 offset:18432
	ds_read_b128 v[174:177], v149 offset:19456
	ds_read_b128 v[178:181], v149 offset:20480
	ds_read_b128 v[182:185], v149 offset:21504
	ds_read_b128 v[186:189], v149 offset:22528
	ds_read_b128 v[190:193], v149 offset:23552
	global_load_lds_dwordx4 v[212:213], off
	v_lshl_add_u64 v[214:215], s[44:45], 0, v[132:133]
	s_mov_b32 m0, s64
	s_nop 0
	global_load_lds_dwordx4 v[214:215], off
	s_add_u32 s22, s42, 0x158000
	s_addc_u32 s23, s43, 0
	s_add_i32 s51, s60, s48
	v_lshl_add_u64 v[232:233], s[22:23], 0, v[0:1]
	s_mov_b32 m0, s51
	s_nop 0
	global_load_lds_dwordx4 v[232:233], off
	v_lshl_add_u64 v[232:233], s[22:23], 0, v[134:135]
	s_add_i32 m0, s51, 0x2000
	s_nop 0
	global_load_lds_dwordx4 v[232:233], off
	s_waitcnt vmcnt(8) lgkmcnt(0)
	s_barrier
; #define PG8_STAGE(bufoff, gbase, voff) do { _Pragma("unroll") for (int _i = 0; _i < 2; ++_i) \
;         __builtin_amdgcn_global_load_lds((const unsigned*)((const char*)(gbase) + (voff)[_i]), (LAS unsigned*)(lds + (bufoff) + ldsw + _i * 8192), 16, 0, 0); } while (0)
; #define PG8_LDA(dst, b, h) do { _Pragma("unroll") for (int m = 0; m < 4; ++m) _Pragma("unroll") for (int k = 0; k < 2; ++k) dst[m][k] = *(const LAS h16x8*)(lds + PG8_SA(b, h) + aoff + m * 2048 + k * 1024); } while (0)
; #define PG8_LDB(dst, b, h) do { _Pragma("unroll") for (int n = 0; n < 2; ++n) _Pragma("unroll") for (int k = 0; k < 2; ++k) dst[n][k] = *(const LAS h16x8*)(lds + PG8_SB(b, h) + boff + n * 2048 + k * 1024); } while (0)
; #define PG8_MMA(ai, bj, At, Bt_) do { __builtin_amdgcn_s_setprio(1); _Pragma("unroll") for (int m = 0; m < 4; ++m) _Pragma("unroll") for (int n = 0; n < 2; ++n) _Pragma("unroll") for (int k = 0; k < 2; ++k) \
;         acc[ai][bj][m][n] = __builtin_amdgcn_mfma_f32_16x16x32_f16(Bt_[n][k], At[m][k], acc[ai][bj][m][n], 0, 0, 0); __builtin_amdgcn_s_setprio(0); } while (0)
; #define PG8_WAIT_V(n) asm volatile("s_waitcnt vmcnt(" #n ")" ::: "memory")
; #define PG8_WAIT_L(n) asm volatile("s_waitcnt lgkmcnt(" #n ")" ::: "memory")
; #define PG8_BAR __builtin_amdgcn_s_barrier()
; #define PG8_SCHED __builtin_amdgcn_sched_barrier(0)
; template <class Epi, class AMap>
; __device__ __forceinline__ void gemm_phase(LAS unsigned char* lds, const AMap am, const int lda, const h16* Bt, const int ldb, const int M, const int N, const int K, const Epi& E) {
;     ...
;             PG8_BAR; PG8_WAIT_L(0); PG8_MMA(0, 1, At, B1); PG8_BAR;
;             PG8_LDA(At, 0, 1); PG8_STAGE(PG8_SA(0, 0), a2, voffA);
;             PG8_BAR; PG8_WAIT_L(0); PG8_MMA(1, 0, At, B0); PG8_BAR; PG8_SCHED;
;             PG8_STAGE(PG8_SB(0, 1), b2 + hstepB, voffB);
;             PG8_WAIT_V(6); PG8_BAR; PG8_MMA(1, 1, At, B1); PG8_BAR;
;             PG8_LDB(B0, 1, 0); PG8_SCHED; PG8_LDA(At, 1, 0); PG8_STAGE(PG8_SA(0, 1), a2 + hstepA, voffA);
;             PG8_WAIT_L(8); PG8_BAR; PG8_WAIT_L(0); PG8_MMA(0, 0, At, B0); PG8_BAR; PG8_SCHED;
;             PG8_LDB(B1, 1, 1); PG8_STAGE(PG8_SB(1, 0), b3, voffB);
;             PG8_BAR; PG8_WAIT_L(0); PG8_MMA(0, 1, At, B1); PG8_BAR;
	v_mfma_f32_16x16x32_f16 v[62:65], v[140:143], v[162:165], v[62:65]
	v_mfma_f32_16x16x32_f16 v[58:61], v[154:157], v[162:165], v[58:61]
	v_mfma_f32_16x16x32_f16 v[46:49], v[140:143], v[170:173], v[46:49]
	v_mfma_f32_16x16x32_f16 v[42:45], v[154:157], v[170:173], v[42:45]
	v_mfma_f32_16x16x32_f16 v[30:33], v[140:143], v[178:181], v[30:33]
	v_mfma_f32_16x16x32_f16 v[26:29], v[154:157], v[178:181], v[26:29]
	v_mfma_f32_16x16x32_f16 v[14:17], v[140:143], v[186:189], v[14:17]
	v_mfma_f32_16x16x32_f16 v[10:13], v[154:157], v[186:189], v[10:13]
	v_mfma_f32_16x16x32_f16 v[62:65], v[150:153], v[166:169], v[62:65]
	v_mfma_f32_16x16x32_f16 v[58:61], v[158:161], v[166:169], v[58:61]
	v_mfma_f32_16x16x32_f16 v[46:49], v[150:153], v[174:177], v[46:49]
	v_mfma_f32_16x16x32_f16 v[42:45], v[158:161], v[174:177], v[42:45]
	v_mfma_f32_16x16x32_f16 v[30:33], v[150:153], v[182:185], v[30:33]
	v_mfma_f32_16x16x32_f16 v[26:29], v[158:161], v[182:185], v[26:29]
	v_mfma_f32_16x16x32_f16 v[14:17], v[150:153], v[190:193], v[14:17]
	v_mfma_f32_16x16x32_f16 v[10:13], v[158:161], v[190:193], v[10:13]
	v_mfma_f32_16x16x32_f16 v[54:57], v[194:197], v[162:165], v[54:57]
	v_mfma_f32_16x16x32_f16 v[50:53], v[202:205], v[162:165], v[50:53]
	v_mfma_f32_16x16x32_f16 v[38:41], v[194:197], v[170:173], v[38:41]
	v_mfma_f32_16x16x32_f16 v[34:37], v[202:205], v[170:173], v[34:37]
	v_mfma_f32_16x16x32_f16 v[22:25], v[194:197], v[178:181], v[22:25]
	v_mfma_f32_16x16x32_f16 v[18:21], v[202:205], v[178:181], v[18:21]
	v_mfma_f32_16x16x32_f16 v[6:9], v[194:197], v[186:189], v[6:9]
	v_mfma_f32_16x16x32_f16 v[2:5], v[202:205], v[186:189], v[2:5]
	v_mfma_f32_16x16x32_f16 v[54:57], v[198:201], v[166:169], v[54:57]
	v_mfma_f32_16x16x32_f16 v[50:53], v[220:223], v[166:169], v[50:53]
	v_mfma_f32_16x16x32_f16 v[38:41], v[198:201], v[174:177], v[38:41]
	v_mfma_f32_16x16x32_f16 v[34:37], v[220:223], v[174:177], v[34:37]
	v_mfma_f32_16x16x32_f16 v[22:25], v[198:201], v[182:185], v[22:25]
	v_mfma_f32_16x16x32_f16 v[18:21], v[220:223], v[182:185], v[18:21]
	v_mfma_f32_16x16x32_f16 v[6:9], v[198:201], v[190:193], v[6:9]
	v_mfma_f32_16x16x32_f16 v[2:5], v[220:223], v[190:193], v[2:5]
	s_barrier
	s_add_i32 s51, 0, 0x18000
	v_add_u32_e32 v234, s51, v147
	ds_read_b128 v[140:143], v234
	ds_read_b128 v[150:153], v234 offset:1024
	ds_read_b128 v[154:157], v234 offset:2048
	ds_read_b128 v[158:161], v234 offset:3072
	s_add_u32 s22, s44, 0x158000
	s_addc_u32 s23, s45, 0
	s_mov_b32 m0, s65
	v_lshl_add_u64 v[232:233], s[22:23], 0, v[130:131]
	ds_read_b128 v[162:165], v149 offset:32768
	ds_read_b128 v[166:169], v149 offset:33792
	ds_read_b128 v[170:173], v149 offset:34816
	ds_read_b128 v[174:177], v149 offset:35840
	ds_read_b128 v[178:181], v149 offset:36864
	ds_read_b128 v[182:185], v149 offset:37888
	ds_read_b128 v[186:189], v149 offset:38912
	ds_read_b128 v[190:193], v149 offset:39936
	global_load_lds_dwordx4 v[232:233], off
	v_lshl_add_u64 v[232:233], s[22:23], 0, v[132:133]
	s_mov_b32 m0, s68
	s_nop 0
	global_load_lds_dwordx4 v[232:233], off
	s_waitcnt lgkmcnt(11)
	s_add_i32 s44, 0, 0x1c000
	s_add_i32 s22, s51, s48
	v_add_u32_e32 v216, s44, v147
	v_lshl_add_u64 v[144:145], v[144:145], 0, s[92:93]
	s_mov_b32 m0, s22
	ds_read_b128 v[194:197], v216
	ds_read_b128 v[198:201], v216 offset:1024
	ds_read_b128 v[202:205], v216 offset:2048
	ds_read_b128 v[220:223], v216 offset:3072
	s_waitcnt vmcnt(8) lgkmcnt(0)
	s_barrier
	v_mfma_f32_16x16x32_f16 v[126:129], v[140:143], v[162:165], v[126:129]
	v_mfma_f32_16x16x32_f16 v[122:125], v[154:157], v[162:165], v[122:125]
	v_mfma_f32_16x16x32_f16 v[110:113], v[140:143], v[170:173], v[110:113]
	v_mfma_f32_16x16x32_f16 v[106:109], v[154:157], v[170:173], v[106:109]
	v_mfma_f32_16x16x32_f16 v[94:97], v[140:143], v[178:181], v[94:97]
	v_mfma_f32_16x16x32_f16 v[90:93], v[154:157], v[178:181], v[90:93]
	v_mfma_f32_16x16x32_f16 v[78:81], v[140:143], v[186:189], v[78:81]
	v_mfma_f32_16x16x32_f16 v[74:77], v[154:157], v[186:189], v[74:77]
	v_mfma_f32_16x16x32_f16 v[126:129], v[150:153], v[166:169], v[126:129]
	v_mfma_f32_16x16x32_f16 v[122:125], v[158:161], v[166:169], v[122:125]
	v_mfma_f32_16x16x32_f16 v[110:113], v[150:153], v[174:177], v[110:113]
	v_mfma_f32_16x16x32_f16 v[106:109], v[158:161], v[174:177], v[106:109]
	v_mfma_f32_16x16x32_f16 v[94:97], v[150:153], v[182:185], v[94:97]
	v_mfma_f32_16x16x32_f16 v[90:93], v[158:161], v[182:185], v[90:93]
	v_mfma_f32_16x16x32_f16 v[78:81], v[150:153], v[190:193], v[78:81]
	v_mfma_f32_16x16x32_f16 v[74:77], v[158:161], v[190:193], v[74:77]
	v_mfma_f32_16x16x32_f16 v[118:121], v[194:197], v[162:165], v[118:121]
	v_mfma_f32_16x16x32_f16 v[114:117], v[202:205], v[162:165], v[114:117]
	v_mfma_f32_16x16x32_f16 v[102:105], v[194:197], v[170:173], v[102:105]
	v_mfma_f32_16x16x32_f16 v[98:101], v[202:205], v[170:173], v[98:101]
	v_mfma_f32_16x16x32_f16 v[86:89], v[194:197], v[178:181], v[86:89]
	v_mfma_f32_16x16x32_f16 v[82:85], v[202:205], v[178:181], v[82:85]
	v_mfma_f32_16x16x32_f16 v[70:73], v[194:197], v[186:189], v[70:73]
	v_mfma_f32_16x16x32_f16 v[66:69], v[202:205], v[186:189], v[66:69]
	v_mfma_f32_16x16x32_f16 v[118:121], v[198:201], v[166:169], v[118:121]
	v_mfma_f32_16x16x32_f16 v[114:117], v[220:223], v[166:169], v[114:117]
	v_mfma_f32_16x16x32_f16 v[102:105], v[198:201], v[174:177], v[102:105]
	v_mfma_f32_16x16x32_f16 v[98:101], v[220:223], v[174:177], v[98:101]
	v_mfma_f32_16x16x32_f16 v[86:89], v[198:201], v[182:185], v[86:89]
	v_mfma_f32_16x16x32_f16 v[82:85], v[220:223], v[182:185], v[82:85]
	v_mfma_f32_16x16x32_f16 v[70:73], v[198:201], v[190:193], v[70:73]
	v_mfma_f32_16x16x32_f16 v[66:69], v[220:223], v[190:193], v[66:69]
	s_barrier
; #define PG8_STAGE(bufoff, gbase, voff) do { _Pragma("unroll") for (int _i = 0; _i < 2; ++_i) \
;         __builtin_amdgcn_global_load_lds((const unsigned*)((const char*)(gbase) + (voff)[_i]), (LAS unsigned*)(lds + (bufoff) + ldsw + _i * 8192), 16, 0, 0); } while (0)
; #define PG8_LDA(dst, b, h) do { _Pragma("unroll") for (int m = 0; m < 4; ++m) _Pragma("unroll") for (int k = 0; k < 2; ++k) dst[m][k] = *(const LAS h16x8*)(lds + PG8_SA(b, h) + aoff + m * 2048 + k * 1024); } while (0)
; #define PG8_LDB(dst, b, h) do { _Pragma("unroll") for (int n = 0; n < 2; ++n) _Pragma("unroll") for (int k = 0; k < 2; ++k) dst[n][k] = *(const LAS h16x8*)(lds + PG8_SB(b, h) + boff + n * 2048 + k * 1024); } while (0)
; #define PG8_MMA(ai, bj, At, Bt_) do { __builtin_amdgcn_s_setprio(1); _Pragma("unroll") for (int m = 0; m < 4; ++m) _Pragma("unroll") for (int n = 0; n < 2; ++n) _Pragma("unroll") for (int k = 0; k < 2; ++k) \
;         acc[ai][bj][m][n] = __builtin_amdgcn_mfma_f32_16x16x32_f16(Bt_[n][k], At[m][k], acc[ai][bj][m][n], 0, 0, 0); __builtin_amdgcn_s_setprio(0); } while (0)
; #define PG8_WAIT_V(n) asm volatile("s_waitcnt vmcnt(" #n ")" ::: "memory")
; template <class Epi, class AMap>
; __device__ __forceinline__ void gemm_phase(LAS unsigned char* lds, const AMap am, const int lda, const h16* Bt, const int ldb, const int M, const int N, const int K, const Epi& E) {
;     ...
;             PG8_WAIT_L(8); PG8_BAR; PG8_WAIT_L(0); PG8_MMA(0, 0, At, B0); PG8_BAR; PG8_SCHED;
;             PG8_LDB(B1, 1, 1); PG8_STAGE(PG8_SB(1, 0), b3, voffB);
;             PG8_BAR; PG8_WAIT_L(0); PG8_MMA(0, 1, At, B1); PG8_BAR;
;             PG8_LDA(At, 1, 1); PG8_STAGE(PG8_SA(1, 0), a3, voffA);
;             PG8_BAR; PG8_WAIT_L(0); PG8_MMA(1, 0, At, B0); PG8_BAR; PG8_SCHED;
;             PG8_STAGE(PG8_SB(1, 1), b3 + hstepB, voffB);
;             PG8_WAIT_V(6); PG8_BAR; PG8_MMA(1, 1, At, B1); PG8_BAR;
;         }
;         E(acc, cur, wr, wc, fr, fq);
;         if (!has_next) break;
;     __device__ __forceinline__ void operator()(const f32x4 (&acc)[2][2][4][2], const Unit& u, int wr, int wc, int fr, int fq) const {
;     ...
;             for (int m = 0; m < 4; ++m) { const size_t off = (size_t)(row0 + ai * 128 + m * 16) * DM + colt;
; #pragma unroll
;                 for (int bj = 0; bj < 2; ++bj) {
;                     const h16x8 x = *(const h16x8*)(X + off + bj * 128);
	global_load_lds_dwordx4 v[144:145], off
	v_lshl_add_u64 v[144:145], v[206:207], 0, s[92:93]
	s_add_i32 m0, s22, 0x2000
	s_nop 0
	global_load_lds_dwordx4 v[144:145], off
	s_mov_b32 m0, s69
	v_lshl_add_u64 v[144:145], v[212:213], 0, s[92:93]
	ds_read_b128 v[162:165], v149 offset:49152
	ds_read_b128 v[166:169], v149 offset:50176
	ds_read_b128 v[170:173], v149 offset:51200
	ds_read_b128 v[174:177], v149 offset:52224
	ds_read_b128 v[178:181], v149 offset:53248
	ds_read_b128 v[182:185], v149 offset:54272
	ds_read_b128 v[186:189], v149 offset:55296
	ds_read_b128 v[190:193], v149 offset:56320
	global_load_lds_dwordx4 v[144:145], off
	v_lshl_add_u64 v[144:145], v[214:215], 0, s[92:93]
	s_mov_b32 m0, s70
	s_nop 0
	global_load_lds_dwordx4 v[144:145], off
	s_add_u32 s22, s42, 0x158080
	s_addc_u32 s23, s43, 0
	s_add_i32 s42, s44, s48
	v_lshl_add_u64 v[232:233], s[22:23], 0, v[0:1]
	s_mov_b32 m0, s42
	s_nop 0
	global_load_lds_dwordx4 v[232:233], off
	v_lshl_add_u64 v[232:233], s[22:23], 0, v[134:135]
	s_add_i32 m0, s42, 0x2000
	s_nop 0
	global_load_lds_dwordx4 v[232:233], off
	s_waitcnt vmcnt(8) lgkmcnt(0)
	s_barrier
	v_mfma_f32_16x16x32_f16 v[62:65], v[140:143], v[162:165], v[62:65]
	v_mfma_f32_16x16x32_f16 v[58:61], v[154:157], v[162:165], v[58:61]
	v_mfma_f32_16x16x32_f16 v[46:49], v[140:143], v[170:173], v[46:49]
	v_mfma_f32_16x16x32_f16 v[42:45], v[154:157], v[170:173], v[42:45]
	v_mfma_f32_16x16x32_f16 v[30:33], v[140:143], v[178:181], v[30:33]
	v_mfma_f32_16x16x32_f16 v[26:29], v[154:157], v[178:181], v[26:29]
	v_mfma_f32_16x16x32_f16 v[14:17], v[140:143], v[186:189], v[14:17]
	v_mfma_f32_16x16x32_f16 v[10:13], v[154:157], v[186:189], v[10:13]
	v_mfma_f32_16x16x32_f16 v[62:65], v[150:153], v[166:169], v[62:65]
	v_mfma_f32_16x16x32_f16 v[58:61], v[158:161], v[166:169], v[58:61]
	v_mfma_f32_16x16x32_f16 v[46:49], v[150:153], v[174:177], v[46:49]
	v_mfma_f32_16x16x32_f16 v[42:45], v[158:161], v[174:177], v[42:45]
	v_mfma_f32_16x16x32_f16 v[30:33], v[150:153], v[182:185], v[30:33]
	v_mfma_f32_16x16x32_f16 v[26:29], v[158:161], v[182:185], v[26:29]
	v_mfma_f32_16x16x32_f16 v[14:17], v[150:153], v[190:193], v[14:17]
	v_mfma_f32_16x16x32_f16 v[10:13], v[158:161], v[190:193], v[10:13]
	v_mfma_f32_16x16x32_f16 v[54:57], v[194:197], v[162:165], v[54:57]
	v_mfma_f32_16x16x32_f16 v[50:53], v[202:205], v[162:165], v[50:53]
	v_mfma_f32_16x16x32_f16 v[38:41], v[194:197], v[170:173], v[38:41]
	v_mfma_f32_16x16x32_f16 v[34:37], v[202:205], v[170:173], v[34:37]
	v_mfma_f32_16x16x32_f16 v[22:25], v[194:197], v[178:181], v[22:25]
	v_mfma_f32_16x16x32_f16 v[18:21], v[202:205], v[178:181], v[18:21]
	v_mfma_f32_16x16x32_f16 v[6:9], v[194:197], v[186:189], v[6:9]
	v_mfma_f32_16x16x32_f16 v[2:5], v[202:205], v[186:189], v[2:5]
	v_mfma_f32_16x16x32_f16 v[54:57], v[198:201], v[166:169], v[54:57]
	v_mfma_f32_16x16x32_f16 v[50:53], v[220:223], v[166:169], v[50:53]
	v_mfma_f32_16x16x32_f16 v[38:41], v[198:201], v[174:177], v[38:41]
	v_mfma_f32_16x16x32_f16 v[34:37], v[220:223], v[174:177], v[34:37]
	v_mfma_f32_16x16x32_f16 v[22:25], v[198:201], v[182:185], v[22:25]
	v_mfma_f32_16x16x32_f16 v[18:21], v[220:223], v[182:185], v[18:21]
	v_mfma_f32_16x16x32_f16 v[6:9], v[198:201], v[190:193], v[6:9]
	v_mfma_f32_16x16x32_f16 v[2:5], v[220:223], v[190:193], v[2:5]
	s_add_i32 s29, s29, 2
	s_add_u32 s20, s20, 0x100
	s_addc_u32 s21, s21, 0
	s_cmpk_gt_u32 s29, 0x53
	s_mov_b64 s[22:23], s[26:27]
	s_barrier
	s_cbranch_scc0 .LBB0_61
	s_cmpk_gt_u32 s46, 0xff
	s_cbranch_scc1 .Lgx0
	s_barrier
.Lgx0:
	v_lshl_add_u32 v144, s35, 8, v146
	v_lshl_or_b32 v142, s50, 8, v148
	v_ashrrev_i32_e32 v145, 31, v144
	v_ashrrev_i32_e32 v143, 31, v142
	v_lshlrev_b64 v[140:141], 11, v[144:145]
	v_lshl_add_u64 v[140:141], v[140:141], 0, v[142:143]
	v_lshlrev_b64 v[140:141], 1, v[140:141]
	v_lshl_add_u64 v[154:155], s[94:95], 0, v[140:141]
	s_mov_b32 s101, 0
	global_load_dwordx4 v[158:161], v[154:155], off
	global_load_dwordx4 v[162:165], v[154:155], off offset:256
	s_mov_b32 s100, 0x10000
	v_lshl_add_u64 v[232:233], v[154:155], 0, s[100:101]
	global_load_dwordx4 v[166:169], v[232:233], off
	global_load_dwordx4 v[170:173], v[232:233], off offset:256
	s_mov_b32 s100, 0x20000
	v_lshl_add_u64 v[232:233], v[154:155], 0, s[100:101]
	global_load_dwordx4 v[174:177], v[232:233], off
	global_load_dwordx4 v[178:181], v[232:233], off offset:256
	s_mov_b32 s100, 0x30000
	v_lshl_add_u64 v[232:233], v[154:155], 0, s[100:101]
	global_load_dwordx4 v[182:185], v[232:233], off
	global_load_dwordx4 v[186:189], v[232:233], off offset:256
	s_mov_b32 s100, 0x80000
	v_lshl_add_u64 v[232:233], v[154:155], 0, s[100:101]
	global_load_dwordx4 v[190:193], v[232:233], off
	global_load_dwordx4 v[194:197], v[232:233], off offset:256
	s_mov_b32 s100, 0x90000
	v_lshl_add_u64 v[232:233], v[154:155], 0, s[100:101]
	global_load_dwordx4 v[198:201], v[232:233], off
	global_load_dwordx4 v[202:205], v[232:233], off offset:256
	s_mov_b32 s100, 0xa0000
	v_lshl_add_u64 v[232:233], v[154:155], 0, s[100:101]
	global_load_dwordx4 v[212:215], v[232:233], off
	global_load_dwordx4 v[220:223], v[232:233], off offset:256
	s_mov_b32 s100, 0xb0000
	v_lshl_add_u64 v[232:233], v[154:155], 0, s[100:101]
	global_load_dwordx4 v[224:227], v[232:233], off
	global_load_dwordx4 v[228:231], v[232:233], off offset:256
	s_mov_b64 s[4:5], 0xb0000
	s_and_b64 vcc, exec, s[38:39]
	s_mov_b32 s50, s72
	s_mov_b64 s[26:27], s[40:41]
	s_mov_b64 s[22:23], s[0:1]
	s_waitcnt vmcnt(15)
;     __device__ __forceinline__ void operator()(const f32x4 (&acc)[2][2][4][2], const Unit& u, int wr, int wc, int fr, int fq) const {
;     ...
;             for (int m = 0; m < 4; ++m) { const size_t off = (size_t)(row0 + ai * 128 + m * 16) * DM + colt;
; #pragma unroll
;                 for (int bj = 0; bj < 2; ++bj) {
;                     const h16x8 x = *(const h16x8*)(X + off + bj * 128);
;                     f32x4 o0, o1;
; #pragma unroll
;                     for (int e = 0; e < 4; ++e) { o0[e] = (float)x[e] * ALPHA + acc[ai][bj][m][0][e]; o1[e] = (float)x[4 + e] * ALPHA + acc[ai][bj][m][1][e]; }
;                     *(u32x4*)(PRE + off + bj * 128) = pack8(o0, o1); } }
	v_mov_b64_e32 v[150:151], v[158:159]
	v_mov_b64_e32 v[152:153], v[160:161]
	v_cvt_f32_f16_e32 v156, v150
	v_cvt_f32_f16_sdwa v157, v150 dst_sel:DWORD dst_unused:UNUSED_PAD src0_sel:WORD_1
	v_cvt_f32_f16_e32 v150, v151
	v_cvt_f32_f16_sdwa v151, v151 dst_sel:DWORD dst_unused:UNUSED_PAD src0_sel:WORD_1
	v_pk_fma_f32 v[126:127], v[156:157], s[34:35], v[126:127] op_sel_hi:[1,0,1]
	s_nop 0
	v_cvt_pk_f16_f32 v126, v126, v127
	v_pk_fma_f32 v[128:129], v[150:151], s[34:35], v[128:129] op_sel_hi:[1,0,1]
	v_lshl_add_u64 v[150:151], s[8:9], 0, v[140:141]
	v_cvt_pk_f16_f32 v127, v128, v129
	v_cvt_f32_f16_e32 v128, v152
	v_cvt_f32_f16_sdwa v129, v152 dst_sel:DWORD dst_unused:UNUSED_PAD src0_sel:WORD_1
	v_pk_fma_f32 v[122:123], v[128:129], s[34:35], v[122:123] op_sel_hi:[1,0,1]
	s_nop 0
	v_cvt_pk_f16_f32 v128, v122, v123
	v_cvt_f32_f16_e32 v122, v153
	v_cvt_f32_f16_sdwa v123, v153 dst_sel:DWORD dst_unused:UNUSED_PAD src0_sel:WORD_1
	v_pk_fma_f32 v[122:123], v[122:123], s[34:35], v[124:125] op_sel_hi:[1,0,1]
	s_nop 0
	v_cvt_pk_f16_f32 v129, v122, v123
	s_nop 0
	global_store_dwordx4 v[150:151], v[126:129], off
	s_waitcnt vmcnt(15)
	v_mov_b64_e32 v[122:123], v[162:163]
	v_mov_b64_e32 v[124:125], v[164:165]
	s_nop 0
	v_cvt_f32_f16_e32 v126, v122
	v_cvt_f32_f16_sdwa v127, v122 dst_sel:DWORD dst_unused:UNUSED_PAD src0_sel:WORD_1
	v_cvt_f32_f16_e32 v122, v123
	v_cvt_f32_f16_sdwa v123, v123 dst_sel:DWORD dst_unused:UNUSED_PAD src0_sel:WORD_1
	v_pk_fma_f32 v[118:119], v[126:127], s[34:35], v[118:119] op_sel_hi:[1,0,1]
	s_nop 0
	v_cvt_pk_f16_f32 v118, v118, v119
	v_pk_fma_f32 v[120:121], v[122:123], s[34:35], v[120:121] op_sel_hi:[1,0,1]
	s_nop 0
	v_cvt_pk_f16_f32 v119, v120, v121
	v_cvt_f32_f16_e32 v120, v124
	v_cvt_f32_f16_sdwa v121, v124 dst_sel:DWORD dst_unused:UNUSED_PAD src0_sel:WORD_1
	v_pk_fma_f32 v[114:115], v[120:121], s[34:35], v[114:115] op_sel_hi:[1,0,1]
	s_nop 0
	v_cvt_pk_f16_f32 v120, v114, v115
	v_cvt_f32_f16_e32 v114, v125
	v_cvt_f32_f16_sdwa v115, v125 dst_sel:DWORD dst_unused:UNUSED_PAD src0_sel:WORD_1
	v_pk_fma_f32 v[114:115], v[114:115], s[34:35], v[116:117] op_sel_hi:[1,0,1]
	s_nop 0
	v_cvt_pk_f16_f32 v121, v114, v115
	v_or_b32_e32 v114, 16, v144
	v_ashrrev_i32_e32 v115, 31, v114
	v_lshlrev_b64 v[114:115], 11, v[114:115]
	v_lshl_add_u64 v[114:115], v[114:115], 0, v[142:143]
	global_store_dwordx4 v[150:151], v[118:121], off offset:256
	s_nop 1
	v_lshlrev_b64 v[118:119], 1, v[114:115]
	v_lshl_add_u64 v[120:121], s[94:95], 0, v[118:119]
	s_waitcnt vmcnt(15)
	v_mov_b64_e32 v[114:115], v[166:167]
	v_mov_b64_e32 v[116:117], v[168:169]
	v_cvt_f32_f16_e32 v122, v114
	v_cvt_f32_f16_sdwa v123, v114 dst_sel:DWORD dst_unused:UNUSED_PAD src0_sel:WORD_1
	v_cvt_f32_f16_e32 v114, v115
	v_cvt_f32_f16_sdwa v115, v115 dst_sel:DWORD dst_unused:UNUSED_PAD src0_sel:WORD_1
	v_pk_fma_f32 v[110:111], v[122:123], s[34:35], v[110:111] op_sel_hi:[1,0,1]
	s_nop 0
	v_cvt_pk_f16_f32 v110, v110, v111
	v_pk_fma_f32 v[112:113], v[114:115], s[34:35], v[112:113] op_sel_hi:[1,0,1]
	v_lshl_add_u64 v[114:115], s[8:9], 0, v[118:119]
	v_cvt_pk_f16_f32 v111, v112, v113
	v_cvt_f32_f16_e32 v112, v116
	v_cvt_f32_f16_sdwa v113, v116 dst_sel:DWORD dst_unused:UNUSED_PAD src0_sel:WORD_1
	v_pk_fma_f32 v[106:107], v[112:113], s[34:35], v[106:107] op_sel_hi:[1,0,1]
	s_nop 0
	v_cvt_pk_f16_f32 v112, v106, v107
	v_cvt_f32_f16_e32 v106, v117
	v_cvt_f32_f16_sdwa v107, v117 dst_sel:DWORD dst_unused:UNUSED_PAD src0_sel:WORD_1
	v_pk_fma_f32 v[106:107], v[106:107], s[34:35], v[108:109] op_sel_hi:[1,0,1]
	s_nop 0
	v_cvt_pk_f16_f32 v113, v106, v107
	s_nop 0
	global_store_dwordx4 v[114:115], v[110:113], off
	s_waitcnt vmcnt(15)
	v_mov_b64_e32 v[106:107], v[170:171]
	v_mov_b64_e32 v[108:109], v[172:173]
	s_nop 0
	v_cvt_f32_f16_e32 v110, v106
	v_cvt_f32_f16_sdwa v111, v106 dst_sel:DWORD dst_unused:UNUSED_PAD src0_sel:WORD_1
	v_cvt_f32_f16_e32 v106, v107
	v_cvt_f32_f16_sdwa v107, v107 dst_sel:DWORD dst_unused:UNUSED_PAD src0_sel:WORD_1
	v_pk_fma_f32 v[102:103], v[110:111], s[34:35], v[102:103] op_sel_hi:[1,0,1]
	s_nop 0
	v_cvt_pk_f16_f32 v102, v102, v103
	v_pk_fma_f32 v[104:105], v[106:107], s[34:35], v[104:105] op_sel_hi:[1,0,1]
	s_nop 0
	v_cvt_pk_f16_f32 v103, v104, v105
	v_cvt_f32_f16_e32 v104, v108
	v_cvt_f32_f16_sdwa v105, v108 dst_sel:DWORD dst_unused:UNUSED_PAD src0_sel:WORD_1
	v_pk_fma_f32 v[98:99], v[104:105], s[34:35], v[98:99] op_sel_hi:[1,0,1]
	s_nop 0
	v_cvt_pk_f16_f32 v104, v98, v99
	v_cvt_f32_f16_e32 v98, v109
	v_cvt_f32_f16_sdwa v99, v109 dst_sel:DWORD dst_unused:UNUSED_PAD src0_sel:WORD_1
	v_pk_fma_f32 v[98:99], v[98:99], s[34:35], v[100:101] op_sel_hi:[1,0,1]
	s_nop 0
	v_cvt_pk_f16_f32 v105, v98, v99
	v_or_b32_e32 v98, 32, v144
	v_ashrrev_i32_e32 v99, 31, v98
	v_lshlrev_b64 v[98:99], 11, v[98:99]
	v_lshl_add_u64 v[98:99], v[98:99], 0, v[142:143]
	global_store_dwordx4 v[114:115], v[102:105], off offset:256
	s_nop 1
	v_lshlrev_b64 v[102:103], 1, v[98:99]
	v_lshl_add_u64 v[104:105], s[94:95], 0, v[102:103]
	s_waitcnt vmcnt(15)
	v_mov_b64_e32 v[98:99], v[174:175]
	v_mov_b64_e32 v[100:101], v[176:177]
	v_cvt_f32_f16_e32 v106, v98
	v_cvt_f32_f16_sdwa v107, v98 dst_sel:DWORD dst_unused:UNUSED_PAD src0_sel:WORD_1
	v_cvt_f32_f16_e32 v98, v99
	v_cvt_f32_f16_sdwa v99, v99 dst_sel:DWORD dst_unused:UNUSED_PAD src0_sel:WORD_1
	v_pk_fma_f32 v[94:95], v[106:107], s[34:35], v[94:95] op_sel_hi:[1,0,1]
	s_nop 0
	v_cvt_pk_f16_f32 v94, v94, v95
	v_pk_fma_f32 v[96:97], v[98:99], s[34:35], v[96:97] op_sel_hi:[1,0,1]
	v_lshl_add_u64 v[98:99], s[8:9], 0, v[102:103]
	v_cvt_pk_f16_f32 v95, v96, v97
	v_cvt_f32_f16_e32 v96, v100
	v_cvt_f32_f16_sdwa v97, v100 dst_sel:DWORD dst_unused:UNUSED_PAD src0_sel:WORD_1
	v_pk_fma_f32 v[90:91], v[96:97], s[34:35], v[90:91] op_sel_hi:[1,0,1]
	s_nop 0
	v_cvt_pk_f16_f32 v96, v90, v91
	v_cvt_f32_f16_e32 v90, v101
	v_cvt_f32_f16_sdwa v91, v101 dst_sel:DWORD dst_unused:UNUSED_PAD src0_sel:WORD_1
	v_pk_fma_f32 v[90:91], v[90:91], s[34:35], v[92:93] op_sel_hi:[1,0,1]
	s_nop 0
	v_cvt_pk_f16_f32 v97, v90, v91
	s_nop 0
	global_store_dwordx4 v[98:99], v[94:97], off
	s_waitcnt vmcnt(15)
;     __device__ __forceinline__ void operator()(const f32x4 (&acc)[2][2][4][2], const Unit& u, int wr, int wc, int fr, int fq) const {
;     ...
;             for (int m = 0; m < 4; ++m) { const size_t off = (size_t)(row0 + ai * 128 + m * 16) * DM + colt;
; #pragma unroll
;                 for (int bj = 0; bj < 2; ++bj) {
;                     const h16x8 x = *(const h16x8*)(X + off + bj * 128);
;                     f32x4 o0, o1;
; #pragma unroll
;                     for (int e = 0; e < 4; ++e) { o0[e] = (float)x[e] * ALPHA + acc[ai][bj][m][0][e]; o1[e] = (float)x[4 + e] * ALPHA + acc[ai][bj][m][1][e]; }
;                     *(u32x4*)(PRE + off + bj * 128) = pack8(o0, o1); } }
	v_mov_b64_e32 v[90:91], v[178:179]
	v_mov_b64_e32 v[92:93], v[180:181]
	s_nop 0
	v_cvt_f32_f16_e32 v94, v90
	v_cvt_f32_f16_sdwa v95, v90 dst_sel:DWORD dst_unused:UNUSED_PAD src0_sel:WORD_1
	v_cvt_f32_f16_e32 v90, v91
	v_cvt_f32_f16_sdwa v91, v91 dst_sel:DWORD dst_unused:UNUSED_PAD src0_sel:WORD_1
	v_pk_fma_f32 v[86:87], v[94:95], s[34:35], v[86:87] op_sel_hi:[1,0,1]
	s_nop 0
	v_cvt_pk_f16_f32 v86, v86, v87
	v_pk_fma_f32 v[88:89], v[90:91], s[34:35], v[88:89] op_sel_hi:[1,0,1]
	s_nop 0
	v_cvt_pk_f16_f32 v87, v88, v89
	v_cvt_f32_f16_e32 v88, v92
	v_cvt_f32_f16_sdwa v89, v92 dst_sel:DWORD dst_unused:UNUSED_PAD src0_sel:WORD_1
	v_pk_fma_f32 v[82:83], v[88:89], s[34:35], v[82:83] op_sel_hi:[1,0,1]
	s_nop 0
	v_cvt_pk_f16_f32 v88, v82, v83
	v_cvt_f32_f16_e32 v82, v93
	v_cvt_f32_f16_sdwa v83, v93 dst_sel:DWORD dst_unused:UNUSED_PAD src0_sel:WORD_1
	v_pk_fma_f32 v[82:83], v[82:83], s[34:35], v[84:85] op_sel_hi:[1,0,1]
	s_nop 0
	v_cvt_pk_f16_f32 v89, v82, v83
	v_or_b32_e32 v82, 48, v144
	v_ashrrev_i32_e32 v83, 31, v82
	v_lshlrev_b64 v[82:83], 11, v[82:83]
	v_lshl_add_u64 v[82:83], v[82:83], 0, v[142:143]
	global_store_dwordx4 v[98:99], v[86:89], off offset:256
	s_nop 1
	v_lshlrev_b64 v[86:87], 1, v[82:83]
	v_lshl_add_u64 v[88:89], s[94:95], 0, v[86:87]
	s_waitcnt vmcnt(15)
	v_mov_b64_e32 v[82:83], v[182:183]
	v_mov_b64_e32 v[84:85], v[184:185]
	v_cvt_f32_f16_e32 v90, v82
	v_cvt_f32_f16_sdwa v91, v82 dst_sel:DWORD dst_unused:UNUSED_PAD src0_sel:WORD_1
	v_cvt_f32_f16_e32 v82, v83
	v_cvt_f32_f16_sdwa v83, v83 dst_sel:DWORD dst_unused:UNUSED_PAD src0_sel:WORD_1
	v_pk_fma_f32 v[78:79], v[90:91], s[34:35], v[78:79] op_sel_hi:[1,0,1]
	s_nop 0
	v_cvt_pk_f16_f32 v78, v78, v79
	v_pk_fma_f32 v[80:81], v[82:83], s[34:35], v[80:81] op_sel_hi:[1,0,1]
	v_lshl_add_u64 v[82:83], s[8:9], 0, v[86:87]
	v_cvt_pk_f16_f32 v79, v80, v81
	v_cvt_f32_f16_e32 v80, v84
	v_cvt_f32_f16_sdwa v81, v84 dst_sel:DWORD dst_unused:UNUSED_PAD src0_sel:WORD_1
	v_pk_fma_f32 v[74:75], v[80:81], s[34:35], v[74:75] op_sel_hi:[1,0,1]
	s_nop 0
	v_cvt_pk_f16_f32 v80, v74, v75
	v_cvt_f32_f16_e32 v74, v85
	v_cvt_f32_f16_sdwa v75, v85 dst_sel:DWORD dst_unused:UNUSED_PAD src0_sel:WORD_1
	v_pk_fma_f32 v[74:75], v[74:75], s[34:35], v[76:77] op_sel_hi:[1,0,1]
	s_nop 0
	v_cvt_pk_f16_f32 v81, v74, v75
	s_nop 0
	global_store_dwordx4 v[82:83], v[78:81], off
	s_waitcnt vmcnt(15)
	v_mov_b64_e32 v[74:75], v[186:187]
	v_mov_b64_e32 v[76:77], v[188:189]
	s_nop 0
	v_cvt_f32_f16_e32 v78, v74
	v_cvt_f32_f16_sdwa v79, v74 dst_sel:DWORD dst_unused:UNUSED_PAD src0_sel:WORD_1
	v_cvt_f32_f16_e32 v74, v75
	v_cvt_f32_f16_sdwa v75, v75 dst_sel:DWORD dst_unused:UNUSED_PAD src0_sel:WORD_1
	v_pk_fma_f32 v[70:71], v[78:79], s[34:35], v[70:71] op_sel_hi:[1,0,1]
	s_nop 0
	v_cvt_pk_f16_f32 v70, v70, v71
	v_pk_fma_f32 v[72:73], v[74:75], s[34:35], v[72:73] op_sel_hi:[1,0,1]
	s_nop 0
	v_cvt_pk_f16_f32 v71, v72, v73
	v_cvt_f32_f16_e32 v72, v76
	v_cvt_f32_f16_sdwa v73, v76 dst_sel:DWORD dst_unused:UNUSED_PAD src0_sel:WORD_1
	v_pk_fma_f32 v[66:67], v[72:73], s[34:35], v[66:67] op_sel_hi:[1,0,1]
	s_nop 0
	v_cvt_pk_f16_f32 v72, v66, v67
	v_cvt_f32_f16_e32 v66, v77
	v_cvt_f32_f16_sdwa v67, v77 dst_sel:DWORD dst_unused:UNUSED_PAD src0_sel:WORD_1
	v_pk_fma_f32 v[66:67], v[66:67], s[34:35], v[68:69] op_sel_hi:[1,0,1]
	s_nop 0
	v_cvt_pk_f16_f32 v73, v66, v67
	global_store_dwordx4 v[82:83], v[70:73], off offset:256
	s_nop 1
	v_lshl_add_u64 v[70:71], v[140:141], 0, s[16:17]
	v_lshl_add_u64 v[72:73], s[94:95], 0, v[70:71]
	s_waitcnt vmcnt(15)
	v_mov_b64_e32 v[66:67], v[190:191]
	v_mov_b64_e32 v[68:69], v[192:193]
	v_cvt_f32_f16_e32 v74, v66
	v_cvt_f32_f16_sdwa v75, v66 dst_sel:DWORD dst_unused:UNUSED_PAD src0_sel:WORD_1
	v_cvt_f32_f16_e32 v66, v67
	v_cvt_f32_f16_sdwa v67, v67 dst_sel:DWORD dst_unused:UNUSED_PAD src0_sel:WORD_1
	v_pk_fma_f32 v[62:63], v[74:75], s[34:35], v[62:63] op_sel_hi:[1,0,1]
	s_nop 0
	v_cvt_pk_f16_f32 v62, v62, v63
	v_pk_fma_f32 v[64:65], v[66:67], s[34:35], v[64:65] op_sel_hi:[1,0,1]
	v_lshl_add_u64 v[66:67], s[8:9], 0, v[70:71]
	v_cvt_pk_f16_f32 v63, v64, v65
	v_cvt_f32_f16_e32 v64, v68
	v_cvt_f32_f16_sdwa v65, v68 dst_sel:DWORD dst_unused:UNUSED_PAD src0_sel:WORD_1
	v_pk_fma_f32 v[58:59], v[64:65], s[34:35], v[58:59] op_sel_hi:[1,0,1]
	s_nop 0
	v_cvt_pk_f16_f32 v64, v58, v59
	v_cvt_f32_f16_e32 v58, v69
	v_cvt_f32_f16_sdwa v59, v69 dst_sel:DWORD dst_unused:UNUSED_PAD src0_sel:WORD_1
	v_pk_fma_f32 v[58:59], v[58:59], s[34:35], v[60:61] op_sel_hi:[1,0,1]
	s_nop 0
	v_cvt_pk_f16_f32 v65, v58, v59
	s_nop 0
	global_store_dwordx4 v[66:67], v[62:65], off
	s_waitcnt vmcnt(15)
	v_mov_b64_e32 v[58:59], v[194:195]
	v_mov_b64_e32 v[60:61], v[196:197]
	s_nop 0
	v_cvt_f32_f16_e32 v62, v58
	v_cvt_f32_f16_sdwa v63, v58 dst_sel:DWORD dst_unused:UNUSED_PAD src0_sel:WORD_1
	v_cvt_f32_f16_e32 v58, v59
	v_cvt_f32_f16_sdwa v59, v59 dst_sel:DWORD dst_unused:UNUSED_PAD src0_sel:WORD_1
	v_pk_fma_f32 v[54:55], v[62:63], s[34:35], v[54:55] op_sel_hi:[1,0,1]
	s_nop 0
	v_cvt_pk_f16_f32 v54, v54, v55
	v_pk_fma_f32 v[56:57], v[58:59], s[34:35], v[56:57] op_sel_hi:[1,0,1]
	s_nop 0
	v_cvt_pk_f16_f32 v55, v56, v57
	v_cvt_f32_f16_e32 v56, v60
	v_cvt_f32_f16_sdwa v57, v60 dst_sel:DWORD dst_unused:UNUSED_PAD src0_sel:WORD_1
	v_pk_fma_f32 v[50:51], v[56:57], s[34:35], v[50:51] op_sel_hi:[1,0,1]
	s_nop 0
	v_cvt_pk_f16_f32 v56, v50, v51
	v_cvt_f32_f16_e32 v50, v61
	v_cvt_f32_f16_sdwa v51, v61 dst_sel:DWORD dst_unused:UNUSED_PAD src0_sel:WORD_1
	v_pk_fma_f32 v[50:51], v[50:51], s[34:35], v[52:53] op_sel_hi:[1,0,1]
	s_nop 0
	v_cvt_pk_f16_f32 v57, v50, v51
	global_store_dwordx4 v[66:67], v[54:57], off offset:256
	s_nop 1
	v_lshl_add_u64 v[54:55], v[140:141], 0, s[18:19]
	v_lshl_add_u64 v[56:57], s[94:95], 0, v[54:55]
	s_waitcnt vmcnt(15)
; template <class Epi, class AMap>
; __device__ __forceinline__ void gemm_phase(LAS unsigned char* lds, const AMap am, const int lda, const h16* Bt, const int ldb, const int M, const int N, const int K, const Epi& E) {
;     ...
;         if (!has_next) break;
; #pragma unroll
;         for (int a = 0; a < 2; ++a)
; #pragma unroll
;             for (int b = 0; b < 2; ++b)
; #pragma unroll
;                 for (int m = 0; m < 4; ++m)
; #pragma unroll
;                     for (int n = 0; n < 2; ++n) acc[a][b][m][n] = (f32x4){0.f, 0.f, 0.f, 0.f};
;         cur = nxt; cA = nA; cB = nB; ++ui;
;     }
;     __device__ __forceinline__ void operator()(const f32x4 (&acc)[2][2][4][2], const Unit& u, int wr, int wc, int fr, int fq) const {
;     ...
;             for (int m = 0; m < 4; ++m) { const size_t off = (size_t)(row0 + ai * 128 + m * 16) * DM + colt;
; #pragma unroll
;                 for (int bj = 0; bj < 2; ++bj) {
;                     const h16x8 x = *(const h16x8*)(X + off + bj * 128);
;                     f32x4 o0, o1;
; #pragma unroll
;                     for (int e = 0; e < 4; ++e) { o0[e] = (float)x[e] * ALPHA + acc[ai][bj][m][0][e]; o1[e] = (float)x[4 + e] * ALPHA + acc[ai][bj][m][1][e]; }
;                     *(u32x4*)(PRE + off + bj * 128) = pack8(o0, o1); } }
	v_mov_b64_e32 v[50:51], v[198:199]
	v_mov_b64_e32 v[52:53], v[200:201]
	v_cvt_f32_f16_e32 v58, v50
	v_cvt_f32_f16_sdwa v59, v50 dst_sel:DWORD dst_unused:UNUSED_PAD src0_sel:WORD_1
	v_cvt_f32_f16_e32 v50, v51
	v_cvt_f32_f16_sdwa v51, v51 dst_sel:DWORD dst_unused:UNUSED_PAD src0_sel:WORD_1
	v_pk_fma_f32 v[46:47], v[58:59], s[34:35], v[46:47] op_sel_hi:[1,0,1]
	s_nop 0
	v_cvt_pk_f16_f32 v46, v46, v47
	v_pk_fma_f32 v[48:49], v[50:51], s[34:35], v[48:49] op_sel_hi:[1,0,1]
	v_lshl_add_u64 v[50:51], s[8:9], 0, v[54:55]
	v_cvt_pk_f16_f32 v47, v48, v49
	v_cvt_f32_f16_e32 v48, v52
	v_cvt_f32_f16_sdwa v49, v52 dst_sel:DWORD dst_unused:UNUSED_PAD src0_sel:WORD_1
	v_pk_fma_f32 v[42:43], v[48:49], s[34:35], v[42:43] op_sel_hi:[1,0,1]
	s_nop 0
	v_cvt_pk_f16_f32 v48, v42, v43
	v_cvt_f32_f16_e32 v42, v53
	v_cvt_f32_f16_sdwa v43, v53 dst_sel:DWORD dst_unused:UNUSED_PAD src0_sel:WORD_1
	v_pk_fma_f32 v[42:43], v[42:43], s[34:35], v[44:45] op_sel_hi:[1,0,1]
	s_nop 0
	v_cvt_pk_f16_f32 v49, v42, v43
	s_nop 0
	global_store_dwordx4 v[50:51], v[46:49], off
	s_waitcnt vmcnt(15)
	v_mov_b64_e32 v[42:43], v[202:203]
	v_mov_b64_e32 v[44:45], v[204:205]
	s_nop 0
	v_cvt_f32_f16_e32 v46, v42
	v_cvt_f32_f16_sdwa v47, v42 dst_sel:DWORD dst_unused:UNUSED_PAD src0_sel:WORD_1
	v_cvt_f32_f16_e32 v42, v43
	v_cvt_f32_f16_sdwa v43, v43 dst_sel:DWORD dst_unused:UNUSED_PAD src0_sel:WORD_1
	v_pk_fma_f32 v[38:39], v[46:47], s[34:35], v[38:39] op_sel_hi:[1,0,1]
	s_nop 0
	v_cvt_pk_f16_f32 v38, v38, v39
	v_pk_fma_f32 v[40:41], v[42:43], s[34:35], v[40:41] op_sel_hi:[1,0,1]
	s_nop 0
	v_cvt_pk_f16_f32 v39, v40, v41
	v_cvt_f32_f16_e32 v40, v44
	v_cvt_f32_f16_sdwa v41, v44 dst_sel:DWORD dst_unused:UNUSED_PAD src0_sel:WORD_1
	v_pk_fma_f32 v[34:35], v[40:41], s[34:35], v[34:35] op_sel_hi:[1,0,1]
	s_nop 0
	v_cvt_pk_f16_f32 v40, v34, v35
	v_cvt_f32_f16_e32 v34, v45
	v_cvt_f32_f16_sdwa v35, v45 dst_sel:DWORD dst_unused:UNUSED_PAD src0_sel:WORD_1
	v_pk_fma_f32 v[34:35], v[34:35], s[34:35], v[36:37] op_sel_hi:[1,0,1]
	s_nop 0
	v_cvt_pk_f16_f32 v41, v34, v35
	global_store_dwordx4 v[50:51], v[38:41], off offset:256
	s_nop 1
	v_lshl_add_u64 v[38:39], v[140:141], 0, s[14:15]
	v_lshl_add_u64 v[40:41], s[94:95], 0, v[38:39]
	s_waitcnt vmcnt(15)
	v_mov_b64_e32 v[34:35], v[212:213]
	v_mov_b64_e32 v[36:37], v[214:215]
	v_cvt_f32_f16_e32 v42, v34
	v_cvt_f32_f16_sdwa v43, v34 dst_sel:DWORD dst_unused:UNUSED_PAD src0_sel:WORD_1
	v_cvt_f32_f16_e32 v34, v35
	v_cvt_f32_f16_sdwa v35, v35 dst_sel:DWORD dst_unused:UNUSED_PAD src0_sel:WORD_1
	v_pk_fma_f32 v[30:31], v[42:43], s[34:35], v[30:31] op_sel_hi:[1,0,1]
	s_nop 0
	v_cvt_pk_f16_f32 v30, v30, v31
	v_pk_fma_f32 v[32:33], v[34:35], s[34:35], v[32:33] op_sel_hi:[1,0,1]
	v_lshl_add_u64 v[34:35], s[8:9], 0, v[38:39]
	v_cvt_pk_f16_f32 v31, v32, v33
	v_cvt_f32_f16_e32 v32, v36
	v_cvt_f32_f16_sdwa v33, v36 dst_sel:DWORD dst_unused:UNUSED_PAD src0_sel:WORD_1
	v_pk_fma_f32 v[26:27], v[32:33], s[34:35], v[26:27] op_sel_hi:[1,0,1]
	s_nop 0
	v_cvt_pk_f16_f32 v32, v26, v27
	v_cvt_f32_f16_e32 v26, v37
	v_cvt_f32_f16_sdwa v27, v37 dst_sel:DWORD dst_unused:UNUSED_PAD src0_sel:WORD_1
	v_pk_fma_f32 v[26:27], v[26:27], s[34:35], v[28:29] op_sel_hi:[1,0,1]
	s_nop 0
	v_cvt_pk_f16_f32 v33, v26, v27
	s_nop 0
	global_store_dwordx4 v[34:35], v[30:33], off
	s_waitcnt vmcnt(15)
	v_mov_b64_e32 v[26:27], v[220:221]
	v_mov_b64_e32 v[28:29], v[222:223]
	s_nop 0
	v_cvt_f32_f16_e32 v30, v26
	v_cvt_f32_f16_sdwa v31, v26 dst_sel:DWORD dst_unused:UNUSED_PAD src0_sel:WORD_1
	v_cvt_f32_f16_e32 v26, v27
	v_cvt_f32_f16_sdwa v27, v27 dst_sel:DWORD dst_unused:UNUSED_PAD src0_sel:WORD_1
	v_pk_fma_f32 v[22:23], v[30:31], s[34:35], v[22:23] op_sel_hi:[1,0,1]
	s_nop 0
	v_cvt_pk_f16_f32 v22, v22, v23
	v_pk_fma_f32 v[24:25], v[26:27], s[34:35], v[24:25] op_sel_hi:[1,0,1]
	s_nop 0
	v_cvt_pk_f16_f32 v23, v24, v25
	v_cvt_f32_f16_e32 v24, v28
	v_cvt_f32_f16_sdwa v25, v28 dst_sel:DWORD dst_unused:UNUSED_PAD src0_sel:WORD_1
	v_pk_fma_f32 v[18:19], v[24:25], s[34:35], v[18:19] op_sel_hi:[1,0,1]
	s_nop 0
	v_cvt_pk_f16_f32 v24, v18, v19
	v_cvt_f32_f16_e32 v18, v29
	v_cvt_f32_f16_sdwa v19, v29 dst_sel:DWORD dst_unused:UNUSED_PAD src0_sel:WORD_1
	v_pk_fma_f32 v[18:19], v[18:19], s[34:35], v[20:21] op_sel_hi:[1,0,1]
	s_nop 0
	v_cvt_pk_f16_f32 v25, v18, v19
	global_store_dwordx4 v[34:35], v[22:25], off offset:256
	s_nop 1
	v_lshl_add_u64 v[22:23], v[140:141], 0, s[4:5]
	v_lshl_add_u64 v[24:25], s[94:95], 0, v[22:23]
	s_waitcnt vmcnt(15)
	v_mov_b64_e32 v[18:19], v[224:225]
	v_mov_b64_e32 v[20:21], v[226:227]
	v_cvt_f32_f16_e32 v26, v18
	v_cvt_f32_f16_sdwa v27, v18 dst_sel:DWORD dst_unused:UNUSED_PAD src0_sel:WORD_1
	v_cvt_f32_f16_e32 v18, v19
	v_cvt_f32_f16_sdwa v19, v19 dst_sel:DWORD dst_unused:UNUSED_PAD src0_sel:WORD_1
	v_pk_fma_f32 v[14:15], v[26:27], s[34:35], v[14:15] op_sel_hi:[1,0,1]
	s_nop 0
	v_cvt_pk_f16_f32 v14, v14, v15
	v_pk_fma_f32 v[16:17], v[18:19], s[34:35], v[16:17] op_sel_hi:[1,0,1]
	v_lshl_add_u64 v[18:19], s[8:9], 0, v[22:23]
	v_cvt_pk_f16_f32 v15, v16, v17
	v_cvt_f32_f16_e32 v16, v20
	v_cvt_f32_f16_sdwa v17, v20 dst_sel:DWORD dst_unused:UNUSED_PAD src0_sel:WORD_1
	v_pk_fma_f32 v[10:11], v[16:17], s[34:35], v[10:11] op_sel_hi:[1,0,1]
	s_nop 0
	v_cvt_pk_f16_f32 v16, v10, v11
	v_cvt_f32_f16_e32 v10, v21
	v_cvt_f32_f16_sdwa v11, v21 dst_sel:DWORD dst_unused:UNUSED_PAD src0_sel:WORD_1
	v_pk_fma_f32 v[10:11], v[10:11], s[34:35], v[12:13] op_sel_hi:[1,0,1]
	s_nop 0
	v_cvt_pk_f16_f32 v17, v10, v11
	s_nop 0
	global_store_dwordx4 v[18:19], v[14:17], off
	s_waitcnt vmcnt(15)
	v_mov_b64_e32 v[10:11], v[228:229]
	v_mov_b64_e32 v[12:13], v[230:231]
	s_nop 0
	v_cvt_f32_f16_e32 v14, v10
	v_cvt_f32_f16_sdwa v15, v10 dst_sel:DWORD dst_unused:UNUSED_PAD src0_sel:WORD_1
	v_cvt_f32_f16_e32 v10, v11
	v_cvt_f32_f16_sdwa v11, v11 dst_sel:DWORD dst_unused:UNUSED_PAD src0_sel:WORD_1
	v_pk_fma_f32 v[6:7], v[14:15], s[34:35], v[6:7] op_sel_hi:[1,0,1]
	s_nop 0
	v_cvt_pk_f16_f32 v6, v6, v7
	v_pk_fma_f32 v[8:9], v[10:11], s[34:35], v[8:9] op_sel_hi:[1,0,1]
	s_nop 0
	v_cvt_pk_f16_f32 v7, v8, v9
	v_cvt_f32_f16_e32 v8, v12
	v_cvt_f32_f16_sdwa v9, v12 dst_sel:DWORD dst_unused:UNUSED_PAD src0_sel:WORD_1
	v_pk_fma_f32 v[2:3], v[8:9], s[34:35], v[2:3] op_sel_hi:[1,0,1]
	s_nop 0
	v_cvt_pk_f16_f32 v8, v2, v3
	v_cvt_f32_f16_e32 v2, v13
	v_cvt_f32_f16_sdwa v3, v13 dst_sel:DWORD dst_unused:UNUSED_PAD src0_sel:WORD_1
	v_pk_fma_f32 v[2:3], v[2:3], s[34:35], v[4:5] op_sel_hi:[1,0,1]
	s_nop 0
	v_cvt_pk_f16_f32 v9, v2, v3
	s_mov_b32 s35, s73
	global_store_dwordx4 v[18:19], v[6:9], off offset:256
	s_cmpk_lt_u32 s46, 0x100
	s_cbranch_scc1 .Lgy0
	s_barrier
.Lgy0:
	s_cbranch_vccz .LBB0_50
	s_waitcnt vmcnt(0)
	s_cmpk_gt_u32 s46, 0xff
	s_cbranch_scc1 .LBB0_65
	s_barrier

; template <class Epi, class AMap>
; __device__ __forceinline__ void gemm_phase(LAS unsigned char* lds, const AMap am, const int lda, const h16* Bt, const int ldb, const int M, const int N, const int K, const Epi& E) {
;     ...
;         if (!has_next) break;
; #pragma unroll
;         for (int a = 0; a < 2; ++a)
; #pragma unroll
;             for (int b = 0; b < 2; ++b)
; #pragma unroll
;                 for (int m = 0; m < 4; ++m)
; #pragma unroll
;                     for (int n = 0; n < 2; ++n) acc[a][b][m][n] = (f32x4){0.f, 0.f, 0.f, 0.f};
;         cur = nxt; cA = nA; cB = nB; ++ui;
;     }
.LBB0_88:
	s_or_b64 exec, exec, s[22:23]
	s_and_b64 vcc, exec, s[46:47]
	s_mov_b32 s23, s72
	s_mov_b32 s22, s68
	s_mov_b64 s[48:49], s[76:77]
	s_mov_b64 s[26:27], s[96:97]
	s_cmpk_lt_u32 s10, 0x100
	s_cbranch_scc1 .Lgy1
	s_barrier
.Lgy1:
	s_cbranch_vccnz .LBB0_105

; #define PG8_STAGE(bufoff, gbase, voff) do { _Pragma("unroll") for (int _i = 0; _i < 2; ++_i) \
;         __builtin_amdgcn_global_load_lds((const unsigned*)((const char*)(gbase) + (voff)[_i]), (LAS unsigned*)(lds + (bufoff) + ldsw + _i * 8192), 16, 0, 0); } while (0)
; #define PG8_LDA(dst, b, h) do { _Pragma("unroll") for (int m = 0; m < 4; ++m) _Pragma("unroll") for (int k = 0; k < 2; ++k) dst[m][k] = *(const LAS h16x8*)(lds + PG8_SA(b, h) + aoff + m * 2048 + k * 1024); } while (0)
; #define PG8_LDB(dst, b, h) do { _Pragma("unroll") for (int n = 0; n < 2; ++n) _Pragma("unroll") for (int k = 0; k < 2; ++k) dst[n][k] = *(const LAS h16x8*)(lds + PG8_SB(b, h) + boff + n * 2048 + k * 1024); } while (0)
; #define PG8_MMA(ai, bj, At, Bt_) do { __builtin_amdgcn_s_setprio(1); _Pragma("unroll") for (int m = 0; m < 4; ++m) _Pragma("unroll") for (int n = 0; n < 2; ++n) _Pragma("unroll") for (int k = 0; k < 2; ++k) \
;         acc[ai][bj][m][n] = __builtin_amdgcn_mfma_f32_16x16x32_f16(Bt_[n][k], At[m][k], acc[ai][bj][m][n], 0, 0, 0); __builtin_amdgcn_s_setprio(0); } while (0)
; #define PG8_WAIT_V(n) asm volatile("s_waitcnt vmcnt(" #n ")" ::: "memory")
; template <class Epi, class AMap>
; __device__ __forceinline__ void gemm_phase(LAS unsigned char* lds, const AMap am, const int lda, const h16* Bt, const int ldb, const int M, const int N, const int K, const Epi& E) {
;     ...
;         for (int t = 0; t < nt; t += 2) {
;             const bool last = (t == nt - 2);
;             const char* a1 = cA + (size_t)(t + 1) * kstep;
;             const char* a2 = last ? nA : cA + (size_t)(t + 2) * kstep; const char* b2 = last ? nB : cB + (size_t)(t + 2) * kstep;
;             const char* a3 = a2 + kstep; const char* b3 = b2 + kstep;
;             PG8_LDB(B0, 0, 0); PG8_SCHED; PG8_LDA(At, 0, 0); PG8_STAGE(PG8_SA(1, 1), a1 + hstepA, voffA);
;             PG8_WAIT_L(8); PG8_BAR; PG8_WAIT_L(0); PG8_MMA(0, 0, At, B0); PG8_BAR; PG8_SCHED;
;             PG8_LDB(B1, 0, 1); PG8_STAGE(PG8_SB(0, 0), b2, voffB);
;             PG8_BAR; PG8_WAIT_L(0); PG8_MMA(0, 1, At, B1); PG8_BAR;
;             PG8_LDA(At, 0, 1); PG8_STAGE(PG8_SA(0, 0), a2, voffA);
;             PG8_BAR; PG8_WAIT_L(0); PG8_MMA(1, 0, At, B0); PG8_BAR; PG8_SCHED;
;             PG8_STAGE(PG8_SB(0, 1), b2 + hstepB, voffB);
;             PG8_WAIT_V(6); PG8_BAR; PG8_MMA(1, 1, At, B1); PG8_BAR;
.LBB0_92:
	s_add_u32 s0, vcc_lo, 0xfff80080
	s_addc_u32 s1, vcc_hi, -1
	s_add_i32 s67, 0, 0x10000
	v_add_u32_e32 v226, s67, v169
	ds_read_b128 v[66:69], v226
	ds_read_b128 v[70:73], v226 offset:1024
	ds_read_b128 v[74:77], v226 offset:2048
	ds_read_b128 v[78:81], v226 offset:3072
	s_cmp_eq_u32 s60, 28
	s_cselect_b32 s27, s69, s1
	s_cselect_b32 s26, s29, s0
	s_cselect_b32 s49, s73, s66
	s_cselect_b32 s48, s20, s21
	v_lshl_add_u64 v[192:193], vcc, 0, v[172:173]
	s_add_i32 m0, s81, 0xc000
	ds_read_b128 v[90:93], v195
	ds_read_b128 v[94:97], v195 offset:1024
	ds_read_b128 v[98:101], v195 offset:2048
	ds_read_b128 v[102:105], v195 offset:3072
	ds_read_b128 v[176:179], v195 offset:4096
	ds_read_b128 v[180:183], v195 offset:5120
	ds_read_b128 v[184:187], v195 offset:6144
	ds_read_b128 v[188:191], v195 offset:7168
	global_load_lds_dwordx4 v[192:193], off
	v_lshl_add_u64 v[192:193], vcc, 0, v[174:175]
	s_add_i32 m0, s81, 0xe000
	s_nop 0
	global_load_lds_dwordx4 v[192:193], off
	s_waitcnt lgkmcnt(11)
	s_add_i32 s65, 0, 0x14000
	v_add_u32_e32 v192, s65, v169
	s_add_i32 s0, s67, s64
	ds_read_b128 v[196:199], v192
	ds_read_b128 v[200:203], v192 offset:1024
	ds_read_b128 v[204:207], v192 offset:2048
	ds_read_b128 v[220:223], v192 offset:3072
	s_waitcnt vmcnt(8) lgkmcnt(0)
	s_barrier
	v_mfma_f32_16x16x32_f16 v[158:161], v[66:69], v[90:93], v[158:161]
	v_mfma_f32_16x16x32_f16 v[154:157], v[74:77], v[90:93], v[154:157]
	v_mfma_f32_16x16x32_f16 v[142:145], v[66:69], v[98:101], v[142:145]
	v_mfma_f32_16x16x32_f16 v[134:137], v[74:77], v[98:101], v[134:137]
	v_mfma_f32_16x16x32_f16 v[126:129], v[66:69], v[176:179], v[126:129]
	v_mfma_f32_16x16x32_f16 v[118:121], v[74:77], v[176:179], v[118:121]
	v_mfma_f32_16x16x32_f16 v[110:113], v[66:69], v[184:187], v[110:113]
	v_mfma_f32_16x16x32_f16 v[106:109], v[74:77], v[184:187], v[106:109]
	v_mfma_f32_16x16x32_f16 v[158:161], v[70:73], v[94:97], v[158:161]
	v_mfma_f32_16x16x32_f16 v[154:157], v[78:81], v[94:97], v[154:157]
	v_mfma_f32_16x16x32_f16 v[142:145], v[70:73], v[102:105], v[142:145]
	v_mfma_f32_16x16x32_f16 v[134:137], v[78:81], v[102:105], v[134:137]
	v_mfma_f32_16x16x32_f16 v[126:129], v[70:73], v[180:183], v[126:129]
	v_mfma_f32_16x16x32_f16 v[118:121], v[78:81], v[180:183], v[118:121]
	v_mfma_f32_16x16x32_f16 v[110:113], v[70:73], v[188:191], v[110:113]
	v_mfma_f32_16x16x32_f16 v[106:109], v[78:81], v[188:191], v[106:109]
	v_mfma_f32_16x16x32_f16 v[150:153], v[196:199], v[90:93], v[150:153]
	v_mfma_f32_16x16x32_f16 v[146:149], v[204:207], v[90:93], v[146:149]
	v_mfma_f32_16x16x32_f16 v[150:153], v[200:203], v[94:97], v[150:153]
	v_mfma_f32_16x16x32_f16 v[146:149], v[220:223], v[94:97], v[146:149]
	v_mfma_f32_16x16x32_f16 v[138:141], v[196:199], v[98:101], v[138:141]
	v_mfma_f32_16x16x32_f16 v[130:133], v[204:207], v[98:101], v[130:133]
	v_mfma_f32_16x16x32_f16 v[114:117], v[204:207], v[176:179], v[114:117]
	v_mfma_f32_16x16x32_f16 v[86:89], v[196:199], v[184:187], v[86:89]
	v_mfma_f32_16x16x32_f16 v[82:85], v[204:207], v[184:187], v[82:85]
	v_mfma_f32_16x16x32_f16 v[138:141], v[200:203], v[102:105], v[138:141]
	v_mfma_f32_16x16x32_f16 v[130:133], v[220:223], v[102:105], v[130:133]
	v_mfma_f32_16x16x32_f16 v[122:125], v[196:199], v[176:179], v[122:125]
	v_mfma_f32_16x16x32_f16 v[114:117], v[220:223], v[180:183], v[114:117]
	v_mfma_f32_16x16x32_f16 v[86:89], v[200:203], v[188:191], v[86:89]
	v_mfma_f32_16x16x32_f16 v[82:85], v[220:223], v[188:191], v[82:85]
	v_mfma_f32_16x16x32_f16 v[122:125], v[200:203], v[180:183], v[122:125]
	s_barrier
	v_lshl_add_u64 v[192:193], s[48:49], 0, v[0:1]
	s_mov_b32 m0, s0
	v_lshl_add_u64 v[212:213], s[48:49], 0, v[162:163]
	global_load_lds_dwordx4 v[192:193], off
	s_add_i32 m0, s0, 0x2000
	s_nop 0
	global_load_lds_dwordx4 v[212:213], off
	s_mov_b32 m0, s81
	v_lshl_add_u64 v[214:215], s[26:27], 0, v[166:167]
	ds_read_b128 v[90:93], v195 offset:16384
	ds_read_b128 v[94:97], v195 offset:17408
	ds_read_b128 v[98:101], v195 offset:18432
	ds_read_b128 v[102:105], v195 offset:19456
	ds_read_b128 v[176:179], v195 offset:20480
	ds_read_b128 v[180:183], v195 offset:21504
	ds_read_b128 v[184:187], v195 offset:22528
	ds_read_b128 v[188:191], v195 offset:23552
	global_load_lds_dwordx4 v[214:215], off
	v_lshl_add_u64 v[216:217], s[26:27], 0, v[164:165]
	s_mov_b32 m0, s82
	s_nop 0
	global_load_lds_dwordx4 v[216:217], off
	s_add_u32 s0, s48, 0x80000
	s_addc_u32 s1, s49, 0
	s_add_i32 s65, s65, s64
	v_lshl_add_u64 v[224:225], s[0:1], 0, v[0:1]
	s_mov_b32 m0, s65
	s_nop 0
	global_load_lds_dwordx4 v[224:225], off
	v_lshl_add_u64 v[224:225], s[0:1], 0, v[162:163]
	s_add_i32 m0, s65, 0x2000
	s_nop 0
	global_load_lds_dwordx4 v[224:225], off
	s_waitcnt vmcnt(8) lgkmcnt(0)
	s_barrier
; #define PG8_STAGE(bufoff, gbase, voff) do { _Pragma("unroll") for (int _i = 0; _i < 2; ++_i) \
;         __builtin_amdgcn_global_load_lds((const unsigned*)((const char*)(gbase) + (voff)[_i]), (LAS unsigned*)(lds + (bufoff) + ldsw + _i * 8192), 16, 0, 0); } while (0)
; #define PG8_LDA(dst, b, h) do { _Pragma("unroll") for (int m = 0; m < 4; ++m) _Pragma("unroll") for (int k = 0; k < 2; ++k) dst[m][k] = *(const LAS h16x8*)(lds + PG8_SA(b, h) + aoff + m * 2048 + k * 1024); } while (0)
; #define PG8_LDB(dst, b, h) do { _Pragma("unroll") for (int n = 0; n < 2; ++n) _Pragma("unroll") for (int k = 0; k < 2; ++k) dst[n][k] = *(const LAS h16x8*)(lds + PG8_SB(b, h) + boff + n * 2048 + k * 1024); } while (0)
; #define PG8_MMA(ai, bj, At, Bt_) do { __builtin_amdgcn_s_setprio(1); _Pragma("unroll") for (int m = 0; m < 4; ++m) _Pragma("unroll") for (int n = 0; n < 2; ++n) _Pragma("unroll") for (int k = 0; k < 2; ++k) \
;         acc[ai][bj][m][n] = __builtin_amdgcn_mfma_f32_16x16x32_f16(Bt_[n][k], At[m][k], acc[ai][bj][m][n], 0, 0, 0); __builtin_amdgcn_s_setprio(0); } while (0)
; #define PG8_WAIT_V(n) asm volatile("s_waitcnt vmcnt(" #n ")" ::: "memory")
; #define PG8_WAIT_L(n) asm volatile("s_waitcnt lgkmcnt(" #n ")" ::: "memory")
; #define PG8_BAR __builtin_amdgcn_s_barrier()
; #define PG8_SCHED __builtin_amdgcn_sched_barrier(0)
; template <class Epi, class AMap>
; __device__ __forceinline__ void gemm_phase(LAS unsigned char* lds, const AMap am, const int lda, const h16* Bt, const int ldb, const int M, const int N, const int K, const Epi& E) {
;     ...
;             PG8_BAR; PG8_WAIT_L(0); PG8_MMA(0, 1, At, B1); PG8_BAR;
;             PG8_LDA(At, 0, 1); PG8_STAGE(PG8_SA(0, 0), a2, voffA);
;             PG8_BAR; PG8_WAIT_L(0); PG8_MMA(1, 0, At, B0); PG8_BAR; PG8_SCHED;
;             PG8_STAGE(PG8_SB(0, 1), b2 + hstepB, voffB);
;             PG8_WAIT_V(6); PG8_BAR; PG8_MMA(1, 1, At, B1); PG8_BAR;
;             PG8_LDB(B0, 1, 0); PG8_SCHED; PG8_LDA(At, 1, 0); PG8_STAGE(PG8_SA(0, 1), a2 + hstepA, voffA);
;             PG8_WAIT_L(8); PG8_BAR; PG8_WAIT_L(0); PG8_MMA(0, 0, At, B0); PG8_BAR; PG8_SCHED;
;             PG8_LDB(B1, 1, 1); PG8_STAGE(PG8_SB(1, 0), b3, voffB);
;             PG8_BAR; PG8_WAIT_L(0); PG8_MMA(0, 1, At, B1); PG8_BAR;
	v_mfma_f32_16x16x32_f16 v[62:65], v[66:69], v[90:93], v[62:65]
	v_mfma_f32_16x16x32_f16 v[58:61], v[74:77], v[90:93], v[58:61]
	v_mfma_f32_16x16x32_f16 v[46:49], v[66:69], v[98:101], v[46:49]
	v_mfma_f32_16x16x32_f16 v[38:41], v[74:77], v[98:101], v[38:41]
	v_mfma_f32_16x16x32_f16 v[30:33], v[66:69], v[176:179], v[30:33]
	v_mfma_f32_16x16x32_f16 v[22:25], v[74:77], v[176:179], v[22:25]
	v_mfma_f32_16x16x32_f16 v[14:17], v[66:69], v[184:187], v[14:17]
	v_mfma_f32_16x16x32_f16 v[10:13], v[74:77], v[184:187], v[10:13]
	v_mfma_f32_16x16x32_f16 v[62:65], v[70:73], v[94:97], v[62:65]
	v_mfma_f32_16x16x32_f16 v[58:61], v[78:81], v[94:97], v[58:61]
	v_mfma_f32_16x16x32_f16 v[46:49], v[70:73], v[102:105], v[46:49]
	v_mfma_f32_16x16x32_f16 v[38:41], v[78:81], v[102:105], v[38:41]
	v_mfma_f32_16x16x32_f16 v[30:33], v[70:73], v[180:183], v[30:33]
	v_mfma_f32_16x16x32_f16 v[22:25], v[78:81], v[180:183], v[22:25]
	v_mfma_f32_16x16x32_f16 v[14:17], v[70:73], v[188:191], v[14:17]
	v_mfma_f32_16x16x32_f16 v[10:13], v[78:81], v[188:191], v[10:13]
	v_mfma_f32_16x16x32_f16 v[54:57], v[196:199], v[90:93], v[54:57]
	v_mfma_f32_16x16x32_f16 v[50:53], v[204:207], v[90:93], v[50:53]
	v_mfma_f32_16x16x32_f16 v[42:45], v[196:199], v[98:101], v[42:45]
	v_mfma_f32_16x16x32_f16 v[34:37], v[204:207], v[98:101], v[34:37]
	v_mfma_f32_16x16x32_f16 v[26:29], v[196:199], v[176:179], v[26:29]
	v_mfma_f32_16x16x32_f16 v[18:21], v[204:207], v[176:179], v[18:21]
	v_mfma_f32_16x16x32_f16 v[6:9], v[196:199], v[184:187], v[6:9]
	v_mfma_f32_16x16x32_f16 v[2:5], v[204:207], v[184:187], v[2:5]
	v_mfma_f32_16x16x32_f16 v[54:57], v[200:203], v[94:97], v[54:57]
	v_mfma_f32_16x16x32_f16 v[50:53], v[220:223], v[94:97], v[50:53]
	v_mfma_f32_16x16x32_f16 v[42:45], v[200:203], v[102:105], v[42:45]
	v_mfma_f32_16x16x32_f16 v[34:37], v[220:223], v[102:105], v[34:37]
	v_mfma_f32_16x16x32_f16 v[26:29], v[200:203], v[180:183], v[26:29]
	v_mfma_f32_16x16x32_f16 v[18:21], v[220:223], v[180:183], v[18:21]
	v_mfma_f32_16x16x32_f16 v[6:9], v[200:203], v[188:191], v[6:9]
	v_mfma_f32_16x16x32_f16 v[2:5], v[220:223], v[188:191], v[2:5]
	s_barrier
	s_add_i32 s65, 0, 0x18000
	v_add_u32_e32 v226, s65, v169
	ds_read_b128 v[66:69], v226
	ds_read_b128 v[70:73], v226 offset:1024
	ds_read_b128 v[74:77], v226 offset:2048
	ds_read_b128 v[78:81], v226 offset:3072
	s_add_u32 s0, s26, 0x80000
	s_addc_u32 s1, s27, 0
	s_mov_b32 m0, s83
	v_lshl_add_u64 v[224:225], s[0:1], 0, v[166:167]
	ds_read_b128 v[90:93], v195 offset:32768
	ds_read_b128 v[94:97], v195 offset:33792
	ds_read_b128 v[98:101], v195 offset:34816
	ds_read_b128 v[102:105], v195 offset:35840
	ds_read_b128 v[176:179], v195 offset:36864
	ds_read_b128 v[180:183], v195 offset:37888
	ds_read_b128 v[184:187], v195 offset:38912
	ds_read_b128 v[188:191], v195 offset:39936
	global_load_lds_dwordx4 v[224:225], off
	v_lshl_add_u64 v[224:225], s[0:1], 0, v[164:165]
	s_mov_b32 m0, s50
	s_nop 0
	global_load_lds_dwordx4 v[224:225], off
	s_waitcnt lgkmcnt(11)
	s_add_i32 s26, 0, 0x1c000
	v_add_u32_e32 v226, s26, v169
	s_add_i32 s0, s65, s64
	ds_read_b128 v[196:199], v226
	ds_read_b128 v[200:203], v226 offset:1024
	ds_read_b128 v[204:207], v226 offset:2048
	ds_read_b128 v[220:223], v226 offset:3072
	s_waitcnt vmcnt(8) lgkmcnt(0)
	s_barrier
	v_mfma_f32_16x16x32_f16 v[158:161], v[66:69], v[90:93], v[158:161]
	v_mfma_f32_16x16x32_f16 v[158:161], v[70:73], v[94:97], v[158:161]
	v_mfma_f32_16x16x32_f16 v[154:157], v[74:77], v[90:93], v[154:157]
	v_mfma_f32_16x16x32_f16 v[154:157], v[78:81], v[94:97], v[154:157]
	v_mfma_f32_16x16x32_f16 v[142:145], v[66:69], v[98:101], v[142:145]
	v_mfma_f32_16x16x32_f16 v[134:137], v[74:77], v[98:101], v[134:137]
	v_mfma_f32_16x16x32_f16 v[126:129], v[66:69], v[176:179], v[126:129]
	v_mfma_f32_16x16x32_f16 v[118:121], v[74:77], v[176:179], v[118:121]
	v_mfma_f32_16x16x32_f16 v[110:113], v[66:69], v[184:187], v[110:113]
	v_mfma_f32_16x16x32_f16 v[106:109], v[74:77], v[184:187], v[106:109]
	v_mfma_f32_16x16x32_f16 v[142:145], v[70:73], v[102:105], v[142:145]
	v_mfma_f32_16x16x32_f16 v[134:137], v[78:81], v[102:105], v[134:137]
	v_mfma_f32_16x16x32_f16 v[126:129], v[70:73], v[180:183], v[126:129]
	v_mfma_f32_16x16x32_f16 v[118:121], v[78:81], v[180:183], v[118:121]
	v_mfma_f32_16x16x32_f16 v[110:113], v[70:73], v[188:191], v[110:113]
	v_mfma_f32_16x16x32_f16 v[106:109], v[78:81], v[188:191], v[106:109]
	v_mfma_f32_16x16x32_f16 v[146:149], v[204:207], v[90:93], v[146:149]
	v_mfma_f32_16x16x32_f16 v[150:153], v[196:199], v[90:93], v[150:153]
	v_mfma_f32_16x16x32_f16 v[146:149], v[220:223], v[94:97], v[146:149]
	v_mfma_f32_16x16x32_f16 v[138:141], v[196:199], v[98:101], v[138:141]
	v_mfma_f32_16x16x32_f16 v[150:153], v[200:203], v[94:97], v[150:153]
	v_mfma_f32_16x16x32_f16 v[138:141], v[200:203], v[102:105], v[138:141]
	v_mfma_f32_16x16x32_f16 v[130:133], v[204:207], v[98:101], v[130:133]
	v_mfma_f32_16x16x32_f16 v[130:133], v[220:223], v[102:105], v[130:133]
	v_mfma_f32_16x16x32_f16 v[122:125], v[196:199], v[176:179], v[122:125]
	v_mfma_f32_16x16x32_f16 v[122:125], v[200:203], v[180:183], v[122:125]
	v_mfma_f32_16x16x32_f16 v[114:117], v[204:207], v[176:179], v[114:117]
	v_mfma_f32_16x16x32_f16 v[86:89], v[196:199], v[184:187], v[86:89]
	v_mfma_f32_16x16x32_f16 v[82:85], v[204:207], v[184:187], v[82:85]
	v_mfma_f32_16x16x32_f16 v[114:117], v[220:223], v[180:183], v[114:117]
	v_mfma_f32_16x16x32_f16 v[86:89], v[200:203], v[188:191], v[86:89]
	v_mfma_f32_16x16x32_f16 v[82:85], v[220:223], v[188:191], v[82:85]
	s_barrier
; #define PG8_STAGE(bufoff, gbase, voff) do { _Pragma("unroll") for (int _i = 0; _i < 2; ++_i) \
;         __builtin_amdgcn_global_load_lds((const unsigned*)((const char*)(gbase) + (voff)[_i]), (LAS unsigned*)(lds + (bufoff) + ldsw + _i * 8192), 16, 0, 0); } while (0)
; #define PG8_LDA(dst, b, h) do { _Pragma("unroll") for (int m = 0; m < 4; ++m) _Pragma("unroll") for (int k = 0; k < 2; ++k) dst[m][k] = *(const LAS h16x8*)(lds + PG8_SA(b, h) + aoff + m * 2048 + k * 1024); } while (0)
; #define PG8_LDB(dst, b, h) do { _Pragma("unroll") for (int n = 0; n < 2; ++n) _Pragma("unroll") for (int k = 0; k < 2; ++k) dst[n][k] = *(const LAS h16x8*)(lds + PG8_SB(b, h) + boff + n * 2048 + k * 1024); } while (0)
; #define PG8_MMA(ai, bj, At, Bt_) do { __builtin_amdgcn_s_setprio(1); _Pragma("unroll") for (int m = 0; m < 4; ++m) _Pragma("unroll") for (int n = 0; n < 2; ++n) _Pragma("unroll") for (int k = 0; k < 2; ++k) \
;         acc[ai][bj][m][n] = __builtin_amdgcn_mfma_f32_16x16x32_f16(Bt_[n][k], At[m][k], acc[ai][bj][m][n], 0, 0, 0); __builtin_amdgcn_s_setprio(0); } while (0)
; #define PG8_WAIT_V(n) asm volatile("s_waitcnt vmcnt(" #n ")" ::: "memory")
; #define PG8_WAIT_L(n) asm volatile("s_waitcnt lgkmcnt(" #n ")" ::: "memory")
; #define PG8_BAR __builtin_amdgcn_s_barrier()
; #define PG8_SCHED __builtin_amdgcn_sched_barrier(0)
; template <class Epi, class AMap>
; __device__ __forceinline__ void gemm_phase(LAS unsigned char* lds, const AMap am, const int lda, const h16* Bt, const int ldb, const int M, const int N, const int K, const Epi& E) {
;     ...
;             PG8_WAIT_V(6); PG8_BAR; PG8_MMA(1, 1, At, B1); PG8_BAR;
;             PG8_LDB(B0, 1, 0); PG8_SCHED; PG8_LDA(At, 1, 0); PG8_STAGE(PG8_SA(0, 1), a2 + hstepA, voffA);
;             PG8_WAIT_L(8); PG8_BAR; PG8_WAIT_L(0); PG8_MMA(0, 0, At, B0); PG8_BAR; PG8_SCHED;
;             PG8_LDB(B1, 1, 1); PG8_STAGE(PG8_SB(1, 0), b3, voffB);
;             PG8_BAR; PG8_WAIT_L(0); PG8_MMA(0, 1, At, B1); PG8_BAR;
;             PG8_LDA(At, 1, 1); PG8_STAGE(PG8_SA(1, 0), a3, voffA);
;             PG8_BAR; PG8_WAIT_L(0); PG8_MMA(1, 0, At, B0); PG8_BAR; PG8_SCHED;
;             PG8_STAGE(PG8_SB(1, 1), b3 + hstepB, voffB);
;             PG8_WAIT_V(6); PG8_BAR; PG8_MMA(1, 1, At, B1); PG8_BAR;
;         }
	v_lshl_add_u64 v[224:225], v[192:193], 0, s[92:93]
	s_mov_b32 m0, s0
	s_nop 0
	global_load_lds_dwordx4 v[224:225], off
	v_lshl_add_u64 v[224:225], v[212:213], 0, s[92:93]
	s_add_i32 m0, s0, 0x2000
	s_nop 0
	global_load_lds_dwordx4 v[224:225], off
	s_mov_b32 m0, s89
	v_lshl_add_u64 v[192:193], v[214:215], 0, s[92:93]
	ds_read_b128 v[90:93], v195 offset:49152
	ds_read_b128 v[94:97], v195 offset:50176
	ds_read_b128 v[98:101], v195 offset:51200
	ds_read_b128 v[102:105], v195 offset:52224
	ds_read_b128 v[176:179], v195 offset:53248
	ds_read_b128 v[180:183], v195 offset:54272
	ds_read_b128 v[184:187], v195 offset:55296
	ds_read_b128 v[188:191], v195 offset:56320
	global_load_lds_dwordx4 v[192:193], off
	v_lshl_add_u64 v[192:193], v[216:217], 0, s[92:93]
	s_mov_b32 m0, s35
	s_nop 0
	global_load_lds_dwordx4 v[192:193], off
	s_add_u32 s0, s48, 0x80080
	s_addc_u32 s1, s49, 0
	s_add_i32 s26, s26, s64
	v_lshl_add_u64 v[224:225], s[0:1], 0, v[0:1]
	s_mov_b32 m0, s26
	s_nop 0
	global_load_lds_dwordx4 v[224:225], off
	v_lshl_add_u64 v[224:225], s[0:1], 0, v[162:163]
	s_add_i32 m0, s26, 0x2000
	s_nop 0
	global_load_lds_dwordx4 v[224:225], off
	s_waitcnt vmcnt(8) lgkmcnt(0)
	s_barrier
	v_mfma_f32_16x16x32_f16 v[62:65], v[66:69], v[90:93], v[62:65]
	v_mfma_f32_16x16x32_f16 v[58:61], v[74:77], v[90:93], v[58:61]
	v_mfma_f32_16x16x32_f16 v[46:49], v[66:69], v[98:101], v[46:49]
	v_mfma_f32_16x16x32_f16 v[38:41], v[74:77], v[98:101], v[38:41]
	v_mfma_f32_16x16x32_f16 v[30:33], v[66:69], v[176:179], v[30:33]
	v_mfma_f32_16x16x32_f16 v[22:25], v[74:77], v[176:179], v[22:25]
	v_mfma_f32_16x16x32_f16 v[14:17], v[66:69], v[184:187], v[14:17]
	v_mfma_f32_16x16x32_f16 v[10:13], v[74:77], v[184:187], v[10:13]
	v_mfma_f32_16x16x32_f16 v[62:65], v[70:73], v[94:97], v[62:65]
	v_mfma_f32_16x16x32_f16 v[58:61], v[78:81], v[94:97], v[58:61]
	v_mfma_f32_16x16x32_f16 v[46:49], v[70:73], v[102:105], v[46:49]
	v_mfma_f32_16x16x32_f16 v[38:41], v[78:81], v[102:105], v[38:41]
	v_mfma_f32_16x16x32_f16 v[30:33], v[70:73], v[180:183], v[30:33]
	v_mfma_f32_16x16x32_f16 v[22:25], v[78:81], v[180:183], v[22:25]
	v_mfma_f32_16x16x32_f16 v[14:17], v[70:73], v[188:191], v[14:17]
	v_mfma_f32_16x16x32_f16 v[10:13], v[78:81], v[188:191], v[10:13]
	v_mfma_f32_16x16x32_f16 v[54:57], v[196:199], v[90:93], v[54:57]
	v_mfma_f32_16x16x32_f16 v[50:53], v[204:207], v[90:93], v[50:53]
	v_mfma_f32_16x16x32_f16 v[42:45], v[196:199], v[98:101], v[42:45]
	v_mfma_f32_16x16x32_f16 v[34:37], v[204:207], v[98:101], v[34:37]
	v_mfma_f32_16x16x32_f16 v[26:29], v[196:199], v[176:179], v[26:29]
	v_mfma_f32_16x16x32_f16 v[18:21], v[204:207], v[176:179], v[18:21]
	v_mfma_f32_16x16x32_f16 v[6:9], v[196:199], v[184:187], v[6:9]
	v_mfma_f32_16x16x32_f16 v[2:5], v[204:207], v[184:187], v[2:5]
	v_mfma_f32_16x16x32_f16 v[54:57], v[200:203], v[94:97], v[54:57]
	v_mfma_f32_16x16x32_f16 v[50:53], v[220:223], v[94:97], v[50:53]
	v_mfma_f32_16x16x32_f16 v[42:45], v[200:203], v[102:105], v[42:45]
	v_mfma_f32_16x16x32_f16 v[34:37], v[220:223], v[102:105], v[34:37]
	v_mfma_f32_16x16x32_f16 v[26:29], v[200:203], v[180:183], v[26:29]
	v_mfma_f32_16x16x32_f16 v[18:21], v[220:223], v[180:183], v[18:21]
	v_mfma_f32_16x16x32_f16 v[6:9], v[200:203], v[188:191], v[6:9]
	v_mfma_f32_16x16x32_f16 v[2:5], v[220:223], v[188:191], v[2:5]
	s_add_i32 s60, s60, 2
	s_add_u32 vcc_lo, vcc_lo, 0x100
	s_addc_u32 vcc_hi, vcc_hi, 0
	s_add_u32 s21, s21, 0x100
	s_addc_u32 s66, s66, 0
	s_cmp_gt_u32 s60, 29
	s_barrier
	s_cbranch_scc0 .LBB0_92
	s_cmpk_gt_u32 s10, 0xff
	s_cbranch_scc1 .Lgx1
	s_barrier
; template <int CTRL> __device__ __forceinline__ float dpp_f(float x) { return __int_as_float(__builtin_amdgcn_update_dpp(0, __float_as_int(x), CTRL, 0xF, 0xF, true)); }
;     __device__ __forceinline__ void operator()(const f32x4 (&acc)[2][2][4][2], const Unit& u, int wr, int wc, int fr, int fq) const {
;         const int row0 = u.pm * 256 + wr * 64 + fr, f0 = u.pn * 128 + wc * 32 + 8 * fq;
;         f32x4 w0[2], w1[2], w2[2], bb[2];
; #pragma unroll
;         for (int n = 0; n < 2; ++n) { w0[n] = *(const f32x4*)(cw + f0 + 4 * n); w1[n] = *(const f32x4*)(cw + FF + f0 + 4 * n); w2[n] = *(const f32x4*)(cw + 2 * FF + f0 + 4 * n); bb[n] = *(const f32x4*)(cb + f0 + 4 * n); }
; #pragma unroll
;         for (int ai = 0; ai < 2; ++ai) {
;             f32x4 p1[2], p2[2];
; #pragma unroll
;             for (int n = 0; n < 2; ++n) { p1[n] = (f32x4){0.f, 0.f, 0.f, 0.f}; p2[n] = p1[n]; }
; #pragma unroll
;             for (int m = 0; m < 4; ++m) {
;                 const int row = row0 + ai * 128 + m * 16;
;                 f32x4 r1[2], r2[2], o[2];
; #pragma unroll
;                 for (int n = 0; n < 2; ++n)
; #pragma unroll
;                     for (int e = 0; e < 4; ++e) {
;                         const float g = acc[ai][1][m][n][e];
;                         r1[n][e] = dpp_f<0x121>(g); r2[n][e] = dpp_f<0x122>(g);
;                         const float g1 = fr >= 1 ? r1[n][e] : p1[n][e], g2 = fr >= 2 ? r2[n][e] : p2[n][e];
;                         const float gc = bb[n][e] + g2 * w0[n][e] + g1 * w1[n][e] + g * w2[n][e];
;                         o[n][e] = gelu_mul(acc[ai][0][m][n][e], gc);
;                     }
;                 if (m > 0 || fr >= 2) *(u32x4*)(ACT + (size_t)row * FF + f0) = pack8(o[0], o[1]);
.Lgx1:
	v_lshl_or_b32 v176, s23, 7, v194
	v_ashrrev_i32_e32 v177, 31, v176
	v_lshlrev_b64 v[66:67], 2, v[176:177]
	v_lshl_add_u64 v[70:71], s[74:75], 0, v[66:67]
	v_lshl_add_u64 v[74:75], s[8:9], 0, v[66:67]
	v_lshl_add_u64 v[78:79], s[70:71], 0, v[66:67]
	v_lshl_add_u64 v[102:103], s[78:79], 0, v[66:67]
	global_load_dwordx4 v[66:69], v[70:71], off offset:16
	global_load_dwordx4 v[90:93], v[70:71], off
	s_nop 0
	global_load_dwordx4 v[70:73], v[74:75], off offset:16
	global_load_dwordx4 v[94:97], v[74:75], off
	s_nop 0
	global_load_dwordx4 v[74:77], v[78:79], off offset:16
	global_load_dwordx4 v[98:101], v[78:79], off
	s_nop 0
	global_load_dwordx4 v[78:81], v[102:103], off offset:16
	s_nop 0
	global_load_dwordx4 v[102:105], v[102:103], off
	s_lshl_b32 s20, s22, 8
	s_add_i32 s20, s20, s51
	v_or_b32_e32 v196, s20, v168
	v_mov_b32_dpp v192, v150 row_ror:1 row_mask:0xf bank_mask:0xf bound_ctrl:1
	v_mov_b32_dpp v190, v150 row_ror:2 row_mask:0xf bank_mask:0xf bound_ctrl:1
	v_mov_b32_dpp v193, v151 row_ror:1 row_mask:0xf bank_mask:0xf bound_ctrl:1
	v_mov_b32_dpp v191, v151 row_ror:2 row_mask:0xf bank_mask:0xf bound_ctrl:1
	v_mov_b32_dpp v188, v152 row_ror:1 row_mask:0xf bank_mask:0xf bound_ctrl:1
	v_mov_b32_dpp v186, v152 row_ror:2 row_mask:0xf bank_mask:0xf bound_ctrl:1
	v_mov_b32_dpp v189, v153 row_ror:1 row_mask:0xf bank_mask:0xf bound_ctrl:1
	v_mov_b32_dpp v187, v153 row_ror:2 row_mask:0xf bank_mask:0xf bound_ctrl:1
	v_mov_b32_dpp v184, v146 row_ror:1 row_mask:0xf bank_mask:0xf bound_ctrl:1
	v_mov_b32_dpp v182, v146 row_ror:2 row_mask:0xf bank_mask:0xf bound_ctrl:1
	v_mov_b32_dpp v185, v147 row_ror:1 row_mask:0xf bank_mask:0xf bound_ctrl:1
	v_mov_b32_dpp v183, v147 row_ror:2 row_mask:0xf bank_mask:0xf bound_ctrl:1
	v_mov_b32_dpp v180, v148 row_ror:1 row_mask:0xf bank_mask:0xf bound_ctrl:1
	v_mov_b32_dpp v178, v148 row_ror:2 row_mask:0xf bank_mask:0xf bound_ctrl:1
	v_mov_b32_dpp v181, v149 row_ror:1 row_mask:0xf bank_mask:0xf bound_ctrl:1
	v_mov_b32_dpp v179, v149 row_ror:2 row_mask:0xf bank_mask:0xf bound_ctrl:1
	s_and_saveexec_b64 s[22:23], s[40:41]
	s_cbranch_execz .LBB0_95
	s_waitcnt vmcnt(0)
	v_pk_fma_f32 v[198:199], v[90:91], v[190:191], v[102:103]
	v_readlane_b32 s0, v254, 58
	v_pk_fma_f32 v[198:199], v[94:95], v[192:193], v[198:199]
	v_readlane_b32 s1, v254, 59
	v_pk_fma_f32 v[198:199], v[150:151], v[98:99], v[198:199]
	s_nop 0
	v_pk_mul_f32 v[200:201], v[198:199], v[198:199]
	v_pk_mul_f32 v[202:203], v[158:159], v[198:199]
	v_fmamk_f32 v197, v201, 0x3dd2d3e7, v241
	v_mul_f32_e64 v197, v199, -v197
	v_exp_f32_e32 v197, v197
	s_nop 0
	v_add_f32_e32 v197, 1.0, v197
	v_rcp_f32_e32 v201, v197
	v_fmamk_f32 v197, v200, 0x3dd2d3e7, v241
	v_mul_f32_e64 v197, v198, -v197
	v_exp_f32_e32 v197, v197
	s_nop 0
	v_add_f32_e32 v197, 1.0, v197
	v_rcp_f32_e32 v200, v197
	s_nop 0
	v_pk_mul_f32 v[198:199], v[202:203], v[200:201]
	v_pk_fma_f32 v[200:201], v[92:93], v[186:187], v[104:105]
	v_cvt_pk_f16_f32 v198, v198, v199
	v_pk_fma_f32 v[200:201], v[96:97], v[188:189], v[200:201]
	s_nop 0
	v_pk_fma_f32 v[200:201], v[152:153], v[100:101], v[200:201]
	s_nop 0
	v_pk_mul_f32 v[202:203], v[200:201], v[200:201]
	v_pk_mul_f32 v[204:205], v[160:161], v[200:201]
	v_fmamk_f32 v197, v203, 0x3dd2d3e7, v241
	v_mul_f32_e64 v197, v201, -v197
	v_exp_f32_e32 v197, v197
	s_nop 0
	v_add_f32_e32 v197, 1.0, v197
	v_rcp_f32_e32 v203, v197
	v_fmamk_f32 v197, v202, 0x3dd2d3e7, v241
	v_mul_f32_e64 v197, v200, -v197
	v_exp_f32_e32 v197, v197
	s_nop 0
	v_add_f32_e32 v197, 1.0, v197
	v_rcp_f32_e32 v202, v197
	s_nop 0
	v_pk_mul_f32 v[200:201], v[204:205], v[202:203]
	s_nop 0
	v_cvt_pk_f16_f32 v199, v200, v201
	v_pk_fma_f32 v[200:201], v[66:67], v[182:183], v[78:79]
	s_nop 0
	v_pk_fma_f32 v[200:201], v[70:71], v[184:185], v[200:201]
	s_nop 0
	v_pk_fma_f32 v[200:201], v[146:147], v[74:75], v[200:201]
	s_nop 0
	v_pk_mul_f32 v[202:203], v[200:201], v[200:201]
	v_pk_mul_f32 v[204:205], v[154:155], v[200:201]
	v_fmamk_f32 v197, v203, 0x3dd2d3e7, v241
	v_mul_f32_e64 v197, v201, -v197
	v_exp_f32_e32 v197, v197
	s_nop 0
	v_add_f32_e32 v197, 1.0, v197
	v_rcp_f32_e32 v203, v197
	v_fmamk_f32 v197, v202, 0x3dd2d3e7, v241
	v_mul_f32_e64 v197, v200, -v197
	v_exp_f32_e32 v197, v197
	s_nop 0
	v_add_f32_e32 v197, 1.0, v197
	v_rcp_f32_e32 v202, v197
	s_nop 0
	v_pk_mul_f32 v[200:201], v[204:205], v[202:203]
	v_pk_fma_f32 v[202:203], v[68:69], v[178:179], v[80:81]
	v_cvt_pk_f16_f32 v200, v200, v201
	v_pk_fma_f32 v[202:203], v[72:73], v[180:181], v[202:203]
	s_nop 0
	v_pk_fma_f32 v[202:203], v[148:149], v[76:77], v[202:203]
	s_nop 0
	v_pk_mul_f32 v[204:205], v[202:203], v[202:203]
	v_pk_mul_f32 v[206:207], v[156:157], v[202:203]
	v_fmamk_f32 v197, v204, 0x3dd2d3e7, v241
	v_mul_f32_e64 v197, v202, -v197
	v_exp_f32_e32 v197, v197
	s_nop 0
	v_add_f32_e32 v197, 1.0, v197
	v_rcp_f32_e32 v204, v197
	v_fmamk_f32 v197, v205, 0x3dd2d3e7, v241
	v_mul_f32_e64 v197, v203, -v197
	v_exp_f32_e32 v197, v197
	s_nop 0
	v_add_f32_e32 v197, 1.0, v197
	v_rcp_f32_e32 v205, v197
	s_nop 0
	v_pk_mul_f32 v[202:203], v[206:207], v[204:205]
	s_nop 0
	v_cvt_pk_f16_f32 v201, v202, v203
	v_mov_b64_e32 v[202:203], s[0:1]
	v_mad_i64_i32 v[202:203], s[26:27], v196, s13, v[202:203]
	v_lshl_add_u64 v[202:203], v[176:177], 1, v[202:203]
	global_store_dwordx4 v[202:203], v[198:201], off

; #define PG8_STAGE(bufoff, gbase, voff) do { _Pragma("unroll") for (int _i = 0; _i < 2; ++_i) \
;         __builtin_amdgcn_global_load_lds((const unsigned*)((const char*)(gbase) + (voff)[_i]), (LAS unsigned*)(lds + (bufoff) + ldsw + _i * 8192), 16, 0, 0); } while (0)
; #define PG8_LDA(dst, b, h) do { _Pragma("unroll") for (int m = 0; m < 4; ++m) _Pragma("unroll") for (int k = 0; k < 2; ++k) dst[m][k] = *(const LAS h16x8*)(lds + PG8_SA(b, h) + aoff + m * 2048 + k * 1024); } while (0)
; #define PG8_LDB(dst, b, h) do { _Pragma("unroll") for (int n = 0; n < 2; ++n) _Pragma("unroll") for (int k = 0; k < 2; ++k) dst[n][k] = *(const LAS h16x8*)(lds + PG8_SB(b, h) + boff + n * 2048 + k * 1024); } while (0)
; #define PG8_MMA(ai, bj, At, Bt_) do { __builtin_amdgcn_s_setprio(1); _Pragma("unroll") for (int m = 0; m < 4; ++m) _Pragma("unroll") for (int n = 0; n < 2; ++n) _Pragma("unroll") for (int k = 0; k < 2; ++k) \
;         acc[ai][bj][m][n] = __builtin_amdgcn_mfma_f32_16x16x32_f16(Bt_[n][k], At[m][k], acc[ai][bj][m][n], 0, 0, 0); __builtin_amdgcn_s_setprio(0); } while (0)
; #define PG8_WAIT_V(n) asm volatile("s_waitcnt vmcnt(" #n ")" ::: "memory")
; template <class Epi, class AMap>
; __device__ __forceinline__ void gemm_phase(LAS unsigned char* lds, const AMap am, const int lda, const h16* Bt, const int ldb, const int M, const int N, const int K, const Epi& E) {
;     ...
;         for (int t = 0; t < nt; t += 2) {
;             const bool last = (t == nt - 2);
;             const char* a1 = cA + (size_t)(t + 1) * kstep;
;             const char* a2 = last ? nA : cA + (size_t)(t + 2) * kstep; const char* b2 = last ? nB : cB + (size_t)(t + 2) * kstep;
;             const char* a3 = a2 + kstep; const char* b3 = b2 + kstep;
;             PG8_LDB(B0, 0, 0); PG8_SCHED; PG8_LDA(At, 0, 0); PG8_STAGE(PG8_SA(1, 1), a1 + hstepA, voffA);
;             PG8_WAIT_L(8); PG8_BAR; PG8_WAIT_L(0); PG8_MMA(0, 0, At, B0); PG8_BAR; PG8_SCHED;
;             PG8_LDB(B1, 0, 1); PG8_STAGE(PG8_SB(0, 0), b2, voffB);
;             PG8_BAR; PG8_WAIT_L(0); PG8_MMA(0, 1, At, B1); PG8_BAR;
;             PG8_LDA(At, 0, 1); PG8_STAGE(PG8_SA(0, 0), a2, voffA);
;             PG8_BAR; PG8_WAIT_L(0); PG8_MMA(1, 0, At, B0); PG8_BAR; PG8_SCHED;
;             PG8_STAGE(PG8_SB(0, 1), b2 + hstepB, voffB);
;             PG8_WAIT_V(6); PG8_BAR; PG8_MMA(1, 1, At, B1); PG8_BAR;
.LBB0_147:
	s_add_u32 s46, s26, 0xfff80080
	s_addc_u32 s47, s27, -1
	s_add_i32 s60, 0, 0x10000
	v_add_u32_e32 v144, s60, v147
	ds_read_b128 v[140:143], v144
	ds_read_b128 v[150:153], v144 offset:1024
	ds_read_b128 v[154:157], v144 offset:2048
	ds_read_b128 v[158:161], v144 offset:3072
	s_cmp_eq_u32 s51, 28
	s_cselect_b32 s49, s41, s47
	s_cselect_b32 s48, s29, s46
	s_cselect_b32 s47, s1, s50
	s_cselect_b32 s46, s20, s21
	v_lshl_add_u64 v[144:145], s[26:27], 0, v[136:137]
	s_add_i32 m0, s23, 0xc000
	ds_read_b128 v[162:165], v149
	ds_read_b128 v[166:169], v149 offset:1024
	ds_read_b128 v[170:173], v149 offset:2048
	ds_read_b128 v[174:177], v149 offset:3072
	ds_read_b128 v[178:181], v149 offset:4096
	ds_read_b128 v[182:185], v149 offset:5120
	ds_read_b128 v[186:189], v149 offset:6144
	ds_read_b128 v[190:193], v149 offset:7168
	global_load_lds_dwordx4 v[144:145], off
	v_lshl_add_u64 v[144:145], s[26:27], 0, v[138:139]
	s_add_i32 m0, s23, 0xe000
	s_nop 0
	global_load_lds_dwordx4 v[144:145], off
	s_waitcnt lgkmcnt(11)
	s_add_i32 s66, 0, 0x14000
	v_add_u32_e32 v144, s66, v147
	s_add_i32 s60, s60, s64
	ds_read_b128 v[194:197], v144
	ds_read_b128 v[198:201], v144 offset:1024
	ds_read_b128 v[202:205], v144 offset:2048
	ds_read_b128 v[220:223], v144 offset:3072
	s_waitcnt vmcnt(8) lgkmcnt(0)
	s_barrier
	v_mfma_f32_16x16x32_f16 v[126:129], v[140:143], v[162:165], v[126:129]
	v_mfma_f32_16x16x32_f16 v[122:125], v[154:157], v[162:165], v[122:125]
	v_mfma_f32_16x16x32_f16 v[110:113], v[140:143], v[170:173], v[110:113]
	v_mfma_f32_16x16x32_f16 v[106:109], v[154:157], v[170:173], v[106:109]
	v_mfma_f32_16x16x32_f16 v[94:97], v[140:143], v[178:181], v[94:97]
	v_mfma_f32_16x16x32_f16 v[90:93], v[154:157], v[178:181], v[90:93]
	v_mfma_f32_16x16x32_f16 v[78:81], v[140:143], v[186:189], v[78:81]
	v_mfma_f32_16x16x32_f16 v[74:77], v[154:157], v[186:189], v[74:77]
	v_mfma_f32_16x16x32_f16 v[126:129], v[150:153], v[166:169], v[126:129]
	v_mfma_f32_16x16x32_f16 v[122:125], v[158:161], v[166:169], v[122:125]
	v_mfma_f32_16x16x32_f16 v[110:113], v[150:153], v[174:177], v[110:113]
	v_mfma_f32_16x16x32_f16 v[106:109], v[158:161], v[174:177], v[106:109]
	v_mfma_f32_16x16x32_f16 v[94:97], v[150:153], v[182:185], v[94:97]
	v_mfma_f32_16x16x32_f16 v[90:93], v[158:161], v[182:185], v[90:93]
	v_mfma_f32_16x16x32_f16 v[78:81], v[150:153], v[190:193], v[78:81]
	v_mfma_f32_16x16x32_f16 v[74:77], v[158:161], v[190:193], v[74:77]
	v_mfma_f32_16x16x32_f16 v[118:121], v[194:197], v[162:165], v[118:121]
	v_mfma_f32_16x16x32_f16 v[114:117], v[202:205], v[162:165], v[114:117]
	v_mfma_f32_16x16x32_f16 v[102:105], v[194:197], v[170:173], v[102:105]
	v_mfma_f32_16x16x32_f16 v[98:101], v[202:205], v[170:173], v[98:101]
	v_mfma_f32_16x16x32_f16 v[86:89], v[194:197], v[178:181], v[86:89]
	v_mfma_f32_16x16x32_f16 v[82:85], v[202:205], v[178:181], v[82:85]
	v_mfma_f32_16x16x32_f16 v[70:73], v[194:197], v[186:189], v[70:73]
	v_mfma_f32_16x16x32_f16 v[66:69], v[202:205], v[186:189], v[66:69]
	v_mfma_f32_16x16x32_f16 v[118:121], v[198:201], v[166:169], v[118:121]
	v_mfma_f32_16x16x32_f16 v[114:117], v[220:223], v[166:169], v[114:117]
	v_mfma_f32_16x16x32_f16 v[102:105], v[198:201], v[174:177], v[102:105]
	v_mfma_f32_16x16x32_f16 v[98:101], v[220:223], v[174:177], v[98:101]
	v_mfma_f32_16x16x32_f16 v[86:89], v[198:201], v[182:185], v[86:89]
	v_mfma_f32_16x16x32_f16 v[82:85], v[220:223], v[182:185], v[82:85]
	v_mfma_f32_16x16x32_f16 v[70:73], v[198:201], v[190:193], v[70:73]
	v_mfma_f32_16x16x32_f16 v[66:69], v[220:223], v[190:193], v[66:69]
	s_barrier
	v_lshl_add_u64 v[144:145], s[46:47], 0, v[0:1]
	s_mov_b32 m0, s60
	v_lshl_add_u64 v[206:207], s[46:47], 0, v[134:135]
	global_load_lds_dwordx4 v[144:145], off
	s_add_i32 m0, s60, 0x2000
	s_nop 0
	global_load_lds_dwordx4 v[206:207], off
	s_mov_b32 m0, s23
	v_lshl_add_u64 v[212:213], s[48:49], 0, v[130:131]
	ds_read_b128 v[162:165], v149 offset:16384
	ds_read_b128 v[166:169], v149 offset:17408
	ds_read_b128 v[170:173], v149 offset:18432
	ds_read_b128 v[174:177], v149 offset:19456
	ds_read_b128 v[178:181], v149 offset:20480
	ds_read_b128 v[182:185], v149 offset:21504
	ds_read_b128 v[186:189], v149 offset:22528
	ds_read_b128 v[190:193], v149 offset:23552
	global_load_lds_dwordx4 v[212:213], off
	v_lshl_add_u64 v[214:215], s[48:49], 0, v[132:133]
	s_mov_b32 m0, s71
	s_nop 0
	global_load_lds_dwordx4 v[214:215], off
	s_add_u32 s78, s46, 0x80000
	s_addc_u32 s79, s47, 0
	s_add_i32 s60, s66, s64
	v_lshl_add_u64 v[232:233], s[78:79], 0, v[0:1]
	s_mov_b32 m0, s60
	s_nop 0
	global_load_lds_dwordx4 v[232:233], off
	v_lshl_add_u64 v[232:233], s[78:79], 0, v[134:135]
	s_add_i32 m0, s60, 0x2000
	s_nop 0
	global_load_lds_dwordx4 v[232:233], off
	s_waitcnt vmcnt(8) lgkmcnt(0)
	s_barrier
; #define PG8_STAGE(bufoff, gbase, voff) do { _Pragma("unroll") for (int _i = 0; _i < 2; ++_i) \
;         __builtin_amdgcn_global_load_lds((const unsigned*)((const char*)(gbase) + (voff)[_i]), (LAS unsigned*)(lds + (bufoff) + ldsw + _i * 8192), 16, 0, 0); } while (0)
; #define PG8_LDA(dst, b, h) do { _Pragma("unroll") for (int m = 0; m < 4; ++m) _Pragma("unroll") for (int k = 0; k < 2; ++k) dst[m][k] = *(const LAS h16x8*)(lds + PG8_SA(b, h) + aoff + m * 2048 + k * 1024); } while (0)
; #define PG8_LDB(dst, b, h) do { _Pragma("unroll") for (int n = 0; n < 2; ++n) _Pragma("unroll") for (int k = 0; k < 2; ++k) dst[n][k] = *(const LAS h16x8*)(lds + PG8_SB(b, h) + boff + n * 2048 + k * 1024); } while (0)
; #define PG8_MMA(ai, bj, At, Bt_) do { __builtin_amdgcn_s_setprio(1); _Pragma("unroll") for (int m = 0; m < 4; ++m) _Pragma("unroll") for (int n = 0; n < 2; ++n) _Pragma("unroll") for (int k = 0; k < 2; ++k) \
;         acc[ai][bj][m][n] = __builtin_amdgcn_mfma_f32_16x16x32_f16(Bt_[n][k], At[m][k], acc[ai][bj][m][n], 0, 0, 0); __builtin_amdgcn_s_setprio(0); } while (0)
; #define PG8_WAIT_V(n) asm volatile("s_waitcnt vmcnt(" #n ")" ::: "memory")
; #define PG8_WAIT_L(n) asm volatile("s_waitcnt lgkmcnt(" #n ")" ::: "memory")
; #define PG8_BAR __builtin_amdgcn_s_barrier()
; #define PG8_SCHED __builtin_amdgcn_sched_barrier(0)
; template <class Epi, class AMap>
; __device__ __forceinline__ void gemm_phase(LAS unsigned char* lds, const AMap am, const int lda, const h16* Bt, const int ldb, const int M, const int N, const int K, const Epi& E) {
;     ...
;             PG8_BAR; PG8_WAIT_L(0); PG8_MMA(0, 1, At, B1); PG8_BAR;
;             PG8_LDA(At, 0, 1); PG8_STAGE(PG8_SA(0, 0), a2, voffA);
;             PG8_BAR; PG8_WAIT_L(0); PG8_MMA(1, 0, At, B0); PG8_BAR; PG8_SCHED;
;             PG8_STAGE(PG8_SB(0, 1), b2 + hstepB, voffB);
;             PG8_WAIT_V(6); PG8_BAR; PG8_MMA(1, 1, At, B1); PG8_BAR;
;             PG8_LDB(B0, 1, 0); PG8_SCHED; PG8_LDA(At, 1, 0); PG8_STAGE(PG8_SA(0, 1), a2 + hstepA, voffA);
;             PG8_WAIT_L(8); PG8_BAR; PG8_WAIT_L(0); PG8_MMA(0, 0, At, B0); PG8_BAR; PG8_SCHED;
;             PG8_LDB(B1, 1, 1); PG8_STAGE(PG8_SB(1, 0), b3, voffB);
;             PG8_BAR; PG8_WAIT_L(0); PG8_MMA(0, 1, At, B1); PG8_BAR;
	v_mfma_f32_16x16x32_f16 v[62:65], v[140:143], v[162:165], v[62:65]
	v_mfma_f32_16x16x32_f16 v[58:61], v[154:157], v[162:165], v[58:61]
	v_mfma_f32_16x16x32_f16 v[46:49], v[140:143], v[170:173], v[46:49]
	v_mfma_f32_16x16x32_f16 v[42:45], v[154:157], v[170:173], v[42:45]
	v_mfma_f32_16x16x32_f16 v[30:33], v[140:143], v[178:181], v[30:33]
	v_mfma_f32_16x16x32_f16 v[26:29], v[154:157], v[178:181], v[26:29]
	v_mfma_f32_16x16x32_f16 v[14:17], v[140:143], v[186:189], v[14:17]
	v_mfma_f32_16x16x32_f16 v[10:13], v[154:157], v[186:189], v[10:13]
	v_mfma_f32_16x16x32_f16 v[62:65], v[150:153], v[166:169], v[62:65]
	v_mfma_f32_16x16x32_f16 v[58:61], v[158:161], v[166:169], v[58:61]
	v_mfma_f32_16x16x32_f16 v[46:49], v[150:153], v[174:177], v[46:49]
	v_mfma_f32_16x16x32_f16 v[42:45], v[158:161], v[174:177], v[42:45]
	v_mfma_f32_16x16x32_f16 v[30:33], v[150:153], v[182:185], v[30:33]
	v_mfma_f32_16x16x32_f16 v[26:29], v[158:161], v[182:185], v[26:29]
	v_mfma_f32_16x16x32_f16 v[14:17], v[150:153], v[190:193], v[14:17]
	v_mfma_f32_16x16x32_f16 v[10:13], v[158:161], v[190:193], v[10:13]
	v_mfma_f32_16x16x32_f16 v[54:57], v[194:197], v[162:165], v[54:57]
	v_mfma_f32_16x16x32_f16 v[50:53], v[202:205], v[162:165], v[50:53]
	v_mfma_f32_16x16x32_f16 v[38:41], v[194:197], v[170:173], v[38:41]
	v_mfma_f32_16x16x32_f16 v[34:37], v[202:205], v[170:173], v[34:37]
	v_mfma_f32_16x16x32_f16 v[22:25], v[194:197], v[178:181], v[22:25]
	v_mfma_f32_16x16x32_f16 v[18:21], v[202:205], v[178:181], v[18:21]
	v_mfma_f32_16x16x32_f16 v[6:9], v[194:197], v[186:189], v[6:9]
	v_mfma_f32_16x16x32_f16 v[2:5], v[202:205], v[186:189], v[2:5]
	v_mfma_f32_16x16x32_f16 v[54:57], v[198:201], v[166:169], v[54:57]
	v_mfma_f32_16x16x32_f16 v[50:53], v[220:223], v[166:169], v[50:53]
	v_mfma_f32_16x16x32_f16 v[38:41], v[198:201], v[174:177], v[38:41]
	v_mfma_f32_16x16x32_f16 v[34:37], v[220:223], v[174:177], v[34:37]
	v_mfma_f32_16x16x32_f16 v[22:25], v[198:201], v[182:185], v[22:25]
	v_mfma_f32_16x16x32_f16 v[18:21], v[220:223], v[182:185], v[18:21]
	v_mfma_f32_16x16x32_f16 v[6:9], v[198:201], v[190:193], v[6:9]
	v_mfma_f32_16x16x32_f16 v[2:5], v[220:223], v[190:193], v[2:5]
	s_barrier
	s_add_i32 s60, 0, 0x18000
	v_add_u32_e32 v234, s60, v147
	ds_read_b128 v[140:143], v234
	ds_read_b128 v[150:153], v234 offset:1024
	ds_read_b128 v[154:157], v234 offset:2048
	ds_read_b128 v[158:161], v234 offset:3072
	s_add_u32 s48, s48, 0x80000
	s_addc_u32 s49, s49, 0
	s_mov_b32 m0, s72
	v_lshl_add_u64 v[232:233], s[48:49], 0, v[130:131]
	ds_read_b128 v[162:165], v149 offset:32768
	ds_read_b128 v[166:169], v149 offset:33792
	ds_read_b128 v[170:173], v149 offset:34816
	ds_read_b128 v[174:177], v149 offset:35840
	ds_read_b128 v[178:181], v149 offset:36864
	ds_read_b128 v[182:185], v149 offset:37888
	ds_read_b128 v[186:189], v149 offset:38912
	ds_read_b128 v[190:193], v149 offset:39936
	global_load_lds_dwordx4 v[232:233], off
	v_lshl_add_u64 v[232:233], s[48:49], 0, v[132:133]
	s_mov_b32 m0, s73
	s_nop 0
	global_load_lds_dwordx4 v[232:233], off
	s_waitcnt lgkmcnt(11)
	s_add_i32 s48, 0, 0x1c000
	s_add_i32 s49, s60, s64
	v_add_u32_e32 v216, s48, v147
	v_lshl_add_u64 v[144:145], v[144:145], 0, s[92:93]
	s_mov_b32 m0, s49
	ds_read_b128 v[194:197], v216
	ds_read_b128 v[198:201], v216 offset:1024
	ds_read_b128 v[202:205], v216 offset:2048
	ds_read_b128 v[220:223], v216 offset:3072
	s_waitcnt vmcnt(8) lgkmcnt(0)
	s_barrier
	v_mfma_f32_16x16x32_f16 v[126:129], v[140:143], v[162:165], v[126:129]
	v_mfma_f32_16x16x32_f16 v[122:125], v[154:157], v[162:165], v[122:125]
	v_mfma_f32_16x16x32_f16 v[110:113], v[140:143], v[170:173], v[110:113]
	v_mfma_f32_16x16x32_f16 v[106:109], v[154:157], v[170:173], v[106:109]
	v_mfma_f32_16x16x32_f16 v[94:97], v[140:143], v[178:181], v[94:97]
	v_mfma_f32_16x16x32_f16 v[90:93], v[154:157], v[178:181], v[90:93]
	v_mfma_f32_16x16x32_f16 v[78:81], v[140:143], v[186:189], v[78:81]
	v_mfma_f32_16x16x32_f16 v[74:77], v[154:157], v[186:189], v[74:77]
	v_mfma_f32_16x16x32_f16 v[126:129], v[150:153], v[166:169], v[126:129]
	v_mfma_f32_16x16x32_f16 v[122:125], v[158:161], v[166:169], v[122:125]
	v_mfma_f32_16x16x32_f16 v[110:113], v[150:153], v[174:177], v[110:113]
	v_mfma_f32_16x16x32_f16 v[106:109], v[158:161], v[174:177], v[106:109]
	v_mfma_f32_16x16x32_f16 v[94:97], v[150:153], v[182:185], v[94:97]
	v_mfma_f32_16x16x32_f16 v[90:93], v[158:161], v[182:185], v[90:93]
	v_mfma_f32_16x16x32_f16 v[78:81], v[150:153], v[190:193], v[78:81]
	v_mfma_f32_16x16x32_f16 v[74:77], v[158:161], v[190:193], v[74:77]
	v_mfma_f32_16x16x32_f16 v[118:121], v[194:197], v[162:165], v[118:121]
	v_mfma_f32_16x16x32_f16 v[114:117], v[202:205], v[162:165], v[114:117]
	v_mfma_f32_16x16x32_f16 v[102:105], v[194:197], v[170:173], v[102:105]
	v_mfma_f32_16x16x32_f16 v[98:101], v[202:205], v[170:173], v[98:101]
	v_mfma_f32_16x16x32_f16 v[86:89], v[194:197], v[178:181], v[86:89]
	v_mfma_f32_16x16x32_f16 v[82:85], v[202:205], v[178:181], v[82:85]
	v_mfma_f32_16x16x32_f16 v[70:73], v[194:197], v[186:189], v[70:73]
	v_mfma_f32_16x16x32_f16 v[66:69], v[202:205], v[186:189], v[66:69]
	v_mfma_f32_16x16x32_f16 v[118:121], v[198:201], v[166:169], v[118:121]
	v_mfma_f32_16x16x32_f16 v[114:117], v[220:223], v[166:169], v[114:117]
	v_mfma_f32_16x16x32_f16 v[102:105], v[198:201], v[174:177], v[102:105]
	v_mfma_f32_16x16x32_f16 v[98:101], v[220:223], v[174:177], v[98:101]
	v_mfma_f32_16x16x32_f16 v[86:89], v[198:201], v[182:185], v[86:89]
	v_mfma_f32_16x16x32_f16 v[82:85], v[220:223], v[182:185], v[82:85]
	v_mfma_f32_16x16x32_f16 v[70:73], v[198:201], v[190:193], v[70:73]
	v_mfma_f32_16x16x32_f16 v[66:69], v[220:223], v[190:193], v[66:69]
	s_barrier
; #define PG8_STAGE(bufoff, gbase, voff) do { _Pragma("unroll") for (int _i = 0; _i < 2; ++_i) \
;         __builtin_amdgcn_global_load_lds((const unsigned*)((const char*)(gbase) + (voff)[_i]), (LAS unsigned*)(lds + (bufoff) + ldsw + _i * 8192), 16, 0, 0); } while (0)
; #define PG8_LDA(dst, b, h) do { _Pragma("unroll") for (int m = 0; m < 4; ++m) _Pragma("unroll") for (int k = 0; k < 2; ++k) dst[m][k] = *(const LAS h16x8*)(lds + PG8_SA(b, h) + aoff + m * 2048 + k * 1024); } while (0)
; #define PG8_MMA(ai, bj, At, Bt_) do { __builtin_amdgcn_s_setprio(1); _Pragma("unroll") for (int m = 0; m < 4; ++m) _Pragma("unroll") for (int n = 0; n < 2; ++n) _Pragma("unroll") for (int k = 0; k < 2; ++k) \
;         acc[ai][bj][m][n] = __builtin_amdgcn_mfma_f32_16x16x32_f16(Bt_[n][k], At[m][k], acc[ai][bj][m][n], 0, 0, 0); __builtin_amdgcn_s_setprio(0); } while (0)
; #define PG8_WAIT_V(n) asm volatile("s_waitcnt vmcnt(" #n ")" ::: "memory")
; #define PG8_WAIT_L(n) asm volatile("s_waitcnt lgkmcnt(" #n ")" ::: "memory")
; #define PG8_BAR __builtin_amdgcn_s_barrier()
; #define PG8_SCHED __builtin_amdgcn_sched_barrier(0)
; template <class Epi, class AMap>
; __device__ __forceinline__ void gemm_phase(LAS unsigned char* lds, const AMap am, const int lda, const h16* Bt, const int ldb, const int M, const int N, const int K, const Epi& E) {
;     ...
;             PG8_BAR; PG8_WAIT_L(0); PG8_MMA(0, 1, At, B1); PG8_BAR;
;             PG8_LDA(At, 1, 1); PG8_STAGE(PG8_SA(1, 0), a3, voffA);
;             PG8_BAR; PG8_WAIT_L(0); PG8_MMA(1, 0, At, B0); PG8_BAR; PG8_SCHED;
;             PG8_STAGE(PG8_SB(1, 1), b3 + hstepB, voffB);
;             PG8_WAIT_V(6); PG8_BAR; PG8_MMA(1, 1, At, B1); PG8_BAR;
;         }
;         E(acc, cur, wr, wc, fr, fq);
;         if (!has_next) break;
;     __device__ __forceinline__ void operator()(const f32x4 (&acc)[2][2][4][2], const Unit& u, int wr, int wc, int fr, int fq) const {
;     ...
;             for (int m = 0; m < 4; ++m) { const size_t off = (size_t)(row0 + ai * 128 + m * 16) * DM + colt;
; #pragma unroll
;                 for (int bj = 0; bj < 2; ++bj) {
;                     const h16x8 x = *(const h16x8*)(X + off + bj * 128);
	global_load_lds_dwordx4 v[144:145], off
	v_lshl_add_u64 v[144:145], v[206:207], 0, s[92:93]
	s_add_i32 m0, s49, 0x2000
	s_nop 0
	global_load_lds_dwordx4 v[144:145], off
	s_mov_b32 m0, s74
	v_lshl_add_u64 v[144:145], v[212:213], 0, s[92:93]
	ds_read_b128 v[162:165], v149 offset:49152
	ds_read_b128 v[166:169], v149 offset:50176
	ds_read_b128 v[170:173], v149 offset:51200
	ds_read_b128 v[174:177], v149 offset:52224
	ds_read_b128 v[178:181], v149 offset:53248
	ds_read_b128 v[182:185], v149 offset:54272
	ds_read_b128 v[186:189], v149 offset:55296
	ds_read_b128 v[190:193], v149 offset:56320
	global_load_lds_dwordx4 v[144:145], off
	v_lshl_add_u64 v[144:145], v[214:215], 0, s[92:93]
	s_mov_b32 m0, s75
	s_nop 0
	global_load_lds_dwordx4 v[144:145], off
	s_add_u32 s46, s46, 0x80080
	s_addc_u32 s47, s47, 0
	s_add_i32 s48, s48, s64
	v_lshl_add_u64 v[232:233], s[46:47], 0, v[0:1]
	s_mov_b32 m0, s48
	s_nop 0
	global_load_lds_dwordx4 v[232:233], off
	v_lshl_add_u64 v[232:233], s[46:47], 0, v[134:135]
	s_add_i32 m0, s48, 0x2000
	s_nop 0
	global_load_lds_dwordx4 v[232:233], off
	s_waitcnt vmcnt(8) lgkmcnt(0)
	s_barrier
	v_mfma_f32_16x16x32_f16 v[62:65], v[140:143], v[162:165], v[62:65]
	v_mfma_f32_16x16x32_f16 v[58:61], v[154:157], v[162:165], v[58:61]
	v_mfma_f32_16x16x32_f16 v[46:49], v[140:143], v[170:173], v[46:49]
	v_mfma_f32_16x16x32_f16 v[42:45], v[154:157], v[170:173], v[42:45]
	v_mfma_f32_16x16x32_f16 v[30:33], v[140:143], v[178:181], v[30:33]
	v_mfma_f32_16x16x32_f16 v[26:29], v[154:157], v[178:181], v[26:29]
	v_mfma_f32_16x16x32_f16 v[14:17], v[140:143], v[186:189], v[14:17]
	v_mfma_f32_16x16x32_f16 v[10:13], v[154:157], v[186:189], v[10:13]
	v_mfma_f32_16x16x32_f16 v[62:65], v[150:153], v[166:169], v[62:65]
	v_mfma_f32_16x16x32_f16 v[58:61], v[158:161], v[166:169], v[58:61]
	v_mfma_f32_16x16x32_f16 v[46:49], v[150:153], v[174:177], v[46:49]
	v_mfma_f32_16x16x32_f16 v[42:45], v[158:161], v[174:177], v[42:45]
	v_mfma_f32_16x16x32_f16 v[30:33], v[150:153], v[182:185], v[30:33]
	v_mfma_f32_16x16x32_f16 v[26:29], v[158:161], v[182:185], v[26:29]
	v_mfma_f32_16x16x32_f16 v[14:17], v[150:153], v[190:193], v[14:17]
	v_mfma_f32_16x16x32_f16 v[10:13], v[158:161], v[190:193], v[10:13]
	v_mfma_f32_16x16x32_f16 v[54:57], v[194:197], v[162:165], v[54:57]
	v_mfma_f32_16x16x32_f16 v[50:53], v[202:205], v[162:165], v[50:53]
	v_mfma_f32_16x16x32_f16 v[38:41], v[194:197], v[170:173], v[38:41]
	v_mfma_f32_16x16x32_f16 v[34:37], v[202:205], v[170:173], v[34:37]
	v_mfma_f32_16x16x32_f16 v[22:25], v[194:197], v[178:181], v[22:25]
	v_mfma_f32_16x16x32_f16 v[18:21], v[202:205], v[178:181], v[18:21]
	v_mfma_f32_16x16x32_f16 v[6:9], v[194:197], v[186:189], v[6:9]
	v_mfma_f32_16x16x32_f16 v[2:5], v[202:205], v[186:189], v[2:5]
	v_mfma_f32_16x16x32_f16 v[54:57], v[198:201], v[166:169], v[54:57]
	v_mfma_f32_16x16x32_f16 v[50:53], v[220:223], v[166:169], v[50:53]
	v_mfma_f32_16x16x32_f16 v[38:41], v[198:201], v[174:177], v[38:41]
	v_mfma_f32_16x16x32_f16 v[34:37], v[220:223], v[174:177], v[34:37]
	v_mfma_f32_16x16x32_f16 v[22:25], v[198:201], v[182:185], v[22:25]
	v_mfma_f32_16x16x32_f16 v[18:21], v[220:223], v[182:185], v[18:21]
	v_mfma_f32_16x16x32_f16 v[6:9], v[198:201], v[190:193], v[6:9]
	v_mfma_f32_16x16x32_f16 v[2:5], v[220:223], v[190:193], v[2:5]
	s_add_i32 s51, s51, 2
	s_add_u32 s26, s26, 0x100
	s_addc_u32 s27, s27, 0
	s_add_u32 s21, s21, 0x100
	s_addc_u32 s50, s50, 0
	s_cmp_gt_u32 s51, 29
	s_barrier
	s_cbranch_scc0 .LBB0_147
	s_cmpk_gt_u32 s62, 0xff
	s_cbranch_scc1 .Lgx2
	s_barrier
.Lgx2:
	v_lshl_add_u32 v144, s22, 8, v146
	v_lshl_or_b32 v142, s35, 8, v148
	v_ashrrev_i32_e32 v145, 31, v144
	v_ashrrev_i32_e32 v143, 31, v142
	v_lshlrev_b64 v[140:141], 11, v[144:145]
	v_lshl_add_u64 v[140:141], v[140:141], 0, v[142:143]
	v_lshlrev_b64 v[140:141], 1, v[140:141]
	v_lshl_add_u64 v[154:155], s[94:95], 0, v[140:141]
	s_mov_b32 s101, 0
	global_load_dwordx4 v[158:161], v[154:155], off
	global_load_dwordx4 v[162:165], v[154:155], off offset:256
	s_mov_b32 s100, 0x10000
	v_lshl_add_u64 v[232:233], v[154:155], 0, s[100:101]
	global_load_dwordx4 v[166:169], v[232:233], off
	global_load_dwordx4 v[170:173], v[232:233], off offset:256
	s_mov_b32 s100, 0x20000
	v_lshl_add_u64 v[232:233], v[154:155], 0, s[100:101]
	global_load_dwordx4 v[174:177], v[232:233], off
	global_load_dwordx4 v[178:181], v[232:233], off offset:256
	s_mov_b32 s100, 0x30000
	v_lshl_add_u64 v[232:233], v[154:155], 0, s[100:101]
	global_load_dwordx4 v[182:185], v[232:233], off
	global_load_dwordx4 v[186:189], v[232:233], off offset:256
	s_mov_b32 s100, 0x80000
	v_lshl_add_u64 v[232:233], v[154:155], 0, s[100:101]
	global_load_dwordx4 v[190:193], v[232:233], off
	global_load_dwordx4 v[194:197], v[232:233], off offset:256
	s_mov_b32 s100, 0x90000
	v_lshl_add_u64 v[232:233], v[154:155], 0, s[100:101]
	global_load_dwordx4 v[198:201], v[232:233], off
	global_load_dwordx4 v[202:205], v[232:233], off offset:256
	s_mov_b32 s100, 0xa0000
	v_lshl_add_u64 v[232:233], v[154:155], 0, s[100:101]
	global_load_dwordx4 v[212:215], v[232:233], off
	global_load_dwordx4 v[220:223], v[232:233], off offset:256
	s_mov_b32 s100, 0xb0000
	v_lshl_add_u64 v[232:233], v[154:155], 0, s[100:101]
	global_load_dwordx4 v[224:227], v[232:233], off
	global_load_dwordx4 v[228:231], v[232:233], off offset:256
	s_mov_b64 s[2:3], 0xb0000
	s_and_b64 vcc, exec, s[38:39]
	s_mov_b32 s22, s40
	s_mov_b64 s[46:47], s[44:45]
	s_mov_b64 s[26:27], s[42:43]
	s_movk_i32 s66, 0x80
	s_waitcnt vmcnt(15)
;     __device__ __forceinline__ void operator()(const f32x4 (&acc)[2][2][4][2], const Unit& u, int wr, int wc, int fr, int fq) const {
;     ...
;             for (int m = 0; m < 4; ++m) { const size_t off = (size_t)(row0 + ai * 128 + m * 16) * DM + colt;
; #pragma unroll
;                 for (int bj = 0; bj < 2; ++bj) {
;                     const h16x8 x = *(const h16x8*)(X + off + bj * 128);
;                     f32x4 o0, o1;
; #pragma unroll
;                     for (int e = 0; e < 4; ++e) { o0[e] = (float)x[e] * ALPHA + acc[ai][bj][m][0][e]; o1[e] = (float)x[4 + e] * ALPHA + acc[ai][bj][m][1][e]; }
;                     *(u32x4*)(PRE + off + bj * 128) = pack8(o0, o1); } }
	v_mov_b64_e32 v[150:151], v[158:159]
	v_mov_b64_e32 v[152:153], v[160:161]
	v_cvt_f32_f16_e32 v156, v150
	v_cvt_f32_f16_sdwa v157, v150 dst_sel:DWORD dst_unused:UNUSED_PAD src0_sel:WORD_1
	v_cvt_f32_f16_e32 v150, v151
	v_cvt_f32_f16_sdwa v151, v151 dst_sel:DWORD dst_unused:UNUSED_PAD src0_sel:WORD_1
	v_pk_fma_f32 v[126:127], v[156:157], s[34:35], v[126:127] op_sel_hi:[1,0,1]
	s_nop 0
	v_cvt_pk_f16_f32 v126, v126, v127
	v_pk_fma_f32 v[128:129], v[150:151], s[34:35], v[128:129] op_sel_hi:[1,0,1]
	v_lshl_add_u64 v[150:151], s[4:5], 0, v[140:141]
	v_cvt_pk_f16_f32 v127, v128, v129
	v_cvt_f32_f16_e32 v128, v152
	v_cvt_f32_f16_sdwa v129, v152 dst_sel:DWORD dst_unused:UNUSED_PAD src0_sel:WORD_1
	v_pk_fma_f32 v[122:123], v[128:129], s[34:35], v[122:123] op_sel_hi:[1,0,1]
	s_nop 0
	v_cvt_pk_f16_f32 v128, v122, v123
	v_cvt_f32_f16_e32 v122, v153
	v_cvt_f32_f16_sdwa v123, v153 dst_sel:DWORD dst_unused:UNUSED_PAD src0_sel:WORD_1
	v_pk_fma_f32 v[122:123], v[122:123], s[34:35], v[124:125] op_sel_hi:[1,0,1]
	s_nop 0
	v_cvt_pk_f16_f32 v129, v122, v123
	s_nop 0
	global_store_dwordx4 v[150:151], v[126:129], off
	s_waitcnt vmcnt(15)
	v_mov_b64_e32 v[122:123], v[162:163]
	v_mov_b64_e32 v[124:125], v[164:165]
	s_nop 0
	v_cvt_f32_f16_e32 v126, v122
	v_cvt_f32_f16_sdwa v127, v122 dst_sel:DWORD dst_unused:UNUSED_PAD src0_sel:WORD_1
	v_cvt_f32_f16_e32 v122, v123
	v_cvt_f32_f16_sdwa v123, v123 dst_sel:DWORD dst_unused:UNUSED_PAD src0_sel:WORD_1
	v_pk_fma_f32 v[118:119], v[126:127], s[34:35], v[118:119] op_sel_hi:[1,0,1]
	s_nop 0
	v_cvt_pk_f16_f32 v118, v118, v119
	v_pk_fma_f32 v[120:121], v[122:123], s[34:35], v[120:121] op_sel_hi:[1,0,1]
	s_nop 0
	v_cvt_pk_f16_f32 v119, v120, v121
	v_cvt_f32_f16_e32 v120, v124
	v_cvt_f32_f16_sdwa v121, v124 dst_sel:DWORD dst_unused:UNUSED_PAD src0_sel:WORD_1
	v_pk_fma_f32 v[114:115], v[120:121], s[34:35], v[114:115] op_sel_hi:[1,0,1]
	s_nop 0
	v_cvt_pk_f16_f32 v120, v114, v115
	v_cvt_f32_f16_e32 v114, v125
	v_cvt_f32_f16_sdwa v115, v125 dst_sel:DWORD dst_unused:UNUSED_PAD src0_sel:WORD_1
	v_pk_fma_f32 v[114:115], v[114:115], s[34:35], v[116:117] op_sel_hi:[1,0,1]
	s_nop 0
	v_cvt_pk_f16_f32 v121, v114, v115
	v_or_b32_e32 v114, 16, v144
	v_ashrrev_i32_e32 v115, 31, v114
	v_lshlrev_b64 v[114:115], 11, v[114:115]
	v_lshl_add_u64 v[114:115], v[114:115], 0, v[142:143]
	global_store_dwordx4 v[150:151], v[118:121], off offset:256
	s_nop 1
	v_lshlrev_b64 v[118:119], 1, v[114:115]
	v_lshl_add_u64 v[120:121], s[94:95], 0, v[118:119]
	s_waitcnt vmcnt(15)
	v_mov_b64_e32 v[114:115], v[166:167]
	v_mov_b64_e32 v[116:117], v[168:169]
	v_cvt_f32_f16_e32 v122, v114
	v_cvt_f32_f16_sdwa v123, v114 dst_sel:DWORD dst_unused:UNUSED_PAD src0_sel:WORD_1
	v_cvt_f32_f16_e32 v114, v115
	v_cvt_f32_f16_sdwa v115, v115 dst_sel:DWORD dst_unused:UNUSED_PAD src0_sel:WORD_1
	v_pk_fma_f32 v[110:111], v[122:123], s[34:35], v[110:111] op_sel_hi:[1,0,1]
	s_nop 0
	v_cvt_pk_f16_f32 v110, v110, v111
	v_pk_fma_f32 v[112:113], v[114:115], s[34:35], v[112:113] op_sel_hi:[1,0,1]
	v_lshl_add_u64 v[114:115], s[4:5], 0, v[118:119]
	v_cvt_pk_f16_f32 v111, v112, v113
	v_cvt_f32_f16_e32 v112, v116
	v_cvt_f32_f16_sdwa v113, v116 dst_sel:DWORD dst_unused:UNUSED_PAD src0_sel:WORD_1
	v_pk_fma_f32 v[106:107], v[112:113], s[34:35], v[106:107] op_sel_hi:[1,0,1]
	s_nop 0
	v_cvt_pk_f16_f32 v112, v106, v107
	v_cvt_f32_f16_e32 v106, v117
	v_cvt_f32_f16_sdwa v107, v117 dst_sel:DWORD dst_unused:UNUSED_PAD src0_sel:WORD_1
	v_pk_fma_f32 v[106:107], v[106:107], s[34:35], v[108:109] op_sel_hi:[1,0,1]
	s_nop 0
	v_cvt_pk_f16_f32 v113, v106, v107
	s_nop 0
	global_store_dwordx4 v[114:115], v[110:113], off
	s_waitcnt vmcnt(15)
	v_mov_b64_e32 v[106:107], v[170:171]
	v_mov_b64_e32 v[108:109], v[172:173]
	s_nop 0
	v_cvt_f32_f16_e32 v110, v106
	v_cvt_f32_f16_sdwa v111, v106 dst_sel:DWORD dst_unused:UNUSED_PAD src0_sel:WORD_1
	v_cvt_f32_f16_e32 v106, v107
	v_cvt_f32_f16_sdwa v107, v107 dst_sel:DWORD dst_unused:UNUSED_PAD src0_sel:WORD_1
	v_pk_fma_f32 v[102:103], v[110:111], s[34:35], v[102:103] op_sel_hi:[1,0,1]
	s_nop 0
	v_cvt_pk_f16_f32 v102, v102, v103
	v_pk_fma_f32 v[104:105], v[106:107], s[34:35], v[104:105] op_sel_hi:[1,0,1]
	s_nop 0
	v_cvt_pk_f16_f32 v103, v104, v105
	v_cvt_f32_f16_e32 v104, v108
	v_cvt_f32_f16_sdwa v105, v108 dst_sel:DWORD dst_unused:UNUSED_PAD src0_sel:WORD_1
	v_pk_fma_f32 v[98:99], v[104:105], s[34:35], v[98:99] op_sel_hi:[1,0,1]
	s_nop 0
	v_cvt_pk_f16_f32 v104, v98, v99
	v_cvt_f32_f16_e32 v98, v109
	v_cvt_f32_f16_sdwa v99, v109 dst_sel:DWORD dst_unused:UNUSED_PAD src0_sel:WORD_1
	v_pk_fma_f32 v[98:99], v[98:99], s[34:35], v[100:101] op_sel_hi:[1,0,1]
	s_nop 0
	v_cvt_pk_f16_f32 v105, v98, v99
	v_or_b32_e32 v98, 32, v144
	v_ashrrev_i32_e32 v99, 31, v98
	v_lshlrev_b64 v[98:99], 11, v[98:99]
	v_lshl_add_u64 v[98:99], v[98:99], 0, v[142:143]
	global_store_dwordx4 v[114:115], v[102:105], off offset:256
	s_nop 1
	v_lshlrev_b64 v[102:103], 1, v[98:99]
	v_lshl_add_u64 v[104:105], s[94:95], 0, v[102:103]
	s_waitcnt vmcnt(15)
	v_mov_b64_e32 v[98:99], v[174:175]
	v_mov_b64_e32 v[100:101], v[176:177]
	v_cvt_f32_f16_e32 v106, v98
	v_cvt_f32_f16_sdwa v107, v98 dst_sel:DWORD dst_unused:UNUSED_PAD src0_sel:WORD_1
	v_cvt_f32_f16_e32 v98, v99
	v_cvt_f32_f16_sdwa v99, v99 dst_sel:DWORD dst_unused:UNUSED_PAD src0_sel:WORD_1
	v_pk_fma_f32 v[94:95], v[106:107], s[34:35], v[94:95] op_sel_hi:[1,0,1]
	s_nop 0
	v_cvt_pk_f16_f32 v94, v94, v95
	v_pk_fma_f32 v[96:97], v[98:99], s[34:35], v[96:97] op_sel_hi:[1,0,1]
	v_lshl_add_u64 v[98:99], s[4:5], 0, v[102:103]
	v_cvt_pk_f16_f32 v95, v96, v97
	v_cvt_f32_f16_e32 v96, v100
	v_cvt_f32_f16_sdwa v97, v100 dst_sel:DWORD dst_unused:UNUSED_PAD src0_sel:WORD_1
	v_pk_fma_f32 v[90:91], v[96:97], s[34:35], v[90:91] op_sel_hi:[1,0,1]
	s_nop 0
	v_cvt_pk_f16_f32 v96, v90, v91
	v_cvt_f32_f16_e32 v90, v101
	v_cvt_f32_f16_sdwa v91, v101 dst_sel:DWORD dst_unused:UNUSED_PAD src0_sel:WORD_1
	v_pk_fma_f32 v[90:91], v[90:91], s[34:35], v[92:93] op_sel_hi:[1,0,1]
	s_nop 0
	v_cvt_pk_f16_f32 v97, v90, v91
	s_nop 0
	global_store_dwordx4 v[98:99], v[94:97], off
	s_waitcnt vmcnt(15)
;     __device__ __forceinline__ void operator()(const f32x4 (&acc)[2][2][4][2], const Unit& u, int wr, int wc, int fr, int fq) const {
;     ...
;             for (int m = 0; m < 4; ++m) { const size_t off = (size_t)(row0 + ai * 128 + m * 16) * DM + colt;
; #pragma unroll
;                 for (int bj = 0; bj < 2; ++bj) {
;                     const h16x8 x = *(const h16x8*)(X + off + bj * 128);
;                     f32x4 o0, o1;
; #pragma unroll
;                     for (int e = 0; e < 4; ++e) { o0[e] = (float)x[e] * ALPHA + acc[ai][bj][m][0][e]; o1[e] = (float)x[4 + e] * ALPHA + acc[ai][bj][m][1][e]; }
;                     *(u32x4*)(PRE + off + bj * 128) = pack8(o0, o1); } }
	v_mov_b64_e32 v[90:91], v[178:179]
	v_mov_b64_e32 v[92:93], v[180:181]
	s_nop 0
	v_cvt_f32_f16_e32 v94, v90
	v_cvt_f32_f16_sdwa v95, v90 dst_sel:DWORD dst_unused:UNUSED_PAD src0_sel:WORD_1
	v_cvt_f32_f16_e32 v90, v91
	v_cvt_f32_f16_sdwa v91, v91 dst_sel:DWORD dst_unused:UNUSED_PAD src0_sel:WORD_1
	v_pk_fma_f32 v[86:87], v[94:95], s[34:35], v[86:87] op_sel_hi:[1,0,1]
	s_nop 0
	v_cvt_pk_f16_f32 v86, v86, v87
	v_pk_fma_f32 v[88:89], v[90:91], s[34:35], v[88:89] op_sel_hi:[1,0,1]
	s_nop 0
	v_cvt_pk_f16_f32 v87, v88, v89
	v_cvt_f32_f16_e32 v88, v92
	v_cvt_f32_f16_sdwa v89, v92 dst_sel:DWORD dst_unused:UNUSED_PAD src0_sel:WORD_1
	v_pk_fma_f32 v[82:83], v[88:89], s[34:35], v[82:83] op_sel_hi:[1,0,1]
	s_nop 0
	v_cvt_pk_f16_f32 v88, v82, v83
	v_cvt_f32_f16_e32 v82, v93
	v_cvt_f32_f16_sdwa v83, v93 dst_sel:DWORD dst_unused:UNUSED_PAD src0_sel:WORD_1
	v_pk_fma_f32 v[82:83], v[82:83], s[34:35], v[84:85] op_sel_hi:[1,0,1]
	s_nop 0
	v_cvt_pk_f16_f32 v89, v82, v83
	v_or_b32_e32 v82, 48, v144
	v_ashrrev_i32_e32 v83, 31, v82
	v_lshlrev_b64 v[82:83], 11, v[82:83]
	v_lshl_add_u64 v[82:83], v[82:83], 0, v[142:143]
	global_store_dwordx4 v[98:99], v[86:89], off offset:256
	s_nop 1
	v_lshlrev_b64 v[86:87], 1, v[82:83]
	v_lshl_add_u64 v[88:89], s[94:95], 0, v[86:87]
	s_waitcnt vmcnt(15)
	v_mov_b64_e32 v[82:83], v[182:183]
	v_mov_b64_e32 v[84:85], v[184:185]
	v_cvt_f32_f16_e32 v90, v82
	v_cvt_f32_f16_sdwa v91, v82 dst_sel:DWORD dst_unused:UNUSED_PAD src0_sel:WORD_1
	v_cvt_f32_f16_e32 v82, v83
	v_cvt_f32_f16_sdwa v83, v83 dst_sel:DWORD dst_unused:UNUSED_PAD src0_sel:WORD_1
	v_pk_fma_f32 v[78:79], v[90:91], s[34:35], v[78:79] op_sel_hi:[1,0,1]
	s_nop 0
	v_cvt_pk_f16_f32 v78, v78, v79
	v_pk_fma_f32 v[80:81], v[82:83], s[34:35], v[80:81] op_sel_hi:[1,0,1]
	v_lshl_add_u64 v[82:83], s[4:5], 0, v[86:87]
	v_cvt_pk_f16_f32 v79, v80, v81
	v_cvt_f32_f16_e32 v80, v84
	v_cvt_f32_f16_sdwa v81, v84 dst_sel:DWORD dst_unused:UNUSED_PAD src0_sel:WORD_1
	v_pk_fma_f32 v[74:75], v[80:81], s[34:35], v[74:75] op_sel_hi:[1,0,1]
	s_nop 0
	v_cvt_pk_f16_f32 v80, v74, v75
	v_cvt_f32_f16_e32 v74, v85
	v_cvt_f32_f16_sdwa v75, v85 dst_sel:DWORD dst_unused:UNUSED_PAD src0_sel:WORD_1
	v_pk_fma_f32 v[74:75], v[74:75], s[34:35], v[76:77] op_sel_hi:[1,0,1]
	s_nop 0
	v_cvt_pk_f16_f32 v81, v74, v75
	s_nop 0
	global_store_dwordx4 v[82:83], v[78:81], off
	s_waitcnt vmcnt(15)
	v_mov_b64_e32 v[74:75], v[186:187]
	v_mov_b64_e32 v[76:77], v[188:189]
	s_nop 0
	v_cvt_f32_f16_e32 v78, v74
	v_cvt_f32_f16_sdwa v79, v74 dst_sel:DWORD dst_unused:UNUSED_PAD src0_sel:WORD_1
	v_cvt_f32_f16_e32 v74, v75
	v_cvt_f32_f16_sdwa v75, v75 dst_sel:DWORD dst_unused:UNUSED_PAD src0_sel:WORD_1
	v_pk_fma_f32 v[70:71], v[78:79], s[34:35], v[70:71] op_sel_hi:[1,0,1]
	s_nop 0
	v_cvt_pk_f16_f32 v70, v70, v71
	v_pk_fma_f32 v[72:73], v[74:75], s[34:35], v[72:73] op_sel_hi:[1,0,1]
	s_nop 0
	v_cvt_pk_f16_f32 v71, v72, v73
	v_cvt_f32_f16_e32 v72, v76
	v_cvt_f32_f16_sdwa v73, v76 dst_sel:DWORD dst_unused:UNUSED_PAD src0_sel:WORD_1
	v_pk_fma_f32 v[66:67], v[72:73], s[34:35], v[66:67] op_sel_hi:[1,0,1]
	s_nop 0
	v_cvt_pk_f16_f32 v72, v66, v67
	v_cvt_f32_f16_e32 v66, v77
	v_cvt_f32_f16_sdwa v67, v77 dst_sel:DWORD dst_unused:UNUSED_PAD src0_sel:WORD_1
	v_pk_fma_f32 v[66:67], v[66:67], s[34:35], v[68:69] op_sel_hi:[1,0,1]
	s_nop 0
	v_cvt_pk_f16_f32 v73, v66, v67
	global_store_dwordx4 v[82:83], v[70:73], off offset:256
	s_nop 1
	v_lshl_add_u64 v[70:71], v[140:141], 0, s[16:17]
	v_lshl_add_u64 v[72:73], s[94:95], 0, v[70:71]
	s_waitcnt vmcnt(15)
	v_mov_b64_e32 v[66:67], v[190:191]
	v_mov_b64_e32 v[68:69], v[192:193]
	v_cvt_f32_f16_e32 v74, v66
	v_cvt_f32_f16_sdwa v75, v66 dst_sel:DWORD dst_unused:UNUSED_PAD src0_sel:WORD_1
	v_cvt_f32_f16_e32 v66, v67
	v_cvt_f32_f16_sdwa v67, v67 dst_sel:DWORD dst_unused:UNUSED_PAD src0_sel:WORD_1
	v_pk_fma_f32 v[62:63], v[74:75], s[34:35], v[62:63] op_sel_hi:[1,0,1]
	s_nop 0
	v_cvt_pk_f16_f32 v62, v62, v63
	v_pk_fma_f32 v[64:65], v[66:67], s[34:35], v[64:65] op_sel_hi:[1,0,1]
	v_lshl_add_u64 v[66:67], s[4:5], 0, v[70:71]
	v_cvt_pk_f16_f32 v63, v64, v65
	v_cvt_f32_f16_e32 v64, v68
	v_cvt_f32_f16_sdwa v65, v68 dst_sel:DWORD dst_unused:UNUSED_PAD src0_sel:WORD_1
	v_pk_fma_f32 v[58:59], v[64:65], s[34:35], v[58:59] op_sel_hi:[1,0,1]
	s_nop 0
	v_cvt_pk_f16_f32 v64, v58, v59
	v_cvt_f32_f16_e32 v58, v69
	v_cvt_f32_f16_sdwa v59, v69 dst_sel:DWORD dst_unused:UNUSED_PAD src0_sel:WORD_1
	v_pk_fma_f32 v[58:59], v[58:59], s[34:35], v[60:61] op_sel_hi:[1,0,1]
	s_nop 0
	v_cvt_pk_f16_f32 v65, v58, v59
	s_nop 0
	global_store_dwordx4 v[66:67], v[62:65], off
	s_waitcnt vmcnt(15)
	v_mov_b64_e32 v[58:59], v[194:195]
	v_mov_b64_e32 v[60:61], v[196:197]
	s_nop 0
	v_cvt_f32_f16_e32 v62, v58
	v_cvt_f32_f16_sdwa v63, v58 dst_sel:DWORD dst_unused:UNUSED_PAD src0_sel:WORD_1
	v_cvt_f32_f16_e32 v58, v59
	v_cvt_f32_f16_sdwa v59, v59 dst_sel:DWORD dst_unused:UNUSED_PAD src0_sel:WORD_1
	v_pk_fma_f32 v[54:55], v[62:63], s[34:35], v[54:55] op_sel_hi:[1,0,1]
	s_nop 0
	v_cvt_pk_f16_f32 v54, v54, v55
	v_pk_fma_f32 v[56:57], v[58:59], s[34:35], v[56:57] op_sel_hi:[1,0,1]
	s_nop 0
	v_cvt_pk_f16_f32 v55, v56, v57
	v_cvt_f32_f16_e32 v56, v60
	v_cvt_f32_f16_sdwa v57, v60 dst_sel:DWORD dst_unused:UNUSED_PAD src0_sel:WORD_1
	v_pk_fma_f32 v[50:51], v[56:57], s[34:35], v[50:51] op_sel_hi:[1,0,1]
	s_nop 0
	v_cvt_pk_f16_f32 v56, v50, v51
	v_cvt_f32_f16_e32 v50, v61
	v_cvt_f32_f16_sdwa v51, v61 dst_sel:DWORD dst_unused:UNUSED_PAD src0_sel:WORD_1
	v_pk_fma_f32 v[50:51], v[50:51], s[34:35], v[52:53] op_sel_hi:[1,0,1]
	s_nop 0
	v_cvt_pk_f16_f32 v57, v50, v51
	global_store_dwordx4 v[66:67], v[54:57], off offset:256
	s_nop 1
	v_lshl_add_u64 v[54:55], v[140:141], 0, s[18:19]
	v_lshl_add_u64 v[56:57], s[94:95], 0, v[54:55]
	s_waitcnt vmcnt(15)
; template <class Epi, class AMap>
; __device__ __forceinline__ void gemm_phase(LAS unsigned char* lds, const AMap am, const int lda, const h16* Bt, const int ldb, const int M, const int N, const int K, const Epi& E) {
;     ...
;         if (!has_next) break;
; #pragma unroll
;         for (int a = 0; a < 2; ++a)
; #pragma unroll
;             for (int b = 0; b < 2; ++b)
; #pragma unroll
;                 for (int m = 0; m < 4; ++m)
; #pragma unroll
;                     for (int n = 0; n < 2; ++n) acc[a][b][m][n] = (f32x4){0.f, 0.f, 0.f, 0.f};
;         cur = nxt; cA = nA; cB = nB; ++ui;
;     }
;     __device__ __forceinline__ void operator()(const f32x4 (&acc)[2][2][4][2], const Unit& u, int wr, int wc, int fr, int fq) const {
;     ...
;             for (int m = 0; m < 4; ++m) { const size_t off = (size_t)(row0 + ai * 128 + m * 16) * DM + colt;
; #pragma unroll
;                 for (int bj = 0; bj < 2; ++bj) {
;                     const h16x8 x = *(const h16x8*)(X + off + bj * 128);
;                     f32x4 o0, o1;
; #pragma unroll
;                     for (int e = 0; e < 4; ++e) { o0[e] = (float)x[e] * ALPHA + acc[ai][bj][m][0][e]; o1[e] = (float)x[4 + e] * ALPHA + acc[ai][bj][m][1][e]; }
;                     *(u32x4*)(PRE + off + bj * 128) = pack8(o0, o1); } }
	v_mov_b64_e32 v[50:51], v[198:199]
	v_mov_b64_e32 v[52:53], v[200:201]
	v_cvt_f32_f16_e32 v58, v50
	v_cvt_f32_f16_sdwa v59, v50 dst_sel:DWORD dst_unused:UNUSED_PAD src0_sel:WORD_1
	v_cvt_f32_f16_e32 v50, v51
	v_cvt_f32_f16_sdwa v51, v51 dst_sel:DWORD dst_unused:UNUSED_PAD src0_sel:WORD_1
	v_pk_fma_f32 v[46:47], v[58:59], s[34:35], v[46:47] op_sel_hi:[1,0,1]
	s_nop 0
	v_cvt_pk_f16_f32 v46, v46, v47
	v_pk_fma_f32 v[48:49], v[50:51], s[34:35], v[48:49] op_sel_hi:[1,0,1]
	v_lshl_add_u64 v[50:51], s[4:5], 0, v[54:55]
	v_cvt_pk_f16_f32 v47, v48, v49
	v_cvt_f32_f16_e32 v48, v52
	v_cvt_f32_f16_sdwa v49, v52 dst_sel:DWORD dst_unused:UNUSED_PAD src0_sel:WORD_1
	v_pk_fma_f32 v[42:43], v[48:49], s[34:35], v[42:43] op_sel_hi:[1,0,1]
	s_nop 0
	v_cvt_pk_f16_f32 v48, v42, v43
	v_cvt_f32_f16_e32 v42, v53
	v_cvt_f32_f16_sdwa v43, v53 dst_sel:DWORD dst_unused:UNUSED_PAD src0_sel:WORD_1
	v_pk_fma_f32 v[42:43], v[42:43], s[34:35], v[44:45] op_sel_hi:[1,0,1]
	s_nop 0
	v_cvt_pk_f16_f32 v49, v42, v43
	s_nop 0
	global_store_dwordx4 v[50:51], v[46:49], off
	s_waitcnt vmcnt(15)
	v_mov_b64_e32 v[42:43], v[202:203]
	v_mov_b64_e32 v[44:45], v[204:205]
	s_nop 0
	v_cvt_f32_f16_e32 v46, v42
	v_cvt_f32_f16_sdwa v47, v42 dst_sel:DWORD dst_unused:UNUSED_PAD src0_sel:WORD_1
	v_cvt_f32_f16_e32 v42, v43
	v_cvt_f32_f16_sdwa v43, v43 dst_sel:DWORD dst_unused:UNUSED_PAD src0_sel:WORD_1
	v_pk_fma_f32 v[38:39], v[46:47], s[34:35], v[38:39] op_sel_hi:[1,0,1]
	s_nop 0
	v_cvt_pk_f16_f32 v38, v38, v39
	v_pk_fma_f32 v[40:41], v[42:43], s[34:35], v[40:41] op_sel_hi:[1,0,1]
	s_nop 0
	v_cvt_pk_f16_f32 v39, v40, v41
	v_cvt_f32_f16_e32 v40, v44
	v_cvt_f32_f16_sdwa v41, v44 dst_sel:DWORD dst_unused:UNUSED_PAD src0_sel:WORD_1
	v_pk_fma_f32 v[34:35], v[40:41], s[34:35], v[34:35] op_sel_hi:[1,0,1]
	s_nop 0
	v_cvt_pk_f16_f32 v40, v34, v35
	v_cvt_f32_f16_e32 v34, v45
	v_cvt_f32_f16_sdwa v35, v45 dst_sel:DWORD dst_unused:UNUSED_PAD src0_sel:WORD_1
	v_pk_fma_f32 v[34:35], v[34:35], s[34:35], v[36:37] op_sel_hi:[1,0,1]
	s_nop 0
	v_cvt_pk_f16_f32 v41, v34, v35
	global_store_dwordx4 v[50:51], v[38:41], off offset:256
	s_nop 1
	v_lshl_add_u64 v[38:39], v[140:141], 0, s[8:9]
	v_lshl_add_u64 v[40:41], s[94:95], 0, v[38:39]
	s_waitcnt vmcnt(15)
	v_mov_b64_e32 v[34:35], v[212:213]
	v_mov_b64_e32 v[36:37], v[214:215]
	v_cvt_f32_f16_e32 v42, v34
	v_cvt_f32_f16_sdwa v43, v34 dst_sel:DWORD dst_unused:UNUSED_PAD src0_sel:WORD_1
	v_cvt_f32_f16_e32 v34, v35
	v_cvt_f32_f16_sdwa v35, v35 dst_sel:DWORD dst_unused:UNUSED_PAD src0_sel:WORD_1
	v_pk_fma_f32 v[30:31], v[42:43], s[34:35], v[30:31] op_sel_hi:[1,0,1]
	s_nop 0
	v_cvt_pk_f16_f32 v30, v30, v31
	v_pk_fma_f32 v[32:33], v[34:35], s[34:35], v[32:33] op_sel_hi:[1,0,1]
	v_lshl_add_u64 v[34:35], s[4:5], 0, v[38:39]
	v_cvt_pk_f16_f32 v31, v32, v33
	v_cvt_f32_f16_e32 v32, v36
	v_cvt_f32_f16_sdwa v33, v36 dst_sel:DWORD dst_unused:UNUSED_PAD src0_sel:WORD_1
	v_pk_fma_f32 v[26:27], v[32:33], s[34:35], v[26:27] op_sel_hi:[1,0,1]
	s_nop 0
	v_cvt_pk_f16_f32 v32, v26, v27
	v_cvt_f32_f16_e32 v26, v37
	v_cvt_f32_f16_sdwa v27, v37 dst_sel:DWORD dst_unused:UNUSED_PAD src0_sel:WORD_1
	v_pk_fma_f32 v[26:27], v[26:27], s[34:35], v[28:29] op_sel_hi:[1,0,1]
	s_nop 0
	v_cvt_pk_f16_f32 v33, v26, v27
	s_nop 0
	global_store_dwordx4 v[34:35], v[30:33], off
	s_waitcnt vmcnt(15)
	v_mov_b64_e32 v[26:27], v[220:221]
	v_mov_b64_e32 v[28:29], v[222:223]
	s_nop 0
	v_cvt_f32_f16_e32 v30, v26
	v_cvt_f32_f16_sdwa v31, v26 dst_sel:DWORD dst_unused:UNUSED_PAD src0_sel:WORD_1
	v_cvt_f32_f16_e32 v26, v27
	v_cvt_f32_f16_sdwa v27, v27 dst_sel:DWORD dst_unused:UNUSED_PAD src0_sel:WORD_1
	v_pk_fma_f32 v[22:23], v[30:31], s[34:35], v[22:23] op_sel_hi:[1,0,1]
	s_nop 0
	v_cvt_pk_f16_f32 v22, v22, v23
	v_pk_fma_f32 v[24:25], v[26:27], s[34:35], v[24:25] op_sel_hi:[1,0,1]
	s_nop 0
	v_cvt_pk_f16_f32 v23, v24, v25
	v_cvt_f32_f16_e32 v24, v28
	v_cvt_f32_f16_sdwa v25, v28 dst_sel:DWORD dst_unused:UNUSED_PAD src0_sel:WORD_1
	v_pk_fma_f32 v[18:19], v[24:25], s[34:35], v[18:19] op_sel_hi:[1,0,1]
	s_nop 0
	v_cvt_pk_f16_f32 v24, v18, v19
	v_cvt_f32_f16_e32 v18, v29
	v_cvt_f32_f16_sdwa v19, v29 dst_sel:DWORD dst_unused:UNUSED_PAD src0_sel:WORD_1
	v_pk_fma_f32 v[18:19], v[18:19], s[34:35], v[20:21] op_sel_hi:[1,0,1]
	s_nop 0
	v_cvt_pk_f16_f32 v25, v18, v19
	global_store_dwordx4 v[34:35], v[22:25], off offset:256
	s_nop 1
	v_lshl_add_u64 v[22:23], v[140:141], 0, s[2:3]
	v_lshl_add_u64 v[24:25], s[94:95], 0, v[22:23]
	s_waitcnt vmcnt(15)
	v_mov_b64_e32 v[18:19], v[224:225]
	v_mov_b64_e32 v[20:21], v[226:227]
	v_cvt_f32_f16_e32 v26, v18
	v_cvt_f32_f16_sdwa v27, v18 dst_sel:DWORD dst_unused:UNUSED_PAD src0_sel:WORD_1
	v_cvt_f32_f16_e32 v18, v19
	v_cvt_f32_f16_sdwa v19, v19 dst_sel:DWORD dst_unused:UNUSED_PAD src0_sel:WORD_1
	v_pk_fma_f32 v[14:15], v[26:27], s[34:35], v[14:15] op_sel_hi:[1,0,1]
	s_nop 0
	v_cvt_pk_f16_f32 v14, v14, v15
	v_pk_fma_f32 v[16:17], v[18:19], s[34:35], v[16:17] op_sel_hi:[1,0,1]
	v_lshl_add_u64 v[18:19], s[4:5], 0, v[22:23]
	v_cvt_pk_f16_f32 v15, v16, v17
	v_cvt_f32_f16_e32 v16, v20
	v_cvt_f32_f16_sdwa v17, v20 dst_sel:DWORD dst_unused:UNUSED_PAD src0_sel:WORD_1
	v_pk_fma_f32 v[10:11], v[16:17], s[34:35], v[10:11] op_sel_hi:[1,0,1]
	s_nop 0
	v_cvt_pk_f16_f32 v16, v10, v11
	v_cvt_f32_f16_e32 v10, v21
	v_cvt_f32_f16_sdwa v11, v21 dst_sel:DWORD dst_unused:UNUSED_PAD src0_sel:WORD_1
	v_pk_fma_f32 v[10:11], v[10:11], s[34:35], v[12:13] op_sel_hi:[1,0,1]
	s_nop 0
	v_cvt_pk_f16_f32 v17, v10, v11
	s_nop 0
	global_store_dwordx4 v[18:19], v[14:17], off
	s_waitcnt vmcnt(15)
	v_mov_b64_e32 v[10:11], v[228:229]
	v_mov_b64_e32 v[12:13], v[230:231]
	s_nop 0
	v_cvt_f32_f16_e32 v14, v10
	v_cvt_f32_f16_sdwa v15, v10 dst_sel:DWORD dst_unused:UNUSED_PAD src0_sel:WORD_1
	v_cvt_f32_f16_e32 v10, v11
	v_cvt_f32_f16_sdwa v11, v11 dst_sel:DWORD dst_unused:UNUSED_PAD src0_sel:WORD_1
	v_pk_fma_f32 v[6:7], v[14:15], s[34:35], v[6:7] op_sel_hi:[1,0,1]
	s_nop 0
	v_cvt_pk_f16_f32 v6, v6, v7
	v_pk_fma_f32 v[8:9], v[10:11], s[34:35], v[8:9] op_sel_hi:[1,0,1]
	s_nop 0
	v_cvt_pk_f16_f32 v7, v8, v9
	v_cvt_f32_f16_e32 v8, v12
	v_cvt_f32_f16_sdwa v9, v12 dst_sel:DWORD dst_unused:UNUSED_PAD src0_sel:WORD_1
	v_pk_fma_f32 v[2:3], v[8:9], s[34:35], v[2:3] op_sel_hi:[1,0,1]
	s_nop 0
	v_cvt_pk_f16_f32 v8, v2, v3
	v_cvt_f32_f16_e32 v2, v13
	v_cvt_f32_f16_sdwa v3, v13 dst_sel:DWORD dst_unused:UNUSED_PAD src0_sel:WORD_1
	v_pk_fma_f32 v[2:3], v[2:3], s[34:35], v[4:5] op_sel_hi:[1,0,1]
	s_nop 0
	v_cvt_pk_f16_f32 v9, v2, v3
	s_mov_b32 s35, s0
	global_store_dwordx4 v[18:19], v[6:9], off offset:256
	s_cmpk_lt_u32 s62, 0x100
	s_cbranch_scc1 .Lgy2
	s_barrier
.Lgy2:
	s_cbranch_vccz .LBB0_140
	s_waitcnt vmcnt(0)
	s_cmpk_gt_u32 s62, 0xff
	s_cbranch_scc1 .LBB0_151
	s_barrier

; template <class Epi, class AMap>
; __device__ __forceinline__ void gemm_phase(LAS unsigned char* lds, const AMap am, const int lda, const h16* Bt, const int ldb, const int M, const int N, const int K, const Epi& E) {
;     ...
;         if (!has_next) break;
; #pragma unroll
;         for (int a = 0; a < 2; ++a)
; #pragma unroll
;             for (int b = 0; b < 2; ++b)
; #pragma unroll
;                 for (int m = 0; m < 4; ++m)
; #pragma unroll
;                     for (int n = 0; n < 2; ++n) acc[a][b][m][n] = (f32x4){0.f, 0.f, 0.f, 0.f};
;         cur = nxt; cA = nA; cB = nB; ++ui;
;     }
.LBB0_264:
	s_and_b64 vcc, exec, s[38:39]
	s_mov_b32 s22, s0
	s_mov_b32 s26, s44
	s_mov_b64 s[42:43], s[70:71]
	s_mov_b64 s[40:41], s[68:69]
	s_cmpk_lt_u32 s64, 0x100
	s_cbranch_scc1 .Lgy3
	s_barrier

; #define PG8_STAGE(bufoff, gbase, voff) do { _Pragma("unroll") for (int _i = 0; _i < 2; ++_i) \
;         __builtin_amdgcn_global_load_lds((const unsigned*)((const char*)(gbase) + (voff)[_i]), (LAS unsigned*)(lds + (bufoff) + ldsw + _i * 8192), 16, 0, 0); } while (0)
; #define PG8_LDA(dst, b, h) do { _Pragma("unroll") for (int m = 0; m < 4; ++m) _Pragma("unroll") for (int k = 0; k < 2; ++k) dst[m][k] = *(const LAS h16x8*)(lds + PG8_SA(b, h) + aoff + m * 2048 + k * 1024); } while (0)
; #define PG8_LDB(dst, b, h) do { _Pragma("unroll") for (int n = 0; n < 2; ++n) _Pragma("unroll") for (int k = 0; k < 2; ++k) dst[n][k] = *(const LAS h16x8*)(lds + PG8_SB(b, h) + boff + n * 2048 + k * 1024); } while (0)
; #define PG8_MMA(ai, bj, At, Bt_) do { __builtin_amdgcn_s_setprio(1); _Pragma("unroll") for (int m = 0; m < 4; ++m) _Pragma("unroll") for (int n = 0; n < 2; ++n) _Pragma("unroll") for (int k = 0; k < 2; ++k) \
;         acc[ai][bj][m][n] = __builtin_amdgcn_mfma_f32_16x16x32_f16(Bt_[n][k], At[m][k], acc[ai][bj][m][n], 0, 0, 0); __builtin_amdgcn_s_setprio(0); } while (0)
; #define PG8_WAIT_V(n) asm volatile("s_waitcnt vmcnt(" #n ")" ::: "memory")
; template <class Epi, class AMap>
; __device__ __forceinline__ void gemm_phase(LAS unsigned char* lds, const AMap am, const int lda, const h16* Bt, const int ldb, const int M, const int N, const int K, const Epi& E) {
;     ...
;         for (int t = 0; t < nt; t += 2) {
;             const bool last = (t == nt - 2);
;             const char* a1 = cA + (size_t)(t + 1) * kstep;
;             const char* a2 = last ? nA : cA + (size_t)(t + 2) * kstep; const char* b2 = last ? nB : cB + (size_t)(t + 2) * kstep;
;             const char* a3 = a2 + kstep; const char* b3 = b2 + kstep;
;             PG8_LDB(B0, 0, 0); PG8_SCHED; PG8_LDA(At, 0, 0); PG8_STAGE(PG8_SA(1, 1), a1 + hstepA, voffA);
;             PG8_WAIT_L(8); PG8_BAR; PG8_WAIT_L(0); PG8_MMA(0, 0, At, B0); PG8_BAR; PG8_SCHED;
;             PG8_LDB(B1, 0, 1); PG8_STAGE(PG8_SB(0, 0), b2, voffB);
;             PG8_BAR; PG8_WAIT_L(0); PG8_MMA(0, 1, At, B1); PG8_BAR;
;             PG8_LDA(At, 0, 1); PG8_STAGE(PG8_SA(0, 0), a2, voffA);
;             PG8_BAR; PG8_WAIT_L(0); PG8_MMA(1, 0, At, B0); PG8_BAR; PG8_SCHED;
;             PG8_STAGE(PG8_SB(0, 1), b2 + hstepB, voffB);
;             PG8_WAIT_V(6); PG8_BAR; PG8_MMA(1, 1, At, B1); PG8_BAR;
.LBB0_268:
	s_add_u32 s42, s40, 0xfff80080
	s_addc_u32 s43, s41, -1
	s_add_i32 s45, 0, 0x10000
	v_add_u32_e32 v0, s45, v149
	ds_read_b128 v[142:145], v0
	ds_read_b128 v[154:157], v0 offset:1024
	ds_read_b128 v[158:161], v0 offset:2048
	ds_read_b128 v[162:165], v0 offset:3072
	s_cmp_eq_u32 s35, 28
	s_cselect_b32 s49, s23, s43
	s_cselect_b32 s48, s27, s42
	s_cselect_b32 s43, s1, s29
	s_cselect_b32 s42, s20, s21
	v_lshl_add_u64 v[146:147], s[40:41], 0, v[138:139]
	s_add_i32 m0, s72, 0xc000
	ds_read_b128 v[166:169], v153
	ds_read_b128 v[170:173], v153 offset:1024
	ds_read_b128 v[174:177], v153 offset:2048
	ds_read_b128 v[178:181], v153 offset:3072
	ds_read_b128 v[182:185], v153 offset:4096
	ds_read_b128 v[186:189], v153 offset:5120
	ds_read_b128 v[190:193], v153 offset:6144
	ds_read_b128 v[194:197], v153 offset:7168
	global_load_lds_dwordx4 v[146:147], off
	v_lshl_add_u64 v[146:147], s[40:41], 0, v[140:141]
	s_add_i32 m0, s72, 0xe000
	s_nop 0
	global_load_lds_dwordx4 v[146:147], off
	s_waitcnt lgkmcnt(11)
	s_add_i32 s60, 0, 0x14000
	s_add_i32 s45, s45, s65
	v_add_u32_e32 v0, s60, v149
	v_lshl_add_u64 v[146:147], s[42:43], 0, v[132:133]
	s_mov_b32 m0, s45
	ds_read_b128 v[198:201], v0
	ds_read_b128 v[202:205], v0 offset:1024
	ds_read_b128 v[220:223], v0 offset:2048
	ds_read_b128 v[224:227], v0 offset:3072
	s_waitcnt vmcnt(8) lgkmcnt(0)
	s_barrier
	v_mfma_f32_16x16x32_f16 v[126:129], v[142:145], v[166:169], v[126:129]
	v_mfma_f32_16x16x32_f16 v[122:125], v[158:161], v[166:169], v[122:125]
	v_mfma_f32_16x16x32_f16 v[110:113], v[142:145], v[174:177], v[110:113]
	v_mfma_f32_16x16x32_f16 v[106:109], v[158:161], v[174:177], v[106:109]
	v_mfma_f32_16x16x32_f16 v[94:97], v[142:145], v[182:185], v[94:97]
	v_mfma_f32_16x16x32_f16 v[90:93], v[158:161], v[182:185], v[90:93]
	v_mfma_f32_16x16x32_f16 v[78:81], v[142:145], v[190:193], v[78:81]
	v_mfma_f32_16x16x32_f16 v[74:77], v[158:161], v[190:193], v[74:77]
	v_mfma_f32_16x16x32_f16 v[126:129], v[154:157], v[170:173], v[126:129]
	v_mfma_f32_16x16x32_f16 v[122:125], v[162:165], v[170:173], v[122:125]
	v_mfma_f32_16x16x32_f16 v[110:113], v[154:157], v[178:181], v[110:113]
	v_mfma_f32_16x16x32_f16 v[106:109], v[162:165], v[178:181], v[106:109]
	v_mfma_f32_16x16x32_f16 v[94:97], v[154:157], v[186:189], v[94:97]
	v_mfma_f32_16x16x32_f16 v[90:93], v[162:165], v[186:189], v[90:93]
	v_mfma_f32_16x16x32_f16 v[78:81], v[154:157], v[194:197], v[78:81]
	v_mfma_f32_16x16x32_f16 v[74:77], v[162:165], v[194:197], v[74:77]
	v_mfma_f32_16x16x32_f16 v[118:121], v[198:201], v[166:169], v[118:121]
	v_mfma_f32_16x16x32_f16 v[114:117], v[220:223], v[166:169], v[114:117]
	v_mfma_f32_16x16x32_f16 v[102:105], v[198:201], v[174:177], v[102:105]
	v_mfma_f32_16x16x32_f16 v[98:101], v[220:223], v[174:177], v[98:101]
	v_mfma_f32_16x16x32_f16 v[86:89], v[198:201], v[182:185], v[86:89]
	v_mfma_f32_16x16x32_f16 v[82:85], v[220:223], v[182:185], v[82:85]
	v_mfma_f32_16x16x32_f16 v[70:73], v[198:201], v[190:193], v[70:73]
	v_mfma_f32_16x16x32_f16 v[66:69], v[220:223], v[190:193], v[66:69]
	v_mfma_f32_16x16x32_f16 v[118:121], v[202:205], v[170:173], v[118:121]
	v_mfma_f32_16x16x32_f16 v[114:117], v[224:227], v[170:173], v[114:117]
	v_mfma_f32_16x16x32_f16 v[102:105], v[202:205], v[178:181], v[102:105]
	v_mfma_f32_16x16x32_f16 v[98:101], v[224:227], v[178:181], v[98:101]
	v_mfma_f32_16x16x32_f16 v[86:89], v[202:205], v[186:189], v[86:89]
	v_mfma_f32_16x16x32_f16 v[82:85], v[224:227], v[186:189], v[82:85]
	v_mfma_f32_16x16x32_f16 v[70:73], v[202:205], v[194:197], v[70:73]
	v_mfma_f32_16x16x32_f16 v[66:69], v[224:227], v[194:197], v[66:69]
	s_barrier
	global_load_lds_dwordx4 v[146:147], off
	v_lshl_add_u64 v[206:207], s[42:43], 0, v[136:137]
	s_add_i32 m0, s45, 0x2000
	s_nop 0
	global_load_lds_dwordx4 v[206:207], off
	s_mov_b32 m0, s72
	v_lshl_add_u64 v[212:213], s[48:49], 0, v[130:131]
	ds_read_b128 v[166:169], v153 offset:16384
	ds_read_b128 v[170:173], v153 offset:17408
	ds_read_b128 v[174:177], v153 offset:18432
	ds_read_b128 v[178:181], v153 offset:19456
	ds_read_b128 v[182:185], v153 offset:20480
	ds_read_b128 v[186:189], v153 offset:21504
	ds_read_b128 v[190:193], v153 offset:22528
	ds_read_b128 v[194:197], v153 offset:23552
	global_load_lds_dwordx4 v[212:213], off
	v_lshl_add_u64 v[228:229], s[48:49], 0, v[134:135]
	s_mov_b32 m0, s73
	s_nop 0
	global_load_lds_dwordx4 v[228:229], off
	s_add_u32 s50, s42, 0x80000
	s_addc_u32 s51, s43, 0
	s_add_i32 s45, s60, s65
	v_lshl_add_u64 v[232:233], s[50:51], 0, v[132:133]
	s_mov_b32 m0, s45
	s_nop 0
	global_load_lds_dwordx4 v[232:233], off
	v_lshl_add_u64 v[232:233], s[50:51], 0, v[136:137]
	s_add_i32 m0, s45, 0x2000
	s_nop 0
	global_load_lds_dwordx4 v[232:233], off
	s_waitcnt vmcnt(8) lgkmcnt(0)
	s_barrier
; #define PG8_STAGE(bufoff, gbase, voff) do { _Pragma("unroll") for (int _i = 0; _i < 2; ++_i) \
;         __builtin_amdgcn_global_load_lds((const unsigned*)((const char*)(gbase) + (voff)[_i]), (LAS unsigned*)(lds + (bufoff) + ldsw + _i * 8192), 16, 0, 0); } while (0)
; #define PG8_LDA(dst, b, h) do { _Pragma("unroll") for (int m = 0; m < 4; ++m) _Pragma("unroll") for (int k = 0; k < 2; ++k) dst[m][k] = *(const LAS h16x8*)(lds + PG8_SA(b, h) + aoff + m * 2048 + k * 1024); } while (0)
; #define PG8_LDB(dst, b, h) do { _Pragma("unroll") for (int n = 0; n < 2; ++n) _Pragma("unroll") for (int k = 0; k < 2; ++k) dst[n][k] = *(const LAS h16x8*)(lds + PG8_SB(b, h) + boff + n * 2048 + k * 1024); } while (0)
; #define PG8_MMA(ai, bj, At, Bt_) do { __builtin_amdgcn_s_setprio(1); _Pragma("unroll") for (int m = 0; m < 4; ++m) _Pragma("unroll") for (int n = 0; n < 2; ++n) _Pragma("unroll") for (int k = 0; k < 2; ++k) \
;         acc[ai][bj][m][n] = __builtin_amdgcn_mfma_f32_16x16x32_f16(Bt_[n][k], At[m][k], acc[ai][bj][m][n], 0, 0, 0); __builtin_amdgcn_s_setprio(0); } while (0)
; #define PG8_WAIT_V(n) asm volatile("s_waitcnt vmcnt(" #n ")" ::: "memory")
; #define PG8_WAIT_L(n) asm volatile("s_waitcnt lgkmcnt(" #n ")" ::: "memory")
; #define PG8_BAR __builtin_amdgcn_s_barrier()
; #define PG8_SCHED __builtin_amdgcn_sched_barrier(0)
; template <class Epi, class AMap>
; __device__ __forceinline__ void gemm_phase(LAS unsigned char* lds, const AMap am, const int lda, const h16* Bt, const int ldb, const int M, const int N, const int K, const Epi& E) {
;     ...
;             PG8_BAR; PG8_WAIT_L(0); PG8_MMA(0, 1, At, B1); PG8_BAR;
;             PG8_LDA(At, 0, 1); PG8_STAGE(PG8_SA(0, 0), a2, voffA);
;             PG8_BAR; PG8_WAIT_L(0); PG8_MMA(1, 0, At, B0); PG8_BAR; PG8_SCHED;
;             PG8_STAGE(PG8_SB(0, 1), b2 + hstepB, voffB);
;             PG8_WAIT_V(6); PG8_BAR; PG8_MMA(1, 1, At, B1); PG8_BAR;
;             PG8_LDB(B0, 1, 0); PG8_SCHED; PG8_LDA(At, 1, 0); PG8_STAGE(PG8_SA(0, 1), a2 + hstepA, voffA);
;             PG8_WAIT_L(8); PG8_BAR; PG8_WAIT_L(0); PG8_MMA(0, 0, At, B0); PG8_BAR; PG8_SCHED;
;             PG8_LDB(B1, 1, 1); PG8_STAGE(PG8_SB(1, 0), b3, voffB);
;             PG8_BAR; PG8_WAIT_L(0); PG8_MMA(0, 1, At, B1); PG8_BAR;
	v_mfma_f32_16x16x32_f16 v[62:65], v[142:145], v[166:169], v[62:65]
	v_mfma_f32_16x16x32_f16 v[58:61], v[158:161], v[166:169], v[58:61]
	v_mfma_f32_16x16x32_f16 v[46:49], v[142:145], v[174:177], v[46:49]
	v_mfma_f32_16x16x32_f16 v[42:45], v[158:161], v[174:177], v[42:45]
	v_mfma_f32_16x16x32_f16 v[30:33], v[142:145], v[182:185], v[30:33]
	v_mfma_f32_16x16x32_f16 v[26:29], v[158:161], v[182:185], v[26:29]
	v_mfma_f32_16x16x32_f16 v[14:17], v[142:145], v[190:193], v[14:17]
	v_mfma_f32_16x16x32_f16 v[10:13], v[158:161], v[190:193], v[10:13]
	v_mfma_f32_16x16x32_f16 v[62:65], v[154:157], v[170:173], v[62:65]
	v_mfma_f32_16x16x32_f16 v[58:61], v[162:165], v[170:173], v[58:61]
	v_mfma_f32_16x16x32_f16 v[46:49], v[154:157], v[178:181], v[46:49]
	v_mfma_f32_16x16x32_f16 v[42:45], v[162:165], v[178:181], v[42:45]
	v_mfma_f32_16x16x32_f16 v[30:33], v[154:157], v[186:189], v[30:33]
	v_mfma_f32_16x16x32_f16 v[26:29], v[162:165], v[186:189], v[26:29]
	v_mfma_f32_16x16x32_f16 v[14:17], v[154:157], v[194:197], v[14:17]
	v_mfma_f32_16x16x32_f16 v[10:13], v[162:165], v[194:197], v[10:13]
	v_mfma_f32_16x16x32_f16 v[54:57], v[198:201], v[166:169], v[54:57]
	v_mfma_f32_16x16x32_f16 v[50:53], v[220:223], v[166:169], v[50:53]
	v_mfma_f32_16x16x32_f16 v[38:41], v[198:201], v[174:177], v[38:41]
	v_mfma_f32_16x16x32_f16 v[34:37], v[220:223], v[174:177], v[34:37]
	v_mfma_f32_16x16x32_f16 v[22:25], v[198:201], v[182:185], v[22:25]
	v_mfma_f32_16x16x32_f16 v[18:21], v[220:223], v[182:185], v[18:21]
	v_mfma_f32_16x16x32_f16 v[6:9], v[198:201], v[190:193], v[6:9]
	v_mfma_f32_16x16x32_f16 v[2:5], v[220:223], v[190:193], v[2:5]
	v_mfma_f32_16x16x32_f16 v[54:57], v[202:205], v[170:173], v[54:57]
	v_mfma_f32_16x16x32_f16 v[50:53], v[224:227], v[170:173], v[50:53]
	v_mfma_f32_16x16x32_f16 v[38:41], v[202:205], v[178:181], v[38:41]
	v_mfma_f32_16x16x32_f16 v[34:37], v[224:227], v[178:181], v[34:37]
	v_mfma_f32_16x16x32_f16 v[22:25], v[202:205], v[186:189], v[22:25]
	v_mfma_f32_16x16x32_f16 v[18:21], v[224:227], v[186:189], v[18:21]
	v_mfma_f32_16x16x32_f16 v[6:9], v[202:205], v[194:197], v[6:9]
	v_mfma_f32_16x16x32_f16 v[2:5], v[224:227], v[194:197], v[2:5]
	s_barrier
	s_add_i32 s45, 0, 0x18000
	v_add_u32_e32 v0, s45, v149
	ds_read_b128 v[142:145], v0
	ds_read_b128 v[154:157], v0 offset:1024
	ds_read_b128 v[158:161], v0 offset:2048
	ds_read_b128 v[162:165], v0 offset:3072
	s_add_u32 s48, s48, 0x80000
	s_addc_u32 s49, s49, 0
	s_mov_b32 m0, s74
	v_lshl_add_u64 v[232:233], s[48:49], 0, v[130:131]
	ds_read_b128 v[166:169], v153 offset:32768
	ds_read_b128 v[170:173], v153 offset:33792
	ds_read_b128 v[174:177], v153 offset:34816
	ds_read_b128 v[178:181], v153 offset:35840
	ds_read_b128 v[182:185], v153 offset:36864
	ds_read_b128 v[186:189], v153 offset:37888
	ds_read_b128 v[190:193], v153 offset:38912
	ds_read_b128 v[194:197], v153 offset:39936
	global_load_lds_dwordx4 v[232:233], off
	v_lshl_add_u64 v[232:233], s[48:49], 0, v[134:135]
	s_mov_b32 m0, s75
	s_nop 0
	global_load_lds_dwordx4 v[232:233], off
	s_waitcnt lgkmcnt(11)
	s_add_i32 s48, 0, 0x1c000
	s_add_i32 s45, s45, s65
	v_add_u32_e32 v0, s48, v149
	v_lshl_add_u64 v[146:147], v[146:147], 0, s[92:93]
	s_mov_b32 m0, s45
	ds_read_b128 v[198:201], v0
	ds_read_b128 v[202:205], v0 offset:1024
	ds_read_b128 v[220:223], v0 offset:2048
	ds_read_b128 v[224:227], v0 offset:3072
	s_waitcnt vmcnt(8) lgkmcnt(0)
	s_barrier
	v_mfma_f32_16x16x32_f16 v[126:129], v[142:145], v[166:169], v[126:129]
	v_mfma_f32_16x16x32_f16 v[122:125], v[158:161], v[166:169], v[122:125]
	v_mfma_f32_16x16x32_f16 v[110:113], v[142:145], v[174:177], v[110:113]
	v_mfma_f32_16x16x32_f16 v[106:109], v[158:161], v[174:177], v[106:109]
	v_mfma_f32_16x16x32_f16 v[94:97], v[142:145], v[182:185], v[94:97]
	v_mfma_f32_16x16x32_f16 v[90:93], v[158:161], v[182:185], v[90:93]
	v_mfma_f32_16x16x32_f16 v[78:81], v[142:145], v[190:193], v[78:81]
	v_mfma_f32_16x16x32_f16 v[74:77], v[158:161], v[190:193], v[74:77]
	v_mfma_f32_16x16x32_f16 v[126:129], v[154:157], v[170:173], v[126:129]
	v_mfma_f32_16x16x32_f16 v[122:125], v[162:165], v[170:173], v[122:125]
	v_mfma_f32_16x16x32_f16 v[110:113], v[154:157], v[178:181], v[110:113]
	v_mfma_f32_16x16x32_f16 v[106:109], v[162:165], v[178:181], v[106:109]
	v_mfma_f32_16x16x32_f16 v[94:97], v[154:157], v[186:189], v[94:97]
	v_mfma_f32_16x16x32_f16 v[90:93], v[162:165], v[186:189], v[90:93]
	v_mfma_f32_16x16x32_f16 v[78:81], v[154:157], v[194:197], v[78:81]
	v_mfma_f32_16x16x32_f16 v[74:77], v[162:165], v[194:197], v[74:77]
	v_mfma_f32_16x16x32_f16 v[118:121], v[198:201], v[166:169], v[118:121]
	v_mfma_f32_16x16x32_f16 v[114:117], v[220:223], v[166:169], v[114:117]
	v_mfma_f32_16x16x32_f16 v[102:105], v[198:201], v[174:177], v[102:105]
	v_mfma_f32_16x16x32_f16 v[98:101], v[220:223], v[174:177], v[98:101]
	v_mfma_f32_16x16x32_f16 v[86:89], v[198:201], v[182:185], v[86:89]
	v_mfma_f32_16x16x32_f16 v[82:85], v[220:223], v[182:185], v[82:85]
	v_mfma_f32_16x16x32_f16 v[70:73], v[198:201], v[190:193], v[70:73]
	v_mfma_f32_16x16x32_f16 v[66:69], v[220:223], v[190:193], v[66:69]
	v_mfma_f32_16x16x32_f16 v[118:121], v[202:205], v[170:173], v[118:121]
	v_mfma_f32_16x16x32_f16 v[114:117], v[224:227], v[170:173], v[114:117]
	v_mfma_f32_16x16x32_f16 v[102:105], v[202:205], v[178:181], v[102:105]
	v_mfma_f32_16x16x32_f16 v[98:101], v[224:227], v[178:181], v[98:101]
	v_mfma_f32_16x16x32_f16 v[86:89], v[202:205], v[186:189], v[86:89]
	v_mfma_f32_16x16x32_f16 v[82:85], v[224:227], v[186:189], v[82:85]
	v_mfma_f32_16x16x32_f16 v[70:73], v[202:205], v[194:197], v[70:73]
	v_mfma_f32_16x16x32_f16 v[66:69], v[224:227], v[194:197], v[66:69]
	s_barrier
; #define PG8_STAGE(bufoff, gbase, voff) do { _Pragma("unroll") for (int _i = 0; _i < 2; ++_i) \
;         __builtin_amdgcn_global_load_lds((const unsigned*)((const char*)(gbase) + (voff)[_i]), (LAS unsigned*)(lds + (bufoff) + ldsw + _i * 8192), 16, 0, 0); } while (0)
; #define PG8_LDA(dst, b, h) do { _Pragma("unroll") for (int m = 0; m < 4; ++m) _Pragma("unroll") for (int k = 0; k < 2; ++k) dst[m][k] = *(const LAS h16x8*)(lds + PG8_SA(b, h) + aoff + m * 2048 + k * 1024); } while (0)
; #define PG8_BAR __builtin_amdgcn_s_barrier()
; template <class Epi, class AMap>
; __device__ __forceinline__ void gemm_phase(LAS unsigned char* lds, const AMap am, const int lda, const h16* Bt, const int ldb, const int M, const int N, const int K, const Epi& E) {
;     ...
;             PG8_BAR; PG8_WAIT_L(0); PG8_MMA(0, 1, At, B1); PG8_BAR;
;             PG8_LDA(At, 1, 1); PG8_STAGE(PG8_SA(1, 0), a3, voffA);
;             PG8_BAR; PG8_WAIT_L(0); PG8_MMA(1, 0, At, B0); PG8_BAR; PG8_SCHED;
;             PG8_STAGE(PG8_SB(1, 1), b3 + hstepB, voffB);
;             PG8_WAIT_V(6); PG8_BAR; PG8_MMA(1, 1, At, B1); PG8_BAR;
;         }
;     __device__ __forceinline__ void operator()(const f32x4 (&acc)[2][2][4][2], const Unit& u, int wr, int wc, int fr, int fq) const {
;         const int row0 = u.pm * 256 + wr * 64 + fr; const int part = u.pn >> 3; const int colt = (u.pn & 7) * 256 + wc * 32 + 8 * fq;
; #pragma unroll
;         for (int ai = 0; ai < 2; ++ai)
; #pragma unroll
;             for (int m = 0; m < 4; ++m) { const int row = row0 + ai * 128 + m * 16;
; #pragma unroll
;                 for (int bj = 0; bj < 2; ++bj) { const int c = colt + bj * 128;
;                     if (part == 0) *(u32x4*)(Qb + (size_t)row * DM + c) = pack8(acc[ai][bj][m][0] * QSCALE, acc[ai][bj][m][1] * QSCALE);
;                     else if (part == 1) *(u32x4*)(Kb + (size_t)row * DM + c) = pack8(acc[ai][bj][m][0], acc[ai][bj][m][1]);
;                     else {
;                         const int b = row >> 13, t = row & 8191, hd = c >> 8, dv = c & 255;
;                         const int pos = (t & ~12) | ((t & 4) << 1) | ((t & 8) >> 1);
;                         h16* vp = Vt + ((size_t)((b * 8 + hd) * 256 + dv)) * SEQ + pos;
; #pragma unroll
;                         for (int j = 0; j < 4; ++j) { vp[(size_t)j * SEQ] = (h16)acc[ai][bj][m][0][j]; vp[(size_t)(4 + j) * SEQ] = (h16)acc[ai][bj][m][1][j]; }
	global_load_lds_dwordx4 v[146:147], off
	v_lshl_add_u64 v[146:147], v[206:207], 0, s[92:93]
	s_add_i32 m0, s45, 0x2000
	s_nop 0
	global_load_lds_dwordx4 v[146:147], off
	s_mov_b32 m0, s77
	v_lshl_add_u64 v[146:147], v[212:213], 0, s[92:93]
	ds_read_b128 v[166:169], v153 offset:49152
	ds_read_b128 v[170:173], v153 offset:50176
	ds_read_b128 v[174:177], v153 offset:51200
	ds_read_b128 v[178:181], v153 offset:52224
	ds_read_b128 v[182:185], v153 offset:53248
	ds_read_b128 v[186:189], v153 offset:54272
	ds_read_b128 v[190:193], v153 offset:55296
	ds_read_b128 v[194:197], v153 offset:56320
	global_load_lds_dwordx4 v[146:147], off
	v_lshl_add_u64 v[146:147], v[228:229], 0, s[92:93]
	s_mov_b32 m0, s78
	s_nop 0
	global_load_lds_dwordx4 v[146:147], off
	s_add_u32 s42, s42, 0x80080
	s_addc_u32 s43, s43, 0
	s_add_i32 s45, s48, s65
	v_lshl_add_u64 v[232:233], s[42:43], 0, v[132:133]
	s_mov_b32 m0, s45
	s_nop 0
	global_load_lds_dwordx4 v[232:233], off
	v_lshl_add_u64 v[232:233], s[42:43], 0, v[136:137]
	s_add_i32 m0, s45, 0x2000
	s_nop 0
	global_load_lds_dwordx4 v[232:233], off
	s_waitcnt vmcnt(8) lgkmcnt(0)
	s_barrier
	v_mfma_f32_16x16x32_f16 v[62:65], v[142:145], v[166:169], v[62:65]
	v_mfma_f32_16x16x32_f16 v[58:61], v[158:161], v[166:169], v[58:61]
	v_mfma_f32_16x16x32_f16 v[46:49], v[142:145], v[174:177], v[46:49]
	v_mfma_f32_16x16x32_f16 v[42:45], v[158:161], v[174:177], v[42:45]
	v_mfma_f32_16x16x32_f16 v[30:33], v[142:145], v[182:185], v[30:33]
	v_mfma_f32_16x16x32_f16 v[26:29], v[158:161], v[182:185], v[26:29]
	v_mfma_f32_16x16x32_f16 v[14:17], v[142:145], v[190:193], v[14:17]
	v_mfma_f32_16x16x32_f16 v[10:13], v[158:161], v[190:193], v[10:13]
	v_mfma_f32_16x16x32_f16 v[62:65], v[154:157], v[170:173], v[62:65]
	v_mfma_f32_16x16x32_f16 v[58:61], v[162:165], v[170:173], v[58:61]
	v_mfma_f32_16x16x32_f16 v[46:49], v[154:157], v[178:181], v[46:49]
	v_mfma_f32_16x16x32_f16 v[42:45], v[162:165], v[178:181], v[42:45]
	v_mfma_f32_16x16x32_f16 v[30:33], v[154:157], v[186:189], v[30:33]
	v_mfma_f32_16x16x32_f16 v[26:29], v[162:165], v[186:189], v[26:29]
	v_mfma_f32_16x16x32_f16 v[14:17], v[154:157], v[194:197], v[14:17]
	v_mfma_f32_16x16x32_f16 v[10:13], v[162:165], v[194:197], v[10:13]
	v_mfma_f32_16x16x32_f16 v[54:57], v[198:201], v[166:169], v[54:57]
	v_mfma_f32_16x16x32_f16 v[50:53], v[220:223], v[166:169], v[50:53]
	v_mfma_f32_16x16x32_f16 v[38:41], v[198:201], v[174:177], v[38:41]
	v_mfma_f32_16x16x32_f16 v[34:37], v[220:223], v[174:177], v[34:37]
	v_mfma_f32_16x16x32_f16 v[22:25], v[198:201], v[182:185], v[22:25]
	v_mfma_f32_16x16x32_f16 v[18:21], v[220:223], v[182:185], v[18:21]
	v_mfma_f32_16x16x32_f16 v[6:9], v[198:201], v[190:193], v[6:9]
	v_mfma_f32_16x16x32_f16 v[2:5], v[220:223], v[190:193], v[2:5]
	v_mfma_f32_16x16x32_f16 v[54:57], v[202:205], v[170:173], v[54:57]
	v_mfma_f32_16x16x32_f16 v[50:53], v[224:227], v[170:173], v[50:53]
	v_mfma_f32_16x16x32_f16 v[38:41], v[202:205], v[178:181], v[38:41]
	v_mfma_f32_16x16x32_f16 v[34:37], v[224:227], v[178:181], v[34:37]
	v_mfma_f32_16x16x32_f16 v[22:25], v[202:205], v[186:189], v[22:25]
	v_mfma_f32_16x16x32_f16 v[18:21], v[224:227], v[186:189], v[18:21]
	v_mfma_f32_16x16x32_f16 v[6:9], v[202:205], v[194:197], v[6:9]
	v_mfma_f32_16x16x32_f16 v[2:5], v[224:227], v[194:197], v[2:5]
	s_add_i32 s35, s35, 2
	s_add_u32 s40, s40, 0x100
	s_addc_u32 s41, s41, 0
	s_add_u32 s21, s21, 0x100
	s_addc_u32 s29, s29, 0
	s_cmp_gt_u32 s35, 29
	s_barrier
	s_cbranch_scc0 .LBB0_268
	s_cmpk_gt_u32 s64, 0xff
	s_cbranch_scc1 .Lgx3
	s_barrier
.Lgx3:
	s_lshl_b32 s1, s26, 8
	s_add_i32 s20, s1, s76
	s_lshl_b32 s1, s22, 8
	s_and_b32 s1, s1, 0x700
	s_cmp_gt_u32 s22, 7
	s_cselect_b64 s[26:27], -1, 0
	s_and_b32 s21, s22, -8
	v_or_b32_e32 v142, s20, v148
	s_cmp_lg_u32 s21, 8
	s_cselect_b64 s[22:23], -1, 0
	s_ashr_i32 s20, s20, 2
	v_ashrrev_i32_e32 v143, 31, v142
	v_or_b32_e32 v154, s1, v150
	s_and_b32 s35, s20, 0xfffff800
	v_and_or_b32 v155, v142, s5, v151
	v_lshlrev_b64 v[144:145], 12, v[142:143]
	s_mov_b64 s[40:41], -1
	s_and_b64 vcc, exec, s[26:27]
	s_cbranch_vccz .LBB0_275
	s_and_b64 vcc, exec, s[22:23]
	s_cbranch_vccz .LBB0_272
	v_or_b32_e32 v146, s35, v154
	v_ashrrev_i32_e32 v147, 31, v146
	v_lshlrev_b64 v[146:147], 14, v[146:147]
	v_lshl_add_u64 v[146:147], s[30:31], 0, v[146:147]
	v_lshlrev_b32_e32 v0, 1, v155
	v_lshl_add_u64 v[146:147], v[146:147], 0, v[0:1]
	v_cvt_f16_f32_e32 v0, v126
	v_add_co_u32_e32 v156, vcc, 0x10000, v146
	s_mov_b64 s[40:41], 0
	global_store_short v[146:147], v0, off
	v_cvt_f16_f32_e32 v0, v122
	v_addc_co_u32_e32 v157, vcc, 0, v147, vcc
	global_store_short v[156:157], v0, off
	v_cvt_f16_f32_e32 v0, v127
	v_add_co_u32_e32 v156, vcc, 0x4000, v146
	s_nop 1
	v_addc_co_u32_e32 v157, vcc, 0, v147, vcc
	global_store_short v[156:157], v0, off
	v_cvt_f16_f32_e32 v0, v123
	v_add_co_u32_e32 v156, vcc, 0x14000, v146
	s_nop 1
	v_addc_co_u32_e32 v157, vcc, 0, v147, vcc
	global_store_short v[156:157], v0, off
	v_cvt_f16_f32_e32 v0, v128
	v_add_co_u32_e32 v156, vcc, 0x8000, v146
	s_nop 1
	v_addc_co_u32_e32 v157, vcc, 0, v147, vcc
	global_store_short v[156:157], v0, off
	v_cvt_f16_f32_e32 v0, v124
	v_add_co_u32_e32 v156, vcc, 0x18000, v146
	s_nop 1
	v_addc_co_u32_e32 v157, vcc, 0, v147, vcc
	global_store_short v[156:157], v0, off
	v_cvt_f16_f32_e32 v0, v129
	v_add_co_u32_e32 v156, vcc, 0xc000, v146
	s_nop 1
	v_addc_co_u32_e32 v157, vcc, 0, v147, vcc
	global_store_short v[156:157], v0, off
	v_cvt_f16_f32_e32 v0, v125
	v_add_co_u32_e32 v146, vcc, 0x1c000, v146
	s_nop 1
	v_addc_co_u32_e32 v147, vcc, 0, v147, vcc
	global_store_short v[146:147], v0, off

; __device__ __forceinline__ float sigmoidf_(float x) { return 1.0f / (1.0f + __expf(-x)); }
;     template <int GI>
;     __device__ __forceinline__ void body(const f32x4 (&acc)[2][2][4][2], int row0, int colt) const {
;     ...
;         for (int bj = 0; bj < 2; ++bj) {
;             const int c = colt + bj * 128;
;             f32x4 b0 = (f32x4){0.f, 0.f, 0.f, 0.f}, b1 = b0;
;             if (GI == 0) { b0 = *(const f32x4*)(w0 + c); b1 = *(const f32x4*)(w0 + c + 4); }
;             else if (GI == 1) { b0 = *(const f32x4*)(a0 + c); b1 = *(const f32x4*)(a0 + c + 4); }
;             else if (GI == 3) { b0 = *(const f32x4*)(v0 + c); b1 = *(const f32x4*)(v0 + c + 4); }
; #pragma unroll
;             for (int ai = 0; ai < 2; ++ai)
; #pragma unroll
;                 for (int m = 0; m < 4; ++m) {
;                     const size_t row = (size_t)(row0 + ai * 128 + m * 16);
;                     f32x4 x0 = acc[ai][bj][m][0] + b0, x1 = acc[ai][bj][m][1] + b1;
;                     if (GI == 0) {
; #pragma unroll
;                         for (int j = 0; j < 4; ++j) {
;                             x0[j] = 0.6065306597126334f * sigmoidf_(x0[j]); x1[j] = 0.6065306597126334f * sigmoidf_(x1[j]); }
;                         *(u32x4*)(DEC + row * DM + c) = pack8(x0, x1);
.LBB0_610:
	v_lshl_or_b32 v152, s50, 8, v156
	v_ashrrev_i32_e32 v153, 31, v152
	v_lshl_add_u64 v[148:149], v[152:153], 2, s[40:41]
	global_load_dwordx4 v[90:93], v[148:149], off offset:16
	global_load_dwordx4 v[94:97], v[148:149], off
	s_mov_b32 s4, 0x3f1b4598
	v_lshl_add_u32 v150, s35, 8, v154
	v_ashrrev_i32_e32 v151, 31, v150
	v_readlane_b32 s6, v254, 56
	v_readlane_b32 s7, v254, 57
	s_waitcnt vmcnt(0)
	v_pk_add_f32 v[160:161], v[136:137], v[92:93]
	v_pk_add_f32 v[130:131], v[130:131], v[94:95]
	v_pk_add_f32 v[158:159], v[132:133], v[96:97]
	v_mul_f32_e32 v130, 0xbfb8aa3b, v130
	v_mul_f32_e32 v131, 0xbfb8aa3b, v131
	v_exp_f32_e32 v130, v130
	v_exp_f32_e32 v131, v131
	v_pk_add_f32 v[132:133], v[134:135], v[90:91]
	v_mul_f32_e32 v134, 0xbfb8aa3b, v158
	v_mul_f32_e32 v135, 0xbfb8aa3b, v159
	v_pk_add_f32 v[130:131], v[130:131], 1.0 op_sel_hi:[1,0]
	v_exp_f32_e32 v136, v134
	v_div_scale_f32 v158, s[0:1], v131, v131, 1.0
	v_rcp_f32_e32 v159, v158
	v_mul_f32_e32 v134, 0xbfb8aa3b, v160
	v_exp_f32_e32 v137, v135
	v_mul_f32_e32 v135, 0xbfb8aa3b, v161
	v_fma_f32 v160, -v158, v159, 1.0
	v_fmac_f32_e32 v159, v160, v159
	v_div_scale_f32 v160, vcc, 1.0, v131, 1.0
	v_mul_f32_e32 v161, v160, v159
	v_fma_f32 v162, -v158, v161, v160
	v_fmac_f32_e32 v161, v162, v159
	v_fma_f32 v158, -v158, v161, v160
	v_div_fmas_f32 v158, v158, v159, v161
	v_div_fixup_f32 v131, v158, v131, 1.0
	v_div_scale_f32 v158, s[0:1], v130, v130, 1.0
	v_rcp_f32_e32 v159, v158
	v_pk_add_f32 v[136:137], v[136:137], 1.0 op_sel_hi:[1,0]
	v_mul_f32_e32 v132, 0xbfb8aa3b, v132
	v_mul_f32_e32 v133, 0xbfb8aa3b, v133
	v_fma_f32 v160, -v158, v159, 1.0
	v_fmac_f32_e32 v159, v160, v159
	v_div_scale_f32 v160, vcc, 1.0, v130, 1.0
	v_mul_f32_e32 v161, v160, v159
	v_fma_f32 v162, -v158, v161, v160
	v_fmac_f32_e32 v161, v162, v159
	v_fma_f32 v158, -v158, v161, v160
	v_div_fmas_f32 v158, v158, v159, v161
	v_div_fixup_f32 v130, v158, v130, 1.0
	v_pk_mul_f32 v[130:131], v[130:131], s[4:5] op_sel_hi:[1,0]
	v_exp_f32_e32 v132, v132
	v_cvt_pk_f16_f32 v130, v130, v131
	v_div_scale_f32 v131, s[0:1], v137, v137, 1.0
	v_rcp_f32_e32 v158, v131
	v_exp_f32_e32 v133, v133
	v_exp_f32_e32 v134, v134
	v_exp_f32_e32 v135, v135
	v_fma_f32 v159, -v131, v158, 1.0
	v_fmac_f32_e32 v158, v159, v158
	v_div_scale_f32 v159, vcc, 1.0, v137, 1.0
	v_mul_f32_e32 v160, v159, v158
	v_fma_f32 v161, -v131, v160, v159
	v_fmac_f32_e32 v160, v161, v158
	v_fma_f32 v131, -v131, v160, v159
	v_div_fmas_f32 v131, v131, v158, v160
	v_div_fixup_f32 v137, v131, v137, 1.0
	v_div_scale_f32 v131, s[0:1], v136, v136, 1.0
	v_rcp_f32_e32 v158, v131
	v_pk_add_f32 v[132:133], v[132:133], 1.0 op_sel_hi:[1,0]
	v_pk_add_f32 v[134:135], v[134:135], 1.0 op_sel_hi:[1,0]
	v_fma_f32 v159, -v131, v158, 1.0
	v_fmac_f32_e32 v158, v159, v158
	v_div_scale_f32 v159, vcc, 1.0, v136, 1.0
	v_mul_f32_e32 v160, v159, v158
	v_fma_f32 v161, -v131, v160, v159
	v_fmac_f32_e32 v160, v161, v158
	v_fma_f32 v131, -v131, v160, v159
	v_div_fmas_f32 v131, v131, v158, v160
	v_div_fixup_f32 v136, v131, v136, 1.0
	v_pk_mul_f32 v[136:137], v[136:137], s[4:5] op_sel_hi:[1,0]
	s_nop 0
	v_cvt_pk_f16_f32 v131, v136, v137
	v_div_scale_f32 v136, s[0:1], v133, v133, 1.0
	v_rcp_f32_e32 v137, v136
	s_nop 0
	v_fma_f32 v158, -v136, v137, 1.0
	v_fmac_f32_e32 v137, v158, v137
	v_div_scale_f32 v158, vcc, 1.0, v133, 1.0
	v_mul_f32_e32 v159, v158, v137
	v_fma_f32 v160, -v136, v159, v158
	v_fmac_f32_e32 v159, v160, v137
	v_fma_f32 v136, -v136, v159, v158
	v_div_fmas_f32 v136, v136, v137, v159
	v_div_fixup_f32 v133, v136, v133, 1.0
	v_div_scale_f32 v136, s[0:1], v132, v132, 1.0
	v_rcp_f32_e32 v137, v136
	s_nop 0
	v_fma_f32 v158, -v136, v137, 1.0
	v_fmac_f32_e32 v137, v158, v137
	v_div_scale_f32 v158, vcc, 1.0, v132, 1.0
	v_mul_f32_e32 v159, v158, v137
	v_fma_f32 v160, -v136, v159, v158
	v_fmac_f32_e32 v159, v160, v137
	v_fma_f32 v136, -v136, v159, v158
	v_div_fmas_f32 v136, v136, v137, v159
	v_div_fixup_f32 v132, v136, v132, 1.0
	v_pk_mul_f32 v[132:133], v[132:133], s[4:5] op_sel_hi:[1,0]
	s_nop 0
	v_cvt_pk_f16_f32 v132, v132, v133
	v_div_scale_f32 v133, s[0:1], v135, v135, 1.0
	v_rcp_f32_e32 v136, v133
	s_nop 0
	v_fma_f32 v137, -v133, v136, 1.0
	v_fmac_f32_e32 v136, v137, v136
	v_div_scale_f32 v137, vcc, 1.0, v135, 1.0
	v_mul_f32_e32 v158, v137, v136
	v_fma_f32 v159, -v133, v158, v137
	v_fmac_f32_e32 v158, v159, v136
	v_fma_f32 v133, -v133, v158, v137
	v_div_fmas_f32 v133, v133, v136, v158
	v_div_fixup_f32 v135, v133, v135, 1.0
	v_div_scale_f32 v133, s[0:1], v134, v134, 1.0
	v_rcp_f32_e32 v136, v133
	s_nop 0
	v_fma_f32 v137, -v133, v136, 1.0
	v_fmac_f32_e32 v136, v137, v136
	v_div_scale_f32 v137, vcc, 1.0, v134, 1.0
	v_mul_f32_e32 v158, v137, v136
	v_fma_f32 v159, -v133, v158, v137
	v_fmac_f32_e32 v158, v159, v136
	v_fma_f32 v133, -v133, v158, v137
	v_div_fmas_f32 v133, v133, v136, v158
	v_div_fixup_f32 v134, v133, v134, 1.0
	v_pk_mul_f32 v[134:135], v[134:135], s[4:5] op_sel_hi:[1,0]
	v_lshlrev_b64 v[136:137], 1, v[152:153]
	v_cvt_pk_f16_f32 v133, v134, v135
	v_lshlrev_b64 v[134:135], 12, v[150:151]
	v_lshl_add_u64 v[134:135], s[6:7], 0, v[134:135]
	v_lshl_add_u64 v[134:135], v[134:135], 0, v[136:137]
	global_store_dwordx4 v[134:135], v[130:133], off
	v_pk_add_f32 v[122:123], v[122:123], v[90:91]
	v_pk_add_f32 v[126:127], v[126:127], v[94:95]
	v_mul_f32_e32 v122, 0xbfb8aa3b, v122
	v_exp_f32_e32 v152, v122
	v_mul_f32_e32 v122, 0xbfb8aa3b, v127
	v_pk_add_f32 v[128:129], v[128:129], v[96:97]
	v_mul_f32_e32 v126, 0xbfb8aa3b, v126
	v_exp_f32_e32 v133, v122
	v_mul_f32_e32 v122, 0xbfb8aa3b, v123
	v_pk_add_f32 v[124:125], v[124:125], v[92:93]
	v_exp_f32_e32 v132, v126
	v_exp_f32_e32 v153, v122
; __device__ __forceinline__ float sigmoidf_(float x) { return 1.0f / (1.0f + __expf(-x)); }
;     template <int GI>
;     __device__ __forceinline__ void body(const f32x4 (&acc)[2][2][4][2], int row0, int colt) const {
;     ...
;         for (int bj = 0; bj < 2; ++bj) {
;             const int c = colt + bj * 128;
;             f32x4 b0 = (f32x4){0.f, 0.f, 0.f, 0.f}, b1 = b0;
;             if (GI == 0) { b0 = *(const f32x4*)(w0 + c); b1 = *(const f32x4*)(w0 + c + 4); }
;             else if (GI == 1) { b0 = *(const f32x4*)(a0 + c); b1 = *(const f32x4*)(a0 + c + 4); }
;             else if (GI == 3) { b0 = *(const f32x4*)(v0 + c); b1 = *(const f32x4*)(v0 + c + 4); }
; #pragma unroll
;             for (int ai = 0; ai < 2; ++ai)
; #pragma unroll
;                 for (int m = 0; m < 4; ++m) {
;                     const size_t row = (size_t)(row0 + ai * 128 + m * 16);
;                     f32x4 x0 = acc[ai][bj][m][0] + b0, x1 = acc[ai][bj][m][1] + b1;
;                     if (GI == 0) {
; #pragma unroll
;                         for (int j = 0; j < 4; ++j) {
;                             x0[j] = 0.6065306597126334f * sigmoidf_(x0[j]); x1[j] = 0.6065306597126334f * sigmoidf_(x1[j]); }
;                         *(u32x4*)(DEC + row * DM + c) = pack8(x0, x1);
	v_mul_f32_e32 v122, 0xbfb8aa3b, v128
	v_exp_f32_e32 v128, v122
	v_mul_f32_e32 v122, 0xbfb8aa3b, v124
	v_exp_f32_e32 v126, v122
	v_mul_f32_e32 v122, 0xbfb8aa3b, v129
	v_exp_f32_e32 v129, v122
	v_mul_f32_e32 v122, 0xbfb8aa3b, v125
	v_exp_f32_e32 v127, v122
	v_pk_add_f32 v[122:123], v[132:133], 1.0 op_sel_hi:[1,0]
	v_or_b32_e32 v130, 16, v150
	v_div_scale_f32 v124, s[0:1], v123, v123, 1.0
	v_rcp_f32_e32 v125, v124
	v_pk_add_f32 v[126:127], v[126:127], 1.0 op_sel_hi:[1,0]
	v_ashrrev_i32_e32 v131, 31, v130
	v_fma_f32 v132, -v124, v125, 1.0
	v_fmac_f32_e32 v125, v132, v125
	v_div_scale_f32 v132, vcc, 1.0, v123, 1.0
	v_mul_f32_e32 v133, v132, v125
	v_fma_f32 v151, -v124, v133, v132
	v_fmac_f32_e32 v133, v151, v125
	v_fma_f32 v124, -v124, v133, v132
	v_div_fmas_f32 v124, v124, v125, v133
	v_div_fixup_f32 v123, v124, v123, 1.0
	v_div_scale_f32 v124, s[0:1], v122, v122, 1.0
	v_rcp_f32_e32 v125, v124
	s_nop 0
	v_fma_f32 v132, -v124, v125, 1.0
	v_fmac_f32_e32 v125, v132, v125
	v_div_scale_f32 v132, vcc, 1.0, v122, 1.0
	v_mul_f32_e32 v133, v132, v125
	v_fma_f32 v151, -v124, v133, v132
	v_fmac_f32_e32 v133, v151, v125
	v_fma_f32 v124, -v124, v133, v132
	v_div_fmas_f32 v124, v124, v125, v133
	v_div_fixup_f32 v122, v124, v122, 1.0
	v_pk_mul_f32 v[122:123], v[122:123], s[4:5] op_sel_hi:[1,0]
	v_pk_add_f32 v[124:125], v[128:129], 1.0 op_sel_hi:[1,0]
	v_cvt_pk_f16_f32 v122, v122, v123
	v_div_scale_f32 v123, s[0:1], v125, v125, 1.0
	v_rcp_f32_e32 v128, v123
	s_nop 0
	v_fma_f32 v129, -v123, v128, 1.0
	v_fmac_f32_e32 v128, v129, v128
	v_div_scale_f32 v129, vcc, 1.0, v125, 1.0
	v_mul_f32_e32 v132, v129, v128
	v_fma_f32 v133, -v123, v132, v129
	v_fmac_f32_e32 v132, v133, v128
	v_fma_f32 v123, -v123, v132, v129
	v_div_fmas_f32 v123, v123, v128, v132
	v_div_fixup_f32 v125, v123, v125, 1.0
	v_div_scale_f32 v123, s[0:1], v124, v124, 1.0
	v_rcp_f32_e32 v128, v123
	s_nop 0
	v_fma_f32 v129, -v123, v128, 1.0
	v_fmac_f32_e32 v128, v129, v128
	v_div_scale_f32 v129, vcc, 1.0, v124, 1.0
	v_mul_f32_e32 v132, v129, v128
	v_fma_f32 v133, -v123, v132, v129
	v_fmac_f32_e32 v132, v133, v128
	v_fma_f32 v123, -v123, v132, v129
	v_div_fmas_f32 v123, v123, v128, v132
	v_div_fixup_f32 v124, v123, v124, 1.0
	v_pk_mul_f32 v[124:125], v[124:125], s[4:5] op_sel_hi:[1,0]
	s_nop 0
	v_cvt_pk_f16_f32 v123, v124, v125
	v_pk_add_f32 v[124:125], v[152:153], 1.0 op_sel_hi:[1,0]
	s_nop 0
	v_div_scale_f32 v128, s[0:1], v125, v125, 1.0
	v_rcp_f32_e32 v129, v128
	s_nop 0
	v_fma_f32 v132, -v128, v129, 1.0
	v_fmac_f32_e32 v129, v132, v129
	v_div_scale_f32 v132, vcc, 1.0, v125, 1.0
	v_mul_f32_e32 v133, v132, v129
	v_fma_f32 v151, -v128, v133, v132
	v_fmac_f32_e32 v133, v151, v129
	v_fma_f32 v128, -v128, v133, v132
	v_div_fmas_f32 v128, v128, v129, v133
	v_div_fixup_f32 v125, v128, v125, 1.0
	v_div_scale_f32 v128, s[0:1], v124, v124, 1.0
	v_rcp_f32_e32 v129, v128
	s_nop 0
	v_fma_f32 v132, -v128, v129, 1.0
	v_fmac_f32_e32 v129, v132, v129
	v_div_scale_f32 v132, vcc, 1.0, v124, 1.0
	v_mul_f32_e32 v133, v132, v129
	v_fma_f32 v151, -v128, v133, v132
	v_fmac_f32_e32 v133, v151, v129
	v_fma_f32 v128, -v128, v133, v132
	v_div_fmas_f32 v128, v128, v129, v133
	v_div_fixup_f32 v124, v128, v124, 1.0
	v_pk_mul_f32 v[124:125], v[124:125], s[4:5] op_sel_hi:[1,0]
	s_nop 0
	v_cvt_pk_f16_f32 v124, v124, v125
	v_div_scale_f32 v125, s[0:1], v127, v127, 1.0
	v_rcp_f32_e32 v128, v125
	s_nop 0
	v_fma_f32 v129, -v125, v128, 1.0
	v_fmac_f32_e32 v128, v129, v128
	v_div_scale_f32 v129, vcc, 1.0, v127, 1.0
	v_mul_f32_e32 v132, v129, v128
	v_fma_f32 v133, -v125, v132, v129
	v_fmac_f32_e32 v132, v133, v128
	v_fma_f32 v125, -v125, v132, v129
	v_div_fmas_f32 v125, v125, v128, v132
	v_div_fixup_f32 v127, v125, v127, 1.0
	v_div_scale_f32 v125, s[0:1], v126, v126, 1.0
	v_rcp_f32_e32 v128, v125
	s_nop 0
	v_fma_f32 v129, -v125, v128, 1.0
	v_fmac_f32_e32 v128, v129, v128
	v_div_scale_f32 v129, vcc, 1.0, v126, 1.0
	v_mul_f32_e32 v132, v129, v128
	v_fma_f32 v133, -v125, v132, v129
	v_fmac_f32_e32 v132, v133, v128
	v_fma_f32 v125, -v125, v132, v129
	v_div_fmas_f32 v125, v125, v128, v132
	v_div_fixup_f32 v126, v125, v126, 1.0
	v_pk_mul_f32 v[126:127], v[126:127], s[4:5] op_sel_hi:[1,0]
	s_nop 0
	v_cvt_pk_f16_f32 v125, v126, v127
	v_lshlrev_b64 v[126:127], 12, v[130:131]
	v_lshl_add_u64 v[126:127], s[6:7], 0, v[126:127]
	v_lshl_add_u64 v[126:127], v[126:127], 0, v[136:137]
	global_store_dwordx4 v[126:127], v[122:125], off
	v_pk_add_f32 v[114:115], v[114:115], v[90:91]
	v_pk_add_f32 v[118:119], v[118:119], v[94:95]
	v_mul_f32_e32 v114, 0xbfb8aa3b, v114
	v_exp_f32_e32 v128, v114
	v_mul_f32_e32 v114, 0xbfb8aa3b, v119
	v_pk_add_f32 v[120:121], v[120:121], v[96:97]
	v_mul_f32_e32 v118, 0xbfb8aa3b, v118
	v_exp_f32_e32 v125, v114
	v_mul_f32_e32 v114, 0xbfb8aa3b, v115
	v_pk_add_f32 v[116:117], v[116:117], v[92:93]
	v_exp_f32_e32 v124, v118
	v_exp_f32_e32 v129, v114
	v_mul_f32_e32 v114, 0xbfb8aa3b, v120
	v_exp_f32_e32 v120, v114
	v_mul_f32_e32 v114, 0xbfb8aa3b, v116
	v_exp_f32_e32 v118, v114
	v_mul_f32_e32 v114, 0xbfb8aa3b, v121
	v_exp_f32_e32 v121, v114
	v_mul_f32_e32 v114, 0xbfb8aa3b, v117
	v_exp_f32_e32 v119, v114
	v_pk_add_f32 v[114:115], v[124:125], 1.0 op_sel_hi:[1,0]
	v_or_b32_e32 v122, 32, v150
	v_div_scale_f32 v116, s[0:1], v115, v115, 1.0
	v_rcp_f32_e32 v117, v116
	v_pk_add_f32 v[118:119], v[118:119], 1.0 op_sel_hi:[1,0]
	v_ashrrev_i32_e32 v123, 31, v122
	v_fma_f32 v124, -v116, v117, 1.0
	v_fmac_f32_e32 v117, v124, v117
	v_div_scale_f32 v124, vcc, 1.0, v115, 1.0
	v_mul_f32_e32 v125, v124, v117
	v_fma_f32 v130, -v116, v125, v124
	v_fmac_f32_e32 v125, v130, v117
	v_fma_f32 v116, -v116, v125, v124
	v_div_fmas_f32 v116, v116, v117, v125
; __device__ __forceinline__ float sigmoidf_(float x) { return 1.0f / (1.0f + __expf(-x)); }
;     template <int GI>
;     __device__ __forceinline__ void body(const f32x4 (&acc)[2][2][4][2], int row0, int colt) const {
;     ...
;         for (int bj = 0; bj < 2; ++bj) {
;             const int c = colt + bj * 128;
;             f32x4 b0 = (f32x4){0.f, 0.f, 0.f, 0.f}, b1 = b0;
;             if (GI == 0) { b0 = *(const f32x4*)(w0 + c); b1 = *(const f32x4*)(w0 + c + 4); }
;             else if (GI == 1) { b0 = *(const f32x4*)(a0 + c); b1 = *(const f32x4*)(a0 + c + 4); }
;             else if (GI == 3) { b0 = *(const f32x4*)(v0 + c); b1 = *(const f32x4*)(v0 + c + 4); }
; #pragma unroll
;             for (int ai = 0; ai < 2; ++ai)
; #pragma unroll
;                 for (int m = 0; m < 4; ++m) {
;                     const size_t row = (size_t)(row0 + ai * 128 + m * 16);
;                     f32x4 x0 = acc[ai][bj][m][0] + b0, x1 = acc[ai][bj][m][1] + b1;
;                     if (GI == 0) {
; #pragma unroll
;                         for (int j = 0; j < 4; ++j) {
;                             x0[j] = 0.6065306597126334f * sigmoidf_(x0[j]); x1[j] = 0.6065306597126334f * sigmoidf_(x1[j]); }
;                         *(u32x4*)(DEC + row * DM + c) = pack8(x0, x1);
	v_div_fixup_f32 v115, v116, v115, 1.0
	v_div_scale_f32 v116, s[0:1], v114, v114, 1.0
	v_rcp_f32_e32 v117, v116
	s_nop 0
	v_fma_f32 v124, -v116, v117, 1.0
	v_fmac_f32_e32 v117, v124, v117
	v_div_scale_f32 v124, vcc, 1.0, v114, 1.0
	v_mul_f32_e32 v125, v124, v117
	v_fma_f32 v130, -v116, v125, v124
	v_fmac_f32_e32 v125, v130, v117
	v_fma_f32 v116, -v116, v125, v124
	v_div_fmas_f32 v116, v116, v117, v125
	v_div_fixup_f32 v114, v116, v114, 1.0
	v_pk_mul_f32 v[114:115], v[114:115], s[4:5] op_sel_hi:[1,0]
	v_pk_add_f32 v[116:117], v[120:121], 1.0 op_sel_hi:[1,0]
	v_cvt_pk_f16_f32 v114, v114, v115
	v_div_scale_f32 v115, s[0:1], v117, v117, 1.0
	v_rcp_f32_e32 v120, v115
	s_nop 0
	v_fma_f32 v121, -v115, v120, 1.0
	v_fmac_f32_e32 v120, v121, v120
	v_div_scale_f32 v121, vcc, 1.0, v117, 1.0
	v_mul_f32_e32 v124, v121, v120
	v_fma_f32 v125, -v115, v124, v121
	v_fmac_f32_e32 v124, v125, v120
	v_fma_f32 v115, -v115, v124, v121
	v_div_fmas_f32 v115, v115, v120, v124
	v_div_fixup_f32 v117, v115, v117, 1.0
	v_div_scale_f32 v115, s[0:1], v116, v116, 1.0
	v_rcp_f32_e32 v120, v115
	s_nop 0
	v_fma_f32 v121, -v115, v120, 1.0
	v_fmac_f32_e32 v120, v121, v120
	v_div_scale_f32 v121, vcc, 1.0, v116, 1.0
	v_mul_f32_e32 v124, v121, v120
	v_fma_f32 v125, -v115, v124, v121
	v_fmac_f32_e32 v124, v125, v120
	v_fma_f32 v115, -v115, v124, v121
	v_div_fmas_f32 v115, v115, v120, v124
	v_div_fixup_f32 v116, v115, v116, 1.0
	v_pk_mul_f32 v[116:117], v[116:117], s[4:5] op_sel_hi:[1,0]
	s_nop 0
	v_cvt_pk_f16_f32 v115, v116, v117
	v_pk_add_f32 v[116:117], v[128:129], 1.0 op_sel_hi:[1,0]
	s_nop 0
	v_div_scale_f32 v120, s[0:1], v117, v117, 1.0
	v_rcp_f32_e32 v121, v120
	s_nop 0
	v_fma_f32 v124, -v120, v121, 1.0
	v_fmac_f32_e32 v121, v124, v121
	v_div_scale_f32 v124, vcc, 1.0, v117, 1.0
	v_mul_f32_e32 v125, v124, v121
	v_fma_f32 v128, -v120, v125, v124
	v_fmac_f32_e32 v125, v128, v121
	v_fma_f32 v120, -v120, v125, v124
	v_div_fmas_f32 v120, v120, v121, v125
	v_div_fixup_f32 v117, v120, v117, 1.0
	v_div_scale_f32 v120, s[0:1], v116, v116, 1.0
	v_rcp_f32_e32 v121, v120
	s_nop 0
	v_fma_f32 v124, -v120, v121, 1.0
	v_fmac_f32_e32 v121, v124, v121
	v_div_scale_f32 v124, vcc, 1.0, v116, 1.0
	v_mul_f32_e32 v125, v124, v121
	v_fma_f32 v128, -v120, v125, v124
	v_fmac_f32_e32 v125, v128, v121
	v_fma_f32 v120, -v120, v125, v124
	v_div_fmas_f32 v120, v120, v121, v125
	v_div_fixup_f32 v116, v120, v116, 1.0
	v_pk_mul_f32 v[116:117], v[116:117], s[4:5] op_sel_hi:[1,0]
	s_nop 0
	v_cvt_pk_f16_f32 v116, v116, v117
	v_div_scale_f32 v117, s[0:1], v119, v119, 1.0
	v_rcp_f32_e32 v120, v117
	s_nop 0
	v_fma_f32 v121, -v117, v120, 1.0
	v_fmac_f32_e32 v120, v121, v120
	v_div_scale_f32 v121, vcc, 1.0, v119, 1.0
	v_mul_f32_e32 v124, v121, v120
	v_fma_f32 v125, -v117, v124, v121
	v_fmac_f32_e32 v124, v125, v120
	v_fma_f32 v117, -v117, v124, v121
	v_div_fmas_f32 v117, v117, v120, v124
	v_div_fixup_f32 v119, v117, v119, 1.0
	v_div_scale_f32 v117, s[0:1], v118, v118, 1.0
	v_rcp_f32_e32 v120, v117
	s_nop 0
	v_fma_f32 v121, -v117, v120, 1.0
	v_fmac_f32_e32 v120, v121, v120
	v_div_scale_f32 v121, vcc, 1.0, v118, 1.0
	v_mul_f32_e32 v124, v121, v120
	v_fma_f32 v125, -v117, v124, v121
	v_fmac_f32_e32 v124, v125, v120
	v_fma_f32 v117, -v117, v124, v121
	v_div_fmas_f32 v117, v117, v120, v124
	v_div_fixup_f32 v118, v117, v118, 1.0
	v_pk_mul_f32 v[118:119], v[118:119], s[4:5] op_sel_hi:[1,0]
	s_nop 0
	v_cvt_pk_f16_f32 v117, v118, v119
	v_lshlrev_b64 v[118:119], 12, v[122:123]
	v_lshl_add_u64 v[118:119], s[6:7], 0, v[118:119]
	v_lshl_add_u64 v[118:119], v[118:119], 0, v[136:137]
	global_store_dwordx4 v[118:119], v[114:117], off
	v_pk_add_f32 v[106:107], v[106:107], v[90:91]
	v_pk_add_f32 v[110:111], v[110:111], v[94:95]
	v_mul_f32_e32 v106, 0xbfb8aa3b, v106
	v_exp_f32_e32 v120, v106
	v_mul_f32_e32 v106, 0xbfb8aa3b, v111
	v_pk_add_f32 v[112:113], v[112:113], v[96:97]
	v_mul_f32_e32 v110, 0xbfb8aa3b, v110
	v_exp_f32_e32 v117, v106
	v_mul_f32_e32 v106, 0xbfb8aa3b, v107
	v_pk_add_f32 v[108:109], v[108:109], v[92:93]
	v_exp_f32_e32 v116, v110
	v_exp_f32_e32 v121, v106
	v_mul_f32_e32 v106, 0xbfb8aa3b, v112
	v_exp_f32_e32 v112, v106
	v_mul_f32_e32 v106, 0xbfb8aa3b, v108
	v_exp_f32_e32 v110, v106
	v_mul_f32_e32 v106, 0xbfb8aa3b, v113
	v_exp_f32_e32 v113, v106
	v_mul_f32_e32 v106, 0xbfb8aa3b, v109
	v_exp_f32_e32 v111, v106
	v_pk_add_f32 v[106:107], v[116:117], 1.0 op_sel_hi:[1,0]
	v_or_b32_e32 v114, 48, v150
	v_div_scale_f32 v108, s[0:1], v107, v107, 1.0
	v_rcp_f32_e32 v109, v108
	v_pk_add_f32 v[110:111], v[110:111], 1.0 op_sel_hi:[1,0]
	v_ashrrev_i32_e32 v115, 31, v114
	v_fma_f32 v116, -v108, v109, 1.0
	v_fmac_f32_e32 v109, v116, v109
	v_div_scale_f32 v116, vcc, 1.0, v107, 1.0
	v_mul_f32_e32 v117, v116, v109
	v_fma_f32 v122, -v108, v117, v116
	v_fmac_f32_e32 v117, v122, v109
	v_fma_f32 v108, -v108, v117, v116
	v_div_fmas_f32 v108, v108, v109, v117
	v_div_fixup_f32 v107, v108, v107, 1.0
	v_div_scale_f32 v108, s[0:1], v106, v106, 1.0
	v_rcp_f32_e32 v109, v108
	s_nop 0
	v_fma_f32 v116, -v108, v109, 1.0
	v_fmac_f32_e32 v109, v116, v109
	v_div_scale_f32 v116, vcc, 1.0, v106, 1.0
	v_mul_f32_e32 v117, v116, v109
	v_fma_f32 v122, -v108, v117, v116
	v_fmac_f32_e32 v117, v122, v109
	v_fma_f32 v108, -v108, v117, v116
	v_div_fmas_f32 v108, v108, v109, v117
	v_div_fixup_f32 v106, v108, v106, 1.0
	v_pk_mul_f32 v[106:107], v[106:107], s[4:5] op_sel_hi:[1,0]
	v_pk_add_f32 v[108:109], v[112:113], 1.0 op_sel_hi:[1,0]
	v_cvt_pk_f16_f32 v106, v106, v107
	v_div_scale_f32 v107, s[0:1], v109, v109, 1.0
	v_rcp_f32_e32 v112, v107
	s_nop 0
	v_fma_f32 v113, -v107, v112, 1.0
	v_fmac_f32_e32 v112, v113, v112
	v_div_scale_f32 v113, vcc, 1.0, v109, 1.0
; __device__ __forceinline__ float sigmoidf_(float x) { return 1.0f / (1.0f + __expf(-x)); }
;     template <int GI>
;     __device__ __forceinline__ void body(const f32x4 (&acc)[2][2][4][2], int row0, int colt) const {
;     ...
;         for (int bj = 0; bj < 2; ++bj) {
;             const int c = colt + bj * 128;
;             f32x4 b0 = (f32x4){0.f, 0.f, 0.f, 0.f}, b1 = b0;
;             if (GI == 0) { b0 = *(const f32x4*)(w0 + c); b1 = *(const f32x4*)(w0 + c + 4); }
;             else if (GI == 1) { b0 = *(const f32x4*)(a0 + c); b1 = *(const f32x4*)(a0 + c + 4); }
;             else if (GI == 3) { b0 = *(const f32x4*)(v0 + c); b1 = *(const f32x4*)(v0 + c + 4); }
; #pragma unroll
;             for (int ai = 0; ai < 2; ++ai)
; #pragma unroll
;                 for (int m = 0; m < 4; ++m) {
;                     const size_t row = (size_t)(row0 + ai * 128 + m * 16);
;                     f32x4 x0 = acc[ai][bj][m][0] + b0, x1 = acc[ai][bj][m][1] + b1;
;                     if (GI == 0) {
; #pragma unroll
;                         for (int j = 0; j < 4; ++j) {
;                             x0[j] = 0.6065306597126334f * sigmoidf_(x0[j]); x1[j] = 0.6065306597126334f * sigmoidf_(x1[j]); }
;                         *(u32x4*)(DEC + row * DM + c) = pack8(x0, x1);
	v_mul_f32_e32 v116, v113, v112
	v_fma_f32 v117, -v107, v116, v113
	v_fmac_f32_e32 v116, v117, v112
	v_fma_f32 v107, -v107, v116, v113
	v_div_fmas_f32 v107, v107, v112, v116
	v_div_fixup_f32 v109, v107, v109, 1.0
	v_div_scale_f32 v107, s[0:1], v108, v108, 1.0
	v_rcp_f32_e32 v112, v107
	s_nop 0
	v_fma_f32 v113, -v107, v112, 1.0
	v_fmac_f32_e32 v112, v113, v112
	v_div_scale_f32 v113, vcc, 1.0, v108, 1.0
	v_mul_f32_e32 v116, v113, v112
	v_fma_f32 v117, -v107, v116, v113
	v_fmac_f32_e32 v116, v117, v112
	v_fma_f32 v107, -v107, v116, v113
	v_div_fmas_f32 v107, v107, v112, v116
	v_div_fixup_f32 v108, v107, v108, 1.0
	v_pk_mul_f32 v[108:109], v[108:109], s[4:5] op_sel_hi:[1,0]
	s_nop 0
	v_cvt_pk_f16_f32 v107, v108, v109
	v_pk_add_f32 v[108:109], v[120:121], 1.0 op_sel_hi:[1,0]
	s_nop 0
	v_div_scale_f32 v112, s[0:1], v109, v109, 1.0
	v_rcp_f32_e32 v113, v112
	s_nop 0
	v_fma_f32 v116, -v112, v113, 1.0
	v_fmac_f32_e32 v113, v116, v113
	v_div_scale_f32 v116, vcc, 1.0, v109, 1.0
	v_mul_f32_e32 v117, v116, v113
	v_fma_f32 v120, -v112, v117, v116
	v_fmac_f32_e32 v117, v120, v113
	v_fma_f32 v112, -v112, v117, v116
	v_div_fmas_f32 v112, v112, v113, v117
	v_div_fixup_f32 v109, v112, v109, 1.0
	v_div_scale_f32 v112, s[0:1], v108, v108, 1.0
	v_rcp_f32_e32 v113, v112
	s_nop 0
	v_fma_f32 v116, -v112, v113, 1.0
	v_fmac_f32_e32 v113, v116, v113
	v_div_scale_f32 v116, vcc, 1.0, v108, 1.0
	v_mul_f32_e32 v117, v116, v113
	v_fma_f32 v120, -v112, v117, v116
	v_fmac_f32_e32 v117, v120, v113
	v_fma_f32 v112, -v112, v117, v116
	v_div_fmas_f32 v112, v112, v113, v117
	v_div_fixup_f32 v108, v112, v108, 1.0
	v_pk_mul_f32 v[108:109], v[108:109], s[4:5] op_sel_hi:[1,0]
	s_nop 0
	v_cvt_pk_f16_f32 v108, v108, v109
	v_div_scale_f32 v109, s[0:1], v111, v111, 1.0
	v_rcp_f32_e32 v112, v109
	s_nop 0
	v_fma_f32 v113, -v109, v112, 1.0
	v_fmac_f32_e32 v112, v113, v112
	v_div_scale_f32 v113, vcc, 1.0, v111, 1.0
	v_mul_f32_e32 v116, v113, v112
	v_fma_f32 v117, -v109, v116, v113
	v_fmac_f32_e32 v116, v117, v112
	v_fma_f32 v109, -v109, v116, v113
	v_div_fmas_f32 v109, v109, v112, v116
	v_div_fixup_f32 v111, v109, v111, 1.0
	v_div_scale_f32 v109, s[0:1], v110, v110, 1.0
	v_rcp_f32_e32 v112, v109
	s_nop 0
	v_fma_f32 v113, -v109, v112, 1.0
	v_fmac_f32_e32 v112, v113, v112
	v_div_scale_f32 v113, vcc, 1.0, v110, 1.0
	v_mul_f32_e32 v116, v113, v112
	v_fma_f32 v117, -v109, v116, v113
	v_fmac_f32_e32 v116, v117, v112
	v_fma_f32 v109, -v109, v116, v113
	v_div_fmas_f32 v109, v109, v112, v116
	v_div_fixup_f32 v110, v109, v110, 1.0
	v_pk_mul_f32 v[110:111], v[110:111], s[4:5] op_sel_hi:[1,0]
	s_nop 0
	v_cvt_pk_f16_f32 v109, v110, v111
	v_lshlrev_b64 v[110:111], 12, v[114:115]
	v_lshl_add_u64 v[110:111], s[6:7], 0, v[110:111]
	v_lshl_add_u64 v[110:111], v[110:111], 0, v[136:137]
	global_store_dwordx4 v[110:111], v[106:109], off
	v_pk_add_f32 v[98:99], v[98:99], v[90:91]
	v_pk_add_f32 v[102:103], v[102:103], v[94:95]
	v_mul_f32_e32 v98, 0xbfb8aa3b, v98
	v_exp_f32_e32 v108, v98
	v_mul_f32_e32 v98, 0xbfb8aa3b, v103
	v_pk_add_f32 v[104:105], v[104:105], v[96:97]
	v_mul_f32_e32 v102, 0xbfb8aa3b, v102
	v_exp_f32_e32 v107, v98
	v_mul_f32_e32 v98, 0xbfb8aa3b, v99
	v_pk_add_f32 v[100:101], v[100:101], v[92:93]
	v_exp_f32_e32 v106, v102
	v_exp_f32_e32 v109, v98
	v_mul_f32_e32 v98, 0xbfb8aa3b, v104
	v_exp_f32_e32 v104, v98
	v_mul_f32_e32 v98, 0xbfb8aa3b, v100
	v_exp_f32_e32 v102, v98
	v_mul_f32_e32 v98, 0xbfb8aa3b, v105
	v_exp_f32_e32 v105, v98
	v_mul_f32_e32 v98, 0xbfb8aa3b, v101
	v_exp_f32_e32 v103, v98
	v_pk_add_f32 v[98:99], v[106:107], 1.0 op_sel_hi:[1,0]
	v_pk_add_f32 v[102:103], v[102:103], 1.0 op_sel_hi:[1,0]
	v_div_scale_f32 v100, s[0:1], v99, v99, 1.0
	v_rcp_f32_e32 v101, v100
	s_nop 0
	v_fma_f32 v106, -v100, v101, 1.0
	v_fmac_f32_e32 v101, v106, v101
	v_div_scale_f32 v106, vcc, 1.0, v99, 1.0
	v_mul_f32_e32 v107, v106, v101
	v_fma_f32 v112, -v100, v107, v106
	v_fmac_f32_e32 v107, v112, v101
	v_fma_f32 v100, -v100, v107, v106
	v_div_fmas_f32 v100, v100, v101, v107
	v_div_fixup_f32 v99, v100, v99, 1.0
	v_div_scale_f32 v100, s[0:1], v98, v98, 1.0
	v_rcp_f32_e32 v101, v100
	s_nop 0
	v_fma_f32 v106, -v100, v101, 1.0
	v_fmac_f32_e32 v101, v106, v101
	v_div_scale_f32 v106, vcc, 1.0, v98, 1.0
	v_mul_f32_e32 v107, v106, v101
	v_fma_f32 v112, -v100, v107, v106
	v_fmac_f32_e32 v107, v112, v101
	v_fma_f32 v100, -v100, v107, v106
	v_div_fmas_f32 v100, v100, v101, v107
	v_div_fixup_f32 v98, v100, v98, 1.0
	v_pk_mul_f32 v[98:99], v[98:99], s[4:5] op_sel_hi:[1,0]
	v_pk_add_f32 v[100:101], v[104:105], 1.0 op_sel_hi:[1,0]
	v_cvt_pk_f16_f32 v98, v98, v99
	v_div_scale_f32 v99, s[0:1], v101, v101, 1.0
	v_rcp_f32_e32 v104, v99
	s_nop 0
	v_fma_f32 v105, -v99, v104, 1.0
	v_fmac_f32_e32 v104, v105, v104
	v_div_scale_f32 v105, vcc, 1.0, v101, 1.0
	v_mul_f32_e32 v106, v105, v104
	v_fma_f32 v107, -v99, v106, v105
	v_fmac_f32_e32 v106, v107, v104
	v_fma_f32 v99, -v99, v106, v105
	v_div_fmas_f32 v99, v99, v104, v106
	v_div_fixup_f32 v101, v99, v101, 1.0
	v_div_scale_f32 v99, s[0:1], v100, v100, 1.0
	v_rcp_f32_e32 v104, v99
	s_nop 0
	v_fma_f32 v105, -v99, v104, 1.0
	v_fmac_f32_e32 v104, v105, v104
	v_div_scale_f32 v105, vcc, 1.0, v100, 1.0
	v_mul_f32_e32 v106, v105, v104
	v_fma_f32 v107, -v99, v106, v105
	v_fmac_f32_e32 v106, v107, v104
	v_fma_f32 v99, -v99, v106, v105
	v_div_fmas_f32 v99, v99, v104, v106
	v_div_fixup_f32 v100, v99, v100, 1.0
	v_pk_mul_f32 v[100:101], v[100:101], s[4:5] op_sel_hi:[1,0]
	s_nop 0
	v_cvt_pk_f16_f32 v99, v100, v101
	v_pk_add_f32 v[100:101], v[108:109], 1.0 op_sel_hi:[1,0]
	s_nop 0
	v_div_scale_f32 v104, s[0:1], v101, v101, 1.0
	v_rcp_f32_e32 v105, v104
	s_nop 0
	v_fma_f32 v106, -v104, v105, 1.0
; __device__ __forceinline__ float sigmoidf_(float x) { return 1.0f / (1.0f + __expf(-x)); }
;     template <int GI>
;     __device__ __forceinline__ void body(const f32x4 (&acc)[2][2][4][2], int row0, int colt) const {
;     ...
;         for (int bj = 0; bj < 2; ++bj) {
;             const int c = colt + bj * 128;
;             f32x4 b0 = (f32x4){0.f, 0.f, 0.f, 0.f}, b1 = b0;
;             if (GI == 0) { b0 = *(const f32x4*)(w0 + c); b1 = *(const f32x4*)(w0 + c + 4); }
;             else if (GI == 1) { b0 = *(const f32x4*)(a0 + c); b1 = *(const f32x4*)(a0 + c + 4); }
;             else if (GI == 3) { b0 = *(const f32x4*)(v0 + c); b1 = *(const f32x4*)(v0 + c + 4); }
; #pragma unroll
;             for (int ai = 0; ai < 2; ++ai)
; #pragma unroll
;                 for (int m = 0; m < 4; ++m) {
;                     const size_t row = (size_t)(row0 + ai * 128 + m * 16);
;                     f32x4 x0 = acc[ai][bj][m][0] + b0, x1 = acc[ai][bj][m][1] + b1;
;                     if (GI == 0) {
; #pragma unroll
;                         for (int j = 0; j < 4; ++j) {
;                             x0[j] = 0.6065306597126334f * sigmoidf_(x0[j]); x1[j] = 0.6065306597126334f * sigmoidf_(x1[j]); }
;                         *(u32x4*)(DEC + row * DM + c) = pack8(x0, x1);
	v_fmac_f32_e32 v105, v106, v105
	v_div_scale_f32 v106, vcc, 1.0, v101, 1.0
	v_mul_f32_e32 v107, v106, v105
	v_fma_f32 v108, -v104, v107, v106
	v_fmac_f32_e32 v107, v108, v105
	v_fma_f32 v104, -v104, v107, v106
	v_div_fmas_f32 v104, v104, v105, v107
	v_div_fixup_f32 v101, v104, v101, 1.0
	v_div_scale_f32 v104, s[0:1], v100, v100, 1.0
	v_rcp_f32_e32 v105, v104
	s_nop 0
	v_fma_f32 v106, -v104, v105, 1.0
	v_fmac_f32_e32 v105, v106, v105
	v_div_scale_f32 v106, vcc, 1.0, v100, 1.0
	v_mul_f32_e32 v107, v106, v105
	v_fma_f32 v108, -v104, v107, v106
	v_fmac_f32_e32 v107, v108, v105
	v_fma_f32 v104, -v104, v107, v106
	v_div_fmas_f32 v104, v104, v105, v107
	v_div_fixup_f32 v100, v104, v100, 1.0
	v_pk_mul_f32 v[100:101], v[100:101], s[4:5] op_sel_hi:[1,0]
	s_nop 0
	v_cvt_pk_f16_f32 v100, v100, v101
	v_div_scale_f32 v101, s[0:1], v103, v103, 1.0
	v_rcp_f32_e32 v104, v101
	s_nop 0
	v_fma_f32 v105, -v101, v104, 1.0
	v_fmac_f32_e32 v104, v105, v104
	v_div_scale_f32 v105, vcc, 1.0, v103, 1.0
	v_mul_f32_e32 v106, v105, v104
	v_fma_f32 v107, -v101, v106, v105
	v_fmac_f32_e32 v106, v107, v104
	v_fma_f32 v101, -v101, v106, v105
	v_div_fmas_f32 v101, v101, v104, v106
	v_div_fixup_f32 v103, v101, v103, 1.0
	v_div_scale_f32 v101, s[0:1], v102, v102, 1.0
	v_rcp_f32_e32 v104, v101
	s_mov_b32 s0, 0x80000
	v_fma_f32 v105, -v101, v104, 1.0
	v_fmac_f32_e32 v104, v105, v104
	v_div_scale_f32 v105, vcc, 1.0, v102, 1.0
	v_mul_f32_e32 v106, v105, v104
	v_fma_f32 v107, -v101, v106, v105
	v_fmac_f32_e32 v106, v107, v104
	v_fma_f32 v101, -v101, v106, v105
	v_div_fmas_f32 v101, v101, v104, v106
	v_div_fixup_f32 v102, v101, v102, 1.0
	v_pk_mul_f32 v[102:103], v[102:103], s[4:5] op_sel_hi:[1,0]
	v_add_co_u32_e32 v104, vcc, s0, v134
	v_cvt_pk_f16_f32 v101, v102, v103
	s_nop 0
	v_addc_co_u32_e32 v105, vcc, 0, v135, vcc
	v_lshl_add_u64 v[102:103], v[134:135], 0, s[10:11]
	global_store_dwordx4 v[104:105], v[98:101], off
	v_pk_add_f32 v[82:83], v[82:83], v[90:91]
	v_pk_add_f32 v[86:87], v[86:87], v[94:95]
	v_mul_f32_e32 v82, 0xbfb8aa3b, v82
	v_exp_f32_e32 v100, v82
	v_mul_f32_e32 v82, 0xbfb8aa3b, v87
	v_pk_add_f32 v[88:89], v[88:89], v[96:97]
	v_mul_f32_e32 v86, 0xbfb8aa3b, v86
	v_exp_f32_e32 v99, v82
	v_mul_f32_e32 v82, 0xbfb8aa3b, v83
	v_pk_add_f32 v[84:85], v[84:85], v[92:93]
	v_exp_f32_e32 v98, v86
	v_exp_f32_e32 v101, v82
	v_mul_f32_e32 v82, 0xbfb8aa3b, v88
	v_exp_f32_e32 v88, v82
	v_mul_f32_e32 v82, 0xbfb8aa3b, v84
	v_exp_f32_e32 v86, v82
	v_mul_f32_e32 v82, 0xbfb8aa3b, v89
	v_exp_f32_e32 v89, v82
	v_mul_f32_e32 v82, 0xbfb8aa3b, v85
	v_exp_f32_e32 v87, v82
	v_pk_add_f32 v[82:83], v[98:99], 1.0 op_sel_hi:[1,0]
	v_pk_add_f32 v[86:87], v[86:87], 1.0 op_sel_hi:[1,0]
	v_div_scale_f32 v84, s[0:1], v83, v83, 1.0
	v_rcp_f32_e32 v85, v84
	s_nop 0
	v_fma_f32 v98, -v84, v85, 1.0
	v_fmac_f32_e32 v85, v98, v85
	v_div_scale_f32 v98, vcc, 1.0, v83, 1.0
	v_mul_f32_e32 v99, v98, v85
	v_fma_f32 v104, -v84, v99, v98
	v_fmac_f32_e32 v99, v104, v85
	v_fma_f32 v84, -v84, v99, v98
	v_div_fmas_f32 v84, v84, v85, v99
	v_div_fixup_f32 v83, v84, v83, 1.0
	v_div_scale_f32 v84, s[0:1], v82, v82, 1.0
	v_rcp_f32_e32 v85, v84
	s_nop 0
	v_fma_f32 v98, -v84, v85, 1.0
	v_fmac_f32_e32 v85, v98, v85
	v_div_scale_f32 v98, vcc, 1.0, v82, 1.0
	v_mul_f32_e32 v99, v98, v85
	v_fma_f32 v104, -v84, v99, v98
	v_fmac_f32_e32 v99, v104, v85
	v_fma_f32 v84, -v84, v99, v98
	v_div_fmas_f32 v84, v84, v85, v99
	v_div_fixup_f32 v82, v84, v82, 1.0
	v_pk_mul_f32 v[82:83], v[82:83], s[4:5] op_sel_hi:[1,0]
	v_pk_add_f32 v[84:85], v[88:89], 1.0 op_sel_hi:[1,0]
	v_cvt_pk_f16_f32 v82, v82, v83
	v_div_scale_f32 v83, s[0:1], v85, v85, 1.0
	v_rcp_f32_e32 v88, v83
	s_nop 0
	v_fma_f32 v89, -v83, v88, 1.0
	v_fmac_f32_e32 v88, v89, v88
	v_div_scale_f32 v89, vcc, 1.0, v85, 1.0
	v_mul_f32_e32 v98, v89, v88
	v_fma_f32 v99, -v83, v98, v89
	v_fmac_f32_e32 v98, v99, v88
	v_fma_f32 v83, -v83, v98, v89
	v_div_fmas_f32 v83, v83, v88, v98
	v_div_fixup_f32 v85, v83, v85, 1.0
	v_div_scale_f32 v83, s[0:1], v84, v84, 1.0
	v_rcp_f32_e32 v88, v83
	s_nop 0
	v_fma_f32 v89, -v83, v88, 1.0
	v_fmac_f32_e32 v88, v89, v88
	v_div_scale_f32 v89, vcc, 1.0, v84, 1.0
	v_mul_f32_e32 v98, v89, v88
	v_fma_f32 v99, -v83, v98, v89
	v_fmac_f32_e32 v98, v99, v88
	v_fma_f32 v83, -v83, v98, v89
	v_div_fmas_f32 v83, v83, v88, v98
	v_div_fixup_f32 v84, v83, v84, 1.0
	v_pk_mul_f32 v[84:85], v[84:85], s[4:5] op_sel_hi:[1,0]
	s_nop 0
	v_cvt_pk_f16_f32 v83, v84, v85
	v_pk_add_f32 v[84:85], v[100:101], 1.0 op_sel_hi:[1,0]
	s_nop 0
	v_div_scale_f32 v88, s[0:1], v85, v85, 1.0
	v_rcp_f32_e32 v89, v88
	s_nop 0
	v_fma_f32 v98, -v88, v89, 1.0
	v_fmac_f32_e32 v89, v98, v89
	v_div_scale_f32 v98, vcc, 1.0, v85, 1.0
	v_mul_f32_e32 v99, v98, v89
	v_fma_f32 v100, -v88, v99, v98
	v_fmac_f32_e32 v99, v100, v89
	v_fma_f32 v88, -v88, v99, v98
	v_div_fmas_f32 v88, v88, v89, v99
	v_div_fixup_f32 v85, v88, v85, 1.0
	v_div_scale_f32 v88, s[0:1], v84, v84, 1.0
	v_rcp_f32_e32 v89, v88
	s_nop 0
	v_fma_f32 v98, -v88, v89, 1.0
	v_fmac_f32_e32 v89, v98, v89
	v_div_scale_f32 v98, vcc, 1.0, v84, 1.0
	v_mul_f32_e32 v99, v98, v89
	v_fma_f32 v100, -v88, v99, v98
	v_fmac_f32_e32 v99, v100, v89
	v_fma_f32 v88, -v88, v99, v98
	v_div_fmas_f32 v88, v88, v89, v99
	v_div_fixup_f32 v84, v88, v84, 1.0
	v_pk_mul_f32 v[84:85], v[84:85], s[4:5] op_sel_hi:[1,0]
	s_nop 0
	v_cvt_pk_f16_f32 v84, v84, v85
	v_div_scale_f32 v85, s[0:1], v87, v87, 1.0
	v_rcp_f32_e32 v88, v85
	s_nop 0
	v_fma_f32 v89, -v85, v88, 1.0
	v_fmac_f32_e32 v88, v89, v88
	v_div_scale_f32 v89, vcc, 1.0, v87, 1.0
	v_mul_f32_e32 v98, v89, v88
	v_fma_f32 v99, -v85, v98, v89
	v_fmac_f32_e32 v98, v99, v88
	v_fma_f32 v85, -v85, v98, v89
	v_div_fmas_f32 v85, v85, v88, v98
; __device__ __forceinline__ float sigmoidf_(float x) { return 1.0f / (1.0f + __expf(-x)); }
;     template <int GI>
;     __device__ __forceinline__ void body(const f32x4 (&acc)[2][2][4][2], int row0, int colt) const {
;     ...
;         for (int bj = 0; bj < 2; ++bj) {
;             const int c = colt + bj * 128;
;             f32x4 b0 = (f32x4){0.f, 0.f, 0.f, 0.f}, b1 = b0;
;             if (GI == 0) { b0 = *(const f32x4*)(w0 + c); b1 = *(const f32x4*)(w0 + c + 4); }
;             else if (GI == 1) { b0 = *(const f32x4*)(a0 + c); b1 = *(const f32x4*)(a0 + c + 4); }
;             else if (GI == 3) { b0 = *(const f32x4*)(v0 + c); b1 = *(const f32x4*)(v0 + c + 4); }
; #pragma unroll
;             for (int ai = 0; ai < 2; ++ai)
; #pragma unroll
;                 for (int m = 0; m < 4; ++m) {
;                     const size_t row = (size_t)(row0 + ai * 128 + m * 16);
;                     f32x4 x0 = acc[ai][bj][m][0] + b0, x1 = acc[ai][bj][m][1] + b1;
;                     if (GI == 0) {
; #pragma unroll
;                         for (int j = 0; j < 4; ++j) {
;                             x0[j] = 0.6065306597126334f * sigmoidf_(x0[j]); x1[j] = 0.6065306597126334f * sigmoidf_(x1[j]); }
;                         *(u32x4*)(DEC + row * DM + c) = pack8(x0, x1);
	v_div_fixup_f32 v87, v85, v87, 1.0
	v_div_scale_f32 v85, s[0:1], v86, v86, 1.0
	v_rcp_f32_e32 v88, v85
	s_mov_b32 s0, 0x90000
	v_fma_f32 v89, -v85, v88, 1.0
	v_fmac_f32_e32 v88, v89, v88
	v_div_scale_f32 v89, vcc, 1.0, v86, 1.0
	v_mul_f32_e32 v98, v89, v88
	v_fma_f32 v99, -v85, v98, v89
	v_fmac_f32_e32 v98, v99, v88
	v_fma_f32 v85, -v85, v98, v89
	v_div_fmas_f32 v85, v85, v88, v98
	v_div_fixup_f32 v86, v85, v86, 1.0
	v_pk_mul_f32 v[86:87], v[86:87], s[4:5] op_sel_hi:[1,0]
	v_add_co_u32_e32 v88, vcc, s0, v134
	v_cvt_pk_f16_f32 v85, v86, v87
	s_nop 0
	v_addc_co_u32_e32 v89, vcc, 0, v135, vcc
	v_lshl_add_u64 v[86:87], v[134:135], 0, s[18:19]
	global_store_dwordx4 v[88:89], v[82:85], off
	v_pk_add_f32 v[74:75], v[74:75], v[90:91]
	v_pk_add_f32 v[78:79], v[78:79], v[94:95]
	v_mul_f32_e32 v74, 0xbfb8aa3b, v74
	v_exp_f32_e32 v84, v74
	v_mul_f32_e32 v74, 0xbfb8aa3b, v79
	v_pk_add_f32 v[80:81], v[80:81], v[96:97]
	v_mul_f32_e32 v78, 0xbfb8aa3b, v78
	v_exp_f32_e32 v83, v74
	v_mul_f32_e32 v74, 0xbfb8aa3b, v75
	v_pk_add_f32 v[76:77], v[76:77], v[92:93]
	v_exp_f32_e32 v82, v78
	v_exp_f32_e32 v85, v74
	v_mul_f32_e32 v74, 0xbfb8aa3b, v80
	v_exp_f32_e32 v80, v74
	v_mul_f32_e32 v74, 0xbfb8aa3b, v76
	v_exp_f32_e32 v78, v74
	v_mul_f32_e32 v74, 0xbfb8aa3b, v81
	v_exp_f32_e32 v81, v74
	v_mul_f32_e32 v74, 0xbfb8aa3b, v77
	v_exp_f32_e32 v79, v74
	v_pk_add_f32 v[74:75], v[82:83], 1.0 op_sel_hi:[1,0]
	v_pk_add_f32 v[78:79], v[78:79], 1.0 op_sel_hi:[1,0]
	v_div_scale_f32 v76, s[0:1], v75, v75, 1.0
	v_rcp_f32_e32 v77, v76
	s_nop 0
	v_fma_f32 v82, -v76, v77, 1.0
	v_fmac_f32_e32 v77, v82, v77
	v_div_scale_f32 v82, vcc, 1.0, v75, 1.0
	v_mul_f32_e32 v83, v82, v77
	v_fma_f32 v88, -v76, v83, v82
	v_fmac_f32_e32 v83, v88, v77
	v_fma_f32 v76, -v76, v83, v82
	v_div_fmas_f32 v76, v76, v77, v83
	v_div_fixup_f32 v75, v76, v75, 1.0
	v_div_scale_f32 v76, s[0:1], v74, v74, 1.0
	v_rcp_f32_e32 v77, v76
	s_nop 0
	v_fma_f32 v82, -v76, v77, 1.0
	v_fmac_f32_e32 v77, v82, v77
	v_div_scale_f32 v82, vcc, 1.0, v74, 1.0
	v_mul_f32_e32 v83, v82, v77
	v_fma_f32 v88, -v76, v83, v82
	v_fmac_f32_e32 v83, v88, v77
	v_fma_f32 v76, -v76, v83, v82
	v_div_fmas_f32 v76, v76, v77, v83
	v_div_fixup_f32 v74, v76, v74, 1.0
	v_pk_mul_f32 v[74:75], v[74:75], s[4:5] op_sel_hi:[1,0]
	v_pk_add_f32 v[76:77], v[80:81], 1.0 op_sel_hi:[1,0]
	v_cvt_pk_f16_f32 v74, v74, v75
	v_div_scale_f32 v75, s[0:1], v77, v77, 1.0
	v_rcp_f32_e32 v80, v75
	s_nop 0
	v_fma_f32 v81, -v75, v80, 1.0
	v_fmac_f32_e32 v80, v81, v80
	v_div_scale_f32 v81, vcc, 1.0, v77, 1.0
	v_mul_f32_e32 v82, v81, v80
	v_fma_f32 v83, -v75, v82, v81
	v_fmac_f32_e32 v82, v83, v80
	v_fma_f32 v75, -v75, v82, v81
	v_div_fmas_f32 v75, v75, v80, v82
	v_div_fixup_f32 v77, v75, v77, 1.0
	v_div_scale_f32 v75, s[0:1], v76, v76, 1.0
	v_rcp_f32_e32 v80, v75
	s_nop 0
	v_fma_f32 v81, -v75, v80, 1.0
	v_fmac_f32_e32 v80, v81, v80
	v_div_scale_f32 v81, vcc, 1.0, v76, 1.0
	v_mul_f32_e32 v82, v81, v80
	v_fma_f32 v83, -v75, v82, v81
	v_fmac_f32_e32 v82, v83, v80
	v_fma_f32 v75, -v75, v82, v81
	v_div_fmas_f32 v75, v75, v80, v82
	v_div_fixup_f32 v76, v75, v76, 1.0
	v_pk_mul_f32 v[76:77], v[76:77], s[4:5] op_sel_hi:[1,0]
	s_nop 0
	v_cvt_pk_f16_f32 v75, v76, v77
	v_pk_add_f32 v[76:77], v[84:85], 1.0 op_sel_hi:[1,0]
	s_nop 0
	v_div_scale_f32 v80, s[0:1], v77, v77, 1.0
	v_rcp_f32_e32 v81, v80
	s_nop 0
	v_fma_f32 v82, -v80, v81, 1.0
	v_fmac_f32_e32 v81, v82, v81
	v_div_scale_f32 v82, vcc, 1.0, v77, 1.0
	v_mul_f32_e32 v83, v82, v81
	v_fma_f32 v84, -v80, v83, v82
	v_fmac_f32_e32 v83, v84, v81
	v_fma_f32 v80, -v80, v83, v82
	v_div_fmas_f32 v80, v80, v81, v83
	v_div_fixup_f32 v77, v80, v77, 1.0
	v_div_scale_f32 v80, s[0:1], v76, v76, 1.0
	v_rcp_f32_e32 v81, v80
	s_nop 0
	v_fma_f32 v82, -v80, v81, 1.0
	v_fmac_f32_e32 v81, v82, v81
	v_div_scale_f32 v82, vcc, 1.0, v76, 1.0
	v_mul_f32_e32 v83, v82, v81
	v_fma_f32 v84, -v80, v83, v82
	v_fmac_f32_e32 v83, v84, v81
	v_fma_f32 v80, -v80, v83, v82
	v_div_fmas_f32 v80, v80, v81, v83
	v_div_fixup_f32 v76, v80, v76, 1.0
	v_pk_mul_f32 v[76:77], v[76:77], s[4:5] op_sel_hi:[1,0]
	s_nop 0
	v_cvt_pk_f16_f32 v76, v76, v77
	v_div_scale_f32 v77, s[0:1], v79, v79, 1.0
	v_rcp_f32_e32 v80, v77
	s_nop 0
	v_fma_f32 v81, -v77, v80, 1.0
	v_fmac_f32_e32 v80, v81, v80
	v_div_scale_f32 v81, vcc, 1.0, v79, 1.0
	v_mul_f32_e32 v82, v81, v80
	v_fma_f32 v83, -v77, v82, v81
	v_fmac_f32_e32 v82, v83, v80
	v_fma_f32 v77, -v77, v82, v81
	v_div_fmas_f32 v77, v77, v80, v82
	v_div_fixup_f32 v79, v77, v79, 1.0
	v_div_scale_f32 v77, s[0:1], v78, v78, 1.0
	v_rcp_f32_e32 v80, v77
	s_mov_b32 s0, 0xa0000
	v_fma_f32 v81, -v77, v80, 1.0
	v_fmac_f32_e32 v80, v81, v80
	v_div_scale_f32 v81, vcc, 1.0, v78, 1.0
	v_mul_f32_e32 v82, v81, v80
	v_fma_f32 v83, -v77, v82, v81
	v_fmac_f32_e32 v82, v83, v80
	v_fma_f32 v77, -v77, v82, v81
	v_div_fmas_f32 v77, v77, v80, v82
	v_div_fixup_f32 v78, v77, v78, 1.0
	v_pk_mul_f32 v[78:79], v[78:79], s[4:5] op_sel_hi:[1,0]
	v_add_co_u32_e32 v80, vcc, s0, v134
	v_cvt_pk_f16_f32 v77, v78, v79
	s_nop 0
	v_addc_co_u32_e32 v81, vcc, 0, v135, vcc
	v_lshl_add_u64 v[78:79], v[134:135], 0, s[14:15]
	global_store_dwordx4 v[80:81], v[74:77], off
	v_pk_add_f32 v[66:67], v[66:67], v[90:91]
	v_pk_add_f32 v[70:71], v[70:71], v[94:95]
	v_mul_f32_e32 v66, 0xbfb8aa3b, v66
	v_mul_f32_e32 v70, 0xbfb8aa3b, v70
	v_exp_f32_e32 v74, v66
	v_mul_f32_e32 v66, 0xbfb8aa3b, v71
	v_exp_f32_e32 v70, v70
	v_exp_f32_e32 v71, v66
	v_pk_add_f32 v[72:73], v[72:73], v[96:97]
	v_pk_add_f32 v[68:69], v[68:69], v[92:93]
	v_mul_f32_e32 v66, 0xbfb8aa3b, v67
	v_pk_add_f32 v[70:71], v[70:71], 1.0 op_sel_hi:[1,0]
	v_exp_f32_e32 v75, v66
	v_mul_f32_e32 v66, 0xbfb8aa3b, v72
	v_mul_f32_e32 v67, 0xbfb8aa3b, v68
; __device__ __forceinline__ float sigmoidf_(float x) { return 1.0f / (1.0f + __expf(-x)); }
;     template <int GI>
;     __device__ __forceinline__ void body(const f32x4 (&acc)[2][2][4][2], int row0, int colt) const {
;     ...
;         for (int bj = 0; bj < 2; ++bj) {
;             const int c = colt + bj * 128;
;             f32x4 b0 = (f32x4){0.f, 0.f, 0.f, 0.f}, b1 = b0;
;             if (GI == 0) { b0 = *(const f32x4*)(w0 + c); b1 = *(const f32x4*)(w0 + c + 4); }
;             else if (GI == 1) { b0 = *(const f32x4*)(a0 + c); b1 = *(const f32x4*)(a0 + c + 4); }
;             else if (GI == 3) { b0 = *(const f32x4*)(v0 + c); b1 = *(const f32x4*)(v0 + c + 4); }
; #pragma unroll
;             for (int ai = 0; ai < 2; ++ai)
; #pragma unroll
;                 for (int m = 0; m < 4; ++m) {
;                     const size_t row = (size_t)(row0 + ai * 128 + m * 16);
;                     f32x4 x0 = acc[ai][bj][m][0] + b0, x1 = acc[ai][bj][m][1] + b1;
;                     if (GI == 0) {
; #pragma unroll
;                         for (int j = 0; j < 4; ++j) {
;                             x0[j] = 0.6065306597126334f * sigmoidf_(x0[j]); x1[j] = 0.6065306597126334f * sigmoidf_(x1[j]); }
;                         *(u32x4*)(DEC + row * DM + c) = pack8(x0, x1);
	v_div_scale_f32 v72, s[0:1], v71, v71, 1.0
	v_exp_f32_e32 v68, v67
	v_mul_f32_e32 v67, 0xbfb8aa3b, v73
	v_rcp_f32_e32 v73, v72
	v_exp_f32_e32 v66, v66
	v_exp_f32_e32 v67, v67
	v_pk_add_f32 v[74:75], v[74:75], 1.0 op_sel_hi:[1,0]
	v_fma_f32 v76, -v72, v73, 1.0
	v_fmac_f32_e32 v73, v76, v73
	v_div_scale_f32 v76, vcc, 1.0, v71, 1.0
	v_mul_f32_e32 v77, v76, v73
	v_fma_f32 v80, -v72, v77, v76
	v_fmac_f32_e32 v77, v80, v73
	v_fma_f32 v72, -v72, v77, v76
	v_div_scale_f32 v76, s[0:1], v70, v70, 1.0
	v_rcp_f32_e32 v80, v76
	v_div_fmas_f32 v72, v72, v73, v77
	v_div_fixup_f32 v71, v72, v71, 1.0
	v_mul_f32_e32 v69, 0xbfb8aa3b, v69
	v_fma_f32 v72, -v76, v80, 1.0
	v_fmac_f32_e32 v80, v72, v80
	v_div_scale_f32 v72, vcc, 1.0, v70, 1.0
	v_mul_f32_e32 v73, v72, v80
	v_fma_f32 v77, -v76, v73, v72
	v_fmac_f32_e32 v73, v77, v80
	v_fma_f32 v72, -v76, v73, v72
	v_div_fmas_f32 v76, v72, v80, v73
	v_pk_add_f32 v[72:73], v[66:67], 1.0 op_sel_hi:[1,0]
	v_div_fixup_f32 v70, v76, v70, 1.0
	v_div_scale_f32 v77, s[0:1], v73, v73, 1.0
	v_rcp_f32_e32 v80, v77
	v_pk_mul_f32 v[66:67], v[70:71], s[4:5] op_sel_hi:[1,0]
	v_div_scale_f32 v76, s[0:1], v72, v72, 1.0
	v_cvt_pk_f16_f32 v66, v66, v67
	v_fma_f32 v67, -v77, v80, 1.0
	v_fmac_f32_e32 v80, v67, v80
	v_div_scale_f32 v67, vcc, 1.0, v73, 1.0
	v_mul_f32_e32 v70, v67, v80
	v_fma_f32 v71, -v77, v70, v67
	v_fmac_f32_e32 v70, v71, v80
	v_fma_f32 v67, -v77, v70, v67
	v_rcp_f32_e32 v77, v76
	v_div_fmas_f32 v67, v67, v80, v70
	v_div_fixup_f32 v71, v67, v73, 1.0
	v_exp_f32_e32 v69, v69
	v_fma_f32 v67, -v76, v77, 1.0
	v_fmac_f32_e32 v77, v67, v77
	v_div_scale_f32 v67, vcc, 1.0, v72, 1.0
	v_mul_f32_e32 v70, v67, v77
	v_fma_f32 v73, -v76, v70, v67
	v_fmac_f32_e32 v70, v73, v77
	v_div_scale_f32 v73, s[0:1], v75, v75, 1.0
	v_fma_f32 v67, -v76, v70, v67
	v_rcp_f32_e32 v76, v73
	v_div_fmas_f32 v67, v67, v77, v70
	v_div_fixup_f32 v70, v67, v72, 1.0
	v_pk_mul_f32 v[70:71], v[70:71], s[4:5] op_sel_hi:[1,0]
	s_nop 0
	v_cvt_pk_f16_f32 v67, v70, v71
	v_fma_f32 v70, -v73, v76, 1.0
	v_fmac_f32_e32 v76, v70, v76
	v_div_scale_f32 v70, vcc, 1.0, v75, 1.0
	v_mul_f32_e32 v71, v70, v76
	v_fma_f32 v72, -v73, v71, v70
	v_fmac_f32_e32 v71, v72, v76
	v_div_scale_f32 v72, s[0:1], v74, v74, 1.0
	v_fma_f32 v70, -v73, v71, v70
	v_rcp_f32_e32 v73, v72
	v_div_fmas_f32 v70, v70, v76, v71
	v_div_fixup_f32 v71, v70, v75, 1.0
	v_fma_f32 v70, -v72, v73, 1.0
	v_fmac_f32_e32 v73, v70, v73
	v_div_scale_f32 v70, vcc, 1.0, v74, 1.0
	v_mul_f32_e32 v75, v70, v73
	v_fma_f32 v76, -v72, v75, v70
	v_fmac_f32_e32 v75, v76, v73
	v_fma_f32 v70, -v72, v75, v70
	v_div_fmas_f32 v70, v70, v73, v75
	v_pk_add_f32 v[72:73], v[68:69], 1.0 op_sel_hi:[1,0]
	v_div_fixup_f32 v70, v70, v74, 1.0
	v_div_scale_f32 v75, s[0:1], v73, v73, 1.0
	v_rcp_f32_e32 v76, v75
	v_pk_mul_f32 v[68:69], v[70:71], s[4:5] op_sel_hi:[1,0]
	v_div_scale_f32 v74, s[0:1], v72, v72, 1.0
	v_cvt_pk_f16_f32 v68, v68, v69
	v_fma_f32 v69, -v75, v76, 1.0
	v_fmac_f32_e32 v76, v69, v76
	v_div_scale_f32 v69, vcc, 1.0, v73, 1.0
	v_mul_f32_e32 v70, v69, v76
	v_fma_f32 v71, -v75, v70, v69
	v_fmac_f32_e32 v70, v71, v76
	v_fma_f32 v69, -v75, v70, v69
	v_rcp_f32_e32 v75, v74
	v_div_fmas_f32 v69, v69, v76, v70
	v_div_fixup_f32 v71, v69, v73, 1.0
	s_mov_b32 s0, 0xb0000
	v_fma_f32 v69, -v74, v75, 1.0
	v_fmac_f32_e32 v75, v69, v75
	v_div_scale_f32 v69, vcc, 1.0, v72, 1.0
	v_mul_f32_e32 v70, v69, v75
	v_fma_f32 v73, -v74, v70, v69
	v_fmac_f32_e32 v70, v73, v75
	v_fma_f32 v69, -v74, v70, v69
	v_div_fmas_f32 v69, v69, v75, v70
	v_div_fixup_f32 v70, v69, v72, 1.0
	v_pk_mul_f32 v[70:71], v[70:71], s[4:5] op_sel_hi:[1,0]
	v_lshl_add_u64 v[74:75], v[134:135], 0, s[16:17]
	v_cvt_pk_f16_f32 v69, v70, v71
	v_add_co_u32_e32 v70, vcc, s0, v134
	s_nop 1
	v_addc_co_u32_e32 v71, vcc, 0, v135, vcc
	global_store_dwordx4 v[70:71], v[66:69], off
	global_load_dwordx4 v[66:69], v[148:149], off offset:528
	s_nop 0
	global_load_dwordx4 v[70:73], v[148:149], off offset:512
	s_waitcnt vmcnt(0)
	v_pk_add_f32 v[58:59], v[58:59], v[66:67]
	v_pk_add_f32 v[62:63], v[62:63], v[70:71]
	v_pk_add_f32 v[76:77], v[60:61], v[68:69]
	v_mul_f32_e32 v60, 0xbfb8aa3b, v62
	v_mul_f32_e32 v58, 0xbfb8aa3b, v58
	v_exp_f32_e32 v80, v60
	v_exp_f32_e32 v60, v58
	v_mul_f32_e32 v58, 0xbfb8aa3b, v63
	v_pk_add_f32 v[64:65], v[64:65], v[72:73]
	v_exp_f32_e32 v81, v58
	v_mul_f32_e32 v58, 0xbfb8aa3b, v59
	v_exp_f32_e32 v61, v58
	v_mul_f32_e32 v58, 0xbfb8aa3b, v64
	v_exp_f32_e32 v64, v58
	v_mul_f32_e32 v58, 0xbfb8aa3b, v76
	v_exp_f32_e32 v62, v58
	v_mul_f32_e32 v58, 0xbfb8aa3b, v65
	v_exp_f32_e32 v65, v58
	v_mul_f32_e32 v58, 0xbfb8aa3b, v77
	v_exp_f32_e32 v63, v58
	v_pk_add_f32 v[58:59], v[80:81], 1.0 op_sel_hi:[1,0]
	v_pk_add_f32 v[64:65], v[64:65], 1.0 op_sel_hi:[1,0]
	v_div_scale_f32 v76, s[0:1], v59, v59, 1.0
	v_rcp_f32_e32 v77, v76
	v_pk_add_f32 v[60:61], v[60:61], 1.0 op_sel_hi:[1,0]
	v_pk_add_f32 v[62:63], v[62:63], 1.0 op_sel_hi:[1,0]
	v_fma_f32 v80, -v76, v77, 1.0
	v_fmac_f32_e32 v77, v80, v77
	v_div_scale_f32 v80, vcc, 1.0, v59, 1.0
	v_mul_f32_e32 v81, v80, v77
	v_fma_f32 v82, -v76, v81, v80
	v_fmac_f32_e32 v81, v82, v77
	v_fma_f32 v76, -v76, v81, v80
	v_div_fmas_f32 v76, v76, v77, v81
	v_div_fixup_f32 v59, v76, v59, 1.0
	v_div_scale_f32 v76, s[0:1], v58, v58, 1.0
	v_rcp_f32_e32 v77, v76
	s_nop 0
	v_fma_f32 v80, -v76, v77, 1.0
	v_fmac_f32_e32 v77, v80, v77
	v_div_scale_f32 v80, vcc, 1.0, v58, 1.0
	v_mul_f32_e32 v81, v80, v77
	v_fma_f32 v82, -v76, v81, v80
	v_fmac_f32_e32 v81, v82, v77
	v_fma_f32 v76, -v76, v81, v80
	v_div_fmas_f32 v76, v76, v77, v81
	v_div_fixup_f32 v58, v76, v58, 1.0
	v_pk_mul_f32 v[58:59], v[58:59], s[4:5] op_sel_hi:[1,0]
	s_nop 0
	v_cvt_pk_f16_f32 v58, v58, v59
; __device__ __forceinline__ float sigmoidf_(float x) { return 1.0f / (1.0f + __expf(-x)); }
;     template <int GI>
;     __device__ __forceinline__ void body(const f32x4 (&acc)[2][2][4][2], int row0, int colt) const {
;     ...
;         for (int bj = 0; bj < 2; ++bj) {
;             const int c = colt + bj * 128;
;             f32x4 b0 = (f32x4){0.f, 0.f, 0.f, 0.f}, b1 = b0;
;             if (GI == 0) { b0 = *(const f32x4*)(w0 + c); b1 = *(const f32x4*)(w0 + c + 4); }
;             else if (GI == 1) { b0 = *(const f32x4*)(a0 + c); b1 = *(const f32x4*)(a0 + c + 4); }
;             else if (GI == 3) { b0 = *(const f32x4*)(v0 + c); b1 = *(const f32x4*)(v0 + c + 4); }
; #pragma unroll
;             for (int ai = 0; ai < 2; ++ai)
; #pragma unroll
;                 for (int m = 0; m < 4; ++m) {
;                     const size_t row = (size_t)(row0 + ai * 128 + m * 16);
;                     f32x4 x0 = acc[ai][bj][m][0] + b0, x1 = acc[ai][bj][m][1] + b1;
;                     if (GI == 0) {
; #pragma unroll
;                         for (int j = 0; j < 4; ++j) {
;                             x0[j] = 0.6065306597126334f * sigmoidf_(x0[j]); x1[j] = 0.6065306597126334f * sigmoidf_(x1[j]); }
;                         *(u32x4*)(DEC + row * DM + c) = pack8(x0, x1);
	v_div_scale_f32 v59, s[0:1], v65, v65, 1.0
	v_rcp_f32_e32 v76, v59
	s_nop 0
	v_fma_f32 v77, -v59, v76, 1.0
	v_fmac_f32_e32 v76, v77, v76
	v_div_scale_f32 v77, vcc, 1.0, v65, 1.0
	v_mul_f32_e32 v80, v77, v76
	v_fma_f32 v81, -v59, v80, v77
	v_fmac_f32_e32 v80, v81, v76
	v_fma_f32 v59, -v59, v80, v77
	v_div_fmas_f32 v59, v59, v76, v80
	v_div_fixup_f32 v65, v59, v65, 1.0
	v_div_scale_f32 v59, s[0:1], v64, v64, 1.0
	v_rcp_f32_e32 v76, v59
	s_nop 0
	v_fma_f32 v77, -v59, v76, 1.0
	v_fmac_f32_e32 v76, v77, v76
	v_div_scale_f32 v77, vcc, 1.0, v64, 1.0
	v_mul_f32_e32 v80, v77, v76
	v_fma_f32 v81, -v59, v80, v77
	v_fmac_f32_e32 v80, v81, v76
	v_fma_f32 v59, -v59, v80, v77
	v_div_fmas_f32 v59, v59, v76, v80
	v_div_fixup_f32 v64, v59, v64, 1.0
	v_pk_mul_f32 v[64:65], v[64:65], s[4:5] op_sel_hi:[1,0]
	s_nop 0
	v_cvt_pk_f16_f32 v59, v64, v65
	v_div_scale_f32 v64, s[0:1], v61, v61, 1.0
	v_rcp_f32_e32 v65, v64
	s_nop 0
	v_fma_f32 v76, -v64, v65, 1.0
	v_fmac_f32_e32 v65, v76, v65
	v_div_scale_f32 v76, vcc, 1.0, v61, 1.0
	v_mul_f32_e32 v77, v76, v65
	v_fma_f32 v80, -v64, v77, v76
	v_fmac_f32_e32 v77, v80, v65
	v_fma_f32 v64, -v64, v77, v76
	v_div_fmas_f32 v64, v64, v65, v77
	v_div_fixup_f32 v61, v64, v61, 1.0
	v_div_scale_f32 v64, s[0:1], v60, v60, 1.0
	v_rcp_f32_e32 v65, v64
	s_nop 0
	v_fma_f32 v76, -v64, v65, 1.0
	v_fmac_f32_e32 v65, v76, v65
	v_div_scale_f32 v76, vcc, 1.0, v60, 1.0
	v_mul_f32_e32 v77, v76, v65
	v_fma_f32 v80, -v64, v77, v76
	v_fmac_f32_e32 v77, v80, v65
	v_fma_f32 v64, -v64, v77, v76
	v_div_fmas_f32 v64, v64, v65, v77
	v_div_fixup_f32 v60, v64, v60, 1.0
	v_pk_mul_f32 v[60:61], v[60:61], s[4:5] op_sel_hi:[1,0]
	s_nop 0
	v_cvt_pk_f16_f32 v60, v60, v61
	v_div_scale_f32 v61, s[0:1], v63, v63, 1.0
	v_rcp_f32_e32 v64, v61
	s_nop 0
	v_fma_f32 v65, -v61, v64, 1.0
	v_fmac_f32_e32 v64, v65, v64
	v_div_scale_f32 v65, vcc, 1.0, v63, 1.0
	v_mul_f32_e32 v76, v65, v64
	v_fma_f32 v77, -v61, v76, v65
	v_fmac_f32_e32 v76, v77, v64
	v_fma_f32 v61, -v61, v76, v65
	v_div_fmas_f32 v61, v61, v64, v76
	v_div_fixup_f32 v63, v61, v63, 1.0
	v_div_scale_f32 v61, s[0:1], v62, v62, 1.0
	v_rcp_f32_e32 v64, v61
	s_nop 0
	v_fma_f32 v65, -v61, v64, 1.0
	v_fmac_f32_e32 v64, v65, v64
	v_div_scale_f32 v65, vcc, 1.0, v62, 1.0
	v_mul_f32_e32 v76, v65, v64
	v_fma_f32 v77, -v61, v76, v65
	v_fmac_f32_e32 v76, v77, v64
	v_fma_f32 v61, -v61, v76, v65
	v_div_fmas_f32 v61, v61, v64, v76
	v_div_fixup_f32 v62, v61, v62, 1.0
	v_pk_mul_f32 v[62:63], v[62:63], s[4:5] op_sel_hi:[1,0]
	s_nop 0
	v_cvt_pk_f16_f32 v61, v62, v63
	global_store_dwordx4 v[134:135], v[58:61], off offset:256
	v_pk_add_f32 v[50:51], v[50:51], v[66:67]
	v_pk_add_f32 v[54:55], v[54:55], v[70:71]
	v_mul_f32_e32 v50, 0xbfb8aa3b, v50
	v_exp_f32_e32 v60, v50
	v_mul_f32_e32 v50, 0xbfb8aa3b, v55
	v_pk_add_f32 v[56:57], v[56:57], v[72:73]
	v_mul_f32_e32 v54, 0xbfb8aa3b, v54
	v_exp_f32_e32 v59, v50
	v_mul_f32_e32 v50, 0xbfb8aa3b, v51
	v_pk_add_f32 v[52:53], v[52:53], v[68:69]
	v_exp_f32_e32 v58, v54
	v_exp_f32_e32 v61, v50
	v_mul_f32_e32 v50, 0xbfb8aa3b, v56
	v_exp_f32_e32 v56, v50
	v_mul_f32_e32 v50, 0xbfb8aa3b, v52
	v_exp_f32_e32 v54, v50
	v_mul_f32_e32 v50, 0xbfb8aa3b, v57
	v_exp_f32_e32 v57, v50
	v_mul_f32_e32 v50, 0xbfb8aa3b, v53
	v_exp_f32_e32 v55, v50
	v_pk_add_f32 v[50:51], v[58:59], 1.0 op_sel_hi:[1,0]
	v_pk_add_f32 v[54:55], v[54:55], 1.0 op_sel_hi:[1,0]
	v_div_scale_f32 v52, s[0:1], v51, v51, 1.0
	v_rcp_f32_e32 v53, v52
	s_nop 0
	v_fma_f32 v58, -v52, v53, 1.0
	v_fmac_f32_e32 v53, v58, v53
	v_div_scale_f32 v58, vcc, 1.0, v51, 1.0
	v_mul_f32_e32 v59, v58, v53
	v_fma_f32 v62, -v52, v59, v58
	v_fmac_f32_e32 v59, v62, v53
	v_fma_f32 v52, -v52, v59, v58
	v_div_fmas_f32 v52, v52, v53, v59
	v_div_fixup_f32 v51, v52, v51, 1.0
	v_div_scale_f32 v52, s[0:1], v50, v50, 1.0
	v_rcp_f32_e32 v53, v52
	s_nop 0
	v_fma_f32 v58, -v52, v53, 1.0
	v_fmac_f32_e32 v53, v58, v53
	v_div_scale_f32 v58, vcc, 1.0, v50, 1.0
	v_mul_f32_e32 v59, v58, v53
	v_fma_f32 v62, -v52, v59, v58
	v_fmac_f32_e32 v59, v62, v53
	v_fma_f32 v52, -v52, v59, v58
	v_div_fmas_f32 v52, v52, v53, v59
	v_div_fixup_f32 v50, v52, v50, 1.0
	v_pk_mul_f32 v[50:51], v[50:51], s[4:5] op_sel_hi:[1,0]
	v_pk_add_f32 v[52:53], v[56:57], 1.0 op_sel_hi:[1,0]
	v_cvt_pk_f16_f32 v50, v50, v51
	v_div_scale_f32 v51, s[0:1], v53, v53, 1.0
	v_rcp_f32_e32 v56, v51
	s_nop 0
	v_fma_f32 v57, -v51, v56, 1.0
	v_fmac_f32_e32 v56, v57, v56
	v_div_scale_f32 v57, vcc, 1.0, v53, 1.0
	v_mul_f32_e32 v58, v57, v56
	v_fma_f32 v59, -v51, v58, v57
	v_fmac_f32_e32 v58, v59, v56
	v_fma_f32 v51, -v51, v58, v57
	v_div_fmas_f32 v51, v51, v56, v58
	v_div_fixup_f32 v53, v51, v53, 1.0
	v_div_scale_f32 v51, s[0:1], v52, v52, 1.0
	v_rcp_f32_e32 v56, v51
	s_nop 0
	v_fma_f32 v57, -v51, v56, 1.0
	v_fmac_f32_e32 v56, v57, v56
	v_div_scale_f32 v57, vcc, 1.0, v52, 1.0
	v_mul_f32_e32 v58, v57, v56
	v_fma_f32 v59, -v51, v58, v57
	v_fmac_f32_e32 v58, v59, v56
	v_fma_f32 v51, -v51, v58, v57
	v_div_fmas_f32 v51, v51, v56, v58
	v_div_fixup_f32 v52, v51, v52, 1.0
	v_pk_mul_f32 v[52:53], v[52:53], s[4:5] op_sel_hi:[1,0]
	s_nop 0
	v_cvt_pk_f16_f32 v51, v52, v53
	v_pk_add_f32 v[52:53], v[60:61], 1.0 op_sel_hi:[1,0]
	s_nop 0
	v_div_scale_f32 v56, s[0:1], v53, v53, 1.0
	v_rcp_f32_e32 v57, v56
	s_nop 0
	v_fma_f32 v58, -v56, v57, 1.0
	v_fmac_f32_e32 v57, v58, v57
	v_div_scale_f32 v58, vcc, 1.0, v53, 1.0
	v_mul_f32_e32 v59, v58, v57
	v_fma_f32 v60, -v56, v59, v58
	v_fmac_f32_e32 v59, v60, v57
	v_fma_f32 v56, -v56, v59, v58
	v_div_fmas_f32 v56, v56, v57, v59
	v_div_fixup_f32 v53, v56, v53, 1.0
	v_div_scale_f32 v56, s[0:1], v52, v52, 1.0
	v_rcp_f32_e32 v57, v56
	s_nop 0
	v_fma_f32 v58, -v56, v57, 1.0
	v_fmac_f32_e32 v57, v58, v57
; __device__ __forceinline__ float sigmoidf_(float x) { return 1.0f / (1.0f + __expf(-x)); }
;     template <int GI>
;     __device__ __forceinline__ void body(const f32x4 (&acc)[2][2][4][2], int row0, int colt) const {
;     ...
;         for (int bj = 0; bj < 2; ++bj) {
;             const int c = colt + bj * 128;
;             f32x4 b0 = (f32x4){0.f, 0.f, 0.f, 0.f}, b1 = b0;
;             if (GI == 0) { b0 = *(const f32x4*)(w0 + c); b1 = *(const f32x4*)(w0 + c + 4); }
;             else if (GI == 1) { b0 = *(const f32x4*)(a0 + c); b1 = *(const f32x4*)(a0 + c + 4); }
;             else if (GI == 3) { b0 = *(const f32x4*)(v0 + c); b1 = *(const f32x4*)(v0 + c + 4); }
; #pragma unroll
;             for (int ai = 0; ai < 2; ++ai)
; #pragma unroll
;                 for (int m = 0; m < 4; ++m) {
;                     const size_t row = (size_t)(row0 + ai * 128 + m * 16);
;                     f32x4 x0 = acc[ai][bj][m][0] + b0, x1 = acc[ai][bj][m][1] + b1;
;                     if (GI == 0) {
; #pragma unroll
;                         for (int j = 0; j < 4; ++j) {
;                             x0[j] = 0.6065306597126334f * sigmoidf_(x0[j]); x1[j] = 0.6065306597126334f * sigmoidf_(x1[j]); }
;                         *(u32x4*)(DEC + row * DM + c) = pack8(x0, x1);
	v_div_scale_f32 v58, vcc, 1.0, v52, 1.0
	v_mul_f32_e32 v59, v58, v57
	v_fma_f32 v60, -v56, v59, v58
	v_fmac_f32_e32 v59, v60, v57
	v_fma_f32 v56, -v56, v59, v58
	v_div_fmas_f32 v56, v56, v57, v59
	v_div_fixup_f32 v52, v56, v52, 1.0
	v_pk_mul_f32 v[52:53], v[52:53], s[4:5] op_sel_hi:[1,0]
	s_nop 0
	v_cvt_pk_f16_f32 v52, v52, v53
	v_div_scale_f32 v53, s[0:1], v55, v55, 1.0
	v_rcp_f32_e32 v56, v53
	s_nop 0
	v_fma_f32 v57, -v53, v56, 1.0
	v_fmac_f32_e32 v56, v57, v56
	v_div_scale_f32 v57, vcc, 1.0, v55, 1.0
	v_mul_f32_e32 v58, v57, v56
	v_fma_f32 v59, -v53, v58, v57
	v_fmac_f32_e32 v58, v59, v56
	v_fma_f32 v53, -v53, v58, v57
	v_div_fmas_f32 v53, v53, v56, v58
	v_div_fixup_f32 v55, v53, v55, 1.0
	v_div_scale_f32 v53, s[0:1], v54, v54, 1.0
	v_rcp_f32_e32 v56, v53
	s_nop 0
	v_fma_f32 v57, -v53, v56, 1.0
	v_fmac_f32_e32 v56, v57, v56
	v_div_scale_f32 v57, vcc, 1.0, v54, 1.0
	v_mul_f32_e32 v58, v57, v56
	v_fma_f32 v59, -v53, v58, v57
	v_fmac_f32_e32 v58, v59, v56
	v_fma_f32 v53, -v53, v58, v57
	v_div_fmas_f32 v53, v53, v56, v58
	v_div_fixup_f32 v54, v53, v54, 1.0
	v_pk_mul_f32 v[54:55], v[54:55], s[4:5] op_sel_hi:[1,0]
	s_nop 0
	v_cvt_pk_f16_f32 v53, v54, v55
	global_store_dwordx4 v[126:127], v[50:53], off offset:256
	v_pk_add_f32 v[42:43], v[42:43], v[66:67]
	v_pk_add_f32 v[46:47], v[46:47], v[70:71]
	v_mul_f32_e32 v42, 0xbfb8aa3b, v42
	v_exp_f32_e32 v52, v42
	v_mul_f32_e32 v42, 0xbfb8aa3b, v47
	v_pk_add_f32 v[48:49], v[48:49], v[72:73]
	v_mul_f32_e32 v46, 0xbfb8aa3b, v46
	v_exp_f32_e32 v51, v42
	v_mul_f32_e32 v42, 0xbfb8aa3b, v43
	v_pk_add_f32 v[44:45], v[44:45], v[68:69]
	v_exp_f32_e32 v50, v46
	v_exp_f32_e32 v53, v42
	v_mul_f32_e32 v42, 0xbfb8aa3b, v48
	v_exp_f32_e32 v48, v42
	v_mul_f32_e32 v42, 0xbfb8aa3b, v44
	v_exp_f32_e32 v46, v42
	v_mul_f32_e32 v42, 0xbfb8aa3b, v49
	v_exp_f32_e32 v49, v42
	v_mul_f32_e32 v42, 0xbfb8aa3b, v45
	v_exp_f32_e32 v47, v42
	v_pk_add_f32 v[42:43], v[50:51], 1.0 op_sel_hi:[1,0]
	v_pk_add_f32 v[46:47], v[46:47], 1.0 op_sel_hi:[1,0]
	v_div_scale_f32 v44, s[0:1], v43, v43, 1.0
	v_rcp_f32_e32 v45, v44
	s_nop 0
	v_fma_f32 v50, -v44, v45, 1.0
	v_fmac_f32_e32 v45, v50, v45
	v_div_scale_f32 v50, vcc, 1.0, v43, 1.0
	v_mul_f32_e32 v51, v50, v45
	v_fma_f32 v54, -v44, v51, v50
	v_fmac_f32_e32 v51, v54, v45
	v_fma_f32 v44, -v44, v51, v50
	v_div_fmas_f32 v44, v44, v45, v51
	v_div_fixup_f32 v43, v44, v43, 1.0
	v_div_scale_f32 v44, s[0:1], v42, v42, 1.0
	v_rcp_f32_e32 v45, v44
	s_nop 0
	v_fma_f32 v50, -v44, v45, 1.0
	v_fmac_f32_e32 v45, v50, v45
	v_div_scale_f32 v50, vcc, 1.0, v42, 1.0
	v_mul_f32_e32 v51, v50, v45
	v_fma_f32 v54, -v44, v51, v50
	v_fmac_f32_e32 v51, v54, v45
	v_fma_f32 v44, -v44, v51, v50
	v_div_fmas_f32 v44, v44, v45, v51
	v_div_fixup_f32 v42, v44, v42, 1.0
	v_pk_mul_f32 v[42:43], v[42:43], s[4:5] op_sel_hi:[1,0]
	v_pk_add_f32 v[44:45], v[48:49], 1.0 op_sel_hi:[1,0]
	v_cvt_pk_f16_f32 v42, v42, v43
	v_div_scale_f32 v43, s[0:1], v45, v45, 1.0
	v_rcp_f32_e32 v48, v43
	s_nop 0
	v_fma_f32 v49, -v43, v48, 1.0
	v_fmac_f32_e32 v48, v49, v48
	v_div_scale_f32 v49, vcc, 1.0, v45, 1.0
	v_mul_f32_e32 v50, v49, v48
	v_fma_f32 v51, -v43, v50, v49
	v_fmac_f32_e32 v50, v51, v48
	v_fma_f32 v43, -v43, v50, v49
	v_div_fmas_f32 v43, v43, v48, v50
	v_div_fixup_f32 v45, v43, v45, 1.0
	v_div_scale_f32 v43, s[0:1], v44, v44, 1.0
	v_rcp_f32_e32 v48, v43
	s_nop 0
	v_fma_f32 v49, -v43, v48, 1.0
	v_fmac_f32_e32 v48, v49, v48
	v_div_scale_f32 v49, vcc, 1.0, v44, 1.0
	v_mul_f32_e32 v50, v49, v48
	v_fma_f32 v51, -v43, v50, v49
	v_fmac_f32_e32 v50, v51, v48
	v_fma_f32 v43, -v43, v50, v49
	v_div_fmas_f32 v43, v43, v48, v50
	v_div_fixup_f32 v44, v43, v44, 1.0
	v_pk_mul_f32 v[44:45], v[44:45], s[4:5] op_sel_hi:[1,0]
	s_nop 0
	v_cvt_pk_f16_f32 v43, v44, v45
	v_pk_add_f32 v[44:45], v[52:53], 1.0 op_sel_hi:[1,0]
	s_nop 0
	v_div_scale_f32 v48, s[0:1], v45, v45, 1.0
	v_rcp_f32_e32 v49, v48
	s_nop 0
	v_fma_f32 v50, -v48, v49, 1.0
	v_fmac_f32_e32 v49, v50, v49
	v_div_scale_f32 v50, vcc, 1.0, v45, 1.0
	v_mul_f32_e32 v51, v50, v49
	v_fma_f32 v52, -v48, v51, v50
	v_fmac_f32_e32 v51, v52, v49
	v_fma_f32 v48, -v48, v51, v50
	v_div_fmas_f32 v48, v48, v49, v51
	v_div_fixup_f32 v45, v48, v45, 1.0
	v_div_scale_f32 v48, s[0:1], v44, v44, 1.0
	v_rcp_f32_e32 v49, v48
	s_nop 0
	v_fma_f32 v50, -v48, v49, 1.0
	v_fmac_f32_e32 v49, v50, v49
	v_div_scale_f32 v50, vcc, 1.0, v44, 1.0
	v_mul_f32_e32 v51, v50, v49
	v_fma_f32 v52, -v48, v51, v50
	v_fmac_f32_e32 v51, v52, v49
	v_fma_f32 v48, -v48, v51, v50
	v_div_fmas_f32 v48, v48, v49, v51
	v_div_fixup_f32 v44, v48, v44, 1.0
	v_pk_mul_f32 v[44:45], v[44:45], s[4:5] op_sel_hi:[1,0]
	s_nop 0
	v_cvt_pk_f16_f32 v44, v44, v45
	v_div_scale_f32 v45, s[0:1], v47, v47, 1.0
	v_rcp_f32_e32 v48, v45
	s_nop 0
	v_fma_f32 v49, -v45, v48, 1.0
	v_fmac_f32_e32 v48, v49, v48
	v_div_scale_f32 v49, vcc, 1.0, v47, 1.0
	v_mul_f32_e32 v50, v49, v48
	v_fma_f32 v51, -v45, v50, v49
	v_fmac_f32_e32 v50, v51, v48
	v_fma_f32 v45, -v45, v50, v49
	v_div_fmas_f32 v45, v45, v48, v50
	v_div_fixup_f32 v47, v45, v47, 1.0
	v_div_scale_f32 v45, s[0:1], v46, v46, 1.0
	v_rcp_f32_e32 v48, v45
	s_nop 0
	v_fma_f32 v49, -v45, v48, 1.0
	v_fmac_f32_e32 v48, v49, v48
	v_div_scale_f32 v49, vcc, 1.0, v46, 1.0
	v_mul_f32_e32 v50, v49, v48
	v_fma_f32 v51, -v45, v50, v49
	v_fmac_f32_e32 v50, v51, v48
	v_fma_f32 v45, -v45, v50, v49
	v_div_fmas_f32 v45, v45, v48, v50
	v_div_fixup_f32 v46, v45, v46, 1.0
	v_pk_mul_f32 v[46:47], v[46:47], s[4:5] op_sel_hi:[1,0]
	s_nop 0
	v_cvt_pk_f16_f32 v45, v46, v47
	global_store_dwordx4 v[118:119], v[42:45], off offset:256
	v_pk_add_f32 v[34:35], v[34:35], v[66:67]
	v_pk_add_f32 v[38:39], v[38:39], v[70:71]
	v_mul_f32_e32 v34, 0xbfb8aa3b, v34
; __device__ __forceinline__ float sigmoidf_(float x) { return 1.0f / (1.0f + __expf(-x)); }
;     template <int GI>
;     __device__ __forceinline__ void body(const f32x4 (&acc)[2][2][4][2], int row0, int colt) const {
;     ...
;         for (int bj = 0; bj < 2; ++bj) {
;             const int c = colt + bj * 128;
;             f32x4 b0 = (f32x4){0.f, 0.f, 0.f, 0.f}, b1 = b0;
;             if (GI == 0) { b0 = *(const f32x4*)(w0 + c); b1 = *(const f32x4*)(w0 + c + 4); }
;             else if (GI == 1) { b0 = *(const f32x4*)(a0 + c); b1 = *(const f32x4*)(a0 + c + 4); }
;             else if (GI == 3) { b0 = *(const f32x4*)(v0 + c); b1 = *(const f32x4*)(v0 + c + 4); }
; #pragma unroll
;             for (int ai = 0; ai < 2; ++ai)
; #pragma unroll
;                 for (int m = 0; m < 4; ++m) {
;                     const size_t row = (size_t)(row0 + ai * 128 + m * 16);
;                     f32x4 x0 = acc[ai][bj][m][0] + b0, x1 = acc[ai][bj][m][1] + b1;
;                     if (GI == 0) {
; #pragma unroll
;                         for (int j = 0; j < 4; ++j) {
;                             x0[j] = 0.6065306597126334f * sigmoidf_(x0[j]); x1[j] = 0.6065306597126334f * sigmoidf_(x1[j]); }
;                         *(u32x4*)(DEC + row * DM + c) = pack8(x0, x1);
	v_exp_f32_e32 v44, v34
	v_mul_f32_e32 v34, 0xbfb8aa3b, v39
	v_pk_add_f32 v[40:41], v[40:41], v[72:73]
	v_mul_f32_e32 v38, 0xbfb8aa3b, v38
	v_exp_f32_e32 v43, v34
	v_mul_f32_e32 v34, 0xbfb8aa3b, v35
	v_pk_add_f32 v[36:37], v[36:37], v[68:69]
	v_exp_f32_e32 v42, v38
	v_exp_f32_e32 v45, v34
	v_mul_f32_e32 v34, 0xbfb8aa3b, v40
	v_exp_f32_e32 v40, v34
	v_mul_f32_e32 v34, 0xbfb8aa3b, v36
	v_exp_f32_e32 v38, v34
	v_mul_f32_e32 v34, 0xbfb8aa3b, v41
	v_exp_f32_e32 v41, v34
	v_mul_f32_e32 v34, 0xbfb8aa3b, v37
	v_exp_f32_e32 v39, v34
	v_pk_add_f32 v[34:35], v[42:43], 1.0 op_sel_hi:[1,0]
	v_pk_add_f32 v[38:39], v[38:39], 1.0 op_sel_hi:[1,0]
	v_div_scale_f32 v36, s[0:1], v35, v35, 1.0
	v_rcp_f32_e32 v37, v36
	s_nop 0
	v_fma_f32 v42, -v36, v37, 1.0
	v_fmac_f32_e32 v37, v42, v37
	v_div_scale_f32 v42, vcc, 1.0, v35, 1.0
	v_mul_f32_e32 v43, v42, v37
	v_fma_f32 v46, -v36, v43, v42
	v_fmac_f32_e32 v43, v46, v37
	v_fma_f32 v36, -v36, v43, v42
	v_div_fmas_f32 v36, v36, v37, v43
	v_div_fixup_f32 v35, v36, v35, 1.0
	v_div_scale_f32 v36, s[0:1], v34, v34, 1.0
	v_rcp_f32_e32 v37, v36
	s_nop 0
	v_fma_f32 v42, -v36, v37, 1.0
	v_fmac_f32_e32 v37, v42, v37
	v_div_scale_f32 v42, vcc, 1.0, v34, 1.0
	v_mul_f32_e32 v43, v42, v37
	v_fma_f32 v46, -v36, v43, v42
	v_fmac_f32_e32 v43, v46, v37
	v_fma_f32 v36, -v36, v43, v42
	v_div_fmas_f32 v36, v36, v37, v43
	v_div_fixup_f32 v34, v36, v34, 1.0
	v_pk_mul_f32 v[34:35], v[34:35], s[4:5] op_sel_hi:[1,0]
	v_pk_add_f32 v[36:37], v[40:41], 1.0 op_sel_hi:[1,0]
	v_cvt_pk_f16_f32 v34, v34, v35
	v_div_scale_f32 v35, s[0:1], v37, v37, 1.0
	v_rcp_f32_e32 v40, v35
	s_nop 0
	v_fma_f32 v41, -v35, v40, 1.0
	v_fmac_f32_e32 v40, v41, v40
	v_div_scale_f32 v41, vcc, 1.0, v37, 1.0
	v_mul_f32_e32 v42, v41, v40
	v_fma_f32 v43, -v35, v42, v41
	v_fmac_f32_e32 v42, v43, v40
	v_fma_f32 v35, -v35, v42, v41
	v_div_fmas_f32 v35, v35, v40, v42
	v_div_fixup_f32 v37, v35, v37, 1.0
	v_div_scale_f32 v35, s[0:1], v36, v36, 1.0
	v_rcp_f32_e32 v40, v35
	s_nop 0
	v_fma_f32 v41, -v35, v40, 1.0
	v_fmac_f32_e32 v40, v41, v40
	v_div_scale_f32 v41, vcc, 1.0, v36, 1.0
	v_mul_f32_e32 v42, v41, v40
	v_fma_f32 v43, -v35, v42, v41
	v_fmac_f32_e32 v42, v43, v40
	v_fma_f32 v35, -v35, v42, v41
	v_div_fmas_f32 v35, v35, v40, v42
	v_div_fixup_f32 v36, v35, v36, 1.0
	v_pk_mul_f32 v[36:37], v[36:37], s[4:5] op_sel_hi:[1,0]
	s_nop 0
	v_cvt_pk_f16_f32 v35, v36, v37
	v_pk_add_f32 v[36:37], v[44:45], 1.0 op_sel_hi:[1,0]
	s_nop 0
	v_div_scale_f32 v40, s[0:1], v37, v37, 1.0
	v_rcp_f32_e32 v41, v40
	s_nop 0
	v_fma_f32 v42, -v40, v41, 1.0
	v_fmac_f32_e32 v41, v42, v41
	v_div_scale_f32 v42, vcc, 1.0, v37, 1.0
	v_mul_f32_e32 v43, v42, v41
	v_fma_f32 v44, -v40, v43, v42
	v_fmac_f32_e32 v43, v44, v41
	v_fma_f32 v40, -v40, v43, v42
	v_div_fmas_f32 v40, v40, v41, v43
	v_div_fixup_f32 v37, v40, v37, 1.0
	v_div_scale_f32 v40, s[0:1], v36, v36, 1.0
	v_rcp_f32_e32 v41, v40
	s_nop 0
	v_fma_f32 v42, -v40, v41, 1.0
	v_fmac_f32_e32 v41, v42, v41
	v_div_scale_f32 v42, vcc, 1.0, v36, 1.0
	v_mul_f32_e32 v43, v42, v41
	v_fma_f32 v44, -v40, v43, v42
	v_fmac_f32_e32 v43, v44, v41
	v_fma_f32 v40, -v40, v43, v42
	v_div_fmas_f32 v40, v40, v41, v43
	v_div_fixup_f32 v36, v40, v36, 1.0
	v_pk_mul_f32 v[36:37], v[36:37], s[4:5] op_sel_hi:[1,0]
	s_nop 0
	v_cvt_pk_f16_f32 v36, v36, v37
	v_div_scale_f32 v37, s[0:1], v39, v39, 1.0
	v_rcp_f32_e32 v40, v37
	s_nop 0
	v_fma_f32 v41, -v37, v40, 1.0
	v_fmac_f32_e32 v40, v41, v40
	v_div_scale_f32 v41, vcc, 1.0, v39, 1.0
	v_mul_f32_e32 v42, v41, v40
	v_fma_f32 v43, -v37, v42, v41
	v_fmac_f32_e32 v42, v43, v40
	v_fma_f32 v37, -v37, v42, v41
	v_div_fmas_f32 v37, v37, v40, v42
	v_div_fixup_f32 v39, v37, v39, 1.0
	v_div_scale_f32 v37, s[0:1], v38, v38, 1.0
	v_rcp_f32_e32 v40, v37
	s_nop 0
	v_fma_f32 v41, -v37, v40, 1.0
	v_fmac_f32_e32 v40, v41, v40
	v_div_scale_f32 v41, vcc, 1.0, v38, 1.0
	v_mul_f32_e32 v42, v41, v40
	v_fma_f32 v43, -v37, v42, v41
	v_fmac_f32_e32 v42, v43, v40
	v_fma_f32 v37, -v37, v42, v41
	v_div_fmas_f32 v37, v37, v40, v42
	v_div_fixup_f32 v38, v37, v38, 1.0
	v_pk_mul_f32 v[38:39], v[38:39], s[4:5] op_sel_hi:[1,0]
	s_nop 0
	v_cvt_pk_f16_f32 v37, v38, v39
	global_store_dwordx4 v[110:111], v[34:37], off offset:256
	v_pk_add_f32 v[26:27], v[26:27], v[66:67]
	v_pk_add_f32 v[30:31], v[30:31], v[70:71]
	v_mul_f32_e32 v26, 0xbfb8aa3b, v26
	v_exp_f32_e32 v36, v26
	v_mul_f32_e32 v26, 0xbfb8aa3b, v31
	v_pk_add_f32 v[32:33], v[32:33], v[72:73]
	v_mul_f32_e32 v30, 0xbfb8aa3b, v30
	v_exp_f32_e32 v35, v26
	v_mul_f32_e32 v26, 0xbfb8aa3b, v27
	v_pk_add_f32 v[28:29], v[28:29], v[68:69]
	v_exp_f32_e32 v34, v30
	v_exp_f32_e32 v37, v26
	v_mul_f32_e32 v26, 0xbfb8aa3b, v32
	v_exp_f32_e32 v32, v26
	v_mul_f32_e32 v26, 0xbfb8aa3b, v28
	v_exp_f32_e32 v30, v26
	v_mul_f32_e32 v26, 0xbfb8aa3b, v33
	v_exp_f32_e32 v33, v26
	v_mul_f32_e32 v26, 0xbfb8aa3b, v29
	v_exp_f32_e32 v31, v26
	v_pk_add_f32 v[26:27], v[34:35], 1.0 op_sel_hi:[1,0]
	v_pk_add_f32 v[30:31], v[30:31], 1.0 op_sel_hi:[1,0]
	v_div_scale_f32 v28, s[0:1], v27, v27, 1.0
	v_rcp_f32_e32 v29, v28
	s_nop 0
	v_fma_f32 v34, -v28, v29, 1.0
	v_fmac_f32_e32 v29, v34, v29
	v_div_scale_f32 v34, vcc, 1.0, v27, 1.0
	v_mul_f32_e32 v35, v34, v29
	v_fma_f32 v38, -v28, v35, v34
	v_fmac_f32_e32 v35, v38, v29
	v_fma_f32 v28, -v28, v35, v34
	v_div_fmas_f32 v28, v28, v29, v35
	v_div_fixup_f32 v27, v28, v27, 1.0
	v_div_scale_f32 v28, s[0:1], v26, v26, 1.0
	v_rcp_f32_e32 v29, v28
	s_nop 0
	v_fma_f32 v34, -v28, v29, 1.0
	v_fmac_f32_e32 v29, v34, v29
	v_div_scale_f32 v34, vcc, 1.0, v26, 1.0
	v_mul_f32_e32 v35, v34, v29
	v_fma_f32 v38, -v28, v35, v34
	v_fmac_f32_e32 v35, v38, v29
	v_fma_f32 v28, -v28, v35, v34
	v_div_fmas_f32 v28, v28, v29, v35
; __device__ __forceinline__ float sigmoidf_(float x) { return 1.0f / (1.0f + __expf(-x)); }
;     template <int GI>
;     __device__ __forceinline__ void body(const f32x4 (&acc)[2][2][4][2], int row0, int colt) const {
;     ...
;         for (int bj = 0; bj < 2; ++bj) {
;             const int c = colt + bj * 128;
;             f32x4 b0 = (f32x4){0.f, 0.f, 0.f, 0.f}, b1 = b0;
;             if (GI == 0) { b0 = *(const f32x4*)(w0 + c); b1 = *(const f32x4*)(w0 + c + 4); }
;             else if (GI == 1) { b0 = *(const f32x4*)(a0 + c); b1 = *(const f32x4*)(a0 + c + 4); }
;             else if (GI == 3) { b0 = *(const f32x4*)(v0 + c); b1 = *(const f32x4*)(v0 + c + 4); }
; #pragma unroll
;             for (int ai = 0; ai < 2; ++ai)
; #pragma unroll
;                 for (int m = 0; m < 4; ++m) {
;                     const size_t row = (size_t)(row0 + ai * 128 + m * 16);
;                     f32x4 x0 = acc[ai][bj][m][0] + b0, x1 = acc[ai][bj][m][1] + b1;
;                     if (GI == 0) {
; #pragma unroll
;                         for (int j = 0; j < 4; ++j) {
;                             x0[j] = 0.6065306597126334f * sigmoidf_(x0[j]); x1[j] = 0.6065306597126334f * sigmoidf_(x1[j]); }
;                         *(u32x4*)(DEC + row * DM + c) = pack8(x0, x1);
	v_div_fixup_f32 v26, v28, v26, 1.0
	v_pk_mul_f32 v[26:27], v[26:27], s[4:5] op_sel_hi:[1,0]
	v_pk_add_f32 v[28:29], v[32:33], 1.0 op_sel_hi:[1,0]
	v_cvt_pk_f16_f32 v26, v26, v27
	v_div_scale_f32 v27, s[0:1], v29, v29, 1.0
	v_rcp_f32_e32 v32, v27
	s_nop 0
	v_fma_f32 v33, -v27, v32, 1.0
	v_fmac_f32_e32 v32, v33, v32
	v_div_scale_f32 v33, vcc, 1.0, v29, 1.0
	v_mul_f32_e32 v34, v33, v32
	v_fma_f32 v35, -v27, v34, v33
	v_fmac_f32_e32 v34, v35, v32
	v_fma_f32 v27, -v27, v34, v33
	v_div_fmas_f32 v27, v27, v32, v34
	v_div_fixup_f32 v29, v27, v29, 1.0
	v_div_scale_f32 v27, s[0:1], v28, v28, 1.0
	v_rcp_f32_e32 v32, v27
	s_nop 0
	v_fma_f32 v33, -v27, v32, 1.0
	v_fmac_f32_e32 v32, v33, v32
	v_div_scale_f32 v33, vcc, 1.0, v28, 1.0
	v_mul_f32_e32 v34, v33, v32
	v_fma_f32 v35, -v27, v34, v33
	v_fmac_f32_e32 v34, v35, v32
	v_fma_f32 v27, -v27, v34, v33
	v_div_fmas_f32 v27, v27, v32, v34
	v_div_fixup_f32 v28, v27, v28, 1.0
	v_pk_mul_f32 v[28:29], v[28:29], s[4:5] op_sel_hi:[1,0]
	s_nop 0
	v_cvt_pk_f16_f32 v27, v28, v29
	v_pk_add_f32 v[28:29], v[36:37], 1.0 op_sel_hi:[1,0]
	s_nop 0
	v_div_scale_f32 v32, s[0:1], v29, v29, 1.0
	v_rcp_f32_e32 v33, v32
	s_nop 0
	v_fma_f32 v34, -v32, v33, 1.0
	v_fmac_f32_e32 v33, v34, v33
	v_div_scale_f32 v34, vcc, 1.0, v29, 1.0
	v_mul_f32_e32 v35, v34, v33
	v_fma_f32 v36, -v32, v35, v34
	v_fmac_f32_e32 v35, v36, v33
	v_fma_f32 v32, -v32, v35, v34
	v_div_fmas_f32 v32, v32, v33, v35
	v_div_fixup_f32 v29, v32, v29, 1.0
	v_div_scale_f32 v32, s[0:1], v28, v28, 1.0
	v_rcp_f32_e32 v33, v32
	s_nop 0
	v_fma_f32 v34, -v32, v33, 1.0
	v_fmac_f32_e32 v33, v34, v33
	v_div_scale_f32 v34, vcc, 1.0, v28, 1.0
	v_mul_f32_e32 v35, v34, v33
	v_fma_f32 v36, -v32, v35, v34
	v_fmac_f32_e32 v35, v36, v33
	v_fma_f32 v32, -v32, v35, v34
	v_div_fmas_f32 v32, v32, v33, v35
	v_div_fixup_f32 v28, v32, v28, 1.0
	v_pk_mul_f32 v[28:29], v[28:29], s[4:5] op_sel_hi:[1,0]
	s_nop 0
	v_cvt_pk_f16_f32 v28, v28, v29
	v_div_scale_f32 v29, s[0:1], v31, v31, 1.0
	v_rcp_f32_e32 v32, v29
	s_nop 0
	v_fma_f32 v33, -v29, v32, 1.0
	v_fmac_f32_e32 v32, v33, v32
	v_div_scale_f32 v33, vcc, 1.0, v31, 1.0
	v_mul_f32_e32 v34, v33, v32
	v_fma_f32 v35, -v29, v34, v33
	v_fmac_f32_e32 v34, v35, v32
	v_fma_f32 v29, -v29, v34, v33
	v_div_fmas_f32 v29, v29, v32, v34
	v_div_fixup_f32 v31, v29, v31, 1.0
	v_div_scale_f32 v29, s[0:1], v30, v30, 1.0
	v_rcp_f32_e32 v32, v29
	s_nop 0
	v_fma_f32 v33, -v29, v32, 1.0
	v_fmac_f32_e32 v32, v33, v32
	v_div_scale_f32 v33, vcc, 1.0, v30, 1.0
	v_mul_f32_e32 v34, v33, v32
	v_fma_f32 v35, -v29, v34, v33
	v_fmac_f32_e32 v34, v35, v32
	v_fma_f32 v29, -v29, v34, v33
	v_div_fmas_f32 v29, v29, v32, v34
	v_div_fixup_f32 v30, v29, v30, 1.0
	v_pk_mul_f32 v[30:31], v[30:31], s[4:5] op_sel_hi:[1,0]
	s_nop 0
	v_cvt_pk_f16_f32 v29, v30, v31
	global_store_dwordx4 v[102:103], v[26:29], off offset:256
	v_pk_add_f32 v[18:19], v[18:19], v[66:67]
	v_pk_add_f32 v[22:23], v[22:23], v[70:71]
	v_mul_f32_e32 v18, 0xbfb8aa3b, v18
	v_exp_f32_e32 v28, v18
	v_mul_f32_e32 v18, 0xbfb8aa3b, v23
	v_pk_add_f32 v[24:25], v[24:25], v[72:73]
	v_mul_f32_e32 v22, 0xbfb8aa3b, v22
	v_exp_f32_e32 v27, v18
	v_mul_f32_e32 v18, 0xbfb8aa3b, v19
	v_pk_add_f32 v[20:21], v[20:21], v[68:69]
	v_exp_f32_e32 v26, v22
	v_exp_f32_e32 v29, v18
	v_mul_f32_e32 v18, 0xbfb8aa3b, v24
	v_exp_f32_e32 v24, v18
	v_mul_f32_e32 v18, 0xbfb8aa3b, v20
	v_exp_f32_e32 v22, v18
	v_mul_f32_e32 v18, 0xbfb8aa3b, v25
	v_exp_f32_e32 v25, v18
	v_mul_f32_e32 v18, 0xbfb8aa3b, v21
	v_exp_f32_e32 v23, v18
	v_pk_add_f32 v[18:19], v[26:27], 1.0 op_sel_hi:[1,0]
	v_pk_add_f32 v[22:23], v[22:23], 1.0 op_sel_hi:[1,0]
	v_div_scale_f32 v20, s[0:1], v19, v19, 1.0
	v_rcp_f32_e32 v21, v20
	s_nop 0
	v_fma_f32 v26, -v20, v21, 1.0
	v_fmac_f32_e32 v21, v26, v21
	v_div_scale_f32 v26, vcc, 1.0, v19, 1.0
	v_mul_f32_e32 v27, v26, v21
	v_fma_f32 v30, -v20, v27, v26
	v_fmac_f32_e32 v27, v30, v21
	v_fma_f32 v20, -v20, v27, v26
	v_div_fmas_f32 v20, v20, v21, v27
	v_div_fixup_f32 v19, v20, v19, 1.0
	v_div_scale_f32 v20, s[0:1], v18, v18, 1.0
	v_rcp_f32_e32 v21, v20
	s_nop 0
	v_fma_f32 v26, -v20, v21, 1.0
	v_fmac_f32_e32 v21, v26, v21
	v_div_scale_f32 v26, vcc, 1.0, v18, 1.0
	v_mul_f32_e32 v27, v26, v21
	v_fma_f32 v30, -v20, v27, v26
	v_fmac_f32_e32 v27, v30, v21
	v_fma_f32 v20, -v20, v27, v26
	v_div_fmas_f32 v20, v20, v21, v27
	v_div_fixup_f32 v18, v20, v18, 1.0
	v_pk_mul_f32 v[18:19], v[18:19], s[4:5] op_sel_hi:[1,0]
	v_pk_add_f32 v[20:21], v[24:25], 1.0 op_sel_hi:[1,0]
	v_cvt_pk_f16_f32 v18, v18, v19
	v_div_scale_f32 v19, s[0:1], v21, v21, 1.0
	v_rcp_f32_e32 v24, v19
	s_nop 0
	v_fma_f32 v25, -v19, v24, 1.0
	v_fmac_f32_e32 v24, v25, v24
	v_div_scale_f32 v25, vcc, 1.0, v21, 1.0
	v_mul_f32_e32 v26, v25, v24
	v_fma_f32 v27, -v19, v26, v25
	v_fmac_f32_e32 v26, v27, v24
	v_fma_f32 v19, -v19, v26, v25
	v_div_fmas_f32 v19, v19, v24, v26
	v_div_fixup_f32 v21, v19, v21, 1.0
	v_div_scale_f32 v19, s[0:1], v20, v20, 1.0
	v_rcp_f32_e32 v24, v19
	s_nop 0
	v_fma_f32 v25, -v19, v24, 1.0
	v_fmac_f32_e32 v24, v25, v24
	v_div_scale_f32 v25, vcc, 1.0, v20, 1.0
	v_mul_f32_e32 v26, v25, v24
	v_fma_f32 v27, -v19, v26, v25
	v_fmac_f32_e32 v26, v27, v24
	v_fma_f32 v19, -v19, v26, v25
	v_div_fmas_f32 v19, v19, v24, v26
	v_div_fixup_f32 v20, v19, v20, 1.0
	v_pk_mul_f32 v[20:21], v[20:21], s[4:5] op_sel_hi:[1,0]
	s_nop 0
	v_cvt_pk_f16_f32 v19, v20, v21
	v_pk_add_f32 v[20:21], v[28:29], 1.0 op_sel_hi:[1,0]
	s_nop 0
	v_div_scale_f32 v24, s[0:1], v21, v21, 1.0
	v_rcp_f32_e32 v25, v24
	s_nop 0
	v_fma_f32 v26, -v24, v25, 1.0
	v_fmac_f32_e32 v25, v26, v25
	v_div_scale_f32 v26, vcc, 1.0, v21, 1.0
	v_mul_f32_e32 v27, v26, v25
	v_fma_f32 v28, -v24, v27, v26
	v_fmac_f32_e32 v27, v28, v25
; __device__ __forceinline__ float sigmoidf_(float x) { return 1.0f / (1.0f + __expf(-x)); }
;     template <int GI>
;     __device__ __forceinline__ void body(const f32x4 (&acc)[2][2][4][2], int row0, int colt) const {
;     ...
;         for (int bj = 0; bj < 2; ++bj) {
;             const int c = colt + bj * 128;
;             f32x4 b0 = (f32x4){0.f, 0.f, 0.f, 0.f}, b1 = b0;
;             if (GI == 0) { b0 = *(const f32x4*)(w0 + c); b1 = *(const f32x4*)(w0 + c + 4); }
;             else if (GI == 1) { b0 = *(const f32x4*)(a0 + c); b1 = *(const f32x4*)(a0 + c + 4); }
;             else if (GI == 3) { b0 = *(const f32x4*)(v0 + c); b1 = *(const f32x4*)(v0 + c + 4); }
; #pragma unroll
;             for (int ai = 0; ai < 2; ++ai)
; #pragma unroll
;                 for (int m = 0; m < 4; ++m) {
;                     const size_t row = (size_t)(row0 + ai * 128 + m * 16);
;                     f32x4 x0 = acc[ai][bj][m][0] + b0, x1 = acc[ai][bj][m][1] + b1;
;                     if (GI == 0) {
; #pragma unroll
;                         for (int j = 0; j < 4; ++j) {
;                             x0[j] = 0.6065306597126334f * sigmoidf_(x0[j]); x1[j] = 0.6065306597126334f * sigmoidf_(x1[j]); }
;                         *(u32x4*)(DEC + row * DM + c) = pack8(x0, x1);
	v_fma_f32 v24, -v24, v27, v26
	v_div_fmas_f32 v24, v24, v25, v27
	v_div_fixup_f32 v21, v24, v21, 1.0
	v_div_scale_f32 v24, s[0:1], v20, v20, 1.0
	v_rcp_f32_e32 v25, v24
	s_nop 0
	v_fma_f32 v26, -v24, v25, 1.0
	v_fmac_f32_e32 v25, v26, v25
	v_div_scale_f32 v26, vcc, 1.0, v20, 1.0
	v_mul_f32_e32 v27, v26, v25
	v_fma_f32 v28, -v24, v27, v26
	v_fmac_f32_e32 v27, v28, v25
	v_fma_f32 v24, -v24, v27, v26
	v_div_fmas_f32 v24, v24, v25, v27
	v_div_fixup_f32 v20, v24, v20, 1.0
	v_pk_mul_f32 v[20:21], v[20:21], s[4:5] op_sel_hi:[1,0]
	s_nop 0
	v_cvt_pk_f16_f32 v20, v20, v21
	v_div_scale_f32 v21, s[0:1], v23, v23, 1.0
	v_rcp_f32_e32 v24, v21
	s_nop 0
	v_fma_f32 v25, -v21, v24, 1.0
	v_fmac_f32_e32 v24, v25, v24
	v_div_scale_f32 v25, vcc, 1.0, v23, 1.0
	v_mul_f32_e32 v26, v25, v24
	v_fma_f32 v27, -v21, v26, v25
	v_fmac_f32_e32 v26, v27, v24
	v_fma_f32 v21, -v21, v26, v25
	v_div_fmas_f32 v21, v21, v24, v26
	v_div_fixup_f32 v23, v21, v23, 1.0
	v_div_scale_f32 v21, s[0:1], v22, v22, 1.0
	v_rcp_f32_e32 v24, v21
	s_nop 0
	v_fma_f32 v25, -v21, v24, 1.0
	v_fmac_f32_e32 v24, v25, v24
	v_div_scale_f32 v25, vcc, 1.0, v22, 1.0
	v_mul_f32_e32 v26, v25, v24
	v_fma_f32 v27, -v21, v26, v25
	v_fmac_f32_e32 v26, v27, v24
	v_fma_f32 v21, -v21, v26, v25
	v_div_fmas_f32 v21, v21, v24, v26
	v_div_fixup_f32 v22, v21, v22, 1.0
	v_pk_mul_f32 v[22:23], v[22:23], s[4:5] op_sel_hi:[1,0]
	s_nop 0
	v_cvt_pk_f16_f32 v21, v22, v23
	global_store_dwordx4 v[86:87], v[18:21], off offset:256
	v_pk_add_f32 v[10:11], v[10:11], v[66:67]
	v_pk_add_f32 v[14:15], v[14:15], v[70:71]
	v_mul_f32_e32 v10, 0xbfb8aa3b, v10
	v_exp_f32_e32 v20, v10
	v_mul_f32_e32 v10, 0xbfb8aa3b, v15
	v_pk_add_f32 v[16:17], v[16:17], v[72:73]
	v_mul_f32_e32 v14, 0xbfb8aa3b, v14
	v_exp_f32_e32 v19, v10
	v_mul_f32_e32 v10, 0xbfb8aa3b, v11
	v_pk_add_f32 v[12:13], v[12:13], v[68:69]
	v_exp_f32_e32 v18, v14
	v_exp_f32_e32 v21, v10
	v_mul_f32_e32 v10, 0xbfb8aa3b, v16
	v_exp_f32_e32 v16, v10
	v_mul_f32_e32 v10, 0xbfb8aa3b, v12
	v_exp_f32_e32 v14, v10
	v_mul_f32_e32 v10, 0xbfb8aa3b, v17
	v_exp_f32_e32 v17, v10
	v_mul_f32_e32 v10, 0xbfb8aa3b, v13
	v_exp_f32_e32 v15, v10
	v_pk_add_f32 v[10:11], v[18:19], 1.0 op_sel_hi:[1,0]
	v_pk_add_f32 v[14:15], v[14:15], 1.0 op_sel_hi:[1,0]
	v_div_scale_f32 v12, s[0:1], v11, v11, 1.0
	v_rcp_f32_e32 v13, v12
	s_nop 0
	v_fma_f32 v18, -v12, v13, 1.0
	v_fmac_f32_e32 v13, v18, v13
	v_div_scale_f32 v18, vcc, 1.0, v11, 1.0
	v_mul_f32_e32 v19, v18, v13
	v_fma_f32 v22, -v12, v19, v18
	v_fmac_f32_e32 v19, v22, v13
	v_fma_f32 v12, -v12, v19, v18
	v_div_fmas_f32 v12, v12, v13, v19
	v_div_fixup_f32 v11, v12, v11, 1.0
	v_div_scale_f32 v12, s[0:1], v10, v10, 1.0
	v_rcp_f32_e32 v13, v12
	s_nop 0
	v_fma_f32 v18, -v12, v13, 1.0
	v_fmac_f32_e32 v13, v18, v13
	v_div_scale_f32 v18, vcc, 1.0, v10, 1.0
	v_mul_f32_e32 v19, v18, v13
	v_fma_f32 v22, -v12, v19, v18
	v_fmac_f32_e32 v19, v22, v13
	v_fma_f32 v12, -v12, v19, v18
	v_div_fmas_f32 v12, v12, v13, v19
	v_div_fixup_f32 v10, v12, v10, 1.0
	v_pk_mul_f32 v[10:11], v[10:11], s[4:5] op_sel_hi:[1,0]
	v_pk_add_f32 v[12:13], v[16:17], 1.0 op_sel_hi:[1,0]
	v_cvt_pk_f16_f32 v10, v10, v11
	v_div_scale_f32 v11, s[0:1], v13, v13, 1.0
	v_rcp_f32_e32 v16, v11
	s_nop 0
	v_fma_f32 v17, -v11, v16, 1.0
	v_fmac_f32_e32 v16, v17, v16
	v_div_scale_f32 v17, vcc, 1.0, v13, 1.0
	v_mul_f32_e32 v18, v17, v16
	v_fma_f32 v19, -v11, v18, v17
	v_fmac_f32_e32 v18, v19, v16
	v_fma_f32 v11, -v11, v18, v17
	v_div_fmas_f32 v11, v11, v16, v18
	v_div_fixup_f32 v13, v11, v13, 1.0
	v_div_scale_f32 v11, s[0:1], v12, v12, 1.0
	v_rcp_f32_e32 v16, v11
	s_nop 0
	v_fma_f32 v17, -v11, v16, 1.0
	v_fmac_f32_e32 v16, v17, v16
	v_div_scale_f32 v17, vcc, 1.0, v12, 1.0
	v_mul_f32_e32 v18, v17, v16
	v_fma_f32 v19, -v11, v18, v17
	v_fmac_f32_e32 v18, v19, v16
	v_fma_f32 v11, -v11, v18, v17
	v_div_fmas_f32 v11, v11, v16, v18
	v_div_fixup_f32 v12, v11, v12, 1.0
	v_pk_mul_f32 v[12:13], v[12:13], s[4:5] op_sel_hi:[1,0]
	s_nop 0
	v_cvt_pk_f16_f32 v11, v12, v13
	v_pk_add_f32 v[12:13], v[20:21], 1.0 op_sel_hi:[1,0]
	s_nop 0
	v_div_scale_f32 v16, s[0:1], v13, v13, 1.0
	v_rcp_f32_e32 v17, v16
	s_nop 0
	v_fma_f32 v18, -v16, v17, 1.0
	v_fmac_f32_e32 v17, v18, v17
	v_div_scale_f32 v18, vcc, 1.0, v13, 1.0
	v_mul_f32_e32 v19, v18, v17
	v_fma_f32 v20, -v16, v19, v18
	v_fmac_f32_e32 v19, v20, v17
	v_fma_f32 v16, -v16, v19, v18
	v_div_fmas_f32 v16, v16, v17, v19
	v_div_fixup_f32 v13, v16, v13, 1.0
	v_div_scale_f32 v16, s[0:1], v12, v12, 1.0
	v_rcp_f32_e32 v17, v16
	s_nop 0
	v_fma_f32 v18, -v16, v17, 1.0
	v_fmac_f32_e32 v17, v18, v17
	v_div_scale_f32 v18, vcc, 1.0, v12, 1.0
	v_mul_f32_e32 v19, v18, v17
	v_fma_f32 v20, -v16, v19, v18
	v_fmac_f32_e32 v19, v20, v17
	v_fma_f32 v16, -v16, v19, v18
	v_div_fmas_f32 v16, v16, v17, v19
	v_div_fixup_f32 v12, v16, v12, 1.0
	v_pk_mul_f32 v[12:13], v[12:13], s[4:5] op_sel_hi:[1,0]
	s_nop 0
	v_cvt_pk_f16_f32 v12, v12, v13
	v_div_scale_f32 v13, s[0:1], v15, v15, 1.0
	v_rcp_f32_e32 v16, v13
	s_nop 0
	v_fma_f32 v17, -v13, v16, 1.0
; __device__ __forceinline__ float sigmoidf_(float x) { return 1.0f / (1.0f + __expf(-x)); }
; template <class Epi, class AMap>
; __device__ __forceinline__ void gemm_phase(LAS unsigned char* lds, const AMap am, const int lda, const h16* Bt, const int ldb, const int M, const int N, const int K, const Epi& E) {
;     ...
;         E(acc, cur, wr, wc, fr, fq);
;         if (!has_next) break;
; #pragma unroll
;         for (int a = 0; a < 2; ++a)
; #pragma unroll
;             for (int b = 0; b < 2; ++b)
; #pragma unroll
;                 for (int m = 0; m < 4; ++m)
; #pragma unroll
;                     for (int n = 0; n < 2; ++n) acc[a][b][m][n] = (f32x4){0.f, 0.f, 0.f, 0.f};
;         cur = nxt; cA = nA; cB = nB; ++ui;
;     template <int GI>
;     __device__ __forceinline__ void body(const f32x4 (&acc)[2][2][4][2], int row0, int colt) const {
;     ...
;         for (int bj = 0; bj < 2; ++bj) {
;             const int c = colt + bj * 128;
;             f32x4 b0 = (f32x4){0.f, 0.f, 0.f, 0.f}, b1 = b0;
;             if (GI == 0) { b0 = *(const f32x4*)(w0 + c); b1 = *(const f32x4*)(w0 + c + 4); }
;             else if (GI == 1) { b0 = *(const f32x4*)(a0 + c); b1 = *(const f32x4*)(a0 + c + 4); }
;             else if (GI == 3) { b0 = *(const f32x4*)(v0 + c); b1 = *(const f32x4*)(v0 + c + 4); }
; #pragma unroll
;             for (int ai = 0; ai < 2; ++ai)
; #pragma unroll
;                 for (int m = 0; m < 4; ++m) {
;                     const size_t row = (size_t)(row0 + ai * 128 + m * 16);
;                     f32x4 x0 = acc[ai][bj][m][0] + b0, x1 = acc[ai][bj][m][1] + b1;
;                     if (GI == 0) {
; #pragma unroll
;                         for (int j = 0; j < 4; ++j) {
;                             x0[j] = 0.6065306597126334f * sigmoidf_(x0[j]); x1[j] = 0.6065306597126334f * sigmoidf_(x1[j]); }
;                         *(u32x4*)(DEC + row * DM + c) = pack8(x0, x1);
	v_fmac_f32_e32 v16, v17, v16
	v_div_scale_f32 v17, vcc, 1.0, v15, 1.0
	v_mul_f32_e32 v18, v17, v16
	v_fma_f32 v19, -v13, v18, v17
	v_fmac_f32_e32 v18, v19, v16
	v_fma_f32 v13, -v13, v18, v17
	v_div_fmas_f32 v13, v13, v16, v18
	v_div_fixup_f32 v15, v13, v15, 1.0
	v_div_scale_f32 v13, s[0:1], v14, v14, 1.0
	v_rcp_f32_e32 v16, v13
	s_nop 0
	v_fma_f32 v17, -v13, v16, 1.0
	v_fmac_f32_e32 v16, v17, v16
	v_div_scale_f32 v17, vcc, 1.0, v14, 1.0
	v_mul_f32_e32 v18, v17, v16
	v_fma_f32 v19, -v13, v18, v17
	v_fmac_f32_e32 v18, v19, v16
	v_fma_f32 v13, -v13, v18, v17
	v_div_fmas_f32 v13, v13, v16, v18
	v_div_fixup_f32 v14, v13, v14, 1.0
	v_pk_mul_f32 v[14:15], v[14:15], s[4:5] op_sel_hi:[1,0]
	s_nop 0
	v_cvt_pk_f16_f32 v13, v14, v15
	global_store_dwordx4 v[78:79], v[10:13], off offset:256
	v_pk_add_f32 v[2:3], v[2:3], v[66:67]
	v_pk_add_f32 v[6:7], v[6:7], v[70:71]
	v_mul_f32_e32 v2, 0xbfb8aa3b, v2
	v_exp_f32_e32 v12, v2
	v_mul_f32_e32 v2, 0xbfb8aa3b, v7
	v_pk_add_f32 v[8:9], v[8:9], v[72:73]
	v_mul_f32_e32 v6, 0xbfb8aa3b, v6
	v_exp_f32_e32 v11, v2
	v_mul_f32_e32 v2, 0xbfb8aa3b, v3
	v_pk_add_f32 v[4:5], v[4:5], v[68:69]
	v_exp_f32_e32 v10, v6
	v_exp_f32_e32 v13, v2
	v_mul_f32_e32 v2, 0xbfb8aa3b, v8
	v_exp_f32_e32 v8, v2
	v_mul_f32_e32 v2, 0xbfb8aa3b, v4
	v_exp_f32_e32 v6, v2
	v_mul_f32_e32 v2, 0xbfb8aa3b, v9
	v_exp_f32_e32 v9, v2
	v_mul_f32_e32 v2, 0xbfb8aa3b, v5
	v_exp_f32_e32 v7, v2
	v_pk_add_f32 v[2:3], v[10:11], 1.0 op_sel_hi:[1,0]
	v_pk_add_f32 v[6:7], v[6:7], 1.0 op_sel_hi:[1,0]
	v_div_scale_f32 v4, s[0:1], v3, v3, 1.0
	v_rcp_f32_e32 v5, v4
	s_nop 0
	v_fma_f32 v10, -v4, v5, 1.0
	v_fmac_f32_e32 v5, v10, v5
	v_div_scale_f32 v10, vcc, 1.0, v3, 1.0
	v_mul_f32_e32 v11, v10, v5
	v_fma_f32 v14, -v4, v11, v10
	v_fmac_f32_e32 v11, v14, v5
	v_fma_f32 v4, -v4, v11, v10
	v_div_fmas_f32 v4, v4, v5, v11
	v_div_fixup_f32 v3, v4, v3, 1.0
	v_div_scale_f32 v4, s[0:1], v2, v2, 1.0
	v_rcp_f32_e32 v5, v4
	s_nop 0
	v_fma_f32 v10, -v4, v5, 1.0
	v_fmac_f32_e32 v5, v10, v5
	v_div_scale_f32 v10, vcc, 1.0, v2, 1.0
	v_mul_f32_e32 v11, v10, v5
	v_fma_f32 v14, -v4, v11, v10
	v_fmac_f32_e32 v11, v14, v5
	v_fma_f32 v4, -v4, v11, v10
	v_div_fmas_f32 v4, v4, v5, v11
	v_div_fixup_f32 v2, v4, v2, 1.0
	v_pk_mul_f32 v[2:3], v[2:3], s[4:5] op_sel_hi:[1,0]
	v_pk_add_f32 v[4:5], v[8:9], 1.0 op_sel_hi:[1,0]
	v_cvt_pk_f16_f32 v2, v2, v3
	v_div_scale_f32 v3, s[0:1], v5, v5, 1.0
	v_rcp_f32_e32 v8, v3
	s_nop 0
	v_fma_f32 v9, -v3, v8, 1.0
	v_fmac_f32_e32 v8, v9, v8
	v_div_scale_f32 v9, vcc, 1.0, v5, 1.0
	v_mul_f32_e32 v10, v9, v8
	v_fma_f32 v11, -v3, v10, v9
	v_fmac_f32_e32 v10, v11, v8
	v_fma_f32 v3, -v3, v10, v9
	v_div_fmas_f32 v3, v3, v8, v10
	v_div_fixup_f32 v5, v3, v5, 1.0
	v_div_scale_f32 v3, s[0:1], v4, v4, 1.0
	v_rcp_f32_e32 v8, v3
	s_nop 0
	v_fma_f32 v9, -v3, v8, 1.0
	v_fmac_f32_e32 v8, v9, v8
	v_div_scale_f32 v9, vcc, 1.0, v4, 1.0
	v_mul_f32_e32 v10, v9, v8
	v_fma_f32 v11, -v3, v10, v9
	v_fmac_f32_e32 v10, v11, v8
	v_fma_f32 v3, -v3, v10, v9
	v_div_fmas_f32 v3, v3, v8, v10
	v_div_fixup_f32 v4, v3, v4, 1.0
	v_pk_mul_f32 v[4:5], v[4:5], s[4:5] op_sel_hi:[1,0]
	s_nop 0
	v_cvt_pk_f16_f32 v3, v4, v5
	v_pk_add_f32 v[4:5], v[12:13], 1.0 op_sel_hi:[1,0]
	s_nop 0
	v_div_scale_f32 v8, s[0:1], v5, v5, 1.0
	v_rcp_f32_e32 v9, v8
	s_nop 0
	v_fma_f32 v10, -v8, v9, 1.0
	v_fmac_f32_e32 v9, v10, v9
	v_div_scale_f32 v10, vcc, 1.0, v5, 1.0
	v_mul_f32_e32 v11, v10, v9
	v_fma_f32 v12, -v8, v11, v10
	v_fmac_f32_e32 v11, v12, v9
	v_fma_f32 v8, -v8, v11, v10
	v_div_fmas_f32 v8, v8, v9, v11
	v_div_fixup_f32 v5, v8, v5, 1.0
	v_div_scale_f32 v8, s[0:1], v4, v4, 1.0
	v_rcp_f32_e32 v9, v8
	s_nop 0
	v_fma_f32 v10, -v8, v9, 1.0
	v_fmac_f32_e32 v9, v10, v9
	v_div_scale_f32 v10, vcc, 1.0, v4, 1.0
	v_mul_f32_e32 v11, v10, v9
	v_fma_f32 v12, -v8, v11, v10
	v_fmac_f32_e32 v11, v12, v9
	v_fma_f32 v8, -v8, v11, v10
	v_div_fmas_f32 v8, v8, v9, v11
	v_div_fixup_f32 v4, v8, v4, 1.0
	v_pk_mul_f32 v[4:5], v[4:5], s[4:5] op_sel_hi:[1,0]
	s_nop 0
	v_cvt_pk_f16_f32 v4, v4, v5
	v_div_scale_f32 v5, s[0:1], v7, v7, 1.0
	v_rcp_f32_e32 v8, v5
	s_nop 0
	v_fma_f32 v9, -v5, v8, 1.0
	v_fmac_f32_e32 v8, v9, v8
	v_div_scale_f32 v9, vcc, 1.0, v7, 1.0
	v_mul_f32_e32 v10, v9, v8
	v_fma_f32 v11, -v5, v10, v9
	v_fmac_f32_e32 v10, v11, v8
	v_fma_f32 v5, -v5, v10, v9
	v_div_fmas_f32 v5, v5, v8, v10
	v_div_fixup_f32 v7, v5, v7, 1.0
	v_div_scale_f32 v5, s[0:1], v6, v6, 1.0
	v_rcp_f32_e32 v8, v5
	s_nop 0
	v_fma_f32 v9, -v5, v8, 1.0
	v_fmac_f32_e32 v8, v9, v8
	v_div_scale_f32 v9, vcc, 1.0, v6, 1.0
	v_mul_f32_e32 v10, v9, v8
	v_fma_f32 v11, -v5, v10, v9
	v_fmac_f32_e32 v10, v11, v8
	v_fma_f32 v5, -v5, v10, v9
	v_div_fmas_f32 v5, v5, v8, v10
	v_div_fixup_f32 v6, v5, v6, 1.0
	v_pk_mul_f32 v[6:7], v[6:7], s[4:5] op_sel_hi:[1,0]
	s_nop 0
	v_cvt_pk_f16_f32 v5, v6, v7
	global_store_dwordx4 v[74:75], v[2:5], off offset:256
	s_and_b64 vcc, exec, s[38:39]
	s_mov_b32 s50, s44
	s_mov_b32 s35, s96
	s_mov_b64 s[26:27], s[68:69]
	s_mov_b64 s[22:23], s[64:65]
	s_cmpk_lt_u32 s71, 0x100
	s_cbranch_scc1 .Lgy4
	s_barrier

; #define PG8_STAGE(bufoff, gbase, voff) do { _Pragma("unroll") for (int _i = 0; _i < 2; ++_i) \
;         __builtin_amdgcn_global_load_lds((const unsigned*)((const char*)(gbase) + (voff)[_i]), (LAS unsigned*)(lds + (bufoff) + ldsw + _i * 8192), 16, 0, 0); } while (0)
; #define PG8_LDA(dst, b, h) do { _Pragma("unroll") for (int m = 0; m < 4; ++m) _Pragma("unroll") for (int k = 0; k < 2; ++k) dst[m][k] = *(const LAS h16x8*)(lds + PG8_SA(b, h) + aoff + m * 2048 + k * 1024); } while (0)
; #define PG8_LDB(dst, b, h) do { _Pragma("unroll") for (int n = 0; n < 2; ++n) _Pragma("unroll") for (int k = 0; k < 2; ++k) dst[n][k] = *(const LAS h16x8*)(lds + PG8_SB(b, h) + boff + n * 2048 + k * 1024); } while (0)
; #define PG8_MMA(ai, bj, At, Bt_) do { __builtin_amdgcn_s_setprio(1); _Pragma("unroll") for (int m = 0; m < 4; ++m) _Pragma("unroll") for (int n = 0; n < 2; ++n) _Pragma("unroll") for (int k = 0; k < 2; ++k) \
;         acc[ai][bj][m][n] = __builtin_amdgcn_mfma_f32_16x16x32_f16(Bt_[n][k], At[m][k], acc[ai][bj][m][n], 0, 0, 0); __builtin_amdgcn_s_setprio(0); } while (0)
; #define PG8_WAIT_V(n) asm volatile("s_waitcnt vmcnt(" #n ")" ::: "memory")
; template <class Epi, class AMap>
; __device__ __forceinline__ void gemm_phase(LAS unsigned char* lds, const AMap am, const int lda, const h16* Bt, const int ldb, const int M, const int N, const int K, const Epi& E) {
;     ...
;         for (int t = 0; t < nt; t += 2) {
;             const bool last = (t == nt - 2);
;             const char* a1 = cA + (size_t)(t + 1) * kstep;
;             const char* a2 = last ? nA : cA + (size_t)(t + 2) * kstep; const char* b2 = last ? nB : cB + (size_t)(t + 2) * kstep;
;             const char* a3 = a2 + kstep; const char* b3 = b2 + kstep;
;             PG8_LDB(B0, 0, 0); PG8_SCHED; PG8_LDA(At, 0, 0); PG8_STAGE(PG8_SA(1, 1), a1 + hstepA, voffA);
;             PG8_WAIT_L(8); PG8_BAR; PG8_WAIT_L(0); PG8_MMA(0, 0, At, B0); PG8_BAR; PG8_SCHED;
;             PG8_LDB(B1, 0, 1); PG8_STAGE(PG8_SB(0, 0), b2, voffB);
;             PG8_BAR; PG8_WAIT_L(0); PG8_MMA(0, 1, At, B1); PG8_BAR;
;             PG8_LDA(At, 0, 1); PG8_STAGE(PG8_SA(0, 0), a2, voffA);
;             PG8_BAR; PG8_WAIT_L(0); PG8_MMA(1, 0, At, B0); PG8_BAR; PG8_SCHED;
;             PG8_STAGE(PG8_SB(0, 1), b2 + hstepB, voffB);
;             PG8_WAIT_V(6); PG8_BAR; PG8_MMA(1, 1, At, B1); PG8_BAR;
.LBB0_621:
	s_add_i32 s51, s26, 2
	s_add_u32 s0, s22, 0x100
	s_addc_u32 s1, s23, 0
	s_add_i32 s60, 0, 0x10000
	v_add_u32_e32 v152, s60, v155
	ds_read_b128 v[90:93], v152
	ds_read_b128 v[94:97], v152 offset:1024
	ds_read_b128 v[148:151], v152 offset:2048
	ds_read_b128 v[158:161], v152 offset:3072
	s_cmp_eq_u32 s82, s26
	s_cselect_b32 s26, s21, s29
	s_cselect_b32 s49, s65, s1
	s_cselect_b32 s48, s64, s0
	s_cselect_b32 s27, s20, s45
	v_lshl_add_u64 v[152:153], s[22:23], 0, v[144:145]
	s_add_i32 m0, s76, 0xc000
	ds_read_b128 v[162:165], v157
	ds_read_b128 v[166:169], v157 offset:1024
	ds_read_b128 v[170:173], v157 offset:2048
	ds_read_b128 v[174:177], v157 offset:3072
	ds_read_b128 v[178:181], v157 offset:4096
	ds_read_b128 v[182:185], v157 offset:5120
	ds_read_b128 v[186:189], v157 offset:6144
	ds_read_b128 v[190:193], v157 offset:7168
	global_load_lds_dwordx4 v[152:153], off
	v_lshl_add_u64 v[152:153], s[22:23], 0, v[146:147]
	s_add_i32 m0, s76, 0xe000
	s_nop 0
	global_load_lds_dwordx4 v[152:153], off
	s_waitcnt lgkmcnt(11)
	s_add_i32 s62, 0, 0x14000
	v_add_u32_e32 v152, s62, v155
	s_add_i32 s22, s60, s73
	ds_read_b128 v[194:197], v152
	ds_read_b128 v[198:201], v152 offset:1024
	ds_read_b128 v[202:205], v152 offset:2048
	ds_read_b128 v[220:223], v152 offset:3072
	s_waitcnt vmcnt(8) lgkmcnt(0)
	s_barrier
	v_mfma_f32_16x16x32_f16 v[130:133], v[90:93], v[162:165], v[130:133]
	v_mfma_f32_16x16x32_f16 v[134:137], v[148:151], v[162:165], v[134:137]
	v_mfma_f32_16x16x32_f16 v[126:129], v[90:93], v[170:173], v[126:129]
	v_mfma_f32_16x16x32_f16 v[122:125], v[148:151], v[170:173], v[122:125]
	v_mfma_f32_16x16x32_f16 v[118:121], v[90:93], v[178:181], v[118:121]
	v_mfma_f32_16x16x32_f16 v[114:117], v[148:151], v[178:181], v[114:117]
	v_mfma_f32_16x16x32_f16 v[110:113], v[90:93], v[186:189], v[110:113]
	v_mfma_f32_16x16x32_f16 v[106:109], v[148:151], v[186:189], v[106:109]
	v_mfma_f32_16x16x32_f16 v[130:133], v[94:97], v[166:169], v[130:133]
	v_mfma_f32_16x16x32_f16 v[134:137], v[158:161], v[166:169], v[134:137]
	v_mfma_f32_16x16x32_f16 v[126:129], v[94:97], v[174:177], v[126:129]
	v_mfma_f32_16x16x32_f16 v[122:125], v[158:161], v[174:177], v[122:125]
	v_mfma_f32_16x16x32_f16 v[118:121], v[94:97], v[182:185], v[118:121]
	v_mfma_f32_16x16x32_f16 v[114:117], v[158:161], v[182:185], v[114:117]
	v_mfma_f32_16x16x32_f16 v[110:113], v[94:97], v[190:193], v[110:113]
	v_mfma_f32_16x16x32_f16 v[106:109], v[158:161], v[190:193], v[106:109]
	v_mfma_f32_16x16x32_f16 v[62:65], v[194:197], v[162:165], v[62:65]
	v_mfma_f32_16x16x32_f16 v[58:61], v[202:205], v[162:165], v[58:61]
	v_mfma_f32_16x16x32_f16 v[54:57], v[194:197], v[170:173], v[54:57]
	v_mfma_f32_16x16x32_f16 v[50:53], v[202:205], v[170:173], v[50:53]
	v_mfma_f32_16x16x32_f16 v[46:49], v[194:197], v[178:181], v[46:49]
	v_mfma_f32_16x16x32_f16 v[42:45], v[202:205], v[178:181], v[42:45]
	v_mfma_f32_16x16x32_f16 v[38:41], v[194:197], v[186:189], v[38:41]
	v_mfma_f32_16x16x32_f16 v[34:37], v[202:205], v[186:189], v[34:37]
	v_mfma_f32_16x16x32_f16 v[62:65], v[198:201], v[166:169], v[62:65]
	v_mfma_f32_16x16x32_f16 v[58:61], v[220:223], v[166:169], v[58:61]
	v_mfma_f32_16x16x32_f16 v[54:57], v[198:201], v[174:177], v[54:57]
	v_mfma_f32_16x16x32_f16 v[50:53], v[220:223], v[174:177], v[50:53]
	v_mfma_f32_16x16x32_f16 v[46:49], v[198:201], v[182:185], v[46:49]
	v_mfma_f32_16x16x32_f16 v[42:45], v[220:223], v[182:185], v[42:45]
	v_mfma_f32_16x16x32_f16 v[38:41], v[198:201], v[190:193], v[38:41]
	v_mfma_f32_16x16x32_f16 v[34:37], v[220:223], v[190:193], v[34:37]
	s_barrier
	v_lshl_add_u64 v[152:153], s[26:27], 0, v[0:1]
	s_mov_b32 m0, s22
	v_lshl_add_u64 v[206:207], s[26:27], 0, v[142:143]
	global_load_lds_dwordx4 v[152:153], off
	s_add_i32 m0, s22, 0x2000
	s_nop 0
	global_load_lds_dwordx4 v[206:207], off
	s_mov_b32 m0, s76
	v_lshl_add_u64 v[212:213], s[48:49], 0, v[138:139]
	ds_read_b128 v[162:165], v157 offset:16384
	ds_read_b128 v[166:169], v157 offset:17408
	ds_read_b128 v[170:173], v157 offset:18432
	ds_read_b128 v[174:177], v157 offset:19456
	ds_read_b128 v[178:181], v157 offset:20480
	ds_read_b128 v[182:185], v157 offset:21504
	ds_read_b128 v[186:189], v157 offset:22528
	ds_read_b128 v[190:193], v157 offset:23552
	global_load_lds_dwordx4 v[212:213], off
	v_lshl_add_u64 v[224:225], s[48:49], 0, v[140:141]
	s_mov_b32 m0, s77
	s_nop 0
	global_load_lds_dwordx4 v[224:225], off
	s_add_u32 s22, s26, 0x10000
	s_addc_u32 s23, s27, 0
	s_add_i32 s60, s62, s73
	v_lshl_add_u64 v[232:233], s[22:23], 0, v[0:1]
	s_mov_b32 m0, s60
	s_nop 0
	global_load_lds_dwordx4 v[232:233], off
	v_lshl_add_u64 v[232:233], s[22:23], 0, v[142:143]
	s_add_i32 m0, s60, 0x2000
	s_nop 0
	global_load_lds_dwordx4 v[232:233], off
	s_waitcnt vmcnt(8) lgkmcnt(0)
	s_barrier
; #define PG8_STAGE(bufoff, gbase, voff) do { _Pragma("unroll") for (int _i = 0; _i < 2; ++_i) \
;         __builtin_amdgcn_global_load_lds((const unsigned*)((const char*)(gbase) + (voff)[_i]), (LAS unsigned*)(lds + (bufoff) + ldsw + _i * 8192), 16, 0, 0); } while (0)
; #define PG8_LDA(dst, b, h) do { _Pragma("unroll") for (int m = 0; m < 4; ++m) _Pragma("unroll") for (int k = 0; k < 2; ++k) dst[m][k] = *(const LAS h16x8*)(lds + PG8_SA(b, h) + aoff + m * 2048 + k * 1024); } while (0)
; #define PG8_LDB(dst, b, h) do { _Pragma("unroll") for (int n = 0; n < 2; ++n) _Pragma("unroll") for (int k = 0; k < 2; ++k) dst[n][k] = *(const LAS h16x8*)(lds + PG8_SB(b, h) + boff + n * 2048 + k * 1024); } while (0)
; #define PG8_MMA(ai, bj, At, Bt_) do { __builtin_amdgcn_s_setprio(1); _Pragma("unroll") for (int m = 0; m < 4; ++m) _Pragma("unroll") for (int n = 0; n < 2; ++n) _Pragma("unroll") for (int k = 0; k < 2; ++k) \
;         acc[ai][bj][m][n] = __builtin_amdgcn_mfma_f32_16x16x32_f16(Bt_[n][k], At[m][k], acc[ai][bj][m][n], 0, 0, 0); __builtin_amdgcn_s_setprio(0); } while (0)
; #define PG8_WAIT_V(n) asm volatile("s_waitcnt vmcnt(" #n ")" ::: "memory")
; #define PG8_WAIT_L(n) asm volatile("s_waitcnt lgkmcnt(" #n ")" ::: "memory")
; #define PG8_BAR __builtin_amdgcn_s_barrier()
; #define PG8_SCHED __builtin_amdgcn_sched_barrier(0)
; template <class Epi, class AMap>
; __device__ __forceinline__ void gemm_phase(LAS unsigned char* lds, const AMap am, const int lda, const h16* Bt, const int ldb, const int M, const int N, const int K, const Epi& E) {
;     ...
;             PG8_WAIT_V(6); PG8_BAR; PG8_MMA(1, 1, At, B1); PG8_BAR;
;             PG8_LDB(B0, 1, 0); PG8_SCHED; PG8_LDA(At, 1, 0); PG8_STAGE(PG8_SA(0, 1), a2 + hstepA, voffA);
;             PG8_WAIT_L(8); PG8_BAR; PG8_WAIT_L(0); PG8_MMA(0, 0, At, B0); PG8_BAR; PG8_SCHED;
;             PG8_LDB(B1, 1, 1); PG8_STAGE(PG8_SB(1, 0), b3, voffB);
;             PG8_BAR; PG8_WAIT_L(0); PG8_MMA(0, 1, At, B1); PG8_BAR;
	v_mfma_f32_16x16x32_f16 v[102:105], v[90:93], v[162:165], v[102:105]
	v_mfma_f32_16x16x32_f16 v[98:101], v[148:151], v[162:165], v[98:101]
	v_mfma_f32_16x16x32_f16 v[86:89], v[90:93], v[170:173], v[86:89]
	v_mfma_f32_16x16x32_f16 v[82:85], v[148:151], v[170:173], v[82:85]
	v_mfma_f32_16x16x32_f16 v[78:81], v[90:93], v[178:181], v[78:81]
	v_mfma_f32_16x16x32_f16 v[74:77], v[148:151], v[178:181], v[74:77]
	v_mfma_f32_16x16x32_f16 v[70:73], v[90:93], v[186:189], v[70:73]
	v_mfma_f32_16x16x32_f16 v[66:69], v[148:151], v[186:189], v[66:69]
	v_mfma_f32_16x16x32_f16 v[102:105], v[94:97], v[166:169], v[102:105]
	v_mfma_f32_16x16x32_f16 v[98:101], v[158:161], v[166:169], v[98:101]
	v_mfma_f32_16x16x32_f16 v[86:89], v[94:97], v[174:177], v[86:89]
	v_mfma_f32_16x16x32_f16 v[82:85], v[158:161], v[174:177], v[82:85]
	v_mfma_f32_16x16x32_f16 v[78:81], v[94:97], v[182:185], v[78:81]
	v_mfma_f32_16x16x32_f16 v[74:77], v[158:161], v[182:185], v[74:77]
	v_mfma_f32_16x16x32_f16 v[70:73], v[94:97], v[190:193], v[70:73]
	v_mfma_f32_16x16x32_f16 v[66:69], v[158:161], v[190:193], v[66:69]
	v_mfma_f32_16x16x32_f16 v[30:33], v[194:197], v[162:165], v[30:33]
	v_mfma_f32_16x16x32_f16 v[26:29], v[202:205], v[162:165], v[26:29]
	v_mfma_f32_16x16x32_f16 v[22:25], v[194:197], v[170:173], v[22:25]
	v_mfma_f32_16x16x32_f16 v[18:21], v[202:205], v[170:173], v[18:21]
	v_mfma_f32_16x16x32_f16 v[14:17], v[194:197], v[178:181], v[14:17]
	v_mfma_f32_16x16x32_f16 v[10:13], v[202:205], v[178:181], v[10:13]
	v_mfma_f32_16x16x32_f16 v[6:9], v[194:197], v[186:189], v[6:9]
	v_mfma_f32_16x16x32_f16 v[2:5], v[202:205], v[186:189], v[2:5]
	v_mfma_f32_16x16x32_f16 v[30:33], v[198:201], v[166:169], v[30:33]
	v_mfma_f32_16x16x32_f16 v[26:29], v[220:223], v[166:169], v[26:29]
	v_mfma_f32_16x16x32_f16 v[22:25], v[198:201], v[174:177], v[22:25]
	v_mfma_f32_16x16x32_f16 v[18:21], v[220:223], v[174:177], v[18:21]
	v_mfma_f32_16x16x32_f16 v[14:17], v[198:201], v[182:185], v[14:17]
	v_mfma_f32_16x16x32_f16 v[10:13], v[220:223], v[182:185], v[10:13]
	v_mfma_f32_16x16x32_f16 v[6:9], v[198:201], v[190:193], v[6:9]
	v_mfma_f32_16x16x32_f16 v[2:5], v[220:223], v[190:193], v[2:5]
	s_barrier
	s_add_i32 s60, 0, 0x18000
	v_add_u32_e32 v234, s60, v155
	ds_read_b128 v[90:93], v234
	ds_read_b128 v[94:97], v234 offset:1024
	ds_read_b128 v[148:151], v234 offset:2048
	ds_read_b128 v[158:161], v234 offset:3072
	s_add_u32 s22, s48, 0x1c0000
	s_addc_u32 s23, s49, 0
	s_mov_b32 m0, s78
	v_lshl_add_u64 v[232:233], s[22:23], 0, v[138:139]
	ds_read_b128 v[162:165], v157 offset:32768
	ds_read_b128 v[166:169], v157 offset:33792
	ds_read_b128 v[170:173], v157 offset:34816
	ds_read_b128 v[174:177], v157 offset:35840
	ds_read_b128 v[178:181], v157 offset:36864
	ds_read_b128 v[182:185], v157 offset:37888
	ds_read_b128 v[186:189], v157 offset:38912
	ds_read_b128 v[190:193], v157 offset:39936
	global_load_lds_dwordx4 v[232:233], off
	v_lshl_add_u64 v[232:233], s[22:23], 0, v[140:141]
	s_mov_b32 m0, s79
	s_nop 0
	global_load_lds_dwordx4 v[232:233], off
	s_waitcnt lgkmcnt(11)
	s_add_i32 s48, 0, 0x1c000
	s_add_i32 s22, s60, s73
	v_add_u32_e32 v214, s48, v155
	v_lshl_add_u64 v[152:153], v[152:153], 0, s[92:93]
	s_mov_b32 m0, s22
	ds_read_b128 v[194:197], v214
	ds_read_b128 v[198:201], v214 offset:1024
	ds_read_b128 v[202:205], v214 offset:2048
	ds_read_b128 v[220:223], v214 offset:3072
	s_waitcnt vmcnt(8) lgkmcnt(0)
	s_barrier
	v_mfma_f32_16x16x32_f16 v[130:133], v[90:93], v[162:165], v[130:133]
	v_mfma_f32_16x16x32_f16 v[134:137], v[148:151], v[162:165], v[134:137]
	v_mfma_f32_16x16x32_f16 v[126:129], v[90:93], v[170:173], v[126:129]
	v_mfma_f32_16x16x32_f16 v[122:125], v[148:151], v[170:173], v[122:125]
	v_mfma_f32_16x16x32_f16 v[118:121], v[90:93], v[178:181], v[118:121]
	v_mfma_f32_16x16x32_f16 v[114:117], v[148:151], v[178:181], v[114:117]
	v_mfma_f32_16x16x32_f16 v[110:113], v[90:93], v[186:189], v[110:113]
	v_mfma_f32_16x16x32_f16 v[106:109], v[148:151], v[186:189], v[106:109]
	v_mfma_f32_16x16x32_f16 v[130:133], v[94:97], v[166:169], v[130:133]
	v_mfma_f32_16x16x32_f16 v[134:137], v[158:161], v[166:169], v[134:137]
	v_mfma_f32_16x16x32_f16 v[126:129], v[94:97], v[174:177], v[126:129]
	v_mfma_f32_16x16x32_f16 v[122:125], v[158:161], v[174:177], v[122:125]
	v_mfma_f32_16x16x32_f16 v[118:121], v[94:97], v[182:185], v[118:121]
	v_mfma_f32_16x16x32_f16 v[114:117], v[158:161], v[182:185], v[114:117]
	v_mfma_f32_16x16x32_f16 v[110:113], v[94:97], v[190:193], v[110:113]
	v_mfma_f32_16x16x32_f16 v[106:109], v[158:161], v[190:193], v[106:109]
	v_mfma_f32_16x16x32_f16 v[62:65], v[194:197], v[162:165], v[62:65]
	v_mfma_f32_16x16x32_f16 v[58:61], v[202:205], v[162:165], v[58:61]
	v_mfma_f32_16x16x32_f16 v[54:57], v[194:197], v[170:173], v[54:57]
	v_mfma_f32_16x16x32_f16 v[50:53], v[202:205], v[170:173], v[50:53]
	v_mfma_f32_16x16x32_f16 v[46:49], v[194:197], v[178:181], v[46:49]
	v_mfma_f32_16x16x32_f16 v[42:45], v[202:205], v[178:181], v[42:45]
	v_mfma_f32_16x16x32_f16 v[38:41], v[194:197], v[186:189], v[38:41]
	v_mfma_f32_16x16x32_f16 v[34:37], v[202:205], v[186:189], v[34:37]
	v_mfma_f32_16x16x32_f16 v[62:65], v[198:201], v[166:169], v[62:65]
	v_mfma_f32_16x16x32_f16 v[58:61], v[220:223], v[166:169], v[58:61]
	v_mfma_f32_16x16x32_f16 v[54:57], v[198:201], v[174:177], v[54:57]
	v_mfma_f32_16x16x32_f16 v[50:53], v[220:223], v[174:177], v[50:53]
	v_mfma_f32_16x16x32_f16 v[46:49], v[198:201], v[182:185], v[46:49]
	v_mfma_f32_16x16x32_f16 v[42:45], v[220:223], v[182:185], v[42:45]
	v_mfma_f32_16x16x32_f16 v[38:41], v[198:201], v[190:193], v[38:41]
	v_mfma_f32_16x16x32_f16 v[34:37], v[220:223], v[190:193], v[34:37]
	s_barrier
; #define PG8_STAGE(bufoff, gbase, voff) do { _Pragma("unroll") for (int _i = 0; _i < 2; ++_i) \
;         __builtin_amdgcn_global_load_lds((const unsigned*)((const char*)(gbase) + (voff)[_i]), (LAS unsigned*)(lds + (bufoff) + ldsw + _i * 8192), 16, 0, 0); } while (0)
; #define PG8_LDA(dst, b, h) do { _Pragma("unroll") for (int m = 0; m < 4; ++m) _Pragma("unroll") for (int k = 0; k < 2; ++k) dst[m][k] = *(const LAS h16x8*)(lds + PG8_SA(b, h) + aoff + m * 2048 + k * 1024); } while (0)
; #define PG8_MMA(ai, bj, At, Bt_) do { __builtin_amdgcn_s_setprio(1); _Pragma("unroll") for (int m = 0; m < 4; ++m) _Pragma("unroll") for (int n = 0; n < 2; ++n) _Pragma("unroll") for (int k = 0; k < 2; ++k) \
;         acc[ai][bj][m][n] = __builtin_amdgcn_mfma_f32_16x16x32_f16(Bt_[n][k], At[m][k], acc[ai][bj][m][n], 0, 0, 0); __builtin_amdgcn_s_setprio(0); } while (0)
; #define PG8_WAIT_V(n) asm volatile("s_waitcnt vmcnt(" #n ")" ::: "memory")
; #define PG8_WAIT_L(n) asm volatile("s_waitcnt lgkmcnt(" #n ")" ::: "memory")
; #define PG8_BAR __builtin_amdgcn_s_barrier()
; #define PG8_SCHED __builtin_amdgcn_sched_barrier(0)
; template <class Epi, class AMap>
; __device__ __forceinline__ void gemm_phase(LAS unsigned char* lds, const AMap am, const int lda, const h16* Bt, const int ldb, const int M, const int N, const int K, const Epi& E) {
;     ...
;             PG8_BAR; PG8_WAIT_L(0); PG8_MMA(0, 1, At, B1); PG8_BAR;
;             PG8_LDA(At, 1, 1); PG8_STAGE(PG8_SA(1, 0), a3, voffA);
;             PG8_BAR; PG8_WAIT_L(0); PG8_MMA(1, 0, At, B0); PG8_BAR; PG8_SCHED;
;             PG8_STAGE(PG8_SB(1, 1), b3 + hstepB, voffB);
;             PG8_WAIT_V(6); PG8_BAR; PG8_MMA(1, 1, At, B1); PG8_BAR;
;         }
	global_load_lds_dwordx4 v[152:153], off
	v_lshl_add_u64 v[152:153], v[206:207], 0, s[92:93]
	s_add_i32 m0, s22, 0x2000
	s_nop 0
	global_load_lds_dwordx4 v[152:153], off
	s_mov_b32 m0, s80
	v_lshl_add_u64 v[152:153], v[212:213], 0, s[92:93]
	ds_read_b128 v[162:165], v157 offset:49152
	ds_read_b128 v[166:169], v157 offset:50176
	ds_read_b128 v[170:173], v157 offset:51200
	ds_read_b128 v[174:177], v157 offset:52224
	ds_read_b128 v[178:181], v157 offset:53248
	ds_read_b128 v[182:185], v157 offset:54272
	ds_read_b128 v[186:189], v157 offset:55296
	ds_read_b128 v[190:193], v157 offset:56320
	global_load_lds_dwordx4 v[152:153], off
	v_lshl_add_u64 v[152:153], v[224:225], 0, s[92:93]
	s_mov_b32 m0, s81
	s_nop 0
	global_load_lds_dwordx4 v[152:153], off
	s_add_u32 s22, s26, 0x10080
	s_addc_u32 s23, s27, 0
	s_add_i32 s26, s48, s73
	v_lshl_add_u64 v[232:233], s[22:23], 0, v[0:1]
	s_mov_b32 m0, s26
	s_nop 0
	global_load_lds_dwordx4 v[232:233], off
	v_lshl_add_u64 v[232:233], s[22:23], 0, v[142:143]
	s_add_i32 m0, s26, 0x2000
	s_nop 0
	global_load_lds_dwordx4 v[232:233], off
	s_waitcnt vmcnt(8) lgkmcnt(0)
	s_barrier
	v_mfma_f32_16x16x32_f16 v[102:105], v[90:93], v[162:165], v[102:105]
	v_mfma_f32_16x16x32_f16 v[98:101], v[148:151], v[162:165], v[98:101]
	v_mfma_f32_16x16x32_f16 v[86:89], v[90:93], v[170:173], v[86:89]
	v_mfma_f32_16x16x32_f16 v[82:85], v[148:151], v[170:173], v[82:85]
	v_mfma_f32_16x16x32_f16 v[78:81], v[90:93], v[178:181], v[78:81]
	v_mfma_f32_16x16x32_f16 v[74:77], v[148:151], v[178:181], v[74:77]
	v_mfma_f32_16x16x32_f16 v[70:73], v[90:93], v[186:189], v[70:73]
	v_mfma_f32_16x16x32_f16 v[66:69], v[148:151], v[186:189], v[66:69]
	v_mfma_f32_16x16x32_f16 v[102:105], v[94:97], v[166:169], v[102:105]
	v_mfma_f32_16x16x32_f16 v[98:101], v[158:161], v[166:169], v[98:101]
	v_mfma_f32_16x16x32_f16 v[86:89], v[94:97], v[174:177], v[86:89]
	v_mfma_f32_16x16x32_f16 v[82:85], v[158:161], v[174:177], v[82:85]
	v_mfma_f32_16x16x32_f16 v[78:81], v[94:97], v[182:185], v[78:81]
	v_mfma_f32_16x16x32_f16 v[74:77], v[158:161], v[182:185], v[74:77]
	v_mfma_f32_16x16x32_f16 v[70:73], v[94:97], v[190:193], v[70:73]
	v_mfma_f32_16x16x32_f16 v[66:69], v[158:161], v[190:193], v[66:69]
	v_mfma_f32_16x16x32_f16 v[30:33], v[194:197], v[162:165], v[30:33]
	v_mfma_f32_16x16x32_f16 v[26:29], v[202:205], v[162:165], v[26:29]
	v_mfma_f32_16x16x32_f16 v[22:25], v[194:197], v[170:173], v[22:25]
	v_mfma_f32_16x16x32_f16 v[18:21], v[202:205], v[170:173], v[18:21]
	v_mfma_f32_16x16x32_f16 v[14:17], v[194:197], v[178:181], v[14:17]
	v_mfma_f32_16x16x32_f16 v[10:13], v[202:205], v[178:181], v[10:13]
	v_mfma_f32_16x16x32_f16 v[6:9], v[194:197], v[186:189], v[6:9]
	v_mfma_f32_16x16x32_f16 v[2:5], v[202:205], v[186:189], v[2:5]
	v_mfma_f32_16x16x32_f16 v[30:33], v[198:201], v[166:169], v[30:33]
	v_mfma_f32_16x16x32_f16 v[26:29], v[220:223], v[166:169], v[26:29]
	v_mfma_f32_16x16x32_f16 v[22:25], v[198:201], v[174:177], v[22:25]
	v_mfma_f32_16x16x32_f16 v[18:21], v[220:223], v[174:177], v[18:21]
	v_mfma_f32_16x16x32_f16 v[14:17], v[198:201], v[182:185], v[14:17]
	v_mfma_f32_16x16x32_f16 v[10:13], v[220:223], v[182:185], v[10:13]
	v_mfma_f32_16x16x32_f16 v[6:9], v[198:201], v[190:193], v[6:9]
	v_mfma_f32_16x16x32_f16 v[2:5], v[220:223], v[190:193], v[2:5]
	s_add_u32 s29, s29, 0x100
	s_addc_u32 s45, s45, 0
	s_cmp_ge_i32 s51, s24
	s_mov_b64 s[22:23], s[0:1]
	s_mov_b32 s26, s51
	s_barrier
	s_cbranch_scc0 .LBB0_621
	s_cmpk_gt_u32 s71, 0xff
	s_cbranch_scc1 .Lgx4
	s_barrier

; __device__ __forceinline__ float sigmoidf_(float x) { return 1.0f / (1.0f + __expf(-x)); }
;     __device__ __forceinline__ void body_a(const f32x4 (&acc)[2][2][4][2], int row0, int cb0) const {
;     ...
;             for (int m = 0; m < 4; ++m) {
;                 const size_t row = (size_t)(row0 + ai * 128 + m * 16);
;                 asm volatile("" ::: "memory");
;                 float a[2][8], kv[2][8], kk[2][8]; float ss = 0.f;
; #pragma unroll
;                 for (int bj = 0; bj < 2; ++bj) {
;                     const int c = cb0 + 32 * bj;
;                     const f32x4 b0 = *(const f32x4*)(a0 + c), b1 = *(const f32x4*)(a0 + c + 4), q0 = *(const f32x4*)(k_k + c), q1 = *(const f32x4*)(k_k + c + 4);
;                     const h16x8 kh = *(const h16x8*)(C1 + row * LDC1 + 2048 + c);
; #pragma unroll
;                     for (int e = 0; e < 4; ++e) {
;                         a[bj][e] = sigmoidf_(acc[ai][bj][m][0][e] + b0[e]); a[bj][4 + e] = sigmoidf_(acc[ai][bj][m][1][e] + b1[e]);
;                         kv[bj][e] = (float)kh[e]; kv[bj][4 + e] = (float)kh[4 + e];
;                         kk[bj][e] = kv[bj][e] * q0[e]; kk[bj][4 + e] = kv[bj][4 + e] * q1[e];
;                         ss += kk[bj][e] * kk[bj][e] + kk[bj][4 + e] * kk[bj][4 + e];
;                     }
.LBB0_633:
	v_lshl_or_b32 v170, s50, 8, v204
	v_ashrrev_i32_e32 v171, 31, v170
	v_lshlrev_b64 v[198:199], 2, v[170:171]
	v_lshl_add_u64 v[154:155], s[40:41], 0, v[198:199]
	global_load_dwordx4 v[162:165], v[154:155], off offset:16
	global_load_dwordx4 v[166:169], v[154:155], off
	v_lshl_add_u32 v158, s35, 8, v202
	v_mov_b64_e32 v[160:161], s[8:9]
	v_mad_i64_i32 v[130:131], s[0:1], v158, s5, v[160:161]
	s_mov_b64 s[6:7], 0x1000
	v_readlane_b32 s0, v255, 15
	v_lshl_add_u64 v[172:173], v[130:131], 0, s[6:7]
	v_readlane_b32 s1, v255, 16
	v_lshlrev_b64 v[152:153], 1, v[170:171]
	v_lshl_add_u64 v[184:185], v[172:173], 0, v[152:153]
	v_lshl_add_u64 v[156:157], s[0:1], 0, v[198:199]
	global_load_dwordx4 v[130:133], v[156:157], off offset:16
	global_load_dwordx4 v[134:137], v[156:157], off
	global_load_dwordx4 v[138:141], v[184:185], off
	v_readlane_b32 s0, v255, 13
	v_readlane_b32 s1, v255, 14
	s_mov_b32 s4, 0xf800000
	v_ashrrev_i32_e32 v159, 31, v158
	v_readlane_b32 s10, v254, 60
	v_readlane_b32 s11, v254, 61
	s_waitcnt vmcnt(0)
	v_add_f32_e32 v122, v122, v166
	v_mul_f32_e32 v122, 0xbfb8aa3b, v122
	v_exp_f32_e32 v196, v122
	v_add_f32_e32 v122, v126, v162
	v_mul_f32_e32 v122, 0xbfb8aa3b, v122
	v_exp_f32_e32 v192, v122
	v_add_f32_e32 v122, v123, v167
	v_mul_f32_e32 v122, 0xbfb8aa3b, v122
	v_exp_f32_e32 v197, v122
	v_add_f32_e32 v122, v127, v163
	v_mul_f32_e32 v122, 0xbfb8aa3b, v122
	v_exp_f32_e32 v193, v122
	v_add_f32_e32 v122, v124, v168
	v_mul_f32_e32 v122, 0xbfb8aa3b, v122
	v_exp_f32_e32 v194, v122
	v_add_f32_e32 v122, v128, v164
	v_mul_f32_e32 v122, 0xbfb8aa3b, v122
	v_exp_f32_e32 v186, v122
	v_add_f32_e32 v122, v125, v169
	v_mul_f32_e32 v122, 0xbfb8aa3b, v122
	v_exp_f32_e32 v195, v122
	v_add_f32_e32 v122, v129, v165
	v_mul_f32_e32 v122, 0xbfb8aa3b, v122
	v_exp_f32_e32 v187, v122
	v_or_b32_e32 v122, 32, v170
	v_ashrrev_i32_e32 v123, 31, v122
	v_lshlrev_b64 v[128:129], 1, v[122:123]
	v_lshl_add_u64 v[122:123], v[172:173], 0, v[128:129]
	global_load_dwordx4 v[124:127], v[154:155], off offset:144
	global_load_dwordx4 v[162:165], v[154:155], off offset:128
	global_load_dwordx4 v[188:191], v[156:157], off offset:144
	global_load_dwordx4 v[220:223], v[156:157], off offset:128
	global_load_dwordx4 v[166:169], v[122:123], off
	v_pk_add_f32 v[196:197], v[196:197], 1.0 op_sel_hi:[1,0]
	s_waitcnt vmcnt(0)
	v_add_f32_e32 v114, v114, v124
	v_mul_f32_e32 v114, 0xbfb8aa3b, v114
	v_exp_f32_e32 v174, v114
	v_add_f32_e32 v114, v119, v163
	v_cvt_f32_f16_e32 v172, v168
	v_cvt_f32_f16_sdwa v173, v168 dst_sel:DWORD dst_unused:UNUSED_PAD src0_sel:WORD_1
	v_cvt_f32_f16_e32 v180, v166
	v_cvt_f32_f16_sdwa v181, v166 dst_sel:DWORD dst_unused:UNUSED_PAD src0_sel:WORD_1
	v_mul_f32_e32 v114, 0xbfb8aa3b, v114
	v_exp_f32_e32 v183, v114
	v_add_f32_e32 v114, v115, v125
	v_mul_f32_e32 v114, 0xbfb8aa3b, v114
	v_pk_mul_f32 v[124:125], v[188:189], v[172:173]
	v_add_f32_e32 v118, v118, v162
	v_exp_f32_e32 v175, v114
	v_pk_mul_f32 v[162:163], v[220:221], v[180:181]
	v_pk_mul_f32 v[114:115], v[124:125], v[124:125]
	v_cvt_f32_f16_e32 v168, v169
	v_pk_fma_f32 v[188:189], v[162:163], v[162:163], v[114:115]
	v_add_f32_e32 v114, v120, v164
	v_mul_f32_e32 v114, 0xbfb8aa3b, v114
	v_exp_f32_e32 v178, v114
	v_add_f32_e32 v114, v116, v126
	v_mul_f32_e32 v114, 0xbfb8aa3b, v114
	v_cvt_f32_f16_sdwa v169, v169 dst_sel:DWORD dst_unused:UNUSED_PAD src0_sel:WORD_1
	v_exp_f32_e32 v170, v114
	v_add_f32_e32 v114, v121, v165
	v_cvt_f32_f16_e32 v176, v167
	v_cvt_f32_f16_sdwa v177, v167 dst_sel:DWORD dst_unused:UNUSED_PAD src0_sel:WORD_1
	v_mul_f32_e32 v114, 0xbfb8aa3b, v114
	v_exp_f32_e32 v179, v114
	v_add_f32_e32 v114, v117, v127
	v_mul_f32_e32 v114, 0xbfb8aa3b, v114
	v_pk_mul_f32 v[164:165], v[190:191], v[168:169]
	v_exp_f32_e32 v171, v114
	v_pk_mul_f32 v[166:167], v[222:223], v[176:177]
	v_pk_mul_f32 v[114:115], v[164:165], v[164:165]
	v_mul_f32_e32 v118, 0xbfb8aa3b, v118
	v_pk_fma_f32 v[190:191], v[166:167], v[166:167], v[114:115]
	v_and_b32_e32 v115, 64, v246
	v_xor_b32_e32 v114, 16, v246
	v_add_u32_e32 v115, 64, v115
	v_cmp_lt_i32_e32 vcc, v114, v115
	v_lshl_add_u64 v[126:127], s[0:1], 0, v[198:199]
	v_exp_f32_e32 v182, v118
	v_cndmask_b32_e32 v114, v246, v114, vcc
	v_lshlrev_b32_e32 v206, 2, v114
	v_xor_b32_e32 v114, 32, v246
	v_cmp_lt_i32_e32 vcc, v114, v115
	v_cvt_f32_f16_e32 v198, v138
	v_cvt_f32_f16_sdwa v199, v138 dst_sel:DWORD dst_unused:UNUSED_PAD src0_sel:WORD_1
	v_cndmask_b32_e32 v114, v246, v114, vcc
	v_lshlrev_b32_e32 v207, 2, v114
	global_load_dwordx4 v[114:117], v[126:127], off offset:16
	global_load_dwordx4 v[118:121], v[126:127], off
	v_div_scale_f32 v138, s[0:1], v197, v197, 1.0
	v_rcp_f32_e32 v200, v138
	s_nop 0
	v_fma_f32 v201, -v138, v200, 1.0
	v_fmac_f32_e32 v200, v201, v200
	v_div_scale_f32 v201, vcc, 1.0, v197, 1.0
	v_mul_f32_e32 v212, v201, v200
	v_fma_f32 v213, -v138, v212, v201
	v_fmac_f32_e32 v212, v213, v200
	v_fma_f32 v138, -v138, v212, v201
	v_div_fmas_f32 v138, v138, v200, v212
	v_div_fixup_f32 v197, v138, v197, 1.0
	v_div_scale_f32 v138, s[0:1], v196, v196, 1.0
	v_rcp_f32_e32 v200, v138
	s_nop 0
	v_fma_f32 v201, -v138, v200, 1.0
	v_fmac_f32_e32 v200, v201, v200
	v_div_scale_f32 v201, vcc, 1.0, v196, 1.0
	v_mul_f32_e32 v212, v201, v200
	v_fma_f32 v213, -v138, v212, v201
	v_fmac_f32_e32 v212, v213, v200
	v_fma_f32 v138, -v138, v212, v201
	v_div_fmas_f32 v138, v138, v200, v212
	v_div_fixup_f32 v196, v138, v196, 1.0
	v_pk_add_f32 v[200:201], v[196:197], -1.0 op_sel_hi:[1,0]
	s_waitcnt vmcnt(0)
; __device__ __forceinline__ float sigmoidf_(float x) { return 1.0f / (1.0f + __expf(-x)); }
;     __device__ __forceinline__ void body_a(const f32x4 (&acc)[2][2][4][2], int row0, int cb0) const {
;     ...
;                         a[bj][e] = sigmoidf_(acc[ai][bj][m][0][e] + b0[e]); a[bj][4 + e] = sigmoidf_(acc[ai][bj][m][1][e] + b1[e]);
;                         kv[bj][e] = (float)kh[e]; kv[bj][4 + e] = (float)kh[4 + e];
;                         kk[bj][e] = kv[bj][e] * q0[e]; kk[bj][4 + e] = kv[bj][4 + e] * q1[e];
;                         ss += kk[bj][e] * kk[bj][e] + kk[bj][4 + e] * kk[bj][4 + e];
;                     }
;                 }
;                 ss += __shfl_xor(ss, 16); ss += __shfl_xor(ss, 32);
;                 const float inv = 1.0f / fmaxf(sqrtf(ss), 1e-12f);
; #pragma unroll
;                 for (int bj = 0; bj < 2; ++bj) {
;                     const int c = cb0 + 32 * bj;
;                     const f32x4 p0 = *(const f32x4*)(k_a + c), p1 = *(const f32x4*)(k_a + c + 4);
;                     f32x4 ko0, ko1, ao0, ao1, bo0, bo1;
; #pragma unroll
;                     for (int e = 0; e < 4; ++e) {
;                         ko0[e] = kv[bj][e] * (1.0f + (a[bj][e] - 1.0f) * p0[e]); ko1[e] = kv[bj][4 + e] * (1.0f + (a[bj][4 + e] - 1.0f) * p1[e]);
;     ...
;                     *(u32x4*)(C1 + row * LDC1 + 2048 + c) = pack8(ko0, ko1);
	v_pk_fma_f32 v[118:119], v[200:201], v[118:119], 1.0 op_sel_hi:[1,1,0]
	s_nop 0
	v_pk_mul_f32 v[118:119], v[118:119], v[198:199]
	v_cvt_f32_f16_e32 v200, v139
	v_cvt_f32_f16_sdwa v201, v139 dst_sel:DWORD dst_unused:UNUSED_PAD src0_sel:WORD_1
	v_pk_add_f32 v[138:139], v[194:195], 1.0 op_sel_hi:[1,0]
	v_cvt_pk_f16_f32 v118, v118, v119
	v_div_scale_f32 v119, s[0:1], v139, v139, 1.0
	v_rcp_f32_e32 v194, v119
	s_nop 0
	v_fma_f32 v195, -v119, v194, 1.0
	v_fmac_f32_e32 v194, v195, v194
	v_div_scale_f32 v195, vcc, 1.0, v139, 1.0
	v_mul_f32_e32 v212, v195, v194
	v_fma_f32 v213, -v119, v212, v195
	v_fmac_f32_e32 v212, v213, v194
	v_fma_f32 v119, -v119, v212, v195
	v_div_fmas_f32 v119, v119, v194, v212
	v_div_fixup_f32 v139, v119, v139, 1.0
	v_div_scale_f32 v119, s[0:1], v138, v138, 1.0
	v_rcp_f32_e32 v194, v119
	s_nop 0
	v_fma_f32 v195, -v119, v194, 1.0
	v_fmac_f32_e32 v194, v195, v194
	v_div_scale_f32 v195, vcc, 1.0, v138, 1.0
	v_mul_f32_e32 v212, v195, v194
	v_fma_f32 v213, -v119, v212, v195
	v_fmac_f32_e32 v212, v213, v194
	v_fma_f32 v119, -v119, v212, v195
	v_div_fmas_f32 v119, v119, v194, v212
	v_div_fixup_f32 v138, v119, v138, 1.0
	v_pk_add_f32 v[194:195], v[138:139], -1.0 op_sel_hi:[1,0]
	s_nop 0
	v_pk_fma_f32 v[120:121], v[194:195], v[120:121], 1.0 op_sel_hi:[1,1,0]
	v_cvt_f32_f16_e32 v194, v140
	v_pk_mul_f32 v[120:121], v[120:121], v[200:201]
	v_cvt_f32_f16_sdwa v195, v140 dst_sel:DWORD dst_unused:UNUSED_PAD src0_sel:WORD_1
	v_cvt_pk_f16_f32 v119, v120, v121
	v_pk_add_f32 v[120:121], v[192:193], 1.0 op_sel_hi:[1,0]
	s_nop 0
	v_div_scale_f32 v140, s[0:1], v121, v121, 1.0
	v_rcp_f32_e32 v192, v140
	s_nop 0
	v_fma_f32 v193, -v140, v192, 1.0
	v_fmac_f32_e32 v192, v193, v192
	v_div_scale_f32 v193, vcc, 1.0, v121, 1.0
	v_mul_f32_e32 v212, v193, v192
	v_fma_f32 v213, -v140, v212, v193
	v_fmac_f32_e32 v212, v213, v192
	v_fma_f32 v140, -v140, v212, v193
	v_div_fmas_f32 v140, v140, v192, v212
	v_div_fixup_f32 v193, v140, v121, 1.0
	v_div_scale_f32 v121, s[0:1], v120, v120, 1.0
	v_rcp_f32_e32 v140, v121
	s_nop 0
	v_fma_f32 v192, -v121, v140, 1.0
	v_fmac_f32_e32 v140, v192, v140
	v_div_scale_f32 v192, vcc, 1.0, v120, 1.0
	v_mul_f32_e32 v212, v192, v140
	v_fma_f32 v213, -v121, v212, v192
	v_fmac_f32_e32 v212, v213, v140
	v_fma_f32 v121, -v121, v212, v192
	v_div_fmas_f32 v121, v121, v140, v212
	v_div_fixup_f32 v192, v121, v120, 1.0
	v_pk_add_f32 v[120:121], v[192:193], -1.0 op_sel_hi:[1,0]
	v_cvt_f32_f16_e32 v140, v141
	v_pk_fma_f32 v[114:115], v[120:121], v[114:115], 1.0 op_sel_hi:[1,1,0]
	v_cvt_f32_f16_sdwa v141, v141 dst_sel:DWORD dst_unused:UNUSED_PAD src0_sel:WORD_1
	v_pk_mul_f32 v[114:115], v[114:115], v[194:195]
	v_pk_mul_f32 v[132:133], v[132:133], v[140:141]
	v_cvt_pk_f16_f32 v120, v114, v115
	v_pk_add_f32 v[114:115], v[186:187], 1.0 op_sel_hi:[1,0]
	s_nop 0
	v_div_scale_f32 v121, s[0:1], v115, v115, 1.0
	v_rcp_f32_e32 v186, v121
	s_nop 0
	v_fma_f32 v187, -v121, v186, 1.0
	v_fmac_f32_e32 v186, v187, v186
	v_div_scale_f32 v187, vcc, 1.0, v115, 1.0
	v_mul_f32_e32 v212, v187, v186
	v_fma_f32 v213, -v121, v212, v187
	v_fmac_f32_e32 v212, v213, v186
	v_fma_f32 v121, -v121, v212, v187
	v_div_fmas_f32 v121, v121, v186, v212
	v_div_fixup_f32 v115, v121, v115, 1.0
	v_div_scale_f32 v121, s[0:1], v114, v114, 1.0
	v_rcp_f32_e32 v186, v121
	s_nop 0
	v_fma_f32 v187, -v121, v186, 1.0
	v_fmac_f32_e32 v186, v187, v186
	v_div_scale_f32 v187, vcc, 1.0, v114, 1.0
	v_mul_f32_e32 v212, v187, v186
	v_fma_f32 v213, -v121, v212, v187
	v_fmac_f32_e32 v212, v213, v186
	v_fma_f32 v121, -v121, v212, v187
	v_div_fmas_f32 v121, v121, v186, v212
	v_div_fixup_f32 v114, v121, v114, 1.0
	v_pk_add_f32 v[186:187], v[114:115], -1.0 op_sel_hi:[1,0]
	s_nop 0
	v_pk_fma_f32 v[116:117], v[186:187], v[116:117], 1.0 op_sel_hi:[1,1,0]
	s_nop 0
	v_pk_mul_f32 v[116:117], v[116:117], v[140:141]
	s_nop 0
	v_cvt_pk_f16_f32 v121, v116, v117
	global_store_dwordx4 v[184:185], v[118:121], off
	v_pk_mul_f32 v[116:117], v[134:135], v[198:199]
	v_pk_mul_f32 v[134:135], v[132:133], v[132:133]
	v_pk_mul_f32 v[120:121], v[130:131], v[194:195]
	v_pk_mul_f32 v[118:119], v[136:137], v[200:201]
	v_pk_mul_f32 v[130:131], v[120:121], v[120:121]
	v_pk_fma_f32 v[134:135], v[118:119], v[118:119], v[134:135]
	v_pk_fma_f32 v[130:131], v[116:117], v[116:117], v[130:131]
	v_lshlrev_b64 v[184:185], 12, v[158:159]
	v_add_f32_e32 v130, v130, v131
	v_add_f32_e32 v130, v134, v130
	v_add_f32_e32 v130, v135, v130
	v_add_f32_e32 v130, v130, v188
	v_add_f32_e32 v130, v189, v130
	v_add_f32_e32 v130, v190, v130
	v_add_f32_e32 v130, v191, v130
	ds_bpermute_b32 v131, v206, v130
	s_waitcnt lgkmcnt(0)
	v_add_f32_e32 v130, v130, v131
	ds_bpermute_b32 v131, v207, v130
	s_waitcnt lgkmcnt(0)
;     __device__ __forceinline__ void body_a(const f32x4 (&acc)[2][2][4][2], int row0, int cb0) const {
;     ...
;                 ss += __shfl_xor(ss, 16); ss += __shfl_xor(ss, 32);
;                 const float inv = 1.0f / fmaxf(sqrtf(ss), 1e-12f);
; #pragma unroll
;                 for (int bj = 0; bj < 2; ++bj) {
;                     const int c = cb0 + 32 * bj;
;                     const f32x4 p0 = *(const f32x4*)(k_a + c), p1 = *(const f32x4*)(k_a + c + 4);
;                     f32x4 ko0, ko1, ao0, ao1, bo0, bo1;
; #pragma unroll
;                     for (int e = 0; e < 4; ++e) {
;                         ko0[e] = kv[bj][e] * (1.0f + (a[bj][e] - 1.0f) * p0[e]); ko1[e] = kv[bj][4 + e] * (1.0f + (a[bj][4 + e] - 1.0f) * p1[e]);
;                         const float n0_ = kk[bj][e] * inv, n1_ = kk[bj][4 + e] * inv;
;                         ao0[e] = -n0_; ao1[e] = -n1_; bo0[e] = n0_ * a[bj][e]; bo1[e] = n1_ * a[bj][4 + e];
;                     }
;                     *(u32x4*)(C1 + row * LDC1 + 2048 + c) = pack8(ko0, ko1);
;                     *(u32x4*)(AA + row * DM + c) = pack8(ao0, ao1);
;                     *(u32x4*)(Ab + row * DM + c) = pack8(bo0, bo1);
	v_add_f32_e32 v130, v130, v131
	v_cmp_gt_f32_e32 vcc, s4, v130
	v_mul_f32_e32 v131, 0x4f800000, v130
	s_nop 0
	v_cndmask_b32_e32 v130, v130, v131, vcc
	v_sqrt_f32_e32 v131, v130
	s_nop 0
	v_add_u32_e32 v134, -1, v131
	v_fma_f32 v135, -v134, v131, v130
	v_cmp_ge_f32_e64 s[0:1], 0, v135
	v_add_u32_e32 v135, 1, v131
	s_nop 0
	v_cndmask_b32_e64 v134, v131, v134, s[0:1]
	v_fma_f32 v131, -v135, v131, v130
	v_cmp_lt_f32_e64 s[0:1], 0, v131
	s_nop 1
	v_cndmask_b32_e64 v131, v134, v135, s[0:1]
	v_mul_f32_e32 v134, 0x37800000, v131
	v_cndmask_b32_e32 v131, v131, v134, vcc
	v_cmp_class_f32_e32 vcc, v130, v244
	s_nop 1
	v_cndmask_b32_e32 v130, v131, v130, vcc
	v_max_f32_e32 v130, 0x2b8cbccc, v130
	v_div_scale_f32 v131, s[0:1], v130, v130, 1.0
	v_rcp_f32_e32 v134, v131
	s_nop 0
	v_fma_f32 v135, -v131, v134, 1.0
	v_fmac_f32_e32 v134, v135, v134
	v_div_scale_f32 v135, vcc, 1.0, v130, 1.0
	v_mul_f32_e32 v136, v135, v134
	v_fma_f32 v137, -v131, v136, v135
	v_fmac_f32_e32 v136, v137, v134
	v_fma_f32 v131, -v131, v136, v135
	v_div_fmas_f32 v131, v131, v134, v136
	v_div_fixup_f32 v134, v131, v130, 1.0
	v_pk_mul_f32 v[140:141], v[118:119], v[134:135] op_sel_hi:[1,0]
	v_pk_mul_f32 v[136:137], v[116:117], v[134:135] op_sel_hi:[1,0]
	v_cvt_pk_f16_f32 v117, v140, v141
	v_cvt_pk_f16_f32 v116, v136, v137
	v_xor_b32_e32 v118, 0x8000, v117
	v_xor_b32_sdwa v117, s63, v117 dst_sel:DWORD dst_unused:UNUSED_PAD src0_sel:DWORD src1_sel:WORD_1
	v_pk_mul_f32 v[120:121], v[120:121], v[134:135] op_sel_hi:[1,0]
	v_pk_mul_f32 v[132:133], v[132:133], v[134:135] op_sel_hi:[1,0]
	v_perm_b32 v117, v117, v118, s33
	v_xor_b32_e32 v118, 0x8000, v116
	v_xor_b32_sdwa v116, s63, v116 dst_sel:DWORD dst_unused:UNUSED_PAD src0_sel:DWORD src1_sel:WORD_1
	v_perm_b32 v116, v116, v118, s33
	v_pk_add_f32 v[118:119], v[120:121], 0 neg_lo:[1,1] neg_hi:[1,1]
	v_pk_add_f32 v[130:131], v[132:133], 0 neg_lo:[1,1] neg_hi:[1,1]
	v_cvt_pk_f16_f32 v118, v118, v119
	v_cvt_pk_f16_f32 v119, v130, v131
	v_lshl_add_u64 v[130:131], s[10:11], 0, v[184:185]
	v_lshl_add_u64 v[130:131], v[130:131], 0, v[152:153]
	global_store_dwordx4 v[130:131], v[116:119], off
	v_fma_mixlo_f16 v135, v196, v136, 0
	v_mul_f32_e32 v159, v162, v134
	v_pk_mov_b32 v[116:117], v[196:197], v[138:139] op_sel:[1,0]
	v_pk_mov_b32 v[118:119], v[136:137], v[140:141] op_sel:[1,0]
	v_pk_mov_b32 v[136:137], v[140:141], v[120:121] op_sel:[1,0]
	v_pk_mul_f32 v[116:117], v[116:117], v[118:119]
	v_pk_mov_b32 v[118:119], v[138:139], v[192:193] op_sel:[1,0]
	v_cvt_pk_f16_f32 v117, v116, v117
	v_pk_mul_f32 v[118:119], v[118:119], v[136:137]
	v_pack_b32_f16 v116, v135, v117
	v_cvt_pk_f16_f32 v135, v118, v119
	v_pk_mov_b32 v[118:119], v[192:193], v[114:115] op_sel:[1,0]
	v_pk_mov_b32 v[120:121], v[120:121], v[132:133] op_sel:[1,0]
	v_alignbit_b32 v117, v135, v117, 16
	v_pk_mul_f32 v[118:119], v[118:119], v[120:121]
	v_pk_add_f32 v[136:137], v[182:183], 1.0 op_sel_hi:[1,0]
	v_cvt_pk_f16_f32 v114, v118, v119
	v_lshrrev_b32_e32 v119, 16, v114
	v_alignbit_b32 v118, v114, v135, 16
	v_fma_mixhi_f16 v119, v115, v133, 0
	v_lshl_add_u64 v[114:115], s[2:3], 0, v[184:185]
	v_lshl_add_u64 v[132:133], v[114:115], 0, v[152:153]
	global_store_dwordx4 v[132:133], v[116:119], off
	global_load_dwordx4 v[114:117], v[126:127], off offset:144
	s_nop 0
	global_load_dwordx4 v[118:121], v[126:127], off offset:128
	v_div_scale_f32 v138, s[0:1], v137, v137, 1.0
	v_rcp_f32_e32 v139, v138
	v_mul_f32_e32 v135, v165, v134
	v_fma_f32 v140, -v138, v139, 1.0
	v_fmac_f32_e32 v139, v140, v139
	v_div_scale_f32 v140, vcc, 1.0, v137, 1.0
	v_mul_f32_e32 v141, v140, v139
	v_fma_f32 v182, -v138, v141, v140
	v_fmac_f32_e32 v141, v182, v139
	v_fma_f32 v138, -v138, v141, v140
	v_div_fmas_f32 v138, v138, v139, v141
	v_div_fixup_f32 v137, v138, v137, 1.0
	v_div_scale_f32 v138, s[0:1], v136, v136, 1.0
	v_rcp_f32_e32 v139, v138
	s_nop 0
	v_fma_f32 v140, -v138, v139, 1.0
	v_fmac_f32_e32 v139, v140, v139
	v_div_scale_f32 v140, vcc, 1.0, v136, 1.0
	v_mul_f32_e32 v141, v140, v139
	v_fma_f32 v182, -v138, v141, v140
	v_fmac_f32_e32 v141, v182, v139
	v_fma_f32 v138, -v138, v141, v140
	v_div_fmas_f32 v138, v138, v139, v141
	v_div_fixup_f32 v136, v138, v136, 1.0
	v_pk_add_f32 v[138:139], v[136:137], -1.0 op_sel_hi:[1,0]
	s_waitcnt vmcnt(0)
;     __device__ __forceinline__ void body_a(const f32x4 (&acc)[2][2][4][2], int row0, int cb0) const {
;     ...
;                 const size_t row = (size_t)(row0 + ai * 128 + m * 16);
;                 asm volatile("" ::: "memory");
;                 float a[2][8], kv[2][8], kk[2][8]; float ss = 0.f;
; #pragma unroll
;                 for (int bj = 0; bj < 2; ++bj) {
;                     const int c = cb0 + 32 * bj;
;                     const f32x4 b0 = *(const f32x4*)(a0 + c), b1 = *(const f32x4*)(a0 + c + 4), q0 = *(const f32x4*)(k_k + c), q1 = *(const f32x4*)(k_k + c + 4);
;                     const h16x8 kh = *(const h16x8*)(C1 + row * LDC1 + 2048 + c);
;     ...
;                         ko0[e] = kv[bj][e] * (1.0f + (a[bj][e] - 1.0f) * p0[e]); ko1[e] = kv[bj][4 + e] * (1.0f + (a[bj][4 + e] - 1.0f) * p1[e]);
;                         const float n0_ = kk[bj][e] * inv, n1_ = kk[bj][4 + e] * inv;
;                         ao0[e] = -n0_; ao1[e] = -n1_; bo0[e] = n0_ * a[bj][e]; bo1[e] = n1_ * a[bj][4 + e];
;                     }
;                     *(u32x4*)(C1 + row * LDC1 + 2048 + c) = pack8(ko0, ko1);
;                     *(u32x4*)(AA + row * DM + c) = pack8(ao0, ao1);
;                     *(u32x4*)(Ab + row * DM + c) = pack8(bo0, bo1);
	v_pk_fma_f32 v[118:119], v[138:139], v[118:119], 1.0 op_sel_hi:[1,1,0]
	s_nop 0
	v_pk_mul_f32 v[118:119], v[118:119], v[180:181]
	v_pk_add_f32 v[138:139], v[178:179], 1.0 op_sel_hi:[1,0]
	v_cvt_pk_f16_f32 v118, v118, v119
	v_div_scale_f32 v119, s[0:1], v139, v139, 1.0
	v_rcp_f32_e32 v140, v119
	s_nop 0
	v_fma_f32 v141, -v119, v140, 1.0
	v_fmac_f32_e32 v140, v141, v140
	v_div_scale_f32 v141, vcc, 1.0, v139, 1.0
	v_mul_f32_e32 v178, v141, v140
	v_fma_f32 v179, -v119, v178, v141
	v_fmac_f32_e32 v178, v179, v140
	v_fma_f32 v119, -v119, v178, v141
	v_div_fmas_f32 v119, v119, v140, v178
	v_div_fixup_f32 v139, v119, v139, 1.0
	v_div_scale_f32 v119, s[0:1], v138, v138, 1.0
	v_rcp_f32_e32 v140, v119
	s_nop 0
	v_fma_f32 v141, -v119, v140, 1.0
	v_fmac_f32_e32 v140, v141, v140
	v_div_scale_f32 v141, vcc, 1.0, v138, 1.0
	v_mul_f32_e32 v178, v141, v140
	v_fma_f32 v179, -v119, v178, v141
	v_fmac_f32_e32 v178, v179, v140
	v_fma_f32 v119, -v119, v178, v141
	v_div_fmas_f32 v119, v119, v140, v178
	v_div_fixup_f32 v138, v119, v138, 1.0
	v_pk_add_f32 v[140:141], v[138:139], -1.0 op_sel_hi:[1,0]
	s_nop 0
	v_pk_fma_f32 v[120:121], v[140:141], v[120:121], 1.0 op_sel_hi:[1,1,0]
	s_nop 0
	v_pk_mul_f32 v[120:121], v[120:121], v[176:177]
	s_nop 0
	v_cvt_pk_f16_f32 v119, v120, v121
	v_pk_add_f32 v[120:121], v[174:175], 1.0 op_sel_hi:[1,0]
	s_nop 0
	v_div_scale_f32 v140, s[0:1], v121, v121, 1.0
	v_rcp_f32_e32 v141, v140
	s_nop 0
	v_fma_f32 v174, -v140, v141, 1.0
	v_fmac_f32_e32 v141, v174, v141
	v_div_scale_f32 v174, vcc, 1.0, v121, 1.0
	v_mul_f32_e32 v175, v174, v141
	v_fma_f32 v176, -v140, v175, v174
	v_fmac_f32_e32 v175, v176, v141
	v_fma_f32 v140, -v140, v175, v174
	v_div_fmas_f32 v140, v140, v141, v175
	v_div_fixup_f32 v141, v140, v121, 1.0
	v_div_scale_f32 v121, s[0:1], v120, v120, 1.0
	v_rcp_f32_e32 v140, v121
	s_nop 0
	v_fma_f32 v174, -v121, v140, 1.0
	v_fmac_f32_e32 v140, v174, v140
	v_div_scale_f32 v174, vcc, 1.0, v120, 1.0
	v_mul_f32_e32 v175, v174, v140
	v_fma_f32 v176, -v121, v175, v174
	v_fmac_f32_e32 v175, v176, v140
	v_fma_f32 v121, -v121, v175, v174
	v_div_fmas_f32 v121, v121, v140, v175
	v_div_fixup_f32 v140, v121, v120, 1.0
	v_pk_add_f32 v[120:121], v[140:141], -1.0 op_sel_hi:[1,0]
	s_nop 0
	v_pk_fma_f32 v[114:115], v[120:121], v[114:115], 1.0 op_sel_hi:[1,1,0]
	s_nop 0
	v_pk_mul_f32 v[114:115], v[114:115], v[172:173]
	s_nop 0
	v_cvt_pk_f16_f32 v120, v114, v115
	v_pk_add_f32 v[114:115], v[170:171], 1.0 op_sel_hi:[1,0]
	s_nop 0
	v_div_scale_f32 v121, s[0:1], v115, v115, 1.0
	v_rcp_f32_e32 v170, v121
	s_nop 0
	v_fma_f32 v171, -v121, v170, 1.0
	v_fmac_f32_e32 v170, v171, v170
	v_div_scale_f32 v171, vcc, 1.0, v115, 1.0
	v_mul_f32_e32 v172, v171, v170
	v_fma_f32 v173, -v121, v172, v171
	v_fmac_f32_e32 v172, v173, v170
	v_fma_f32 v121, -v121, v172, v171
	v_div_fmas_f32 v121, v121, v170, v172
	v_div_fixup_f32 v171, v121, v115, 1.0
	v_div_scale_f32 v115, s[0:1], v114, v114, 1.0
	v_rcp_f32_e32 v121, v115
	s_nop 0
	v_fma_f32 v170, -v115, v121, 1.0
	v_fmac_f32_e32 v121, v170, v121
	v_div_scale_f32 v170, vcc, 1.0, v114, 1.0
	v_mul_f32_e32 v172, v170, v121
	v_fma_f32 v173, -v115, v172, v170
	v_fmac_f32_e32 v172, v173, v121
	v_fma_f32 v115, -v115, v172, v170
	v_div_fmas_f32 v115, v115, v121, v172
	v_div_fixup_f32 v170, v115, v114, 1.0
	v_pk_add_f32 v[114:115], v[170:171], -1.0 op_sel_hi:[1,0]
	s_nop 0
	v_pk_fma_f32 v[114:115], v[114:115], v[116:117], 1.0 op_sel_hi:[1,1,0]
	v_cvt_f16_f32_e64 v116, -v159
	v_pk_mul_f32 v[114:115], v[114:115], v[168:169]
	s_nop 0
	v_cvt_pk_f16_f32 v121, v114, v115
	v_pk_mov_b32 v[114:115], v[162:163], v[166:167] op_sel:[1,0]
	global_store_dwordx4 v[122:123], v[118:121], off
	s_nop 1
	v_pk_mul_f32 v[118:119], v[114:115], v[134:135] op_sel_hi:[1,0]
	s_nop 0
	v_cvt_pk_f16_f32 v115, v118, v119
	v_pack_b32_f16 v114, v116, -v115
	v_pk_mov_b32 v[116:117], v[166:167], v[124:125] op_sel:[1,0]
	v_xor_b32_sdwa v115, s63, v115 dst_sel:DWORD dst_unused:UNUSED_PAD src0_sel:DWORD src1_sel:WORD_1
	v_pk_mul_f32 v[120:121], v[116:117], v[134:135] op_sel_hi:[1,0]
	s_nop 0
	v_cvt_pk_f16_f32 v116, v120, v121
	v_xor_b32_e32 v117, 0x8000, v116
	v_perm_b32 v115, v117, v115, s33
	v_xor_b32_sdwa v162, s63, v116 dst_sel:DWORD dst_unused:UNUSED_PAD src0_sel:DWORD src1_sel:WORD_1
	v_pk_mov_b32 v[116:117], v[124:125], v[164:165] op_sel:[1,0]
	v_cvt_f16_f32_e64 v124, -v135
	v_pk_mul_f32 v[122:123], v[116:117], v[134:135] op_sel_hi:[1,0]
	s_nop 0
	v_cvt_pk_f16_f32 v117, v122, v123
	v_xor_b32_e32 v116, 0x8000, v117
	v_xor_b32_sdwa v117, s63, v117 dst_sel:DWORD dst_unused:UNUSED_PAD src0_sel:DWORD src1_sel:WORD_1
	v_perm_b32 v116, v116, v162, s33
	v_perm_b32 v117, v124, v117, s33
	global_store_dwordx4 v[130:131], v[114:117], off offset:64
	s_nop 1
	v_pk_mov_b32 v[114:115], v[136:137], v[138:139] op_sel:[1,0]
	v_fma_mixlo_f16 v116, v136, v159, 0
	v_pk_mul_f32 v[114:115], v[114:115], v[118:119]
	s_nop 0
	v_cvt_pk_f16_f32 v115, v114, v115
	v_pack_b32_f16 v114, v116, v115
	v_pk_mov_b32 v[116:117], v[138:139], v[140:141] op_sel:[1,0]
	s_nop 0
	v_pk_mul_f32 v[116:117], v[116:117], v[120:121]
	s_nop 0
	v_cvt_pk_f16_f32 v118, v116, v117
	v_pk_mov_b32 v[116:117], v[140:141], v[170:171] op_sel:[1,0]
	v_alignbit_b32 v115, v118, v115, 16
	v_pk_mul_f32 v[116:117], v[116:117], v[122:123]
	s_nop 0
	v_cvt_pk_f16_f32 v117, v116, v117
	v_alignbit_b32 v116, v117, v118, 16
	v_lshrrev_b32_e32 v117, 16, v117
	v_fma_mixhi_f16 v117, v171, v135, 0
	global_store_dwordx4 v[132:133], v[114:117], off offset:64
	v_or_b32_e32 v162, 16, v158
	s_nop 0
	v_mad_i64_i32 v[114:115], s[0:1], v162, s5, v[160:161]
	v_lshl_add_u64 v[138:139], v[114:115], 0, s[6:7]
	global_load_dwordx4 v[130:133], v[154:155], off offset:16
	global_load_dwordx4 v[134:137], v[154:155], off
	global_load_dwordx4 v[114:117], v[156:157], off offset:16
	global_load_dwordx4 v[118:121], v[156:157], off
	v_lshl_add_u64 v[170:171], v[138:139], 0, v[152:153]
	global_load_dwordx4 v[122:125], v[170:171], off
	v_ashrrev_i32_e32 v163, 31, v162
	s_waitcnt vmcnt(4)
; __device__ __forceinline__ float sigmoidf_(float x) { return 1.0f / (1.0f + __expf(-x)); }
;     __device__ __forceinline__ void body_a(const f32x4 (&acc)[2][2][4][2], int row0, int cb0) const {
;     ...
;                 for (int bj = 0; bj < 2; ++bj) {
;                     const int c = cb0 + 32 * bj;
;                     const f32x4 b0 = *(const f32x4*)(a0 + c), b1 = *(const f32x4*)(a0 + c + 4), q0 = *(const f32x4*)(k_k + c), q1 = *(const f32x4*)(k_k + c + 4);
;                     const h16x8 kh = *(const h16x8*)(C1 + row * LDC1 + 2048 + c);
; #pragma unroll
;                     for (int e = 0; e < 4; ++e) {
;                         a[bj][e] = sigmoidf_(acc[ai][bj][m][0][e] + b0[e]); a[bj][4 + e] = sigmoidf_(acc[ai][bj][m][1][e] + b1[e]);
;                         kv[bj][e] = (float)kh[e]; kv[bj][4 + e] = (float)kh[4 + e];
;                         kk[bj][e] = kv[bj][e] * q0[e]; kk[bj][4 + e] = kv[bj][4 + e] * q1[e];
;                         ss += kk[bj][e] * kk[bj][e] + kk[bj][4 + e] * kk[bj][4 + e];
;                     }
	v_add_f32_e32 v106, v106, v130
	v_mul_f32_e32 v106, 0xbfb8aa3b, v106
	v_exp_f32_e32 v178, v106
	s_waitcnt vmcnt(3)
	v_add_f32_e32 v106, v111, v135
	v_mul_f32_e32 v106, 0xbfb8aa3b, v106
	v_exp_f32_e32 v181, v106
	v_add_f32_e32 v106, v107, v131
	v_mul_f32_e32 v106, 0xbfb8aa3b, v106
	v_exp_f32_e32 v179, v106
	v_add_f32_e32 v106, v112, v136
	v_mul_f32_e32 v106, 0xbfb8aa3b, v106
	v_exp_f32_e32 v182, v106
	v_add_f32_e32 v106, v108, v132
	v_mul_f32_e32 v106, 0xbfb8aa3b, v106
	v_exp_f32_e32 v172, v106
	v_add_f32_e32 v106, v113, v137
	v_mul_f32_e32 v106, 0xbfb8aa3b, v106
	v_exp_f32_e32 v183, v106
	v_add_f32_e32 v106, v109, v133
	v_add_f32_e32 v110, v110, v134
	v_mul_f32_e32 v106, 0xbfb8aa3b, v106
	v_mul_f32_e32 v110, 0xbfb8aa3b, v110
	v_exp_f32_e32 v173, v106
	v_lshl_add_u64 v[106:107], v[138:139], 0, v[128:129]
	v_exp_f32_e32 v180, v110
	global_load_dwordx4 v[110:113], v[154:155], off offset:144
	global_load_dwordx4 v[130:133], v[154:155], off offset:128
	global_load_dwordx4 v[174:177], v[156:157], off offset:144
	global_load_dwordx4 v[184:187], v[156:157], off offset:128
	global_load_dwordx4 v[188:191], v[106:107], off
	v_pk_add_f32 v[182:183], v[182:183], 1.0 op_sel_hi:[1,0]
	v_pk_add_f32 v[180:181], v[180:181], 1.0 op_sel_hi:[1,0]
	s_waitcnt vmcnt(4)
	v_add_f32_e32 v98, v98, v110
	v_mul_f32_e32 v98, 0xbfb8aa3b, v98
	v_exp_f32_e32 v138, v98
	s_waitcnt vmcnt(3)
	v_add_f32_e32 v98, v103, v131
	s_waitcnt vmcnt(0)
	v_cvt_f32_f16_e32 v136, v190
	v_cvt_f32_f16_sdwa v137, v190 dst_sel:DWORD dst_unused:UNUSED_PAD src0_sel:WORD_1
	v_cvt_f32_f16_e32 v166, v188
	v_cvt_f32_f16_sdwa v167, v188 dst_sel:DWORD dst_unused:UNUSED_PAD src0_sel:WORD_1
	v_mul_f32_e32 v98, 0xbfb8aa3b, v98
	v_exp_f32_e32 v169, v98
	v_add_f32_e32 v98, v99, v111
	v_mul_f32_e32 v98, 0xbfb8aa3b, v98
	v_pk_mul_f32 v[108:109], v[174:175], v[136:137]
	v_exp_f32_e32 v139, v98
	v_pk_mul_f32 v[110:111], v[184:185], v[166:167]
	v_pk_mul_f32 v[98:99], v[108:109], v[108:109]
	v_cvt_f32_f16_e32 v140, v189
	v_pk_fma_f32 v[174:175], v[110:111], v[110:111], v[98:99]
	v_add_f32_e32 v98, v104, v132
	v_mul_f32_e32 v98, 0xbfb8aa3b, v98
	v_exp_f32_e32 v164, v98
	v_add_f32_e32 v98, v100, v112
	v_mul_f32_e32 v98, 0xbfb8aa3b, v98
	v_exp_f32_e32 v134, v98
	v_add_f32_e32 v98, v105, v133
	v_cvt_f32_f16_e32 v132, v191
	v_cvt_f32_f16_sdwa v133, v191 dst_sel:DWORD dst_unused:UNUSED_PAD src0_sel:WORD_1
	v_cvt_f32_f16_sdwa v141, v189 dst_sel:DWORD dst_unused:UNUSED_PAD src0_sel:WORD_1
	v_mul_f32_e32 v98, 0xbfb8aa3b, v98
	v_exp_f32_e32 v165, v98
	v_add_f32_e32 v98, v101, v113
	v_add_f32_e32 v102, v102, v130
	v_mul_f32_e32 v98, 0xbfb8aa3b, v98
	v_pk_mul_f32 v[112:113], v[176:177], v[132:133]
	v_mul_f32_e32 v102, 0xbfb8aa3b, v102
	v_exp_f32_e32 v135, v98
	v_pk_mul_f32 v[130:131], v[186:187], v[140:141]
	v_pk_mul_f32 v[98:99], v[112:113], v[112:113]
	v_exp_f32_e32 v168, v102
	v_pk_fma_f32 v[176:177], v[130:131], v[130:131], v[98:99]
	global_load_dwordx4 v[98:101], v[126:127], off offset:16
	global_load_dwordx4 v[102:105], v[126:127], off
	v_cvt_f32_f16_e32 v184, v122
	v_cvt_f32_f16_sdwa v185, v122 dst_sel:DWORD dst_unused:UNUSED_PAD src0_sel:WORD_1
	v_div_scale_f32 v122, s[0:1], v181, v181, 1.0
	v_rcp_f32_e32 v159, v122
	s_nop 0
	v_fma_f32 v186, -v122, v159, 1.0
	v_fmac_f32_e32 v159, v186, v159
	v_div_scale_f32 v186, vcc, 1.0, v181, 1.0
	v_mul_f32_e32 v187, v186, v159
	v_fma_f32 v188, -v122, v187, v186
	v_fmac_f32_e32 v187, v188, v159
	v_fma_f32 v122, -v122, v187, v186
	v_div_fmas_f32 v122, v122, v159, v187
	v_div_fixup_f32 v181, v122, v181, 1.0
	v_div_scale_f32 v122, s[0:1], v180, v180, 1.0
	v_rcp_f32_e32 v159, v122
	s_nop 0
	v_fma_f32 v186, -v122, v159, 1.0
	v_fmac_f32_e32 v159, v186, v159
	v_div_scale_f32 v186, vcc, 1.0, v180, 1.0
	v_mul_f32_e32 v187, v186, v159
	v_fma_f32 v188, -v122, v187, v186
	v_fmac_f32_e32 v187, v188, v159
	v_fma_f32 v122, -v122, v187, v186
	v_div_fmas_f32 v122, v122, v159, v187
	v_div_fixup_f32 v180, v122, v180, 1.0
	v_pk_add_f32 v[186:187], v[180:181], -1.0 op_sel_hi:[1,0]
	v_cvt_f32_f16_e32 v122, v123
	v_cvt_f32_f16_sdwa v123, v123 dst_sel:DWORD dst_unused:UNUSED_PAD src0_sel:WORD_1
	s_waitcnt vmcnt(0)
	v_pk_fma_f32 v[102:103], v[186:187], v[102:103], 1.0 op_sel_hi:[1,1,0]
	s_nop 0
	v_pk_mul_f32 v[102:103], v[102:103], v[184:185]
	s_nop 0
	v_cvt_pk_f16_f32 v102, v102, v103
	v_div_scale_f32 v103, s[0:1], v183, v183, 1.0
	v_rcp_f32_e32 v159, v103
	s_nop 0
	v_fma_f32 v186, -v103, v159, 1.0
	v_fmac_f32_e32 v159, v186, v159
	v_div_scale_f32 v186, vcc, 1.0, v183, 1.0
	v_mul_f32_e32 v187, v186, v159
	v_fma_f32 v188, -v103, v187, v186
	v_fmac_f32_e32 v187, v188, v159
	v_fma_f32 v103, -v103, v187, v186
	v_div_fmas_f32 v103, v103, v159, v187
	v_div_fixup_f32 v183, v103, v183, 1.0
	v_div_scale_f32 v103, s[0:1], v182, v182, 1.0
	v_rcp_f32_e32 v159, v103
	s_nop 0
	v_fma_f32 v186, -v103, v159, 1.0
	v_fmac_f32_e32 v159, v186, v159
	v_div_scale_f32 v186, vcc, 1.0, v182, 1.0
	v_mul_f32_e32 v187, v186, v159
	v_fma_f32 v188, -v103, v187, v186
	v_fmac_f32_e32 v187, v188, v159
	v_fma_f32 v103, -v103, v187, v186
	v_div_fmas_f32 v103, v103, v159, v187
	v_div_fixup_f32 v182, v103, v182, 1.0
	v_pk_add_f32 v[186:187], v[182:183], -1.0 op_sel_hi:[1,0]
	s_nop 0
	v_pk_fma_f32 v[104:105], v[186:187], v[104:105], 1.0 op_sel_hi:[1,1,0]
	v_cvt_f32_f16_e32 v186, v124
	v_pk_mul_f32 v[104:105], v[104:105], v[122:123]
	v_cvt_f32_f16_sdwa v187, v124 dst_sel:DWORD dst_unused:UNUSED_PAD src0_sel:WORD_1
	v_cvt_pk_f16_f32 v103, v104, v105
	v_pk_add_f32 v[104:105], v[178:179], 1.0 op_sel_hi:[1,0]
	s_nop 0
	v_div_scale_f32 v124, s[0:1], v105, v105, 1.0
	v_rcp_f32_e32 v159, v124
	s_nop 0
	v_fma_f32 v178, -v124, v159, 1.0
; __device__ __forceinline__ float sigmoidf_(float x) { return 1.0f / (1.0f + __expf(-x)); }
;     __device__ __forceinline__ void body_a(const f32x4 (&acc)[2][2][4][2], int row0, int cb0) const {
;     ...
;                         a[bj][e] = sigmoidf_(acc[ai][bj][m][0][e] + b0[e]); a[bj][4 + e] = sigmoidf_(acc[ai][bj][m][1][e] + b1[e]);
;                         kv[bj][e] = (float)kh[e]; kv[bj][4 + e] = (float)kh[4 + e];
;                         kk[bj][e] = kv[bj][e] * q0[e]; kk[bj][4 + e] = kv[bj][4 + e] * q1[e];
;                         ss += kk[bj][e] * kk[bj][e] + kk[bj][4 + e] * kk[bj][4 + e];
;                     }
;                 }
;                 ss += __shfl_xor(ss, 16); ss += __shfl_xor(ss, 32);
;                 const float inv = 1.0f / fmaxf(sqrtf(ss), 1e-12f);
; #pragma unroll
;                 for (int bj = 0; bj < 2; ++bj) {
;                     const int c = cb0 + 32 * bj;
;                     const f32x4 p0 = *(const f32x4*)(k_a + c), p1 = *(const f32x4*)(k_a + c + 4);
;                     f32x4 ko0, ko1, ao0, ao1, bo0, bo1;
; #pragma unroll
;                     for (int e = 0; e < 4; ++e) {
;                         ko0[e] = kv[bj][e] * (1.0f + (a[bj][e] - 1.0f) * p0[e]); ko1[e] = kv[bj][4 + e] * (1.0f + (a[bj][4 + e] - 1.0f) * p1[e]);
;                         const float n0_ = kk[bj][e] * inv, n1_ = kk[bj][4 + e] * inv;
;                         ao0[e] = -n0_; ao1[e] = -n1_; bo0[e] = n0_ * a[bj][e]; bo1[e] = n1_ * a[bj][4 + e];
;                     }
;                     *(u32x4*)(C1 + row * LDC1 + 2048 + c) = pack8(ko0, ko1);
;                     *(u32x4*)(AA + row * DM + c) = pack8(ao0, ao1);
	v_fmac_f32_e32 v159, v178, v159
	v_div_scale_f32 v178, vcc, 1.0, v105, 1.0
	v_mul_f32_e32 v179, v178, v159
	v_fma_f32 v188, -v124, v179, v178
	v_fmac_f32_e32 v179, v188, v159
	v_fma_f32 v124, -v124, v179, v178
	v_div_fmas_f32 v124, v124, v159, v179
	v_div_fixup_f32 v179, v124, v105, 1.0
	v_div_scale_f32 v105, s[0:1], v104, v104, 1.0
	v_rcp_f32_e32 v124, v105
	s_nop 0
	v_fma_f32 v159, -v105, v124, 1.0
	v_fmac_f32_e32 v124, v159, v124
	v_div_scale_f32 v159, vcc, 1.0, v104, 1.0
	v_mul_f32_e32 v178, v159, v124
	v_fma_f32 v188, -v105, v178, v159
	v_fmac_f32_e32 v178, v188, v124
	v_fma_f32 v105, -v105, v178, v159
	v_div_fmas_f32 v105, v105, v124, v178
	v_div_fixup_f32 v178, v105, v104, 1.0
	v_pk_add_f32 v[104:105], v[178:179], -1.0 op_sel_hi:[1,0]
	v_cvt_f32_f16_e32 v124, v125
	v_pk_fma_f32 v[98:99], v[104:105], v[98:99], 1.0 op_sel_hi:[1,1,0]
	v_cvt_f32_f16_sdwa v125, v125 dst_sel:DWORD dst_unused:UNUSED_PAD src0_sel:WORD_1
	v_pk_mul_f32 v[98:99], v[98:99], v[186:187]
	v_pk_mul_f32 v[116:117], v[116:117], v[124:125]
	v_cvt_pk_f16_f32 v104, v98, v99
	v_pk_add_f32 v[98:99], v[172:173], 1.0 op_sel_hi:[1,0]
	s_nop 0
	v_div_scale_f32 v105, s[0:1], v99, v99, 1.0
	v_rcp_f32_e32 v159, v105
	s_nop 0
	v_fma_f32 v172, -v105, v159, 1.0
	v_fmac_f32_e32 v159, v172, v159
	v_div_scale_f32 v172, vcc, 1.0, v99, 1.0
	v_mul_f32_e32 v173, v172, v159
	v_fma_f32 v188, -v105, v173, v172
	v_fmac_f32_e32 v173, v188, v159
	v_fma_f32 v105, -v105, v173, v172
	v_div_fmas_f32 v105, v105, v159, v173
	v_div_fixup_f32 v99, v105, v99, 1.0
	v_div_scale_f32 v105, s[0:1], v98, v98, 1.0
	v_rcp_f32_e32 v159, v105
	s_nop 0
	v_fma_f32 v172, -v105, v159, 1.0
	v_fmac_f32_e32 v159, v172, v159
	v_div_scale_f32 v172, vcc, 1.0, v98, 1.0
	v_mul_f32_e32 v173, v172, v159
	v_fma_f32 v188, -v105, v173, v172
	v_fmac_f32_e32 v173, v188, v159
	v_fma_f32 v105, -v105, v173, v172
	v_div_fmas_f32 v105, v105, v159, v173
	v_div_fixup_f32 v98, v105, v98, 1.0
	v_pk_add_f32 v[172:173], v[98:99], -1.0 op_sel_hi:[1,0]
	s_nop 0
	v_pk_fma_f32 v[100:101], v[172:173], v[100:101], 1.0 op_sel_hi:[1,1,0]
	s_nop 0
	v_pk_mul_f32 v[100:101], v[100:101], v[124:125]
	v_lshlrev_b64 v[124:125], 12, v[162:163]
	v_cvt_pk_f16_f32 v105, v100, v101
	global_store_dwordx4 v[170:171], v[102:105], off
	v_pk_mul_f32 v[100:101], v[118:119], v[184:185]
	v_pk_mul_f32 v[118:119], v[116:117], v[116:117]
	v_pk_mul_f32 v[104:105], v[114:115], v[186:187]
	v_pk_mul_f32 v[102:103], v[120:121], v[122:123]
	v_pk_mul_f32 v[114:115], v[104:105], v[104:105]
	v_pk_fma_f32 v[118:119], v[102:103], v[102:103], v[118:119]
	v_pk_fma_f32 v[114:115], v[100:101], v[100:101], v[114:115]
	s_nop 0
	v_add_f32_e32 v114, v114, v115
	v_add_f32_e32 v114, v118, v114
	v_add_f32_e32 v114, v119, v114
	v_add_f32_e32 v114, v114, v174
	v_add_f32_e32 v114, v175, v114
	v_add_f32_e32 v114, v176, v114
	v_add_f32_e32 v114, v177, v114
	ds_bpermute_b32 v115, v206, v114
	s_waitcnt lgkmcnt(0)
	v_add_f32_e32 v114, v114, v115
	ds_bpermute_b32 v115, v207, v114
	s_waitcnt lgkmcnt(0)
	v_add_f32_e32 v114, v114, v115
	v_cmp_gt_f32_e32 vcc, s4, v114
	v_mul_f32_e32 v115, 0x4f800000, v114
	s_nop 0
	v_cndmask_b32_e32 v114, v114, v115, vcc
	v_sqrt_f32_e32 v115, v114
	s_nop 0
	v_add_u32_e32 v118, -1, v115
	v_fma_f32 v119, -v118, v115, v114
	v_cmp_ge_f32_e64 s[0:1], 0, v119
	v_add_u32_e32 v119, 1, v115
	s_nop 0
	v_cndmask_b32_e64 v118, v115, v118, s[0:1]
	v_fma_f32 v115, -v119, v115, v114
	v_cmp_lt_f32_e64 s[0:1], 0, v115
	s_nop 1
	v_cndmask_b32_e64 v115, v118, v119, s[0:1]
	v_mul_f32_e32 v118, 0x37800000, v115
	v_cndmask_b32_e32 v115, v115, v118, vcc
	v_cmp_class_f32_e32 vcc, v114, v244
	s_nop 1
	v_cndmask_b32_e32 v114, v115, v114, vcc
	v_max_f32_e32 v114, 0x2b8cbccc, v114
	v_div_scale_f32 v115, s[0:1], v114, v114, 1.0
	v_rcp_f32_e32 v118, v115
	s_nop 0
	v_fma_f32 v119, -v115, v118, 1.0
	v_fmac_f32_e32 v118, v119, v118
	v_div_scale_f32 v119, vcc, 1.0, v114, 1.0
	v_mul_f32_e32 v120, v119, v118
	v_fma_f32 v121, -v115, v120, v119
	v_fmac_f32_e32 v120, v121, v118
	v_fma_f32 v115, -v115, v120, v119
	v_div_fmas_f32 v115, v115, v118, v120
	v_div_fixup_f32 v118, v115, v114, 1.0
	v_pk_mul_f32 v[122:123], v[102:103], v[118:119] op_sel_hi:[1,0]
	v_pk_mul_f32 v[120:121], v[100:101], v[118:119] op_sel_hi:[1,0]
	v_cvt_pk_f16_f32 v101, v122, v123
	v_cvt_pk_f16_f32 v100, v120, v121
	v_xor_b32_e32 v102, 0x8000, v101
	v_xor_b32_sdwa v101, s63, v101 dst_sel:DWORD dst_unused:UNUSED_PAD src0_sel:DWORD src1_sel:WORD_1
	v_pk_mul_f32 v[104:105], v[104:105], v[118:119] op_sel_hi:[1,0]
	v_pk_mul_f32 v[116:117], v[116:117], v[118:119] op_sel_hi:[1,0]
	v_perm_b32 v101, v101, v102, s33
	v_xor_b32_e32 v102, 0x8000, v100
	v_xor_b32_sdwa v100, s63, v100 dst_sel:DWORD dst_unused:UNUSED_PAD src0_sel:DWORD src1_sel:WORD_1
	v_perm_b32 v100, v100, v102, s33
	v_pk_add_f32 v[102:103], v[104:105], 0 neg_lo:[1,1] neg_hi:[1,1]
	v_pk_add_f32 v[114:115], v[116:117], 0 neg_lo:[1,1] neg_hi:[1,1]
	v_cvt_pk_f16_f32 v102, v102, v103
	v_cvt_pk_f16_f32 v103, v114, v115
	v_lshl_add_u64 v[114:115], s[10:11], 0, v[124:125]
	v_lshl_add_u64 v[114:115], v[114:115], 0, v[152:153]
	global_store_dwordx4 v[114:115], v[100:103], off
	v_fma_mixlo_f16 v119, v180, v120, 0
	v_mul_f32_e32 v159, v110, v118
	v_pk_mov_b32 v[100:101], v[180:181], v[182:183] op_sel:[1,0]
	v_pk_mov_b32 v[102:103], v[120:121], v[122:123] op_sel:[1,0]
	v_pk_mov_b32 v[120:121], v[122:123], v[104:105] op_sel:[1,0]
	v_pk_mul_f32 v[100:101], v[100:101], v[102:103]
	v_pk_mov_b32 v[102:103], v[182:183], v[178:179] op_sel:[1,0]
	v_cvt_pk_f16_f32 v101, v100, v101
	v_pk_mul_f32 v[102:103], v[102:103], v[120:121]
	v_pack_b32_f16 v100, v119, v101
	v_cvt_pk_f16_f32 v119, v102, v103
;     __device__ __forceinline__ void body_a(const f32x4 (&acc)[2][2][4][2], int row0, int cb0) const {
;     ...
;                         ko0[e] = kv[bj][e] * (1.0f + (a[bj][e] - 1.0f) * p0[e]); ko1[e] = kv[bj][4 + e] * (1.0f + (a[bj][4 + e] - 1.0f) * p1[e]);
;                         const float n0_ = kk[bj][e] * inv, n1_ = kk[bj][4 + e] * inv;
;                         ao0[e] = -n0_; ao1[e] = -n1_; bo0[e] = n0_ * a[bj][e]; bo1[e] = n1_ * a[bj][4 + e];
;                     }
;                     *(u32x4*)(C1 + row * LDC1 + 2048 + c) = pack8(ko0, ko1);
;                     *(u32x4*)(AA + row * DM + c) = pack8(ao0, ao1);
;                     *(u32x4*)(Ab + row * DM + c) = pack8(bo0, bo1);
	v_pk_mov_b32 v[102:103], v[178:179], v[98:99] op_sel:[1,0]
	v_pk_mov_b32 v[104:105], v[104:105], v[116:117] op_sel:[1,0]
	v_alignbit_b32 v101, v119, v101, 16
	v_pk_mul_f32 v[102:103], v[102:103], v[104:105]
	v_pk_add_f32 v[120:121], v[168:169], 1.0 op_sel_hi:[1,0]
	v_cvt_pk_f16_f32 v98, v102, v103
	v_lshrrev_b32_e32 v103, 16, v98
	v_alignbit_b32 v102, v98, v119, 16
	v_fma_mixhi_f16 v103, v99, v117, 0
	v_lshl_add_u64 v[98:99], s[2:3], 0, v[124:125]
	v_lshl_add_u64 v[116:117], v[98:99], 0, v[152:153]
	global_store_dwordx4 v[116:117], v[100:103], off
	global_load_dwordx4 v[98:101], v[126:127], off offset:144
	s_nop 0
	global_load_dwordx4 v[102:105], v[126:127], off offset:128
	v_div_scale_f32 v122, s[0:1], v121, v121, 1.0
	v_rcp_f32_e32 v123, v122
	v_mul_f32_e32 v119, v113, v118
	v_fma_f32 v124, -v122, v123, 1.0
	v_fmac_f32_e32 v123, v124, v123
	v_div_scale_f32 v124, vcc, 1.0, v121, 1.0
	v_mul_f32_e32 v125, v124, v123
	v_fma_f32 v162, -v122, v125, v124
	v_fmac_f32_e32 v125, v162, v123
	v_fma_f32 v122, -v122, v125, v124
	v_div_fmas_f32 v122, v122, v123, v125
	v_div_fixup_f32 v121, v122, v121, 1.0
	v_div_scale_f32 v122, s[0:1], v120, v120, 1.0
	v_rcp_f32_e32 v123, v122
	s_nop 0
	v_fma_f32 v124, -v122, v123, 1.0
	v_fmac_f32_e32 v123, v124, v123
	v_div_scale_f32 v124, vcc, 1.0, v120, 1.0
	v_mul_f32_e32 v125, v124, v123
	v_fma_f32 v162, -v122, v125, v124
	v_fmac_f32_e32 v125, v162, v123
	v_fma_f32 v122, -v122, v125, v124
	v_div_fmas_f32 v122, v122, v123, v125
	v_div_fixup_f32 v120, v122, v120, 1.0
	v_pk_add_f32 v[122:123], v[120:121], -1.0 op_sel_hi:[1,0]
	s_waitcnt vmcnt(0)
	v_pk_fma_f32 v[102:103], v[122:123], v[102:103], 1.0 op_sel_hi:[1,1,0]
	s_nop 0
	v_pk_mul_f32 v[102:103], v[102:103], v[166:167]
	v_pk_add_f32 v[122:123], v[164:165], 1.0 op_sel_hi:[1,0]
	v_cvt_pk_f16_f32 v102, v102, v103
	v_div_scale_f32 v103, s[0:1], v123, v123, 1.0
	v_rcp_f32_e32 v124, v103
	s_nop 0
	v_fma_f32 v125, -v103, v124, 1.0
	v_fmac_f32_e32 v124, v125, v124
	v_div_scale_f32 v125, vcc, 1.0, v123, 1.0
	v_mul_f32_e32 v162, v125, v124
	v_fma_f32 v163, -v103, v162, v125
	v_fmac_f32_e32 v162, v163, v124
	v_fma_f32 v103, -v103, v162, v125
	v_div_fmas_f32 v103, v103, v124, v162
	v_div_fixup_f32 v123, v103, v123, 1.0
	v_div_scale_f32 v103, s[0:1], v122, v122, 1.0
	v_rcp_f32_e32 v124, v103
	s_nop 0
	v_fma_f32 v125, -v103, v124, 1.0
	v_fmac_f32_e32 v124, v125, v124
	v_div_scale_f32 v125, vcc, 1.0, v122, 1.0
	v_mul_f32_e32 v162, v125, v124
	v_fma_f32 v163, -v103, v162, v125
	v_fmac_f32_e32 v162, v163, v124
	v_fma_f32 v103, -v103, v162, v125
	v_div_fmas_f32 v103, v103, v124, v162
	v_div_fixup_f32 v122, v103, v122, 1.0
	v_pk_add_f32 v[124:125], v[122:123], -1.0 op_sel_hi:[1,0]
	s_nop 0
	v_pk_fma_f32 v[104:105], v[124:125], v[104:105], 1.0 op_sel_hi:[1,1,0]
	s_nop 0
	v_pk_mul_f32 v[104:105], v[104:105], v[140:141]
	s_nop 0
	v_cvt_pk_f16_f32 v103, v104, v105
	v_pk_add_f32 v[104:105], v[138:139], 1.0 op_sel_hi:[1,0]
	s_nop 0
	v_div_scale_f32 v124, s[0:1], v105, v105, 1.0
	v_rcp_f32_e32 v125, v124
	s_nop 0
	v_fma_f32 v138, -v124, v125, 1.0
	v_fmac_f32_e32 v125, v138, v125
	v_div_scale_f32 v138, vcc, 1.0, v105, 1.0
	v_mul_f32_e32 v139, v138, v125
	v_fma_f32 v140, -v124, v139, v138
	v_fmac_f32_e32 v139, v140, v125
	v_fma_f32 v124, -v124, v139, v138
	v_div_fmas_f32 v124, v124, v125, v139
	v_div_fixup_f32 v125, v124, v105, 1.0
	v_div_scale_f32 v105, s[0:1], v104, v104, 1.0
	v_rcp_f32_e32 v124, v105
	s_nop 0
	v_fma_f32 v138, -v105, v124, 1.0
	v_fmac_f32_e32 v124, v138, v124
	v_div_scale_f32 v138, vcc, 1.0, v104, 1.0
	v_mul_f32_e32 v139, v138, v124
	v_fma_f32 v140, -v105, v139, v138
	v_fmac_f32_e32 v139, v140, v124
	v_fma_f32 v105, -v105, v139, v138
	v_div_fmas_f32 v105, v105, v124, v139
	v_div_fixup_f32 v124, v105, v104, 1.0
	v_pk_add_f32 v[104:105], v[124:125], -1.0 op_sel_hi:[1,0]
	s_nop 0
	v_pk_fma_f32 v[98:99], v[104:105], v[98:99], 1.0 op_sel_hi:[1,1,0]
	s_nop 0
	v_pk_mul_f32 v[98:99], v[98:99], v[136:137]
	s_nop 0
	v_cvt_pk_f16_f32 v104, v98, v99
	v_pk_add_f32 v[98:99], v[134:135], 1.0 op_sel_hi:[1,0]
	s_nop 0
	v_div_scale_f32 v105, s[0:1], v99, v99, 1.0
	v_rcp_f32_e32 v134, v105
	s_nop 0
	v_fma_f32 v135, -v105, v134, 1.0
	v_fmac_f32_e32 v134, v135, v134
	v_div_scale_f32 v135, vcc, 1.0, v99, 1.0
	v_mul_f32_e32 v136, v135, v134
	v_fma_f32 v137, -v105, v136, v135
	v_fmac_f32_e32 v136, v137, v134
	v_fma_f32 v105, -v105, v136, v135
	v_div_fmas_f32 v105, v105, v134, v136
	v_div_fixup_f32 v135, v105, v99, 1.0
	v_div_scale_f32 v99, s[0:1], v98, v98, 1.0
	v_rcp_f32_e32 v105, v99
	s_nop 0
	v_fma_f32 v134, -v99, v105, 1.0
	v_fmac_f32_e32 v105, v134, v105
	v_div_scale_f32 v134, vcc, 1.0, v98, 1.0
	v_mul_f32_e32 v136, v134, v105
	v_fma_f32 v137, -v99, v136, v134
	v_fmac_f32_e32 v136, v137, v105
	v_fma_f32 v99, -v99, v136, v134
	v_div_fmas_f32 v99, v99, v105, v136
	v_div_fixup_f32 v134, v99, v98, 1.0
	v_pk_add_f32 v[98:99], v[134:135], -1.0 op_sel_hi:[1,0]
	s_nop 0
	v_pk_fma_f32 v[98:99], v[98:99], v[100:101], 1.0 op_sel_hi:[1,1,0]
	v_cvt_f16_f32_e64 v100, -v159
	v_pk_mul_f32 v[98:99], v[98:99], v[132:133]
	s_nop 0
	v_cvt_pk_f16_f32 v105, v98, v99
	v_pk_mov_b32 v[98:99], v[110:111], v[130:131] op_sel:[1,0]
	global_store_dwordx4 v[106:107], v[102:105], off
	s_nop 1
	v_pk_mul_f32 v[102:103], v[98:99], v[118:119] op_sel_hi:[1,0]
	s_nop 0
	v_cvt_pk_f16_f32 v99, v102, v103
	v_pack_b32_f16 v98, v100, -v99
	v_pk_mov_b32 v[100:101], v[130:131], v[108:109] op_sel:[1,0]
	v_xor_b32_sdwa v99, s63, v99 dst_sel:DWORD dst_unused:UNUSED_PAD src0_sel:DWORD src1_sel:WORD_1
	v_pk_mul_f32 v[104:105], v[100:101], v[118:119] op_sel_hi:[1,0]
	s_nop 0
	v_cvt_pk_f16_f32 v100, v104, v105
	v_xor_b32_e32 v101, 0x8000, v100
;     __device__ __forceinline__ void body_a(const f32x4 (&acc)[2][2][4][2], int row0, int cb0) const {
; #pragma unroll
;         for (int ai = 0; ai < 2; ++ai)
; #pragma unroll
;             for (int m = 0; m < 4; ++m) {
;                 const size_t row = (size_t)(row0 + ai * 128 + m * 16);
;                 asm volatile("" ::: "memory");
;                 float a[2][8], kv[2][8], kk[2][8]; float ss = 0.f;
; #pragma unroll
;                 for (int bj = 0; bj < 2; ++bj) {
;                     const int c = cb0 + 32 * bj;
;                     const f32x4 b0 = *(const f32x4*)(a0 + c), b1 = *(const f32x4*)(a0 + c + 4), q0 = *(const f32x4*)(k_k + c), q1 = *(const f32x4*)(k_k + c + 4);
;                     const h16x8 kh = *(const h16x8*)(C1 + row * LDC1 + 2048 + c);
; #pragma unroll
;                     for (int e = 0; e < 4; ++e) {
;                         a[bj][e] = sigmoidf_(acc[ai][bj][m][0][e] + b0[e]); a[bj][4 + e] = sigmoidf_(acc[ai][bj][m][1][e] + b1[e]);
;                         kv[bj][e] = (float)kh[e]; kv[bj][4 + e] = (float)kh[4 + e];
;                         kk[bj][e] = kv[bj][e] * q0[e]; kk[bj][4 + e] = kv[bj][4 + e] * q1[e];
;                         ss += kk[bj][e] * kk[bj][e] + kk[bj][4 + e] * kk[bj][4 + e];
;                     }
;                 }
;                 ss += __shfl_xor(ss, 16); ss += __shfl_xor(ss, 32);
;                 const float inv = 1.0f / fmaxf(sqrtf(ss), 1e-12f);
; #pragma unroll
;                 for (int bj = 0; bj < 2; ++bj) {
;                     const int c = cb0 + 32 * bj;
;                     const f32x4 p0 = *(const f32x4*)(k_a + c), p1 = *(const f32x4*)(k_a + c + 4);
;                     f32x4 ko0, ko1, ao0, ao1, bo0, bo1;
; #pragma unroll
;                     for (int e = 0; e < 4; ++e) {
;                         ko0[e] = kv[bj][e] * (1.0f + (a[bj][e] - 1.0f) * p0[e]); ko1[e] = kv[bj][4 + e] * (1.0f + (a[bj][4 + e] - 1.0f) * p1[e]);
;                         const float n0_ = kk[bj][e] * inv, n1_ = kk[bj][4 + e] * inv;
;                         ao0[e] = -n0_; ao1[e] = -n1_; bo0[e] = n0_ * a[bj][e]; bo1[e] = n1_ * a[bj][4 + e];
;                     }
;                     *(u32x4*)(C1 + row * LDC1 + 2048 + c) = pack8(ko0, ko1);
;                     *(u32x4*)(AA + row * DM + c) = pack8(ao0, ao1);
;                     *(u32x4*)(Ab + row * DM + c) = pack8(bo0, bo1);
;                 }
	v_perm_b32 v99, v101, v99, s33
	v_xor_b32_sdwa v110, s63, v100 dst_sel:DWORD dst_unused:UNUSED_PAD src0_sel:DWORD src1_sel:WORD_1
	v_pk_mov_b32 v[100:101], v[108:109], v[112:113] op_sel:[1,0]
	v_cvt_f16_f32_e64 v108, -v119
	v_pk_mul_f32 v[106:107], v[100:101], v[118:119] op_sel_hi:[1,0]
	s_nop 0
	v_cvt_pk_f16_f32 v101, v106, v107
	v_xor_b32_e32 v100, 0x8000, v101
	v_xor_b32_sdwa v101, s63, v101 dst_sel:DWORD dst_unused:UNUSED_PAD src0_sel:DWORD src1_sel:WORD_1
	v_perm_b32 v100, v100, v110, s33
	v_perm_b32 v101, v108, v101, s33
	global_store_dwordx4 v[114:115], v[98:101], off offset:64
	s_nop 1
	v_pk_mov_b32 v[98:99], v[120:121], v[122:123] op_sel:[1,0]
	v_fma_mixlo_f16 v100, v120, v159, 0
	v_pk_mul_f32 v[98:99], v[98:99], v[102:103]
	s_nop 0
	v_cvt_pk_f16_f32 v99, v98, v99
	v_pack_b32_f16 v98, v100, v99
	v_pk_mov_b32 v[100:101], v[122:123], v[124:125] op_sel:[1,0]
	s_nop 0
	v_pk_mul_f32 v[100:101], v[100:101], v[104:105]
	s_nop 0
	v_cvt_pk_f16_f32 v102, v100, v101
	v_pk_mov_b32 v[100:101], v[124:125], v[134:135] op_sel:[1,0]
	v_alignbit_b32 v99, v102, v99, 16
	v_pk_mul_f32 v[100:101], v[100:101], v[106:107]
	s_nop 0
	v_cvt_pk_f16_f32 v101, v100, v101
	v_alignbit_b32 v100, v101, v102, 16
	v_lshrrev_b32_e32 v101, 16, v101
	v_fma_mixhi_f16 v101, v135, v119, 0
	global_store_dwordx4 v[116:117], v[98:101], off offset:64
	v_or_b32_e32 v122, 32, v158
	s_nop 0
	v_mad_i64_i32 v[98:99], s[0:1], v122, s5, v[160:161]
	v_lshl_add_u64 v[118:119], v[98:99], 0, s[6:7]
	global_load_dwordx4 v[110:113], v[154:155], off offset:16
	global_load_dwordx4 v[114:117], v[154:155], off
	global_load_dwordx4 v[98:101], v[156:157], off offset:16
	global_load_dwordx4 v[102:105], v[156:157], off
	v_lshl_add_u64 v[134:135], v[118:119], 0, v[152:153]
	global_load_dwordx4 v[106:109], v[134:135], off
	v_ashrrev_i32_e32 v123, 31, v122
	s_waitcnt vmcnt(4)
	v_add_f32_e32 v90, v90, v110
	v_mul_f32_e32 v90, 0xbfb8aa3b, v90
	v_exp_f32_e32 v162, v90
	s_waitcnt vmcnt(3)
	v_add_f32_e32 v90, v95, v115
	v_mul_f32_e32 v90, 0xbfb8aa3b, v90
	v_exp_f32_e32 v165, v90
	v_add_f32_e32 v90, v91, v111
	v_mul_f32_e32 v90, 0xbfb8aa3b, v90
	v_exp_f32_e32 v163, v90
	v_add_f32_e32 v90, v96, v116
	v_mul_f32_e32 v90, 0xbfb8aa3b, v90
	v_exp_f32_e32 v166, v90
	v_add_f32_e32 v90, v92, v112
	v_mul_f32_e32 v90, 0xbfb8aa3b, v90
	v_exp_f32_e32 v136, v90
	v_add_f32_e32 v90, v97, v117
	v_mul_f32_e32 v90, 0xbfb8aa3b, v90
	v_exp_f32_e32 v167, v90
	v_add_f32_e32 v90, v93, v113
	v_add_f32_e32 v94, v94, v114
	v_mul_f32_e32 v90, 0xbfb8aa3b, v90
	v_mul_f32_e32 v94, 0xbfb8aa3b, v94
	v_exp_f32_e32 v137, v90
	v_lshl_add_u64 v[90:91], v[118:119], 0, v[128:129]
	v_exp_f32_e32 v164, v94
	global_load_dwordx4 v[94:97], v[154:155], off offset:144
	global_load_dwordx4 v[110:113], v[154:155], off offset:128
	global_load_dwordx4 v[138:141], v[156:157], off offset:144
	global_load_dwordx4 v[168:171], v[156:157], off offset:128
	global_load_dwordx4 v[172:175], v[90:91], off
	v_pk_add_f32 v[166:167], v[166:167], 1.0 op_sel_hi:[1,0]
	v_pk_add_f32 v[164:165], v[164:165], 1.0 op_sel_hi:[1,0]
	s_waitcnt vmcnt(4)
	v_add_f32_e32 v82, v82, v94
	v_mul_f32_e32 v82, 0xbfb8aa3b, v82
	v_exp_f32_e32 v118, v82
	s_waitcnt vmcnt(3)
	v_add_f32_e32 v82, v87, v111
	s_waitcnt vmcnt(0)
	v_cvt_f32_f16_e32 v116, v174
	v_cvt_f32_f16_sdwa v117, v174 dst_sel:DWORD dst_unused:UNUSED_PAD src0_sel:WORD_1
	v_cvt_f32_f16_e32 v130, v172
	v_cvt_f32_f16_sdwa v131, v172 dst_sel:DWORD dst_unused:UNUSED_PAD src0_sel:WORD_1
	v_mul_f32_e32 v82, 0xbfb8aa3b, v82
	v_exp_f32_e32 v133, v82
	v_add_f32_e32 v82, v83, v95
	v_mul_f32_e32 v82, 0xbfb8aa3b, v82
	v_pk_mul_f32 v[92:93], v[138:139], v[116:117]
	v_exp_f32_e32 v119, v82
	v_pk_mul_f32 v[94:95], v[168:169], v[130:131]
	v_pk_mul_f32 v[82:83], v[92:93], v[92:93]
	v_cvt_f32_f16_e32 v120, v173
	v_pk_fma_f32 v[138:139], v[94:95], v[94:95], v[82:83]
	v_add_f32_e32 v82, v88, v112
	v_mul_f32_e32 v82, 0xbfb8aa3b, v82
	v_exp_f32_e32 v124, v82
	v_add_f32_e32 v82, v84, v96
	v_mul_f32_e32 v82, 0xbfb8aa3b, v82
	v_exp_f32_e32 v114, v82
	v_add_f32_e32 v82, v89, v113
	v_cvt_f32_f16_e32 v112, v175
	v_cvt_f32_f16_sdwa v113, v175 dst_sel:DWORD dst_unused:UNUSED_PAD src0_sel:WORD_1
	v_cvt_f32_f16_sdwa v121, v173 dst_sel:DWORD dst_unused:UNUSED_PAD src0_sel:WORD_1
	v_mul_f32_e32 v82, 0xbfb8aa3b, v82
	v_exp_f32_e32 v125, v82
	v_add_f32_e32 v82, v85, v97
	v_add_f32_e32 v86, v86, v110
	v_mul_f32_e32 v82, 0xbfb8aa3b, v82
	v_pk_mul_f32 v[96:97], v[140:141], v[112:113]
	v_mul_f32_e32 v86, 0xbfb8aa3b, v86
	v_exp_f32_e32 v115, v82
	v_pk_mul_f32 v[110:111], v[170:171], v[120:121]
	v_pk_mul_f32 v[82:83], v[96:97], v[96:97]
	v_exp_f32_e32 v132, v86
	v_pk_fma_f32 v[140:141], v[110:111], v[110:111], v[82:83]
	global_load_dwordx4 v[82:85], v[126:127], off offset:16
	global_load_dwordx4 v[86:89], v[126:127], off
	v_cvt_f32_f16_e32 v168, v106
	v_cvt_f32_f16_sdwa v169, v106 dst_sel:DWORD dst_unused:UNUSED_PAD src0_sel:WORD_1
	v_div_scale_f32 v106, s[0:1], v165, v165, 1.0
	v_rcp_f32_e32 v159, v106
	s_nop 0
	v_fma_f32 v170, -v106, v159, 1.0
	v_fmac_f32_e32 v159, v170, v159
	v_div_scale_f32 v170, vcc, 1.0, v165, 1.0
	v_mul_f32_e32 v171, v170, v159
	v_fma_f32 v172, -v106, v171, v170
	v_fmac_f32_e32 v171, v172, v159
	v_fma_f32 v106, -v106, v171, v170
	v_div_fmas_f32 v106, v106, v159, v171
	v_div_fixup_f32 v165, v106, v165, 1.0
	v_div_scale_f32 v106, s[0:1], v164, v164, 1.0
	v_rcp_f32_e32 v159, v106
	s_nop 0
	v_fma_f32 v170, -v106, v159, 1.0
	v_fmac_f32_e32 v159, v170, v159
	v_div_scale_f32 v170, vcc, 1.0, v164, 1.0
	v_mul_f32_e32 v171, v170, v159
	v_fma_f32 v172, -v106, v171, v170
	v_fmac_f32_e32 v171, v172, v159
	v_fma_f32 v106, -v106, v171, v170
	v_div_fmas_f32 v106, v106, v159, v171
	v_div_fixup_f32 v164, v106, v164, 1.0
	v_pk_add_f32 v[170:171], v[164:165], -1.0 op_sel_hi:[1,0]
	v_cvt_f32_f16_e32 v106, v107
	v_cvt_f32_f16_sdwa v107, v107 dst_sel:DWORD dst_unused:UNUSED_PAD src0_sel:WORD_1
	s_waitcnt vmcnt(0)
; __device__ __forceinline__ float sigmoidf_(float x) { return 1.0f / (1.0f + __expf(-x)); }
;     __device__ __forceinline__ void body_a(const f32x4 (&acc)[2][2][4][2], int row0, int cb0) const {
;     ...
;                     const int c = cb0 + 32 * bj;
;                     const f32x4 b0 = *(const f32x4*)(a0 + c), b1 = *(const f32x4*)(a0 + c + 4), q0 = *(const f32x4*)(k_k + c), q1 = *(const f32x4*)(k_k + c + 4);
;                     const h16x8 kh = *(const h16x8*)(C1 + row * LDC1 + 2048 + c);
; #pragma unroll
;                     for (int e = 0; e < 4; ++e) {
;                         a[bj][e] = sigmoidf_(acc[ai][bj][m][0][e] + b0[e]); a[bj][4 + e] = sigmoidf_(acc[ai][bj][m][1][e] + b1[e]);
;                         kv[bj][e] = (float)kh[e]; kv[bj][4 + e] = (float)kh[4 + e];
;                         kk[bj][e] = kv[bj][e] * q0[e]; kk[bj][4 + e] = kv[bj][4 + e] * q1[e];
;                         ss += kk[bj][e] * kk[bj][e] + kk[bj][4 + e] * kk[bj][4 + e];
;                     }
;                 }
;                 ss += __shfl_xor(ss, 16); ss += __shfl_xor(ss, 32);
	v_pk_fma_f32 v[86:87], v[170:171], v[86:87], 1.0 op_sel_hi:[1,1,0]
	s_nop 0
	v_pk_mul_f32 v[86:87], v[86:87], v[168:169]
	s_nop 0
	v_cvt_pk_f16_f32 v86, v86, v87
	v_div_scale_f32 v87, s[0:1], v167, v167, 1.0
	v_rcp_f32_e32 v159, v87
	s_nop 0
	v_fma_f32 v170, -v87, v159, 1.0
	v_fmac_f32_e32 v159, v170, v159
	v_div_scale_f32 v170, vcc, 1.0, v167, 1.0
	v_mul_f32_e32 v171, v170, v159
	v_fma_f32 v172, -v87, v171, v170
	v_fmac_f32_e32 v171, v172, v159
	v_fma_f32 v87, -v87, v171, v170
	v_div_fmas_f32 v87, v87, v159, v171
	v_div_fixup_f32 v167, v87, v167, 1.0
	v_div_scale_f32 v87, s[0:1], v166, v166, 1.0
	v_rcp_f32_e32 v159, v87
	s_nop 0
	v_fma_f32 v170, -v87, v159, 1.0
	v_fmac_f32_e32 v159, v170, v159
	v_div_scale_f32 v170, vcc, 1.0, v166, 1.0
	v_mul_f32_e32 v171, v170, v159
	v_fma_f32 v172, -v87, v171, v170
	v_fmac_f32_e32 v171, v172, v159
	v_fma_f32 v87, -v87, v171, v170
	v_div_fmas_f32 v87, v87, v159, v171
	v_div_fixup_f32 v166, v87, v166, 1.0
	v_pk_add_f32 v[170:171], v[166:167], -1.0 op_sel_hi:[1,0]
	s_nop 0
	v_pk_fma_f32 v[88:89], v[170:171], v[88:89], 1.0 op_sel_hi:[1,1,0]
	v_cvt_f32_f16_e32 v170, v108
	v_pk_mul_f32 v[88:89], v[88:89], v[106:107]
	v_cvt_f32_f16_sdwa v171, v108 dst_sel:DWORD dst_unused:UNUSED_PAD src0_sel:WORD_1
	v_cvt_pk_f16_f32 v87, v88, v89
	v_pk_add_f32 v[88:89], v[162:163], 1.0 op_sel_hi:[1,0]
	s_nop 0
	v_div_scale_f32 v108, s[0:1], v89, v89, 1.0
	v_rcp_f32_e32 v159, v108
	s_nop 0
	v_fma_f32 v162, -v108, v159, 1.0
	v_fmac_f32_e32 v159, v162, v159
	v_div_scale_f32 v162, vcc, 1.0, v89, 1.0
	v_mul_f32_e32 v163, v162, v159
	v_fma_f32 v172, -v108, v163, v162
	v_fmac_f32_e32 v163, v172, v159
	v_fma_f32 v108, -v108, v163, v162
	v_div_fmas_f32 v108, v108, v159, v163
	v_div_fixup_f32 v163, v108, v89, 1.0
	v_div_scale_f32 v89, s[0:1], v88, v88, 1.0
	v_rcp_f32_e32 v108, v89
	s_nop 0
	v_fma_f32 v159, -v89, v108, 1.0
	v_fmac_f32_e32 v108, v159, v108
	v_div_scale_f32 v159, vcc, 1.0, v88, 1.0
	v_mul_f32_e32 v162, v159, v108
	v_fma_f32 v172, -v89, v162, v159
	v_fmac_f32_e32 v162, v172, v108
	v_fma_f32 v89, -v89, v162, v159
	v_div_fmas_f32 v89, v89, v108, v162
	v_div_fixup_f32 v162, v89, v88, 1.0
	v_pk_add_f32 v[88:89], v[162:163], -1.0 op_sel_hi:[1,0]
	v_cvt_f32_f16_e32 v108, v109
	v_pk_fma_f32 v[82:83], v[88:89], v[82:83], 1.0 op_sel_hi:[1,1,0]
	v_cvt_f32_f16_sdwa v109, v109 dst_sel:DWORD dst_unused:UNUSED_PAD src0_sel:WORD_1
	v_pk_mul_f32 v[82:83], v[82:83], v[170:171]
	v_pk_mul_f32 v[100:101], v[100:101], v[108:109]
	v_cvt_pk_f16_f32 v88, v82, v83
	v_pk_add_f32 v[82:83], v[136:137], 1.0 op_sel_hi:[1,0]
	s_nop 0
	v_div_scale_f32 v89, s[0:1], v83, v83, 1.0
	v_rcp_f32_e32 v136, v89
	s_nop 0
	v_fma_f32 v137, -v89, v136, 1.0
	v_fmac_f32_e32 v136, v137, v136
	v_div_scale_f32 v137, vcc, 1.0, v83, 1.0
	v_mul_f32_e32 v159, v137, v136
	v_fma_f32 v172, -v89, v159, v137
	v_fmac_f32_e32 v159, v172, v136
	v_fma_f32 v89, -v89, v159, v137
	v_div_fmas_f32 v89, v89, v136, v159
	v_div_fixup_f32 v83, v89, v83, 1.0
	v_div_scale_f32 v89, s[0:1], v82, v82, 1.0
	v_rcp_f32_e32 v136, v89
	s_nop 0
	v_fma_f32 v137, -v89, v136, 1.0
	v_fmac_f32_e32 v136, v137, v136
	v_div_scale_f32 v137, vcc, 1.0, v82, 1.0
	v_mul_f32_e32 v159, v137, v136
	v_fma_f32 v172, -v89, v159, v137
	v_fmac_f32_e32 v159, v172, v136
	v_fma_f32 v89, -v89, v159, v137
	v_div_fmas_f32 v89, v89, v136, v159
	v_div_fixup_f32 v82, v89, v82, 1.0
	v_pk_add_f32 v[136:137], v[82:83], -1.0 op_sel_hi:[1,0]
	s_nop 0
	v_pk_fma_f32 v[84:85], v[136:137], v[84:85], 1.0 op_sel_hi:[1,1,0]
	s_nop 0
	v_pk_mul_f32 v[84:85], v[84:85], v[108:109]
	v_lshlrev_b64 v[108:109], 12, v[122:123]
	v_cvt_pk_f16_f32 v89, v84, v85
	global_store_dwordx4 v[134:135], v[86:89], off
	v_pk_mul_f32 v[84:85], v[102:103], v[168:169]
	v_pk_mul_f32 v[102:103], v[100:101], v[100:101]
	v_pk_mul_f32 v[88:89], v[98:99], v[170:171]
	v_pk_mul_f32 v[86:87], v[104:105], v[106:107]
	v_pk_mul_f32 v[98:99], v[88:89], v[88:89]
	v_pk_fma_f32 v[102:103], v[86:87], v[86:87], v[102:103]
	v_pk_fma_f32 v[98:99], v[84:85], v[84:85], v[98:99]
	s_nop 0
	v_add_f32_e32 v98, v98, v99
	v_add_f32_e32 v98, v102, v98
	v_add_f32_e32 v98, v103, v98
	v_add_f32_e32 v98, v98, v138
	v_add_f32_e32 v98, v139, v98
	v_add_f32_e32 v98, v140, v98
	v_add_f32_e32 v98, v141, v98
	ds_bpermute_b32 v99, v206, v98
	s_waitcnt lgkmcnt(0)
	v_add_f32_e32 v98, v98, v99
	ds_bpermute_b32 v99, v207, v98
	s_waitcnt lgkmcnt(0)
;     __device__ __forceinline__ void body_a(const f32x4 (&acc)[2][2][4][2], int row0, int cb0) const {
;     ...
;                 ss += __shfl_xor(ss, 16); ss += __shfl_xor(ss, 32);
;                 const float inv = 1.0f / fmaxf(sqrtf(ss), 1e-12f);
; #pragma unroll
;                 for (int bj = 0; bj < 2; ++bj) {
;                     const int c = cb0 + 32 * bj;
;                     const f32x4 p0 = *(const f32x4*)(k_a + c), p1 = *(const f32x4*)(k_a + c + 4);
;                     f32x4 ko0, ko1, ao0, ao1, bo0, bo1;
; #pragma unroll
;                     for (int e = 0; e < 4; ++e) {
;                         ko0[e] = kv[bj][e] * (1.0f + (a[bj][e] - 1.0f) * p0[e]); ko1[e] = kv[bj][4 + e] * (1.0f + (a[bj][4 + e] - 1.0f) * p1[e]);
;                         const float n0_ = kk[bj][e] * inv, n1_ = kk[bj][4 + e] * inv;
;                         ao0[e] = -n0_; ao1[e] = -n1_; bo0[e] = n0_ * a[bj][e]; bo1[e] = n1_ * a[bj][4 + e];
;                     }
;                     *(u32x4*)(C1 + row * LDC1 + 2048 + c) = pack8(ko0, ko1);
;                     *(u32x4*)(AA + row * DM + c) = pack8(ao0, ao1);
;                     *(u32x4*)(Ab + row * DM + c) = pack8(bo0, bo1);
;                 }
	v_add_f32_e32 v98, v98, v99
	v_cmp_gt_f32_e32 vcc, s4, v98
	v_mul_f32_e32 v99, 0x4f800000, v98
	s_nop 0
	v_cndmask_b32_e32 v98, v98, v99, vcc
	v_sqrt_f32_e32 v99, v98
	s_nop 0
	v_add_u32_e32 v102, -1, v99
	v_fma_f32 v103, -v102, v99, v98
	v_cmp_ge_f32_e64 s[0:1], 0, v103
	v_add_u32_e32 v103, 1, v99
	s_nop 0
	v_cndmask_b32_e64 v102, v99, v102, s[0:1]
	v_fma_f32 v99, -v103, v99, v98
	v_cmp_lt_f32_e64 s[0:1], 0, v99
	s_nop 1
	v_cndmask_b32_e64 v99, v102, v103, s[0:1]
	v_mul_f32_e32 v102, 0x37800000, v99
	v_cndmask_b32_e32 v99, v99, v102, vcc
	v_cmp_class_f32_e32 vcc, v98, v244
	s_nop 1
	v_cndmask_b32_e32 v98, v99, v98, vcc
	v_max_f32_e32 v98, 0x2b8cbccc, v98
	v_div_scale_f32 v99, s[0:1], v98, v98, 1.0
	v_rcp_f32_e32 v102, v99
	s_nop 0
	v_fma_f32 v103, -v99, v102, 1.0
	v_fmac_f32_e32 v102, v103, v102
	v_div_scale_f32 v103, vcc, 1.0, v98, 1.0
	v_mul_f32_e32 v104, v103, v102
	v_fma_f32 v105, -v99, v104, v103
	v_fmac_f32_e32 v104, v105, v102
	v_fma_f32 v99, -v99, v104, v103
	v_div_fmas_f32 v99, v99, v102, v104
	v_div_fixup_f32 v102, v99, v98, 1.0
	v_pk_mul_f32 v[106:107], v[86:87], v[102:103] op_sel_hi:[1,0]
	v_pk_mul_f32 v[104:105], v[84:85], v[102:103] op_sel_hi:[1,0]
	v_cvt_pk_f16_f32 v85, v106, v107
	v_cvt_pk_f16_f32 v84, v104, v105
	v_xor_b32_e32 v86, 0x8000, v85
	v_xor_b32_sdwa v85, s63, v85 dst_sel:DWORD dst_unused:UNUSED_PAD src0_sel:DWORD src1_sel:WORD_1
	v_pk_mul_f32 v[88:89], v[88:89], v[102:103] op_sel_hi:[1,0]
	v_pk_mul_f32 v[100:101], v[100:101], v[102:103] op_sel_hi:[1,0]
	v_perm_b32 v85, v85, v86, s33
	v_xor_b32_e32 v86, 0x8000, v84
	v_xor_b32_sdwa v84, s63, v84 dst_sel:DWORD dst_unused:UNUSED_PAD src0_sel:DWORD src1_sel:WORD_1
	v_perm_b32 v84, v84, v86, s33
	v_pk_add_f32 v[86:87], v[88:89], 0 neg_lo:[1,1] neg_hi:[1,1]
	v_pk_add_f32 v[98:99], v[100:101], 0 neg_lo:[1,1] neg_hi:[1,1]
	v_cvt_pk_f16_f32 v86, v86, v87
	v_cvt_pk_f16_f32 v87, v98, v99
	v_lshl_add_u64 v[98:99], s[10:11], 0, v[108:109]
	v_lshl_add_u64 v[98:99], v[98:99], 0, v[152:153]
	global_store_dwordx4 v[98:99], v[84:87], off
	v_fma_mixlo_f16 v103, v164, v104, 0
	v_mul_f32_e32 v122, v94, v102
	v_pk_mov_b32 v[84:85], v[164:165], v[166:167] op_sel:[1,0]
	v_pk_mov_b32 v[86:87], v[104:105], v[106:107] op_sel:[1,0]
	v_pk_mov_b32 v[104:105], v[106:107], v[88:89] op_sel:[1,0]
	v_pk_mul_f32 v[84:85], v[84:85], v[86:87]
	v_pk_mov_b32 v[86:87], v[166:167], v[162:163] op_sel:[1,0]
	v_cvt_pk_f16_f32 v85, v84, v85
	v_pk_mul_f32 v[86:87], v[86:87], v[104:105]
	v_pack_b32_f16 v84, v103, v85
	v_cvt_pk_f16_f32 v103, v86, v87
	v_pk_mov_b32 v[86:87], v[162:163], v[82:83] op_sel:[1,0]
	v_pk_mov_b32 v[88:89], v[88:89], v[100:101] op_sel:[1,0]
	v_alignbit_b32 v85, v103, v85, 16
	v_pk_mul_f32 v[86:87], v[86:87], v[88:89]
	v_pk_add_f32 v[104:105], v[132:133], 1.0 op_sel_hi:[1,0]
	v_cvt_pk_f16_f32 v82, v86, v87
	v_lshrrev_b32_e32 v87, 16, v82
	v_alignbit_b32 v86, v82, v103, 16
	v_fma_mixhi_f16 v87, v83, v101, 0
	v_lshl_add_u64 v[82:83], s[2:3], 0, v[108:109]
	v_lshl_add_u64 v[100:101], v[82:83], 0, v[152:153]
	global_store_dwordx4 v[100:101], v[84:87], off
	global_load_dwordx4 v[82:85], v[126:127], off offset:144
	s_nop 0
	global_load_dwordx4 v[86:89], v[126:127], off offset:128
	v_div_scale_f32 v106, s[0:1], v105, v105, 1.0
	v_rcp_f32_e32 v107, v106
	v_mul_f32_e32 v103, v97, v102
	v_fma_f32 v108, -v106, v107, 1.0
	v_fmac_f32_e32 v107, v108, v107
	v_div_scale_f32 v108, vcc, 1.0, v105, 1.0
	v_mul_f32_e32 v109, v108, v107
	v_fma_f32 v123, -v106, v109, v108
	v_fmac_f32_e32 v109, v123, v107
	v_fma_f32 v106, -v106, v109, v108
	v_div_fmas_f32 v106, v106, v107, v109
	v_div_fixup_f32 v105, v106, v105, 1.0
	v_div_scale_f32 v106, s[0:1], v104, v104, 1.0
	v_rcp_f32_e32 v107, v106
	s_nop 0
	v_fma_f32 v108, -v106, v107, 1.0
	v_fmac_f32_e32 v107, v108, v107
	v_div_scale_f32 v108, vcc, 1.0, v104, 1.0
	v_mul_f32_e32 v109, v108, v107
	v_fma_f32 v123, -v106, v109, v108
	v_fmac_f32_e32 v109, v123, v107
	v_fma_f32 v106, -v106, v109, v108
	v_div_fmas_f32 v106, v106, v107, v109
	v_div_fixup_f32 v104, v106, v104, 1.0
	v_pk_add_f32 v[106:107], v[104:105], -1.0 op_sel_hi:[1,0]
	s_waitcnt vmcnt(0)
	v_pk_fma_f32 v[86:87], v[106:107], v[86:87], 1.0 op_sel_hi:[1,1,0]
	s_nop 0
	v_pk_mul_f32 v[86:87], v[86:87], v[130:131]
	v_pk_add_f32 v[106:107], v[124:125], 1.0 op_sel_hi:[1,0]
	v_cvt_pk_f16_f32 v86, v86, v87
	v_div_scale_f32 v87, s[0:1], v107, v107, 1.0
	v_rcp_f32_e32 v108, v87
	s_nop 0
	v_fma_f32 v109, -v87, v108, 1.0
	v_fmac_f32_e32 v108, v109, v108
	v_div_scale_f32 v109, vcc, 1.0, v107, 1.0
	v_mul_f32_e32 v123, v109, v108
	v_fma_f32 v124, -v87, v123, v109
	v_fmac_f32_e32 v123, v124, v108
	v_fma_f32 v87, -v87, v123, v109
	v_div_fmas_f32 v87, v87, v108, v123
	v_div_fixup_f32 v107, v87, v107, 1.0
	v_div_scale_f32 v87, s[0:1], v106, v106, 1.0
	v_rcp_f32_e32 v108, v87
	s_nop 0
	v_fma_f32 v109, -v87, v108, 1.0
	v_fmac_f32_e32 v108, v109, v108
	v_div_scale_f32 v109, vcc, 1.0, v106, 1.0
	v_mul_f32_e32 v123, v109, v108
	v_fma_f32 v124, -v87, v123, v109
	v_fmac_f32_e32 v123, v124, v108
	v_fma_f32 v87, -v87, v123, v109
	v_div_fmas_f32 v87, v87, v108, v123
	v_div_fixup_f32 v106, v87, v106, 1.0
	v_pk_add_f32 v[108:109], v[106:107], -1.0 op_sel_hi:[1,0]
	s_nop 0
	v_pk_fma_f32 v[88:89], v[108:109], v[88:89], 1.0 op_sel_hi:[1,1,0]
	s_nop 0
	v_pk_mul_f32 v[88:89], v[88:89], v[120:121]
	s_nop 0
	v_cvt_pk_f16_f32 v87, v88, v89
	v_pk_add_f32 v[88:89], v[118:119], 1.0 op_sel_hi:[1,0]
	s_nop 0
	v_div_scale_f32 v108, s[0:1], v89, v89, 1.0
	v_rcp_f32_e32 v109, v108
	s_nop 0
	v_fma_f32 v118, -v108, v109, 1.0
	v_fmac_f32_e32 v109, v118, v109
	v_div_scale_f32 v118, vcc, 1.0, v89, 1.0
	v_mul_f32_e32 v119, v118, v109
	v_fma_f32 v120, -v108, v119, v118
; __device__ __forceinline__ float sigmoidf_(float x) { return 1.0f / (1.0f + __expf(-x)); }
;     __device__ __forceinline__ void body_a(const f32x4 (&acc)[2][2][4][2], int row0, int cb0) const {
;     ...
;                     const int c = cb0 + 32 * bj;
;                     const f32x4 b0 = *(const f32x4*)(a0 + c), b1 = *(const f32x4*)(a0 + c + 4), q0 = *(const f32x4*)(k_k + c), q1 = *(const f32x4*)(k_k + c + 4);
;                     const h16x8 kh = *(const h16x8*)(C1 + row * LDC1 + 2048 + c);
; #pragma unroll
;                     for (int e = 0; e < 4; ++e) {
;                         a[bj][e] = sigmoidf_(acc[ai][bj][m][0][e] + b0[e]); a[bj][4 + e] = sigmoidf_(acc[ai][bj][m][1][e] + b1[e]);
;                         kv[bj][e] = (float)kh[e]; kv[bj][4 + e] = (float)kh[4 + e];
;                         kk[bj][e] = kv[bj][e] * q0[e]; kk[bj][4 + e] = kv[bj][4 + e] * q1[e];
;                         ss += kk[bj][e] * kk[bj][e] + kk[bj][4 + e] * kk[bj][4 + e];
;                     }
;                 }
;                 ss += __shfl_xor(ss, 16); ss += __shfl_xor(ss, 32);
;                 const float inv = 1.0f / fmaxf(sqrtf(ss), 1e-12f);
; #pragma unroll
;                 for (int bj = 0; bj < 2; ++bj) {
;                     const int c = cb0 + 32 * bj;
;                     const f32x4 p0 = *(const f32x4*)(k_a + c), p1 = *(const f32x4*)(k_a + c + 4);
;                     f32x4 ko0, ko1, ao0, ao1, bo0, bo1;
; #pragma unroll
;                     for (int e = 0; e < 4; ++e) {
;                         ko0[e] = kv[bj][e] * (1.0f + (a[bj][e] - 1.0f) * p0[e]); ko1[e] = kv[bj][4 + e] * (1.0f + (a[bj][4 + e] - 1.0f) * p1[e]);
;                         const float n0_ = kk[bj][e] * inv, n1_ = kk[bj][4 + e] * inv;
;                         ao0[e] = -n0_; ao1[e] = -n1_; bo0[e] = n0_ * a[bj][e]; bo1[e] = n1_ * a[bj][4 + e];
;                     }
;                     *(u32x4*)(C1 + row * LDC1 + 2048 + c) = pack8(ko0, ko1);
;                     *(u32x4*)(AA + row * DM + c) = pack8(ao0, ao1);
;                     *(u32x4*)(Ab + row * DM + c) = pack8(bo0, bo1);
;                 }
	v_fmac_f32_e32 v119, v120, v109
	v_fma_f32 v108, -v108, v119, v118
	v_div_fmas_f32 v108, v108, v109, v119
	v_div_fixup_f32 v109, v108, v89, 1.0
	v_div_scale_f32 v89, s[0:1], v88, v88, 1.0
	v_rcp_f32_e32 v108, v89
	s_nop 0
	v_fma_f32 v118, -v89, v108, 1.0
	v_fmac_f32_e32 v108, v118, v108
	v_div_scale_f32 v118, vcc, 1.0, v88, 1.0
	v_mul_f32_e32 v119, v118, v108
	v_fma_f32 v120, -v89, v119, v118
	v_fmac_f32_e32 v119, v120, v108
	v_fma_f32 v89, -v89, v119, v118
	v_div_fmas_f32 v89, v89, v108, v119
	v_div_fixup_f32 v108, v89, v88, 1.0
	v_pk_add_f32 v[88:89], v[108:109], -1.0 op_sel_hi:[1,0]
	s_nop 0
	v_pk_fma_f32 v[82:83], v[88:89], v[82:83], 1.0 op_sel_hi:[1,1,0]
	s_nop 0
	v_pk_mul_f32 v[82:83], v[82:83], v[116:117]
	s_nop 0
	v_cvt_pk_f16_f32 v88, v82, v83
	v_pk_add_f32 v[82:83], v[114:115], 1.0 op_sel_hi:[1,0]
	s_nop 0
	v_div_scale_f32 v89, s[0:1], v83, v83, 1.0
	v_rcp_f32_e32 v114, v89
	s_nop 0
	v_fma_f32 v115, -v89, v114, 1.0
	v_fmac_f32_e32 v114, v115, v114
	v_div_scale_f32 v115, vcc, 1.0, v83, 1.0
	v_mul_f32_e32 v116, v115, v114
	v_fma_f32 v117, -v89, v116, v115
	v_fmac_f32_e32 v116, v117, v114
	v_fma_f32 v89, -v89, v116, v115
	v_div_fmas_f32 v89, v89, v114, v116
	v_div_fixup_f32 v115, v89, v83, 1.0
	v_div_scale_f32 v83, s[0:1], v82, v82, 1.0
	v_rcp_f32_e32 v89, v83
	s_nop 0
	v_fma_f32 v114, -v83, v89, 1.0
	v_fmac_f32_e32 v89, v114, v89
	v_div_scale_f32 v114, vcc, 1.0, v82, 1.0
	v_mul_f32_e32 v116, v114, v89
	v_fma_f32 v117, -v83, v116, v114
	v_fmac_f32_e32 v116, v117, v89
	v_fma_f32 v83, -v83, v116, v114
	v_div_fmas_f32 v83, v83, v89, v116
	v_div_fixup_f32 v114, v83, v82, 1.0
	v_pk_add_f32 v[82:83], v[114:115], -1.0 op_sel_hi:[1,0]
	s_nop 0
	v_pk_fma_f32 v[82:83], v[82:83], v[84:85], 1.0 op_sel_hi:[1,1,0]
	v_cvt_f16_f32_e64 v84, -v122
	v_pk_mul_f32 v[82:83], v[82:83], v[112:113]
	s_nop 0
	v_cvt_pk_f16_f32 v89, v82, v83
	v_pk_mov_b32 v[82:83], v[94:95], v[110:111] op_sel:[1,0]
	global_store_dwordx4 v[90:91], v[86:89], off
	s_nop 1
	v_pk_mul_f32 v[86:87], v[82:83], v[102:103] op_sel_hi:[1,0]
	s_nop 0
	v_cvt_pk_f16_f32 v83, v86, v87
	v_pack_b32_f16 v82, v84, -v83
	v_pk_mov_b32 v[84:85], v[110:111], v[92:93] op_sel:[1,0]
	v_xor_b32_sdwa v83, s63, v83 dst_sel:DWORD dst_unused:UNUSED_PAD src0_sel:DWORD src1_sel:WORD_1
	v_pk_mul_f32 v[88:89], v[84:85], v[102:103] op_sel_hi:[1,0]
	s_nop 0
	v_cvt_pk_f16_f32 v84, v88, v89
	v_xor_b32_e32 v85, 0x8000, v84
	v_perm_b32 v83, v85, v83, s33
	v_xor_b32_sdwa v94, s63, v84 dst_sel:DWORD dst_unused:UNUSED_PAD src0_sel:DWORD src1_sel:WORD_1
	v_pk_mov_b32 v[84:85], v[92:93], v[96:97] op_sel:[1,0]
	v_cvt_f16_f32_e64 v92, -v103
	v_pk_mul_f32 v[90:91], v[84:85], v[102:103] op_sel_hi:[1,0]
	s_nop 0
	v_cvt_pk_f16_f32 v85, v90, v91
	v_xor_b32_e32 v84, 0x8000, v85
	v_xor_b32_sdwa v85, s63, v85 dst_sel:DWORD dst_unused:UNUSED_PAD src0_sel:DWORD src1_sel:WORD_1
	v_perm_b32 v84, v84, v94, s33
	v_perm_b32 v85, v92, v85, s33
	global_store_dwordx4 v[98:99], v[82:85], off offset:64
	s_nop 1
	v_pk_mov_b32 v[82:83], v[104:105], v[106:107] op_sel:[1,0]
	v_fma_mixlo_f16 v84, v104, v122, 0
	v_pk_mul_f32 v[82:83], v[82:83], v[86:87]
	s_nop 0
	v_cvt_pk_f16_f32 v83, v82, v83
	v_pack_b32_f16 v82, v84, v83
	v_pk_mov_b32 v[84:85], v[106:107], v[108:109] op_sel:[1,0]
	s_nop 0
	v_pk_mul_f32 v[84:85], v[84:85], v[88:89]
	s_nop 0
	v_cvt_pk_f16_f32 v86, v84, v85
	v_pk_mov_b32 v[84:85], v[108:109], v[114:115] op_sel:[1,0]
	v_alignbit_b32 v83, v86, v83, 16
	v_pk_mul_f32 v[84:85], v[84:85], v[90:91]
	s_nop 0
	v_cvt_pk_f16_f32 v85, v84, v85
	v_alignbit_b32 v84, v85, v86, 16
	v_lshrrev_b32_e32 v85, 16, v85
	v_fma_mixhi_f16 v85, v115, v103, 0
	global_store_dwordx4 v[100:101], v[82:85], off offset:64
	v_or_b32_e32 v106, 48, v158
	s_nop 0
	v_mad_i64_i32 v[82:83], s[0:1], v106, s5, v[160:161]
	v_lshl_add_u64 v[102:103], v[82:83], 0, s[6:7]
	global_load_dwordx4 v[94:97], v[154:155], off offset:16
	global_load_dwordx4 v[98:101], v[154:155], off
	global_load_dwordx4 v[82:85], v[156:157], off offset:16
	global_load_dwordx4 v[86:89], v[156:157], off
	v_lshl_add_u64 v[114:115], v[102:103], 0, v[152:153]
	global_load_dwordx4 v[90:93], v[114:115], off
	v_ashrrev_i32_e32 v107, 31, v106
	s_waitcnt vmcnt(4)
	v_add_f32_e32 v74, v74, v94
	v_mul_f32_e32 v74, 0xbfb8aa3b, v74
	v_exp_f32_e32 v122, v74
	s_waitcnt vmcnt(3)
	v_add_f32_e32 v74, v79, v99
	v_mul_f32_e32 v74, 0xbfb8aa3b, v74
	v_exp_f32_e32 v125, v74
	v_add_f32_e32 v74, v75, v95
	v_mul_f32_e32 v74, 0xbfb8aa3b, v74
	v_exp_f32_e32 v123, v74
	v_add_f32_e32 v74, v80, v100
	v_mul_f32_e32 v74, 0xbfb8aa3b, v74
	v_exp_f32_e32 v130, v74
	v_add_f32_e32 v74, v76, v96
	v_mul_f32_e32 v74, 0xbfb8aa3b, v74
	v_exp_f32_e32 v116, v74
	v_add_f32_e32 v74, v81, v101
	v_mul_f32_e32 v74, 0xbfb8aa3b, v74
	v_exp_f32_e32 v131, v74
	v_add_f32_e32 v74, v77, v97
	v_add_f32_e32 v78, v78, v98
	v_mul_f32_e32 v74, 0xbfb8aa3b, v74
	v_mul_f32_e32 v78, 0xbfb8aa3b, v78
	v_exp_f32_e32 v117, v74
	v_lshl_add_u64 v[74:75], v[102:103], 0, v[128:129]
	v_exp_f32_e32 v124, v78
	global_load_dwordx4 v[78:81], v[154:155], off offset:144
	global_load_dwordx4 v[94:97], v[154:155], off offset:128
	global_load_dwordx4 v[118:121], v[156:157], off offset:144
	global_load_dwordx4 v[132:135], v[156:157], off offset:128
	global_load_dwordx4 v[136:139], v[74:75], off
	v_pk_add_f32 v[130:131], v[130:131], 1.0 op_sel_hi:[1,0]
	v_pk_add_f32 v[124:125], v[124:125], 1.0 op_sel_hi:[1,0]
	s_waitcnt vmcnt(4)
	v_add_f32_e32 v66, v66, v78
	v_mul_f32_e32 v66, 0xbfb8aa3b, v66
	v_exp_f32_e32 v102, v66
	s_waitcnt vmcnt(3)
	v_add_f32_e32 v66, v71, v95
	s_waitcnt vmcnt(0)
; __device__ __forceinline__ float sigmoidf_(float x) { return 1.0f / (1.0f + __expf(-x)); }
;     __device__ __forceinline__ void body_a(const f32x4 (&acc)[2][2][4][2], int row0, int cb0) const {
;     ...
;                     const int c = cb0 + 32 * bj;
;                     const f32x4 b0 = *(const f32x4*)(a0 + c), b1 = *(const f32x4*)(a0 + c + 4), q0 = *(const f32x4*)(k_k + c), q1 = *(const f32x4*)(k_k + c + 4);
;                     const h16x8 kh = *(const h16x8*)(C1 + row * LDC1 + 2048 + c);
; #pragma unroll
;                     for (int e = 0; e < 4; ++e) {
;                         a[bj][e] = sigmoidf_(acc[ai][bj][m][0][e] + b0[e]); a[bj][4 + e] = sigmoidf_(acc[ai][bj][m][1][e] + b1[e]);
;                         kv[bj][e] = (float)kh[e]; kv[bj][4 + e] = (float)kh[4 + e];
;                         kk[bj][e] = kv[bj][e] * q0[e]; kk[bj][4 + e] = kv[bj][4 + e] * q1[e];
;                         ss += kk[bj][e] * kk[bj][e] + kk[bj][4 + e] * kk[bj][4 + e];
;                     }
;                 }
;                 ss += __shfl_xor(ss, 16); ss += __shfl_xor(ss, 32);
	v_cvt_f32_f16_e32 v100, v138
	v_cvt_f32_f16_sdwa v101, v138 dst_sel:DWORD dst_unused:UNUSED_PAD src0_sel:WORD_1
	v_cvt_f32_f16_e32 v110, v136
	v_cvt_f32_f16_sdwa v111, v136 dst_sel:DWORD dst_unused:UNUSED_PAD src0_sel:WORD_1
	v_mul_f32_e32 v66, 0xbfb8aa3b, v66
	v_exp_f32_e32 v113, v66
	v_add_f32_e32 v66, v67, v79
	v_mul_f32_e32 v66, 0xbfb8aa3b, v66
	v_pk_mul_f32 v[76:77], v[118:119], v[100:101]
	v_exp_f32_e32 v103, v66
	v_pk_mul_f32 v[78:79], v[132:133], v[110:111]
	v_pk_mul_f32 v[66:67], v[76:77], v[76:77]
	v_cvt_f32_f16_e32 v104, v137
	v_pk_fma_f32 v[118:119], v[78:79], v[78:79], v[66:67]
	v_add_f32_e32 v66, v72, v96
	v_mul_f32_e32 v66, 0xbfb8aa3b, v66
	v_exp_f32_e32 v108, v66
	v_add_f32_e32 v66, v68, v80
	v_mul_f32_e32 v66, 0xbfb8aa3b, v66
	v_exp_f32_e32 v98, v66
	v_add_f32_e32 v66, v73, v97
	v_cvt_f32_f16_e32 v96, v139
	v_cvt_f32_f16_sdwa v97, v139 dst_sel:DWORD dst_unused:UNUSED_PAD src0_sel:WORD_1
	v_cvt_f32_f16_sdwa v105, v137 dst_sel:DWORD dst_unused:UNUSED_PAD src0_sel:WORD_1
	v_mul_f32_e32 v66, 0xbfb8aa3b, v66
	v_exp_f32_e32 v109, v66
	v_add_f32_e32 v66, v69, v81
	v_add_f32_e32 v70, v70, v94
	v_mul_f32_e32 v66, 0xbfb8aa3b, v66
	v_pk_mul_f32 v[80:81], v[120:121], v[96:97]
	v_mul_f32_e32 v70, 0xbfb8aa3b, v70
	v_exp_f32_e32 v99, v66
	v_pk_mul_f32 v[94:95], v[134:135], v[104:105]
	v_pk_mul_f32 v[66:67], v[80:81], v[80:81]
	v_exp_f32_e32 v112, v70
	v_pk_fma_f32 v[120:121], v[94:95], v[94:95], v[66:67]
	global_load_dwordx4 v[66:69], v[126:127], off offset:16
	global_load_dwordx4 v[70:73], v[126:127], off
	v_cvt_f32_f16_e32 v132, v90
	v_cvt_f32_f16_sdwa v133, v90 dst_sel:DWORD dst_unused:UNUSED_PAD src0_sel:WORD_1
	v_div_scale_f32 v90, s[0:1], v125, v125, 1.0
	v_rcp_f32_e32 v134, v90
	s_nop 0
	v_fma_f32 v135, -v90, v134, 1.0
	v_fmac_f32_e32 v134, v135, v134
	v_div_scale_f32 v135, vcc, 1.0, v125, 1.0
	v_mul_f32_e32 v136, v135, v134
	v_fma_f32 v137, -v90, v136, v135
	v_fmac_f32_e32 v136, v137, v134
	v_fma_f32 v90, -v90, v136, v135
	v_div_fmas_f32 v90, v90, v134, v136
	v_div_fixup_f32 v125, v90, v125, 1.0
	v_div_scale_f32 v90, s[0:1], v124, v124, 1.0
	v_rcp_f32_e32 v134, v90
	s_nop 0
	v_fma_f32 v135, -v90, v134, 1.0
	v_fmac_f32_e32 v134, v135, v134
	v_div_scale_f32 v135, vcc, 1.0, v124, 1.0
	v_mul_f32_e32 v136, v135, v134
	v_fma_f32 v137, -v90, v136, v135
	v_fmac_f32_e32 v136, v137, v134
	v_fma_f32 v90, -v90, v136, v135
	v_div_fmas_f32 v90, v90, v134, v136
	v_div_fixup_f32 v124, v90, v124, 1.0
	v_pk_add_f32 v[134:135], v[124:125], -1.0 op_sel_hi:[1,0]
	v_cvt_f32_f16_e32 v90, v91
	v_cvt_f32_f16_sdwa v91, v91 dst_sel:DWORD dst_unused:UNUSED_PAD src0_sel:WORD_1
	s_waitcnt vmcnt(0)
	v_pk_fma_f32 v[70:71], v[134:135], v[70:71], 1.0 op_sel_hi:[1,1,0]
	s_nop 0
	v_pk_mul_f32 v[70:71], v[70:71], v[132:133]
	s_nop 0
	v_cvt_pk_f16_f32 v70, v70, v71
	v_div_scale_f32 v71, s[0:1], v131, v131, 1.0
	v_rcp_f32_e32 v134, v71
	s_nop 0
	v_fma_f32 v135, -v71, v134, 1.0
	v_fmac_f32_e32 v134, v135, v134
	v_div_scale_f32 v135, vcc, 1.0, v131, 1.0
	v_mul_f32_e32 v136, v135, v134
	v_fma_f32 v137, -v71, v136, v135
	v_fmac_f32_e32 v136, v137, v134
	v_fma_f32 v71, -v71, v136, v135
	v_div_fmas_f32 v71, v71, v134, v136
	v_div_fixup_f32 v131, v71, v131, 1.0
	v_div_scale_f32 v71, s[0:1], v130, v130, 1.0
	v_rcp_f32_e32 v134, v71
	s_nop 0
	v_fma_f32 v135, -v71, v134, 1.0
	v_fmac_f32_e32 v134, v135, v134
	v_div_scale_f32 v135, vcc, 1.0, v130, 1.0
	v_mul_f32_e32 v136, v135, v134
	v_fma_f32 v137, -v71, v136, v135
	v_fmac_f32_e32 v136, v137, v134
	v_fma_f32 v71, -v71, v136, v135
	v_div_fmas_f32 v71, v71, v134, v136
	v_div_fixup_f32 v130, v71, v130, 1.0
	v_pk_add_f32 v[134:135], v[130:131], -1.0 op_sel_hi:[1,0]
	s_nop 0
	v_pk_fma_f32 v[72:73], v[134:135], v[72:73], 1.0 op_sel_hi:[1,1,0]
	v_cvt_f32_f16_e32 v134, v92
	v_pk_mul_f32 v[72:73], v[72:73], v[90:91]
	v_cvt_f32_f16_sdwa v135, v92 dst_sel:DWORD dst_unused:UNUSED_PAD src0_sel:WORD_1
	v_cvt_pk_f16_f32 v71, v72, v73
	v_pk_add_f32 v[72:73], v[122:123], 1.0 op_sel_hi:[1,0]
	s_nop 0
	v_div_scale_f32 v92, s[0:1], v73, v73, 1.0
	v_rcp_f32_e32 v122, v92
	s_nop 0
	v_fma_f32 v123, -v92, v122, 1.0
	v_fmac_f32_e32 v122, v123, v122
	v_div_scale_f32 v123, vcc, 1.0, v73, 1.0
	v_mul_f32_e32 v136, v123, v122
	v_fma_f32 v137, -v92, v136, v123
	v_fmac_f32_e32 v136, v137, v122
	v_fma_f32 v92, -v92, v136, v123
	v_div_fmas_f32 v92, v92, v122, v136
	v_div_fixup_f32 v123, v92, v73, 1.0
	v_div_scale_f32 v73, s[0:1], v72, v72, 1.0
	v_rcp_f32_e32 v92, v73
	s_nop 0
	v_fma_f32 v122, -v73, v92, 1.0
	v_fmac_f32_e32 v92, v122, v92
	v_div_scale_f32 v122, vcc, 1.0, v72, 1.0
	v_mul_f32_e32 v136, v122, v92
	v_fma_f32 v137, -v73, v136, v122
	v_fmac_f32_e32 v136, v137, v92
	v_fma_f32 v73, -v73, v136, v122
	v_div_fmas_f32 v73, v73, v92, v136
	v_div_fixup_f32 v122, v73, v72, 1.0
	v_pk_add_f32 v[72:73], v[122:123], -1.0 op_sel_hi:[1,0]
	v_cvt_f32_f16_e32 v92, v93
	v_pk_fma_f32 v[66:67], v[72:73], v[66:67], 1.0 op_sel_hi:[1,1,0]
	v_cvt_f32_f16_sdwa v93, v93 dst_sel:DWORD dst_unused:UNUSED_PAD src0_sel:WORD_1
	v_pk_mul_f32 v[66:67], v[66:67], v[134:135]
	v_pk_mul_f32 v[84:85], v[84:85], v[92:93]
	v_cvt_pk_f16_f32 v72, v66, v67
	v_pk_add_f32 v[66:67], v[116:117], 1.0 op_sel_hi:[1,0]
	s_nop 0
	v_div_scale_f32 v73, s[0:1], v67, v67, 1.0
	v_rcp_f32_e32 v116, v73
	s_nop 0
	v_fma_f32 v117, -v73, v116, 1.0
	v_fmac_f32_e32 v116, v117, v116
	v_div_scale_f32 v117, vcc, 1.0, v67, 1.0
	v_mul_f32_e32 v136, v117, v116
	v_fma_f32 v137, -v73, v136, v117
	v_fmac_f32_e32 v136, v137, v116
	v_fma_f32 v73, -v73, v136, v117
	v_div_fmas_f32 v73, v73, v116, v136
	v_div_fixup_f32 v67, v73, v67, 1.0
	v_div_scale_f32 v73, s[0:1], v66, v66, 1.0
	v_rcp_f32_e32 v116, v73
	s_nop 0
	v_fma_f32 v117, -v73, v116, 1.0
	v_fmac_f32_e32 v116, v117, v116
	v_div_scale_f32 v117, vcc, 1.0, v66, 1.0
	v_mul_f32_e32 v136, v117, v116
	v_fma_f32 v137, -v73, v136, v117
	v_fmac_f32_e32 v136, v137, v116
	v_fma_f32 v73, -v73, v136, v117
	v_div_fmas_f32 v73, v73, v116, v136
	v_div_fixup_f32 v66, v73, v66, 1.0
	v_pk_add_f32 v[116:117], v[66:67], -1.0 op_sel_hi:[1,0]
	s_nop 0
	v_pk_fma_f32 v[68:69], v[116:117], v[68:69], 1.0 op_sel_hi:[1,1,0]
	s_nop 0
	v_pk_mul_f32 v[68:69], v[68:69], v[92:93]
	v_lshlrev_b64 v[92:93], 12, v[106:107]
	v_cvt_pk_f16_f32 v73, v68, v69
	global_store_dwordx4 v[114:115], v[70:73], off
	v_pk_mul_f32 v[68:69], v[86:87], v[132:133]
	v_pk_mul_f32 v[86:87], v[84:85], v[84:85]
	v_pk_mul_f32 v[72:73], v[82:83], v[134:135]
	v_pk_mul_f32 v[70:71], v[88:89], v[90:91]
	v_pk_mul_f32 v[82:83], v[72:73], v[72:73]
	v_pk_fma_f32 v[86:87], v[70:71], v[70:71], v[86:87]
	v_pk_fma_f32 v[82:83], v[68:69], v[68:69], v[82:83]
	s_nop 0
	v_add_f32_e32 v82, v82, v83
	v_add_f32_e32 v82, v86, v82
	v_add_f32_e32 v82, v87, v82
	v_add_f32_e32 v82, v82, v118
	v_add_f32_e32 v82, v119, v82
	v_add_f32_e32 v82, v120, v82
	v_add_f32_e32 v82, v121, v82
	ds_bpermute_b32 v83, v206, v82
	s_waitcnt lgkmcnt(0)
;     __device__ __forceinline__ void body_a(const f32x4 (&acc)[2][2][4][2], int row0, int cb0) const {
;     ...
;                 ss += __shfl_xor(ss, 16); ss += __shfl_xor(ss, 32);
;                 const float inv = 1.0f / fmaxf(sqrtf(ss), 1e-12f);
; #pragma unroll
;                 for (int bj = 0; bj < 2; ++bj) {
;                     const int c = cb0 + 32 * bj;
;                     const f32x4 p0 = *(const f32x4*)(k_a + c), p1 = *(const f32x4*)(k_a + c + 4);
;                     f32x4 ko0, ko1, ao0, ao1, bo0, bo1;
; #pragma unroll
;                     for (int e = 0; e < 4; ++e) {
;                         ko0[e] = kv[bj][e] * (1.0f + (a[bj][e] - 1.0f) * p0[e]); ko1[e] = kv[bj][4 + e] * (1.0f + (a[bj][4 + e] - 1.0f) * p1[e]);
;                         const float n0_ = kk[bj][e] * inv, n1_ = kk[bj][4 + e] * inv;
;                         ao0[e] = -n0_; ao1[e] = -n1_; bo0[e] = n0_ * a[bj][e]; bo1[e] = n1_ * a[bj][4 + e];
;                     }
;                     *(u32x4*)(C1 + row * LDC1 + 2048 + c) = pack8(ko0, ko1);
;                     *(u32x4*)(AA + row * DM + c) = pack8(ao0, ao1);
;                     *(u32x4*)(Ab + row * DM + c) = pack8(bo0, bo1);
;                 }
	v_add_f32_e32 v82, v82, v83
	ds_bpermute_b32 v83, v207, v82
	s_waitcnt lgkmcnt(0)
	v_add_f32_e32 v82, v82, v83
	v_cmp_gt_f32_e32 vcc, s4, v82
	v_mul_f32_e32 v83, 0x4f800000, v82
	s_nop 0
	v_cndmask_b32_e32 v82, v82, v83, vcc
	v_sqrt_f32_e32 v83, v82
	s_nop 0
	v_add_u32_e32 v86, -1, v83
	v_fma_f32 v87, -v86, v83, v82
	v_cmp_ge_f32_e64 s[0:1], 0, v87
	v_add_u32_e32 v87, 1, v83
	s_nop 0
	v_cndmask_b32_e64 v86, v83, v86, s[0:1]
	v_fma_f32 v83, -v87, v83, v82
	v_cmp_lt_f32_e64 s[0:1], 0, v83
	s_nop 1
	v_cndmask_b32_e64 v83, v86, v87, s[0:1]
	v_mul_f32_e32 v86, 0x37800000, v83
	v_cndmask_b32_e32 v83, v83, v86, vcc
	v_cmp_class_f32_e32 vcc, v82, v244
	s_nop 1
	v_cndmask_b32_e32 v82, v83, v82, vcc
	v_max_f32_e32 v82, 0x2b8cbccc, v82
	v_div_scale_f32 v83, s[0:1], v82, v82, 1.0
	v_rcp_f32_e32 v86, v83
	s_nop 0
	v_fma_f32 v87, -v83, v86, 1.0
	v_fmac_f32_e32 v86, v87, v86
	v_div_scale_f32 v87, vcc, 1.0, v82, 1.0
	v_mul_f32_e32 v88, v87, v86
	v_fma_f32 v89, -v83, v88, v87
	v_fmac_f32_e32 v88, v89, v86
	v_fma_f32 v83, -v83, v88, v87
	v_div_fmas_f32 v83, v83, v86, v88
	v_div_fixup_f32 v86, v83, v82, 1.0
	v_pk_mul_f32 v[90:91], v[70:71], v[86:87] op_sel_hi:[1,0]
	v_pk_mul_f32 v[88:89], v[68:69], v[86:87] op_sel_hi:[1,0]
	v_cvt_pk_f16_f32 v69, v90, v91
	v_cvt_pk_f16_f32 v68, v88, v89
	v_xor_b32_e32 v70, 0x8000, v69
	v_xor_b32_sdwa v69, s63, v69 dst_sel:DWORD dst_unused:UNUSED_PAD src0_sel:DWORD src1_sel:WORD_1
	v_pk_mul_f32 v[72:73], v[72:73], v[86:87] op_sel_hi:[1,0]
	v_pk_mul_f32 v[84:85], v[84:85], v[86:87] op_sel_hi:[1,0]
	v_perm_b32 v69, v69, v70, s33
	v_xor_b32_e32 v70, 0x8000, v68
	v_xor_b32_sdwa v68, s63, v68 dst_sel:DWORD dst_unused:UNUSED_PAD src0_sel:DWORD src1_sel:WORD_1
	v_perm_b32 v68, v68, v70, s33
	v_pk_add_f32 v[70:71], v[72:73], 0 neg_lo:[1,1] neg_hi:[1,1]
	v_pk_add_f32 v[82:83], v[84:85], 0 neg_lo:[1,1] neg_hi:[1,1]
	v_cvt_pk_f16_f32 v70, v70, v71
	v_cvt_pk_f16_f32 v71, v82, v83
	v_lshl_add_u64 v[82:83], s[10:11], 0, v[92:93]
	v_lshl_add_u64 v[82:83], v[82:83], 0, v[152:153]
	global_store_dwordx4 v[82:83], v[68:71], off
	v_fma_mixlo_f16 v87, v124, v88, 0
	v_mul_f32_e32 v106, v78, v86
	v_pk_mov_b32 v[68:69], v[124:125], v[130:131] op_sel:[1,0]
	v_pk_mov_b32 v[70:71], v[88:89], v[90:91] op_sel:[1,0]
	v_pk_mov_b32 v[88:89], v[90:91], v[72:73] op_sel:[1,0]
	v_pk_mul_f32 v[68:69], v[68:69], v[70:71]
	v_pk_mov_b32 v[70:71], v[130:131], v[122:123] op_sel:[1,0]
	v_cvt_pk_f16_f32 v69, v68, v69
	v_pk_mul_f32 v[70:71], v[70:71], v[88:89]
	v_pack_b32_f16 v68, v87, v69
	v_cvt_pk_f16_f32 v87, v70, v71
	v_pk_mov_b32 v[70:71], v[122:123], v[66:67] op_sel:[1,0]
	v_pk_mov_b32 v[72:73], v[72:73], v[84:85] op_sel:[1,0]
	v_alignbit_b32 v69, v87, v69, 16
	v_pk_mul_f32 v[70:71], v[70:71], v[72:73]
	v_pk_add_f32 v[88:89], v[112:113], 1.0 op_sel_hi:[1,0]
	v_cvt_pk_f16_f32 v66, v70, v71
	v_lshrrev_b32_e32 v71, 16, v66
	v_alignbit_b32 v70, v66, v87, 16
	v_fma_mixhi_f16 v71, v67, v85, 0
	v_lshl_add_u64 v[66:67], s[2:3], 0, v[92:93]
	v_lshl_add_u64 v[84:85], v[66:67], 0, v[152:153]
	global_store_dwordx4 v[84:85], v[68:71], off
	global_load_dwordx4 v[66:69], v[126:127], off offset:144
	s_nop 0
	global_load_dwordx4 v[70:73], v[126:127], off offset:128
	v_div_scale_f32 v90, s[0:1], v89, v89, 1.0
	v_rcp_f32_e32 v91, v90
	v_mul_f32_e32 v87, v81, v86
	v_fma_f32 v92, -v90, v91, 1.0
	v_fmac_f32_e32 v91, v92, v91
	v_div_scale_f32 v92, vcc, 1.0, v89, 1.0
	v_mul_f32_e32 v93, v92, v91
	v_fma_f32 v107, -v90, v93, v92
	v_fmac_f32_e32 v93, v107, v91
	v_fma_f32 v90, -v90, v93, v92
	v_div_fmas_f32 v90, v90, v91, v93
	v_div_fixup_f32 v89, v90, v89, 1.0
	v_div_scale_f32 v90, s[0:1], v88, v88, 1.0
	v_rcp_f32_e32 v91, v90
	s_nop 0
	v_fma_f32 v92, -v90, v91, 1.0
	v_fmac_f32_e32 v91, v92, v91
	v_div_scale_f32 v92, vcc, 1.0, v88, 1.0
	v_mul_f32_e32 v93, v92, v91
	v_fma_f32 v107, -v90, v93, v92
	v_fmac_f32_e32 v93, v107, v91
	v_fma_f32 v90, -v90, v93, v92
	v_div_fmas_f32 v90, v90, v91, v93
	v_div_fixup_f32 v88, v90, v88, 1.0
	v_pk_add_f32 v[90:91], v[88:89], -1.0 op_sel_hi:[1,0]
	s_waitcnt vmcnt(0)
	v_pk_fma_f32 v[70:71], v[90:91], v[70:71], 1.0 op_sel_hi:[1,1,0]
	s_nop 0
	v_pk_mul_f32 v[70:71], v[70:71], v[110:111]
	v_pk_add_f32 v[90:91], v[108:109], 1.0 op_sel_hi:[1,0]
	v_cvt_pk_f16_f32 v70, v70, v71
	v_div_scale_f32 v71, s[0:1], v91, v91, 1.0
	v_rcp_f32_e32 v92, v71
	s_nop 0
	v_fma_f32 v93, -v71, v92, 1.0
	v_fmac_f32_e32 v92, v93, v92
	v_div_scale_f32 v93, vcc, 1.0, v91, 1.0
	v_mul_f32_e32 v107, v93, v92
	v_fma_f32 v108, -v71, v107, v93
	v_fmac_f32_e32 v107, v108, v92
	v_fma_f32 v71, -v71, v107, v93
	v_div_fmas_f32 v71, v71, v92, v107
	v_div_fixup_f32 v91, v71, v91, 1.0
	v_div_scale_f32 v71, s[0:1], v90, v90, 1.0
	v_rcp_f32_e32 v92, v71
	s_nop 0
	v_fma_f32 v93, -v71, v92, 1.0
	v_fmac_f32_e32 v92, v93, v92
	v_div_scale_f32 v93, vcc, 1.0, v90, 1.0
	v_mul_f32_e32 v107, v93, v92
	v_fma_f32 v108, -v71, v107, v93
	v_fmac_f32_e32 v107, v108, v92
	v_fma_f32 v71, -v71, v107, v93
	v_div_fmas_f32 v71, v71, v92, v107
	v_div_fixup_f32 v90, v71, v90, 1.0
	v_pk_add_f32 v[92:93], v[90:91], -1.0 op_sel_hi:[1,0]
	s_nop 0
	v_pk_fma_f32 v[72:73], v[92:93], v[72:73], 1.0 op_sel_hi:[1,1,0]
	s_nop 0
	v_pk_mul_f32 v[72:73], v[72:73], v[104:105]
	s_nop 0
	v_cvt_pk_f16_f32 v71, v72, v73
	v_pk_add_f32 v[72:73], v[102:103], 1.0 op_sel_hi:[1,0]
	s_nop 0
	v_div_scale_f32 v92, s[0:1], v73, v73, 1.0
	v_rcp_f32_e32 v93, v92
	s_nop 0
	v_fma_f32 v102, -v92, v93, 1.0
	v_fmac_f32_e32 v93, v102, v93
	v_div_scale_f32 v102, vcc, 1.0, v73, 1.0
	v_mul_f32_e32 v103, v102, v93
	v_fma_f32 v104, -v92, v103, v102
	v_fmac_f32_e32 v103, v104, v93
	v_fma_f32 v92, -v92, v103, v102
	v_div_fmas_f32 v92, v92, v93, v103
; __device__ __forceinline__ float sigmoidf_(float x) { return 1.0f / (1.0f + __expf(-x)); }
;     __device__ __forceinline__ void body_a(const f32x4 (&acc)[2][2][4][2], int row0, int cb0) const {
;     ...
;                     const int c = cb0 + 32 * bj;
;                     const f32x4 b0 = *(const f32x4*)(a0 + c), b1 = *(const f32x4*)(a0 + c + 4), q0 = *(const f32x4*)(k_k + c), q1 = *(const f32x4*)(k_k + c + 4);
;                     const h16x8 kh = *(const h16x8*)(C1 + row * LDC1 + 2048 + c);
; #pragma unroll
;                     for (int e = 0; e < 4; ++e) {
;                         a[bj][e] = sigmoidf_(acc[ai][bj][m][0][e] + b0[e]); a[bj][4 + e] = sigmoidf_(acc[ai][bj][m][1][e] + b1[e]);
;                         kv[bj][e] = (float)kh[e]; kv[bj][4 + e] = (float)kh[4 + e];
;                         kk[bj][e] = kv[bj][e] * q0[e]; kk[bj][4 + e] = kv[bj][4 + e] * q1[e];
;                         ss += kk[bj][e] * kk[bj][e] + kk[bj][4 + e] * kk[bj][4 + e];
;                     }
;                 }
;                 ss += __shfl_xor(ss, 16); ss += __shfl_xor(ss, 32);
;                 const float inv = 1.0f / fmaxf(sqrtf(ss), 1e-12f);
; #pragma unroll
;                 for (int bj = 0; bj < 2; ++bj) {
;                     const int c = cb0 + 32 * bj;
;                     const f32x4 p0 = *(const f32x4*)(k_a + c), p1 = *(const f32x4*)(k_a + c + 4);
;                     f32x4 ko0, ko1, ao0, ao1, bo0, bo1;
; #pragma unroll
;                     for (int e = 0; e < 4; ++e) {
;                         ko0[e] = kv[bj][e] * (1.0f + (a[bj][e] - 1.0f) * p0[e]); ko1[e] = kv[bj][4 + e] * (1.0f + (a[bj][4 + e] - 1.0f) * p1[e]);
;                         const float n0_ = kk[bj][e] * inv, n1_ = kk[bj][4 + e] * inv;
;                         ao0[e] = -n0_; ao1[e] = -n1_; bo0[e] = n0_ * a[bj][e]; bo1[e] = n1_ * a[bj][4 + e];
;                     }
;                     *(u32x4*)(C1 + row * LDC1 + 2048 + c) = pack8(ko0, ko1);
;                     *(u32x4*)(AA + row * DM + c) = pack8(ao0, ao1);
;                     *(u32x4*)(Ab + row * DM + c) = pack8(bo0, bo1);
;                 }
	v_div_fixup_f32 v93, v92, v73, 1.0
	v_div_scale_f32 v73, s[0:1], v72, v72, 1.0
	v_rcp_f32_e32 v92, v73
	s_nop 0
	v_fma_f32 v102, -v73, v92, 1.0
	v_fmac_f32_e32 v92, v102, v92
	v_div_scale_f32 v102, vcc, 1.0, v72, 1.0
	v_mul_f32_e32 v103, v102, v92
	v_fma_f32 v104, -v73, v103, v102
	v_fmac_f32_e32 v103, v104, v92
	v_fma_f32 v73, -v73, v103, v102
	v_div_fmas_f32 v73, v73, v92, v103
	v_div_fixup_f32 v92, v73, v72, 1.0
	v_pk_add_f32 v[72:73], v[92:93], -1.0 op_sel_hi:[1,0]
	s_nop 0
	v_pk_fma_f32 v[66:67], v[72:73], v[66:67], 1.0 op_sel_hi:[1,1,0]
	s_nop 0
	v_pk_mul_f32 v[66:67], v[66:67], v[100:101]
	s_nop 0
	v_cvt_pk_f16_f32 v72, v66, v67
	v_pk_add_f32 v[66:67], v[98:99], 1.0 op_sel_hi:[1,0]
	s_nop 0
	v_div_scale_f32 v73, s[0:1], v67, v67, 1.0
	v_rcp_f32_e32 v98, v73
	s_nop 0
	v_fma_f32 v99, -v73, v98, 1.0
	v_fmac_f32_e32 v98, v99, v98
	v_div_scale_f32 v99, vcc, 1.0, v67, 1.0
	v_mul_f32_e32 v100, v99, v98
	v_fma_f32 v101, -v73, v100, v99
	v_fmac_f32_e32 v100, v101, v98
	v_fma_f32 v73, -v73, v100, v99
	v_div_fmas_f32 v73, v73, v98, v100
	v_div_fixup_f32 v99, v73, v67, 1.0
	v_div_scale_f32 v67, s[0:1], v66, v66, 1.0
	v_rcp_f32_e32 v73, v67
	s_nop 0
	v_fma_f32 v98, -v67, v73, 1.0
	v_fmac_f32_e32 v73, v98, v73
	v_div_scale_f32 v98, vcc, 1.0, v66, 1.0
	v_mul_f32_e32 v100, v98, v73
	v_fma_f32 v101, -v67, v100, v98
	v_fmac_f32_e32 v100, v101, v73
	v_fma_f32 v67, -v67, v100, v98
	v_div_fmas_f32 v67, v67, v73, v100
	v_div_fixup_f32 v98, v67, v66, 1.0
	v_pk_add_f32 v[66:67], v[98:99], -1.0 op_sel_hi:[1,0]
	s_nop 0
	v_pk_fma_f32 v[66:67], v[66:67], v[68:69], 1.0 op_sel_hi:[1,1,0]
	v_cvt_f16_f32_e64 v68, -v106
	v_pk_mul_f32 v[66:67], v[66:67], v[96:97]
	s_nop 0
	v_cvt_pk_f16_f32 v73, v66, v67
	v_pk_mov_b32 v[66:67], v[78:79], v[94:95] op_sel:[1,0]
	global_store_dwordx4 v[74:75], v[70:73], off
	s_nop 1
	v_pk_mul_f32 v[70:71], v[66:67], v[86:87] op_sel_hi:[1,0]
	s_nop 0
	v_cvt_pk_f16_f32 v67, v70, v71
	v_pack_b32_f16 v66, v68, -v67
	v_pk_mov_b32 v[68:69], v[94:95], v[76:77] op_sel:[1,0]
	v_xor_b32_sdwa v67, s63, v67 dst_sel:DWORD dst_unused:UNUSED_PAD src0_sel:DWORD src1_sel:WORD_1
	v_pk_mul_f32 v[72:73], v[68:69], v[86:87] op_sel_hi:[1,0]
	s_nop 0
	v_cvt_pk_f16_f32 v68, v72, v73
	v_xor_b32_e32 v69, 0x8000, v68
	v_perm_b32 v67, v69, v67, s33
	v_xor_b32_sdwa v78, s63, v68 dst_sel:DWORD dst_unused:UNUSED_PAD src0_sel:DWORD src1_sel:WORD_1
	v_pk_mov_b32 v[68:69], v[76:77], v[80:81] op_sel:[1,0]
	v_cvt_f16_f32_e64 v76, -v87
	v_pk_mul_f32 v[74:75], v[68:69], v[86:87] op_sel_hi:[1,0]
	s_nop 0
	v_cvt_pk_f16_f32 v69, v74, v75
	v_xor_b32_e32 v68, 0x8000, v69
	v_xor_b32_sdwa v69, s63, v69 dst_sel:DWORD dst_unused:UNUSED_PAD src0_sel:DWORD src1_sel:WORD_1
	v_perm_b32 v68, v68, v78, s33
	v_perm_b32 v69, v76, v69, s33
	global_store_dwordx4 v[82:83], v[66:69], off offset:64
	s_nop 1
	v_pk_mov_b32 v[66:67], v[88:89], v[90:91] op_sel:[1,0]
	v_fma_mixlo_f16 v68, v88, v106, 0
	v_pk_mul_f32 v[66:67], v[66:67], v[70:71]
	s_nop 0
	v_cvt_pk_f16_f32 v67, v66, v67
	v_pack_b32_f16 v66, v68, v67
	v_pk_mov_b32 v[68:69], v[90:91], v[92:93] op_sel:[1,0]
	s_nop 0
	v_pk_mul_f32 v[68:69], v[68:69], v[72:73]
	s_nop 0
	v_cvt_pk_f16_f32 v70, v68, v69
	v_pk_mov_b32 v[68:69], v[92:93], v[98:99] op_sel:[1,0]
	v_alignbit_b32 v67, v70, v67, 16
	v_pk_mul_f32 v[68:69], v[68:69], v[74:75]
	s_nop 0
	v_cvt_pk_f16_f32 v69, v68, v69
	v_alignbit_b32 v68, v69, v70, 16
	v_lshrrev_b32_e32 v69, 16, v69
	v_fma_mixhi_f16 v69, v99, v87, 0
	global_store_dwordx4 v[84:85], v[66:69], off offset:64
	v_add_u32_e32 v90, 0x80, v158
	s_nop 0
	v_mad_i64_i32 v[66:67], s[0:1], v90, s5, v[160:161]
	v_lshl_add_u64 v[86:87], v[66:67], 0, s[6:7]
	global_load_dwordx4 v[78:81], v[154:155], off offset:16
	global_load_dwordx4 v[82:85], v[154:155], off
	global_load_dwordx4 v[66:69], v[156:157], off offset:16
	global_load_dwordx4 v[70:73], v[156:157], off
	v_lshl_add_u64 v[98:99], v[86:87], 0, v[152:153]
	global_load_dwordx4 v[74:77], v[98:99], off
	v_ashrrev_i32_e32 v91, 31, v90
	s_waitcnt vmcnt(4)
	v_add_f32_e32 v58, v58, v78
	v_mul_f32_e32 v58, 0xbfb8aa3b, v58
	v_exp_f32_e32 v106, v58
	s_waitcnt vmcnt(3)
	v_add_f32_e32 v58, v63, v83
	v_mul_f32_e32 v58, 0xbfb8aa3b, v58
	v_exp_f32_e32 v109, v58
	v_add_f32_e32 v58, v59, v79
	v_mul_f32_e32 v58, 0xbfb8aa3b, v58
	v_exp_f32_e32 v107, v58
	v_add_f32_e32 v58, v64, v84
	v_mul_f32_e32 v58, 0xbfb8aa3b, v58
	v_exp_f32_e32 v110, v58
	v_add_f32_e32 v58, v60, v80
	v_mul_f32_e32 v58, 0xbfb8aa3b, v58
	v_exp_f32_e32 v100, v58
	v_add_f32_e32 v58, v65, v85
	v_mul_f32_e32 v58, 0xbfb8aa3b, v58
	v_exp_f32_e32 v111, v58
	v_add_f32_e32 v58, v61, v81
	v_add_f32_e32 v62, v62, v82
	v_mul_f32_e32 v58, 0xbfb8aa3b, v58
	v_mul_f32_e32 v62, 0xbfb8aa3b, v62
	v_exp_f32_e32 v101, v58
	v_lshl_add_u64 v[58:59], v[86:87], 0, v[128:129]
	v_exp_f32_e32 v108, v62
	global_load_dwordx4 v[62:65], v[154:155], off offset:144
	global_load_dwordx4 v[78:81], v[154:155], off offset:128
	global_load_dwordx4 v[102:105], v[156:157], off offset:144
	global_load_dwordx4 v[112:115], v[156:157], off offset:128
	global_load_dwordx4 v[116:119], v[58:59], off
	v_pk_add_f32 v[110:111], v[110:111], 1.0 op_sel_hi:[1,0]
	v_pk_add_f32 v[108:109], v[108:109], 1.0 op_sel_hi:[1,0]
	s_waitcnt vmcnt(4)
	v_add_f32_e32 v50, v50, v62
	v_mul_f32_e32 v50, 0xbfb8aa3b, v50
	v_exp_f32_e32 v86, v50
	s_waitcnt vmcnt(3)
	v_add_f32_e32 v50, v55, v79
	s_waitcnt vmcnt(0)
; __device__ __forceinline__ float sigmoidf_(float x) { return 1.0f / (1.0f + __expf(-x)); }
;     __device__ __forceinline__ void body_a(const f32x4 (&acc)[2][2][4][2], int row0, int cb0) const {
;     ...
;                     const int c = cb0 + 32 * bj;
;                     const f32x4 b0 = *(const f32x4*)(a0 + c), b1 = *(const f32x4*)(a0 + c + 4), q0 = *(const f32x4*)(k_k + c), q1 = *(const f32x4*)(k_k + c + 4);
;                     const h16x8 kh = *(const h16x8*)(C1 + row * LDC1 + 2048 + c);
; #pragma unroll
;                     for (int e = 0; e < 4; ++e) {
;                         a[bj][e] = sigmoidf_(acc[ai][bj][m][0][e] + b0[e]); a[bj][4 + e] = sigmoidf_(acc[ai][bj][m][1][e] + b1[e]);
;                         kv[bj][e] = (float)kh[e]; kv[bj][4 + e] = (float)kh[4 + e];
;                         kk[bj][e] = kv[bj][e] * q0[e]; kk[bj][4 + e] = kv[bj][4 + e] * q1[e];
;                         ss += kk[bj][e] * kk[bj][e] + kk[bj][4 + e] * kk[bj][4 + e];
;                     }
;                 }
;                 ss += __shfl_xor(ss, 16); ss += __shfl_xor(ss, 32);
	v_cvt_f32_f16_e32 v84, v118
	v_cvt_f32_f16_sdwa v85, v118 dst_sel:DWORD dst_unused:UNUSED_PAD src0_sel:WORD_1
	v_cvt_f32_f16_e32 v94, v116
	v_cvt_f32_f16_sdwa v95, v116 dst_sel:DWORD dst_unused:UNUSED_PAD src0_sel:WORD_1
	v_mul_f32_e32 v50, 0xbfb8aa3b, v50
	v_exp_f32_e32 v97, v50
	v_add_f32_e32 v50, v51, v63
	v_mul_f32_e32 v50, 0xbfb8aa3b, v50
	v_pk_mul_f32 v[60:61], v[102:103], v[84:85]
	v_exp_f32_e32 v87, v50
	v_pk_mul_f32 v[62:63], v[112:113], v[94:95]
	v_pk_mul_f32 v[50:51], v[60:61], v[60:61]
	v_cvt_f32_f16_e32 v88, v117
	v_pk_fma_f32 v[102:103], v[62:63], v[62:63], v[50:51]
	v_add_f32_e32 v50, v56, v80
	v_mul_f32_e32 v50, 0xbfb8aa3b, v50
	v_exp_f32_e32 v92, v50
	v_add_f32_e32 v50, v52, v64
	v_mul_f32_e32 v50, 0xbfb8aa3b, v50
	v_exp_f32_e32 v82, v50
	v_add_f32_e32 v50, v57, v81
	v_cvt_f32_f16_e32 v80, v119
	v_cvt_f32_f16_sdwa v81, v119 dst_sel:DWORD dst_unused:UNUSED_PAD src0_sel:WORD_1
	v_cvt_f32_f16_sdwa v89, v117 dst_sel:DWORD dst_unused:UNUSED_PAD src0_sel:WORD_1
	v_mul_f32_e32 v50, 0xbfb8aa3b, v50
	v_exp_f32_e32 v93, v50
	v_add_f32_e32 v50, v53, v65
	v_add_f32_e32 v54, v54, v78
	v_mul_f32_e32 v50, 0xbfb8aa3b, v50
	v_pk_mul_f32 v[64:65], v[104:105], v[80:81]
	v_mul_f32_e32 v54, 0xbfb8aa3b, v54
	v_exp_f32_e32 v83, v50
	v_pk_mul_f32 v[78:79], v[114:115], v[88:89]
	v_pk_mul_f32 v[50:51], v[64:65], v[64:65]
	v_exp_f32_e32 v96, v54
	v_pk_fma_f32 v[104:105], v[78:79], v[78:79], v[50:51]
	global_load_dwordx4 v[50:53], v[126:127], off offset:16
	global_load_dwordx4 v[54:57], v[126:127], off
	v_cvt_f32_f16_e32 v112, v74
	v_cvt_f32_f16_sdwa v113, v74 dst_sel:DWORD dst_unused:UNUSED_PAD src0_sel:WORD_1
	v_div_scale_f32 v74, s[0:1], v109, v109, 1.0
	v_rcp_f32_e32 v114, v74
	s_nop 0
	v_fma_f32 v115, -v74, v114, 1.0
	v_fmac_f32_e32 v114, v115, v114
	v_div_scale_f32 v115, vcc, 1.0, v109, 1.0
	v_mul_f32_e32 v116, v115, v114
	v_fma_f32 v117, -v74, v116, v115
	v_fmac_f32_e32 v116, v117, v114
	v_fma_f32 v74, -v74, v116, v115
	v_div_fmas_f32 v74, v74, v114, v116
	v_div_fixup_f32 v109, v74, v109, 1.0
	v_div_scale_f32 v74, s[0:1], v108, v108, 1.0
	v_rcp_f32_e32 v114, v74
	s_nop 0
	v_fma_f32 v115, -v74, v114, 1.0
	v_fmac_f32_e32 v114, v115, v114
	v_div_scale_f32 v115, vcc, 1.0, v108, 1.0
	v_mul_f32_e32 v116, v115, v114
	v_fma_f32 v117, -v74, v116, v115
	v_fmac_f32_e32 v116, v117, v114
	v_fma_f32 v74, -v74, v116, v115
	v_div_fmas_f32 v74, v74, v114, v116
	v_div_fixup_f32 v108, v74, v108, 1.0
	v_pk_add_f32 v[114:115], v[108:109], -1.0 op_sel_hi:[1,0]
	v_cvt_f32_f16_e32 v74, v75
	v_cvt_f32_f16_sdwa v75, v75 dst_sel:DWORD dst_unused:UNUSED_PAD src0_sel:WORD_1
	s_waitcnt vmcnt(0)
	v_pk_fma_f32 v[54:55], v[114:115], v[54:55], 1.0 op_sel_hi:[1,1,0]
	s_nop 0
	v_pk_mul_f32 v[54:55], v[54:55], v[112:113]
	s_nop 0
	v_cvt_pk_f16_f32 v54, v54, v55
	v_div_scale_f32 v55, s[0:1], v111, v111, 1.0
	v_rcp_f32_e32 v114, v55
	s_nop 0
	v_fma_f32 v115, -v55, v114, 1.0
	v_fmac_f32_e32 v114, v115, v114
	v_div_scale_f32 v115, vcc, 1.0, v111, 1.0
	v_mul_f32_e32 v116, v115, v114
	v_fma_f32 v117, -v55, v116, v115
	v_fmac_f32_e32 v116, v117, v114
	v_fma_f32 v55, -v55, v116, v115
	v_div_fmas_f32 v55, v55, v114, v116
	v_div_fixup_f32 v111, v55, v111, 1.0
	v_div_scale_f32 v55, s[0:1], v110, v110, 1.0
	v_rcp_f32_e32 v114, v55
	s_nop 0
	v_fma_f32 v115, -v55, v114, 1.0
	v_fmac_f32_e32 v114, v115, v114
	v_div_scale_f32 v115, vcc, 1.0, v110, 1.0
	v_mul_f32_e32 v116, v115, v114
	v_fma_f32 v117, -v55, v116, v115
	v_fmac_f32_e32 v116, v117, v114
	v_fma_f32 v55, -v55, v116, v115
	v_div_fmas_f32 v55, v55, v114, v116
	v_div_fixup_f32 v110, v55, v110, 1.0
	v_pk_add_f32 v[114:115], v[110:111], -1.0 op_sel_hi:[1,0]
	s_nop 0
	v_pk_fma_f32 v[56:57], v[114:115], v[56:57], 1.0 op_sel_hi:[1,1,0]
	v_cvt_f32_f16_e32 v114, v76
	v_pk_mul_f32 v[56:57], v[56:57], v[74:75]
	v_cvt_f32_f16_sdwa v115, v76 dst_sel:DWORD dst_unused:UNUSED_PAD src0_sel:WORD_1
	v_cvt_pk_f16_f32 v55, v56, v57
	v_pk_add_f32 v[56:57], v[106:107], 1.0 op_sel_hi:[1,0]
	s_nop 0
	v_div_scale_f32 v76, s[0:1], v57, v57, 1.0
	v_rcp_f32_e32 v106, v76
	s_nop 0
	v_fma_f32 v107, -v76, v106, 1.0
	v_fmac_f32_e32 v106, v107, v106
	v_div_scale_f32 v107, vcc, 1.0, v57, 1.0
	v_mul_f32_e32 v116, v107, v106
	v_fma_f32 v117, -v76, v116, v107
	v_fmac_f32_e32 v116, v117, v106
	v_fma_f32 v76, -v76, v116, v107
	v_div_fmas_f32 v76, v76, v106, v116
	v_div_fixup_f32 v107, v76, v57, 1.0
	v_div_scale_f32 v57, s[0:1], v56, v56, 1.0
	v_rcp_f32_e32 v76, v57
	s_nop 0
	v_fma_f32 v106, -v57, v76, 1.0
	v_fmac_f32_e32 v76, v106, v76
	v_div_scale_f32 v106, vcc, 1.0, v56, 1.0
	v_mul_f32_e32 v116, v106, v76
	v_fma_f32 v117, -v57, v116, v106
	v_fmac_f32_e32 v116, v117, v76
	v_fma_f32 v57, -v57, v116, v106
	v_div_fmas_f32 v57, v57, v76, v116
	v_div_fixup_f32 v106, v57, v56, 1.0
	v_pk_add_f32 v[56:57], v[106:107], -1.0 op_sel_hi:[1,0]
	v_cvt_f32_f16_e32 v76, v77
	v_pk_fma_f32 v[50:51], v[56:57], v[50:51], 1.0 op_sel_hi:[1,1,0]
	v_cvt_f32_f16_sdwa v77, v77 dst_sel:DWORD dst_unused:UNUSED_PAD src0_sel:WORD_1
	v_pk_mul_f32 v[50:51], v[50:51], v[114:115]
	v_pk_mul_f32 v[68:69], v[68:69], v[76:77]
	v_cvt_pk_f16_f32 v56, v50, v51
	v_pk_add_f32 v[50:51], v[100:101], 1.0 op_sel_hi:[1,0]
	s_nop 0
	v_div_scale_f32 v57, s[0:1], v51, v51, 1.0
	v_rcp_f32_e32 v100, v57
	s_nop 0
	v_fma_f32 v101, -v57, v100, 1.0
	v_fmac_f32_e32 v100, v101, v100
	v_div_scale_f32 v101, vcc, 1.0, v51, 1.0
	v_mul_f32_e32 v116, v101, v100
	v_fma_f32 v117, -v57, v116, v101
	v_fmac_f32_e32 v116, v117, v100
	v_fma_f32 v57, -v57, v116, v101
	v_div_fmas_f32 v57, v57, v100, v116
	v_div_fixup_f32 v51, v57, v51, 1.0
	v_div_scale_f32 v57, s[0:1], v50, v50, 1.0
	v_rcp_f32_e32 v100, v57
	s_nop 0
	v_fma_f32 v101, -v57, v100, 1.0
	v_fmac_f32_e32 v100, v101, v100
	v_div_scale_f32 v101, vcc, 1.0, v50, 1.0
	v_mul_f32_e32 v116, v101, v100
	v_fma_f32 v117, -v57, v116, v101
	v_fmac_f32_e32 v116, v117, v100
	v_fma_f32 v57, -v57, v116, v101
	v_div_fmas_f32 v57, v57, v100, v116
	v_div_fixup_f32 v50, v57, v50, 1.0
	v_pk_add_f32 v[100:101], v[50:51], -1.0 op_sel_hi:[1,0]
	s_nop 0
	v_pk_fma_f32 v[52:53], v[100:101], v[52:53], 1.0 op_sel_hi:[1,1,0]
	s_nop 0
	v_pk_mul_f32 v[52:53], v[52:53], v[76:77]
	v_lshlrev_b64 v[76:77], 12, v[90:91]
	v_cvt_pk_f16_f32 v57, v52, v53
	global_store_dwordx4 v[98:99], v[54:57], off
	v_pk_mul_f32 v[52:53], v[70:71], v[112:113]
	v_pk_mul_f32 v[70:71], v[68:69], v[68:69]
	v_pk_mul_f32 v[56:57], v[66:67], v[114:115]
	v_pk_mul_f32 v[54:55], v[72:73], v[74:75]
	v_pk_mul_f32 v[66:67], v[56:57], v[56:57]
	v_pk_fma_f32 v[70:71], v[54:55], v[54:55], v[70:71]
	v_pk_fma_f32 v[66:67], v[52:53], v[52:53], v[66:67]
	s_nop 0
	v_add_f32_e32 v66, v66, v67
	v_add_f32_e32 v66, v70, v66
	v_add_f32_e32 v66, v71, v66
	v_add_f32_e32 v66, v66, v102
	v_add_f32_e32 v66, v103, v66
	v_add_f32_e32 v66, v104, v66
	v_add_f32_e32 v66, v105, v66
	ds_bpermute_b32 v67, v206, v66
	s_waitcnt lgkmcnt(0)
;     __device__ __forceinline__ void body_a(const f32x4 (&acc)[2][2][4][2], int row0, int cb0) const {
;     ...
;                 ss += __shfl_xor(ss, 16); ss += __shfl_xor(ss, 32);
;                 const float inv = 1.0f / fmaxf(sqrtf(ss), 1e-12f);
; #pragma unroll
;                 for (int bj = 0; bj < 2; ++bj) {
;                     const int c = cb0 + 32 * bj;
;                     const f32x4 p0 = *(const f32x4*)(k_a + c), p1 = *(const f32x4*)(k_a + c + 4);
;                     f32x4 ko0, ko1, ao0, ao1, bo0, bo1;
; #pragma unroll
;                     for (int e = 0; e < 4; ++e) {
;                         ko0[e] = kv[bj][e] * (1.0f + (a[bj][e] - 1.0f) * p0[e]); ko1[e] = kv[bj][4 + e] * (1.0f + (a[bj][4 + e] - 1.0f) * p1[e]);
;                         const float n0_ = kk[bj][e] * inv, n1_ = kk[bj][4 + e] * inv;
;                         ao0[e] = -n0_; ao1[e] = -n1_; bo0[e] = n0_ * a[bj][e]; bo1[e] = n1_ * a[bj][4 + e];
;                     }
;                     *(u32x4*)(C1 + row * LDC1 + 2048 + c) = pack8(ko0, ko1);
;                     *(u32x4*)(AA + row * DM + c) = pack8(ao0, ao1);
;                     *(u32x4*)(Ab + row * DM + c) = pack8(bo0, bo1);
;                 }
	v_add_f32_e32 v66, v66, v67
	ds_bpermute_b32 v67, v207, v66
	s_waitcnt lgkmcnt(0)
	v_add_f32_e32 v66, v66, v67
	v_cmp_gt_f32_e32 vcc, s4, v66
	v_mul_f32_e32 v67, 0x4f800000, v66
	s_nop 0
	v_cndmask_b32_e32 v66, v66, v67, vcc
	v_sqrt_f32_e32 v67, v66
	s_nop 0
	v_add_u32_e32 v70, -1, v67
	v_fma_f32 v71, -v70, v67, v66
	v_cmp_ge_f32_e64 s[0:1], 0, v71
	v_add_u32_e32 v71, 1, v67
	s_nop 0
	v_cndmask_b32_e64 v70, v67, v70, s[0:1]
	v_fma_f32 v67, -v71, v67, v66
	v_cmp_lt_f32_e64 s[0:1], 0, v67
	s_nop 1
	v_cndmask_b32_e64 v67, v70, v71, s[0:1]
	v_mul_f32_e32 v70, 0x37800000, v67
	v_cndmask_b32_e32 v67, v67, v70, vcc
	v_cmp_class_f32_e32 vcc, v66, v244
	s_nop 1
	v_cndmask_b32_e32 v66, v67, v66, vcc
	v_max_f32_e32 v66, 0x2b8cbccc, v66
	v_div_scale_f32 v67, s[0:1], v66, v66, 1.0
	v_rcp_f32_e32 v70, v67
	s_nop 0
	v_fma_f32 v71, -v67, v70, 1.0
	v_fmac_f32_e32 v70, v71, v70
	v_div_scale_f32 v71, vcc, 1.0, v66, 1.0
	v_mul_f32_e32 v72, v71, v70
	v_fma_f32 v73, -v67, v72, v71
	v_fmac_f32_e32 v72, v73, v70
	v_fma_f32 v67, -v67, v72, v71
	v_div_fmas_f32 v67, v67, v70, v72
	v_div_fixup_f32 v70, v67, v66, 1.0
	v_pk_mul_f32 v[74:75], v[54:55], v[70:71] op_sel_hi:[1,0]
	v_pk_mul_f32 v[72:73], v[52:53], v[70:71] op_sel_hi:[1,0]
	v_cvt_pk_f16_f32 v53, v74, v75
	v_cvt_pk_f16_f32 v52, v72, v73
	v_xor_b32_e32 v54, 0x8000, v53
	v_xor_b32_sdwa v53, s63, v53 dst_sel:DWORD dst_unused:UNUSED_PAD src0_sel:DWORD src1_sel:WORD_1
	v_pk_mul_f32 v[56:57], v[56:57], v[70:71] op_sel_hi:[1,0]
	v_pk_mul_f32 v[68:69], v[68:69], v[70:71] op_sel_hi:[1,0]
	v_perm_b32 v53, v53, v54, s33
	v_xor_b32_e32 v54, 0x8000, v52
	v_xor_b32_sdwa v52, s63, v52 dst_sel:DWORD dst_unused:UNUSED_PAD src0_sel:DWORD src1_sel:WORD_1
	v_perm_b32 v52, v52, v54, s33
	v_pk_add_f32 v[54:55], v[56:57], 0 neg_lo:[1,1] neg_hi:[1,1]
	v_pk_add_f32 v[66:67], v[68:69], 0 neg_lo:[1,1] neg_hi:[1,1]
	v_cvt_pk_f16_f32 v54, v54, v55
	v_cvt_pk_f16_f32 v55, v66, v67
	v_lshl_add_u64 v[66:67], s[10:11], 0, v[76:77]
	v_lshl_add_u64 v[66:67], v[66:67], 0, v[152:153]
	global_store_dwordx4 v[66:67], v[52:55], off
	v_fma_mixlo_f16 v71, v108, v72, 0
	v_mul_f32_e32 v90, v62, v70
	v_pk_mov_b32 v[52:53], v[108:109], v[110:111] op_sel:[1,0]
	v_pk_mov_b32 v[54:55], v[72:73], v[74:75] op_sel:[1,0]
	v_pk_mov_b32 v[72:73], v[74:75], v[56:57] op_sel:[1,0]
	v_pk_mul_f32 v[52:53], v[52:53], v[54:55]
	v_pk_mov_b32 v[54:55], v[110:111], v[106:107] op_sel:[1,0]
	v_cvt_pk_f16_f32 v53, v52, v53
	v_pk_mul_f32 v[54:55], v[54:55], v[72:73]
	v_pack_b32_f16 v52, v71, v53
	v_cvt_pk_f16_f32 v71, v54, v55
	v_pk_mov_b32 v[54:55], v[106:107], v[50:51] op_sel:[1,0]
	v_pk_mov_b32 v[56:57], v[56:57], v[68:69] op_sel:[1,0]
	v_alignbit_b32 v53, v71, v53, 16
	v_pk_mul_f32 v[54:55], v[54:55], v[56:57]
	v_pk_add_f32 v[72:73], v[96:97], 1.0 op_sel_hi:[1,0]
	v_cvt_pk_f16_f32 v50, v54, v55
	v_lshrrev_b32_e32 v55, 16, v50
	v_alignbit_b32 v54, v50, v71, 16
	v_fma_mixhi_f16 v55, v51, v69, 0
	v_lshl_add_u64 v[50:51], s[2:3], 0, v[76:77]
	v_lshl_add_u64 v[68:69], v[50:51], 0, v[152:153]
	global_store_dwordx4 v[68:69], v[52:55], off
	global_load_dwordx4 v[50:53], v[126:127], off offset:144
	s_nop 0
	global_load_dwordx4 v[54:57], v[126:127], off offset:128
	v_div_scale_f32 v74, s[0:1], v73, v73, 1.0
	v_rcp_f32_e32 v75, v74
	v_mul_f32_e32 v71, v65, v70
	v_fma_f32 v76, -v74, v75, 1.0
	v_fmac_f32_e32 v75, v76, v75
	v_div_scale_f32 v76, vcc, 1.0, v73, 1.0
	v_mul_f32_e32 v77, v76, v75
	v_fma_f32 v91, -v74, v77, v76
	v_fmac_f32_e32 v77, v91, v75
	v_fma_f32 v74, -v74, v77, v76
	v_div_fmas_f32 v74, v74, v75, v77
	v_div_fixup_f32 v73, v74, v73, 1.0
	v_div_scale_f32 v74, s[0:1], v72, v72, 1.0
	v_rcp_f32_e32 v75, v74
	s_nop 0
	v_fma_f32 v76, -v74, v75, 1.0
	v_fmac_f32_e32 v75, v76, v75
	v_div_scale_f32 v76, vcc, 1.0, v72, 1.0
	v_mul_f32_e32 v77, v76, v75
	v_fma_f32 v91, -v74, v77, v76
	v_fmac_f32_e32 v77, v91, v75
	v_fma_f32 v74, -v74, v77, v76
	v_div_fmas_f32 v74, v74, v75, v77
	v_div_fixup_f32 v72, v74, v72, 1.0
	v_pk_add_f32 v[74:75], v[72:73], -1.0 op_sel_hi:[1,0]
	s_waitcnt vmcnt(0)
	v_pk_fma_f32 v[54:55], v[74:75], v[54:55], 1.0 op_sel_hi:[1,1,0]
	s_nop 0
	v_pk_mul_f32 v[54:55], v[54:55], v[94:95]
	v_pk_add_f32 v[74:75], v[92:93], 1.0 op_sel_hi:[1,0]
	v_cvt_pk_f16_f32 v54, v54, v55
	v_div_scale_f32 v55, s[0:1], v75, v75, 1.0
	v_rcp_f32_e32 v76, v55
	s_nop 0
	v_fma_f32 v77, -v55, v76, 1.0
	v_fmac_f32_e32 v76, v77, v76
	v_div_scale_f32 v77, vcc, 1.0, v75, 1.0
	v_mul_f32_e32 v91, v77, v76
	v_fma_f32 v92, -v55, v91, v77
	v_fmac_f32_e32 v91, v92, v76
	v_fma_f32 v55, -v55, v91, v77
	v_div_fmas_f32 v55, v55, v76, v91
	v_div_fixup_f32 v75, v55, v75, 1.0
	v_div_scale_f32 v55, s[0:1], v74, v74, 1.0
	v_rcp_f32_e32 v76, v55
	s_nop 0
	v_fma_f32 v77, -v55, v76, 1.0
	v_fmac_f32_e32 v76, v77, v76
	v_div_scale_f32 v77, vcc, 1.0, v74, 1.0
	v_mul_f32_e32 v91, v77, v76
	v_fma_f32 v92, -v55, v91, v77
	v_fmac_f32_e32 v91, v92, v76
	v_fma_f32 v55, -v55, v91, v77
	v_div_fmas_f32 v55, v55, v76, v91
	v_div_fixup_f32 v74, v55, v74, 1.0
	v_pk_add_f32 v[76:77], v[74:75], -1.0 op_sel_hi:[1,0]
	s_nop 0
	v_pk_fma_f32 v[56:57], v[76:77], v[56:57], 1.0 op_sel_hi:[1,1,0]
	s_nop 0
	v_pk_mul_f32 v[56:57], v[56:57], v[88:89]
	s_nop 0
	v_cvt_pk_f16_f32 v55, v56, v57
	v_pk_add_f32 v[56:57], v[86:87], 1.0 op_sel_hi:[1,0]
	s_nop 0
	v_div_scale_f32 v76, s[0:1], v57, v57, 1.0
	v_rcp_f32_e32 v77, v76
	s_nop 0
	v_fma_f32 v86, -v76, v77, 1.0
	v_fmac_f32_e32 v77, v86, v77
	v_div_scale_f32 v86, vcc, 1.0, v57, 1.0
	v_mul_f32_e32 v87, v86, v77
	v_fma_f32 v88, -v76, v87, v86
	v_fmac_f32_e32 v87, v88, v77
	v_fma_f32 v76, -v76, v87, v86
	v_div_fmas_f32 v76, v76, v77, v87
	v_div_fixup_f32 v77, v76, v57, 1.0
; __device__ __forceinline__ float sigmoidf_(float x) { return 1.0f / (1.0f + __expf(-x)); }
;     __device__ __forceinline__ void body_a(const f32x4 (&acc)[2][2][4][2], int row0, int cb0) const {
;     ...
;                     const int c = cb0 + 32 * bj;
;                     const f32x4 b0 = *(const f32x4*)(a0 + c), b1 = *(const f32x4*)(a0 + c + 4), q0 = *(const f32x4*)(k_k + c), q1 = *(const f32x4*)(k_k + c + 4);
;                     const h16x8 kh = *(const h16x8*)(C1 + row * LDC1 + 2048 + c);
; #pragma unroll
;                     for (int e = 0; e < 4; ++e) {
;                         a[bj][e] = sigmoidf_(acc[ai][bj][m][0][e] + b0[e]); a[bj][4 + e] = sigmoidf_(acc[ai][bj][m][1][e] + b1[e]);
;                         kv[bj][e] = (float)kh[e]; kv[bj][4 + e] = (float)kh[4 + e];
;                         kk[bj][e] = kv[bj][e] * q0[e]; kk[bj][4 + e] = kv[bj][4 + e] * q1[e];
;                         ss += kk[bj][e] * kk[bj][e] + kk[bj][4 + e] * kk[bj][4 + e];
;                     }
;                 }
;                 ss += __shfl_xor(ss, 16); ss += __shfl_xor(ss, 32);
;                 const float inv = 1.0f / fmaxf(sqrtf(ss), 1e-12f);
; #pragma unroll
;                 for (int bj = 0; bj < 2; ++bj) {
;                     const int c = cb0 + 32 * bj;
;                     const f32x4 p0 = *(const f32x4*)(k_a + c), p1 = *(const f32x4*)(k_a + c + 4);
;                     f32x4 ko0, ko1, ao0, ao1, bo0, bo1;
; #pragma unroll
;                     for (int e = 0; e < 4; ++e) {
;                         ko0[e] = kv[bj][e] * (1.0f + (a[bj][e] - 1.0f) * p0[e]); ko1[e] = kv[bj][4 + e] * (1.0f + (a[bj][4 + e] - 1.0f) * p1[e]);
;                         const float n0_ = kk[bj][e] * inv, n1_ = kk[bj][4 + e] * inv;
;                         ao0[e] = -n0_; ao1[e] = -n1_; bo0[e] = n0_ * a[bj][e]; bo1[e] = n1_ * a[bj][4 + e];
;                     }
;                     *(u32x4*)(C1 + row * LDC1 + 2048 + c) = pack8(ko0, ko1);
;                     *(u32x4*)(AA + row * DM + c) = pack8(ao0, ao1);
;                     *(u32x4*)(Ab + row * DM + c) = pack8(bo0, bo1);
;                 }
	v_div_scale_f32 v57, s[0:1], v56, v56, 1.0
	v_rcp_f32_e32 v76, v57
	s_nop 0
	v_fma_f32 v86, -v57, v76, 1.0
	v_fmac_f32_e32 v76, v86, v76
	v_div_scale_f32 v86, vcc, 1.0, v56, 1.0
	v_mul_f32_e32 v87, v86, v76
	v_fma_f32 v88, -v57, v87, v86
	v_fmac_f32_e32 v87, v88, v76
	v_fma_f32 v57, -v57, v87, v86
	v_div_fmas_f32 v57, v57, v76, v87
	v_div_fixup_f32 v76, v57, v56, 1.0
	v_pk_add_f32 v[56:57], v[76:77], -1.0 op_sel_hi:[1,0]
	s_nop 0
	v_pk_fma_f32 v[50:51], v[56:57], v[50:51], 1.0 op_sel_hi:[1,1,0]
	s_nop 0
	v_pk_mul_f32 v[50:51], v[50:51], v[84:85]
	s_nop 0
	v_cvt_pk_f16_f32 v56, v50, v51
	v_pk_add_f32 v[50:51], v[82:83], 1.0 op_sel_hi:[1,0]
	s_nop 0
	v_div_scale_f32 v57, s[0:1], v51, v51, 1.0
	v_rcp_f32_e32 v82, v57
	s_nop 0
	v_fma_f32 v83, -v57, v82, 1.0
	v_fmac_f32_e32 v82, v83, v82
	v_div_scale_f32 v83, vcc, 1.0, v51, 1.0
	v_mul_f32_e32 v84, v83, v82
	v_fma_f32 v85, -v57, v84, v83
	v_fmac_f32_e32 v84, v85, v82
	v_fma_f32 v57, -v57, v84, v83
	v_div_fmas_f32 v57, v57, v82, v84
	v_div_fixup_f32 v83, v57, v51, 1.0
	v_div_scale_f32 v51, s[0:1], v50, v50, 1.0
	v_rcp_f32_e32 v57, v51
	s_nop 0
	v_fma_f32 v82, -v51, v57, 1.0
	v_fmac_f32_e32 v57, v82, v57
	v_div_scale_f32 v82, vcc, 1.0, v50, 1.0
	v_mul_f32_e32 v84, v82, v57
	v_fma_f32 v85, -v51, v84, v82
	v_fmac_f32_e32 v84, v85, v57
	v_fma_f32 v51, -v51, v84, v82
	v_div_fmas_f32 v51, v51, v57, v84
	v_div_fixup_f32 v82, v51, v50, 1.0
	v_pk_add_f32 v[50:51], v[82:83], -1.0 op_sel_hi:[1,0]
	s_nop 0
	v_pk_fma_f32 v[50:51], v[50:51], v[52:53], 1.0 op_sel_hi:[1,1,0]
	v_cvt_f16_f32_e64 v52, -v90
	v_pk_mul_f32 v[50:51], v[50:51], v[80:81]
	s_nop 0
	v_cvt_pk_f16_f32 v57, v50, v51
	v_pk_mov_b32 v[50:51], v[62:63], v[78:79] op_sel:[1,0]
	global_store_dwordx4 v[58:59], v[54:57], off
	s_nop 1
	v_pk_mul_f32 v[54:55], v[50:51], v[70:71] op_sel_hi:[1,0]
	s_nop 0
	v_cvt_pk_f16_f32 v51, v54, v55
	v_pack_b32_f16 v50, v52, -v51
	v_pk_mov_b32 v[52:53], v[78:79], v[60:61] op_sel:[1,0]
	v_xor_b32_sdwa v51, s63, v51 dst_sel:DWORD dst_unused:UNUSED_PAD src0_sel:DWORD src1_sel:WORD_1
	v_pk_mul_f32 v[56:57], v[52:53], v[70:71] op_sel_hi:[1,0]
	s_nop 0
	v_cvt_pk_f16_f32 v52, v56, v57
	v_xor_b32_e32 v53, 0x8000, v52
	v_perm_b32 v51, v53, v51, s33
	v_xor_b32_sdwa v62, s63, v52 dst_sel:DWORD dst_unused:UNUSED_PAD src0_sel:DWORD src1_sel:WORD_1
	v_pk_mov_b32 v[52:53], v[60:61], v[64:65] op_sel:[1,0]
	v_cvt_f16_f32_e64 v60, -v71
	v_pk_mul_f32 v[58:59], v[52:53], v[70:71] op_sel_hi:[1,0]
	s_nop 0
	v_cvt_pk_f16_f32 v53, v58, v59
	v_xor_b32_e32 v52, 0x8000, v53
	v_xor_b32_sdwa v53, s63, v53 dst_sel:DWORD dst_unused:UNUSED_PAD src0_sel:DWORD src1_sel:WORD_1
	v_perm_b32 v52, v52, v62, s33
	v_perm_b32 v53, v60, v53, s33
	global_store_dwordx4 v[66:67], v[50:53], off offset:64
	s_nop 1
	v_pk_mov_b32 v[50:51], v[72:73], v[74:75] op_sel:[1,0]
	v_fma_mixlo_f16 v52, v72, v90, 0
	v_pk_mul_f32 v[50:51], v[50:51], v[54:55]
	s_nop 0
	v_cvt_pk_f16_f32 v51, v50, v51
	v_pack_b32_f16 v50, v52, v51
	v_pk_mov_b32 v[52:53], v[74:75], v[76:77] op_sel:[1,0]
	s_nop 0
	v_pk_mul_f32 v[52:53], v[52:53], v[56:57]
	s_nop 0
	v_cvt_pk_f16_f32 v54, v52, v53
	v_pk_mov_b32 v[52:53], v[76:77], v[82:83] op_sel:[1,0]
	v_alignbit_b32 v51, v54, v51, 16
	v_pk_mul_f32 v[52:53], v[52:53], v[58:59]
	s_nop 0
	v_cvt_pk_f16_f32 v53, v52, v53
	v_alignbit_b32 v52, v53, v54, 16
	v_lshrrev_b32_e32 v53, 16, v53
	v_fma_mixhi_f16 v53, v83, v71, 0
	global_store_dwordx4 v[68:69], v[50:53], off offset:64
	v_add_u32_e32 v74, 0x90, v158
	s_nop 0
	v_mad_i64_i32 v[50:51], s[0:1], v74, s5, v[160:161]
	v_lshl_add_u64 v[70:71], v[50:51], 0, s[6:7]
	global_load_dwordx4 v[62:65], v[154:155], off offset:16
	global_load_dwordx4 v[66:69], v[154:155], off
	global_load_dwordx4 v[50:53], v[156:157], off offset:16
	global_load_dwordx4 v[54:57], v[156:157], off
	v_lshl_add_u64 v[82:83], v[70:71], 0, v[152:153]
	global_load_dwordx4 v[58:61], v[82:83], off
	v_ashrrev_i32_e32 v75, 31, v74
	s_waitcnt vmcnt(4)
	v_add_f32_e32 v42, v42, v62
	v_mul_f32_e32 v42, 0xbfb8aa3b, v42
	v_exp_f32_e32 v90, v42
	s_waitcnt vmcnt(3)
	v_add_f32_e32 v42, v47, v67
	v_mul_f32_e32 v42, 0xbfb8aa3b, v42
	v_exp_f32_e32 v93, v42
	v_add_f32_e32 v42, v43, v63
	v_mul_f32_e32 v42, 0xbfb8aa3b, v42
	v_exp_f32_e32 v91, v42
	v_add_f32_e32 v42, v48, v68
	v_mul_f32_e32 v42, 0xbfb8aa3b, v42
	v_exp_f32_e32 v94, v42
	v_add_f32_e32 v42, v44, v64
	v_mul_f32_e32 v42, 0xbfb8aa3b, v42
	v_exp_f32_e32 v84, v42
	v_add_f32_e32 v42, v49, v69
	v_mul_f32_e32 v42, 0xbfb8aa3b, v42
	v_exp_f32_e32 v95, v42
	v_add_f32_e32 v42, v45, v65
	v_add_f32_e32 v46, v46, v66
	v_mul_f32_e32 v42, 0xbfb8aa3b, v42
	v_mul_f32_e32 v46, 0xbfb8aa3b, v46
	v_exp_f32_e32 v85, v42
	v_lshl_add_u64 v[42:43], v[70:71], 0, v[128:129]
	v_exp_f32_e32 v92, v46
	global_load_dwordx4 v[46:49], v[154:155], off offset:144
	global_load_dwordx4 v[62:65], v[154:155], off offset:128
	global_load_dwordx4 v[86:89], v[156:157], off offset:144
	global_load_dwordx4 v[96:99], v[156:157], off offset:128
	global_load_dwordx4 v[100:103], v[42:43], off
	v_pk_add_f32 v[94:95], v[94:95], 1.0 op_sel_hi:[1,0]
	v_pk_add_f32 v[92:93], v[92:93], 1.0 op_sel_hi:[1,0]
	s_waitcnt vmcnt(4)
	v_add_f32_e32 v34, v34, v46
	v_mul_f32_e32 v34, 0xbfb8aa3b, v34
	v_exp_f32_e32 v70, v34
	s_waitcnt vmcnt(3)
	v_add_f32_e32 v34, v39, v63
	s_waitcnt vmcnt(0)
; __device__ __forceinline__ float sigmoidf_(float x) { return 1.0f / (1.0f + __expf(-x)); }
;     __device__ __forceinline__ void body_a(const f32x4 (&acc)[2][2][4][2], int row0, int cb0) const {
;     ...
;                     const int c = cb0 + 32 * bj;
;                     const f32x4 b0 = *(const f32x4*)(a0 + c), b1 = *(const f32x4*)(a0 + c + 4), q0 = *(const f32x4*)(k_k + c), q1 = *(const f32x4*)(k_k + c + 4);
;                     const h16x8 kh = *(const h16x8*)(C1 + row * LDC1 + 2048 + c);
; #pragma unroll
;                     for (int e = 0; e < 4; ++e) {
;                         a[bj][e] = sigmoidf_(acc[ai][bj][m][0][e] + b0[e]); a[bj][4 + e] = sigmoidf_(acc[ai][bj][m][1][e] + b1[e]);
;                         kv[bj][e] = (float)kh[e]; kv[bj][4 + e] = (float)kh[4 + e];
;                         kk[bj][e] = kv[bj][e] * q0[e]; kk[bj][4 + e] = kv[bj][4 + e] * q1[e];
;                         ss += kk[bj][e] * kk[bj][e] + kk[bj][4 + e] * kk[bj][4 + e];
;                     }
;                 }
;                 ss += __shfl_xor(ss, 16); ss += __shfl_xor(ss, 32);
	v_cvt_f32_f16_e32 v68, v102
	v_cvt_f32_f16_sdwa v69, v102 dst_sel:DWORD dst_unused:UNUSED_PAD src0_sel:WORD_1
	v_cvt_f32_f16_e32 v78, v100
	v_cvt_f32_f16_sdwa v79, v100 dst_sel:DWORD dst_unused:UNUSED_PAD src0_sel:WORD_1
	v_mul_f32_e32 v34, 0xbfb8aa3b, v34
	v_exp_f32_e32 v81, v34
	v_add_f32_e32 v34, v35, v47
	v_mul_f32_e32 v34, 0xbfb8aa3b, v34
	v_pk_mul_f32 v[44:45], v[86:87], v[68:69]
	v_exp_f32_e32 v71, v34
	v_pk_mul_f32 v[46:47], v[96:97], v[78:79]
	v_pk_mul_f32 v[34:35], v[44:45], v[44:45]
	v_cvt_f32_f16_e32 v72, v101
	v_pk_fma_f32 v[86:87], v[46:47], v[46:47], v[34:35]
	v_add_f32_e32 v34, v40, v64
	v_mul_f32_e32 v34, 0xbfb8aa3b, v34
	v_exp_f32_e32 v76, v34
	v_add_f32_e32 v34, v36, v48
	v_mul_f32_e32 v34, 0xbfb8aa3b, v34
	v_exp_f32_e32 v66, v34
	v_add_f32_e32 v34, v41, v65
	v_cvt_f32_f16_e32 v64, v103
	v_cvt_f32_f16_sdwa v65, v103 dst_sel:DWORD dst_unused:UNUSED_PAD src0_sel:WORD_1
	v_cvt_f32_f16_sdwa v73, v101 dst_sel:DWORD dst_unused:UNUSED_PAD src0_sel:WORD_1
	v_mul_f32_e32 v34, 0xbfb8aa3b, v34
	v_exp_f32_e32 v77, v34
	v_add_f32_e32 v34, v37, v49
	v_add_f32_e32 v38, v38, v62
	v_mul_f32_e32 v34, 0xbfb8aa3b, v34
	v_pk_mul_f32 v[48:49], v[88:89], v[64:65]
	v_mul_f32_e32 v38, 0xbfb8aa3b, v38
	v_exp_f32_e32 v67, v34
	v_pk_mul_f32 v[62:63], v[98:99], v[72:73]
	v_pk_mul_f32 v[34:35], v[48:49], v[48:49]
	v_exp_f32_e32 v80, v38
	v_pk_fma_f32 v[88:89], v[62:63], v[62:63], v[34:35]
	global_load_dwordx4 v[34:37], v[126:127], off offset:16
	global_load_dwordx4 v[38:41], v[126:127], off
	v_cvt_f32_f16_e32 v96, v58
	v_cvt_f32_f16_sdwa v97, v58 dst_sel:DWORD dst_unused:UNUSED_PAD src0_sel:WORD_1
	v_div_scale_f32 v58, s[0:1], v93, v93, 1.0
	v_rcp_f32_e32 v98, v58
	s_nop 0
	v_fma_f32 v99, -v58, v98, 1.0
	v_fmac_f32_e32 v98, v99, v98
	v_div_scale_f32 v99, vcc, 1.0, v93, 1.0
	v_mul_f32_e32 v100, v99, v98
	v_fma_f32 v101, -v58, v100, v99
	v_fmac_f32_e32 v100, v101, v98
	v_fma_f32 v58, -v58, v100, v99
	v_div_fmas_f32 v58, v58, v98, v100
	v_div_fixup_f32 v93, v58, v93, 1.0
	v_div_scale_f32 v58, s[0:1], v92, v92, 1.0
	v_rcp_f32_e32 v98, v58
	s_nop 0
	v_fma_f32 v99, -v58, v98, 1.0
	v_fmac_f32_e32 v98, v99, v98
	v_div_scale_f32 v99, vcc, 1.0, v92, 1.0
	v_mul_f32_e32 v100, v99, v98
	v_fma_f32 v101, -v58, v100, v99
	v_fmac_f32_e32 v100, v101, v98
	v_fma_f32 v58, -v58, v100, v99
	v_div_fmas_f32 v58, v58, v98, v100
	v_div_fixup_f32 v92, v58, v92, 1.0
	v_pk_add_f32 v[98:99], v[92:93], -1.0 op_sel_hi:[1,0]
	v_cvt_f32_f16_e32 v58, v59
	v_cvt_f32_f16_sdwa v59, v59 dst_sel:DWORD dst_unused:UNUSED_PAD src0_sel:WORD_1
	s_waitcnt vmcnt(0)
	v_pk_fma_f32 v[38:39], v[98:99], v[38:39], 1.0 op_sel_hi:[1,1,0]
	s_nop 0
	v_pk_mul_f32 v[38:39], v[38:39], v[96:97]
	s_nop 0
	v_cvt_pk_f16_f32 v38, v38, v39
	v_div_scale_f32 v39, s[0:1], v95, v95, 1.0
	v_rcp_f32_e32 v98, v39
	s_nop 0
	v_fma_f32 v99, -v39, v98, 1.0
	v_fmac_f32_e32 v98, v99, v98
	v_div_scale_f32 v99, vcc, 1.0, v95, 1.0
	v_mul_f32_e32 v100, v99, v98
	v_fma_f32 v101, -v39, v100, v99
	v_fmac_f32_e32 v100, v101, v98
	v_fma_f32 v39, -v39, v100, v99
	v_div_fmas_f32 v39, v39, v98, v100
	v_div_fixup_f32 v95, v39, v95, 1.0
	v_div_scale_f32 v39, s[0:1], v94, v94, 1.0
	v_rcp_f32_e32 v98, v39
	s_nop 0
	v_fma_f32 v99, -v39, v98, 1.0
	v_fmac_f32_e32 v98, v99, v98
	v_div_scale_f32 v99, vcc, 1.0, v94, 1.0
	v_mul_f32_e32 v100, v99, v98
	v_fma_f32 v101, -v39, v100, v99
	v_fmac_f32_e32 v100, v101, v98
	v_fma_f32 v39, -v39, v100, v99
	v_div_fmas_f32 v39, v39, v98, v100
	v_div_fixup_f32 v94, v39, v94, 1.0
	v_pk_add_f32 v[98:99], v[94:95], -1.0 op_sel_hi:[1,0]
	s_nop 0
	v_pk_fma_f32 v[40:41], v[98:99], v[40:41], 1.0 op_sel_hi:[1,1,0]
	v_cvt_f32_f16_e32 v98, v60
	v_pk_mul_f32 v[40:41], v[40:41], v[58:59]
	v_cvt_f32_f16_sdwa v99, v60 dst_sel:DWORD dst_unused:UNUSED_PAD src0_sel:WORD_1
	v_cvt_pk_f16_f32 v39, v40, v41
	v_pk_add_f32 v[40:41], v[90:91], 1.0 op_sel_hi:[1,0]
	s_nop 0
	v_div_scale_f32 v60, s[0:1], v41, v41, 1.0
	v_rcp_f32_e32 v90, v60
	s_nop 0
	v_fma_f32 v91, -v60, v90, 1.0
	v_fmac_f32_e32 v90, v91, v90
	v_div_scale_f32 v91, vcc, 1.0, v41, 1.0
	v_mul_f32_e32 v100, v91, v90
	v_fma_f32 v101, -v60, v100, v91
	v_fmac_f32_e32 v100, v101, v90
	v_fma_f32 v60, -v60, v100, v91
	v_div_fmas_f32 v60, v60, v90, v100
	v_div_fixup_f32 v91, v60, v41, 1.0
	v_div_scale_f32 v41, s[0:1], v40, v40, 1.0
	v_rcp_f32_e32 v60, v41
	s_nop 0
	v_fma_f32 v90, -v41, v60, 1.0
	v_fmac_f32_e32 v60, v90, v60
	v_div_scale_f32 v90, vcc, 1.0, v40, 1.0
	v_mul_f32_e32 v100, v90, v60
	v_fma_f32 v101, -v41, v100, v90
	v_fmac_f32_e32 v100, v101, v60
	v_fma_f32 v41, -v41, v100, v90
	v_div_fmas_f32 v41, v41, v60, v100
	v_div_fixup_f32 v90, v41, v40, 1.0
	v_pk_add_f32 v[40:41], v[90:91], -1.0 op_sel_hi:[1,0]
	v_cvt_f32_f16_e32 v60, v61
	v_pk_fma_f32 v[34:35], v[40:41], v[34:35], 1.0 op_sel_hi:[1,1,0]
	v_cvt_f32_f16_sdwa v61, v61 dst_sel:DWORD dst_unused:UNUSED_PAD src0_sel:WORD_1
	v_pk_mul_f32 v[34:35], v[34:35], v[98:99]
	v_pk_mul_f32 v[52:53], v[52:53], v[60:61]
	v_cvt_pk_f16_f32 v40, v34, v35
	v_pk_add_f32 v[34:35], v[84:85], 1.0 op_sel_hi:[1,0]
	s_nop 0
	v_div_scale_f32 v41, s[0:1], v35, v35, 1.0
	v_rcp_f32_e32 v84, v41
	s_nop 0
	v_fma_f32 v85, -v41, v84, 1.0
	v_fmac_f32_e32 v84, v85, v84
	v_div_scale_f32 v85, vcc, 1.0, v35, 1.0
	v_mul_f32_e32 v100, v85, v84
	v_fma_f32 v101, -v41, v100, v85
	v_fmac_f32_e32 v100, v101, v84
	v_fma_f32 v41, -v41, v100, v85
	v_div_fmas_f32 v41, v41, v84, v100
	v_div_fixup_f32 v35, v41, v35, 1.0
	v_div_scale_f32 v41, s[0:1], v34, v34, 1.0
	v_rcp_f32_e32 v84, v41
	s_nop 0
	v_fma_f32 v85, -v41, v84, 1.0
	v_fmac_f32_e32 v84, v85, v84
	v_div_scale_f32 v85, vcc, 1.0, v34, 1.0
	v_mul_f32_e32 v100, v85, v84
	v_fma_f32 v101, -v41, v100, v85
	v_fmac_f32_e32 v100, v101, v84
	v_fma_f32 v41, -v41, v100, v85
	v_div_fmas_f32 v41, v41, v84, v100
	v_div_fixup_f32 v34, v41, v34, 1.0
	v_pk_add_f32 v[84:85], v[34:35], -1.0 op_sel_hi:[1,0]
	s_nop 0
	v_pk_fma_f32 v[36:37], v[84:85], v[36:37], 1.0 op_sel_hi:[1,1,0]
	s_nop 0
	v_pk_mul_f32 v[36:37], v[36:37], v[60:61]
	v_lshlrev_b64 v[60:61], 12, v[74:75]
	v_cvt_pk_f16_f32 v41, v36, v37
	global_store_dwordx4 v[82:83], v[38:41], off
	v_pk_mul_f32 v[36:37], v[54:55], v[96:97]
	v_pk_mul_f32 v[54:55], v[52:53], v[52:53]
	v_pk_mul_f32 v[40:41], v[50:51], v[98:99]
	v_pk_mul_f32 v[38:39], v[56:57], v[58:59]
	v_pk_mul_f32 v[50:51], v[40:41], v[40:41]
	v_pk_fma_f32 v[54:55], v[38:39], v[38:39], v[54:55]
	v_pk_fma_f32 v[50:51], v[36:37], v[36:37], v[50:51]
	s_nop 0
	v_add_f32_e32 v50, v50, v51
	v_add_f32_e32 v50, v54, v50
	v_add_f32_e32 v50, v55, v50
	v_add_f32_e32 v50, v50, v86
	v_add_f32_e32 v50, v87, v50
	v_add_f32_e32 v50, v88, v50
	v_add_f32_e32 v50, v89, v50
	ds_bpermute_b32 v51, v206, v50
	s_waitcnt lgkmcnt(0)
;     __device__ __forceinline__ void body_a(const f32x4 (&acc)[2][2][4][2], int row0, int cb0) const {
;     ...
;                 ss += __shfl_xor(ss, 16); ss += __shfl_xor(ss, 32);
;                 const float inv = 1.0f / fmaxf(sqrtf(ss), 1e-12f);
; #pragma unroll
;                 for (int bj = 0; bj < 2; ++bj) {
;                     const int c = cb0 + 32 * bj;
;                     const f32x4 p0 = *(const f32x4*)(k_a + c), p1 = *(const f32x4*)(k_a + c + 4);
;                     f32x4 ko0, ko1, ao0, ao1, bo0, bo1;
; #pragma unroll
;                     for (int e = 0; e < 4; ++e) {
;                         ko0[e] = kv[bj][e] * (1.0f + (a[bj][e] - 1.0f) * p0[e]); ko1[e] = kv[bj][4 + e] * (1.0f + (a[bj][4 + e] - 1.0f) * p1[e]);
;                         const float n0_ = kk[bj][e] * inv, n1_ = kk[bj][4 + e] * inv;
;                         ao0[e] = -n0_; ao1[e] = -n1_; bo0[e] = n0_ * a[bj][e]; bo1[e] = n1_ * a[bj][4 + e];
;                     }
;                     *(u32x4*)(C1 + row * LDC1 + 2048 + c) = pack8(ko0, ko1);
;                     *(u32x4*)(AA + row * DM + c) = pack8(ao0, ao1);
;                     *(u32x4*)(Ab + row * DM + c) = pack8(bo0, bo1);
;                 }
	v_add_f32_e32 v50, v50, v51
	ds_bpermute_b32 v51, v207, v50
	s_waitcnt lgkmcnt(0)
	v_add_f32_e32 v50, v50, v51
	v_cmp_gt_f32_e32 vcc, s4, v50
	v_mul_f32_e32 v51, 0x4f800000, v50
	s_nop 0
	v_cndmask_b32_e32 v50, v50, v51, vcc
	v_sqrt_f32_e32 v51, v50
	s_nop 0
	v_add_u32_e32 v54, -1, v51
	v_fma_f32 v55, -v54, v51, v50
	v_cmp_ge_f32_e64 s[0:1], 0, v55
	v_add_u32_e32 v55, 1, v51
	s_nop 0
	v_cndmask_b32_e64 v54, v51, v54, s[0:1]
	v_fma_f32 v51, -v55, v51, v50
	v_cmp_lt_f32_e64 s[0:1], 0, v51
	s_nop 1
	v_cndmask_b32_e64 v51, v54, v55, s[0:1]
	v_mul_f32_e32 v54, 0x37800000, v51
	v_cndmask_b32_e32 v51, v51, v54, vcc
	v_cmp_class_f32_e32 vcc, v50, v244
	s_nop 1
	v_cndmask_b32_e32 v50, v51, v50, vcc
	v_max_f32_e32 v50, 0x2b8cbccc, v50
	v_div_scale_f32 v51, s[0:1], v50, v50, 1.0
	v_rcp_f32_e32 v54, v51
	s_nop 0
	v_fma_f32 v55, -v51, v54, 1.0
	v_fmac_f32_e32 v54, v55, v54
	v_div_scale_f32 v55, vcc, 1.0, v50, 1.0
	v_mul_f32_e32 v56, v55, v54
	v_fma_f32 v57, -v51, v56, v55
	v_fmac_f32_e32 v56, v57, v54
	v_fma_f32 v51, -v51, v56, v55
	v_div_fmas_f32 v51, v51, v54, v56
	v_div_fixup_f32 v54, v51, v50, 1.0
	v_pk_mul_f32 v[58:59], v[38:39], v[54:55] op_sel_hi:[1,0]
	v_pk_mul_f32 v[56:57], v[36:37], v[54:55] op_sel_hi:[1,0]
	v_cvt_pk_f16_f32 v37, v58, v59
	v_cvt_pk_f16_f32 v36, v56, v57
	v_xor_b32_e32 v38, 0x8000, v37
	v_xor_b32_sdwa v37, s63, v37 dst_sel:DWORD dst_unused:UNUSED_PAD src0_sel:DWORD src1_sel:WORD_1
	v_pk_mul_f32 v[40:41], v[40:41], v[54:55] op_sel_hi:[1,0]
	v_pk_mul_f32 v[52:53], v[52:53], v[54:55] op_sel_hi:[1,0]
	v_perm_b32 v37, v37, v38, s33
	v_xor_b32_e32 v38, 0x8000, v36
	v_xor_b32_sdwa v36, s63, v36 dst_sel:DWORD dst_unused:UNUSED_PAD src0_sel:DWORD src1_sel:WORD_1
	v_perm_b32 v36, v36, v38, s33
	v_pk_add_f32 v[38:39], v[40:41], 0 neg_lo:[1,1] neg_hi:[1,1]
	v_pk_add_f32 v[50:51], v[52:53], 0 neg_lo:[1,1] neg_hi:[1,1]
	v_cvt_pk_f16_f32 v38, v38, v39
	v_cvt_pk_f16_f32 v39, v50, v51
	v_lshl_add_u64 v[50:51], s[10:11], 0, v[60:61]
	v_lshl_add_u64 v[50:51], v[50:51], 0, v[152:153]
	global_store_dwordx4 v[50:51], v[36:39], off
	v_fma_mixlo_f16 v55, v92, v56, 0
	v_mul_f32_e32 v74, v46, v54
	v_pk_mov_b32 v[36:37], v[92:93], v[94:95] op_sel:[1,0]
	v_pk_mov_b32 v[38:39], v[56:57], v[58:59] op_sel:[1,0]
	v_pk_mov_b32 v[56:57], v[58:59], v[40:41] op_sel:[1,0]
	v_pk_mul_f32 v[36:37], v[36:37], v[38:39]
	v_pk_mov_b32 v[38:39], v[94:95], v[90:91] op_sel:[1,0]
	v_cvt_pk_f16_f32 v37, v36, v37
	v_pk_mul_f32 v[38:39], v[38:39], v[56:57]
	v_pack_b32_f16 v36, v55, v37
	v_cvt_pk_f16_f32 v55, v38, v39
	v_pk_mov_b32 v[38:39], v[90:91], v[34:35] op_sel:[1,0]
	v_pk_mov_b32 v[40:41], v[40:41], v[52:53] op_sel:[1,0]
	v_alignbit_b32 v37, v55, v37, 16
	v_pk_mul_f32 v[38:39], v[38:39], v[40:41]
	v_pk_add_f32 v[56:57], v[80:81], 1.0 op_sel_hi:[1,0]
	v_cvt_pk_f16_f32 v34, v38, v39
	v_lshrrev_b32_e32 v39, 16, v34
	v_alignbit_b32 v38, v34, v55, 16
	v_fma_mixhi_f16 v39, v35, v53, 0
	v_lshl_add_u64 v[34:35], s[2:3], 0, v[60:61]
	v_lshl_add_u64 v[52:53], v[34:35], 0, v[152:153]
	global_store_dwordx4 v[52:53], v[36:39], off
	global_load_dwordx4 v[34:37], v[126:127], off offset:144
	s_nop 0
	global_load_dwordx4 v[38:41], v[126:127], off offset:128
	v_div_scale_f32 v58, s[0:1], v57, v57, 1.0
	v_rcp_f32_e32 v59, v58
	v_mul_f32_e32 v55, v49, v54
	v_fma_f32 v60, -v58, v59, 1.0
	v_fmac_f32_e32 v59, v60, v59
	v_div_scale_f32 v60, vcc, 1.0, v57, 1.0
	v_mul_f32_e32 v61, v60, v59
	v_fma_f32 v75, -v58, v61, v60
	v_fmac_f32_e32 v61, v75, v59
	v_fma_f32 v58, -v58, v61, v60
	v_div_fmas_f32 v58, v58, v59, v61
	v_div_fixup_f32 v57, v58, v57, 1.0
	v_div_scale_f32 v58, s[0:1], v56, v56, 1.0
	v_rcp_f32_e32 v59, v58
	s_nop 0
	v_fma_f32 v60, -v58, v59, 1.0
	v_fmac_f32_e32 v59, v60, v59
	v_div_scale_f32 v60, vcc, 1.0, v56, 1.0
	v_mul_f32_e32 v61, v60, v59
	v_fma_f32 v75, -v58, v61, v60
	v_fmac_f32_e32 v61, v75, v59
	v_fma_f32 v58, -v58, v61, v60
	v_div_fmas_f32 v58, v58, v59, v61
	v_div_fixup_f32 v56, v58, v56, 1.0
	v_pk_add_f32 v[58:59], v[56:57], -1.0 op_sel_hi:[1,0]
	s_waitcnt vmcnt(0)
	v_pk_fma_f32 v[38:39], v[58:59], v[38:39], 1.0 op_sel_hi:[1,1,0]
	s_nop 0
	v_pk_mul_f32 v[38:39], v[38:39], v[78:79]
	v_pk_add_f32 v[58:59], v[76:77], 1.0 op_sel_hi:[1,0]
	v_cvt_pk_f16_f32 v38, v38, v39
	v_div_scale_f32 v39, s[0:1], v59, v59, 1.0
	v_rcp_f32_e32 v60, v39
	s_nop 0
	v_fma_f32 v61, -v39, v60, 1.0
	v_fmac_f32_e32 v60, v61, v60
	v_div_scale_f32 v61, vcc, 1.0, v59, 1.0
	v_mul_f32_e32 v75, v61, v60
	v_fma_f32 v76, -v39, v75, v61
	v_fmac_f32_e32 v75, v76, v60
	v_fma_f32 v39, -v39, v75, v61
	v_div_fmas_f32 v39, v39, v60, v75
	v_div_fixup_f32 v59, v39, v59, 1.0
	v_div_scale_f32 v39, s[0:1], v58, v58, 1.0
	v_rcp_f32_e32 v60, v39
	s_nop 0
	v_fma_f32 v61, -v39, v60, 1.0
	v_fmac_f32_e32 v60, v61, v60
	v_div_scale_f32 v61, vcc, 1.0, v58, 1.0
	v_mul_f32_e32 v75, v61, v60
	v_fma_f32 v76, -v39, v75, v61
	v_fmac_f32_e32 v75, v76, v60
	v_fma_f32 v39, -v39, v75, v61
	v_div_fmas_f32 v39, v39, v60, v75
	v_div_fixup_f32 v58, v39, v58, 1.0
	v_pk_add_f32 v[60:61], v[58:59], -1.0 op_sel_hi:[1,0]
	s_nop 0
	v_pk_fma_f32 v[40:41], v[60:61], v[40:41], 1.0 op_sel_hi:[1,1,0]
	s_nop 0
	v_pk_mul_f32 v[40:41], v[40:41], v[72:73]
	s_nop 0
	v_cvt_pk_f16_f32 v39, v40, v41
	v_pk_add_f32 v[40:41], v[70:71], 1.0 op_sel_hi:[1,0]
	s_nop 0
	v_div_scale_f32 v60, s[0:1], v41, v41, 1.0
	v_rcp_f32_e32 v61, v60
	s_nop 0
	v_fma_f32 v70, -v60, v61, 1.0
	v_fmac_f32_e32 v61, v70, v61
	v_div_scale_f32 v70, vcc, 1.0, v41, 1.0
	v_mul_f32_e32 v71, v70, v61
	v_fma_f32 v72, -v60, v71, v70
	v_fmac_f32_e32 v71, v72, v61
	v_fma_f32 v60, -v60, v71, v70
	v_div_fmas_f32 v60, v60, v61, v71
	v_div_fixup_f32 v61, v60, v41, 1.0
	v_div_scale_f32 v41, s[0:1], v40, v40, 1.0
; __device__ __forceinline__ float sigmoidf_(float x) { return 1.0f / (1.0f + __expf(-x)); }
;     __device__ __forceinline__ void body_a(const f32x4 (&acc)[2][2][4][2], int row0, int cb0) const {
;     ...
;                     const int c = cb0 + 32 * bj;
;                     const f32x4 b0 = *(const f32x4*)(a0 + c), b1 = *(const f32x4*)(a0 + c + 4), q0 = *(const f32x4*)(k_k + c), q1 = *(const f32x4*)(k_k + c + 4);
;                     const h16x8 kh = *(const h16x8*)(C1 + row * LDC1 + 2048 + c);
; #pragma unroll
;                     for (int e = 0; e < 4; ++e) {
;                         a[bj][e] = sigmoidf_(acc[ai][bj][m][0][e] + b0[e]); a[bj][4 + e] = sigmoidf_(acc[ai][bj][m][1][e] + b1[e]);
;                         kv[bj][e] = (float)kh[e]; kv[bj][4 + e] = (float)kh[4 + e];
;                         kk[bj][e] = kv[bj][e] * q0[e]; kk[bj][4 + e] = kv[bj][4 + e] * q1[e];
;                         ss += kk[bj][e] * kk[bj][e] + kk[bj][4 + e] * kk[bj][4 + e];
;                     }
;                 }
;                 ss += __shfl_xor(ss, 16); ss += __shfl_xor(ss, 32);
;                 const float inv = 1.0f / fmaxf(sqrtf(ss), 1e-12f);
; #pragma unroll
;                 for (int bj = 0; bj < 2; ++bj) {
;                     const int c = cb0 + 32 * bj;
;                     const f32x4 p0 = *(const f32x4*)(k_a + c), p1 = *(const f32x4*)(k_a + c + 4);
;                     f32x4 ko0, ko1, ao0, ao1, bo0, bo1;
; #pragma unroll
;                     for (int e = 0; e < 4; ++e) {
;                         ko0[e] = kv[bj][e] * (1.0f + (a[bj][e] - 1.0f) * p0[e]); ko1[e] = kv[bj][4 + e] * (1.0f + (a[bj][4 + e] - 1.0f) * p1[e]);
;                         const float n0_ = kk[bj][e] * inv, n1_ = kk[bj][4 + e] * inv;
;                         ao0[e] = -n0_; ao1[e] = -n1_; bo0[e] = n0_ * a[bj][e]; bo1[e] = n1_ * a[bj][4 + e];
;                     }
;                     *(u32x4*)(C1 + row * LDC1 + 2048 + c) = pack8(ko0, ko1);
;                     *(u32x4*)(AA + row * DM + c) = pack8(ao0, ao1);
;                     *(u32x4*)(Ab + row * DM + c) = pack8(bo0, bo1);
;                 }
	v_rcp_f32_e32 v60, v41
	s_nop 0
	v_fma_f32 v70, -v41, v60, 1.0
	v_fmac_f32_e32 v60, v70, v60
	v_div_scale_f32 v70, vcc, 1.0, v40, 1.0
	v_mul_f32_e32 v71, v70, v60
	v_fma_f32 v72, -v41, v71, v70
	v_fmac_f32_e32 v71, v72, v60
	v_fma_f32 v41, -v41, v71, v70
	v_div_fmas_f32 v41, v41, v60, v71
	v_div_fixup_f32 v60, v41, v40, 1.0
	v_pk_add_f32 v[40:41], v[60:61], -1.0 op_sel_hi:[1,0]
	s_nop 0
	v_pk_fma_f32 v[34:35], v[40:41], v[34:35], 1.0 op_sel_hi:[1,1,0]
	s_nop 0
	v_pk_mul_f32 v[34:35], v[34:35], v[68:69]
	s_nop 0
	v_cvt_pk_f16_f32 v40, v34, v35
	v_pk_add_f32 v[34:35], v[66:67], 1.0 op_sel_hi:[1,0]
	s_nop 0
	v_div_scale_f32 v41, s[0:1], v35, v35, 1.0
	v_rcp_f32_e32 v66, v41
	s_nop 0
	v_fma_f32 v67, -v41, v66, 1.0
	v_fmac_f32_e32 v66, v67, v66
	v_div_scale_f32 v67, vcc, 1.0, v35, 1.0
	v_mul_f32_e32 v68, v67, v66
	v_fma_f32 v69, -v41, v68, v67
	v_fmac_f32_e32 v68, v69, v66
	v_fma_f32 v41, -v41, v68, v67
	v_div_fmas_f32 v41, v41, v66, v68
	v_div_fixup_f32 v67, v41, v35, 1.0
	v_div_scale_f32 v35, s[0:1], v34, v34, 1.0
	v_rcp_f32_e32 v41, v35
	s_nop 0
	v_fma_f32 v66, -v35, v41, 1.0
	v_fmac_f32_e32 v41, v66, v41
	v_div_scale_f32 v66, vcc, 1.0, v34, 1.0
	v_mul_f32_e32 v68, v66, v41
	v_fma_f32 v69, -v35, v68, v66
	v_fmac_f32_e32 v68, v69, v41
	v_fma_f32 v35, -v35, v68, v66
	v_div_fmas_f32 v35, v35, v41, v68
	v_div_fixup_f32 v66, v35, v34, 1.0
	v_pk_add_f32 v[34:35], v[66:67], -1.0 op_sel_hi:[1,0]
	s_nop 0
	v_pk_fma_f32 v[34:35], v[34:35], v[36:37], 1.0 op_sel_hi:[1,1,0]
	v_cvt_f16_f32_e64 v36, -v74
	v_pk_mul_f32 v[34:35], v[34:35], v[64:65]
	s_nop 0
	v_cvt_pk_f16_f32 v41, v34, v35
	v_pk_mov_b32 v[34:35], v[46:47], v[62:63] op_sel:[1,0]
	global_store_dwordx4 v[42:43], v[38:41], off
	s_nop 1
	v_pk_mul_f32 v[38:39], v[34:35], v[54:55] op_sel_hi:[1,0]
	s_nop 0
	v_cvt_pk_f16_f32 v35, v38, v39
	v_pack_b32_f16 v34, v36, -v35
	v_pk_mov_b32 v[36:37], v[62:63], v[44:45] op_sel:[1,0]
	v_xor_b32_sdwa v35, s63, v35 dst_sel:DWORD dst_unused:UNUSED_PAD src0_sel:DWORD src1_sel:WORD_1
	v_pk_mul_f32 v[40:41], v[36:37], v[54:55] op_sel_hi:[1,0]
	s_nop 0
	v_cvt_pk_f16_f32 v36, v40, v41
	v_xor_b32_e32 v37, 0x8000, v36
	v_perm_b32 v35, v37, v35, s33
	v_xor_b32_sdwa v46, s63, v36 dst_sel:DWORD dst_unused:UNUSED_PAD src0_sel:DWORD src1_sel:WORD_1
	v_pk_mov_b32 v[36:37], v[44:45], v[48:49] op_sel:[1,0]
	v_cvt_f16_f32_e64 v44, -v55
	v_pk_mul_f32 v[42:43], v[36:37], v[54:55] op_sel_hi:[1,0]
	s_nop 0
	v_cvt_pk_f16_f32 v37, v42, v43
	v_xor_b32_e32 v36, 0x8000, v37
	v_xor_b32_sdwa v37, s63, v37 dst_sel:DWORD dst_unused:UNUSED_PAD src0_sel:DWORD src1_sel:WORD_1
	v_perm_b32 v36, v36, v46, s33
	v_perm_b32 v37, v44, v37, s33
	global_store_dwordx4 v[50:51], v[34:37], off offset:64
	s_nop 1
	v_pk_mov_b32 v[34:35], v[56:57], v[58:59] op_sel:[1,0]
	v_fma_mixlo_f16 v36, v56, v74, 0
	v_pk_mul_f32 v[34:35], v[34:35], v[38:39]
	s_nop 0
	v_cvt_pk_f16_f32 v35, v34, v35
	v_pack_b32_f16 v34, v36, v35
	v_pk_mov_b32 v[36:37], v[58:59], v[60:61] op_sel:[1,0]
	s_nop 0
	v_pk_mul_f32 v[36:37], v[36:37], v[40:41]
	s_nop 0
	v_cvt_pk_f16_f32 v38, v36, v37
	v_pk_mov_b32 v[36:37], v[60:61], v[66:67] op_sel:[1,0]
	v_alignbit_b32 v35, v38, v35, 16
	v_pk_mul_f32 v[36:37], v[36:37], v[42:43]
	s_nop 0
	v_cvt_pk_f16_f32 v37, v36, v37
	v_alignbit_b32 v36, v37, v38, 16
	v_lshrrev_b32_e32 v37, 16, v37
	v_fma_mixhi_f16 v37, v67, v55, 0
	global_store_dwordx4 v[52:53], v[34:37], off offset:64
	v_add_u32_e32 v58, 0xa0, v158
	s_nop 0
	v_mad_i64_i32 v[34:35], s[0:1], v58, s5, v[160:161]
	v_lshl_add_u64 v[54:55], v[34:35], 0, s[6:7]
	global_load_dwordx4 v[46:49], v[154:155], off offset:16
	global_load_dwordx4 v[50:53], v[154:155], off
	global_load_dwordx4 v[34:37], v[156:157], off offset:16
	global_load_dwordx4 v[38:41], v[156:157], off
	v_lshl_add_u64 v[66:67], v[54:55], 0, v[152:153]
	global_load_dwordx4 v[42:45], v[66:67], off
	v_ashrrev_i32_e32 v59, 31, v58
	s_waitcnt vmcnt(4)
	v_add_f32_e32 v26, v26, v46
	v_mul_f32_e32 v26, 0xbfb8aa3b, v26
	v_exp_f32_e32 v74, v26
	s_waitcnt vmcnt(3)
	v_add_f32_e32 v26, v31, v51
	v_mul_f32_e32 v26, 0xbfb8aa3b, v26
	v_exp_f32_e32 v77, v26
	v_add_f32_e32 v26, v27, v47
	v_mul_f32_e32 v26, 0xbfb8aa3b, v26
	v_exp_f32_e32 v75, v26
	v_add_f32_e32 v26, v32, v52
	v_mul_f32_e32 v26, 0xbfb8aa3b, v26
	v_exp_f32_e32 v78, v26
	v_add_f32_e32 v26, v28, v48
	v_mul_f32_e32 v26, 0xbfb8aa3b, v26
	v_exp_f32_e32 v68, v26
	v_add_f32_e32 v26, v33, v53
	v_mul_f32_e32 v26, 0xbfb8aa3b, v26
	v_exp_f32_e32 v79, v26
	v_add_f32_e32 v26, v29, v49
	v_add_f32_e32 v30, v30, v50
	v_mul_f32_e32 v26, 0xbfb8aa3b, v26
	v_mul_f32_e32 v30, 0xbfb8aa3b, v30
	v_exp_f32_e32 v69, v26
	v_lshl_add_u64 v[26:27], v[54:55], 0, v[128:129]
	v_exp_f32_e32 v76, v30
	global_load_dwordx4 v[30:33], v[154:155], off offset:144
	global_load_dwordx4 v[46:49], v[154:155], off offset:128
	global_load_dwordx4 v[70:73], v[156:157], off offset:144
	global_load_dwordx4 v[80:83], v[156:157], off offset:128
	global_load_dwordx4 v[84:87], v[26:27], off
	v_pk_add_f32 v[78:79], v[78:79], 1.0 op_sel_hi:[1,0]
	v_pk_add_f32 v[76:77], v[76:77], 1.0 op_sel_hi:[1,0]
	s_waitcnt vmcnt(4)
	v_add_f32_e32 v18, v18, v30
	v_mul_f32_e32 v18, 0xbfb8aa3b, v18
	v_exp_f32_e32 v54, v18
	s_waitcnt vmcnt(3)
	v_add_f32_e32 v18, v23, v47
	s_waitcnt vmcnt(0)
; __device__ __forceinline__ float sigmoidf_(float x) { return 1.0f / (1.0f + __expf(-x)); }
;     __device__ __forceinline__ void body_a(const f32x4 (&acc)[2][2][4][2], int row0, int cb0) const {
;     ...
;                     const int c = cb0 + 32 * bj;
;                     const f32x4 b0 = *(const f32x4*)(a0 + c), b1 = *(const f32x4*)(a0 + c + 4), q0 = *(const f32x4*)(k_k + c), q1 = *(const f32x4*)(k_k + c + 4);
;                     const h16x8 kh = *(const h16x8*)(C1 + row * LDC1 + 2048 + c);
; #pragma unroll
;                     for (int e = 0; e < 4; ++e) {
;                         a[bj][e] = sigmoidf_(acc[ai][bj][m][0][e] + b0[e]); a[bj][4 + e] = sigmoidf_(acc[ai][bj][m][1][e] + b1[e]);
;                         kv[bj][e] = (float)kh[e]; kv[bj][4 + e] = (float)kh[4 + e];
;                         kk[bj][e] = kv[bj][e] * q0[e]; kk[bj][4 + e] = kv[bj][4 + e] * q1[e];
;                         ss += kk[bj][e] * kk[bj][e] + kk[bj][4 + e] * kk[bj][4 + e];
;                     }
;                 }
;                 ss += __shfl_xor(ss, 16); ss += __shfl_xor(ss, 32);
	v_cvt_f32_f16_e32 v52, v86
	v_cvt_f32_f16_sdwa v53, v86 dst_sel:DWORD dst_unused:UNUSED_PAD src0_sel:WORD_1
	v_cvt_f32_f16_e32 v62, v84
	v_cvt_f32_f16_sdwa v63, v84 dst_sel:DWORD dst_unused:UNUSED_PAD src0_sel:WORD_1
	v_mul_f32_e32 v18, 0xbfb8aa3b, v18
	v_exp_f32_e32 v65, v18
	v_add_f32_e32 v18, v19, v31
	v_mul_f32_e32 v18, 0xbfb8aa3b, v18
	v_pk_mul_f32 v[28:29], v[70:71], v[52:53]
	v_exp_f32_e32 v55, v18
	v_pk_mul_f32 v[30:31], v[80:81], v[62:63]
	v_pk_mul_f32 v[18:19], v[28:29], v[28:29]
	v_cvt_f32_f16_e32 v56, v85
	v_pk_fma_f32 v[70:71], v[30:31], v[30:31], v[18:19]
	v_add_f32_e32 v18, v24, v48
	v_mul_f32_e32 v18, 0xbfb8aa3b, v18
	v_exp_f32_e32 v60, v18
	v_add_f32_e32 v18, v20, v32
	v_mul_f32_e32 v18, 0xbfb8aa3b, v18
	v_exp_f32_e32 v50, v18
	v_add_f32_e32 v18, v25, v49
	v_cvt_f32_f16_e32 v48, v87
	v_cvt_f32_f16_sdwa v49, v87 dst_sel:DWORD dst_unused:UNUSED_PAD src0_sel:WORD_1
	v_cvt_f32_f16_sdwa v57, v85 dst_sel:DWORD dst_unused:UNUSED_PAD src0_sel:WORD_1
	v_mul_f32_e32 v18, 0xbfb8aa3b, v18
	v_exp_f32_e32 v61, v18
	v_add_f32_e32 v18, v21, v33
	v_add_f32_e32 v22, v22, v46
	v_mul_f32_e32 v18, 0xbfb8aa3b, v18
	v_pk_mul_f32 v[32:33], v[72:73], v[48:49]
	v_mul_f32_e32 v22, 0xbfb8aa3b, v22
	v_exp_f32_e32 v51, v18
	v_pk_mul_f32 v[46:47], v[82:83], v[56:57]
	v_pk_mul_f32 v[18:19], v[32:33], v[32:33]
	v_exp_f32_e32 v64, v22
	v_pk_fma_f32 v[72:73], v[46:47], v[46:47], v[18:19]
	global_load_dwordx4 v[18:21], v[126:127], off offset:16
	global_load_dwordx4 v[22:25], v[126:127], off
	v_cvt_f32_f16_e32 v80, v42
	v_cvt_f32_f16_sdwa v81, v42 dst_sel:DWORD dst_unused:UNUSED_PAD src0_sel:WORD_1
	v_div_scale_f32 v42, s[0:1], v77, v77, 1.0
	v_rcp_f32_e32 v82, v42
	s_nop 0
	v_fma_f32 v83, -v42, v82, 1.0
	v_fmac_f32_e32 v82, v83, v82
	v_div_scale_f32 v83, vcc, 1.0, v77, 1.0
	v_mul_f32_e32 v84, v83, v82
	v_fma_f32 v85, -v42, v84, v83
	v_fmac_f32_e32 v84, v85, v82
	v_fma_f32 v42, -v42, v84, v83
	v_div_fmas_f32 v42, v42, v82, v84
	v_div_fixup_f32 v77, v42, v77, 1.0
	v_div_scale_f32 v42, s[0:1], v76, v76, 1.0
	v_rcp_f32_e32 v82, v42
	s_nop 0
	v_fma_f32 v83, -v42, v82, 1.0
	v_fmac_f32_e32 v82, v83, v82
	v_div_scale_f32 v83, vcc, 1.0, v76, 1.0
	v_mul_f32_e32 v84, v83, v82
	v_fma_f32 v85, -v42, v84, v83
	v_fmac_f32_e32 v84, v85, v82
	v_fma_f32 v42, -v42, v84, v83
	v_div_fmas_f32 v42, v42, v82, v84
	v_div_fixup_f32 v76, v42, v76, 1.0
	v_pk_add_f32 v[82:83], v[76:77], -1.0 op_sel_hi:[1,0]
	v_cvt_f32_f16_e32 v42, v43
	v_cvt_f32_f16_sdwa v43, v43 dst_sel:DWORD dst_unused:UNUSED_PAD src0_sel:WORD_1
	s_waitcnt vmcnt(0)
	v_pk_fma_f32 v[22:23], v[82:83], v[22:23], 1.0 op_sel_hi:[1,1,0]
	s_nop 0
	v_pk_mul_f32 v[22:23], v[22:23], v[80:81]
	s_nop 0
	v_cvt_pk_f16_f32 v22, v22, v23
	v_div_scale_f32 v23, s[0:1], v79, v79, 1.0
	v_rcp_f32_e32 v82, v23
	s_nop 0
	v_fma_f32 v83, -v23, v82, 1.0
	v_fmac_f32_e32 v82, v83, v82
	v_div_scale_f32 v83, vcc, 1.0, v79, 1.0
	v_mul_f32_e32 v84, v83, v82
	v_fma_f32 v85, -v23, v84, v83
	v_fmac_f32_e32 v84, v85, v82
	v_fma_f32 v23, -v23, v84, v83
	v_div_fmas_f32 v23, v23, v82, v84
	v_div_fixup_f32 v79, v23, v79, 1.0
	v_div_scale_f32 v23, s[0:1], v78, v78, 1.0
	v_rcp_f32_e32 v82, v23
	s_nop 0
	v_fma_f32 v83, -v23, v82, 1.0
	v_fmac_f32_e32 v82, v83, v82
	v_div_scale_f32 v83, vcc, 1.0, v78, 1.0
	v_mul_f32_e32 v84, v83, v82
	v_fma_f32 v85, -v23, v84, v83
	v_fmac_f32_e32 v84, v85, v82
	v_fma_f32 v23, -v23, v84, v83
	v_div_fmas_f32 v23, v23, v82, v84
	v_div_fixup_f32 v78, v23, v78, 1.0
	v_pk_add_f32 v[82:83], v[78:79], -1.0 op_sel_hi:[1,0]
	s_nop 0
	v_pk_fma_f32 v[24:25], v[82:83], v[24:25], 1.0 op_sel_hi:[1,1,0]
	v_cvt_f32_f16_e32 v82, v44
	v_pk_mul_f32 v[24:25], v[24:25], v[42:43]
	v_cvt_f32_f16_sdwa v83, v44 dst_sel:DWORD dst_unused:UNUSED_PAD src0_sel:WORD_1
	v_cvt_pk_f16_f32 v23, v24, v25
	v_pk_add_f32 v[24:25], v[74:75], 1.0 op_sel_hi:[1,0]
	s_nop 0
	v_div_scale_f32 v44, s[0:1], v25, v25, 1.0
	v_rcp_f32_e32 v74, v44
	s_nop 0
	v_fma_f32 v75, -v44, v74, 1.0
	v_fmac_f32_e32 v74, v75, v74
	v_div_scale_f32 v75, vcc, 1.0, v25, 1.0
	v_mul_f32_e32 v84, v75, v74
	v_fma_f32 v85, -v44, v84, v75
	v_fmac_f32_e32 v84, v85, v74
	v_fma_f32 v44, -v44, v84, v75
	v_div_fmas_f32 v44, v44, v74, v84
	v_div_fixup_f32 v75, v44, v25, 1.0
	v_div_scale_f32 v25, s[0:1], v24, v24, 1.0
	v_rcp_f32_e32 v44, v25
	s_nop 0
	v_fma_f32 v74, -v25, v44, 1.0
	v_fmac_f32_e32 v44, v74, v44
	v_div_scale_f32 v74, vcc, 1.0, v24, 1.0
	v_mul_f32_e32 v84, v74, v44
	v_fma_f32 v85, -v25, v84, v74
	v_fmac_f32_e32 v84, v85, v44
	v_fma_f32 v25, -v25, v84, v74
	v_div_fmas_f32 v25, v25, v44, v84
	v_div_fixup_f32 v74, v25, v24, 1.0
	v_pk_add_f32 v[24:25], v[74:75], -1.0 op_sel_hi:[1,0]
	v_cvt_f32_f16_e32 v44, v45
	v_pk_fma_f32 v[18:19], v[24:25], v[18:19], 1.0 op_sel_hi:[1,1,0]
	v_cvt_f32_f16_sdwa v45, v45 dst_sel:DWORD dst_unused:UNUSED_PAD src0_sel:WORD_1
	v_pk_mul_f32 v[18:19], v[18:19], v[82:83]
	v_pk_mul_f32 v[36:37], v[36:37], v[44:45]
	v_cvt_pk_f16_f32 v24, v18, v19
	v_pk_add_f32 v[18:19], v[68:69], 1.0 op_sel_hi:[1,0]
	s_nop 0
	v_div_scale_f32 v25, s[0:1], v19, v19, 1.0
	v_rcp_f32_e32 v68, v25
	s_nop 0
	v_fma_f32 v69, -v25, v68, 1.0
	v_fmac_f32_e32 v68, v69, v68
	v_div_scale_f32 v69, vcc, 1.0, v19, 1.0
	v_mul_f32_e32 v84, v69, v68
	v_fma_f32 v85, -v25, v84, v69
	v_fmac_f32_e32 v84, v85, v68
	v_fma_f32 v25, -v25, v84, v69
	v_div_fmas_f32 v25, v25, v68, v84
	v_div_fixup_f32 v19, v25, v19, 1.0
	v_div_scale_f32 v25, s[0:1], v18, v18, 1.0
	v_rcp_f32_e32 v68, v25
	s_nop 0
	v_fma_f32 v69, -v25, v68, 1.0
	v_fmac_f32_e32 v68, v69, v68
	v_div_scale_f32 v69, vcc, 1.0, v18, 1.0
	v_mul_f32_e32 v84, v69, v68
	v_fma_f32 v85, -v25, v84, v69
	v_fmac_f32_e32 v84, v85, v68
	v_fma_f32 v25, -v25, v84, v69
	v_div_fmas_f32 v25, v25, v68, v84
	v_div_fixup_f32 v18, v25, v18, 1.0
	v_pk_add_f32 v[68:69], v[18:19], -1.0 op_sel_hi:[1,0]
	s_nop 0
	v_pk_fma_f32 v[20:21], v[68:69], v[20:21], 1.0 op_sel_hi:[1,1,0]
	s_nop 0
	v_pk_mul_f32 v[20:21], v[20:21], v[44:45]
	v_lshlrev_b64 v[44:45], 12, v[58:59]
	v_cvt_pk_f16_f32 v25, v20, v21
	global_store_dwordx4 v[66:67], v[22:25], off
	v_pk_mul_f32 v[20:21], v[38:39], v[80:81]
	v_pk_mul_f32 v[38:39], v[36:37], v[36:37]
	v_pk_mul_f32 v[24:25], v[34:35], v[82:83]
	v_pk_mul_f32 v[22:23], v[40:41], v[42:43]
	v_pk_mul_f32 v[34:35], v[24:25], v[24:25]
	v_pk_fma_f32 v[38:39], v[22:23], v[22:23], v[38:39]
	v_pk_fma_f32 v[34:35], v[20:21], v[20:21], v[34:35]
	s_nop 0
	v_add_f32_e32 v34, v34, v35
	v_add_f32_e32 v34, v38, v34
	v_add_f32_e32 v34, v39, v34
	v_add_f32_e32 v34, v34, v70
	v_add_f32_e32 v34, v71, v34
	v_add_f32_e32 v34, v72, v34
	v_add_f32_e32 v34, v73, v34
	ds_bpermute_b32 v35, v206, v34
	s_waitcnt lgkmcnt(0)
;     __device__ __forceinline__ void body_a(const f32x4 (&acc)[2][2][4][2], int row0, int cb0) const {
;     ...
;                 ss += __shfl_xor(ss, 16); ss += __shfl_xor(ss, 32);
;                 const float inv = 1.0f / fmaxf(sqrtf(ss), 1e-12f);
; #pragma unroll
;                 for (int bj = 0; bj < 2; ++bj) {
;                     const int c = cb0 + 32 * bj;
;                     const f32x4 p0 = *(const f32x4*)(k_a + c), p1 = *(const f32x4*)(k_a + c + 4);
;                     f32x4 ko0, ko1, ao0, ao1, bo0, bo1;
; #pragma unroll
;                     for (int e = 0; e < 4; ++e) {
;                         ko0[e] = kv[bj][e] * (1.0f + (a[bj][e] - 1.0f) * p0[e]); ko1[e] = kv[bj][4 + e] * (1.0f + (a[bj][4 + e] - 1.0f) * p1[e]);
;                         const float n0_ = kk[bj][e] * inv, n1_ = kk[bj][4 + e] * inv;
;                         ao0[e] = -n0_; ao1[e] = -n1_; bo0[e] = n0_ * a[bj][e]; bo1[e] = n1_ * a[bj][4 + e];
;                     }
;                     *(u32x4*)(C1 + row * LDC1 + 2048 + c) = pack8(ko0, ko1);
;                     *(u32x4*)(AA + row * DM + c) = pack8(ao0, ao1);
;                     *(u32x4*)(Ab + row * DM + c) = pack8(bo0, bo1);
;                 }
	v_add_f32_e32 v34, v34, v35
	ds_bpermute_b32 v35, v207, v34
	s_waitcnt lgkmcnt(0)
	v_add_f32_e32 v34, v34, v35
	v_cmp_gt_f32_e32 vcc, s4, v34
	v_mul_f32_e32 v35, 0x4f800000, v34
	s_nop 0
	v_cndmask_b32_e32 v34, v34, v35, vcc
	v_sqrt_f32_e32 v35, v34
	s_nop 0
	v_add_u32_e32 v38, -1, v35
	v_fma_f32 v39, -v38, v35, v34
	v_cmp_ge_f32_e64 s[0:1], 0, v39
	v_add_u32_e32 v39, 1, v35
	s_nop 0
	v_cndmask_b32_e64 v38, v35, v38, s[0:1]
	v_fma_f32 v35, -v39, v35, v34
	v_cmp_lt_f32_e64 s[0:1], 0, v35
	s_nop 1
	v_cndmask_b32_e64 v35, v38, v39, s[0:1]
	v_mul_f32_e32 v38, 0x37800000, v35
	v_cndmask_b32_e32 v35, v35, v38, vcc
	v_cmp_class_f32_e32 vcc, v34, v244
	s_nop 1
	v_cndmask_b32_e32 v34, v35, v34, vcc
	v_max_f32_e32 v34, 0x2b8cbccc, v34
	v_div_scale_f32 v35, s[0:1], v34, v34, 1.0
	v_rcp_f32_e32 v38, v35
	s_nop 0
	v_fma_f32 v39, -v35, v38, 1.0
	v_fmac_f32_e32 v38, v39, v38
	v_div_scale_f32 v39, vcc, 1.0, v34, 1.0
	v_mul_f32_e32 v40, v39, v38
	v_fma_f32 v41, -v35, v40, v39
	v_fmac_f32_e32 v40, v41, v38
	v_fma_f32 v35, -v35, v40, v39
	v_div_fmas_f32 v35, v35, v38, v40
	v_div_fixup_f32 v38, v35, v34, 1.0
	v_pk_mul_f32 v[42:43], v[22:23], v[38:39] op_sel_hi:[1,0]
	v_pk_mul_f32 v[40:41], v[20:21], v[38:39] op_sel_hi:[1,0]
	v_cvt_pk_f16_f32 v21, v42, v43
	v_cvt_pk_f16_f32 v20, v40, v41
	v_xor_b32_e32 v22, 0x8000, v21
	v_xor_b32_sdwa v21, s63, v21 dst_sel:DWORD dst_unused:UNUSED_PAD src0_sel:DWORD src1_sel:WORD_1
	v_pk_mul_f32 v[24:25], v[24:25], v[38:39] op_sel_hi:[1,0]
	v_pk_mul_f32 v[36:37], v[36:37], v[38:39] op_sel_hi:[1,0]
	v_perm_b32 v21, v21, v22, s33
	v_xor_b32_e32 v22, 0x8000, v20
	v_xor_b32_sdwa v20, s63, v20 dst_sel:DWORD dst_unused:UNUSED_PAD src0_sel:DWORD src1_sel:WORD_1
	v_perm_b32 v20, v20, v22, s33
	v_pk_add_f32 v[22:23], v[24:25], 0 neg_lo:[1,1] neg_hi:[1,1]
	v_pk_add_f32 v[34:35], v[36:37], 0 neg_lo:[1,1] neg_hi:[1,1]
	v_cvt_pk_f16_f32 v22, v22, v23
	v_cvt_pk_f16_f32 v23, v34, v35
	v_lshl_add_u64 v[34:35], s[10:11], 0, v[44:45]
	v_lshl_add_u64 v[34:35], v[34:35], 0, v[152:153]
	global_store_dwordx4 v[34:35], v[20:23], off
	v_fma_mixlo_f16 v39, v76, v40, 0
	v_mul_f32_e32 v58, v30, v38
	v_pk_mov_b32 v[20:21], v[76:77], v[78:79] op_sel:[1,0]
	v_pk_mov_b32 v[22:23], v[40:41], v[42:43] op_sel:[1,0]
	v_pk_mov_b32 v[40:41], v[42:43], v[24:25] op_sel:[1,0]
	v_pk_mul_f32 v[20:21], v[20:21], v[22:23]
	v_pk_mov_b32 v[22:23], v[78:79], v[74:75] op_sel:[1,0]
	v_cvt_pk_f16_f32 v21, v20, v21
	v_pk_mul_f32 v[22:23], v[22:23], v[40:41]
	v_pack_b32_f16 v20, v39, v21
	v_cvt_pk_f16_f32 v39, v22, v23
	v_pk_mov_b32 v[22:23], v[74:75], v[18:19] op_sel:[1,0]
	v_pk_mov_b32 v[24:25], v[24:25], v[36:37] op_sel:[1,0]
	v_alignbit_b32 v21, v39, v21, 16
	v_pk_mul_f32 v[22:23], v[22:23], v[24:25]
	v_pk_add_f32 v[40:41], v[64:65], 1.0 op_sel_hi:[1,0]
	v_cvt_pk_f16_f32 v18, v22, v23
	v_lshrrev_b32_e32 v23, 16, v18
	v_alignbit_b32 v22, v18, v39, 16
	v_fma_mixhi_f16 v23, v19, v37, 0
	v_lshl_add_u64 v[18:19], s[2:3], 0, v[44:45]
	v_lshl_add_u64 v[36:37], v[18:19], 0, v[152:153]
	global_store_dwordx4 v[36:37], v[20:23], off
	global_load_dwordx4 v[18:21], v[126:127], off offset:144
	s_nop 0
	global_load_dwordx4 v[22:25], v[126:127], off offset:128
	v_div_scale_f32 v42, s[0:1], v41, v41, 1.0
	v_rcp_f32_e32 v43, v42
	v_mul_f32_e32 v39, v33, v38
	v_fma_f32 v44, -v42, v43, 1.0
	v_fmac_f32_e32 v43, v44, v43
	v_div_scale_f32 v44, vcc, 1.0, v41, 1.0
	v_mul_f32_e32 v45, v44, v43
	v_fma_f32 v59, -v42, v45, v44
	v_fmac_f32_e32 v45, v59, v43
	v_fma_f32 v42, -v42, v45, v44
	v_div_fmas_f32 v42, v42, v43, v45
	v_div_fixup_f32 v41, v42, v41, 1.0
	v_div_scale_f32 v42, s[0:1], v40, v40, 1.0
	v_rcp_f32_e32 v43, v42
	s_nop 0
	v_fma_f32 v44, -v42, v43, 1.0
	v_fmac_f32_e32 v43, v44, v43
	v_div_scale_f32 v44, vcc, 1.0, v40, 1.0
	v_mul_f32_e32 v45, v44, v43
	v_fma_f32 v59, -v42, v45, v44
	v_fmac_f32_e32 v45, v59, v43
	v_fma_f32 v42, -v42, v45, v44
	v_div_fmas_f32 v42, v42, v43, v45
	v_div_fixup_f32 v40, v42, v40, 1.0
	v_pk_add_f32 v[42:43], v[40:41], -1.0 op_sel_hi:[1,0]
	s_waitcnt vmcnt(0)
	v_pk_fma_f32 v[22:23], v[42:43], v[22:23], 1.0 op_sel_hi:[1,1,0]
	s_nop 0
	v_pk_mul_f32 v[22:23], v[22:23], v[62:63]
	v_pk_add_f32 v[42:43], v[60:61], 1.0 op_sel_hi:[1,0]
	v_cvt_pk_f16_f32 v22, v22, v23
	v_div_scale_f32 v23, s[0:1], v43, v43, 1.0
	v_rcp_f32_e32 v44, v23
	s_nop 0
	v_fma_f32 v45, -v23, v44, 1.0
	v_fmac_f32_e32 v44, v45, v44
	v_div_scale_f32 v45, vcc, 1.0, v43, 1.0
	v_mul_f32_e32 v59, v45, v44
	v_fma_f32 v60, -v23, v59, v45
	v_fmac_f32_e32 v59, v60, v44
	v_fma_f32 v23, -v23, v59, v45
	v_div_fmas_f32 v23, v23, v44, v59
	v_div_fixup_f32 v43, v23, v43, 1.0
	v_div_scale_f32 v23, s[0:1], v42, v42, 1.0
	v_rcp_f32_e32 v44, v23
	s_nop 0
	v_fma_f32 v45, -v23, v44, 1.0
	v_fmac_f32_e32 v44, v45, v44
	v_div_scale_f32 v45, vcc, 1.0, v42, 1.0
	v_mul_f32_e32 v59, v45, v44
	v_fma_f32 v60, -v23, v59, v45
	v_fmac_f32_e32 v59, v60, v44
	v_fma_f32 v23, -v23, v59, v45
	v_div_fmas_f32 v23, v23, v44, v59
	v_div_fixup_f32 v42, v23, v42, 1.0
	v_pk_add_f32 v[44:45], v[42:43], -1.0 op_sel_hi:[1,0]
	s_nop 0
	v_pk_fma_f32 v[24:25], v[44:45], v[24:25], 1.0 op_sel_hi:[1,1,0]
	s_nop 0
	v_pk_mul_f32 v[24:25], v[24:25], v[56:57]
	s_nop 0
	v_cvt_pk_f16_f32 v23, v24, v25
	v_pk_add_f32 v[24:25], v[54:55], 1.0 op_sel_hi:[1,0]
	s_nop 0
	v_div_scale_f32 v44, s[0:1], v25, v25, 1.0
	v_rcp_f32_e32 v45, v44
	s_nop 0
	v_fma_f32 v54, -v44, v45, 1.0
	v_fmac_f32_e32 v45, v54, v45
	v_div_scale_f32 v54, vcc, 1.0, v25, 1.0
	v_mul_f32_e32 v55, v54, v45
	v_fma_f32 v56, -v44, v55, v54
	v_fmac_f32_e32 v55, v56, v45
	v_fma_f32 v44, -v44, v55, v54
	v_div_fmas_f32 v44, v44, v45, v55
	v_div_fixup_f32 v45, v44, v25, 1.0
	v_div_scale_f32 v25, s[0:1], v24, v24, 1.0
; __device__ __forceinline__ float sigmoidf_(float x) { return 1.0f / (1.0f + __expf(-x)); }
;     __device__ __forceinline__ void body_a(const f32x4 (&acc)[2][2][4][2], int row0, int cb0) const {
;     ...
;                     const int c = cb0 + 32 * bj;
;                     const f32x4 b0 = *(const f32x4*)(a0 + c), b1 = *(const f32x4*)(a0 + c + 4), q0 = *(const f32x4*)(k_k + c), q1 = *(const f32x4*)(k_k + c + 4);
;                     const h16x8 kh = *(const h16x8*)(C1 + row * LDC1 + 2048 + c);
; #pragma unroll
;                     for (int e = 0; e < 4; ++e) {
;                         a[bj][e] = sigmoidf_(acc[ai][bj][m][0][e] + b0[e]); a[bj][4 + e] = sigmoidf_(acc[ai][bj][m][1][e] + b1[e]);
;                         kv[bj][e] = (float)kh[e]; kv[bj][4 + e] = (float)kh[4 + e];
;                         kk[bj][e] = kv[bj][e] * q0[e]; kk[bj][4 + e] = kv[bj][4 + e] * q1[e];
;                         ss += kk[bj][e] * kk[bj][e] + kk[bj][4 + e] * kk[bj][4 + e];
;                     }
;                 }
;                 ss += __shfl_xor(ss, 16); ss += __shfl_xor(ss, 32);
;                 const float inv = 1.0f / fmaxf(sqrtf(ss), 1e-12f);
; #pragma unroll
;                 for (int bj = 0; bj < 2; ++bj) {
;                     const int c = cb0 + 32 * bj;
;                     const f32x4 p0 = *(const f32x4*)(k_a + c), p1 = *(const f32x4*)(k_a + c + 4);
;                     f32x4 ko0, ko1, ao0, ao1, bo0, bo1;
; #pragma unroll
;                     for (int e = 0; e < 4; ++e) {
;                         ko0[e] = kv[bj][e] * (1.0f + (a[bj][e] - 1.0f) * p0[e]); ko1[e] = kv[bj][4 + e] * (1.0f + (a[bj][4 + e] - 1.0f) * p1[e]);
;                         const float n0_ = kk[bj][e] * inv, n1_ = kk[bj][4 + e] * inv;
;                         ao0[e] = -n0_; ao1[e] = -n1_; bo0[e] = n0_ * a[bj][e]; bo1[e] = n1_ * a[bj][4 + e];
;                     }
;                     *(u32x4*)(C1 + row * LDC1 + 2048 + c) = pack8(ko0, ko1);
;                     *(u32x4*)(AA + row * DM + c) = pack8(ao0, ao1);
;                     *(u32x4*)(Ab + row * DM + c) = pack8(bo0, bo1);
;                 }
	v_rcp_f32_e32 v44, v25
	s_nop 0
	v_fma_f32 v54, -v25, v44, 1.0
	v_fmac_f32_e32 v44, v54, v44
	v_div_scale_f32 v54, vcc, 1.0, v24, 1.0
	v_mul_f32_e32 v55, v54, v44
	v_fma_f32 v56, -v25, v55, v54
	v_fmac_f32_e32 v55, v56, v44
	v_fma_f32 v25, -v25, v55, v54
	v_div_fmas_f32 v25, v25, v44, v55
	v_div_fixup_f32 v44, v25, v24, 1.0
	v_pk_add_f32 v[24:25], v[44:45], -1.0 op_sel_hi:[1,0]
	s_nop 0
	v_pk_fma_f32 v[18:19], v[24:25], v[18:19], 1.0 op_sel_hi:[1,1,0]
	s_nop 0
	v_pk_mul_f32 v[18:19], v[18:19], v[52:53]
	s_nop 0
	v_cvt_pk_f16_f32 v24, v18, v19
	v_pk_add_f32 v[18:19], v[50:51], 1.0 op_sel_hi:[1,0]
	s_nop 0
	v_div_scale_f32 v25, s[0:1], v19, v19, 1.0
	v_rcp_f32_e32 v50, v25
	s_nop 0
	v_fma_f32 v51, -v25, v50, 1.0
	v_fmac_f32_e32 v50, v51, v50
	v_div_scale_f32 v51, vcc, 1.0, v19, 1.0
	v_mul_f32_e32 v52, v51, v50
	v_fma_f32 v53, -v25, v52, v51
	v_fmac_f32_e32 v52, v53, v50
	v_fma_f32 v25, -v25, v52, v51
	v_div_fmas_f32 v25, v25, v50, v52
	v_div_fixup_f32 v51, v25, v19, 1.0
	v_div_scale_f32 v19, s[0:1], v18, v18, 1.0
	v_rcp_f32_e32 v25, v19
	s_nop 0
	v_fma_f32 v50, -v19, v25, 1.0
	v_fmac_f32_e32 v25, v50, v25
	v_div_scale_f32 v50, vcc, 1.0, v18, 1.0
	v_mul_f32_e32 v52, v50, v25
	v_fma_f32 v53, -v19, v52, v50
	v_fmac_f32_e32 v52, v53, v25
	v_fma_f32 v19, -v19, v52, v50
	v_div_fmas_f32 v19, v19, v25, v52
	v_div_fixup_f32 v50, v19, v18, 1.0
	v_pk_add_f32 v[18:19], v[50:51], -1.0 op_sel_hi:[1,0]
	s_nop 0
	v_pk_fma_f32 v[18:19], v[18:19], v[20:21], 1.0 op_sel_hi:[1,1,0]
	v_cvt_f16_f32_e64 v20, -v58
	v_pk_mul_f32 v[18:19], v[18:19], v[48:49]
	s_nop 0
	v_cvt_pk_f16_f32 v25, v18, v19
	v_pk_mov_b32 v[18:19], v[30:31], v[46:47] op_sel:[1,0]
	global_store_dwordx4 v[26:27], v[22:25], off
	s_nop 1
	v_pk_mul_f32 v[22:23], v[18:19], v[38:39] op_sel_hi:[1,0]
	s_nop 0
	v_cvt_pk_f16_f32 v19, v22, v23
	v_pack_b32_f16 v18, v20, -v19
	v_pk_mov_b32 v[20:21], v[46:47], v[28:29] op_sel:[1,0]
	v_xor_b32_sdwa v19, s63, v19 dst_sel:DWORD dst_unused:UNUSED_PAD src0_sel:DWORD src1_sel:WORD_1
	v_pk_mul_f32 v[24:25], v[20:21], v[38:39] op_sel_hi:[1,0]
	s_nop 0
	v_cvt_pk_f16_f32 v20, v24, v25
	v_xor_b32_e32 v21, 0x8000, v20
	v_perm_b32 v19, v21, v19, s33
	v_xor_b32_sdwa v30, s63, v20 dst_sel:DWORD dst_unused:UNUSED_PAD src0_sel:DWORD src1_sel:WORD_1
	v_pk_mov_b32 v[20:21], v[28:29], v[32:33] op_sel:[1,0]
	v_cvt_f16_f32_e64 v28, -v39
	v_pk_mul_f32 v[26:27], v[20:21], v[38:39] op_sel_hi:[1,0]
	s_nop 0
	v_cvt_pk_f16_f32 v21, v26, v27
	v_xor_b32_e32 v20, 0x8000, v21
	v_xor_b32_sdwa v21, s63, v21 dst_sel:DWORD dst_unused:UNUSED_PAD src0_sel:DWORD src1_sel:WORD_1
	v_perm_b32 v20, v20, v30, s33
	v_perm_b32 v21, v28, v21, s33
	global_store_dwordx4 v[34:35], v[18:21], off offset:64
	s_nop 1
	v_pk_mov_b32 v[18:19], v[40:41], v[42:43] op_sel:[1,0]
	v_fma_mixlo_f16 v20, v40, v58, 0
	v_pk_mul_f32 v[18:19], v[18:19], v[22:23]
	s_nop 0
	v_cvt_pk_f16_f32 v19, v18, v19
	v_pack_b32_f16 v18, v20, v19
	v_pk_mov_b32 v[20:21], v[42:43], v[44:45] op_sel:[1,0]
	s_nop 0
	v_pk_mul_f32 v[20:21], v[20:21], v[24:25]
	s_nop 0
	v_cvt_pk_f16_f32 v22, v20, v21
	v_pk_mov_b32 v[20:21], v[44:45], v[50:51] op_sel:[1,0]
	v_alignbit_b32 v19, v22, v19, 16
	v_pk_mul_f32 v[20:21], v[20:21], v[26:27]
	s_nop 0
	v_cvt_pk_f16_f32 v21, v20, v21
	v_alignbit_b32 v20, v21, v22, 16
	v_lshrrev_b32_e32 v21, 16, v21
	v_fma_mixhi_f16 v21, v51, v39, 0
	global_store_dwordx4 v[36:37], v[18:21], off offset:64
	v_add_u32_e32 v42, 0xb0, v158
	s_nop 0
	v_mad_i64_i32 v[18:19], s[0:1], v42, s5, v[160:161]
	v_lshl_add_u64 v[38:39], v[18:19], 0, s[6:7]
	global_load_dwordx4 v[30:33], v[154:155], off offset:16
	global_load_dwordx4 v[34:37], v[154:155], off
	global_load_dwordx4 v[18:21], v[156:157], off offset:16
	global_load_dwordx4 v[22:25], v[156:157], off
	v_lshl_add_u64 v[50:51], v[38:39], 0, v[152:153]
	global_load_dwordx4 v[26:29], v[50:51], off
	v_ashrrev_i32_e32 v43, 31, v42
	s_waitcnt vmcnt(4)
	v_add_f32_e32 v10, v10, v30
	v_mul_f32_e32 v10, 0xbfb8aa3b, v10
	v_exp_f32_e32 v58, v10
	s_waitcnt vmcnt(3)
	v_add_f32_e32 v10, v15, v35
	v_mul_f32_e32 v10, 0xbfb8aa3b, v10
	v_exp_f32_e32 v61, v10
	v_add_f32_e32 v10, v11, v31
	v_mul_f32_e32 v10, 0xbfb8aa3b, v10
	v_exp_f32_e32 v59, v10
	v_add_f32_e32 v10, v16, v36
	v_mul_f32_e32 v10, 0xbfb8aa3b, v10
	v_exp_f32_e32 v62, v10
	v_add_f32_e32 v10, v12, v32
	v_mul_f32_e32 v10, 0xbfb8aa3b, v10
	v_exp_f32_e32 v52, v10
	v_add_f32_e32 v10, v17, v37
	v_mul_f32_e32 v10, 0xbfb8aa3b, v10
	v_exp_f32_e32 v63, v10
	v_add_f32_e32 v10, v13, v33
	v_add_f32_e32 v14, v14, v34
	v_mul_f32_e32 v10, 0xbfb8aa3b, v10
	v_mul_f32_e32 v14, 0xbfb8aa3b, v14
	v_exp_f32_e32 v53, v10
	v_lshl_add_u64 v[10:11], v[38:39], 0, v[128:129]
	v_exp_f32_e32 v60, v14
	global_load_dwordx4 v[14:17], v[154:155], off offset:144
	global_load_dwordx4 v[30:33], v[154:155], off offset:128
	global_load_dwordx4 v[54:57], v[156:157], off offset:144
	global_load_dwordx4 v[64:67], v[156:157], off offset:128
	global_load_dwordx4 v[68:71], v[10:11], off
	v_pk_add_f32 v[62:63], v[62:63], 1.0 op_sel_hi:[1,0]
	v_pk_add_f32 v[60:61], v[60:61], 1.0 op_sel_hi:[1,0]
	s_waitcnt vmcnt(4)
	v_add_f32_e32 v2, v2, v14
	v_mul_f32_e32 v2, 0xbfb8aa3b, v2
	v_exp_f32_e32 v38, v2
	s_waitcnt vmcnt(3)
	v_add_f32_e32 v2, v7, v31
	s_waitcnt vmcnt(0)
; __device__ __forceinline__ float sigmoidf_(float x) { return 1.0f / (1.0f + __expf(-x)); }
;     __device__ __forceinline__ void body_a(const f32x4 (&acc)[2][2][4][2], int row0, int cb0) const {
;     ...
;                     const int c = cb0 + 32 * bj;
;                     const f32x4 b0 = *(const f32x4*)(a0 + c), b1 = *(const f32x4*)(a0 + c + 4), q0 = *(const f32x4*)(k_k + c), q1 = *(const f32x4*)(k_k + c + 4);
;                     const h16x8 kh = *(const h16x8*)(C1 + row * LDC1 + 2048 + c);
; #pragma unroll
;                     for (int e = 0; e < 4; ++e) {
;                         a[bj][e] = sigmoidf_(acc[ai][bj][m][0][e] + b0[e]); a[bj][4 + e] = sigmoidf_(acc[ai][bj][m][1][e] + b1[e]);
;                         kv[bj][e] = (float)kh[e]; kv[bj][4 + e] = (float)kh[4 + e];
;                         kk[bj][e] = kv[bj][e] * q0[e]; kk[bj][4 + e] = kv[bj][4 + e] * q1[e];
;                         ss += kk[bj][e] * kk[bj][e] + kk[bj][4 + e] * kk[bj][4 + e];
;                     }
;                 }
;                 ss += __shfl_xor(ss, 16); ss += __shfl_xor(ss, 32);
	v_cvt_f32_f16_e32 v36, v70
	v_cvt_f32_f16_sdwa v37, v70 dst_sel:DWORD dst_unused:UNUSED_PAD src0_sel:WORD_1
	v_cvt_f32_f16_e32 v46, v68
	v_cvt_f32_f16_sdwa v47, v68 dst_sel:DWORD dst_unused:UNUSED_PAD src0_sel:WORD_1
	v_mul_f32_e32 v2, 0xbfb8aa3b, v2
	v_exp_f32_e32 v49, v2
	v_add_f32_e32 v2, v3, v15
	v_mul_f32_e32 v2, 0xbfb8aa3b, v2
	v_pk_mul_f32 v[12:13], v[54:55], v[36:37]
	v_exp_f32_e32 v39, v2
	v_pk_mul_f32 v[14:15], v[64:65], v[46:47]
	v_pk_mul_f32 v[2:3], v[12:13], v[12:13]
	v_cvt_f32_f16_e32 v40, v69
	v_pk_fma_f32 v[54:55], v[14:15], v[14:15], v[2:3]
	v_add_f32_e32 v2, v8, v32
	v_mul_f32_e32 v2, 0xbfb8aa3b, v2
	v_exp_f32_e32 v44, v2
	v_add_f32_e32 v2, v4, v16
	v_mul_f32_e32 v2, 0xbfb8aa3b, v2
	v_exp_f32_e32 v34, v2
	v_add_f32_e32 v2, v9, v33
	v_cvt_f32_f16_e32 v32, v71
	v_cvt_f32_f16_sdwa v33, v71 dst_sel:DWORD dst_unused:UNUSED_PAD src0_sel:WORD_1
	v_cvt_f32_f16_sdwa v41, v69 dst_sel:DWORD dst_unused:UNUSED_PAD src0_sel:WORD_1
	v_mul_f32_e32 v2, 0xbfb8aa3b, v2
	v_exp_f32_e32 v45, v2
	v_add_f32_e32 v2, v5, v17
	v_add_f32_e32 v6, v6, v30
	v_mul_f32_e32 v2, 0xbfb8aa3b, v2
	v_pk_mul_f32 v[16:17], v[56:57], v[32:33]
	v_mul_f32_e32 v6, 0xbfb8aa3b, v6
	v_exp_f32_e32 v35, v2
	v_pk_mul_f32 v[30:31], v[66:67], v[40:41]
	v_pk_mul_f32 v[2:3], v[16:17], v[16:17]
	v_exp_f32_e32 v48, v6
	v_pk_fma_f32 v[56:57], v[30:31], v[30:31], v[2:3]
	global_load_dwordx4 v[2:5], v[126:127], off offset:16
	global_load_dwordx4 v[6:9], v[126:127], off
	v_cvt_f32_f16_e32 v64, v26
	v_cvt_f32_f16_sdwa v65, v26 dst_sel:DWORD dst_unused:UNUSED_PAD src0_sel:WORD_1
	v_div_scale_f32 v26, s[0:1], v61, v61, 1.0
	v_rcp_f32_e32 v66, v26
	s_nop 0
	v_fma_f32 v67, -v26, v66, 1.0
	v_fmac_f32_e32 v66, v67, v66
	v_div_scale_f32 v67, vcc, 1.0, v61, 1.0
	v_mul_f32_e32 v68, v67, v66
	v_fma_f32 v69, -v26, v68, v67
	v_fmac_f32_e32 v68, v69, v66
	v_fma_f32 v26, -v26, v68, v67
	v_div_fmas_f32 v26, v26, v66, v68
	v_div_fixup_f32 v61, v26, v61, 1.0
	v_div_scale_f32 v26, s[0:1], v60, v60, 1.0
	v_rcp_f32_e32 v66, v26
	s_nop 0
	v_fma_f32 v67, -v26, v66, 1.0
	v_fmac_f32_e32 v66, v67, v66
	v_div_scale_f32 v67, vcc, 1.0, v60, 1.0
	v_mul_f32_e32 v68, v67, v66
	v_fma_f32 v69, -v26, v68, v67
	v_fmac_f32_e32 v68, v69, v66
	v_fma_f32 v26, -v26, v68, v67
	v_div_fmas_f32 v26, v26, v66, v68
	v_div_fixup_f32 v60, v26, v60, 1.0
	v_pk_add_f32 v[66:67], v[60:61], -1.0 op_sel_hi:[1,0]
	v_cvt_f32_f16_e32 v26, v27
	v_cvt_f32_f16_sdwa v27, v27 dst_sel:DWORD dst_unused:UNUSED_PAD src0_sel:WORD_1
	s_waitcnt vmcnt(0)
	v_pk_fma_f32 v[6:7], v[66:67], v[6:7], 1.0 op_sel_hi:[1,1,0]
	s_nop 0
	v_pk_mul_f32 v[6:7], v[6:7], v[64:65]
	s_nop 0
	v_cvt_pk_f16_f32 v6, v6, v7
	v_div_scale_f32 v7, s[0:1], v63, v63, 1.0
	v_rcp_f32_e32 v66, v7
	s_nop 0
	v_fma_f32 v67, -v7, v66, 1.0
	v_fmac_f32_e32 v66, v67, v66
	v_div_scale_f32 v67, vcc, 1.0, v63, 1.0
	v_mul_f32_e32 v68, v67, v66
	v_fma_f32 v69, -v7, v68, v67
	v_fmac_f32_e32 v68, v69, v66
	v_fma_f32 v7, -v7, v68, v67
	v_div_fmas_f32 v7, v7, v66, v68
	v_div_fixup_f32 v63, v7, v63, 1.0
	v_div_scale_f32 v7, s[0:1], v62, v62, 1.0
	v_rcp_f32_e32 v66, v7
	s_nop 0
	v_fma_f32 v67, -v7, v66, 1.0
	v_fmac_f32_e32 v66, v67, v66
	v_div_scale_f32 v67, vcc, 1.0, v62, 1.0
	v_mul_f32_e32 v68, v67, v66
	v_fma_f32 v69, -v7, v68, v67
	v_fmac_f32_e32 v68, v69, v66
	v_fma_f32 v7, -v7, v68, v67
	v_div_fmas_f32 v7, v7, v66, v68
	v_div_fixup_f32 v62, v7, v62, 1.0
	v_pk_add_f32 v[66:67], v[62:63], -1.0 op_sel_hi:[1,0]
	s_nop 0
	v_pk_fma_f32 v[8:9], v[66:67], v[8:9], 1.0 op_sel_hi:[1,1,0]
	v_cvt_f32_f16_e32 v66, v28
	v_pk_mul_f32 v[8:9], v[8:9], v[26:27]
	v_cvt_f32_f16_sdwa v67, v28 dst_sel:DWORD dst_unused:UNUSED_PAD src0_sel:WORD_1
	v_cvt_pk_f16_f32 v7, v8, v9
	v_pk_add_f32 v[8:9], v[58:59], 1.0 op_sel_hi:[1,0]
	s_nop 0
	v_div_scale_f32 v28, s[0:1], v9, v9, 1.0
	v_rcp_f32_e32 v58, v28
	s_nop 0
	v_fma_f32 v59, -v28, v58, 1.0
	v_fmac_f32_e32 v58, v59, v58
	v_div_scale_f32 v59, vcc, 1.0, v9, 1.0
	v_mul_f32_e32 v68, v59, v58
	v_fma_f32 v69, -v28, v68, v59
	v_fmac_f32_e32 v68, v69, v58
	v_fma_f32 v28, -v28, v68, v59
	v_div_fmas_f32 v28, v28, v58, v68
	v_div_fixup_f32 v59, v28, v9, 1.0
	v_div_scale_f32 v9, s[0:1], v8, v8, 1.0
	v_rcp_f32_e32 v28, v9
	s_nop 0
	v_fma_f32 v58, -v9, v28, 1.0
	v_fmac_f32_e32 v28, v58, v28
	v_div_scale_f32 v58, vcc, 1.0, v8, 1.0
	v_mul_f32_e32 v68, v58, v28
	v_fma_f32 v69, -v9, v68, v58
	v_fmac_f32_e32 v68, v69, v28
	v_fma_f32 v9, -v9, v68, v58
	v_div_fmas_f32 v9, v9, v28, v68
	v_div_fixup_f32 v58, v9, v8, 1.0
	v_pk_add_f32 v[8:9], v[58:59], -1.0 op_sel_hi:[1,0]
	v_cvt_f32_f16_e32 v28, v29
	v_pk_fma_f32 v[2:3], v[8:9], v[2:3], 1.0 op_sel_hi:[1,1,0]
	v_cvt_f32_f16_sdwa v29, v29 dst_sel:DWORD dst_unused:UNUSED_PAD src0_sel:WORD_1
	v_pk_mul_f32 v[2:3], v[2:3], v[66:67]
	v_pk_mul_f32 v[20:21], v[20:21], v[28:29]
	v_cvt_pk_f16_f32 v8, v2, v3
	v_pk_add_f32 v[2:3], v[52:53], 1.0 op_sel_hi:[1,0]
	s_nop 0
	v_div_scale_f32 v9, s[0:1], v3, v3, 1.0
	v_rcp_f32_e32 v52, v9
	s_nop 0
	v_fma_f32 v53, -v9, v52, 1.0
	v_fmac_f32_e32 v52, v53, v52
	v_div_scale_f32 v53, vcc, 1.0, v3, 1.0
	v_mul_f32_e32 v68, v53, v52
	v_fma_f32 v69, -v9, v68, v53
	v_fmac_f32_e32 v68, v69, v52
	v_fma_f32 v9, -v9, v68, v53
	v_div_fmas_f32 v9, v9, v52, v68
	v_div_fixup_f32 v3, v9, v3, 1.0
	v_div_scale_f32 v9, s[0:1], v2, v2, 1.0
	v_rcp_f32_e32 v52, v9
	s_nop 0
	v_fma_f32 v53, -v9, v52, 1.0
	v_fmac_f32_e32 v52, v53, v52
	v_div_scale_f32 v53, vcc, 1.0, v2, 1.0
	v_mul_f32_e32 v68, v53, v52
	v_fma_f32 v69, -v9, v68, v53
	v_fmac_f32_e32 v68, v69, v52
	v_fma_f32 v9, -v9, v68, v53
	v_div_fmas_f32 v9, v9, v52, v68
	v_div_fixup_f32 v2, v9, v2, 1.0
	v_pk_add_f32 v[52:53], v[2:3], -1.0 op_sel_hi:[1,0]
	s_nop 0
	v_pk_fma_f32 v[4:5], v[52:53], v[4:5], 1.0 op_sel_hi:[1,1,0]
	s_nop 0
	v_pk_mul_f32 v[4:5], v[4:5], v[28:29]
	v_lshlrev_b64 v[28:29], 12, v[42:43]
	v_cvt_pk_f16_f32 v9, v4, v5
	global_store_dwordx4 v[50:51], v[6:9], off
	v_pk_mul_f32 v[4:5], v[22:23], v[64:65]
	v_pk_mul_f32 v[22:23], v[20:21], v[20:21]
	v_pk_mul_f32 v[8:9], v[18:19], v[66:67]
	v_pk_mul_f32 v[6:7], v[24:25], v[26:27]
	v_pk_mul_f32 v[18:19], v[8:9], v[8:9]
	v_pk_fma_f32 v[22:23], v[6:7], v[6:7], v[22:23]
	v_pk_fma_f32 v[18:19], v[4:5], v[4:5], v[18:19]
	s_nop 0
	v_add_f32_e32 v18, v18, v19
	v_add_f32_e32 v18, v22, v18
	v_add_f32_e32 v18, v23, v18
	v_add_f32_e32 v18, v18, v54
	v_add_f32_e32 v18, v55, v18
	v_add_f32_e32 v18, v56, v18
	v_add_f32_e32 v18, v57, v18
	ds_bpermute_b32 v19, v206, v18
	s_waitcnt lgkmcnt(0)
;     __device__ __forceinline__ void body_a(const f32x4 (&acc)[2][2][4][2], int row0, int cb0) const {
;     ...
;                 ss += __shfl_xor(ss, 16); ss += __shfl_xor(ss, 32);
;                 const float inv = 1.0f / fmaxf(sqrtf(ss), 1e-12f);
; #pragma unroll
;                 for (int bj = 0; bj < 2; ++bj) {
;                     const int c = cb0 + 32 * bj;
;                     const f32x4 p0 = *(const f32x4*)(k_a + c), p1 = *(const f32x4*)(k_a + c + 4);
;                     f32x4 ko0, ko1, ao0, ao1, bo0, bo1;
; #pragma unroll
;                     for (int e = 0; e < 4; ++e) {
;                         ko0[e] = kv[bj][e] * (1.0f + (a[bj][e] - 1.0f) * p0[e]); ko1[e] = kv[bj][4 + e] * (1.0f + (a[bj][4 + e] - 1.0f) * p1[e]);
;                         const float n0_ = kk[bj][e] * inv, n1_ = kk[bj][4 + e] * inv;
;                         ao0[e] = -n0_; ao1[e] = -n1_; bo0[e] = n0_ * a[bj][e]; bo1[e] = n1_ * a[bj][4 + e];
;                     }
;                     *(u32x4*)(C1 + row * LDC1 + 2048 + c) = pack8(ko0, ko1);
;                     *(u32x4*)(AA + row * DM + c) = pack8(ao0, ao1);
;                     *(u32x4*)(Ab + row * DM + c) = pack8(bo0, bo1);
;                 }
	v_add_f32_e32 v18, v18, v19
	ds_bpermute_b32 v19, v207, v18
	s_waitcnt lgkmcnt(0)
	v_add_f32_e32 v18, v18, v19
	v_cmp_gt_f32_e32 vcc, s4, v18
	v_mul_f32_e32 v19, 0x4f800000, v18
	s_nop 0
	v_cndmask_b32_e32 v18, v18, v19, vcc
	v_sqrt_f32_e32 v19, v18
	s_nop 0
	v_add_u32_e32 v22, -1, v19
	v_fma_f32 v23, -v22, v19, v18
	v_cmp_ge_f32_e64 s[0:1], 0, v23
	v_add_u32_e32 v23, 1, v19
	s_nop 0
	v_cndmask_b32_e64 v22, v19, v22, s[0:1]
	v_fma_f32 v19, -v23, v19, v18
	v_cmp_lt_f32_e64 s[0:1], 0, v19
	s_nop 1
	v_cndmask_b32_e64 v19, v22, v23, s[0:1]
	v_mul_f32_e32 v22, 0x37800000, v19
	v_cndmask_b32_e32 v19, v19, v22, vcc
	v_cmp_class_f32_e32 vcc, v18, v244
	s_nop 1
	v_cndmask_b32_e32 v18, v19, v18, vcc
	v_max_f32_e32 v18, 0x2b8cbccc, v18
	v_div_scale_f32 v19, s[0:1], v18, v18, 1.0
	v_rcp_f32_e32 v22, v19
	s_nop 0
	v_fma_f32 v23, -v19, v22, 1.0
	v_fmac_f32_e32 v22, v23, v22
	v_div_scale_f32 v23, vcc, 1.0, v18, 1.0
	v_mul_f32_e32 v24, v23, v22
	v_fma_f32 v25, -v19, v24, v23
	v_fmac_f32_e32 v24, v25, v22
	v_fma_f32 v19, -v19, v24, v23
	v_div_fmas_f32 v19, v19, v22, v24
	v_div_fixup_f32 v22, v19, v18, 1.0
	v_pk_mul_f32 v[26:27], v[6:7], v[22:23] op_sel_hi:[1,0]
	v_pk_mul_f32 v[24:25], v[4:5], v[22:23] op_sel_hi:[1,0]
	v_cvt_pk_f16_f32 v5, v26, v27
	v_cvt_pk_f16_f32 v4, v24, v25
	v_xor_b32_e32 v6, 0x8000, v5
	v_xor_b32_sdwa v5, s63, v5 dst_sel:DWORD dst_unused:UNUSED_PAD src0_sel:DWORD src1_sel:WORD_1
	v_pk_mul_f32 v[8:9], v[8:9], v[22:23] op_sel_hi:[1,0]
	v_pk_mul_f32 v[20:21], v[20:21], v[22:23] op_sel_hi:[1,0]
	v_perm_b32 v5, v5, v6, s33
	v_xor_b32_e32 v6, 0x8000, v4
	v_xor_b32_sdwa v4, s63, v4 dst_sel:DWORD dst_unused:UNUSED_PAD src0_sel:DWORD src1_sel:WORD_1
	v_perm_b32 v4, v4, v6, s33
	v_pk_add_f32 v[6:7], v[8:9], 0 neg_lo:[1,1] neg_hi:[1,1]
	v_pk_add_f32 v[18:19], v[20:21], 0 neg_lo:[1,1] neg_hi:[1,1]
	v_cvt_pk_f16_f32 v6, v6, v7
	v_cvt_pk_f16_f32 v7, v18, v19
	v_lshl_add_u64 v[18:19], s[10:11], 0, v[28:29]
	v_lshl_add_u64 v[18:19], v[18:19], 0, v[152:153]
	global_store_dwordx4 v[18:19], v[4:7], off
	v_fma_mixlo_f16 v23, v60, v24, 0
	v_mul_f32_e32 v42, v14, v22
	v_pk_mov_b32 v[4:5], v[60:61], v[62:63] op_sel:[1,0]
	v_pk_mov_b32 v[6:7], v[24:25], v[26:27] op_sel:[1,0]
	v_pk_mov_b32 v[24:25], v[26:27], v[8:9] op_sel:[1,0]
	v_pk_mul_f32 v[4:5], v[4:5], v[6:7]
	v_pk_mov_b32 v[6:7], v[62:63], v[58:59] op_sel:[1,0]
	v_cvt_pk_f16_f32 v5, v4, v5
	v_pk_mul_f32 v[6:7], v[6:7], v[24:25]
	v_pack_b32_f16 v4, v23, v5
	v_cvt_pk_f16_f32 v23, v6, v7
	v_pk_mov_b32 v[6:7], v[58:59], v[2:3] op_sel:[1,0]
	v_pk_mov_b32 v[8:9], v[8:9], v[20:21] op_sel:[1,0]
	v_alignbit_b32 v5, v23, v5, 16
	v_pk_mul_f32 v[6:7], v[6:7], v[8:9]
	v_pk_add_f32 v[24:25], v[48:49], 1.0 op_sel_hi:[1,0]
	v_cvt_pk_f16_f32 v2, v6, v7
	v_lshrrev_b32_e32 v7, 16, v2
	v_alignbit_b32 v6, v2, v23, 16
	v_fma_mixhi_f16 v7, v3, v21, 0
	v_lshl_add_u64 v[2:3], s[2:3], 0, v[28:29]
	v_lshl_add_u64 v[20:21], v[2:3], 0, v[152:153]
	global_store_dwordx4 v[20:21], v[4:7], off
	global_load_dwordx4 v[2:5], v[126:127], off offset:144
	s_nop 0
	global_load_dwordx4 v[6:9], v[126:127], off offset:128
	v_div_scale_f32 v26, s[0:1], v25, v25, 1.0
	v_rcp_f32_e32 v27, v26
	v_mul_f32_e32 v23, v17, v22
	v_fma_f32 v28, -v26, v27, 1.0
	v_fmac_f32_e32 v27, v28, v27
	v_div_scale_f32 v28, vcc, 1.0, v25, 1.0
	v_mul_f32_e32 v29, v28, v27
	v_fma_f32 v43, -v26, v29, v28
	v_fmac_f32_e32 v29, v43, v27
	v_fma_f32 v26, -v26, v29, v28
	v_div_fmas_f32 v26, v26, v27, v29
	v_div_fixup_f32 v25, v26, v25, 1.0
	v_div_scale_f32 v26, s[0:1], v24, v24, 1.0
	v_rcp_f32_e32 v27, v26
	s_nop 0
	v_fma_f32 v28, -v26, v27, 1.0
	v_fmac_f32_e32 v27, v28, v27
	v_div_scale_f32 v28, vcc, 1.0, v24, 1.0
	v_mul_f32_e32 v29, v28, v27
	v_fma_f32 v43, -v26, v29, v28
	v_fmac_f32_e32 v29, v43, v27
	v_fma_f32 v26, -v26, v29, v28
	v_div_fmas_f32 v26, v26, v27, v29
	v_div_fixup_f32 v24, v26, v24, 1.0
	v_pk_add_f32 v[26:27], v[24:25], -1.0 op_sel_hi:[1,0]
	s_waitcnt vmcnt(0)
; template <class Epi, class AMap>
; __device__ __forceinline__ void gemm_phase(LAS unsigned char* lds, const AMap am, const int lda, const h16* Bt, const int ldb, const int M, const int N, const int K, const Epi& E) {
;     ...
;         if (!has_next) break;
; #pragma unroll
;         for (int a = 0; a < 2; ++a)
; #pragma unroll
;             for (int b = 0; b < 2; ++b)
; #pragma unroll
;                 for (int m = 0; m < 4; ++m)
; #pragma unroll
;                     for (int n = 0; n < 2; ++n) acc[a][b][m][n] = (f32x4){0.f, 0.f, 0.f, 0.f};
;         cur = nxt; cA = nA; cB = nB; ++ui;
;     __device__ __forceinline__ void body_a(const f32x4 (&acc)[2][2][4][2], int row0, int cb0) const {
;     ...
;                 for (int bj = 0; bj < 2; ++bj) {
;                     const int c = cb0 + 32 * bj;
;                     const f32x4 p0 = *(const f32x4*)(k_a + c), p1 = *(const f32x4*)(k_a + c + 4);
;                     f32x4 ko0, ko1, ao0, ao1, bo0, bo1;
; #pragma unroll
;                     for (int e = 0; e < 4; ++e) {
;                         ko0[e] = kv[bj][e] * (1.0f + (a[bj][e] - 1.0f) * p0[e]); ko1[e] = kv[bj][4 + e] * (1.0f + (a[bj][4 + e] - 1.0f) * p1[e]);
;                         const float n0_ = kk[bj][e] * inv, n1_ = kk[bj][4 + e] * inv;
;                         ao0[e] = -n0_; ao1[e] = -n1_; bo0[e] = n0_ * a[bj][e]; bo1[e] = n1_ * a[bj][4 + e];
;                     }
;                     *(u32x4*)(C1 + row * LDC1 + 2048 + c) = pack8(ko0, ko1);
;                     *(u32x4*)(AA + row * DM + c) = pack8(ao0, ao1);
;                     *(u32x4*)(Ab + row * DM + c) = pack8(bo0, bo1);
;                 }
	v_pk_fma_f32 v[6:7], v[26:27], v[6:7], 1.0 op_sel_hi:[1,1,0]
	s_nop 0
	v_pk_mul_f32 v[6:7], v[6:7], v[46:47]
	v_pk_add_f32 v[26:27], v[44:45], 1.0 op_sel_hi:[1,0]
	v_cvt_pk_f16_f32 v6, v6, v7
	v_div_scale_f32 v7, s[0:1], v27, v27, 1.0
	v_rcp_f32_e32 v28, v7
	s_nop 0
	v_fma_f32 v29, -v7, v28, 1.0
	v_fmac_f32_e32 v28, v29, v28
	v_div_scale_f32 v29, vcc, 1.0, v27, 1.0
	v_mul_f32_e32 v43, v29, v28
	v_fma_f32 v44, -v7, v43, v29
	v_fmac_f32_e32 v43, v44, v28
	v_fma_f32 v7, -v7, v43, v29
	v_div_fmas_f32 v7, v7, v28, v43
	v_div_fixup_f32 v27, v7, v27, 1.0
	v_div_scale_f32 v7, s[0:1], v26, v26, 1.0
	v_rcp_f32_e32 v28, v7
	s_nop 0
	v_fma_f32 v29, -v7, v28, 1.0
	v_fmac_f32_e32 v28, v29, v28
	v_div_scale_f32 v29, vcc, 1.0, v26, 1.0
	v_mul_f32_e32 v43, v29, v28
	v_fma_f32 v44, -v7, v43, v29
	v_fmac_f32_e32 v43, v44, v28
	v_fma_f32 v7, -v7, v43, v29
	v_div_fmas_f32 v7, v7, v28, v43
	v_div_fixup_f32 v26, v7, v26, 1.0
	v_pk_add_f32 v[28:29], v[26:27], -1.0 op_sel_hi:[1,0]
	s_nop 0
	v_pk_fma_f32 v[8:9], v[28:29], v[8:9], 1.0 op_sel_hi:[1,1,0]
	s_nop 0
	v_pk_mul_f32 v[8:9], v[8:9], v[40:41]
	s_nop 0
	v_cvt_pk_f16_f32 v7, v8, v9
	v_pk_add_f32 v[8:9], v[38:39], 1.0 op_sel_hi:[1,0]
	s_nop 0
	v_div_scale_f32 v28, s[0:1], v9, v9, 1.0
	v_rcp_f32_e32 v29, v28
	s_nop 0
	v_fma_f32 v38, -v28, v29, 1.0
	v_fmac_f32_e32 v29, v38, v29
	v_div_scale_f32 v38, vcc, 1.0, v9, 1.0
	v_mul_f32_e32 v39, v38, v29
	v_fma_f32 v40, -v28, v39, v38
	v_fmac_f32_e32 v39, v40, v29
	v_fma_f32 v28, -v28, v39, v38
	v_div_fmas_f32 v28, v28, v29, v39
	v_div_fixup_f32 v29, v28, v9, 1.0
	v_div_scale_f32 v9, s[0:1], v8, v8, 1.0
	v_rcp_f32_e32 v28, v9
	s_nop 0
	v_fma_f32 v38, -v9, v28, 1.0
	v_fmac_f32_e32 v28, v38, v28
	v_div_scale_f32 v38, vcc, 1.0, v8, 1.0
	v_mul_f32_e32 v39, v38, v28
	v_fma_f32 v40, -v9, v39, v38
	v_fmac_f32_e32 v39, v40, v28
	v_fma_f32 v9, -v9, v39, v38
	v_div_fmas_f32 v9, v9, v28, v39
	v_div_fixup_f32 v28, v9, v8, 1.0
	v_pk_add_f32 v[8:9], v[28:29], -1.0 op_sel_hi:[1,0]
	s_nop 0
	v_pk_fma_f32 v[2:3], v[8:9], v[2:3], 1.0 op_sel_hi:[1,1,0]
	s_nop 0
	v_pk_mul_f32 v[2:3], v[2:3], v[36:37]
	s_nop 0
	v_cvt_pk_f16_f32 v8, v2, v3
	v_pk_add_f32 v[2:3], v[34:35], 1.0 op_sel_hi:[1,0]
	s_nop 0
	v_div_scale_f32 v9, s[0:1], v3, v3, 1.0
	v_rcp_f32_e32 v34, v9
	s_nop 0
	v_fma_f32 v35, -v9, v34, 1.0
	v_fmac_f32_e32 v34, v35, v34
	v_div_scale_f32 v35, vcc, 1.0, v3, 1.0
	v_mul_f32_e32 v36, v35, v34
	v_fma_f32 v37, -v9, v36, v35
	v_fmac_f32_e32 v36, v37, v34
	v_fma_f32 v9, -v9, v36, v35
	v_div_fmas_f32 v9, v9, v34, v36
	v_div_fixup_f32 v35, v9, v3, 1.0
	v_div_scale_f32 v3, s[0:1], v2, v2, 1.0
	v_rcp_f32_e32 v9, v3
	s_nop 0
	v_fma_f32 v34, -v3, v9, 1.0
	v_fmac_f32_e32 v9, v34, v9
	v_div_scale_f32 v34, vcc, 1.0, v2, 1.0
	v_mul_f32_e32 v36, v34, v9
	v_fma_f32 v37, -v3, v36, v34
	v_fmac_f32_e32 v36, v37, v9
	v_fma_f32 v3, -v3, v36, v34
	v_div_fmas_f32 v3, v3, v9, v36
	v_div_fixup_f32 v34, v3, v2, 1.0
	v_pk_add_f32 v[2:3], v[34:35], -1.0 op_sel_hi:[1,0]
	s_nop 0
	v_pk_fma_f32 v[2:3], v[2:3], v[4:5], 1.0 op_sel_hi:[1,1,0]
	v_cvt_f16_f32_e64 v4, -v42
	v_pk_mul_f32 v[2:3], v[2:3], v[32:33]
	s_nop 0
	v_cvt_pk_f16_f32 v9, v2, v3
	v_pk_mov_b32 v[2:3], v[14:15], v[30:31] op_sel:[1,0]
	global_store_dwordx4 v[10:11], v[6:9], off
	s_nop 1
	v_pk_mul_f32 v[6:7], v[2:3], v[22:23] op_sel_hi:[1,0]
	s_nop 0
	v_cvt_pk_f16_f32 v3, v6, v7
	v_pack_b32_f16 v2, v4, -v3
	v_pk_mov_b32 v[4:5], v[30:31], v[12:13] op_sel:[1,0]
	v_xor_b32_sdwa v3, s63, v3 dst_sel:DWORD dst_unused:UNUSED_PAD src0_sel:DWORD src1_sel:WORD_1
	v_pk_mul_f32 v[8:9], v[4:5], v[22:23] op_sel_hi:[1,0]
	s_nop 0
	v_cvt_pk_f16_f32 v4, v8, v9
	v_xor_b32_e32 v5, 0x8000, v4
	v_perm_b32 v3, v5, v3, s33
	v_xor_b32_sdwa v14, s63, v4 dst_sel:DWORD dst_unused:UNUSED_PAD src0_sel:DWORD src1_sel:WORD_1
	v_pk_mov_b32 v[4:5], v[12:13], v[16:17] op_sel:[1,0]
	v_cvt_f16_f32_e64 v12, -v23
	v_pk_mul_f32 v[10:11], v[4:5], v[22:23] op_sel_hi:[1,0]
	s_nop 0
	v_cvt_pk_f16_f32 v5, v10, v11
	v_xor_b32_e32 v4, 0x8000, v5
	v_xor_b32_sdwa v5, s63, v5 dst_sel:DWORD dst_unused:UNUSED_PAD src0_sel:DWORD src1_sel:WORD_1
	v_perm_b32 v4, v4, v14, s33
	v_perm_b32 v5, v12, v5, s33
	global_store_dwordx4 v[18:19], v[2:5], off offset:64
	s_nop 1
	v_pk_mov_b32 v[2:3], v[24:25], v[26:27] op_sel:[1,0]
	v_fma_mixlo_f16 v4, v24, v42, 0
	v_pk_mul_f32 v[2:3], v[2:3], v[6:7]
	s_nop 0
	v_cvt_pk_f16_f32 v3, v2, v3
	v_pack_b32_f16 v2, v4, v3
	v_pk_mov_b32 v[4:5], v[26:27], v[28:29] op_sel:[1,0]
	s_nop 0
	v_pk_mul_f32 v[4:5], v[4:5], v[8:9]
	s_nop 0
	v_cvt_pk_f16_f32 v6, v4, v5
	v_pk_mov_b32 v[4:5], v[28:29], v[34:35] op_sel:[1,0]
	v_alignbit_b32 v3, v6, v3, 16
	v_pk_mul_f32 v[4:5], v[4:5], v[10:11]
	s_nop 0
	v_cvt_pk_f16_f32 v5, v4, v5
	v_alignbit_b32 v4, v5, v6, 16
	v_lshrrev_b32_e32 v5, 16, v5
	v_fma_mixhi_f16 v5, v35, v23, 0
	global_store_dwordx4 v[20:21], v[2:5], off offset:64
	s_and_b64 vcc, exec, s[38:39]
	s_mov_b32 s50, s44
	s_mov_b32 s35, s82
	s_mov_b64 s[26:27], s[64:65]
	s_mov_b64 s[22:23], s[46:47]
	s_cmpk_lt_u32 s69, 0x100
	s_cbranch_scc1 .Lgy5
	s_barrier

; #define PG8_STAGE(bufoff, gbase, voff) do { _Pragma("unroll") for (int _i = 0; _i < 2; ++_i) \
;         __builtin_amdgcn_global_load_lds((const unsigned*)((const char*)(gbase) + (voff)[_i]), (LAS unsigned*)(lds + (bufoff) + ldsw + _i * 8192), 16, 0, 0); } while (0)
; #define PG8_LDA(dst, b, h) do { _Pragma("unroll") for (int m = 0; m < 4; ++m) _Pragma("unroll") for (int k = 0; k < 2; ++k) dst[m][k] = *(const LAS h16x8*)(lds + PG8_SA(b, h) + aoff + m * 2048 + k * 1024); } while (0)
; #define PG8_LDB(dst, b, h) do { _Pragma("unroll") for (int n = 0; n < 2; ++n) _Pragma("unroll") for (int k = 0; k < 2; ++k) dst[n][k] = *(const LAS h16x8*)(lds + PG8_SB(b, h) + boff + n * 2048 + k * 1024); } while (0)
; #define PG8_MMA(ai, bj, At, Bt_) do { __builtin_amdgcn_s_setprio(1); _Pragma("unroll") for (int m = 0; m < 4; ++m) _Pragma("unroll") for (int n = 0; n < 2; ++n) _Pragma("unroll") for (int k = 0; k < 2; ++k) \
;         acc[ai][bj][m][n] = __builtin_amdgcn_mfma_f32_16x16x32_f16(Bt_[n][k], At[m][k], acc[ai][bj][m][n], 0, 0, 0); __builtin_amdgcn_s_setprio(0); } while (0)
; #define PG8_WAIT_L(n) asm volatile("s_waitcnt lgkmcnt(" #n ")" ::: "memory")
; #define PG8_BAR __builtin_amdgcn_s_barrier()
; #define PG8_SCHED __builtin_amdgcn_sched_barrier(0)
; template <class Epi, class AMap>
; __device__ __forceinline__ void gemm_phase(LAS unsigned char* lds, const AMap am, const int lda, const h16* Bt, const int ldb, const int M, const int N, const int K, const Epi& E) {
;     ...
;         for (int t = 0; t < nt; t += 2) {
;             const bool last = (t == nt - 2);
;             const char* a1 = cA + (size_t)(t + 1) * kstep;
;             const char* a2 = last ? nA : cA + (size_t)(t + 2) * kstep; const char* b2 = last ? nB : cB + (size_t)(t + 2) * kstep;
;             const char* a3 = a2 + kstep; const char* b3 = b2 + kstep;
;             PG8_LDB(B0, 0, 0); PG8_SCHED; PG8_LDA(At, 0, 0); PG8_STAGE(PG8_SA(1, 1), a1 + hstepA, voffA);
;             PG8_WAIT_L(8); PG8_BAR; PG8_WAIT_L(0); PG8_MMA(0, 0, At, B0); PG8_BAR; PG8_SCHED;
;             PG8_LDB(B1, 0, 1); PG8_STAGE(PG8_SB(0, 0), b2, voffB);
;             PG8_BAR; PG8_WAIT_L(0); PG8_MMA(0, 1, At, B1); PG8_BAR;
;             PG8_LDA(At, 0, 1); PG8_STAGE(PG8_SA(0, 0), a2, voffA);
;             PG8_BAR; PG8_WAIT_L(0); PG8_MMA(1, 0, At, B0); PG8_BAR; PG8_SCHED;
.LBB0_644:
	s_add_i32 s51, s26, 2
	s_add_u32 s0, s22, 0x100
	s_addc_u32 s1, s23, 0
	s_add_i32 s60, 0, 0x10000
	v_add_u32_e32 v234, s60, v203
	ds_read_b128 v[130:133], v234
	ds_read_b128 v[134:137], v234 offset:1024
	ds_read_b128 v[138:141], v234 offset:2048
	ds_read_b128 v[152:155], v234 offset:3072
	s_cmp_eq_u32 s80, s26
	s_cselect_b32 s26, s21, s29
	s_cselect_b32 s49, s47, s1
	s_cselect_b32 s48, s46, s0
	s_cselect_b32 s27, s20, s45
	v_lshl_add_u64 v[232:233], s[22:23], 0, v[148:149]
	s_add_i32 m0, s74, 0xc000
	ds_read_b128 v[156:159], v205
	ds_read_b128 v[160:163], v205 offset:1024
	ds_read_b128 v[164:167], v205 offset:2048
	ds_read_b128 v[168:171], v205 offset:3072
	ds_read_b128 v[172:175], v205 offset:4096
	ds_read_b128 v[176:179], v205 offset:5120
	ds_read_b128 v[180:183], v205 offset:6144
	ds_read_b128 v[184:187], v205 offset:7168
	global_load_lds_dwordx4 v[232:233], off
	v_lshl_add_u64 v[232:233], s[22:23], 0, v[150:151]
	s_add_i32 m0, s74, 0xe000
	s_nop 0
	global_load_lds_dwordx4 v[232:233], off
	s_waitcnt lgkmcnt(11)
	s_add_i32 s62, 0, 0x14000
	v_add_u32_e32 v200, s62, v203
	s_add_i32 s22, s60, s71
	ds_read_b128 v[188:191], v200
	ds_read_b128 v[192:195], v200 offset:1024
	ds_read_b128 v[196:199], v200 offset:2048
	ds_read_b128 v[220:223], v200 offset:3072
	s_waitcnt vmcnt(8) lgkmcnt(0)
	s_barrier
	v_mfma_f32_16x16x32_f16 v[122:125], v[130:133], v[156:159], v[122:125]
	v_mfma_f32_16x16x32_f16 v[126:129], v[138:141], v[156:159], v[126:129]
	v_mfma_f32_16x16x32_f16 v[110:113], v[130:133], v[164:167], v[110:113]
	v_mfma_f32_16x16x32_f16 v[106:109], v[138:141], v[164:167], v[106:109]
	v_mfma_f32_16x16x32_f16 v[94:97], v[130:133], v[172:175], v[94:97]
	v_mfma_f32_16x16x32_f16 v[90:93], v[138:141], v[172:175], v[90:93]
	v_mfma_f32_16x16x32_f16 v[78:81], v[130:133], v[180:183], v[78:81]
	v_mfma_f32_16x16x32_f16 v[74:77], v[138:141], v[180:183], v[74:77]
	v_mfma_f32_16x16x32_f16 v[122:125], v[134:137], v[160:163], v[122:125]
	v_mfma_f32_16x16x32_f16 v[126:129], v[152:155], v[160:163], v[126:129]
	v_mfma_f32_16x16x32_f16 v[110:113], v[134:137], v[168:171], v[110:113]
	v_mfma_f32_16x16x32_f16 v[106:109], v[152:155], v[168:171], v[106:109]
	v_mfma_f32_16x16x32_f16 v[94:97], v[134:137], v[176:179], v[94:97]
	v_mfma_f32_16x16x32_f16 v[90:93], v[152:155], v[176:179], v[90:93]
	v_mfma_f32_16x16x32_f16 v[78:81], v[134:137], v[184:187], v[78:81]
	v_mfma_f32_16x16x32_f16 v[74:77], v[152:155], v[184:187], v[74:77]
	v_mfma_f32_16x16x32_f16 v[118:121], v[188:191], v[156:159], v[118:121]
	v_mfma_f32_16x16x32_f16 v[114:117], v[196:199], v[156:159], v[114:117]
	v_mfma_f32_16x16x32_f16 v[102:105], v[188:191], v[164:167], v[102:105]
	v_mfma_f32_16x16x32_f16 v[98:101], v[196:199], v[164:167], v[98:101]
	v_mfma_f32_16x16x32_f16 v[86:89], v[188:191], v[172:175], v[86:89]
	v_mfma_f32_16x16x32_f16 v[82:85], v[196:199], v[172:175], v[82:85]
	v_mfma_f32_16x16x32_f16 v[70:73], v[188:191], v[180:183], v[70:73]
	v_mfma_f32_16x16x32_f16 v[66:69], v[196:199], v[180:183], v[66:69]
	v_mfma_f32_16x16x32_f16 v[118:121], v[192:195], v[160:163], v[118:121]
	v_mfma_f32_16x16x32_f16 v[114:117], v[220:223], v[160:163], v[114:117]
	v_mfma_f32_16x16x32_f16 v[102:105], v[192:195], v[168:171], v[102:105]
	v_mfma_f32_16x16x32_f16 v[98:101], v[220:223], v[168:171], v[98:101]
	v_mfma_f32_16x16x32_f16 v[86:89], v[192:195], v[176:179], v[86:89]
	v_mfma_f32_16x16x32_f16 v[82:85], v[220:223], v[176:179], v[82:85]
	v_mfma_f32_16x16x32_f16 v[70:73], v[192:195], v[184:187], v[70:73]
	v_mfma_f32_16x16x32_f16 v[66:69], v[220:223], v[184:187], v[66:69]
	s_barrier
	v_lshl_add_u64 v[200:201], s[26:27], 0, v[0:1]
	s_mov_b32 m0, s22
	v_lshl_add_u64 v[206:207], s[26:27], 0, v[146:147]
	global_load_lds_dwordx4 v[200:201], off
	s_add_i32 m0, s22, 0x2000
	s_nop 0
	global_load_lds_dwordx4 v[206:207], off
	s_mov_b32 m0, s74
	v_lshl_add_u64 v[212:213], s[48:49], 0, v[142:143]
	ds_read_b128 v[156:159], v205 offset:16384
	ds_read_b128 v[160:163], v205 offset:17408
	ds_read_b128 v[164:167], v205 offset:18432
	ds_read_b128 v[168:171], v205 offset:19456
	ds_read_b128 v[172:175], v205 offset:20480
	ds_read_b128 v[176:179], v205 offset:21504
	ds_read_b128 v[180:183], v205 offset:22528
	ds_read_b128 v[184:187], v205 offset:23552
	global_load_lds_dwordx4 v[212:213], off
	v_lshl_add_u64 v[224:225], s[48:49], 0, v[144:145]
	s_mov_b32 m0, s75
	s_nop 0
	global_load_lds_dwordx4 v[224:225], off
	s_add_u32 s22, s26, 0x10000
	s_addc_u32 s23, s27, 0
	s_add_i32 s60, s62, s71
	v_lshl_add_u64 v[232:233], s[22:23], 0, v[0:1]
	s_mov_b32 m0, s60
	s_nop 0
	global_load_lds_dwordx4 v[232:233], off
	v_lshl_add_u64 v[232:233], s[22:23], 0, v[146:147]
	s_add_i32 m0, s60, 0x2000
	s_nop 0
	global_load_lds_dwordx4 v[232:233], off
	s_waitcnt vmcnt(8) lgkmcnt(0)
	s_barrier
; #define PG8_STAGE(bufoff, gbase, voff) do { _Pragma("unroll") for (int _i = 0; _i < 2; ++_i) \
;         __builtin_amdgcn_global_load_lds((const unsigned*)((const char*)(gbase) + (voff)[_i]), (LAS unsigned*)(lds + (bufoff) + ldsw + _i * 8192), 16, 0, 0); } while (0)
; #define PG8_LDA(dst, b, h) do { _Pragma("unroll") for (int m = 0; m < 4; ++m) _Pragma("unroll") for (int k = 0; k < 2; ++k) dst[m][k] = *(const LAS h16x8*)(lds + PG8_SA(b, h) + aoff + m * 2048 + k * 1024); } while (0)
; #define PG8_LDB(dst, b, h) do { _Pragma("unroll") for (int n = 0; n < 2; ++n) _Pragma("unroll") for (int k = 0; k < 2; ++k) dst[n][k] = *(const LAS h16x8*)(lds + PG8_SB(b, h) + boff + n * 2048 + k * 1024); } while (0)
; #define PG8_MMA(ai, bj, At, Bt_) do { __builtin_amdgcn_s_setprio(1); _Pragma("unroll") for (int m = 0; m < 4; ++m) _Pragma("unroll") for (int n = 0; n < 2; ++n) _Pragma("unroll") for (int k = 0; k < 2; ++k) \
;         acc[ai][bj][m][n] = __builtin_amdgcn_mfma_f32_16x16x32_f16(Bt_[n][k], At[m][k], acc[ai][bj][m][n], 0, 0, 0); __builtin_amdgcn_s_setprio(0); } while (0)
; #define PG8_WAIT_V(n) asm volatile("s_waitcnt vmcnt(" #n ")" ::: "memory")
; #define PG8_WAIT_L(n) asm volatile("s_waitcnt lgkmcnt(" #n ")" ::: "memory")
; #define PG8_BAR __builtin_amdgcn_s_barrier()
; #define PG8_SCHED __builtin_amdgcn_sched_barrier(0)
; template <class Epi, class AMap>
; __device__ __forceinline__ void gemm_phase(LAS unsigned char* lds, const AMap am, const int lda, const h16* Bt, const int ldb, const int M, const int N, const int K, const Epi& E) {
;     ...
;             PG8_BAR; PG8_WAIT_L(0); PG8_MMA(1, 0, At, B0); PG8_BAR; PG8_SCHED;
;             PG8_STAGE(PG8_SB(0, 1), b2 + hstepB, voffB);
;             PG8_WAIT_V(6); PG8_BAR; PG8_MMA(1, 1, At, B1); PG8_BAR;
;             PG8_LDB(B0, 1, 0); PG8_SCHED; PG8_LDA(At, 1, 0); PG8_STAGE(PG8_SA(0, 1), a2 + hstepA, voffA);
;             PG8_WAIT_L(8); PG8_BAR; PG8_WAIT_L(0); PG8_MMA(0, 0, At, B0); PG8_BAR; PG8_SCHED;
;             PG8_LDB(B1, 1, 1); PG8_STAGE(PG8_SB(1, 0), b3, voffB);
;             PG8_BAR; PG8_WAIT_L(0); PG8_MMA(0, 1, At, B1); PG8_BAR;
;             PG8_LDA(At, 1, 1); PG8_STAGE(PG8_SA(1, 0), a3, voffA);
;             PG8_BAR; PG8_WAIT_L(0); PG8_MMA(1, 0, At, B0); PG8_BAR; PG8_SCHED;
	v_mfma_f32_16x16x32_f16 v[62:65], v[130:133], v[156:159], v[62:65]
	v_mfma_f32_16x16x32_f16 v[58:61], v[138:141], v[156:159], v[58:61]
	v_mfma_f32_16x16x32_f16 v[46:49], v[130:133], v[164:167], v[46:49]
	v_mfma_f32_16x16x32_f16 v[42:45], v[138:141], v[164:167], v[42:45]
	v_mfma_f32_16x16x32_f16 v[30:33], v[130:133], v[172:175], v[30:33]
	v_mfma_f32_16x16x32_f16 v[26:29], v[138:141], v[172:175], v[26:29]
	v_mfma_f32_16x16x32_f16 v[14:17], v[130:133], v[180:183], v[14:17]
	v_mfma_f32_16x16x32_f16 v[10:13], v[138:141], v[180:183], v[10:13]
	v_mfma_f32_16x16x32_f16 v[62:65], v[134:137], v[160:163], v[62:65]
	v_mfma_f32_16x16x32_f16 v[58:61], v[152:155], v[160:163], v[58:61]
	v_mfma_f32_16x16x32_f16 v[46:49], v[134:137], v[168:171], v[46:49]
	v_mfma_f32_16x16x32_f16 v[42:45], v[152:155], v[168:171], v[42:45]
	v_mfma_f32_16x16x32_f16 v[30:33], v[134:137], v[176:179], v[30:33]
	v_mfma_f32_16x16x32_f16 v[26:29], v[152:155], v[176:179], v[26:29]
	v_mfma_f32_16x16x32_f16 v[14:17], v[134:137], v[184:187], v[14:17]
	v_mfma_f32_16x16x32_f16 v[10:13], v[152:155], v[184:187], v[10:13]
	v_mfma_f32_16x16x32_f16 v[54:57], v[188:191], v[156:159], v[54:57]
	v_mfma_f32_16x16x32_f16 v[50:53], v[196:199], v[156:159], v[50:53]
	v_mfma_f32_16x16x32_f16 v[38:41], v[188:191], v[164:167], v[38:41]
	v_mfma_f32_16x16x32_f16 v[34:37], v[196:199], v[164:167], v[34:37]
	v_mfma_f32_16x16x32_f16 v[22:25], v[188:191], v[172:175], v[22:25]
	v_mfma_f32_16x16x32_f16 v[18:21], v[196:199], v[172:175], v[18:21]
	v_mfma_f32_16x16x32_f16 v[6:9], v[188:191], v[180:183], v[6:9]
	v_mfma_f32_16x16x32_f16 v[2:5], v[196:199], v[180:183], v[2:5]
	v_mfma_f32_16x16x32_f16 v[54:57], v[192:195], v[160:163], v[54:57]
	v_mfma_f32_16x16x32_f16 v[50:53], v[220:223], v[160:163], v[50:53]
	v_mfma_f32_16x16x32_f16 v[38:41], v[192:195], v[168:171], v[38:41]
	v_mfma_f32_16x16x32_f16 v[34:37], v[220:223], v[168:171], v[34:37]
	v_mfma_f32_16x16x32_f16 v[22:25], v[192:195], v[176:179], v[22:25]
	v_mfma_f32_16x16x32_f16 v[18:21], v[220:223], v[176:179], v[18:21]
	v_mfma_f32_16x16x32_f16 v[6:9], v[192:195], v[184:187], v[6:9]
	v_mfma_f32_16x16x32_f16 v[2:5], v[220:223], v[184:187], v[2:5]
	s_barrier
	s_add_i32 s60, 0, 0x18000
	v_add_u32_e32 v234, s60, v203
	ds_read_b128 v[130:133], v234
	ds_read_b128 v[134:137], v234 offset:1024
	ds_read_b128 v[138:141], v234 offset:2048
	ds_read_b128 v[152:155], v234 offset:3072
	s_add_u32 s22, s48, 0x1c0000
	s_addc_u32 s23, s49, 0
	s_mov_b32 m0, s76
	v_lshl_add_u64 v[232:233], s[22:23], 0, v[142:143]
	ds_read_b128 v[156:159], v205 offset:32768
	ds_read_b128 v[160:163], v205 offset:33792
	ds_read_b128 v[164:167], v205 offset:34816
	ds_read_b128 v[168:171], v205 offset:35840
	ds_read_b128 v[172:175], v205 offset:36864
	ds_read_b128 v[176:179], v205 offset:37888
	ds_read_b128 v[180:183], v205 offset:38912
	ds_read_b128 v[184:187], v205 offset:39936
	global_load_lds_dwordx4 v[232:233], off
	v_lshl_add_u64 v[232:233], s[22:23], 0, v[144:145]
	s_mov_b32 m0, s77
	s_nop 0
	global_load_lds_dwordx4 v[232:233], off
	s_waitcnt lgkmcnt(11)
	s_add_i32 s48, 0, 0x1c000
	s_add_i32 s22, s60, s71
	v_add_u32_e32 v214, s48, v203
	v_lshl_add_u64 v[200:201], v[200:201], 0, s[92:93]
	s_mov_b32 m0, s22
	ds_read_b128 v[188:191], v214
	ds_read_b128 v[192:195], v214 offset:1024
	ds_read_b128 v[196:199], v214 offset:2048
	ds_read_b128 v[220:223], v214 offset:3072
	s_waitcnt vmcnt(8) lgkmcnt(0)
	s_barrier
	v_mfma_f32_16x16x32_f16 v[122:125], v[130:133], v[156:159], v[122:125]
	v_mfma_f32_16x16x32_f16 v[126:129], v[138:141], v[156:159], v[126:129]
	v_mfma_f32_16x16x32_f16 v[110:113], v[130:133], v[164:167], v[110:113]
	v_mfma_f32_16x16x32_f16 v[106:109], v[138:141], v[164:167], v[106:109]
	v_mfma_f32_16x16x32_f16 v[94:97], v[130:133], v[172:175], v[94:97]
	v_mfma_f32_16x16x32_f16 v[90:93], v[138:141], v[172:175], v[90:93]
	v_mfma_f32_16x16x32_f16 v[78:81], v[130:133], v[180:183], v[78:81]
	v_mfma_f32_16x16x32_f16 v[74:77], v[138:141], v[180:183], v[74:77]
	v_mfma_f32_16x16x32_f16 v[122:125], v[134:137], v[160:163], v[122:125]
	v_mfma_f32_16x16x32_f16 v[126:129], v[152:155], v[160:163], v[126:129]
	v_mfma_f32_16x16x32_f16 v[110:113], v[134:137], v[168:171], v[110:113]
	v_mfma_f32_16x16x32_f16 v[106:109], v[152:155], v[168:171], v[106:109]
	v_mfma_f32_16x16x32_f16 v[94:97], v[134:137], v[176:179], v[94:97]
	v_mfma_f32_16x16x32_f16 v[90:93], v[152:155], v[176:179], v[90:93]
	v_mfma_f32_16x16x32_f16 v[78:81], v[134:137], v[184:187], v[78:81]
	v_mfma_f32_16x16x32_f16 v[74:77], v[152:155], v[184:187], v[74:77]
	v_mfma_f32_16x16x32_f16 v[118:121], v[188:191], v[156:159], v[118:121]
	v_mfma_f32_16x16x32_f16 v[114:117], v[196:199], v[156:159], v[114:117]
	v_mfma_f32_16x16x32_f16 v[102:105], v[188:191], v[164:167], v[102:105]
	v_mfma_f32_16x16x32_f16 v[98:101], v[196:199], v[164:167], v[98:101]
	v_mfma_f32_16x16x32_f16 v[86:89], v[188:191], v[172:175], v[86:89]
	v_mfma_f32_16x16x32_f16 v[82:85], v[196:199], v[172:175], v[82:85]
	v_mfma_f32_16x16x32_f16 v[70:73], v[188:191], v[180:183], v[70:73]
	v_mfma_f32_16x16x32_f16 v[66:69], v[196:199], v[180:183], v[66:69]
	v_mfma_f32_16x16x32_f16 v[118:121], v[192:195], v[160:163], v[118:121]
	v_mfma_f32_16x16x32_f16 v[114:117], v[220:223], v[160:163], v[114:117]
	v_mfma_f32_16x16x32_f16 v[102:105], v[192:195], v[168:171], v[102:105]
	v_mfma_f32_16x16x32_f16 v[98:101], v[220:223], v[168:171], v[98:101]
	v_mfma_f32_16x16x32_f16 v[86:89], v[192:195], v[176:179], v[86:89]
	v_mfma_f32_16x16x32_f16 v[82:85], v[220:223], v[176:179], v[82:85]
	v_mfma_f32_16x16x32_f16 v[70:73], v[192:195], v[184:187], v[70:73]
	v_mfma_f32_16x16x32_f16 v[66:69], v[220:223], v[184:187], v[66:69]
	s_barrier
; #define PG8_STAGE(bufoff, gbase, voff) do { _Pragma("unroll") for (int _i = 0; _i < 2; ++_i) \
;         __builtin_amdgcn_global_load_lds((const unsigned*)((const char*)(gbase) + (voff)[_i]), (LAS unsigned*)(lds + (bufoff) + ldsw + _i * 8192), 16, 0, 0); } while (0)
; #define PG8_LDA(dst, b, h) do { _Pragma("unroll") for (int m = 0; m < 4; ++m) _Pragma("unroll") for (int k = 0; k < 2; ++k) dst[m][k] = *(const LAS h16x8*)(lds + PG8_SA(b, h) + aoff + m * 2048 + k * 1024); } while (0)
; #define PG8_MMA(ai, bj, At, Bt_) do { __builtin_amdgcn_s_setprio(1); _Pragma("unroll") for (int m = 0; m < 4; ++m) _Pragma("unroll") for (int n = 0; n < 2; ++n) _Pragma("unroll") for (int k = 0; k < 2; ++k) \
;         acc[ai][bj][m][n] = __builtin_amdgcn_mfma_f32_16x16x32_f16(Bt_[n][k], At[m][k], acc[ai][bj][m][n], 0, 0, 0); __builtin_amdgcn_s_setprio(0); } while (0)
; #define PG8_WAIT_V(n) asm volatile("s_waitcnt vmcnt(" #n ")" ::: "memory")
; #define PG8_WAIT_L(n) asm volatile("s_waitcnt lgkmcnt(" #n ")" ::: "memory")
; #define PG8_BAR __builtin_amdgcn_s_barrier()
; #define PG8_SCHED __builtin_amdgcn_sched_barrier(0)
; template <class Epi, class AMap>
; __device__ __forceinline__ void gemm_phase(LAS unsigned char* lds, const AMap am, const int lda, const h16* Bt, const int ldb, const int M, const int N, const int K, const Epi& E) {
;     ...
;             PG8_LDA(At, 1, 1); PG8_STAGE(PG8_SA(1, 0), a3, voffA);
;             PG8_BAR; PG8_WAIT_L(0); PG8_MMA(1, 0, At, B0); PG8_BAR; PG8_SCHED;
;             PG8_STAGE(PG8_SB(1, 1), b3 + hstepB, voffB);
;             PG8_WAIT_V(6); PG8_BAR; PG8_MMA(1, 1, At, B1); PG8_BAR;
;         }
;         E(acc, cur, wr, wc, fr, fq);
	global_load_lds_dwordx4 v[200:201], off
	v_lshl_add_u64 v[200:201], v[206:207], 0, s[92:93]
	s_add_i32 m0, s22, 0x2000
	s_nop 0
	global_load_lds_dwordx4 v[200:201], off
	s_mov_b32 m0, s78
	v_lshl_add_u64 v[200:201], v[212:213], 0, s[92:93]
	ds_read_b128 v[156:159], v205 offset:49152
	ds_read_b128 v[160:163], v205 offset:50176
	ds_read_b128 v[164:167], v205 offset:51200
	ds_read_b128 v[168:171], v205 offset:52224
	ds_read_b128 v[172:175], v205 offset:53248
	ds_read_b128 v[176:179], v205 offset:54272
	ds_read_b128 v[180:183], v205 offset:55296
	ds_read_b128 v[184:187], v205 offset:56320
	global_load_lds_dwordx4 v[200:201], off
	v_lshl_add_u64 v[200:201], v[224:225], 0, s[92:93]
	s_mov_b32 m0, s79
	s_nop 0
	global_load_lds_dwordx4 v[200:201], off
	s_add_u32 s22, s26, 0x10080
	s_addc_u32 s23, s27, 0
	s_add_i32 s26, s48, s71
	v_lshl_add_u64 v[232:233], s[22:23], 0, v[0:1]
	s_mov_b32 m0, s26
	s_nop 0
	global_load_lds_dwordx4 v[232:233], off
	v_lshl_add_u64 v[232:233], s[22:23], 0, v[146:147]
	s_add_i32 m0, s26, 0x2000
	s_nop 0
	global_load_lds_dwordx4 v[232:233], off
	s_waitcnt vmcnt(8) lgkmcnt(0)
	s_barrier
	v_mfma_f32_16x16x32_f16 v[62:65], v[130:133], v[156:159], v[62:65]
	v_mfma_f32_16x16x32_f16 v[58:61], v[138:141], v[156:159], v[58:61]
	v_mfma_f32_16x16x32_f16 v[46:49], v[130:133], v[164:167], v[46:49]
	v_mfma_f32_16x16x32_f16 v[42:45], v[138:141], v[164:167], v[42:45]
	v_mfma_f32_16x16x32_f16 v[30:33], v[130:133], v[172:175], v[30:33]
	v_mfma_f32_16x16x32_f16 v[26:29], v[138:141], v[172:175], v[26:29]
	v_mfma_f32_16x16x32_f16 v[14:17], v[130:133], v[180:183], v[14:17]
	v_mfma_f32_16x16x32_f16 v[10:13], v[138:141], v[180:183], v[10:13]
	v_mfma_f32_16x16x32_f16 v[62:65], v[134:137], v[160:163], v[62:65]
	v_mfma_f32_16x16x32_f16 v[58:61], v[152:155], v[160:163], v[58:61]
	v_mfma_f32_16x16x32_f16 v[46:49], v[134:137], v[168:171], v[46:49]
	v_mfma_f32_16x16x32_f16 v[42:45], v[152:155], v[168:171], v[42:45]
	v_mfma_f32_16x16x32_f16 v[30:33], v[134:137], v[176:179], v[30:33]
	v_mfma_f32_16x16x32_f16 v[26:29], v[152:155], v[176:179], v[26:29]
	v_mfma_f32_16x16x32_f16 v[14:17], v[134:137], v[184:187], v[14:17]
	v_mfma_f32_16x16x32_f16 v[10:13], v[152:155], v[184:187], v[10:13]
	v_mfma_f32_16x16x32_f16 v[54:57], v[188:191], v[156:159], v[54:57]
	v_mfma_f32_16x16x32_f16 v[50:53], v[196:199], v[156:159], v[50:53]
	v_mfma_f32_16x16x32_f16 v[38:41], v[188:191], v[164:167], v[38:41]
	v_mfma_f32_16x16x32_f16 v[34:37], v[196:199], v[164:167], v[34:37]
	v_mfma_f32_16x16x32_f16 v[22:25], v[188:191], v[172:175], v[22:25]
	v_mfma_f32_16x16x32_f16 v[18:21], v[196:199], v[172:175], v[18:21]
	v_mfma_f32_16x16x32_f16 v[6:9], v[188:191], v[180:183], v[6:9]
	v_mfma_f32_16x16x32_f16 v[2:5], v[196:199], v[180:183], v[2:5]
	v_mfma_f32_16x16x32_f16 v[54:57], v[192:195], v[160:163], v[54:57]
	v_mfma_f32_16x16x32_f16 v[50:53], v[220:223], v[160:163], v[50:53]
	v_mfma_f32_16x16x32_f16 v[38:41], v[192:195], v[168:171], v[38:41]
	v_mfma_f32_16x16x32_f16 v[34:37], v[220:223], v[168:171], v[34:37]
	v_mfma_f32_16x16x32_f16 v[22:25], v[192:195], v[176:179], v[22:25]
	v_mfma_f32_16x16x32_f16 v[18:21], v[220:223], v[176:179], v[18:21]
	v_mfma_f32_16x16x32_f16 v[6:9], v[192:195], v[184:187], v[6:9]
	v_mfma_f32_16x16x32_f16 v[2:5], v[220:223], v[184:187], v[2:5]
	s_add_u32 s29, s29, 0x100
	s_addc_u32 s45, s45, 0
	s_cmp_ge_i32 s51, s24
	s_mov_b64 s[22:23], s[0:1]
	s_mov_b32 s26, s51
	s_barrier
	s_cbranch_scc0 .LBB0_644
	s_cmpk_gt_u32 s69, 0xff
	s_cbranch_scc1 .Lgx5
	s_barrier

; __device__ __forceinline__ float sigmoidf_(float x) { return 1.0f / (1.0f + __expf(-x)); }
; template <class Epi, class AMap>
; __device__ __forceinline__ void gemm_phase(LAS unsigned char* lds, const AMap am, const int lda, const h16* Bt, const int ldb, const int M, const int N, const int K, const Epi& E) {
;     ...
;         if (!has_next) break;
; #pragma unroll
;         for (int a = 0; a < 2; ++a)
; #pragma unroll
;             for (int b = 0; b < 2; ++b)
; #pragma unroll
;                 for (int m = 0; m < 4; ++m)
; #pragma unroll
;                     for (int n = 0; n < 2; ++n) acc[a][b][m][n] = (f32x4){0.f, 0.f, 0.f, 0.f};
;         cur = nxt; cA = nA; cB = nB; ++ui;
;     template <int GI>
;     __device__ __forceinline__ void body(const f32x4 (&acc)[2][2][4][2], int row0, int colt) const {
;     ...
;             for (int ai = 0; ai < 2; ++ai)
; #pragma unroll
;                 for (int m = 0; m < 4; ++m) {
;                     const size_t row = (size_t)(row0 + ai * 128 + m * 16);
;                     f32x4 x0 = acc[ai][bj][m][0] + b0, x1 = acc[ai][bj][m][1] + b1;
;                     if (GI == 0) {
; #pragma unroll
;                         for (int j = 0; j < 4; ++j) {
;                             x0[j] = 0.6065306597126334f * sigmoidf_(x0[j]); x1[j] = 0.6065306597126334f * sigmoidf_(x1[j]); }
;                         *(u32x4*)(DEC + row * DM + c) = pack8(x0, x1);
;                     } else if (GI == 1) {
; #pragma unroll
;                         for (int j = 0; j < 4; ++j) { x0[j] = sigmoidf_(x0[j]); x1[j] = sigmoidf_(x1[j]); }
;                         *(u32x4*)(Ab + row * DM + c) = pack8(x0, x1);
;                     } else if (GI == 2) {
;                         *(u32x4*)(Gb + row * DM + c) = pack8(x0, x1);
.LBB0_656:
	v_lshl_add_u32 v70, s74, 8, v160
	v_lshl_or_b32 v72, s76, 8, v162
	v_ashrrev_i32_e32 v71, 31, v70
	v_ashrrev_i32_e32 v73, 31, v72
	v_lshlrev_b64 v[78:79], 12, v[70:71]
	v_lshl_add_u64 v[78:79], s[2:3], 0, v[78:79]
	v_lshlrev_b64 v[72:73], 1, v[72:73]
	v_cvt_pk_f16_f32 v65, v124, v125
	v_cvt_pk_f16_f32 v64, v122, v123
	v_cvt_pk_f16_f32 v63, v128, v129
	v_cvt_pk_f16_f32 v62, v126, v127
	v_lshl_add_u64 v[78:79], v[78:79], 0, v[72:73]
	global_store_dwordx4 v[78:79], v[62:65], off
	v_or_b32_e32 v80, 16, v70
	v_ashrrev_i32_e32 v81, 31, v80
	v_lshlrev_b64 v[80:81], 12, v[80:81]
	v_lshl_add_u64 v[80:81], s[2:3], 0, v[80:81]
	v_cvt_pk_f16_f32 v65, v116, v117
	v_cvt_pk_f16_f32 v64, v114, v115
	v_cvt_pk_f16_f32 v63, v120, v121
	v_cvt_pk_f16_f32 v62, v118, v119
	v_lshl_add_u64 v[80:81], v[80:81], 0, v[72:73]
	global_store_dwordx4 v[80:81], v[62:65], off
	v_or_b32_e32 v86, 32, v70
	v_ashrrev_i32_e32 v87, 31, v86
	v_lshlrev_b64 v[86:87], 12, v[86:87]
	v_lshl_add_u64 v[86:87], s[2:3], 0, v[86:87]
	v_cvt_pk_f16_f32 v65, v108, v109
	v_cvt_pk_f16_f32 v64, v106, v107
	v_cvt_pk_f16_f32 v63, v112, v113
	v_cvt_pk_f16_f32 v62, v110, v111
	v_lshl_add_u64 v[86:87], v[86:87], 0, v[72:73]
	global_store_dwordx4 v[86:87], v[62:65], off
	v_or_b32_e32 v70, 48, v70
	v_ashrrev_i32_e32 v71, 31, v70
	v_lshlrev_b64 v[70:71], 12, v[70:71]
	v_lshl_add_u64 v[70:71], s[2:3], 0, v[70:71]
	v_cvt_pk_f16_f32 v65, v100, v101
	v_cvt_pk_f16_f32 v64, v98, v99
	v_cvt_pk_f16_f32 v63, v104, v105
	v_cvt_pk_f16_f32 v62, v102, v103
	v_lshl_add_u64 v[70:71], v[70:71], 0, v[72:73]
	global_store_dwordx4 v[70:71], v[62:65], off
	s_mov_b32 s0, 0x80000
	v_add_co_u32_e32 v88, vcc, s0, v78
	v_cvt_pk_f16_f32 v65, v144, v145
	v_cvt_pk_f16_f32 v64, v152, v153
	v_cvt_pk_f16_f32 v63, v92, v93
	v_cvt_pk_f16_f32 v62, v90, v91
	v_addc_co_u32_e32 v89, vcc, 0, v79, vcc
	v_lshl_add_u64 v[72:73], v[78:79], 0, s[96:97]
	global_store_dwordx4 v[88:89], v[62:65], off
	s_mov_b32 s0, 0x90000
	s_nop 0
	v_cvt_pk_f16_f32 v62, v84, v85
	v_add_co_u32_e32 v84, vcc, s0, v78
	v_cvt_pk_f16_f32 v65, v146, v147
	v_cvt_pk_f16_f32 v64, v154, v155
	v_cvt_pk_f16_f32 v63, v76, v77
	v_addc_co_u32_e32 v85, vcc, 0, v79, vcc
	v_lshl_add_u64 v[76:77], v[78:79], 0, s[18:19]
	global_store_dwordx4 v[84:85], v[62:65], off
	s_mov_b32 s0, 0xa0000
	v_add_co_u32_e32 v84, vcc, s0, v78
	v_cvt_pk_f16_f32 v65, v148, v149
	v_cvt_pk_f16_f32 v64, v156, v157
	v_cvt_pk_f16_f32 v63, v74, v75
	v_cvt_pk_f16_f32 v62, v140, v141
	v_addc_co_u32_e32 v85, vcc, 0, v79, vcc
	v_lshl_add_u64 v[74:75], v[78:79], 0, s[14:15]
	global_store_dwordx4 v[84:85], v[62:65], off
	s_mov_b32 s0, 0xb0000
	v_add_co_u32_e32 v84, vcc, s0, v78
	v_cvt_pk_f16_f32 v65, v150, v151
	v_cvt_pk_f16_f32 v64, v158, v159
	v_cvt_pk_f16_f32 v63, v82, v83
	v_cvt_pk_f16_f32 v62, v142, v143
	v_addc_co_u32_e32 v85, vcc, 0, v79, vcc
	v_lshl_add_u64 v[82:83], v[78:79], 0, s[16:17]
	global_store_dwordx4 v[84:85], v[62:65], off
	s_nop 1
	v_cvt_pk_f16_f32 v65, v50, v51
	v_cvt_pk_f16_f32 v64, v52, v53
	v_cvt_pk_f16_f32 v63, v34, v35
	v_cvt_pk_f16_f32 v62, v36, v37
	global_store_dwordx4 v[78:79], v[62:65], off offset:256
	v_cvt_pk_f16_f32 v37, v66, v67
	v_cvt_pk_f16_f32 v36, v68, v69
	v_cvt_pk_f16_f32 v35, v42, v43
	v_cvt_pk_f16_f32 v34, v44, v45
	global_store_dwordx4 v[80:81], v[34:37], off offset:256
	s_nop 1
	v_cvt_pk_f16_f32 v37, v56, v57
	v_cvt_pk_f16_f32 v36, v54, v55
	v_cvt_pk_f16_f32 v35, v58, v59
	v_cvt_pk_f16_f32 v34, v60, v61
	global_store_dwordx4 v[86:87], v[34:37], off offset:256
	s_nop 1
	v_cvt_pk_f16_f32 v37, v40, v41
	v_cvt_pk_f16_f32 v36, v38, v39
	v_cvt_pk_f16_f32 v35, v48, v49
	v_cvt_pk_f16_f32 v34, v46, v47
	global_store_dwordx4 v[70:71], v[34:37], off offset:256
	v_cvt_pk_f16_f32 v29, v28, v29
	v_cvt_pk_f16_f32 v28, v26, v27
	v_cvt_pk_f16_f32 v27, v32, v33
	v_cvt_pk_f16_f32 v26, v30, v31
	global_store_dwordx4 v[72:73], v[26:29], off offset:256
	v_cvt_pk_f16_f32 v21, v20, v21
	v_cvt_pk_f16_f32 v20, v18, v19
	v_cvt_pk_f16_f32 v19, v24, v25
	v_cvt_pk_f16_f32 v18, v22, v23
	global_store_dwordx4 v[76:77], v[18:21], off offset:256
	v_cvt_pk_f16_f32 v13, v12, v13
	v_cvt_pk_f16_f32 v12, v10, v11
	v_cvt_pk_f16_f32 v11, v16, v17
	v_cvt_pk_f16_f32 v10, v14, v15
	global_store_dwordx4 v[74:75], v[10:13], off offset:256
	v_cvt_pk_f16_f32 v5, v4, v5
	v_cvt_pk_f16_f32 v4, v2, v3
	v_cvt_pk_f16_f32 v3, v8, v9
	v_cvt_pk_f16_f32 v2, v6, v7
	global_store_dwordx4 v[82:83], v[2:5], off offset:256
	s_and_b64 vcc, exec, s[38:39]
	s_mov_b32 s76, s26
	s_mov_b32 s74, s77
	s_mov_b64 s[46:47], s[42:43]
	s_mov_b64 s[44:45], s[40:41]
	s_cmpk_lt_u32 s50, 0x100
	s_cbranch_scc1 .Lgy6
	s_barrier

; #define PG8_STAGE(bufoff, gbase, voff) do { _Pragma("unroll") for (int _i = 0; _i < 2; ++_i) \
;         __builtin_amdgcn_global_load_lds((const unsigned*)((const char*)(gbase) + (voff)[_i]), (LAS unsigned*)(lds + (bufoff) + ldsw + _i * 8192), 16, 0, 0); } while (0)
; #define PG8_LDA(dst, b, h) do { _Pragma("unroll") for (int m = 0; m < 4; ++m) _Pragma("unroll") for (int k = 0; k < 2; ++k) dst[m][k] = *(const LAS h16x8*)(lds + PG8_SA(b, h) + aoff + m * 2048 + k * 1024); } while (0)
; #define PG8_LDB(dst, b, h) do { _Pragma("unroll") for (int n = 0; n < 2; ++n) _Pragma("unroll") for (int k = 0; k < 2; ++k) dst[n][k] = *(const LAS h16x8*)(lds + PG8_SB(b, h) + boff + n * 2048 + k * 1024); } while (0)
; #define PG8_MMA(ai, bj, At, Bt_) do { __builtin_amdgcn_s_setprio(1); _Pragma("unroll") for (int m = 0; m < 4; ++m) _Pragma("unroll") for (int n = 0; n < 2; ++n) _Pragma("unroll") for (int k = 0; k < 2; ++k) \
;         acc[ai][bj][m][n] = __builtin_amdgcn_mfma_f32_16x16x32_f16(Bt_[n][k], At[m][k], acc[ai][bj][m][n], 0, 0, 0); __builtin_amdgcn_s_setprio(0); } while (0)
; #define PG8_WAIT_V(n) asm volatile("s_waitcnt vmcnt(" #n ")" ::: "memory")
; #define PG8_WAIT_L(n) asm volatile("s_waitcnt lgkmcnt(" #n ")" ::: "memory")
; #define PG8_BAR __builtin_amdgcn_s_barrier()
; #define PG8_SCHED __builtin_amdgcn_sched_barrier(0)
; template <class Epi, class AMap>
; __device__ __forceinline__ void gemm_phase(LAS unsigned char* lds, const AMap am, const int lda, const h16* Bt, const int ldb, const int M, const int N, const int K, const Epi& E) {
;     ...
;             PG8_LDB(B0, 0, 0); PG8_SCHED; PG8_LDA(At, 0, 0); PG8_STAGE(PG8_SA(1, 1), a1 + hstepA, voffA);
;             PG8_WAIT_L(8); PG8_BAR; PG8_WAIT_L(0); PG8_MMA(0, 0, At, B0); PG8_BAR; PG8_SCHED;
;             PG8_LDB(B1, 0, 1); PG8_STAGE(PG8_SB(0, 0), b2, voffB);
;             PG8_BAR; PG8_WAIT_L(0); PG8_MMA(0, 1, At, B1); PG8_BAR;
;             PG8_LDA(At, 0, 1); PG8_STAGE(PG8_SA(0, 0), a2, voffA);
;             PG8_BAR; PG8_WAIT_L(0); PG8_MMA(1, 0, At, B0); PG8_BAR; PG8_SCHED;
;             PG8_STAGE(PG8_SB(0, 1), b2 + hstepB, voffB);
;             PG8_WAIT_V(6); PG8_BAR; PG8_MMA(1, 1, At, B1); PG8_BAR;
.LBB0_667:
	s_add_i32 s60, s46, 2
	s_add_u32 s0, s44, 0x100
	s_addc_u32 s1, s45, 0
	s_add_i32 s66, 0, 0x10000
	v_add_u32_e32 v234, s66, v161
	ds_read_b128 v[140:143], v234
	ds_read_b128 v[144:147], v234 offset:1024
	ds_read_b128 v[148:151], v234 offset:2048
	ds_read_b128 v[152:155], v234 offset:3072
	s_cmp_eq_u32 s73, s46
	s_cselect_b32 s46, s21, s27
	s_cselect_b32 s49, s41, s1
	s_cselect_b32 s48, s40, s0
	s_cselect_b32 s47, s20, s29
	v_lshl_add_u64 v[232:233], s[44:45], 0, v[136:137]
	s_add_i32 m0, s65, 0xc000
	ds_read_b128 v[156:159], v163
	ds_read_b128 v[164:167], v163 offset:1024
	ds_read_b128 v[168:171], v163 offset:2048
	ds_read_b128 v[172:175], v163 offset:3072
	ds_read_b128 v[176:179], v163 offset:4096
	ds_read_b128 v[180:183], v163 offset:5120
	ds_read_b128 v[184:187], v163 offset:6144
	ds_read_b128 v[188:191], v163 offset:7168
	global_load_lds_dwordx4 v[232:233], off
	v_lshl_add_u64 v[232:233], s[44:45], 0, v[138:139]
	s_add_i32 m0, s65, 0xe000
	s_nop 0
	global_load_lds_dwordx4 v[232:233], off
	s_waitcnt lgkmcnt(11)
	s_add_i32 s78, 0, 0x14000
	s_add_i32 s44, s66, s62
	v_add_u32_e32 v234, s78, v161
	v_lshl_add_u64 v[212:213], s[46:47], 0, v[0:1]
	s_mov_b32 m0, s44
	ds_read_b128 v[192:195], v234
	ds_read_b128 v[196:199], v234 offset:1024
	ds_read_b128 v[200:203], v234 offset:2048
	ds_read_b128 v[204:207], v234 offset:3072
	s_waitcnt vmcnt(8) lgkmcnt(0)
	s_barrier
	v_mfma_f32_16x16x32_f16 v[126:129], v[140:143], v[156:159], v[126:129]
	v_mfma_f32_16x16x32_f16 v[122:125], v[148:151], v[156:159], v[122:125]
	v_mfma_f32_16x16x32_f16 v[118:121], v[140:143], v[168:171], v[118:121]
	v_mfma_f32_16x16x32_f16 v[114:117], v[148:151], v[168:171], v[114:117]
	v_mfma_f32_16x16x32_f16 v[110:113], v[140:143], v[176:179], v[110:113]
	v_mfma_f32_16x16x32_f16 v[106:109], v[148:151], v[176:179], v[106:109]
	v_mfma_f32_16x16x32_f16 v[102:105], v[140:143], v[184:187], v[102:105]
	v_mfma_f32_16x16x32_f16 v[98:101], v[148:151], v[184:187], v[98:101]
	v_mfma_f32_16x16x32_f16 v[126:129], v[144:147], v[164:167], v[126:129]
	v_mfma_f32_16x16x32_f16 v[122:125], v[152:155], v[164:167], v[122:125]
	v_mfma_f32_16x16x32_f16 v[118:121], v[144:147], v[172:175], v[118:121]
	v_mfma_f32_16x16x32_f16 v[114:117], v[152:155], v[172:175], v[114:117]
	v_mfma_f32_16x16x32_f16 v[110:113], v[144:147], v[180:183], v[110:113]
	v_mfma_f32_16x16x32_f16 v[106:109], v[152:155], v[180:183], v[106:109]
	v_mfma_f32_16x16x32_f16 v[102:105], v[144:147], v[188:191], v[102:105]
	v_mfma_f32_16x16x32_f16 v[98:101], v[152:155], v[188:191], v[98:101]
	v_mfma_f32_16x16x32_f16 v[94:97], v[192:195], v[156:159], v[94:97]
	v_mfma_f32_16x16x32_f16 v[86:89], v[200:203], v[156:159], v[86:89]
	v_mfma_f32_16x16x32_f16 v[78:81], v[192:195], v[168:171], v[78:81]
	v_mfma_f32_16x16x32_f16 v[70:73], v[200:203], v[168:171], v[70:73]
	v_mfma_f32_16x16x32_f16 v[62:65], v[192:195], v[176:179], v[62:65]
	v_mfma_f32_16x16x32_f16 v[54:57], v[200:203], v[176:179], v[54:57]
	v_mfma_f32_16x16x32_f16 v[46:49], v[192:195], v[184:187], v[46:49]
	v_mfma_f32_16x16x32_f16 v[38:41], v[200:203], v[184:187], v[38:41]
	v_mfma_f32_16x16x32_f16 v[94:97], v[196:199], v[164:167], v[94:97]
	v_mfma_f32_16x16x32_f16 v[86:89], v[204:207], v[164:167], v[86:89]
	v_mfma_f32_16x16x32_f16 v[78:81], v[196:199], v[172:175], v[78:81]
	v_mfma_f32_16x16x32_f16 v[70:73], v[204:207], v[172:175], v[70:73]
	v_mfma_f32_16x16x32_f16 v[62:65], v[196:199], v[180:183], v[62:65]
	v_mfma_f32_16x16x32_f16 v[54:57], v[204:207], v[180:183], v[54:57]
	v_mfma_f32_16x16x32_f16 v[46:49], v[196:199], v[188:191], v[46:49]
	v_mfma_f32_16x16x32_f16 v[38:41], v[204:207], v[188:191], v[38:41]
	s_barrier
	global_load_lds_dwordx4 v[212:213], off
	v_lshl_add_u64 v[220:221], s[46:47], 0, v[134:135]
	s_add_i32 m0, s44, 0x2000
	s_nop 0
	global_load_lds_dwordx4 v[220:221], off
	s_mov_b32 m0, s65
	v_lshl_add_u64 v[222:223], s[48:49], 0, v[130:131]
	ds_read_b128 v[156:159], v163 offset:16384
	ds_read_b128 v[164:167], v163 offset:17408
	ds_read_b128 v[168:171], v163 offset:18432
	ds_read_b128 v[172:175], v163 offset:19456
	ds_read_b128 v[176:179], v163 offset:20480
	ds_read_b128 v[180:183], v163 offset:21504
	ds_read_b128 v[184:187], v163 offset:22528
	ds_read_b128 v[188:191], v163 offset:23552
	global_load_lds_dwordx4 v[222:223], off
	v_lshl_add_u64 v[224:225], s[48:49], 0, v[132:133]
	s_mov_b32 m0, s68
	s_nop 0
	global_load_lds_dwordx4 v[224:225], off
	s_add_u32 s44, s46, 0x10000
	s_addc_u32 s45, s47, 0
	s_add_i32 s66, s78, s62
	v_lshl_add_u64 v[232:233], s[44:45], 0, v[0:1]
	s_mov_b32 m0, s66
	s_nop 0
	global_load_lds_dwordx4 v[232:233], off
	v_lshl_add_u64 v[232:233], s[44:45], 0, v[134:135]
	s_add_i32 m0, s66, 0x2000
	s_nop 0
	global_load_lds_dwordx4 v[232:233], off
	s_waitcnt vmcnt(8) lgkmcnt(0)
	s_barrier
; #define PG8_STAGE(bufoff, gbase, voff) do { _Pragma("unroll") for (int _i = 0; _i < 2; ++_i) \
;         __builtin_amdgcn_global_load_lds((const unsigned*)((const char*)(gbase) + (voff)[_i]), (LAS unsigned*)(lds + (bufoff) + ldsw + _i * 8192), 16, 0, 0); } while (0)
; #define PG8_LDA(dst, b, h) do { _Pragma("unroll") for (int m = 0; m < 4; ++m) _Pragma("unroll") for (int k = 0; k < 2; ++k) dst[m][k] = *(const LAS h16x8*)(lds + PG8_SA(b, h) + aoff + m * 2048 + k * 1024); } while (0)
; #define PG8_LDB(dst, b, h) do { _Pragma("unroll") for (int n = 0; n < 2; ++n) _Pragma("unroll") for (int k = 0; k < 2; ++k) dst[n][k] = *(const LAS h16x8*)(lds + PG8_SB(b, h) + boff + n * 2048 + k * 1024); } while (0)
; #define PG8_MMA(ai, bj, At, Bt_) do { __builtin_amdgcn_s_setprio(1); _Pragma("unroll") for (int m = 0; m < 4; ++m) _Pragma("unroll") for (int n = 0; n < 2; ++n) _Pragma("unroll") for (int k = 0; k < 2; ++k) \
;         acc[ai][bj][m][n] = __builtin_amdgcn_mfma_f32_16x16x32_f16(Bt_[n][k], At[m][k], acc[ai][bj][m][n], 0, 0, 0); __builtin_amdgcn_s_setprio(0); } while (0)
; #define PG8_WAIT_V(n) asm volatile("s_waitcnt vmcnt(" #n ")" ::: "memory")
; #define PG8_WAIT_L(n) asm volatile("s_waitcnt lgkmcnt(" #n ")" ::: "memory")
; #define PG8_BAR __builtin_amdgcn_s_barrier()
; #define PG8_SCHED __builtin_amdgcn_sched_barrier(0)
; template <class Epi, class AMap>
; __device__ __forceinline__ void gemm_phase(LAS unsigned char* lds, const AMap am, const int lda, const h16* Bt, const int ldb, const int M, const int N, const int K, const Epi& E) {
;     ...
;             PG8_WAIT_V(6); PG8_BAR; PG8_MMA(1, 1, At, B1); PG8_BAR;
;             PG8_LDB(B0, 1, 0); PG8_SCHED; PG8_LDA(At, 1, 0); PG8_STAGE(PG8_SA(0, 1), a2 + hstepA, voffA);
;             PG8_WAIT_L(8); PG8_BAR; PG8_WAIT_L(0); PG8_MMA(0, 0, At, B0); PG8_BAR; PG8_SCHED;
;             PG8_LDB(B1, 1, 1); PG8_STAGE(PG8_SB(1, 0), b3, voffB);
;             PG8_BAR; PG8_WAIT_L(0); PG8_MMA(0, 1, At, B1); PG8_BAR;
;             PG8_LDA(At, 1, 1); PG8_STAGE(PG8_SA(1, 0), a3, voffA);
;             PG8_BAR; PG8_WAIT_L(0); PG8_MMA(1, 0, At, B0); PG8_BAR; PG8_SCHED;
	v_mfma_f32_16x16x32_f16 v[90:93], v[140:143], v[156:159], v[90:93]
	v_mfma_f32_16x16x32_f16 v[82:85], v[148:151], v[156:159], v[82:85]
	v_mfma_f32_16x16x32_f16 v[74:77], v[140:143], v[168:171], v[74:77]
	v_mfma_f32_16x16x32_f16 v[66:69], v[148:151], v[168:171], v[66:69]
	v_mfma_f32_16x16x32_f16 v[58:61], v[140:143], v[176:179], v[58:61]
	v_mfma_f32_16x16x32_f16 v[50:53], v[148:151], v[176:179], v[50:53]
	v_mfma_f32_16x16x32_f16 v[42:45], v[140:143], v[184:187], v[42:45]
	v_mfma_f32_16x16x32_f16 v[34:37], v[148:151], v[184:187], v[34:37]
	v_mfma_f32_16x16x32_f16 v[90:93], v[144:147], v[164:167], v[90:93]
	v_mfma_f32_16x16x32_f16 v[82:85], v[152:155], v[164:167], v[82:85]
	v_mfma_f32_16x16x32_f16 v[74:77], v[144:147], v[172:175], v[74:77]
	v_mfma_f32_16x16x32_f16 v[66:69], v[152:155], v[172:175], v[66:69]
	v_mfma_f32_16x16x32_f16 v[58:61], v[144:147], v[180:183], v[58:61]
	v_mfma_f32_16x16x32_f16 v[50:53], v[152:155], v[180:183], v[50:53]
	v_mfma_f32_16x16x32_f16 v[42:45], v[144:147], v[188:191], v[42:45]
	v_mfma_f32_16x16x32_f16 v[34:37], v[152:155], v[188:191], v[34:37]
	v_mfma_f32_16x16x32_f16 v[30:33], v[192:195], v[156:159], v[30:33]
	v_mfma_f32_16x16x32_f16 v[26:29], v[200:203], v[156:159], v[26:29]
	v_mfma_f32_16x16x32_f16 v[22:25], v[192:195], v[168:171], v[22:25]
	v_mfma_f32_16x16x32_f16 v[18:21], v[200:203], v[168:171], v[18:21]
	v_mfma_f32_16x16x32_f16 v[14:17], v[192:195], v[176:179], v[14:17]
	v_mfma_f32_16x16x32_f16 v[10:13], v[200:203], v[176:179], v[10:13]
	v_mfma_f32_16x16x32_f16 v[6:9], v[192:195], v[184:187], v[6:9]
	v_mfma_f32_16x16x32_f16 v[2:5], v[200:203], v[184:187], v[2:5]
	v_mfma_f32_16x16x32_f16 v[30:33], v[196:199], v[164:167], v[30:33]
	v_mfma_f32_16x16x32_f16 v[26:29], v[204:207], v[164:167], v[26:29]
	v_mfma_f32_16x16x32_f16 v[22:25], v[196:199], v[172:175], v[22:25]
	v_mfma_f32_16x16x32_f16 v[18:21], v[204:207], v[172:175], v[18:21]
	v_mfma_f32_16x16x32_f16 v[14:17], v[196:199], v[180:183], v[14:17]
	v_mfma_f32_16x16x32_f16 v[10:13], v[204:207], v[180:183], v[10:13]
	v_mfma_f32_16x16x32_f16 v[6:9], v[196:199], v[188:191], v[6:9]
	v_mfma_f32_16x16x32_f16 v[2:5], v[204:207], v[188:191], v[2:5]
	s_barrier
	s_add_i32 s66, 0, 0x18000
	v_add_u32_e32 v234, s66, v161
	ds_read_b128 v[140:143], v234
	ds_read_b128 v[144:147], v234 offset:1024
	ds_read_b128 v[148:151], v234 offset:2048
	ds_read_b128 v[152:155], v234 offset:3072
	s_add_u32 s44, s48, 0x1c0000
	s_addc_u32 s45, s49, 0
	s_mov_b32 m0, s69
	v_lshl_add_u64 v[232:233], s[44:45], 0, v[130:131]
	ds_read_b128 v[156:159], v163 offset:32768
	ds_read_b128 v[164:167], v163 offset:33792
	ds_read_b128 v[168:171], v163 offset:34816
	ds_read_b128 v[172:175], v163 offset:35840
	ds_read_b128 v[176:179], v163 offset:36864
	ds_read_b128 v[180:183], v163 offset:37888
	ds_read_b128 v[184:187], v163 offset:38912
	ds_read_b128 v[188:191], v163 offset:39936
	global_load_lds_dwordx4 v[232:233], off
	v_lshl_add_u64 v[232:233], s[44:45], 0, v[132:133]
	s_mov_b32 m0, s70
	s_nop 0
	global_load_lds_dwordx4 v[232:233], off
	s_waitcnt lgkmcnt(11)
	s_add_i32 s48, 0, 0x1c000
	s_add_i32 s44, s66, s62
	v_add_u32_e32 v234, s48, v161
	v_lshl_add_u64 v[212:213], v[212:213], 0, s[92:93]
	s_mov_b32 m0, s44
	ds_read_b128 v[192:195], v234
	ds_read_b128 v[196:199], v234 offset:1024
	ds_read_b128 v[200:203], v234 offset:2048
	ds_read_b128 v[204:207], v234 offset:3072
	s_waitcnt vmcnt(8) lgkmcnt(0)
	s_barrier
	v_mfma_f32_16x16x32_f16 v[126:129], v[140:143], v[156:159], v[126:129]
	v_mfma_f32_16x16x32_f16 v[122:125], v[148:151], v[156:159], v[122:125]
	v_mfma_f32_16x16x32_f16 v[118:121], v[140:143], v[168:171], v[118:121]
	v_mfma_f32_16x16x32_f16 v[114:117], v[148:151], v[168:171], v[114:117]
	v_mfma_f32_16x16x32_f16 v[110:113], v[140:143], v[176:179], v[110:113]
	v_mfma_f32_16x16x32_f16 v[106:109], v[148:151], v[176:179], v[106:109]
	v_mfma_f32_16x16x32_f16 v[102:105], v[140:143], v[184:187], v[102:105]
	v_mfma_f32_16x16x32_f16 v[98:101], v[148:151], v[184:187], v[98:101]
	v_mfma_f32_16x16x32_f16 v[126:129], v[144:147], v[164:167], v[126:129]
	v_mfma_f32_16x16x32_f16 v[122:125], v[152:155], v[164:167], v[122:125]
	v_mfma_f32_16x16x32_f16 v[118:121], v[144:147], v[172:175], v[118:121]
	v_mfma_f32_16x16x32_f16 v[114:117], v[152:155], v[172:175], v[114:117]
	v_mfma_f32_16x16x32_f16 v[110:113], v[144:147], v[180:183], v[110:113]
	v_mfma_f32_16x16x32_f16 v[106:109], v[152:155], v[180:183], v[106:109]
	v_mfma_f32_16x16x32_f16 v[102:105], v[144:147], v[188:191], v[102:105]
	v_mfma_f32_16x16x32_f16 v[98:101], v[152:155], v[188:191], v[98:101]
	v_mfma_f32_16x16x32_f16 v[94:97], v[192:195], v[156:159], v[94:97]
	v_mfma_f32_16x16x32_f16 v[86:89], v[200:203], v[156:159], v[86:89]
	v_mfma_f32_16x16x32_f16 v[78:81], v[192:195], v[168:171], v[78:81]
	v_mfma_f32_16x16x32_f16 v[70:73], v[200:203], v[168:171], v[70:73]
	v_mfma_f32_16x16x32_f16 v[62:65], v[192:195], v[176:179], v[62:65]
	v_mfma_f32_16x16x32_f16 v[54:57], v[200:203], v[176:179], v[54:57]
	v_mfma_f32_16x16x32_f16 v[46:49], v[192:195], v[184:187], v[46:49]
	v_mfma_f32_16x16x32_f16 v[38:41], v[200:203], v[184:187], v[38:41]
	v_mfma_f32_16x16x32_f16 v[94:97], v[196:199], v[164:167], v[94:97]
	v_mfma_f32_16x16x32_f16 v[86:89], v[204:207], v[164:167], v[86:89]
	v_mfma_f32_16x16x32_f16 v[78:81], v[196:199], v[172:175], v[78:81]
	v_mfma_f32_16x16x32_f16 v[70:73], v[204:207], v[172:175], v[70:73]
	v_mfma_f32_16x16x32_f16 v[62:65], v[196:199], v[180:183], v[62:65]
	v_mfma_f32_16x16x32_f16 v[54:57], v[204:207], v[180:183], v[54:57]
	v_mfma_f32_16x16x32_f16 v[46:49], v[196:199], v[188:191], v[46:49]
	v_mfma_f32_16x16x32_f16 v[38:41], v[204:207], v[188:191], v[38:41]
	s_barrier
; #define PG8_STAGE(bufoff, gbase, voff) do { _Pragma("unroll") for (int _i = 0; _i < 2; ++_i) \
;         __builtin_amdgcn_global_load_lds((const unsigned*)((const char*)(gbase) + (voff)[_i]), (LAS unsigned*)(lds + (bufoff) + ldsw + _i * 8192), 16, 0, 0); } while (0)
; #define PG8_MMA(ai, bj, At, Bt_) do { __builtin_amdgcn_s_setprio(1); _Pragma("unroll") for (int m = 0; m < 4; ++m) _Pragma("unroll") for (int n = 0; n < 2; ++n) _Pragma("unroll") for (int k = 0; k < 2; ++k) \
;         acc[ai][bj][m][n] = __builtin_amdgcn_mfma_f32_16x16x32_f16(Bt_[n][k], At[m][k], acc[ai][bj][m][n], 0, 0, 0); __builtin_amdgcn_s_setprio(0); } while (0)
; #define PG8_WAIT_V(n) asm volatile("s_waitcnt vmcnt(" #n ")" ::: "memory")
; #define PG8_WAIT_L(n) asm volatile("s_waitcnt lgkmcnt(" #n ")" ::: "memory")
; #define PG8_BAR __builtin_amdgcn_s_barrier()
; #define PG8_SCHED __builtin_amdgcn_sched_barrier(0)
; template <class Epi, class AMap>
; __device__ __forceinline__ void gemm_phase(LAS unsigned char* lds, const AMap am, const int lda, const h16* Bt, const int ldb, const int M, const int N, const int K, const Epi& E) {
;     ...
;             PG8_BAR; PG8_WAIT_L(0); PG8_MMA(1, 0, At, B0); PG8_BAR; PG8_SCHED;
;             PG8_STAGE(PG8_SB(1, 1), b3 + hstepB, voffB);
;             PG8_WAIT_V(6); PG8_BAR; PG8_MMA(1, 1, At, B1); PG8_BAR;
;         }
;         E(acc, cur, wr, wc, fr, fq);
;     template <int GI>
;     __device__ __forceinline__ void body(const f32x4 (&acc)[2][2][4][2], int row0, int colt) const {
;     ...
;                     f32x4 x0 = acc[ai][bj][m][0] + b0, x1 = acc[ai][bj][m][1] + b1;
	global_load_lds_dwordx4 v[212:213], off
	v_lshl_add_u64 v[212:213], v[220:221], 0, s[92:93]
	s_add_i32 m0, s44, 0x2000
	s_nop 0
	global_load_lds_dwordx4 v[212:213], off
	s_mov_b32 m0, s71
	v_lshl_add_u64 v[212:213], v[222:223], 0, s[92:93]
	ds_read_b128 v[156:159], v163 offset:49152
	ds_read_b128 v[164:167], v163 offset:50176
	ds_read_b128 v[168:171], v163 offset:51200
	ds_read_b128 v[172:175], v163 offset:52224
	ds_read_b128 v[176:179], v163 offset:53248
	ds_read_b128 v[180:183], v163 offset:54272
	ds_read_b128 v[184:187], v163 offset:55296
	ds_read_b128 v[188:191], v163 offset:56320
	global_load_lds_dwordx4 v[212:213], off
	v_lshl_add_u64 v[212:213], v[224:225], 0, s[92:93]
	s_mov_b32 m0, s72
	s_nop 0
	global_load_lds_dwordx4 v[212:213], off
	s_add_u32 s44, s46, 0x10080
	s_addc_u32 s45, s47, 0
	s_add_i32 s46, s48, s62
	v_lshl_add_u64 v[232:233], s[44:45], 0, v[0:1]
	s_mov_b32 m0, s46
	s_nop 0
	global_load_lds_dwordx4 v[232:233], off
	v_lshl_add_u64 v[232:233], s[44:45], 0, v[134:135]
	s_add_i32 m0, s46, 0x2000
	s_nop 0
	global_load_lds_dwordx4 v[232:233], off
	s_waitcnt vmcnt(8) lgkmcnt(0)
	s_barrier
	v_mfma_f32_16x16x32_f16 v[90:93], v[140:143], v[156:159], v[90:93]
	v_mfma_f32_16x16x32_f16 v[82:85], v[148:151], v[156:159], v[82:85]
	v_mfma_f32_16x16x32_f16 v[74:77], v[140:143], v[168:171], v[74:77]
	v_mfma_f32_16x16x32_f16 v[66:69], v[148:151], v[168:171], v[66:69]
	v_mfma_f32_16x16x32_f16 v[58:61], v[140:143], v[176:179], v[58:61]
	v_mfma_f32_16x16x32_f16 v[50:53], v[148:151], v[176:179], v[50:53]
	v_mfma_f32_16x16x32_f16 v[42:45], v[140:143], v[184:187], v[42:45]
	v_mfma_f32_16x16x32_f16 v[34:37], v[148:151], v[184:187], v[34:37]
	v_mfma_f32_16x16x32_f16 v[90:93], v[144:147], v[164:167], v[90:93]
	v_mfma_f32_16x16x32_f16 v[82:85], v[152:155], v[164:167], v[82:85]
	v_mfma_f32_16x16x32_f16 v[74:77], v[144:147], v[172:175], v[74:77]
	v_mfma_f32_16x16x32_f16 v[66:69], v[152:155], v[172:175], v[66:69]
	v_mfma_f32_16x16x32_f16 v[58:61], v[144:147], v[180:183], v[58:61]
	v_mfma_f32_16x16x32_f16 v[50:53], v[152:155], v[180:183], v[50:53]
	v_mfma_f32_16x16x32_f16 v[42:45], v[144:147], v[188:191], v[42:45]
	v_mfma_f32_16x16x32_f16 v[34:37], v[152:155], v[188:191], v[34:37]
	v_mfma_f32_16x16x32_f16 v[30:33], v[192:195], v[156:159], v[30:33]
	v_mfma_f32_16x16x32_f16 v[26:29], v[200:203], v[156:159], v[26:29]
	v_mfma_f32_16x16x32_f16 v[22:25], v[192:195], v[168:171], v[22:25]
	v_mfma_f32_16x16x32_f16 v[18:21], v[200:203], v[168:171], v[18:21]
	v_mfma_f32_16x16x32_f16 v[14:17], v[192:195], v[176:179], v[14:17]
	v_mfma_f32_16x16x32_f16 v[10:13], v[200:203], v[176:179], v[10:13]
	v_mfma_f32_16x16x32_f16 v[6:9], v[192:195], v[184:187], v[6:9]
	v_mfma_f32_16x16x32_f16 v[2:5], v[200:203], v[184:187], v[2:5]
	v_mfma_f32_16x16x32_f16 v[30:33], v[196:199], v[164:167], v[30:33]
	v_mfma_f32_16x16x32_f16 v[26:29], v[204:207], v[164:167], v[26:29]
	v_mfma_f32_16x16x32_f16 v[22:25], v[196:199], v[172:175], v[22:25]
	v_mfma_f32_16x16x32_f16 v[18:21], v[204:207], v[172:175], v[18:21]
	v_mfma_f32_16x16x32_f16 v[14:17], v[196:199], v[180:183], v[14:17]
	v_mfma_f32_16x16x32_f16 v[10:13], v[204:207], v[180:183], v[10:13]
	v_mfma_f32_16x16x32_f16 v[6:9], v[196:199], v[188:191], v[6:9]
	v_mfma_f32_16x16x32_f16 v[2:5], v[204:207], v[188:191], v[2:5]
	s_add_u32 s27, s27, 0x100
	s_addc_u32 s29, s29, 0
	s_cmp_ge_i32 s60, s24
	s_mov_b64 s[44:45], s[0:1]
	s_mov_b32 s46, s60
	s_barrier
	s_cbranch_scc0 .LBB0_667
	s_cmpk_gt_u32 s50, 0xff
	s_cbranch_scc1 .Lgx6
	s_barrier
.Lgx6:
	v_pk_add_f32 v[128:129], v[128:129], 0 op_sel_hi:[1,0]
	v_pk_add_f32 v[126:127], v[126:127], 0 op_sel_hi:[1,0]
	v_pk_add_f32 v[124:125], v[124:125], 0 op_sel_hi:[1,0]
	v_pk_add_f32 v[122:123], v[122:123], 0 op_sel_hi:[1,0]
	v_pk_add_f32 v[120:121], v[120:121], 0 op_sel_hi:[1,0]
	v_pk_add_f32 v[118:119], v[118:119], 0 op_sel_hi:[1,0]
	v_pk_add_f32 v[116:117], v[116:117], 0 op_sel_hi:[1,0]
	v_pk_add_f32 v[114:115], v[114:115], 0 op_sel_hi:[1,0]
	v_pk_add_f32 v[112:113], v[112:113], 0 op_sel_hi:[1,0]
	v_pk_add_f32 v[110:111], v[110:111], 0 op_sel_hi:[1,0]
	v_pk_add_f32 v[108:109], v[108:109], 0 op_sel_hi:[1,0]
	v_pk_add_f32 v[106:107], v[106:107], 0 op_sel_hi:[1,0]
	v_pk_add_f32 v[104:105], v[104:105], 0 op_sel_hi:[1,0]
	v_pk_add_f32 v[102:103], v[102:103], 0 op_sel_hi:[1,0]
	v_pk_add_f32 v[100:101], v[100:101], 0 op_sel_hi:[1,0]
	v_pk_add_f32 v[98:99], v[98:99], 0 op_sel_hi:[1,0]
	v_pk_add_f32 v[92:93], v[92:93], 0 op_sel_hi:[1,0]
	v_pk_add_f32 v[90:91], v[90:91], 0 op_sel_hi:[1,0]
	v_pk_add_f32 v[144:145], v[84:85], 0 op_sel_hi:[1,0]
	v_pk_add_f32 v[152:153], v[82:83], 0 op_sel_hi:[1,0]
	v_pk_add_f32 v[76:77], v[76:77], 0 op_sel_hi:[1,0]
	v_pk_add_f32 v[84:85], v[74:75], 0 op_sel_hi:[1,0]
	v_pk_add_f32 v[146:147], v[68:69], 0 op_sel_hi:[1,0]
	v_pk_add_f32 v[154:155], v[66:67], 0 op_sel_hi:[1,0]
	v_pk_add_f32 v[74:75], v[60:61], 0 op_sel_hi:[1,0]
	v_pk_add_f32 v[140:141], v[58:59], 0 op_sel_hi:[1,0]
	v_pk_add_f32 v[148:149], v[52:53], 0 op_sel_hi:[1,0]
	v_pk_add_f32 v[156:157], v[50:51], 0 op_sel_hi:[1,0]
	v_pk_add_f32 v[82:83], v[44:45], 0 op_sel_hi:[1,0]
	v_pk_add_f32 v[142:143], v[42:43], 0 op_sel_hi:[1,0]
	v_pk_add_f32 v[150:151], v[36:37], 0 op_sel_hi:[1,0]
	v_pk_add_f32 v[158:159], v[34:35], 0 op_sel_hi:[1,0]
	v_pk_add_f32 v[34:35], v[96:97], 0 op_sel_hi:[1,0]
	v_pk_add_f32 v[36:37], v[94:95], 0 op_sel_hi:[1,0]
	v_pk_add_f32 v[50:51], v[88:89], 0 op_sel_hi:[1,0]
	v_pk_add_f32 v[52:53], v[86:87], 0 op_sel_hi:[1,0]
	v_pk_add_f32 v[42:43], v[80:81], 0 op_sel_hi:[1,0]
	v_pk_add_f32 v[44:45], v[78:79], 0 op_sel_hi:[1,0]
	v_pk_add_f32 v[66:67], v[72:73], 0 op_sel_hi:[1,0]
	v_pk_add_f32 v[68:69], v[70:71], 0 op_sel_hi:[1,0]
	v_pk_add_f32 v[58:59], v[64:65], 0 op_sel_hi:[1,0]
	v_pk_add_f32 v[60:61], v[62:63], 0 op_sel_hi:[1,0]
	v_pk_add_f32 v[56:57], v[56:57], 0 op_sel_hi:[1,0]
	v_pk_add_f32 v[54:55], v[54:55], 0 op_sel_hi:[1,0]
	v_pk_add_f32 v[48:49], v[48:49], 0 op_sel_hi:[1,0]
	v_pk_add_f32 v[46:47], v[46:47], 0 op_sel_hi:[1,0]
	v_pk_add_f32 v[40:41], v[40:41], 0 op_sel_hi:[1,0]
	v_pk_add_f32 v[38:39], v[38:39], 0 op_sel_hi:[1,0]
	v_pk_add_f32 v[32:33], v[32:33], 0 op_sel_hi:[1,0]
	v_pk_add_f32 v[30:31], v[30:31], 0 op_sel_hi:[1,0]
	v_pk_add_f32 v[28:29], v[28:29], 0 op_sel_hi:[1,0]
	v_pk_add_f32 v[26:27], v[26:27], 0 op_sel_hi:[1,0]
	v_pk_add_f32 v[24:25], v[24:25], 0 op_sel_hi:[1,0]
	v_pk_add_f32 v[22:23], v[22:23], 0 op_sel_hi:[1,0]
	v_pk_add_f32 v[20:21], v[20:21], 0 op_sel_hi:[1,0]
	v_pk_add_f32 v[18:19], v[18:19], 0 op_sel_hi:[1,0]
	v_pk_add_f32 v[16:17], v[16:17], 0 op_sel_hi:[1,0]
	v_pk_add_f32 v[14:15], v[14:15], 0 op_sel_hi:[1,0]
	v_pk_add_f32 v[12:13], v[12:13], 0 op_sel_hi:[1,0]
	v_pk_add_f32 v[10:11], v[10:11], 0 op_sel_hi:[1,0]
	v_pk_add_f32 v[8:9], v[8:9], 0 op_sel_hi:[1,0]
	v_pk_add_f32 v[6:7], v[6:7], 0 op_sel_hi:[1,0]
	v_pk_add_f32 v[4:5], v[4:5], 0 op_sel_hi:[1,0]
	v_pk_add_f32 v[2:3], v[2:3], 0 op_sel_hi:[1,0]
	s_movk_i32 s66, 0x80
	s_branch .LBB0_656

; __device__ __forceinline__ float sigmoidf_(float x) { return 1.0f / (1.0f + __expf(-x)); }
;     template <int GI>
;     __device__ __forceinline__ void body(const f32x4 (&acc)[2][2][4][2], int row0, int colt) const {
;     ...
;             if (GI == 0) { b0 = *(const f32x4*)(w0 + c); b1 = *(const f32x4*)(w0 + c + 4); }
;             else if (GI == 1) { b0 = *(const f32x4*)(a0 + c); b1 = *(const f32x4*)(a0 + c + 4); }
;             else if (GI == 3) { b0 = *(const f32x4*)(v0 + c); b1 = *(const f32x4*)(v0 + c + 4); }
; #pragma unroll
;             for (int ai = 0; ai < 2; ++ai)
; #pragma unroll
;                 for (int m = 0; m < 4; ++m) {
;                     const size_t row = (size_t)(row0 + ai * 128 + m * 16);
;                     f32x4 x0 = acc[ai][bj][m][0] + b0, x1 = acc[ai][bj][m][1] + b1;
;                     if (GI == 0) {
; #pragma unroll
;                         for (int j = 0; j < 4; ++j) {
;                             x0[j] = 0.6065306597126334f * sigmoidf_(x0[j]); x1[j] = 0.6065306597126334f * sigmoidf_(x1[j]); }
;                         *(u32x4*)(DEC + row * DM + c) = pack8(x0, x1);
;                     } else if (GI == 1) {
; #pragma unroll
;                         for (int j = 0; j < 4; ++j) { x0[j] = sigmoidf_(x0[j]); x1[j] = sigmoidf_(x1[j]); }
;                         *(u32x4*)(Ab + row * DM + c) = pack8(x0, x1);
;                     } else if (GI == 2) {
;                         *(u32x4*)(Gb + row * DM + c) = pack8(x0, x1);
;                     } else {
;                         h16* vp = C1 + row * LDC1 + 4096 + c;
;                         const h16x8 vv = *(const h16x8*)vp; const h16x8 vf = *(const h16x8*)(VF + row * DM + c);
;                         f32x4 o0, o1;
; #pragma unroll
;                         for (int j = 0; j < 4; ++j) { float v = (float)vv[j], f = (float)vf[j]; o0[j] = v + (f - v) * sigmoidf_(x0[j]); v = (float)vv[4 + j]; f = (float)vf[4 + j]; o1[j] = v + (f - v) * sigmoidf_(x1[j]); }
;                         *(u32x4*)vp = pack8(o0, o1);
.LBB0_681:
	v_lshl_or_b32 v158, s50, 8, v176
	v_ashrrev_i32_e32 v159, 31, v158
	v_lshl_add_u64 v[156:157], v[158:159], 2, s[40:41]
	global_load_dwordx4 v[82:85], v[156:157], off offset:16
	global_load_dwordx4 v[86:89], v[156:157], off
	v_lshl_add_u32 v164, s35, 8, v174
	v_mov_b64_e32 v[168:169], s[8:9]
	v_ashrrev_i32_e32 v165, 31, v164
	v_mad_i64_i32 v[138:139], s[0:1], v164, s5, v[168:169]
	v_lshl_add_u64 v[160:161], v[138:139], 0, s[90:91]
	v_lshlrev_b64 v[166:167], 1, v[158:159]
	v_lshlrev_b64 v[142:143], 12, v[164:165]
	v_lshl_add_u64 v[170:171], v[160:161], 0, v[166:167]
	v_lshl_add_u64 v[142:143], s[2:3], 0, v[142:143]
	global_load_dwordx4 v[138:141], v[170:171], off
	v_lshl_add_u64 v[162:163], v[142:143], 0, v[166:167]
	global_load_dwordx4 v[142:145], v[162:163], off
	s_waitcnt vmcnt(0)
	v_add_f32_e32 v130, v130, v82
	v_mul_f32_e32 v130, 0xbfb8aa3b, v130
	v_exp_f32_e32 v172, v130
	v_add_f32_e32 v130, v135, v87
	v_mul_f32_e32 v130, 0xbfb8aa3b, v130
	v_exp_f32_e32 v179, v130
	v_add_f32_e32 v130, v131, v83
	v_mul_f32_e32 v130, 0xbfb8aa3b, v130
	v_exp_f32_e32 v173, v130
	v_add_f32_e32 v130, v136, v88
	v_add_f32_e32 v134, v134, v86
	v_mul_f32_e32 v130, 0xbfb8aa3b, v130
	v_mul_f32_e32 v134, 0xbfb8aa3b, v134
	v_exp_f32_e32 v136, v130
	v_add_f32_e32 v130, v132, v84
	v_exp_f32_e32 v178, v134
	v_mul_f32_e32 v130, 0xbfb8aa3b, v130
	v_exp_f32_e32 v134, v130
	v_add_f32_e32 v130, v137, v89
	v_mul_f32_e32 v130, 0xbfb8aa3b, v130
	v_exp_f32_e32 v137, v130
	v_add_f32_e32 v130, v133, v85
	v_mul_f32_e32 v130, 0xbfb8aa3b, v130
	v_pk_add_f32 v[178:179], v[178:179], 1.0 op_sel_hi:[1,0]
	v_exp_f32_e32 v135, v130
	v_cvt_f32_f16_e32 v130, v138
	v_cvt_f32_f16_sdwa v131, v138 dst_sel:DWORD dst_unused:UNUSED_PAD src0_sel:WORD_1
	v_div_scale_f32 v138, s[0:1], v179, v179, 1.0
	v_cvt_f32_f16_e32 v132, v142
	v_cvt_f32_f16_sdwa v133, v142 dst_sel:DWORD dst_unused:UNUSED_PAD src0_sel:WORD_1
	v_rcp_f32_e32 v142, v138
	v_pk_add_f32 v[136:137], v[136:137], 1.0 op_sel_hi:[1,0]
	v_pk_add_f32 v[134:135], v[134:135], 1.0 op_sel_hi:[1,0]
	v_pk_add_f32 v[132:133], v[132:133], v[130:131] neg_lo:[0,1] neg_hi:[0,1]
	v_fma_f32 v159, -v138, v142, 1.0
	v_fmac_f32_e32 v142, v159, v142
	v_div_scale_f32 v159, vcc, 1.0, v179, 1.0
	v_mul_f32_e32 v165, v159, v142
	v_fma_f32 v180, -v138, v165, v159
	v_fmac_f32_e32 v165, v180, v142
	v_fma_f32 v138, -v138, v165, v159
	v_div_fmas_f32 v138, v138, v142, v165
	v_div_fixup_f32 v179, v138, v179, 1.0
	v_div_scale_f32 v138, s[0:1], v178, v178, 1.0
	v_rcp_f32_e32 v142, v138
	s_nop 0
	v_fma_f32 v159, -v138, v142, 1.0
	v_fmac_f32_e32 v142, v159, v142
	v_div_scale_f32 v159, vcc, 1.0, v178, 1.0
	v_mul_f32_e32 v165, v159, v142
	v_fma_f32 v180, -v138, v165, v159
	v_fmac_f32_e32 v165, v180, v142
	v_fma_f32 v138, -v138, v165, v159
	v_div_fmas_f32 v138, v138, v142, v165
	v_div_fixup_f32 v178, v138, v178, 1.0
	v_pk_fma_f32 v[130:131], v[178:179], v[132:133], v[130:131]
	v_cvt_f32_f16_e32 v132, v139
	v_cvt_pk_f16_f32 v130, v130, v131
	v_div_scale_f32 v131, s[0:1], v137, v137, 1.0
	v_rcp_f32_e32 v142, v131
	v_cvt_f32_f16_sdwa v133, v139 dst_sel:DWORD dst_unused:UNUSED_PAD src0_sel:WORD_1
	v_cvt_f32_f16_e32 v138, v143
	v_cvt_f32_f16_sdwa v139, v143 dst_sel:DWORD dst_unused:UNUSED_PAD src0_sel:WORD_1
	v_fma_f32 v143, -v131, v142, 1.0
	v_fmac_f32_e32 v142, v143, v142
	v_div_scale_f32 v143, vcc, 1.0, v137, 1.0
	v_mul_f32_e32 v159, v143, v142
	v_fma_f32 v165, -v131, v159, v143
	v_fmac_f32_e32 v159, v165, v142
	v_fma_f32 v131, -v131, v159, v143
	v_div_fmas_f32 v131, v131, v142, v159
	v_div_fixup_f32 v137, v131, v137, 1.0
	v_div_scale_f32 v131, s[0:1], v136, v136, 1.0
	v_rcp_f32_e32 v142, v131
	v_pk_add_f32 v[138:139], v[138:139], v[132:133] neg_lo:[0,1] neg_hi:[0,1]
	v_fma_f32 v143, -v131, v142, 1.0
	v_fmac_f32_e32 v142, v143, v142
	v_div_scale_f32 v143, vcc, 1.0, v136, 1.0
	v_mul_f32_e32 v159, v143, v142
	v_fma_f32 v165, -v131, v159, v143
	v_fmac_f32_e32 v159, v165, v142
	v_fma_f32 v131, -v131, v159, v143
	v_div_fmas_f32 v131, v131, v142, v159
	v_div_fixup_f32 v136, v131, v136, 1.0
	v_pk_fma_f32 v[132:133], v[136:137], v[138:139], v[132:133]
	v_pk_add_f32 v[138:139], v[172:173], 1.0 op_sel_hi:[1,0]
	v_cvt_pk_f16_f32 v131, v132, v133
	v_cvt_f32_f16_e32 v132, v140
	v_cvt_f32_f16_sdwa v133, v140 dst_sel:DWORD dst_unused:UNUSED_PAD src0_sel:WORD_1
	v_div_scale_f32 v140, s[0:1], v139, v139, 1.0
	v_rcp_f32_e32 v142, v140
	v_cvt_f32_f16_e32 v136, v144
	v_cvt_f32_f16_sdwa v137, v144 dst_sel:DWORD dst_unused:UNUSED_PAD src0_sel:WORD_1
	v_fma_f32 v143, -v140, v142, 1.0
	v_fmac_f32_e32 v142, v143, v142
	v_div_scale_f32 v143, vcc, 1.0, v139, 1.0
	v_mul_f32_e32 v144, v143, v142
	v_fma_f32 v159, -v140, v144, v143
	v_fmac_f32_e32 v144, v159, v142
	v_fma_f32 v140, -v140, v144, v143
	v_div_fmas_f32 v140, v140, v142, v144
	v_div_fixup_f32 v139, v140, v139, 1.0
	v_div_scale_f32 v140, s[0:1], v138, v138, 1.0
	v_rcp_f32_e32 v142, v140
	v_pk_add_f32 v[136:137], v[136:137], v[132:133] neg_lo:[0,1] neg_hi:[0,1]
	v_fma_f32 v143, -v140, v142, 1.0
	v_fmac_f32_e32 v142, v143, v142
	v_div_scale_f32 v143, vcc, 1.0, v138, 1.0
	v_mul_f32_e32 v144, v143, v142
	v_fma_f32 v159, -v140, v144, v143
	v_fmac_f32_e32 v144, v159, v142
	v_fma_f32 v140, -v140, v144, v143
	v_div_fmas_f32 v140, v140, v142, v144
	v_div_fixup_f32 v138, v140, v138, 1.0
	v_pk_fma_f32 v[132:133], v[136:137], v[138:139], v[132:133]
	v_cvt_f32_f16_e32 v136, v141
	v_cvt_pk_f16_f32 v132, v132, v133
	v_div_scale_f32 v133, s[0:1], v135, v135, 1.0
	v_rcp_f32_e32 v140, v133
	v_cvt_f32_f16_sdwa v137, v141 dst_sel:DWORD dst_unused:UNUSED_PAD src0_sel:WORD_1
	v_cvt_f32_f16_e32 v138, v145
	v_cvt_f32_f16_sdwa v139, v145 dst_sel:DWORD dst_unused:UNUSED_PAD src0_sel:WORD_1
; __device__ __forceinline__ float sigmoidf_(float x) { return 1.0f / (1.0f + __expf(-x)); }
;     template <int GI>
;     __device__ __forceinline__ void body(const f32x4 (&acc)[2][2][4][2], int row0, int colt) const {
;     ...
;                     const size_t row = (size_t)(row0 + ai * 128 + m * 16);
;                     f32x4 x0 = acc[ai][bj][m][0] + b0, x1 = acc[ai][bj][m][1] + b1;
;                     if (GI == 0) {
; #pragma unroll
;                         for (int j = 0; j < 4; ++j) {
;                             x0[j] = 0.6065306597126334f * sigmoidf_(x0[j]); x1[j] = 0.6065306597126334f * sigmoidf_(x1[j]); }
;                         *(u32x4*)(DEC + row * DM + c) = pack8(x0, x1);
;                     } else if (GI == 1) {
; #pragma unroll
;                         for (int j = 0; j < 4; ++j) { x0[j] = sigmoidf_(x0[j]); x1[j] = sigmoidf_(x1[j]); }
;                         *(u32x4*)(Ab + row * DM + c) = pack8(x0, x1);
;                     } else if (GI == 2) {
;                         *(u32x4*)(Gb + row * DM + c) = pack8(x0, x1);
;                     } else {
;                         h16* vp = C1 + row * LDC1 + 4096 + c;
;                         const h16x8 vv = *(const h16x8*)vp; const h16x8 vf = *(const h16x8*)(VF + row * DM + c);
;                         f32x4 o0, o1;
; #pragma unroll
;                         for (int j = 0; j < 4; ++j) { float v = (float)vv[j], f = (float)vf[j]; o0[j] = v + (f - v) * sigmoidf_(x0[j]); v = (float)vv[4 + j]; f = (float)vf[4 + j]; o1[j] = v + (f - v) * sigmoidf_(x1[j]); }
;                         *(u32x4*)vp = pack8(o0, o1);
	v_fma_f32 v141, -v133, v140, 1.0
	v_fmac_f32_e32 v140, v141, v140
	v_div_scale_f32 v141, vcc, 1.0, v135, 1.0
	v_mul_f32_e32 v142, v141, v140
	v_fma_f32 v143, -v133, v142, v141
	v_fmac_f32_e32 v142, v143, v140
	v_fma_f32 v133, -v133, v142, v141
	v_div_fmas_f32 v133, v133, v140, v142
	v_div_fixup_f32 v135, v133, v135, 1.0
	v_div_scale_f32 v133, s[0:1], v134, v134, 1.0
	v_rcp_f32_e32 v140, v133
	v_pk_add_f32 v[138:139], v[138:139], v[136:137] neg_lo:[0,1] neg_hi:[0,1]
	v_fma_f32 v141, -v133, v140, 1.0
	v_fmac_f32_e32 v140, v141, v140
	v_div_scale_f32 v141, vcc, 1.0, v134, 1.0
	v_mul_f32_e32 v142, v141, v140
	v_fma_f32 v143, -v133, v142, v141
	v_fmac_f32_e32 v142, v143, v140
	v_fma_f32 v133, -v133, v142, v141
	v_div_fmas_f32 v133, v133, v140, v142
	v_div_fixup_f32 v134, v133, v134, 1.0
	v_pk_fma_f32 v[134:135], v[138:139], v[134:135], v[136:137]
	s_nop 0
	v_cvt_pk_f16_f32 v133, v134, v135
	global_store_dwordx4 v[170:171], v[130:133], off
	v_or_b32_e32 v134, 16, v164
	v_ashrrev_i32_e32 v135, 31, v134
	v_mad_i64_i32 v[130:131], s[0:1], v134, s5, v[168:169]
	v_lshl_add_u64 v[138:139], v[130:131], 0, s[90:91]
	v_lshlrev_b64 v[134:135], 12, v[134:135]
	v_lshl_add_u64 v[142:143], v[138:139], 0, v[166:167]
	v_lshl_add_u64 v[134:135], s[2:3], 0, v[134:135]
	global_load_dwordx4 v[130:133], v[142:143], off
	v_lshl_add_u64 v[140:141], v[134:135], 0, v[166:167]
	global_load_dwordx4 v[134:137], v[140:141], off
	v_add_f32_e32 v122, v122, v82
	v_mul_f32_e32 v122, 0xbfb8aa3b, v122
	v_exp_f32_e32 v144, v122
	v_add_f32_e32 v122, v127, v87
	v_mul_f32_e32 v122, 0xbfb8aa3b, v122
	v_exp_f32_e32 v173, v122
	v_add_f32_e32 v122, v123, v83
	v_mul_f32_e32 v122, 0xbfb8aa3b, v122
	v_exp_f32_e32 v145, v122
	v_add_f32_e32 v122, v128, v88
	v_add_f32_e32 v126, v126, v86
	v_mul_f32_e32 v122, 0xbfb8aa3b, v122
	v_mul_f32_e32 v126, 0xbfb8aa3b, v126
	v_exp_f32_e32 v170, v122
	v_add_f32_e32 v122, v124, v84
	v_exp_f32_e32 v172, v126
	v_mul_f32_e32 v122, 0xbfb8aa3b, v122
	v_exp_f32_e32 v126, v122
	v_add_f32_e32 v122, v129, v89
	v_mul_f32_e32 v122, 0xbfb8aa3b, v122
	v_exp_f32_e32 v171, v122
	v_add_f32_e32 v122, v125, v85
	v_mul_f32_e32 v122, 0xbfb8aa3b, v122
	v_pk_add_f32 v[128:129], v[172:173], 1.0 op_sel_hi:[1,0]
	v_exp_f32_e32 v127, v122
	s_waitcnt vmcnt(0)
	v_cvt_f32_f16_e32 v122, v130
	v_cvt_f32_f16_sdwa v123, v130 dst_sel:DWORD dst_unused:UNUSED_PAD src0_sel:WORD_1
	v_div_scale_f32 v130, s[0:1], v129, v129, 1.0
	v_cvt_f32_f16_e32 v124, v134
	v_cvt_f32_f16_sdwa v125, v134 dst_sel:DWORD dst_unused:UNUSED_PAD src0_sel:WORD_1
	v_rcp_f32_e32 v134, v130
	v_pk_add_f32 v[126:127], v[126:127], 1.0 op_sel_hi:[1,0]
	v_pk_add_f32 v[124:125], v[124:125], v[122:123] neg_lo:[0,1] neg_hi:[0,1]
	v_fma_f32 v159, -v130, v134, 1.0
	v_fmac_f32_e32 v134, v159, v134
	v_div_scale_f32 v159, vcc, 1.0, v129, 1.0
	v_mul_f32_e32 v165, v159, v134
	v_fma_f32 v172, -v130, v165, v159
	v_fmac_f32_e32 v165, v172, v134
	v_fma_f32 v130, -v130, v165, v159
	v_div_fmas_f32 v130, v130, v134, v165
	v_div_fixup_f32 v129, v130, v129, 1.0
	v_div_scale_f32 v130, s[0:1], v128, v128, 1.0
	v_rcp_f32_e32 v134, v130
	s_nop 0
	v_fma_f32 v159, -v130, v134, 1.0
	v_fmac_f32_e32 v134, v159, v134
	v_div_scale_f32 v159, vcc, 1.0, v128, 1.0
	v_mul_f32_e32 v165, v159, v134
	v_fma_f32 v172, -v130, v165, v159
	v_fmac_f32_e32 v165, v172, v134
	v_fma_f32 v130, -v130, v165, v159
	v_div_fmas_f32 v130, v130, v134, v165
	v_div_fixup_f32 v128, v130, v128, 1.0
	v_pk_fma_f32 v[122:123], v[128:129], v[124:125], v[122:123]
	v_cvt_f32_f16_e32 v124, v131
	v_cvt_f32_f16_sdwa v125, v131 dst_sel:DWORD dst_unused:UNUSED_PAD src0_sel:WORD_1
	v_pk_add_f32 v[130:131], v[170:171], 1.0 op_sel_hi:[1,0]
	v_cvt_pk_f16_f32 v122, v122, v123
	v_div_scale_f32 v123, s[0:1], v131, v131, 1.0
	v_rcp_f32_e32 v134, v123
	v_cvt_f32_f16_e32 v128, v135
	v_cvt_f32_f16_sdwa v129, v135 dst_sel:DWORD dst_unused:UNUSED_PAD src0_sel:WORD_1
	v_fma_f32 v135, -v123, v134, 1.0
	v_fmac_f32_e32 v134, v135, v134
	v_div_scale_f32 v135, vcc, 1.0, v131, 1.0
	v_mul_f32_e32 v159, v135, v134
	v_fma_f32 v165, -v123, v159, v135
	v_fmac_f32_e32 v159, v165, v134
	v_fma_f32 v123, -v123, v159, v135
	v_div_fmas_f32 v123, v123, v134, v159
	v_div_fixup_f32 v131, v123, v131, 1.0
	v_div_scale_f32 v123, s[0:1], v130, v130, 1.0
	v_rcp_f32_e32 v134, v123
	v_pk_add_f32 v[128:129], v[128:129], v[124:125] neg_lo:[0,1] neg_hi:[0,1]
	v_fma_f32 v135, -v123, v134, 1.0
	v_fmac_f32_e32 v134, v135, v134
	v_div_scale_f32 v135, vcc, 1.0, v130, 1.0
	v_mul_f32_e32 v159, v135, v134
	v_fma_f32 v165, -v123, v159, v135
	v_fmac_f32_e32 v159, v165, v134
	v_fma_f32 v123, -v123, v159, v135
	v_div_fmas_f32 v123, v123, v134, v159
	v_div_fixup_f32 v130, v123, v130, 1.0
	v_pk_fma_f32 v[124:125], v[130:131], v[128:129], v[124:125]
	v_pk_add_f32 v[130:131], v[144:145], 1.0 op_sel_hi:[1,0]
	v_cvt_pk_f16_f32 v123, v124, v125
	v_cvt_f32_f16_e32 v124, v132
	v_cvt_f32_f16_sdwa v125, v132 dst_sel:DWORD dst_unused:UNUSED_PAD src0_sel:WORD_1
	v_div_scale_f32 v132, s[0:1], v131, v131, 1.0
	v_rcp_f32_e32 v134, v132
	v_cvt_f32_f16_e32 v128, v136
	v_cvt_f32_f16_sdwa v129, v136 dst_sel:DWORD dst_unused:UNUSED_PAD src0_sel:WORD_1
	v_fma_f32 v135, -v132, v134, 1.0
	v_fmac_f32_e32 v134, v135, v134
	v_div_scale_f32 v135, vcc, 1.0, v131, 1.0
	v_mul_f32_e32 v136, v135, v134
	v_fma_f32 v144, -v132, v136, v135
	v_fmac_f32_e32 v136, v144, v134
	v_fma_f32 v132, -v132, v136, v135
	v_div_fmas_f32 v132, v132, v134, v136
	v_div_fixup_f32 v131, v132, v131, 1.0
	v_div_scale_f32 v132, s[0:1], v130, v130, 1.0
	v_rcp_f32_e32 v134, v132
	v_pk_add_f32 v[128:129], v[128:129], v[124:125] neg_lo:[0,1] neg_hi:[0,1]
	v_fma_f32 v135, -v132, v134, 1.0
	v_fmac_f32_e32 v134, v135, v134
; __device__ __forceinline__ float sigmoidf_(float x) { return 1.0f / (1.0f + __expf(-x)); }
;     template <int GI>
;     __device__ __forceinline__ void body(const f32x4 (&acc)[2][2][4][2], int row0, int colt) const {
;     ...
;                     const size_t row = (size_t)(row0 + ai * 128 + m * 16);
;                     f32x4 x0 = acc[ai][bj][m][0] + b0, x1 = acc[ai][bj][m][1] + b1;
;                     if (GI == 0) {
; #pragma unroll
;                         for (int j = 0; j < 4; ++j) {
;                             x0[j] = 0.6065306597126334f * sigmoidf_(x0[j]); x1[j] = 0.6065306597126334f * sigmoidf_(x1[j]); }
;                         *(u32x4*)(DEC + row * DM + c) = pack8(x0, x1);
;                     } else if (GI == 1) {
; #pragma unroll
;                         for (int j = 0; j < 4; ++j) { x0[j] = sigmoidf_(x0[j]); x1[j] = sigmoidf_(x1[j]); }
;                         *(u32x4*)(Ab + row * DM + c) = pack8(x0, x1);
;                     } else if (GI == 2) {
;                         *(u32x4*)(Gb + row * DM + c) = pack8(x0, x1);
;                     } else {
;                         h16* vp = C1 + row * LDC1 + 4096 + c;
;                         const h16x8 vv = *(const h16x8*)vp; const h16x8 vf = *(const h16x8*)(VF + row * DM + c);
;                         f32x4 o0, o1;
; #pragma unroll
;                         for (int j = 0; j < 4; ++j) { float v = (float)vv[j], f = (float)vf[j]; o0[j] = v + (f - v) * sigmoidf_(x0[j]); v = (float)vv[4 + j]; f = (float)vf[4 + j]; o1[j] = v + (f - v) * sigmoidf_(x1[j]); }
;                         *(u32x4*)vp = pack8(o0, o1);
	v_div_scale_f32 v135, vcc, 1.0, v130, 1.0
	v_mul_f32_e32 v136, v135, v134
	v_fma_f32 v144, -v132, v136, v135
	v_fmac_f32_e32 v136, v144, v134
	v_fma_f32 v132, -v132, v136, v135
	v_div_fmas_f32 v132, v132, v134, v136
	v_div_fixup_f32 v130, v132, v130, 1.0
	v_pk_fma_f32 v[124:125], v[130:131], v[128:129], v[124:125]
	v_cvt_f32_f16_e32 v128, v133
	v_cvt_pk_f16_f32 v124, v124, v125
	v_div_scale_f32 v125, s[0:1], v127, v127, 1.0
	v_rcp_f32_e32 v132, v125
	v_cvt_f32_f16_sdwa v129, v133 dst_sel:DWORD dst_unused:UNUSED_PAD src0_sel:WORD_1
	v_cvt_f32_f16_e32 v130, v137
	v_cvt_f32_f16_sdwa v131, v137 dst_sel:DWORD dst_unused:UNUSED_PAD src0_sel:WORD_1
	v_fma_f32 v133, -v125, v132, 1.0
	v_fmac_f32_e32 v132, v133, v132
	v_div_scale_f32 v133, vcc, 1.0, v127, 1.0
	v_mul_f32_e32 v134, v133, v132
	v_fma_f32 v135, -v125, v134, v133
	v_fmac_f32_e32 v134, v135, v132
	v_fma_f32 v125, -v125, v134, v133
	v_div_fmas_f32 v125, v125, v132, v134
	v_div_fixup_f32 v127, v125, v127, 1.0
	v_div_scale_f32 v125, s[0:1], v126, v126, 1.0
	v_rcp_f32_e32 v132, v125
	v_pk_add_f32 v[130:131], v[130:131], v[128:129] neg_lo:[0,1] neg_hi:[0,1]
	v_fma_f32 v133, -v125, v132, 1.0
	v_fmac_f32_e32 v132, v133, v132
	v_div_scale_f32 v133, vcc, 1.0, v126, 1.0
	v_mul_f32_e32 v134, v133, v132
	v_fma_f32 v135, -v125, v134, v133
	v_fmac_f32_e32 v134, v135, v132
	v_fma_f32 v125, -v125, v134, v133
	v_div_fmas_f32 v125, v125, v132, v134
	v_div_fixup_f32 v126, v125, v126, 1.0
	v_pk_fma_f32 v[126:127], v[126:127], v[130:131], v[128:129]
	s_nop 0
	v_cvt_pk_f16_f32 v125, v126, v127
	global_store_dwordx4 v[142:143], v[122:125], off
	v_or_b32_e32 v126, 32, v164
	v_ashrrev_i32_e32 v127, 31, v126
	v_mad_i64_i32 v[122:123], s[0:1], v126, s5, v[168:169]
	v_lshl_add_u64 v[130:131], v[122:123], 0, s[90:91]
	v_lshlrev_b64 v[126:127], 12, v[126:127]
	v_lshl_add_u64 v[134:135], v[130:131], 0, v[166:167]
	v_lshl_add_u64 v[126:127], s[2:3], 0, v[126:127]
	global_load_dwordx4 v[122:125], v[134:135], off
	v_lshl_add_u64 v[132:133], v[126:127], 0, v[166:167]
	global_load_dwordx4 v[126:129], v[132:133], off
	v_add_f32_e32 v114, v114, v82
	v_mul_f32_e32 v114, 0xbfb8aa3b, v114
	v_exp_f32_e32 v136, v114
	v_add_f32_e32 v114, v119, v87
	v_mul_f32_e32 v114, 0xbfb8aa3b, v114
	v_exp_f32_e32 v145, v114
	v_add_f32_e32 v114, v115, v83
	v_mul_f32_e32 v114, 0xbfb8aa3b, v114
	v_exp_f32_e32 v137, v114
	v_add_f32_e32 v114, v120, v88
	v_add_f32_e32 v118, v118, v86
	v_mul_f32_e32 v114, 0xbfb8aa3b, v114
	v_mul_f32_e32 v118, 0xbfb8aa3b, v118
	v_exp_f32_e32 v142, v114
	v_add_f32_e32 v114, v116, v84
	v_exp_f32_e32 v144, v118
	v_mul_f32_e32 v114, 0xbfb8aa3b, v114
	v_exp_f32_e32 v118, v114
	v_add_f32_e32 v114, v121, v89
	v_mul_f32_e32 v114, 0xbfb8aa3b, v114
	v_exp_f32_e32 v143, v114
	v_add_f32_e32 v114, v117, v85
	v_mul_f32_e32 v114, 0xbfb8aa3b, v114
	v_pk_add_f32 v[120:121], v[144:145], 1.0 op_sel_hi:[1,0]
	v_exp_f32_e32 v119, v114
	s_waitcnt vmcnt(0)
	v_cvt_f32_f16_e32 v114, v122
	v_cvt_f32_f16_sdwa v115, v122 dst_sel:DWORD dst_unused:UNUSED_PAD src0_sel:WORD_1
	v_div_scale_f32 v122, s[0:1], v121, v121, 1.0
	v_cvt_f32_f16_e32 v116, v126
	v_cvt_f32_f16_sdwa v117, v126 dst_sel:DWORD dst_unused:UNUSED_PAD src0_sel:WORD_1
	v_rcp_f32_e32 v126, v122
	v_pk_add_f32 v[118:119], v[118:119], 1.0 op_sel_hi:[1,0]
	v_pk_add_f32 v[116:117], v[116:117], v[114:115] neg_lo:[0,1] neg_hi:[0,1]
	v_fma_f32 v144, -v122, v126, 1.0
	v_fmac_f32_e32 v126, v144, v126
	v_div_scale_f32 v144, vcc, 1.0, v121, 1.0
	v_mul_f32_e32 v145, v144, v126
	v_fma_f32 v159, -v122, v145, v144
	v_fmac_f32_e32 v145, v159, v126
	v_fma_f32 v122, -v122, v145, v144
	v_div_fmas_f32 v122, v122, v126, v145
	v_div_fixup_f32 v121, v122, v121, 1.0
	v_div_scale_f32 v122, s[0:1], v120, v120, 1.0
	v_rcp_f32_e32 v126, v122
	s_nop 0
	v_fma_f32 v144, -v122, v126, 1.0
	v_fmac_f32_e32 v126, v144, v126
	v_div_scale_f32 v144, vcc, 1.0, v120, 1.0
	v_mul_f32_e32 v145, v144, v126
	v_fma_f32 v159, -v122, v145, v144
	v_fmac_f32_e32 v145, v159, v126
	v_fma_f32 v122, -v122, v145, v144
	v_div_fmas_f32 v122, v122, v126, v145
	v_div_fixup_f32 v120, v122, v120, 1.0
	v_pk_fma_f32 v[114:115], v[120:121], v[116:117], v[114:115]
	v_cvt_f32_f16_e32 v116, v123
	v_cvt_f32_f16_sdwa v117, v123 dst_sel:DWORD dst_unused:UNUSED_PAD src0_sel:WORD_1
	v_pk_add_f32 v[122:123], v[142:143], 1.0 op_sel_hi:[1,0]
	v_cvt_pk_f16_f32 v114, v114, v115
	v_div_scale_f32 v115, s[0:1], v123, v123, 1.0
	v_rcp_f32_e32 v126, v115
	v_cvt_f32_f16_e32 v120, v127
	v_cvt_f32_f16_sdwa v121, v127 dst_sel:DWORD dst_unused:UNUSED_PAD src0_sel:WORD_1
	v_fma_f32 v127, -v115, v126, 1.0
	v_fmac_f32_e32 v126, v127, v126
	v_div_scale_f32 v127, vcc, 1.0, v123, 1.0
	v_mul_f32_e32 v142, v127, v126
	v_fma_f32 v143, -v115, v142, v127
	v_fmac_f32_e32 v142, v143, v126
	v_fma_f32 v115, -v115, v142, v127
	v_div_fmas_f32 v115, v115, v126, v142
	v_div_fixup_f32 v123, v115, v123, 1.0
	v_div_scale_f32 v115, s[0:1], v122, v122, 1.0
	v_rcp_f32_e32 v126, v115
	v_pk_add_f32 v[120:121], v[120:121], v[116:117] neg_lo:[0,1] neg_hi:[0,1]
	v_fma_f32 v127, -v115, v126, 1.0
	v_fmac_f32_e32 v126, v127, v126
	v_div_scale_f32 v127, vcc, 1.0, v122, 1.0
	v_mul_f32_e32 v142, v127, v126
	v_fma_f32 v143, -v115, v142, v127
	v_fmac_f32_e32 v142, v143, v126
	v_fma_f32 v115, -v115, v142, v127
	v_div_fmas_f32 v115, v115, v126, v142
	v_div_fixup_f32 v122, v115, v122, 1.0
	v_pk_fma_f32 v[116:117], v[122:123], v[120:121], v[116:117]
	v_pk_add_f32 v[122:123], v[136:137], 1.0 op_sel_hi:[1,0]
	v_cvt_pk_f16_f32 v115, v116, v117
	v_cvt_f32_f16_e32 v116, v124
	v_cvt_f32_f16_sdwa v117, v124 dst_sel:DWORD dst_unused:UNUSED_PAD src0_sel:WORD_1
	v_div_scale_f32 v124, s[0:1], v123, v123, 1.0
; __device__ __forceinline__ float sigmoidf_(float x) { return 1.0f / (1.0f + __expf(-x)); }
;     template <int GI>
;     __device__ __forceinline__ void body(const f32x4 (&acc)[2][2][4][2], int row0, int colt) const {
;     ...
;                     const size_t row = (size_t)(row0 + ai * 128 + m * 16);
;                     f32x4 x0 = acc[ai][bj][m][0] + b0, x1 = acc[ai][bj][m][1] + b1;
;                     if (GI == 0) {
; #pragma unroll
;                         for (int j = 0; j < 4; ++j) {
;                             x0[j] = 0.6065306597126334f * sigmoidf_(x0[j]); x1[j] = 0.6065306597126334f * sigmoidf_(x1[j]); }
;                         *(u32x4*)(DEC + row * DM + c) = pack8(x0, x1);
;                     } else if (GI == 1) {
; #pragma unroll
;                         for (int j = 0; j < 4; ++j) { x0[j] = sigmoidf_(x0[j]); x1[j] = sigmoidf_(x1[j]); }
;                         *(u32x4*)(Ab + row * DM + c) = pack8(x0, x1);
;                     } else if (GI == 2) {
;                         *(u32x4*)(Gb + row * DM + c) = pack8(x0, x1);
;                     } else {
;                         h16* vp = C1 + row * LDC1 + 4096 + c;
;                         const h16x8 vv = *(const h16x8*)vp; const h16x8 vf = *(const h16x8*)(VF + row * DM + c);
;                         f32x4 o0, o1;
; #pragma unroll
;                         for (int j = 0; j < 4; ++j) { float v = (float)vv[j], f = (float)vf[j]; o0[j] = v + (f - v) * sigmoidf_(x0[j]); v = (float)vv[4 + j]; f = (float)vf[4 + j]; o1[j] = v + (f - v) * sigmoidf_(x1[j]); }
;                         *(u32x4*)vp = pack8(o0, o1);
	v_rcp_f32_e32 v126, v124
	v_cvt_f32_f16_e32 v120, v128
	v_cvt_f32_f16_sdwa v121, v128 dst_sel:DWORD dst_unused:UNUSED_PAD src0_sel:WORD_1
	v_fma_f32 v127, -v124, v126, 1.0
	v_fmac_f32_e32 v126, v127, v126
	v_div_scale_f32 v127, vcc, 1.0, v123, 1.0
	v_mul_f32_e32 v128, v127, v126
	v_fma_f32 v136, -v124, v128, v127
	v_fmac_f32_e32 v128, v136, v126
	v_fma_f32 v124, -v124, v128, v127
	v_div_fmas_f32 v124, v124, v126, v128
	v_div_fixup_f32 v123, v124, v123, 1.0
	v_div_scale_f32 v124, s[0:1], v122, v122, 1.0
	v_rcp_f32_e32 v126, v124
	v_pk_add_f32 v[120:121], v[120:121], v[116:117] neg_lo:[0,1] neg_hi:[0,1]
	v_fma_f32 v127, -v124, v126, 1.0
	v_fmac_f32_e32 v126, v127, v126
	v_div_scale_f32 v127, vcc, 1.0, v122, 1.0
	v_mul_f32_e32 v128, v127, v126
	v_fma_f32 v136, -v124, v128, v127
	v_fmac_f32_e32 v128, v136, v126
	v_fma_f32 v124, -v124, v128, v127
	v_div_fmas_f32 v124, v124, v126, v128
	v_div_fixup_f32 v122, v124, v122, 1.0
	v_pk_fma_f32 v[116:117], v[122:123], v[120:121], v[116:117]
	v_cvt_f32_f16_e32 v120, v125
	v_cvt_pk_f16_f32 v116, v116, v117
	v_div_scale_f32 v117, s[0:1], v119, v119, 1.0
	v_rcp_f32_e32 v124, v117
	v_cvt_f32_f16_sdwa v121, v125 dst_sel:DWORD dst_unused:UNUSED_PAD src0_sel:WORD_1
	v_cvt_f32_f16_e32 v122, v129
	v_cvt_f32_f16_sdwa v123, v129 dst_sel:DWORD dst_unused:UNUSED_PAD src0_sel:WORD_1
	v_fma_f32 v125, -v117, v124, 1.0
	v_fmac_f32_e32 v124, v125, v124
	v_div_scale_f32 v125, vcc, 1.0, v119, 1.0
	v_mul_f32_e32 v126, v125, v124
	v_fma_f32 v127, -v117, v126, v125
	v_fmac_f32_e32 v126, v127, v124
	v_fma_f32 v117, -v117, v126, v125
	v_div_fmas_f32 v117, v117, v124, v126
	v_div_fixup_f32 v119, v117, v119, 1.0
	v_div_scale_f32 v117, s[0:1], v118, v118, 1.0
	v_rcp_f32_e32 v124, v117
	v_pk_add_f32 v[122:123], v[122:123], v[120:121] neg_lo:[0,1] neg_hi:[0,1]
	v_fma_f32 v125, -v117, v124, 1.0
	v_fmac_f32_e32 v124, v125, v124
	v_div_scale_f32 v125, vcc, 1.0, v118, 1.0
	v_mul_f32_e32 v126, v125, v124
	v_fma_f32 v127, -v117, v126, v125
	v_fmac_f32_e32 v126, v127, v124
	v_fma_f32 v117, -v117, v126, v125
	v_div_fmas_f32 v117, v117, v124, v126
	v_div_fixup_f32 v118, v117, v118, 1.0
	v_pk_fma_f32 v[118:119], v[118:119], v[122:123], v[120:121]
	s_nop 0
	v_cvt_pk_f16_f32 v117, v118, v119
	global_store_dwordx4 v[134:135], v[114:117], off
	v_or_b32_e32 v118, 48, v164
	v_ashrrev_i32_e32 v119, 31, v118
	v_mad_i64_i32 v[114:115], s[0:1], v118, s5, v[168:169]
	v_lshl_add_u64 v[122:123], v[114:115], 0, s[90:91]
	v_lshlrev_b64 v[118:119], 12, v[118:119]
	v_lshl_add_u64 v[126:127], v[122:123], 0, v[166:167]
	v_lshl_add_u64 v[118:119], s[2:3], 0, v[118:119]
	global_load_dwordx4 v[114:117], v[126:127], off
	v_lshl_add_u64 v[124:125], v[118:119], 0, v[166:167]
	global_load_dwordx4 v[118:121], v[124:125], off
	v_add_f32_e32 v106, v106, v82
	v_mul_f32_e32 v106, 0xbfb8aa3b, v106
	v_exp_f32_e32 v128, v106
	v_add_f32_e32 v106, v111, v87
	v_mul_f32_e32 v106, 0xbfb8aa3b, v106
	v_exp_f32_e32 v137, v106
	v_add_f32_e32 v106, v107, v83
	v_mul_f32_e32 v106, 0xbfb8aa3b, v106
	v_exp_f32_e32 v129, v106
	v_add_f32_e32 v106, v112, v88
	v_add_f32_e32 v110, v110, v86
	v_mul_f32_e32 v106, 0xbfb8aa3b, v106
	v_mul_f32_e32 v110, 0xbfb8aa3b, v110
	v_exp_f32_e32 v134, v106
	v_add_f32_e32 v106, v108, v84
	v_exp_f32_e32 v136, v110
	v_mul_f32_e32 v106, 0xbfb8aa3b, v106
	v_exp_f32_e32 v110, v106
	v_add_f32_e32 v106, v113, v89
	v_mul_f32_e32 v106, 0xbfb8aa3b, v106
	v_exp_f32_e32 v135, v106
	v_add_f32_e32 v106, v109, v85
	v_mul_f32_e32 v106, 0xbfb8aa3b, v106
	v_pk_add_f32 v[112:113], v[136:137], 1.0 op_sel_hi:[1,0]
	v_exp_f32_e32 v111, v106
	s_waitcnt vmcnt(0)
	v_cvt_f32_f16_e32 v106, v114
	v_cvt_f32_f16_sdwa v107, v114 dst_sel:DWORD dst_unused:UNUSED_PAD src0_sel:WORD_1
	v_div_scale_f32 v114, s[0:1], v113, v113, 1.0
	v_cvt_f32_f16_e32 v108, v118
	v_cvt_f32_f16_sdwa v109, v118 dst_sel:DWORD dst_unused:UNUSED_PAD src0_sel:WORD_1
	v_rcp_f32_e32 v118, v114
	v_pk_add_f32 v[110:111], v[110:111], 1.0 op_sel_hi:[1,0]
	v_pk_add_f32 v[108:109], v[108:109], v[106:107] neg_lo:[0,1] neg_hi:[0,1]
	v_fma_f32 v136, -v114, v118, 1.0
	v_fmac_f32_e32 v118, v136, v118
	v_div_scale_f32 v136, vcc, 1.0, v113, 1.0
	v_mul_f32_e32 v137, v136, v118
	v_fma_f32 v142, -v114, v137, v136
	v_fmac_f32_e32 v137, v142, v118
	v_fma_f32 v114, -v114, v137, v136
	v_div_fmas_f32 v114, v114, v118, v137
	v_div_fixup_f32 v113, v114, v113, 1.0
	v_div_scale_f32 v114, s[0:1], v112, v112, 1.0
	v_rcp_f32_e32 v118, v114
	s_nop 0
	v_fma_f32 v136, -v114, v118, 1.0
	v_fmac_f32_e32 v118, v136, v118
	v_div_scale_f32 v136, vcc, 1.0, v112, 1.0
	v_mul_f32_e32 v137, v136, v118
	v_fma_f32 v142, -v114, v137, v136
	v_fmac_f32_e32 v137, v142, v118
	v_fma_f32 v114, -v114, v137, v136
	v_div_fmas_f32 v114, v114, v118, v137
	v_div_fixup_f32 v112, v114, v112, 1.0
	v_pk_fma_f32 v[106:107], v[112:113], v[108:109], v[106:107]
	v_cvt_f32_f16_e32 v108, v115
	v_cvt_f32_f16_sdwa v109, v115 dst_sel:DWORD dst_unused:UNUSED_PAD src0_sel:WORD_1
	v_pk_add_f32 v[114:115], v[134:135], 1.0 op_sel_hi:[1,0]
	v_cvt_pk_f16_f32 v106, v106, v107
	v_div_scale_f32 v107, s[0:1], v115, v115, 1.0
	v_rcp_f32_e32 v118, v107
	v_cvt_f32_f16_e32 v112, v119
	v_cvt_f32_f16_sdwa v113, v119 dst_sel:DWORD dst_unused:UNUSED_PAD src0_sel:WORD_1
	v_fma_f32 v119, -v107, v118, 1.0
	v_fmac_f32_e32 v118, v119, v118
	v_div_scale_f32 v119, vcc, 1.0, v115, 1.0
	v_mul_f32_e32 v134, v119, v118
	v_fma_f32 v135, -v107, v134, v119
	v_fmac_f32_e32 v134, v135, v118
	v_fma_f32 v107, -v107, v134, v119
	v_div_fmas_f32 v107, v107, v118, v134
	v_div_fixup_f32 v115, v107, v115, 1.0
	v_div_scale_f32 v107, s[0:1], v114, v114, 1.0
	v_rcp_f32_e32 v118, v107
	v_pk_add_f32 v[112:113], v[112:113], v[108:109] neg_lo:[0,1] neg_hi:[0,1]
; __device__ __forceinline__ float sigmoidf_(float x) { return 1.0f / (1.0f + __expf(-x)); }
;     template <int GI>
;     __device__ __forceinline__ void body(const f32x4 (&acc)[2][2][4][2], int row0, int colt) const {
;     ...
;                     const size_t row = (size_t)(row0 + ai * 128 + m * 16);
;                     f32x4 x0 = acc[ai][bj][m][0] + b0, x1 = acc[ai][bj][m][1] + b1;
;                     if (GI == 0) {
; #pragma unroll
;                         for (int j = 0; j < 4; ++j) {
;                             x0[j] = 0.6065306597126334f * sigmoidf_(x0[j]); x1[j] = 0.6065306597126334f * sigmoidf_(x1[j]); }
;                         *(u32x4*)(DEC + row * DM + c) = pack8(x0, x1);
;                     } else if (GI == 1) {
; #pragma unroll
;                         for (int j = 0; j < 4; ++j) { x0[j] = sigmoidf_(x0[j]); x1[j] = sigmoidf_(x1[j]); }
;                         *(u32x4*)(Ab + row * DM + c) = pack8(x0, x1);
;                     } else if (GI == 2) {
;                         *(u32x4*)(Gb + row * DM + c) = pack8(x0, x1);
;                     } else {
;                         h16* vp = C1 + row * LDC1 + 4096 + c;
;                         const h16x8 vv = *(const h16x8*)vp; const h16x8 vf = *(const h16x8*)(VF + row * DM + c);
;                         f32x4 o0, o1;
; #pragma unroll
;                         for (int j = 0; j < 4; ++j) { float v = (float)vv[j], f = (float)vf[j]; o0[j] = v + (f - v) * sigmoidf_(x0[j]); v = (float)vv[4 + j]; f = (float)vf[4 + j]; o1[j] = v + (f - v) * sigmoidf_(x1[j]); }
;                         *(u32x4*)vp = pack8(o0, o1);
	v_fma_f32 v119, -v107, v118, 1.0
	v_fmac_f32_e32 v118, v119, v118
	v_div_scale_f32 v119, vcc, 1.0, v114, 1.0
	v_mul_f32_e32 v134, v119, v118
	v_fma_f32 v135, -v107, v134, v119
	v_fmac_f32_e32 v134, v135, v118
	v_fma_f32 v107, -v107, v134, v119
	v_div_fmas_f32 v107, v107, v118, v134
	v_div_fixup_f32 v114, v107, v114, 1.0
	v_pk_fma_f32 v[108:109], v[114:115], v[112:113], v[108:109]
	v_pk_add_f32 v[114:115], v[128:129], 1.0 op_sel_hi:[1,0]
	v_cvt_pk_f16_f32 v107, v108, v109
	v_cvt_f32_f16_e32 v108, v116
	v_cvt_f32_f16_sdwa v109, v116 dst_sel:DWORD dst_unused:UNUSED_PAD src0_sel:WORD_1
	v_div_scale_f32 v116, s[0:1], v115, v115, 1.0
	v_rcp_f32_e32 v118, v116
	v_cvt_f32_f16_e32 v112, v120
	v_cvt_f32_f16_sdwa v113, v120 dst_sel:DWORD dst_unused:UNUSED_PAD src0_sel:WORD_1
	v_fma_f32 v119, -v116, v118, 1.0
	v_fmac_f32_e32 v118, v119, v118
	v_div_scale_f32 v119, vcc, 1.0, v115, 1.0
	v_mul_f32_e32 v120, v119, v118
	v_fma_f32 v128, -v116, v120, v119
	v_fmac_f32_e32 v120, v128, v118
	v_fma_f32 v116, -v116, v120, v119
	v_div_fmas_f32 v116, v116, v118, v120
	v_div_fixup_f32 v115, v116, v115, 1.0
	v_div_scale_f32 v116, s[0:1], v114, v114, 1.0
	v_rcp_f32_e32 v118, v116
	v_pk_add_f32 v[112:113], v[112:113], v[108:109] neg_lo:[0,1] neg_hi:[0,1]
	v_fma_f32 v119, -v116, v118, 1.0
	v_fmac_f32_e32 v118, v119, v118
	v_div_scale_f32 v119, vcc, 1.0, v114, 1.0
	v_mul_f32_e32 v120, v119, v118
	v_fma_f32 v128, -v116, v120, v119
	v_fmac_f32_e32 v120, v128, v118
	v_fma_f32 v116, -v116, v120, v119
	v_div_fmas_f32 v116, v116, v118, v120
	v_div_fixup_f32 v114, v116, v114, 1.0
	v_pk_fma_f32 v[108:109], v[114:115], v[112:113], v[108:109]
	v_cvt_f32_f16_e32 v112, v117
	v_cvt_pk_f16_f32 v108, v108, v109
	v_div_scale_f32 v109, s[0:1], v111, v111, 1.0
	v_rcp_f32_e32 v116, v109
	v_cvt_f32_f16_sdwa v113, v117 dst_sel:DWORD dst_unused:UNUSED_PAD src0_sel:WORD_1
	v_cvt_f32_f16_e32 v114, v121
	v_cvt_f32_f16_sdwa v115, v121 dst_sel:DWORD dst_unused:UNUSED_PAD src0_sel:WORD_1
	v_fma_f32 v117, -v109, v116, 1.0
	v_fmac_f32_e32 v116, v117, v116
	v_div_scale_f32 v117, vcc, 1.0, v111, 1.0
	v_mul_f32_e32 v118, v117, v116
	v_fma_f32 v119, -v109, v118, v117
	v_fmac_f32_e32 v118, v119, v116
	v_fma_f32 v109, -v109, v118, v117
	v_div_fmas_f32 v109, v109, v116, v118
	v_div_fixup_f32 v111, v109, v111, 1.0
	v_div_scale_f32 v109, s[0:1], v110, v110, 1.0
	v_rcp_f32_e32 v116, v109
	v_pk_add_f32 v[114:115], v[114:115], v[112:113] neg_lo:[0,1] neg_hi:[0,1]
	v_fma_f32 v117, -v109, v116, 1.0
	v_fmac_f32_e32 v116, v117, v116
	v_div_scale_f32 v117, vcc, 1.0, v110, 1.0
	v_mul_f32_e32 v118, v117, v116
	v_fma_f32 v119, -v109, v118, v117
	v_fmac_f32_e32 v118, v119, v116
	v_fma_f32 v109, -v109, v118, v117
	v_div_fmas_f32 v109, v109, v116, v118
	v_div_fixup_f32 v110, v109, v110, 1.0
	v_pk_fma_f32 v[110:111], v[110:111], v[114:115], v[112:113]
	s_nop 0
	v_cvt_pk_f16_f32 v109, v110, v111
	global_store_dwordx4 v[126:127], v[106:109], off
	v_add_u32_e32 v110, 0x80, v164
	v_ashrrev_i32_e32 v111, 31, v110
	v_mad_i64_i32 v[106:107], s[0:1], v110, s5, v[168:169]
	v_lshl_add_u64 v[114:115], v[106:107], 0, s[90:91]
	v_lshlrev_b64 v[110:111], 12, v[110:111]
	v_lshl_add_u64 v[118:119], v[114:115], 0, v[166:167]
	v_lshl_add_u64 v[110:111], s[2:3], 0, v[110:111]
	global_load_dwordx4 v[106:109], v[118:119], off
	v_lshl_add_u64 v[116:117], v[110:111], 0, v[166:167]
	global_load_dwordx4 v[110:113], v[116:117], off
	v_add_f32_e32 v98, v98, v82
	v_mul_f32_e32 v98, 0xbfb8aa3b, v98
	v_exp_f32_e32 v120, v98
	v_add_f32_e32 v98, v103, v87
	v_mul_f32_e32 v98, 0xbfb8aa3b, v98
	v_exp_f32_e32 v129, v98
	v_add_f32_e32 v98, v99, v83
	v_mul_f32_e32 v98, 0xbfb8aa3b, v98
	v_exp_f32_e32 v121, v98
	v_add_f32_e32 v98, v104, v88
	v_add_f32_e32 v102, v102, v86
	v_mul_f32_e32 v98, 0xbfb8aa3b, v98
	v_mul_f32_e32 v102, 0xbfb8aa3b, v102
	v_exp_f32_e32 v126, v98
	v_add_f32_e32 v98, v100, v84
	v_exp_f32_e32 v128, v102
	v_mul_f32_e32 v98, 0xbfb8aa3b, v98
	v_exp_f32_e32 v102, v98
	v_add_f32_e32 v98, v105, v89
	v_mul_f32_e32 v98, 0xbfb8aa3b, v98
	v_exp_f32_e32 v127, v98
	v_add_f32_e32 v98, v101, v85
	v_mul_f32_e32 v98, 0xbfb8aa3b, v98
	v_pk_add_f32 v[104:105], v[128:129], 1.0 op_sel_hi:[1,0]
	v_exp_f32_e32 v103, v98
	s_waitcnt vmcnt(0)
	v_cvt_f32_f16_e32 v98, v106
	v_cvt_f32_f16_sdwa v99, v106 dst_sel:DWORD dst_unused:UNUSED_PAD src0_sel:WORD_1
	v_div_scale_f32 v106, s[0:1], v105, v105, 1.0
	v_cvt_f32_f16_e32 v100, v110
	v_cvt_f32_f16_sdwa v101, v110 dst_sel:DWORD dst_unused:UNUSED_PAD src0_sel:WORD_1
	v_rcp_f32_e32 v110, v106
	v_pk_add_f32 v[102:103], v[102:103], 1.0 op_sel_hi:[1,0]
	v_pk_add_f32 v[100:101], v[100:101], v[98:99] neg_lo:[0,1] neg_hi:[0,1]
	v_fma_f32 v128, -v106, v110, 1.0
	v_fmac_f32_e32 v110, v128, v110
	v_div_scale_f32 v128, vcc, 1.0, v105, 1.0
	v_mul_f32_e32 v129, v128, v110
	v_fma_f32 v134, -v106, v129, v128
	v_fmac_f32_e32 v129, v134, v110
	v_fma_f32 v106, -v106, v129, v128
	v_div_fmas_f32 v106, v106, v110, v129
	v_div_fixup_f32 v105, v106, v105, 1.0
	v_div_scale_f32 v106, s[0:1], v104, v104, 1.0
	v_rcp_f32_e32 v110, v106
	s_nop 0
	v_fma_f32 v128, -v106, v110, 1.0
	v_fmac_f32_e32 v110, v128, v110
	v_div_scale_f32 v128, vcc, 1.0, v104, 1.0
	v_mul_f32_e32 v129, v128, v110
	v_fma_f32 v134, -v106, v129, v128
	v_fmac_f32_e32 v129, v134, v110
	v_fma_f32 v106, -v106, v129, v128
	v_div_fmas_f32 v106, v106, v110, v129
	v_div_fixup_f32 v104, v106, v104, 1.0
	v_pk_fma_f32 v[98:99], v[104:105], v[100:101], v[98:99]
	v_cvt_f32_f16_e32 v100, v107
	v_cvt_f32_f16_sdwa v101, v107 dst_sel:DWORD dst_unused:UNUSED_PAD src0_sel:WORD_1
	v_pk_add_f32 v[106:107], v[126:127], 1.0 op_sel_hi:[1,0]
	v_cvt_pk_f16_f32 v98, v98, v99
	v_div_scale_f32 v99, s[0:1], v107, v107, 1.0
; __device__ __forceinline__ float sigmoidf_(float x) { return 1.0f / (1.0f + __expf(-x)); }
;     template <int GI>
;     __device__ __forceinline__ void body(const f32x4 (&acc)[2][2][4][2], int row0, int colt) const {
;     ...
;                     const size_t row = (size_t)(row0 + ai * 128 + m * 16);
;                     f32x4 x0 = acc[ai][bj][m][0] + b0, x1 = acc[ai][bj][m][1] + b1;
;                     if (GI == 0) {
; #pragma unroll
;                         for (int j = 0; j < 4; ++j) {
;                             x0[j] = 0.6065306597126334f * sigmoidf_(x0[j]); x1[j] = 0.6065306597126334f * sigmoidf_(x1[j]); }
;                         *(u32x4*)(DEC + row * DM + c) = pack8(x0, x1);
;                     } else if (GI == 1) {
; #pragma unroll
;                         for (int j = 0; j < 4; ++j) { x0[j] = sigmoidf_(x0[j]); x1[j] = sigmoidf_(x1[j]); }
;                         *(u32x4*)(Ab + row * DM + c) = pack8(x0, x1);
;                     } else if (GI == 2) {
;                         *(u32x4*)(Gb + row * DM + c) = pack8(x0, x1);
;                     } else {
;                         h16* vp = C1 + row * LDC1 + 4096 + c;
;                         const h16x8 vv = *(const h16x8*)vp; const h16x8 vf = *(const h16x8*)(VF + row * DM + c);
;                         f32x4 o0, o1;
; #pragma unroll
;                         for (int j = 0; j < 4; ++j) { float v = (float)vv[j], f = (float)vf[j]; o0[j] = v + (f - v) * sigmoidf_(x0[j]); v = (float)vv[4 + j]; f = (float)vf[4 + j]; o1[j] = v + (f - v) * sigmoidf_(x1[j]); }
;                         *(u32x4*)vp = pack8(o0, o1);
	v_rcp_f32_e32 v110, v99
	v_cvt_f32_f16_e32 v104, v111
	v_cvt_f32_f16_sdwa v105, v111 dst_sel:DWORD dst_unused:UNUSED_PAD src0_sel:WORD_1
	v_fma_f32 v111, -v99, v110, 1.0
	v_fmac_f32_e32 v110, v111, v110
	v_div_scale_f32 v111, vcc, 1.0, v107, 1.0
	v_mul_f32_e32 v126, v111, v110
	v_fma_f32 v127, -v99, v126, v111
	v_fmac_f32_e32 v126, v127, v110
	v_fma_f32 v99, -v99, v126, v111
	v_div_fmas_f32 v99, v99, v110, v126
	v_div_fixup_f32 v107, v99, v107, 1.0
	v_div_scale_f32 v99, s[0:1], v106, v106, 1.0
	v_rcp_f32_e32 v110, v99
	v_pk_add_f32 v[104:105], v[104:105], v[100:101] neg_lo:[0,1] neg_hi:[0,1]
	v_fma_f32 v111, -v99, v110, 1.0
	v_fmac_f32_e32 v110, v111, v110
	v_div_scale_f32 v111, vcc, 1.0, v106, 1.0
	v_mul_f32_e32 v126, v111, v110
	v_fma_f32 v127, -v99, v126, v111
	v_fmac_f32_e32 v126, v127, v110
	v_fma_f32 v99, -v99, v126, v111
	v_div_fmas_f32 v99, v99, v110, v126
	v_div_fixup_f32 v106, v99, v106, 1.0
	v_pk_fma_f32 v[100:101], v[106:107], v[104:105], v[100:101]
	v_pk_add_f32 v[106:107], v[120:121], 1.0 op_sel_hi:[1,0]
	v_cvt_pk_f16_f32 v99, v100, v101
	v_cvt_f32_f16_e32 v100, v108
	v_cvt_f32_f16_sdwa v101, v108 dst_sel:DWORD dst_unused:UNUSED_PAD src0_sel:WORD_1
	v_div_scale_f32 v108, s[0:1], v107, v107, 1.0
	v_rcp_f32_e32 v110, v108
	v_cvt_f32_f16_e32 v104, v112
	v_cvt_f32_f16_sdwa v105, v112 dst_sel:DWORD dst_unused:UNUSED_PAD src0_sel:WORD_1
	v_fma_f32 v111, -v108, v110, 1.0
	v_fmac_f32_e32 v110, v111, v110
	v_div_scale_f32 v111, vcc, 1.0, v107, 1.0
	v_mul_f32_e32 v112, v111, v110
	v_fma_f32 v120, -v108, v112, v111
	v_fmac_f32_e32 v112, v120, v110
	v_fma_f32 v108, -v108, v112, v111
	v_div_fmas_f32 v108, v108, v110, v112
	v_div_fixup_f32 v107, v108, v107, 1.0
	v_div_scale_f32 v108, s[0:1], v106, v106, 1.0
	v_rcp_f32_e32 v110, v108
	v_pk_add_f32 v[104:105], v[104:105], v[100:101] neg_lo:[0,1] neg_hi:[0,1]
	v_fma_f32 v111, -v108, v110, 1.0
	v_fmac_f32_e32 v110, v111, v110
	v_div_scale_f32 v111, vcc, 1.0, v106, 1.0
	v_mul_f32_e32 v112, v111, v110
	v_fma_f32 v120, -v108, v112, v111
	v_fmac_f32_e32 v112, v120, v110
	v_fma_f32 v108, -v108, v112, v111
	v_div_fmas_f32 v108, v108, v110, v112
	v_div_fixup_f32 v106, v108, v106, 1.0
	v_pk_fma_f32 v[100:101], v[106:107], v[104:105], v[100:101]
	v_cvt_f32_f16_e32 v104, v109
	v_cvt_pk_f16_f32 v100, v100, v101
	v_div_scale_f32 v101, s[0:1], v103, v103, 1.0
	v_rcp_f32_e32 v108, v101
	v_cvt_f32_f16_sdwa v105, v109 dst_sel:DWORD dst_unused:UNUSED_PAD src0_sel:WORD_1
	v_cvt_f32_f16_e32 v106, v113
	v_cvt_f32_f16_sdwa v107, v113 dst_sel:DWORD dst_unused:UNUSED_PAD src0_sel:WORD_1
	v_fma_f32 v109, -v101, v108, 1.0
	v_fmac_f32_e32 v108, v109, v108
	v_div_scale_f32 v109, vcc, 1.0, v103, 1.0
	v_mul_f32_e32 v110, v109, v108
	v_fma_f32 v111, -v101, v110, v109
	v_fmac_f32_e32 v110, v111, v108
	v_fma_f32 v101, -v101, v110, v109
	v_div_fmas_f32 v101, v101, v108, v110
	v_div_fixup_f32 v103, v101, v103, 1.0
	v_div_scale_f32 v101, s[0:1], v102, v102, 1.0
	v_rcp_f32_e32 v108, v101
	v_pk_add_f32 v[106:107], v[106:107], v[104:105] neg_lo:[0,1] neg_hi:[0,1]
	v_fma_f32 v109, -v101, v108, 1.0
	v_fmac_f32_e32 v108, v109, v108
	v_div_scale_f32 v109, vcc, 1.0, v102, 1.0
	v_mul_f32_e32 v110, v109, v108
	v_fma_f32 v111, -v101, v110, v109
	v_fmac_f32_e32 v110, v111, v108
	v_fma_f32 v101, -v101, v110, v109
	v_div_fmas_f32 v101, v101, v108, v110
	v_div_fixup_f32 v102, v101, v102, 1.0
	v_pk_fma_f32 v[102:103], v[102:103], v[106:107], v[104:105]
	s_nop 0
	v_cvt_pk_f16_f32 v101, v102, v103
	global_store_dwordx4 v[118:119], v[98:101], off
	v_add_u32_e32 v102, 0x90, v164
	v_ashrrev_i32_e32 v103, 31, v102
	v_mad_i64_i32 v[98:99], s[0:1], v102, s5, v[168:169]
	v_lshl_add_u64 v[106:107], v[98:99], 0, s[90:91]
	v_lshlrev_b64 v[102:103], 12, v[102:103]
	v_lshl_add_u64 v[110:111], v[106:107], 0, v[166:167]
	v_lshl_add_u64 v[102:103], s[2:3], 0, v[102:103]
	global_load_dwordx4 v[98:101], v[110:111], off
	v_lshl_add_u64 v[108:109], v[102:103], 0, v[166:167]
	global_load_dwordx4 v[102:105], v[108:109], off
	v_add_f32_e32 v90, v90, v82
	v_mul_f32_e32 v90, 0xbfb8aa3b, v90
	v_exp_f32_e32 v112, v90
	v_add_f32_e32 v90, v95, v87
	v_mul_f32_e32 v90, 0xbfb8aa3b, v90
	v_exp_f32_e32 v121, v90
	v_add_f32_e32 v90, v91, v83
	v_mul_f32_e32 v90, 0xbfb8aa3b, v90
	v_exp_f32_e32 v113, v90
	v_add_f32_e32 v90, v96, v88
	v_add_f32_e32 v94, v94, v86
	v_mul_f32_e32 v90, 0xbfb8aa3b, v90
	v_mul_f32_e32 v94, 0xbfb8aa3b, v94
	v_exp_f32_e32 v118, v90
	v_add_f32_e32 v90, v92, v84
	v_exp_f32_e32 v120, v94
	v_mul_f32_e32 v90, 0xbfb8aa3b, v90
	v_exp_f32_e32 v94, v90
	v_add_f32_e32 v90, v97, v89
	v_mul_f32_e32 v90, 0xbfb8aa3b, v90
	v_exp_f32_e32 v119, v90
	v_add_f32_e32 v90, v93, v85
	v_mul_f32_e32 v90, 0xbfb8aa3b, v90
	v_pk_add_f32 v[96:97], v[120:121], 1.0 op_sel_hi:[1,0]
	v_exp_f32_e32 v95, v90
	s_waitcnt vmcnt(0)
; __device__ __forceinline__ float sigmoidf_(float x) { return 1.0f / (1.0f + __expf(-x)); }
;     template <int GI>
;     __device__ __forceinline__ void body(const f32x4 (&acc)[2][2][4][2], int row0, int colt) const {
;     ...
;                     const size_t row = (size_t)(row0 + ai * 128 + m * 16);
;                     f32x4 x0 = acc[ai][bj][m][0] + b0, x1 = acc[ai][bj][m][1] + b1;
;                     if (GI == 0) {
; #pragma unroll
;                         for (int j = 0; j < 4; ++j) {
;                             x0[j] = 0.6065306597126334f * sigmoidf_(x0[j]); x1[j] = 0.6065306597126334f * sigmoidf_(x1[j]); }
;                         *(u32x4*)(DEC + row * DM + c) = pack8(x0, x1);
;                     } else if (GI == 1) {
; #pragma unroll
;                         for (int j = 0; j < 4; ++j) { x0[j] = sigmoidf_(x0[j]); x1[j] = sigmoidf_(x1[j]); }
;                         *(u32x4*)(Ab + row * DM + c) = pack8(x0, x1);
;                     } else if (GI == 2) {
;                         *(u32x4*)(Gb + row * DM + c) = pack8(x0, x1);
;                     } else {
;                         h16* vp = C1 + row * LDC1 + 4096 + c;
;                         const h16x8 vv = *(const h16x8*)vp; const h16x8 vf = *(const h16x8*)(VF + row * DM + c);
;                         f32x4 o0, o1;
; #pragma unroll
;                         for (int j = 0; j < 4; ++j) { float v = (float)vv[j], f = (float)vf[j]; o0[j] = v + (f - v) * sigmoidf_(x0[j]); v = (float)vv[4 + j]; f = (float)vf[4 + j]; o1[j] = v + (f - v) * sigmoidf_(x1[j]); }
;                         *(u32x4*)vp = pack8(o0, o1);
	v_cvt_f32_f16_e32 v90, v98
	v_cvt_f32_f16_sdwa v91, v98 dst_sel:DWORD dst_unused:UNUSED_PAD src0_sel:WORD_1
	v_div_scale_f32 v98, s[0:1], v97, v97, 1.0
	v_cvt_f32_f16_e32 v92, v102
	v_cvt_f32_f16_sdwa v93, v102 dst_sel:DWORD dst_unused:UNUSED_PAD src0_sel:WORD_1
	v_rcp_f32_e32 v102, v98
	v_pk_add_f32 v[94:95], v[94:95], 1.0 op_sel_hi:[1,0]
	v_pk_add_f32 v[92:93], v[92:93], v[90:91] neg_lo:[0,1] neg_hi:[0,1]
	v_fma_f32 v120, -v98, v102, 1.0
	v_fmac_f32_e32 v102, v120, v102
	v_div_scale_f32 v120, vcc, 1.0, v97, 1.0
	v_mul_f32_e32 v121, v120, v102
	v_fma_f32 v126, -v98, v121, v120
	v_fmac_f32_e32 v121, v126, v102
	v_fma_f32 v98, -v98, v121, v120
	v_div_fmas_f32 v98, v98, v102, v121
	v_div_fixup_f32 v97, v98, v97, 1.0
	v_div_scale_f32 v98, s[0:1], v96, v96, 1.0
	v_rcp_f32_e32 v102, v98
	s_nop 0
	v_fma_f32 v120, -v98, v102, 1.0
	v_fmac_f32_e32 v102, v120, v102
	v_div_scale_f32 v120, vcc, 1.0, v96, 1.0
	v_mul_f32_e32 v121, v120, v102
	v_fma_f32 v126, -v98, v121, v120
	v_fmac_f32_e32 v121, v126, v102
	v_fma_f32 v98, -v98, v121, v120
	v_div_fmas_f32 v98, v98, v102, v121
	v_div_fixup_f32 v96, v98, v96, 1.0
	v_pk_fma_f32 v[90:91], v[96:97], v[92:93], v[90:91]
	v_cvt_f32_f16_e32 v92, v99
	v_cvt_f32_f16_sdwa v93, v99 dst_sel:DWORD dst_unused:UNUSED_PAD src0_sel:WORD_1
	v_pk_add_f32 v[98:99], v[118:119], 1.0 op_sel_hi:[1,0]
	v_cvt_pk_f16_f32 v90, v90, v91
	v_div_scale_f32 v91, s[0:1], v99, v99, 1.0
	v_rcp_f32_e32 v102, v91
	v_cvt_f32_f16_e32 v96, v103
	v_cvt_f32_f16_sdwa v97, v103 dst_sel:DWORD dst_unused:UNUSED_PAD src0_sel:WORD_1
	v_fma_f32 v103, -v91, v102, 1.0
	v_fmac_f32_e32 v102, v103, v102
	v_div_scale_f32 v103, vcc, 1.0, v99, 1.0
	v_mul_f32_e32 v118, v103, v102
	v_fma_f32 v119, -v91, v118, v103
	v_fmac_f32_e32 v118, v119, v102
	v_fma_f32 v91, -v91, v118, v103
	v_div_fmas_f32 v91, v91, v102, v118
	v_div_fixup_f32 v99, v91, v99, 1.0
	v_div_scale_f32 v91, s[0:1], v98, v98, 1.0
	v_rcp_f32_e32 v102, v91
	v_pk_add_f32 v[96:97], v[96:97], v[92:93] neg_lo:[0,1] neg_hi:[0,1]
	v_fma_f32 v103, -v91, v102, 1.0
	v_fmac_f32_e32 v102, v103, v102
	v_div_scale_f32 v103, vcc, 1.0, v98, 1.0
	v_mul_f32_e32 v118, v103, v102
	v_fma_f32 v119, -v91, v118, v103
	v_fmac_f32_e32 v118, v119, v102
	v_fma_f32 v91, -v91, v118, v103
	v_div_fmas_f32 v91, v91, v102, v118
	v_div_fixup_f32 v98, v91, v98, 1.0
	v_pk_fma_f32 v[92:93], v[98:99], v[96:97], v[92:93]
	v_pk_add_f32 v[98:99], v[112:113], 1.0 op_sel_hi:[1,0]
	v_cvt_pk_f16_f32 v91, v92, v93
	v_cvt_f32_f16_e32 v92, v100
	v_cvt_f32_f16_sdwa v93, v100 dst_sel:DWORD dst_unused:UNUSED_PAD src0_sel:WORD_1
	v_div_scale_f32 v100, s[0:1], v99, v99, 1.0
	v_rcp_f32_e32 v102, v100
	v_cvt_f32_f16_e32 v96, v104
	v_cvt_f32_f16_sdwa v97, v104 dst_sel:DWORD dst_unused:UNUSED_PAD src0_sel:WORD_1
	v_fma_f32 v103, -v100, v102, 1.0
	v_fmac_f32_e32 v102, v103, v102
	v_div_scale_f32 v103, vcc, 1.0, v99, 1.0
	v_mul_f32_e32 v104, v103, v102
	v_fma_f32 v112, -v100, v104, v103
	v_fmac_f32_e32 v104, v112, v102
	v_fma_f32 v100, -v100, v104, v103
	v_div_fmas_f32 v100, v100, v102, v104
	v_div_fixup_f32 v99, v100, v99, 1.0
	v_div_scale_f32 v100, s[0:1], v98, v98, 1.0
	v_rcp_f32_e32 v102, v100
	v_pk_add_f32 v[96:97], v[96:97], v[92:93] neg_lo:[0,1] neg_hi:[0,1]
	v_fma_f32 v103, -v100, v102, 1.0
	v_fmac_f32_e32 v102, v103, v102
	v_div_scale_f32 v103, vcc, 1.0, v98, 1.0
	v_mul_f32_e32 v104, v103, v102
	v_fma_f32 v112, -v100, v104, v103
	v_fmac_f32_e32 v104, v112, v102
	v_fma_f32 v100, -v100, v104, v103
	v_div_fmas_f32 v100, v100, v102, v104
	v_div_fixup_f32 v98, v100, v98, 1.0
	v_pk_fma_f32 v[92:93], v[98:99], v[96:97], v[92:93]
	v_cvt_f32_f16_e32 v96, v101
	v_cvt_pk_f16_f32 v92, v92, v93
	v_div_scale_f32 v93, s[0:1], v95, v95, 1.0
	v_rcp_f32_e32 v100, v93
	v_cvt_f32_f16_sdwa v97, v101 dst_sel:DWORD dst_unused:UNUSED_PAD src0_sel:WORD_1
	v_cvt_f32_f16_e32 v98, v105
	v_cvt_f32_f16_sdwa v99, v105 dst_sel:DWORD dst_unused:UNUSED_PAD src0_sel:WORD_1
	v_fma_f32 v101, -v93, v100, 1.0
	v_fmac_f32_e32 v100, v101, v100
	v_div_scale_f32 v101, vcc, 1.0, v95, 1.0
	v_mul_f32_e32 v102, v101, v100
	v_fma_f32 v103, -v93, v102, v101
	v_fmac_f32_e32 v102, v103, v100
	v_fma_f32 v93, -v93, v102, v101
	v_div_fmas_f32 v93, v93, v100, v102
	v_div_fixup_f32 v95, v93, v95, 1.0
	v_div_scale_f32 v93, s[0:1], v94, v94, 1.0
	v_rcp_f32_e32 v100, v93
	v_pk_add_f32 v[98:99], v[98:99], v[96:97] neg_lo:[0,1] neg_hi:[0,1]
	v_fma_f32 v101, -v93, v100, 1.0
	v_fmac_f32_e32 v100, v101, v100
	v_div_scale_f32 v101, vcc, 1.0, v94, 1.0
	v_mul_f32_e32 v102, v101, v100
	v_fma_f32 v103, -v93, v102, v101
	v_fmac_f32_e32 v102, v103, v100
	v_fma_f32 v93, -v93, v102, v101
	v_div_fmas_f32 v93, v93, v100, v102
	v_div_fixup_f32 v94, v93, v94, 1.0
	v_pk_fma_f32 v[94:95], v[94:95], v[98:99], v[96:97]
	s_nop 0
	v_cvt_pk_f16_f32 v93, v94, v95
	global_store_dwordx4 v[110:111], v[90:93], off
	v_add_u32_e32 v94, 0xa0, v164
	v_ashrrev_i32_e32 v95, 31, v94
	v_mad_i64_i32 v[90:91], s[0:1], v94, s5, v[168:169]
	v_lshl_add_u64 v[98:99], v[90:91], 0, s[90:91]
	v_lshlrev_b64 v[94:95], 12, v[94:95]
	v_lshl_add_u64 v[102:103], v[98:99], 0, v[166:167]
	v_lshl_add_u64 v[94:95], s[2:3], 0, v[94:95]
	global_load_dwordx4 v[90:93], v[102:103], off
	v_lshl_add_u64 v[100:101], v[94:95], 0, v[166:167]
	global_load_dwordx4 v[94:97], v[100:101], off
	v_add_f32_e32 v74, v74, v82
	v_mul_f32_e32 v74, 0xbfb8aa3b, v74
	v_exp_f32_e32 v104, v74
	v_add_f32_e32 v74, v79, v87
	v_mul_f32_e32 v74, 0xbfb8aa3b, v74
	v_exp_f32_e32 v113, v74
	v_add_f32_e32 v74, v75, v83
	v_mul_f32_e32 v74, 0xbfb8aa3b, v74
	v_exp_f32_e32 v105, v74
	v_add_f32_e32 v74, v80, v88
	v_add_f32_e32 v78, v78, v86
	v_mul_f32_e32 v74, 0xbfb8aa3b, v74
	v_mul_f32_e32 v78, 0xbfb8aa3b, v78
	v_exp_f32_e32 v110, v74
	v_add_f32_e32 v74, v76, v84
	v_exp_f32_e32 v112, v78
	v_mul_f32_e32 v74, 0xbfb8aa3b, v74
	v_exp_f32_e32 v78, v74
	v_add_f32_e32 v74, v81, v89
	v_mul_f32_e32 v74, 0xbfb8aa3b, v74
	v_exp_f32_e32 v111, v74
	v_add_f32_e32 v74, v77, v85
	v_mul_f32_e32 v74, 0xbfb8aa3b, v74
	v_pk_add_f32 v[80:81], v[112:113], 1.0 op_sel_hi:[1,0]
	v_exp_f32_e32 v79, v74
	s_waitcnt vmcnt(0)
; __device__ __forceinline__ float sigmoidf_(float x) { return 1.0f / (1.0f + __expf(-x)); }
;     template <int GI>
;     __device__ __forceinline__ void body(const f32x4 (&acc)[2][2][4][2], int row0, int colt) const {
;     ...
;                     const size_t row = (size_t)(row0 + ai * 128 + m * 16);
;                     f32x4 x0 = acc[ai][bj][m][0] + b0, x1 = acc[ai][bj][m][1] + b1;
;                     if (GI == 0) {
; #pragma unroll
;                         for (int j = 0; j < 4; ++j) {
;                             x0[j] = 0.6065306597126334f * sigmoidf_(x0[j]); x1[j] = 0.6065306597126334f * sigmoidf_(x1[j]); }
;                         *(u32x4*)(DEC + row * DM + c) = pack8(x0, x1);
;                     } else if (GI == 1) {
; #pragma unroll
;                         for (int j = 0; j < 4; ++j) { x0[j] = sigmoidf_(x0[j]); x1[j] = sigmoidf_(x1[j]); }
;                         *(u32x4*)(Ab + row * DM + c) = pack8(x0, x1);
;                     } else if (GI == 2) {
;                         *(u32x4*)(Gb + row * DM + c) = pack8(x0, x1);
;                     } else {
;                         h16* vp = C1 + row * LDC1 + 4096 + c;
;                         const h16x8 vv = *(const h16x8*)vp; const h16x8 vf = *(const h16x8*)(VF + row * DM + c);
;                         f32x4 o0, o1;
; #pragma unroll
;                         for (int j = 0; j < 4; ++j) { float v = (float)vv[j], f = (float)vf[j]; o0[j] = v + (f - v) * sigmoidf_(x0[j]); v = (float)vv[4 + j]; f = (float)vf[4 + j]; o1[j] = v + (f - v) * sigmoidf_(x1[j]); }
;                         *(u32x4*)vp = pack8(o0, o1);
	v_cvt_f32_f16_e32 v74, v90
	v_cvt_f32_f16_sdwa v75, v90 dst_sel:DWORD dst_unused:UNUSED_PAD src0_sel:WORD_1
	v_div_scale_f32 v90, s[0:1], v81, v81, 1.0
	v_cvt_f32_f16_e32 v76, v94
	v_cvt_f32_f16_sdwa v77, v94 dst_sel:DWORD dst_unused:UNUSED_PAD src0_sel:WORD_1
	v_rcp_f32_e32 v94, v90
	v_pk_add_f32 v[78:79], v[78:79], 1.0 op_sel_hi:[1,0]
	v_pk_add_f32 v[76:77], v[76:77], v[74:75] neg_lo:[0,1] neg_hi:[0,1]
	v_fma_f32 v112, -v90, v94, 1.0
	v_fmac_f32_e32 v94, v112, v94
	v_div_scale_f32 v112, vcc, 1.0, v81, 1.0
	v_mul_f32_e32 v113, v112, v94
	v_fma_f32 v118, -v90, v113, v112
	v_fmac_f32_e32 v113, v118, v94
	v_fma_f32 v90, -v90, v113, v112
	v_div_fmas_f32 v90, v90, v94, v113
	v_div_fixup_f32 v81, v90, v81, 1.0
	v_div_scale_f32 v90, s[0:1], v80, v80, 1.0
	v_rcp_f32_e32 v94, v90
	s_nop 0
	v_fma_f32 v112, -v90, v94, 1.0
	v_fmac_f32_e32 v94, v112, v94
	v_div_scale_f32 v112, vcc, 1.0, v80, 1.0
	v_mul_f32_e32 v113, v112, v94
	v_fma_f32 v118, -v90, v113, v112
	v_fmac_f32_e32 v113, v118, v94
	v_fma_f32 v90, -v90, v113, v112
	v_div_fmas_f32 v90, v90, v94, v113
	v_div_fixup_f32 v80, v90, v80, 1.0
	v_pk_fma_f32 v[74:75], v[80:81], v[76:77], v[74:75]
	v_cvt_f32_f16_e32 v76, v91
	v_cvt_f32_f16_sdwa v77, v91 dst_sel:DWORD dst_unused:UNUSED_PAD src0_sel:WORD_1
	v_pk_add_f32 v[90:91], v[110:111], 1.0 op_sel_hi:[1,0]
	v_cvt_pk_f16_f32 v74, v74, v75
	v_div_scale_f32 v75, s[0:1], v91, v91, 1.0
	v_rcp_f32_e32 v94, v75
	v_cvt_f32_f16_e32 v80, v95
	v_cvt_f32_f16_sdwa v81, v95 dst_sel:DWORD dst_unused:UNUSED_PAD src0_sel:WORD_1
	v_fma_f32 v95, -v75, v94, 1.0
	v_fmac_f32_e32 v94, v95, v94
	v_div_scale_f32 v95, vcc, 1.0, v91, 1.0
	v_mul_f32_e32 v110, v95, v94
	v_fma_f32 v111, -v75, v110, v95
	v_fmac_f32_e32 v110, v111, v94
	v_fma_f32 v75, -v75, v110, v95
	v_div_fmas_f32 v75, v75, v94, v110
	v_div_fixup_f32 v91, v75, v91, 1.0
	v_div_scale_f32 v75, s[0:1], v90, v90, 1.0
	v_rcp_f32_e32 v94, v75
	v_pk_add_f32 v[80:81], v[80:81], v[76:77] neg_lo:[0,1] neg_hi:[0,1]
	v_fma_f32 v95, -v75, v94, 1.0
	v_fmac_f32_e32 v94, v95, v94
	v_div_scale_f32 v95, vcc, 1.0, v90, 1.0
	v_mul_f32_e32 v110, v95, v94
	v_fma_f32 v111, -v75, v110, v95
	v_fmac_f32_e32 v110, v111, v94
	v_fma_f32 v75, -v75, v110, v95
	v_div_fmas_f32 v75, v75, v94, v110
	v_div_fixup_f32 v90, v75, v90, 1.0
	v_pk_fma_f32 v[76:77], v[90:91], v[80:81], v[76:77]
	v_pk_add_f32 v[90:91], v[104:105], 1.0 op_sel_hi:[1,0]
	v_cvt_pk_f16_f32 v75, v76, v77
	v_cvt_f32_f16_e32 v76, v92
	v_cvt_f32_f16_sdwa v77, v92 dst_sel:DWORD dst_unused:UNUSED_PAD src0_sel:WORD_1
	v_div_scale_f32 v92, s[0:1], v91, v91, 1.0
	v_rcp_f32_e32 v94, v92
	v_cvt_f32_f16_e32 v80, v96
	v_cvt_f32_f16_sdwa v81, v96 dst_sel:DWORD dst_unused:UNUSED_PAD src0_sel:WORD_1
	v_fma_f32 v95, -v92, v94, 1.0
	v_fmac_f32_e32 v94, v95, v94
	v_div_scale_f32 v95, vcc, 1.0, v91, 1.0
	v_mul_f32_e32 v96, v95, v94
	v_fma_f32 v104, -v92, v96, v95
	v_fmac_f32_e32 v96, v104, v94
	v_fma_f32 v92, -v92, v96, v95
	v_div_fmas_f32 v92, v92, v94, v96
	v_div_fixup_f32 v91, v92, v91, 1.0
	v_div_scale_f32 v92, s[0:1], v90, v90, 1.0
	v_rcp_f32_e32 v94, v92
	v_pk_add_f32 v[80:81], v[80:81], v[76:77] neg_lo:[0,1] neg_hi:[0,1]
	v_fma_f32 v95, -v92, v94, 1.0
	v_fmac_f32_e32 v94, v95, v94
	v_div_scale_f32 v95, vcc, 1.0, v90, 1.0
	v_mul_f32_e32 v96, v95, v94
	v_fma_f32 v104, -v92, v96, v95
	v_fmac_f32_e32 v96, v104, v94
	v_fma_f32 v92, -v92, v96, v95
	v_div_fmas_f32 v92, v92, v94, v96
	v_div_fixup_f32 v90, v92, v90, 1.0
	v_pk_fma_f32 v[76:77], v[90:91], v[80:81], v[76:77]
	v_cvt_f32_f16_e32 v80, v93
	v_cvt_pk_f16_f32 v76, v76, v77
	v_div_scale_f32 v77, s[0:1], v79, v79, 1.0
	v_rcp_f32_e32 v92, v77
	v_cvt_f32_f16_sdwa v81, v93 dst_sel:DWORD dst_unused:UNUSED_PAD src0_sel:WORD_1
	v_cvt_f32_f16_e32 v90, v97
	v_cvt_f32_f16_sdwa v91, v97 dst_sel:DWORD dst_unused:UNUSED_PAD src0_sel:WORD_1
	v_fma_f32 v93, -v77, v92, 1.0
	v_fmac_f32_e32 v92, v93, v92
	v_div_scale_f32 v93, vcc, 1.0, v79, 1.0
	v_mul_f32_e32 v94, v93, v92
	v_fma_f32 v95, -v77, v94, v93
	v_fmac_f32_e32 v94, v95, v92
	v_fma_f32 v77, -v77, v94, v93
	v_div_fmas_f32 v77, v77, v92, v94
	v_div_fixup_f32 v79, v77, v79, 1.0
	v_div_scale_f32 v77, s[0:1], v78, v78, 1.0
	v_rcp_f32_e32 v92, v77
	v_pk_add_f32 v[90:91], v[90:91], v[80:81] neg_lo:[0,1] neg_hi:[0,1]
	v_fma_f32 v93, -v77, v92, 1.0
	v_fmac_f32_e32 v92, v93, v92
	v_div_scale_f32 v93, vcc, 1.0, v78, 1.0
	v_mul_f32_e32 v94, v93, v92
	v_fma_f32 v95, -v77, v94, v93
	v_fmac_f32_e32 v94, v95, v92
	v_fma_f32 v77, -v77, v94, v93
	v_div_fmas_f32 v77, v77, v92, v94
	v_div_fixup_f32 v78, v77, v78, 1.0
	v_pk_fma_f32 v[78:79], v[78:79], v[90:91], v[80:81]
	s_nop 0
	v_cvt_pk_f16_f32 v77, v78, v79
	global_store_dwordx4 v[102:103], v[74:77], off
	v_add_u32_e32 v78, 0xb0, v164
	v_ashrrev_i32_e32 v79, 31, v78
	v_mad_i64_i32 v[74:75], s[0:1], v78, s5, v[168:169]
	v_lshl_add_u64 v[90:91], v[74:75], 0, s[90:91]
	v_lshlrev_b64 v[78:79], 12, v[78:79]
	v_lshl_add_u64 v[94:95], v[90:91], 0, v[166:167]
	v_lshl_add_u64 v[78:79], s[2:3], 0, v[78:79]
	global_load_dwordx4 v[74:77], v[94:95], off
	v_lshl_add_u64 v[92:93], v[78:79], 0, v[166:167]
	global_load_dwordx4 v[78:81], v[92:93], off
	v_add_f32_e32 v66, v66, v82
	v_mul_f32_e32 v66, 0xbfb8aa3b, v66
	v_exp_f32_e32 v82, v66
	v_add_f32_e32 v66, v71, v87
	v_mul_f32_e32 v66, 0xbfb8aa3b, v66
	v_exp_f32_e32 v97, v66
	v_add_f32_e32 v66, v67, v83
	v_mul_f32_e32 v66, 0xbfb8aa3b, v66
	v_exp_f32_e32 v83, v66
	v_add_f32_e32 v66, v72, v88
	v_add_f32_e32 v70, v70, v86
	v_mul_f32_e32 v66, 0xbfb8aa3b, v66
	v_mul_f32_e32 v70, 0xbfb8aa3b, v70
	v_exp_f32_e32 v86, v66
	v_add_f32_e32 v66, v68, v84
	v_exp_f32_e32 v96, v70
	v_mul_f32_e32 v66, 0xbfb8aa3b, v66
	v_exp_f32_e32 v70, v66
	v_add_f32_e32 v66, v73, v89
	v_mul_f32_e32 v66, 0xbfb8aa3b, v66
	v_exp_f32_e32 v87, v66
	v_add_f32_e32 v66, v69, v85
	v_mul_f32_e32 v66, 0xbfb8aa3b, v66
	v_pk_add_f32 v[72:73], v[96:97], 1.0 op_sel_hi:[1,0]
	v_exp_f32_e32 v71, v66
	s_waitcnt vmcnt(0)
; __device__ __forceinline__ float sigmoidf_(float x) { return 1.0f / (1.0f + __expf(-x)); }
;     template <int GI>
;     __device__ __forceinline__ void body(const f32x4 (&acc)[2][2][4][2], int row0, int colt) const {
;     ...
;             if (GI == 0) { b0 = *(const f32x4*)(w0 + c); b1 = *(const f32x4*)(w0 + c + 4); }
;             else if (GI == 1) { b0 = *(const f32x4*)(a0 + c); b1 = *(const f32x4*)(a0 + c + 4); }
;             else if (GI == 3) { b0 = *(const f32x4*)(v0 + c); b1 = *(const f32x4*)(v0 + c + 4); }
; #pragma unroll
;             for (int ai = 0; ai < 2; ++ai)
; #pragma unroll
;                 for (int m = 0; m < 4; ++m) {
;                     const size_t row = (size_t)(row0 + ai * 128 + m * 16);
;                     f32x4 x0 = acc[ai][bj][m][0] + b0, x1 = acc[ai][bj][m][1] + b1;
;                     if (GI == 0) {
; #pragma unroll
;                         for (int j = 0; j < 4; ++j) {
;                             x0[j] = 0.6065306597126334f * sigmoidf_(x0[j]); x1[j] = 0.6065306597126334f * sigmoidf_(x1[j]); }
;                         *(u32x4*)(DEC + row * DM + c) = pack8(x0, x1);
;                     } else if (GI == 1) {
; #pragma unroll
;                         for (int j = 0; j < 4; ++j) { x0[j] = sigmoidf_(x0[j]); x1[j] = sigmoidf_(x1[j]); }
;                         *(u32x4*)(Ab + row * DM + c) = pack8(x0, x1);
;                     } else if (GI == 2) {
;                         *(u32x4*)(Gb + row * DM + c) = pack8(x0, x1);
;                     } else {
;                         h16* vp = C1 + row * LDC1 + 4096 + c;
;                         const h16x8 vv = *(const h16x8*)vp; const h16x8 vf = *(const h16x8*)(VF + row * DM + c);
;                         f32x4 o0, o1;
; #pragma unroll
;                         for (int j = 0; j < 4; ++j) { float v = (float)vv[j], f = (float)vf[j]; o0[j] = v + (f - v) * sigmoidf_(x0[j]); v = (float)vv[4 + j]; f = (float)vf[4 + j]; o1[j] = v + (f - v) * sigmoidf_(x1[j]); }
;                         *(u32x4*)vp = pack8(o0, o1);
	v_cvt_f32_f16_e32 v66, v74
	v_cvt_f32_f16_sdwa v67, v74 dst_sel:DWORD dst_unused:UNUSED_PAD src0_sel:WORD_1
	v_div_scale_f32 v74, s[0:1], v73, v73, 1.0
	v_cvt_f32_f16_e32 v68, v78
	v_cvt_f32_f16_sdwa v69, v78 dst_sel:DWORD dst_unused:UNUSED_PAD src0_sel:WORD_1
	v_rcp_f32_e32 v78, v74
	v_pk_add_f32 v[70:71], v[70:71], 1.0 op_sel_hi:[1,0]
	v_pk_add_f32 v[68:69], v[68:69], v[66:67] neg_lo:[0,1] neg_hi:[0,1]
	v_fma_f32 v84, -v74, v78, 1.0
	v_fmac_f32_e32 v78, v84, v78
	v_div_scale_f32 v84, vcc, 1.0, v73, 1.0
	v_mul_f32_e32 v85, v84, v78
	v_fma_f32 v88, -v74, v85, v84
	v_fmac_f32_e32 v85, v88, v78
	v_fma_f32 v74, -v74, v85, v84
	v_div_fmas_f32 v74, v74, v78, v85
	v_div_fixup_f32 v73, v74, v73, 1.0
	v_div_scale_f32 v74, s[0:1], v72, v72, 1.0
	v_rcp_f32_e32 v78, v74
	s_nop 0
	v_fma_f32 v84, -v74, v78, 1.0
	v_fmac_f32_e32 v78, v84, v78
	v_div_scale_f32 v84, vcc, 1.0, v72, 1.0
	v_mul_f32_e32 v85, v84, v78
	v_fma_f32 v88, -v74, v85, v84
	v_fmac_f32_e32 v85, v88, v78
	v_fma_f32 v74, -v74, v85, v84
	v_div_fmas_f32 v74, v74, v78, v85
	v_div_fixup_f32 v72, v74, v72, 1.0
	v_pk_fma_f32 v[66:67], v[72:73], v[68:69], v[66:67]
	v_cvt_f32_f16_e32 v68, v75
	v_cvt_f32_f16_sdwa v69, v75 dst_sel:DWORD dst_unused:UNUSED_PAD src0_sel:WORD_1
	v_pk_add_f32 v[74:75], v[86:87], 1.0 op_sel_hi:[1,0]
	v_cvt_pk_f16_f32 v66, v66, v67
	v_div_scale_f32 v67, s[0:1], v75, v75, 1.0
	v_rcp_f32_e32 v78, v67
	v_cvt_f32_f16_e32 v72, v79
	v_cvt_f32_f16_sdwa v73, v79 dst_sel:DWORD dst_unused:UNUSED_PAD src0_sel:WORD_1
	v_fma_f32 v79, -v67, v78, 1.0
	v_fmac_f32_e32 v78, v79, v78
	v_div_scale_f32 v79, vcc, 1.0, v75, 1.0
	v_mul_f32_e32 v84, v79, v78
	v_fma_f32 v85, -v67, v84, v79
	v_fmac_f32_e32 v84, v85, v78
	v_fma_f32 v67, -v67, v84, v79
	v_div_fmas_f32 v67, v67, v78, v84
	v_div_fixup_f32 v75, v67, v75, 1.0
	v_div_scale_f32 v67, s[0:1], v74, v74, 1.0
	v_rcp_f32_e32 v78, v67
	v_pk_add_f32 v[72:73], v[72:73], v[68:69] neg_lo:[0,1] neg_hi:[0,1]
	v_fma_f32 v79, -v67, v78, 1.0
	v_fmac_f32_e32 v78, v79, v78
	v_div_scale_f32 v79, vcc, 1.0, v74, 1.0
	v_mul_f32_e32 v84, v79, v78
	v_fma_f32 v85, -v67, v84, v79
	v_fmac_f32_e32 v84, v85, v78
	v_fma_f32 v67, -v67, v84, v79
	v_div_fmas_f32 v67, v67, v78, v84
	v_div_fixup_f32 v74, v67, v74, 1.0
	v_pk_fma_f32 v[68:69], v[74:75], v[72:73], v[68:69]
	v_pk_add_f32 v[74:75], v[82:83], 1.0 op_sel_hi:[1,0]
	v_cvt_pk_f16_f32 v67, v68, v69
	v_cvt_f32_f16_e32 v68, v76
	v_cvt_f32_f16_sdwa v69, v76 dst_sel:DWORD dst_unused:UNUSED_PAD src0_sel:WORD_1
	v_div_scale_f32 v76, s[0:1], v75, v75, 1.0
	v_rcp_f32_e32 v78, v76
	v_cvt_f32_f16_e32 v72, v80
	v_cvt_f32_f16_sdwa v73, v80 dst_sel:DWORD dst_unused:UNUSED_PAD src0_sel:WORD_1
	v_fma_f32 v79, -v76, v78, 1.0
	v_fmac_f32_e32 v78, v79, v78
	v_div_scale_f32 v79, vcc, 1.0, v75, 1.0
	v_mul_f32_e32 v80, v79, v78
	v_fma_f32 v82, -v76, v80, v79
	v_fmac_f32_e32 v80, v82, v78
	v_fma_f32 v76, -v76, v80, v79
	v_div_fmas_f32 v76, v76, v78, v80
	v_div_fixup_f32 v75, v76, v75, 1.0
	v_div_scale_f32 v76, s[0:1], v74, v74, 1.0
	v_rcp_f32_e32 v78, v76
	v_pk_add_f32 v[72:73], v[72:73], v[68:69] neg_lo:[0,1] neg_hi:[0,1]
	v_fma_f32 v79, -v76, v78, 1.0
	v_fmac_f32_e32 v78, v79, v78
	v_div_scale_f32 v79, vcc, 1.0, v74, 1.0
	v_mul_f32_e32 v80, v79, v78
	v_fma_f32 v82, -v76, v80, v79
	v_fmac_f32_e32 v80, v82, v78
	v_fma_f32 v76, -v76, v80, v79
	v_div_fmas_f32 v76, v76, v78, v80
	v_div_fixup_f32 v74, v76, v74, 1.0
	v_pk_fma_f32 v[68:69], v[74:75], v[72:73], v[68:69]
	v_cvt_f32_f16_e32 v72, v77
	v_cvt_pk_f16_f32 v68, v68, v69
	v_div_scale_f32 v69, s[0:1], v71, v71, 1.0
	v_rcp_f32_e32 v76, v69
	v_cvt_f32_f16_sdwa v73, v77 dst_sel:DWORD dst_unused:UNUSED_PAD src0_sel:WORD_1
	v_cvt_f32_f16_e32 v74, v81
	v_cvt_f32_f16_sdwa v75, v81 dst_sel:DWORD dst_unused:UNUSED_PAD src0_sel:WORD_1
	v_fma_f32 v77, -v69, v76, 1.0
	v_fmac_f32_e32 v76, v77, v76
	v_div_scale_f32 v77, vcc, 1.0, v71, 1.0
	v_mul_f32_e32 v78, v77, v76
	v_fma_f32 v79, -v69, v78, v77
	v_fmac_f32_e32 v78, v79, v76
	v_fma_f32 v69, -v69, v78, v77
	v_div_fmas_f32 v69, v69, v76, v78
	v_div_fixup_f32 v71, v69, v71, 1.0
	v_div_scale_f32 v69, s[0:1], v70, v70, 1.0
	v_rcp_f32_e32 v76, v69
	v_pk_add_f32 v[74:75], v[74:75], v[72:73] neg_lo:[0,1] neg_hi:[0,1]
	v_fma_f32 v77, -v69, v76, 1.0
	v_fmac_f32_e32 v76, v77, v76
	v_div_scale_f32 v77, vcc, 1.0, v70, 1.0
	v_mul_f32_e32 v78, v77, v76
	v_fma_f32 v79, -v69, v78, v77
	v_fmac_f32_e32 v78, v79, v76
	v_fma_f32 v69, -v69, v78, v77
	v_div_fmas_f32 v69, v69, v76, v78
	v_div_fixup_f32 v70, v69, v70, 1.0
	v_pk_fma_f32 v[70:71], v[70:71], v[74:75], v[72:73]
	s_nop 0
	v_cvt_pk_f16_f32 v69, v70, v71
	global_store_dwordx4 v[94:95], v[66:69], off
	global_load_dwordx4 v[66:69], v[156:157], off offset:528
	s_nop 0
	global_load_dwordx4 v[70:73], v[156:157], off offset:512
	v_or_b32_e32 v74, 0x80, v158
	v_ashrrev_i32_e32 v75, 31, v74
	v_lshlrev_b64 v[82:83], 1, v[74:75]
	v_lshl_add_u64 v[84:85], v[160:161], 0, v[82:83]
	global_load_dwordx4 v[74:77], v[84:85], off
	global_load_dwordx4 v[78:81], v[162:163], off offset:256
	s_waitcnt vmcnt(0)
; __device__ __forceinline__ float sigmoidf_(float x) { return 1.0f / (1.0f + __expf(-x)); }
;     template <int GI>
;     __device__ __forceinline__ void body(const f32x4 (&acc)[2][2][4][2], int row0, int colt) const {
;     ...
;                     const size_t row = (size_t)(row0 + ai * 128 + m * 16);
;                     f32x4 x0 = acc[ai][bj][m][0] + b0, x1 = acc[ai][bj][m][1] + b1;
;                     if (GI == 0) {
; #pragma unroll
;                         for (int j = 0; j < 4; ++j) {
;                             x0[j] = 0.6065306597126334f * sigmoidf_(x0[j]); x1[j] = 0.6065306597126334f * sigmoidf_(x1[j]); }
;                         *(u32x4*)(DEC + row * DM + c) = pack8(x0, x1);
;                     } else if (GI == 1) {
; #pragma unroll
;                         for (int j = 0; j < 4; ++j) { x0[j] = sigmoidf_(x0[j]); x1[j] = sigmoidf_(x1[j]); }
;                         *(u32x4*)(Ab + row * DM + c) = pack8(x0, x1);
;                     } else if (GI == 2) {
;                         *(u32x4*)(Gb + row * DM + c) = pack8(x0, x1);
;                     } else {
;                         h16* vp = C1 + row * LDC1 + 4096 + c;
;                         const h16x8 vv = *(const h16x8*)vp; const h16x8 vf = *(const h16x8*)(VF + row * DM + c);
;                         f32x4 o0, o1;
; #pragma unroll
;                         for (int j = 0; j < 4; ++j) { float v = (float)vv[j], f = (float)vf[j]; o0[j] = v + (f - v) * sigmoidf_(x0[j]); v = (float)vv[4 + j]; f = (float)vf[4 + j]; o1[j] = v + (f - v) * sigmoidf_(x1[j]); }
;                         *(u32x4*)vp = pack8(o0, o1);
	v_add_f32_e32 v58, v58, v66
	v_mul_f32_e32 v58, 0xbfb8aa3b, v58
	v_exp_f32_e32 v86, v58
	v_add_f32_e32 v58, v63, v71
	v_mul_f32_e32 v58, 0xbfb8aa3b, v58
	v_exp_f32_e32 v89, v58
	v_add_f32_e32 v58, v59, v67
	v_mul_f32_e32 v58, 0xbfb8aa3b, v58
	v_exp_f32_e32 v87, v58
	v_add_f32_e32 v58, v64, v72
	v_add_f32_e32 v62, v62, v70
	v_mul_f32_e32 v58, 0xbfb8aa3b, v58
	v_mul_f32_e32 v62, 0xbfb8aa3b, v62
	v_exp_f32_e32 v64, v58
	v_add_f32_e32 v58, v60, v68
	v_exp_f32_e32 v88, v62
	v_mul_f32_e32 v58, 0xbfb8aa3b, v58
	v_exp_f32_e32 v62, v58
	v_add_f32_e32 v58, v65, v73
	v_mul_f32_e32 v58, 0xbfb8aa3b, v58
	v_exp_f32_e32 v65, v58
	v_add_f32_e32 v58, v61, v69
	v_mul_f32_e32 v58, 0xbfb8aa3b, v58
	v_pk_add_f32 v[88:89], v[88:89], 1.0 op_sel_hi:[1,0]
	v_exp_f32_e32 v63, v58
	v_cvt_f32_f16_e32 v58, v74
	v_cvt_f32_f16_sdwa v59, v74 dst_sel:DWORD dst_unused:UNUSED_PAD src0_sel:WORD_1
	v_div_scale_f32 v74, s[0:1], v89, v89, 1.0
	v_cvt_f32_f16_e32 v60, v78
	v_cvt_f32_f16_sdwa v61, v78 dst_sel:DWORD dst_unused:UNUSED_PAD src0_sel:WORD_1
	v_rcp_f32_e32 v78, v74
	v_pk_add_f32 v[64:65], v[64:65], 1.0 op_sel_hi:[1,0]
	v_pk_add_f32 v[62:63], v[62:63], 1.0 op_sel_hi:[1,0]
	v_pk_add_f32 v[60:61], v[60:61], v[58:59] neg_lo:[0,1] neg_hi:[0,1]
	v_fma_f32 v94, -v74, v78, 1.0
	v_fmac_f32_e32 v78, v94, v78
	v_div_scale_f32 v94, vcc, 1.0, v89, 1.0
	v_mul_f32_e32 v95, v94, v78
	v_fma_f32 v96, -v74, v95, v94
	v_fmac_f32_e32 v95, v96, v78
	v_fma_f32 v74, -v74, v95, v94
	v_div_fmas_f32 v74, v74, v78, v95
	v_div_fixup_f32 v89, v74, v89, 1.0
	v_div_scale_f32 v74, s[0:1], v88, v88, 1.0
	v_rcp_f32_e32 v78, v74
	s_nop 0
	v_fma_f32 v94, -v74, v78, 1.0
	v_fmac_f32_e32 v78, v94, v78
	v_div_scale_f32 v94, vcc, 1.0, v88, 1.0
	v_mul_f32_e32 v95, v94, v78
	v_fma_f32 v96, -v74, v95, v94
	v_fmac_f32_e32 v95, v96, v78
	v_fma_f32 v74, -v74, v95, v94
	v_div_fmas_f32 v74, v74, v78, v95
	v_div_fixup_f32 v88, v74, v88, 1.0
	v_pk_fma_f32 v[58:59], v[88:89], v[60:61], v[58:59]
	v_cvt_f32_f16_e32 v60, v75
	v_cvt_pk_f16_f32 v58, v58, v59
	v_div_scale_f32 v59, s[0:1], v65, v65, 1.0
	v_rcp_f32_e32 v78, v59
	v_cvt_f32_f16_sdwa v61, v75 dst_sel:DWORD dst_unused:UNUSED_PAD src0_sel:WORD_1
	v_cvt_f32_f16_e32 v74, v79
	v_cvt_f32_f16_sdwa v75, v79 dst_sel:DWORD dst_unused:UNUSED_PAD src0_sel:WORD_1
	v_fma_f32 v79, -v59, v78, 1.0
	v_fmac_f32_e32 v78, v79, v78
	v_div_scale_f32 v79, vcc, 1.0, v65, 1.0
	v_mul_f32_e32 v88, v79, v78
	v_fma_f32 v89, -v59, v88, v79
	v_fmac_f32_e32 v88, v89, v78
	v_fma_f32 v59, -v59, v88, v79
	v_div_fmas_f32 v59, v59, v78, v88
	v_div_fixup_f32 v65, v59, v65, 1.0
	v_div_scale_f32 v59, s[0:1], v64, v64, 1.0
	v_rcp_f32_e32 v78, v59
	v_pk_add_f32 v[74:75], v[74:75], v[60:61] neg_lo:[0,1] neg_hi:[0,1]
	v_fma_f32 v79, -v59, v78, 1.0
	v_fmac_f32_e32 v78, v79, v78
	v_div_scale_f32 v79, vcc, 1.0, v64, 1.0
	v_mul_f32_e32 v88, v79, v78
	v_fma_f32 v89, -v59, v88, v79
	v_fmac_f32_e32 v88, v89, v78
	v_fma_f32 v59, -v59, v88, v79
	v_div_fmas_f32 v59, v59, v78, v88
	v_div_fixup_f32 v64, v59, v64, 1.0
	v_pk_fma_f32 v[60:61], v[64:65], v[74:75], v[60:61]
	v_pk_add_f32 v[74:75], v[86:87], 1.0 op_sel_hi:[1,0]
	v_cvt_pk_f16_f32 v59, v60, v61
	v_cvt_f32_f16_e32 v60, v76
	v_cvt_f32_f16_sdwa v61, v76 dst_sel:DWORD dst_unused:UNUSED_PAD src0_sel:WORD_1
	v_div_scale_f32 v76, s[0:1], v75, v75, 1.0
	v_rcp_f32_e32 v78, v76
	v_cvt_f32_f16_e32 v64, v80
	v_cvt_f32_f16_sdwa v65, v80 dst_sel:DWORD dst_unused:UNUSED_PAD src0_sel:WORD_1
	v_fma_f32 v79, -v76, v78, 1.0
	v_fmac_f32_e32 v78, v79, v78
	v_div_scale_f32 v79, vcc, 1.0, v75, 1.0
	v_mul_f32_e32 v80, v79, v78
	v_fma_f32 v86, -v76, v80, v79
	v_fmac_f32_e32 v80, v86, v78
	v_fma_f32 v76, -v76, v80, v79
	v_div_fmas_f32 v76, v76, v78, v80
	v_div_fixup_f32 v75, v76, v75, 1.0
	v_div_scale_f32 v76, s[0:1], v74, v74, 1.0
	v_rcp_f32_e32 v78, v76
	v_pk_add_f32 v[64:65], v[64:65], v[60:61] neg_lo:[0,1] neg_hi:[0,1]
	v_fma_f32 v79, -v76, v78, 1.0
	v_fmac_f32_e32 v78, v79, v78
	v_div_scale_f32 v79, vcc, 1.0, v74, 1.0
	v_mul_f32_e32 v80, v79, v78
	v_fma_f32 v86, -v76, v80, v79
	v_fmac_f32_e32 v80, v86, v78
	v_fma_f32 v76, -v76, v80, v79
	v_div_fmas_f32 v76, v76, v78, v80
	v_div_fixup_f32 v74, v76, v74, 1.0
	v_pk_fma_f32 v[60:61], v[64:65], v[74:75], v[60:61]
	v_cvt_f32_f16_e32 v64, v77
	v_cvt_pk_f16_f32 v60, v60, v61
	v_div_scale_f32 v61, s[0:1], v63, v63, 1.0
	v_rcp_f32_e32 v76, v61
	v_cvt_f32_f16_sdwa v65, v77 dst_sel:DWORD dst_unused:UNUSED_PAD src0_sel:WORD_1
	v_cvt_f32_f16_e32 v74, v81
	v_cvt_f32_f16_sdwa v75, v81 dst_sel:DWORD dst_unused:UNUSED_PAD src0_sel:WORD_1
	v_fma_f32 v77, -v61, v76, 1.0
	v_fmac_f32_e32 v76, v77, v76
	v_div_scale_f32 v77, vcc, 1.0, v63, 1.0
	v_mul_f32_e32 v78, v77, v76
	v_fma_f32 v79, -v61, v78, v77
	v_fmac_f32_e32 v78, v79, v76
	v_fma_f32 v61, -v61, v78, v77
	v_div_fmas_f32 v61, v61, v76, v78
	v_div_fixup_f32 v63, v61, v63, 1.0
	v_div_scale_f32 v61, s[0:1], v62, v62, 1.0
	v_rcp_f32_e32 v76, v61
	v_pk_add_f32 v[74:75], v[74:75], v[64:65] neg_lo:[0,1] neg_hi:[0,1]
	v_fma_f32 v77, -v61, v76, 1.0
	v_fmac_f32_e32 v76, v77, v76
	v_div_scale_f32 v77, vcc, 1.0, v62, 1.0
	v_mul_f32_e32 v78, v77, v76
	v_fma_f32 v79, -v61, v78, v77
	v_fmac_f32_e32 v78, v79, v76
	v_fma_f32 v61, -v61, v78, v77
	v_div_fmas_f32 v61, v61, v76, v78
	v_div_fixup_f32 v62, v61, v62, 1.0
	v_pk_fma_f32 v[62:63], v[74:75], v[62:63], v[64:65]
	s_nop 0
	v_cvt_pk_f16_f32 v61, v62, v63
	global_store_dwordx4 v[84:85], v[58:61], off
	v_lshl_add_u64 v[74:75], v[138:139], 0, v[82:83]
	global_load_dwordx4 v[62:65], v[74:75], off
	global_load_dwordx4 v[58:61], v[140:141], off offset:256
	v_add_f32_e32 v50, v50, v66
	v_mul_f32_e32 v50, 0xbfb8aa3b, v50
	v_exp_f32_e32 v76, v50
	v_add_f32_e32 v50, v55, v71
	v_mul_f32_e32 v50, 0xbfb8aa3b, v50
	v_exp_f32_e32 v81, v50
	v_add_f32_e32 v50, v51, v67
	v_mul_f32_e32 v50, 0xbfb8aa3b, v50
	v_add_f32_e32 v54, v54, v70
	v_exp_f32_e32 v77, v50
	v_add_f32_e32 v50, v56, v72
	v_mul_f32_e32 v54, 0xbfb8aa3b, v54
	v_mul_f32_e32 v50, 0xbfb8aa3b, v50
	v_exp_f32_e32 v80, v54
	v_exp_f32_e32 v78, v50
	v_add_f32_e32 v50, v52, v68
	v_mul_f32_e32 v50, 0xbfb8aa3b, v50
	v_exp_f32_e32 v54, v50
	v_add_f32_e32 v50, v57, v73
	v_mul_f32_e32 v50, 0xbfb8aa3b, v50
	v_exp_f32_e32 v79, v50
	v_add_f32_e32 v50, v53, v69
	v_pk_add_f32 v[56:57], v[80:81], 1.0 op_sel_hi:[1,0]
	v_mul_f32_e32 v50, 0xbfb8aa3b, v50
	v_exp_f32_e32 v55, v50
	s_waitcnt vmcnt(0)
; __device__ __forceinline__ float sigmoidf_(float x) { return 1.0f / (1.0f + __expf(-x)); }
;     template <int GI>
;     __device__ __forceinline__ void body(const f32x4 (&acc)[2][2][4][2], int row0, int colt) const {
;     ...
;                     const size_t row = (size_t)(row0 + ai * 128 + m * 16);
;                     f32x4 x0 = acc[ai][bj][m][0] + b0, x1 = acc[ai][bj][m][1] + b1;
;                     if (GI == 0) {
; #pragma unroll
;                         for (int j = 0; j < 4; ++j) {
;                             x0[j] = 0.6065306597126334f * sigmoidf_(x0[j]); x1[j] = 0.6065306597126334f * sigmoidf_(x1[j]); }
;                         *(u32x4*)(DEC + row * DM + c) = pack8(x0, x1);
;                     } else if (GI == 1) {
; #pragma unroll
;                         for (int j = 0; j < 4; ++j) { x0[j] = sigmoidf_(x0[j]); x1[j] = sigmoidf_(x1[j]); }
;                         *(u32x4*)(Ab + row * DM + c) = pack8(x0, x1);
;                     } else if (GI == 2) {
;                         *(u32x4*)(Gb + row * DM + c) = pack8(x0, x1);
;                     } else {
;                         h16* vp = C1 + row * LDC1 + 4096 + c;
;                         const h16x8 vv = *(const h16x8*)vp; const h16x8 vf = *(const h16x8*)(VF + row * DM + c);
;                         f32x4 o0, o1;
; #pragma unroll
;                         for (int j = 0; j < 4; ++j) { float v = (float)vv[j], f = (float)vf[j]; o0[j] = v + (f - v) * sigmoidf_(x0[j]); v = (float)vv[4 + j]; f = (float)vf[4 + j]; o1[j] = v + (f - v) * sigmoidf_(x1[j]); }
;                         *(u32x4*)vp = pack8(o0, o1);
	v_cvt_f32_f16_e32 v50, v62
	v_cvt_f32_f16_e32 v52, v58
	v_cvt_f32_f16_sdwa v53, v58 dst_sel:DWORD dst_unused:UNUSED_PAD src0_sel:WORD_1
	v_div_scale_f32 v58, s[0:1], v57, v57, 1.0
	v_cvt_f32_f16_sdwa v51, v62 dst_sel:DWORD dst_unused:UNUSED_PAD src0_sel:WORD_1
	v_rcp_f32_e32 v62, v58
	v_pk_add_f32 v[54:55], v[54:55], 1.0 op_sel_hi:[1,0]
	v_pk_add_f32 v[52:53], v[52:53], v[50:51] neg_lo:[0,1] neg_hi:[0,1]
	v_fma_f32 v80, -v58, v62, 1.0
	v_fmac_f32_e32 v62, v80, v62
	v_div_scale_f32 v80, vcc, 1.0, v57, 1.0
	v_mul_f32_e32 v81, v80, v62
	v_fma_f32 v84, -v58, v81, v80
	v_fmac_f32_e32 v81, v84, v62
	v_fma_f32 v58, -v58, v81, v80
	v_div_fmas_f32 v58, v58, v62, v81
	v_div_fixup_f32 v57, v58, v57, 1.0
	v_div_scale_f32 v58, s[0:1], v56, v56, 1.0
	v_rcp_f32_e32 v62, v58
	s_nop 0
	v_fma_f32 v80, -v58, v62, 1.0
	v_fmac_f32_e32 v62, v80, v62
	v_div_scale_f32 v80, vcc, 1.0, v56, 1.0
	v_mul_f32_e32 v81, v80, v62
	v_fma_f32 v84, -v58, v81, v80
	v_fmac_f32_e32 v81, v84, v62
	v_fma_f32 v58, -v58, v81, v80
	v_div_fmas_f32 v58, v58, v62, v81
	v_div_fixup_f32 v56, v58, v56, 1.0
	v_pk_fma_f32 v[50:51], v[56:57], v[52:53], v[50:51]
	v_cvt_f32_f16_e32 v56, v59
	v_cvt_f32_f16_sdwa v57, v59 dst_sel:DWORD dst_unused:UNUSED_PAD src0_sel:WORD_1
	v_pk_add_f32 v[58:59], v[78:79], 1.0 op_sel_hi:[1,0]
	v_cvt_pk_f16_f32 v50, v50, v51
	v_div_scale_f32 v51, s[0:1], v59, v59, 1.0
	v_rcp_f32_e32 v62, v51
	v_cvt_f32_f16_e32 v52, v63
	v_cvt_f32_f16_sdwa v53, v63 dst_sel:DWORD dst_unused:UNUSED_PAD src0_sel:WORD_1
	v_fma_f32 v63, -v51, v62, 1.0
	v_fmac_f32_e32 v62, v63, v62
	v_div_scale_f32 v63, vcc, 1.0, v59, 1.0
	v_mul_f32_e32 v78, v63, v62
	v_fma_f32 v79, -v51, v78, v63
	v_fmac_f32_e32 v78, v79, v62
	v_fma_f32 v51, -v51, v78, v63
	v_div_fmas_f32 v51, v51, v62, v78
	v_div_fixup_f32 v59, v51, v59, 1.0
	v_div_scale_f32 v51, s[0:1], v58, v58, 1.0
	v_rcp_f32_e32 v62, v51
	v_pk_add_f32 v[56:57], v[56:57], v[52:53] neg_lo:[0,1] neg_hi:[0,1]
	v_fma_f32 v63, -v51, v62, 1.0
	v_fmac_f32_e32 v62, v63, v62
	v_div_scale_f32 v63, vcc, 1.0, v58, 1.0
	v_mul_f32_e32 v78, v63, v62
	v_fma_f32 v79, -v51, v78, v63
	v_fmac_f32_e32 v78, v79, v62
	v_fma_f32 v51, -v51, v78, v63
	v_div_fmas_f32 v51, v51, v62, v78
	v_div_fixup_f32 v58, v51, v58, 1.0
	v_pk_fma_f32 v[52:53], v[58:59], v[56:57], v[52:53]
	v_pk_add_f32 v[58:59], v[76:77], 1.0 op_sel_hi:[1,0]
	v_cvt_f32_f16_e32 v56, v60
	v_cvt_f32_f16_sdwa v57, v60 dst_sel:DWORD dst_unused:UNUSED_PAD src0_sel:WORD_1
	v_div_scale_f32 v60, s[0:1], v59, v59, 1.0
	v_rcp_f32_e32 v62, v60
	v_cvt_pk_f16_f32 v51, v52, v53
	v_cvt_f32_f16_e32 v52, v64
	v_cvt_f32_f16_sdwa v53, v64 dst_sel:DWORD dst_unused:UNUSED_PAD src0_sel:WORD_1
	v_fma_f32 v63, -v60, v62, 1.0
	v_fmac_f32_e32 v62, v63, v62
	v_div_scale_f32 v63, vcc, 1.0, v59, 1.0
	v_mul_f32_e32 v64, v63, v62
	v_fma_f32 v76, -v60, v64, v63
	v_fmac_f32_e32 v64, v76, v62
	v_fma_f32 v60, -v60, v64, v63
	v_div_fmas_f32 v60, v60, v62, v64
	v_div_fixup_f32 v59, v60, v59, 1.0
	v_div_scale_f32 v60, s[0:1], v58, v58, 1.0
	v_rcp_f32_e32 v62, v60
	v_pk_add_f32 v[56:57], v[56:57], v[52:53] neg_lo:[0,1] neg_hi:[0,1]
	v_fma_f32 v63, -v60, v62, 1.0
	v_fmac_f32_e32 v62, v63, v62
	v_div_scale_f32 v63, vcc, 1.0, v58, 1.0
	v_mul_f32_e32 v64, v63, v62
	v_fma_f32 v76, -v60, v64, v63
	v_fmac_f32_e32 v64, v76, v62
	v_fma_f32 v60, -v60, v64, v63
	v_div_fmas_f32 v60, v60, v62, v64
	v_div_fixup_f32 v58, v60, v58, 1.0
	v_pk_fma_f32 v[52:53], v[58:59], v[56:57], v[52:53]
	v_cvt_f32_f16_e32 v58, v61
	v_cvt_pk_f16_f32 v52, v52, v53
	v_div_scale_f32 v53, s[0:1], v55, v55, 1.0
	v_rcp_f32_e32 v60, v53
	v_cvt_f32_f16_sdwa v59, v61 dst_sel:DWORD dst_unused:UNUSED_PAD src0_sel:WORD_1
	v_cvt_f32_f16_e32 v56, v65
	v_cvt_f32_f16_sdwa v57, v65 dst_sel:DWORD dst_unused:UNUSED_PAD src0_sel:WORD_1
	v_fma_f32 v61, -v53, v60, 1.0
	v_fmac_f32_e32 v60, v61, v60
	v_div_scale_f32 v61, vcc, 1.0, v55, 1.0
	v_mul_f32_e32 v62, v61, v60
	v_fma_f32 v63, -v53, v62, v61
	v_fmac_f32_e32 v62, v63, v60
	v_fma_f32 v53, -v53, v62, v61
	v_div_fmas_f32 v53, v53, v60, v62
	v_div_fixup_f32 v55, v53, v55, 1.0
	v_div_scale_f32 v53, s[0:1], v54, v54, 1.0
	v_rcp_f32_e32 v60, v53
	v_pk_add_f32 v[58:59], v[58:59], v[56:57] neg_lo:[0,1] neg_hi:[0,1]
	v_fma_f32 v61, -v53, v60, 1.0
	v_fmac_f32_e32 v60, v61, v60
	v_div_scale_f32 v61, vcc, 1.0, v54, 1.0
	v_mul_f32_e32 v62, v61, v60
	v_fma_f32 v63, -v53, v62, v61
	v_fmac_f32_e32 v62, v63, v60
	v_fma_f32 v53, -v53, v62, v61
	v_div_fmas_f32 v53, v53, v60, v62
	v_div_fixup_f32 v54, v53, v54, 1.0
	v_pk_fma_f32 v[54:55], v[54:55], v[58:59], v[56:57]
	s_nop 0
	v_cvt_pk_f16_f32 v53, v54, v55
	global_store_dwordx4 v[74:75], v[50:53], off
	v_lshl_add_u64 v[58:59], v[130:131], 0, v[82:83]
	global_load_dwordx4 v[54:57], v[58:59], off
	global_load_dwordx4 v[50:53], v[132:133], off offset:256
	v_add_f32_e32 v42, v42, v66
	v_mul_f32_e32 v42, 0xbfb8aa3b, v42
	v_exp_f32_e32 v60, v42
	v_add_f32_e32 v42, v47, v71
	v_mul_f32_e32 v42, 0xbfb8aa3b, v42
	v_exp_f32_e32 v65, v42
	v_add_f32_e32 v42, v43, v67
	v_mul_f32_e32 v42, 0xbfb8aa3b, v42
	v_add_f32_e32 v46, v46, v70
	v_exp_f32_e32 v61, v42
	v_add_f32_e32 v42, v48, v72
	v_mul_f32_e32 v46, 0xbfb8aa3b, v46
	v_mul_f32_e32 v42, 0xbfb8aa3b, v42
	v_exp_f32_e32 v64, v46
	v_exp_f32_e32 v62, v42
	v_add_f32_e32 v42, v44, v68
	v_mul_f32_e32 v42, 0xbfb8aa3b, v42
	v_exp_f32_e32 v46, v42
	v_add_f32_e32 v42, v49, v73
	v_mul_f32_e32 v42, 0xbfb8aa3b, v42
	v_exp_f32_e32 v63, v42
	v_add_f32_e32 v42, v45, v69
	v_pk_add_f32 v[48:49], v[64:65], 1.0 op_sel_hi:[1,0]
	v_mul_f32_e32 v42, 0xbfb8aa3b, v42
	v_exp_f32_e32 v47, v42
	s_waitcnt vmcnt(0)
; __device__ __forceinline__ float sigmoidf_(float x) { return 1.0f / (1.0f + __expf(-x)); }
;     template <int GI>
;     __device__ __forceinline__ void body(const f32x4 (&acc)[2][2][4][2], int row0, int colt) const {
;     ...
;                     const size_t row = (size_t)(row0 + ai * 128 + m * 16);
;                     f32x4 x0 = acc[ai][bj][m][0] + b0, x1 = acc[ai][bj][m][1] + b1;
;                     if (GI == 0) {
; #pragma unroll
;                         for (int j = 0; j < 4; ++j) {
;                             x0[j] = 0.6065306597126334f * sigmoidf_(x0[j]); x1[j] = 0.6065306597126334f * sigmoidf_(x1[j]); }
;                         *(u32x4*)(DEC + row * DM + c) = pack8(x0, x1);
;                     } else if (GI == 1) {
; #pragma unroll
;                         for (int j = 0; j < 4; ++j) { x0[j] = sigmoidf_(x0[j]); x1[j] = sigmoidf_(x1[j]); }
;                         *(u32x4*)(Ab + row * DM + c) = pack8(x0, x1);
;                     } else if (GI == 2) {
;                         *(u32x4*)(Gb + row * DM + c) = pack8(x0, x1);
;                     } else {
;                         h16* vp = C1 + row * LDC1 + 4096 + c;
;                         const h16x8 vv = *(const h16x8*)vp; const h16x8 vf = *(const h16x8*)(VF + row * DM + c);
;                         f32x4 o0, o1;
; #pragma unroll
;                         for (int j = 0; j < 4; ++j) { float v = (float)vv[j], f = (float)vf[j]; o0[j] = v + (f - v) * sigmoidf_(x0[j]); v = (float)vv[4 + j]; f = (float)vf[4 + j]; o1[j] = v + (f - v) * sigmoidf_(x1[j]); }
;                         *(u32x4*)vp = pack8(o0, o1);
	v_cvt_f32_f16_e32 v42, v54
	v_cvt_f32_f16_e32 v44, v50
	v_cvt_f32_f16_sdwa v45, v50 dst_sel:DWORD dst_unused:UNUSED_PAD src0_sel:WORD_1
	v_div_scale_f32 v50, s[0:1], v49, v49, 1.0
	v_cvt_f32_f16_sdwa v43, v54 dst_sel:DWORD dst_unused:UNUSED_PAD src0_sel:WORD_1
	v_rcp_f32_e32 v54, v50
	v_pk_add_f32 v[46:47], v[46:47], 1.0 op_sel_hi:[1,0]
	v_pk_add_f32 v[44:45], v[44:45], v[42:43] neg_lo:[0,1] neg_hi:[0,1]
	v_fma_f32 v64, -v50, v54, 1.0
	v_fmac_f32_e32 v54, v64, v54
	v_div_scale_f32 v64, vcc, 1.0, v49, 1.0
	v_mul_f32_e32 v65, v64, v54
	v_fma_f32 v74, -v50, v65, v64
	v_fmac_f32_e32 v65, v74, v54
	v_fma_f32 v50, -v50, v65, v64
	v_div_fmas_f32 v50, v50, v54, v65
	v_div_fixup_f32 v49, v50, v49, 1.0
	v_div_scale_f32 v50, s[0:1], v48, v48, 1.0
	v_rcp_f32_e32 v54, v50
	s_nop 0
	v_fma_f32 v64, -v50, v54, 1.0
	v_fmac_f32_e32 v54, v64, v54
	v_div_scale_f32 v64, vcc, 1.0, v48, 1.0
	v_mul_f32_e32 v65, v64, v54
	v_fma_f32 v74, -v50, v65, v64
	v_fmac_f32_e32 v65, v74, v54
	v_fma_f32 v50, -v50, v65, v64
	v_div_fmas_f32 v50, v50, v54, v65
	v_div_fixup_f32 v48, v50, v48, 1.0
	v_pk_fma_f32 v[42:43], v[48:49], v[44:45], v[42:43]
	v_cvt_f32_f16_e32 v48, v51
	v_cvt_f32_f16_sdwa v49, v51 dst_sel:DWORD dst_unused:UNUSED_PAD src0_sel:WORD_1
	v_pk_add_f32 v[50:51], v[62:63], 1.0 op_sel_hi:[1,0]
	v_cvt_pk_f16_f32 v42, v42, v43
	v_div_scale_f32 v43, s[0:1], v51, v51, 1.0
	v_rcp_f32_e32 v54, v43
	v_cvt_f32_f16_e32 v44, v55
	v_cvt_f32_f16_sdwa v45, v55 dst_sel:DWORD dst_unused:UNUSED_PAD src0_sel:WORD_1
	v_fma_f32 v55, -v43, v54, 1.0
	v_fmac_f32_e32 v54, v55, v54
	v_div_scale_f32 v55, vcc, 1.0, v51, 1.0
	v_mul_f32_e32 v62, v55, v54
	v_fma_f32 v63, -v43, v62, v55
	v_fmac_f32_e32 v62, v63, v54
	v_fma_f32 v43, -v43, v62, v55
	v_div_fmas_f32 v43, v43, v54, v62
	v_div_fixup_f32 v51, v43, v51, 1.0
	v_div_scale_f32 v43, s[0:1], v50, v50, 1.0
	v_rcp_f32_e32 v54, v43
	v_pk_add_f32 v[48:49], v[48:49], v[44:45] neg_lo:[0,1] neg_hi:[0,1]
	v_fma_f32 v55, -v43, v54, 1.0
	v_fmac_f32_e32 v54, v55, v54
	v_div_scale_f32 v55, vcc, 1.0, v50, 1.0
	v_mul_f32_e32 v62, v55, v54
	v_fma_f32 v63, -v43, v62, v55
	v_fmac_f32_e32 v62, v63, v54
	v_fma_f32 v43, -v43, v62, v55
	v_div_fmas_f32 v43, v43, v54, v62
	v_div_fixup_f32 v50, v43, v50, 1.0
	v_pk_fma_f32 v[44:45], v[50:51], v[48:49], v[44:45]
	v_pk_add_f32 v[50:51], v[60:61], 1.0 op_sel_hi:[1,0]
	v_cvt_f32_f16_e32 v48, v52
	v_cvt_f32_f16_sdwa v49, v52 dst_sel:DWORD dst_unused:UNUSED_PAD src0_sel:WORD_1
	v_div_scale_f32 v52, s[0:1], v51, v51, 1.0
	v_rcp_f32_e32 v54, v52
	v_cvt_pk_f16_f32 v43, v44, v45
	v_cvt_f32_f16_e32 v44, v56
	v_cvt_f32_f16_sdwa v45, v56 dst_sel:DWORD dst_unused:UNUSED_PAD src0_sel:WORD_1
	v_fma_f32 v55, -v52, v54, 1.0
	v_fmac_f32_e32 v54, v55, v54
	v_div_scale_f32 v55, vcc, 1.0, v51, 1.0
	v_mul_f32_e32 v56, v55, v54
	v_fma_f32 v60, -v52, v56, v55
	v_fmac_f32_e32 v56, v60, v54
	v_fma_f32 v52, -v52, v56, v55
	v_div_fmas_f32 v52, v52, v54, v56
	v_div_fixup_f32 v51, v52, v51, 1.0
	v_div_scale_f32 v52, s[0:1], v50, v50, 1.0
	v_rcp_f32_e32 v54, v52
	v_pk_add_f32 v[48:49], v[48:49], v[44:45] neg_lo:[0,1] neg_hi:[0,1]
	v_fma_f32 v55, -v52, v54, 1.0
	v_fmac_f32_e32 v54, v55, v54
	v_div_scale_f32 v55, vcc, 1.0, v50, 1.0
	v_mul_f32_e32 v56, v55, v54
	v_fma_f32 v60, -v52, v56, v55
	v_fmac_f32_e32 v56, v60, v54
	v_fma_f32 v52, -v52, v56, v55
	v_div_fmas_f32 v52, v52, v54, v56
	v_div_fixup_f32 v50, v52, v50, 1.0
	v_pk_fma_f32 v[44:45], v[50:51], v[48:49], v[44:45]
	v_cvt_f32_f16_e32 v50, v53
	v_cvt_pk_f16_f32 v44, v44, v45
	v_div_scale_f32 v45, s[0:1], v47, v47, 1.0
	v_rcp_f32_e32 v52, v45
	v_cvt_f32_f16_sdwa v51, v53 dst_sel:DWORD dst_unused:UNUSED_PAD src0_sel:WORD_1
	v_cvt_f32_f16_e32 v48, v57
	v_cvt_f32_f16_sdwa v49, v57 dst_sel:DWORD dst_unused:UNUSED_PAD src0_sel:WORD_1
	v_fma_f32 v53, -v45, v52, 1.0
	v_fmac_f32_e32 v52, v53, v52
	v_div_scale_f32 v53, vcc, 1.0, v47, 1.0
	v_mul_f32_e32 v54, v53, v52
	v_fma_f32 v55, -v45, v54, v53
	v_fmac_f32_e32 v54, v55, v52
	v_fma_f32 v45, -v45, v54, v53
	v_div_fmas_f32 v45, v45, v52, v54
	v_div_fixup_f32 v47, v45, v47, 1.0
	v_div_scale_f32 v45, s[0:1], v46, v46, 1.0
	v_rcp_f32_e32 v52, v45
	v_pk_add_f32 v[50:51], v[50:51], v[48:49] neg_lo:[0,1] neg_hi:[0,1]
	v_fma_f32 v53, -v45, v52, 1.0
	v_fmac_f32_e32 v52, v53, v52
	v_div_scale_f32 v53, vcc, 1.0, v46, 1.0
	v_mul_f32_e32 v54, v53, v52
	v_fma_f32 v55, -v45, v54, v53
	v_fmac_f32_e32 v54, v55, v52
	v_fma_f32 v45, -v45, v54, v53
	v_div_fmas_f32 v45, v45, v52, v54
	v_div_fixup_f32 v46, v45, v46, 1.0
	v_pk_fma_f32 v[46:47], v[46:47], v[50:51], v[48:49]
	s_nop 0
	v_cvt_pk_f16_f32 v45, v46, v47
	global_store_dwordx4 v[58:59], v[42:45], off
	v_lshl_add_u64 v[50:51], v[122:123], 0, v[82:83]
	global_load_dwordx4 v[46:49], v[50:51], off
	global_load_dwordx4 v[42:45], v[124:125], off offset:256
	v_add_f32_e32 v34, v34, v66
	v_mul_f32_e32 v34, 0xbfb8aa3b, v34
	v_exp_f32_e32 v52, v34
	v_add_f32_e32 v34, v39, v71
	v_mul_f32_e32 v34, 0xbfb8aa3b, v34
	v_exp_f32_e32 v57, v34
	v_add_f32_e32 v34, v35, v67
	v_mul_f32_e32 v34, 0xbfb8aa3b, v34
	v_add_f32_e32 v38, v38, v70
	v_exp_f32_e32 v53, v34
	v_add_f32_e32 v34, v40, v72
	v_mul_f32_e32 v38, 0xbfb8aa3b, v38
	v_mul_f32_e32 v34, 0xbfb8aa3b, v34
	v_exp_f32_e32 v56, v38
	v_exp_f32_e32 v54, v34
	v_add_f32_e32 v34, v36, v68
	v_mul_f32_e32 v34, 0xbfb8aa3b, v34
	v_exp_f32_e32 v38, v34
	v_add_f32_e32 v34, v41, v73
	v_mul_f32_e32 v34, 0xbfb8aa3b, v34
	v_exp_f32_e32 v55, v34
	v_add_f32_e32 v34, v37, v69
	v_pk_add_f32 v[40:41], v[56:57], 1.0 op_sel_hi:[1,0]
	v_mul_f32_e32 v34, 0xbfb8aa3b, v34
	v_exp_f32_e32 v39, v34
	s_waitcnt vmcnt(0)
; __device__ __forceinline__ float sigmoidf_(float x) { return 1.0f / (1.0f + __expf(-x)); }
;     template <int GI>
;     __device__ __forceinline__ void body(const f32x4 (&acc)[2][2][4][2], int row0, int colt) const {
;     ...
;                     const size_t row = (size_t)(row0 + ai * 128 + m * 16);
;                     f32x4 x0 = acc[ai][bj][m][0] + b0, x1 = acc[ai][bj][m][1] + b1;
;                     if (GI == 0) {
; #pragma unroll
;                         for (int j = 0; j < 4; ++j) {
;                             x0[j] = 0.6065306597126334f * sigmoidf_(x0[j]); x1[j] = 0.6065306597126334f * sigmoidf_(x1[j]); }
;                         *(u32x4*)(DEC + row * DM + c) = pack8(x0, x1);
;                     } else if (GI == 1) {
; #pragma unroll
;                         for (int j = 0; j < 4; ++j) { x0[j] = sigmoidf_(x0[j]); x1[j] = sigmoidf_(x1[j]); }
;                         *(u32x4*)(Ab + row * DM + c) = pack8(x0, x1);
;                     } else if (GI == 2) {
;                         *(u32x4*)(Gb + row * DM + c) = pack8(x0, x1);
;                     } else {
;                         h16* vp = C1 + row * LDC1 + 4096 + c;
;                         const h16x8 vv = *(const h16x8*)vp; const h16x8 vf = *(const h16x8*)(VF + row * DM + c);
;                         f32x4 o0, o1;
; #pragma unroll
;                         for (int j = 0; j < 4; ++j) { float v = (float)vv[j], f = (float)vf[j]; o0[j] = v + (f - v) * sigmoidf_(x0[j]); v = (float)vv[4 + j]; f = (float)vf[4 + j]; o1[j] = v + (f - v) * sigmoidf_(x1[j]); }
;                         *(u32x4*)vp = pack8(o0, o1);
	v_cvt_f32_f16_e32 v34, v46
	v_cvt_f32_f16_e32 v36, v42
	v_cvt_f32_f16_sdwa v37, v42 dst_sel:DWORD dst_unused:UNUSED_PAD src0_sel:WORD_1
	v_div_scale_f32 v42, s[0:1], v41, v41, 1.0
	v_cvt_f32_f16_sdwa v35, v46 dst_sel:DWORD dst_unused:UNUSED_PAD src0_sel:WORD_1
	v_rcp_f32_e32 v46, v42
	v_pk_add_f32 v[38:39], v[38:39], 1.0 op_sel_hi:[1,0]
	v_pk_add_f32 v[36:37], v[36:37], v[34:35] neg_lo:[0,1] neg_hi:[0,1]
	v_fma_f32 v56, -v42, v46, 1.0
	v_fmac_f32_e32 v46, v56, v46
	v_div_scale_f32 v56, vcc, 1.0, v41, 1.0
	v_mul_f32_e32 v57, v56, v46
	v_fma_f32 v58, -v42, v57, v56
	v_fmac_f32_e32 v57, v58, v46
	v_fma_f32 v42, -v42, v57, v56
	v_div_fmas_f32 v42, v42, v46, v57
	v_div_fixup_f32 v41, v42, v41, 1.0
	v_div_scale_f32 v42, s[0:1], v40, v40, 1.0
	v_rcp_f32_e32 v46, v42
	s_nop 0
	v_fma_f32 v56, -v42, v46, 1.0
	v_fmac_f32_e32 v46, v56, v46
	v_div_scale_f32 v56, vcc, 1.0, v40, 1.0
	v_mul_f32_e32 v57, v56, v46
	v_fma_f32 v58, -v42, v57, v56
	v_fmac_f32_e32 v57, v58, v46
	v_fma_f32 v42, -v42, v57, v56
	v_div_fmas_f32 v42, v42, v46, v57
	v_div_fixup_f32 v40, v42, v40, 1.0
	v_pk_fma_f32 v[34:35], v[40:41], v[36:37], v[34:35]
	v_cvt_f32_f16_e32 v40, v43
	v_cvt_f32_f16_sdwa v41, v43 dst_sel:DWORD dst_unused:UNUSED_PAD src0_sel:WORD_1
	v_pk_add_f32 v[42:43], v[54:55], 1.0 op_sel_hi:[1,0]
	v_cvt_pk_f16_f32 v34, v34, v35
	v_div_scale_f32 v35, s[0:1], v43, v43, 1.0
	v_rcp_f32_e32 v46, v35
	v_cvt_f32_f16_e32 v36, v47
	v_cvt_f32_f16_sdwa v37, v47 dst_sel:DWORD dst_unused:UNUSED_PAD src0_sel:WORD_1
	v_fma_f32 v47, -v35, v46, 1.0
	v_fmac_f32_e32 v46, v47, v46
	v_div_scale_f32 v47, vcc, 1.0, v43, 1.0
	v_mul_f32_e32 v54, v47, v46
	v_fma_f32 v55, -v35, v54, v47
	v_fmac_f32_e32 v54, v55, v46
	v_fma_f32 v35, -v35, v54, v47
	v_div_fmas_f32 v35, v35, v46, v54
	v_div_fixup_f32 v43, v35, v43, 1.0
	v_div_scale_f32 v35, s[0:1], v42, v42, 1.0
	v_rcp_f32_e32 v46, v35
	v_pk_add_f32 v[40:41], v[40:41], v[36:37] neg_lo:[0,1] neg_hi:[0,1]
	v_fma_f32 v47, -v35, v46, 1.0
	v_fmac_f32_e32 v46, v47, v46
	v_div_scale_f32 v47, vcc, 1.0, v42, 1.0
	v_mul_f32_e32 v54, v47, v46
	v_fma_f32 v55, -v35, v54, v47
	v_fmac_f32_e32 v54, v55, v46
	v_fma_f32 v35, -v35, v54, v47
	v_div_fmas_f32 v35, v35, v46, v54
	v_div_fixup_f32 v42, v35, v42, 1.0
	v_pk_fma_f32 v[36:37], v[42:43], v[40:41], v[36:37]
	v_pk_add_f32 v[42:43], v[52:53], 1.0 op_sel_hi:[1,0]
	v_cvt_f32_f16_e32 v40, v44
	v_cvt_f32_f16_sdwa v41, v44 dst_sel:DWORD dst_unused:UNUSED_PAD src0_sel:WORD_1
	v_div_scale_f32 v44, s[0:1], v43, v43, 1.0
	v_rcp_f32_e32 v46, v44
	v_cvt_pk_f16_f32 v35, v36, v37
	v_cvt_f32_f16_e32 v36, v48
	v_cvt_f32_f16_sdwa v37, v48 dst_sel:DWORD dst_unused:UNUSED_PAD src0_sel:WORD_1
	v_fma_f32 v47, -v44, v46, 1.0
	v_fmac_f32_e32 v46, v47, v46
	v_div_scale_f32 v47, vcc, 1.0, v43, 1.0
	v_mul_f32_e32 v48, v47, v46
	v_fma_f32 v52, -v44, v48, v47
	v_fmac_f32_e32 v48, v52, v46
	v_fma_f32 v44, -v44, v48, v47
	v_div_fmas_f32 v44, v44, v46, v48
	v_div_fixup_f32 v43, v44, v43, 1.0
	v_div_scale_f32 v44, s[0:1], v42, v42, 1.0
	v_rcp_f32_e32 v46, v44
	v_pk_add_f32 v[40:41], v[40:41], v[36:37] neg_lo:[0,1] neg_hi:[0,1]
	v_fma_f32 v47, -v44, v46, 1.0
	v_fmac_f32_e32 v46, v47, v46
	v_div_scale_f32 v47, vcc, 1.0, v42, 1.0
	v_mul_f32_e32 v48, v47, v46
	v_fma_f32 v52, -v44, v48, v47
	v_fmac_f32_e32 v48, v52, v46
	v_fma_f32 v44, -v44, v48, v47
	v_div_fmas_f32 v44, v44, v46, v48
	v_div_fixup_f32 v42, v44, v42, 1.0
	v_pk_fma_f32 v[36:37], v[42:43], v[40:41], v[36:37]
	v_cvt_f32_f16_e32 v42, v45
	v_cvt_pk_f16_f32 v36, v36, v37
	v_div_scale_f32 v37, s[0:1], v39, v39, 1.0
	v_rcp_f32_e32 v44, v37
	v_cvt_f32_f16_sdwa v43, v45 dst_sel:DWORD dst_unused:UNUSED_PAD src0_sel:WORD_1
	v_cvt_f32_f16_e32 v40, v49
	v_cvt_f32_f16_sdwa v41, v49 dst_sel:DWORD dst_unused:UNUSED_PAD src0_sel:WORD_1
	v_fma_f32 v45, -v37, v44, 1.0
	v_fmac_f32_e32 v44, v45, v44
	v_div_scale_f32 v45, vcc, 1.0, v39, 1.0
	v_mul_f32_e32 v46, v45, v44
	v_fma_f32 v47, -v37, v46, v45
	v_fmac_f32_e32 v46, v47, v44
	v_fma_f32 v37, -v37, v46, v45
	v_div_fmas_f32 v37, v37, v44, v46
	v_div_fixup_f32 v39, v37, v39, 1.0
	v_div_scale_f32 v37, s[0:1], v38, v38, 1.0
	v_rcp_f32_e32 v44, v37
	v_pk_add_f32 v[42:43], v[42:43], v[40:41] neg_lo:[0,1] neg_hi:[0,1]
	v_fma_f32 v45, -v37, v44, 1.0
	v_fmac_f32_e32 v44, v45, v44
	v_div_scale_f32 v45, vcc, 1.0, v38, 1.0
	v_mul_f32_e32 v46, v45, v44
	v_fma_f32 v47, -v37, v46, v45
	v_fmac_f32_e32 v46, v47, v44
	v_fma_f32 v37, -v37, v46, v45
	v_div_fmas_f32 v37, v37, v44, v46
	v_div_fixup_f32 v38, v37, v38, 1.0
	v_pk_fma_f32 v[38:39], v[38:39], v[42:43], v[40:41]
	s_nop 0
	v_cvt_pk_f16_f32 v37, v38, v39
	global_store_dwordx4 v[50:51], v[34:37], off
	v_lshl_add_u64 v[42:43], v[114:115], 0, v[82:83]
	global_load_dwordx4 v[38:41], v[42:43], off
	global_load_dwordx4 v[34:37], v[116:117], off offset:256
	v_add_f32_e32 v26, v26, v66
	v_mul_f32_e32 v26, 0xbfb8aa3b, v26
	v_exp_f32_e32 v44, v26
	v_add_f32_e32 v26, v31, v71
	v_mul_f32_e32 v26, 0xbfb8aa3b, v26
	v_exp_f32_e32 v49, v26
	v_add_f32_e32 v26, v27, v67
	v_mul_f32_e32 v26, 0xbfb8aa3b, v26
	v_add_f32_e32 v30, v30, v70
	v_exp_f32_e32 v45, v26
	v_add_f32_e32 v26, v32, v72
	v_mul_f32_e32 v30, 0xbfb8aa3b, v30
	v_mul_f32_e32 v26, 0xbfb8aa3b, v26
	v_exp_f32_e32 v48, v30
	v_exp_f32_e32 v46, v26
	v_add_f32_e32 v26, v28, v68
	v_mul_f32_e32 v26, 0xbfb8aa3b, v26
	v_exp_f32_e32 v30, v26
	v_add_f32_e32 v26, v33, v73
	v_mul_f32_e32 v26, 0xbfb8aa3b, v26
	v_exp_f32_e32 v47, v26
	v_add_f32_e32 v26, v29, v69
	v_pk_add_f32 v[32:33], v[48:49], 1.0 op_sel_hi:[1,0]
	v_mul_f32_e32 v26, 0xbfb8aa3b, v26
	v_exp_f32_e32 v31, v26
	s_waitcnt vmcnt(0)
; __device__ __forceinline__ float sigmoidf_(float x) { return 1.0f / (1.0f + __expf(-x)); }
;     template <int GI>
;     __device__ __forceinline__ void body(const f32x4 (&acc)[2][2][4][2], int row0, int colt) const {
;     ...
;                     const size_t row = (size_t)(row0 + ai * 128 + m * 16);
;                     f32x4 x0 = acc[ai][bj][m][0] + b0, x1 = acc[ai][bj][m][1] + b1;
;                     if (GI == 0) {
; #pragma unroll
;                         for (int j = 0; j < 4; ++j) {
;                             x0[j] = 0.6065306597126334f * sigmoidf_(x0[j]); x1[j] = 0.6065306597126334f * sigmoidf_(x1[j]); }
;                         *(u32x4*)(DEC + row * DM + c) = pack8(x0, x1);
;                     } else if (GI == 1) {
; #pragma unroll
;                         for (int j = 0; j < 4; ++j) { x0[j] = sigmoidf_(x0[j]); x1[j] = sigmoidf_(x1[j]); }
;                         *(u32x4*)(Ab + row * DM + c) = pack8(x0, x1);
;                     } else if (GI == 2) {
;                         *(u32x4*)(Gb + row * DM + c) = pack8(x0, x1);
;                     } else {
;                         h16* vp = C1 + row * LDC1 + 4096 + c;
;                         const h16x8 vv = *(const h16x8*)vp; const h16x8 vf = *(const h16x8*)(VF + row * DM + c);
;                         f32x4 o0, o1;
; #pragma unroll
;                         for (int j = 0; j < 4; ++j) { float v = (float)vv[j], f = (float)vf[j]; o0[j] = v + (f - v) * sigmoidf_(x0[j]); v = (float)vv[4 + j]; f = (float)vf[4 + j]; o1[j] = v + (f - v) * sigmoidf_(x1[j]); }
;                         *(u32x4*)vp = pack8(o0, o1);
	v_cvt_f32_f16_e32 v26, v38
	v_cvt_f32_f16_e32 v28, v34
	v_cvt_f32_f16_sdwa v29, v34 dst_sel:DWORD dst_unused:UNUSED_PAD src0_sel:WORD_1
	v_div_scale_f32 v34, s[0:1], v33, v33, 1.0
	v_cvt_f32_f16_sdwa v27, v38 dst_sel:DWORD dst_unused:UNUSED_PAD src0_sel:WORD_1
	v_rcp_f32_e32 v38, v34
	v_pk_add_f32 v[30:31], v[30:31], 1.0 op_sel_hi:[1,0]
	v_pk_add_f32 v[28:29], v[28:29], v[26:27] neg_lo:[0,1] neg_hi:[0,1]
	v_fma_f32 v48, -v34, v38, 1.0
	v_fmac_f32_e32 v38, v48, v38
	v_div_scale_f32 v48, vcc, 1.0, v33, 1.0
	v_mul_f32_e32 v49, v48, v38
	v_fma_f32 v50, -v34, v49, v48
	v_fmac_f32_e32 v49, v50, v38
	v_fma_f32 v34, -v34, v49, v48
	v_div_fmas_f32 v34, v34, v38, v49
	v_div_fixup_f32 v33, v34, v33, 1.0
	v_div_scale_f32 v34, s[0:1], v32, v32, 1.0
	v_rcp_f32_e32 v38, v34
	s_nop 0
	v_fma_f32 v48, -v34, v38, 1.0
	v_fmac_f32_e32 v38, v48, v38
	v_div_scale_f32 v48, vcc, 1.0, v32, 1.0
	v_mul_f32_e32 v49, v48, v38
	v_fma_f32 v50, -v34, v49, v48
	v_fmac_f32_e32 v49, v50, v38
	v_fma_f32 v34, -v34, v49, v48
	v_div_fmas_f32 v34, v34, v38, v49
	v_div_fixup_f32 v32, v34, v32, 1.0
	v_pk_fma_f32 v[26:27], v[32:33], v[28:29], v[26:27]
	v_cvt_f32_f16_e32 v32, v35
	v_cvt_f32_f16_sdwa v33, v35 dst_sel:DWORD dst_unused:UNUSED_PAD src0_sel:WORD_1
	v_pk_add_f32 v[34:35], v[46:47], 1.0 op_sel_hi:[1,0]
	v_cvt_pk_f16_f32 v26, v26, v27
	v_div_scale_f32 v27, s[0:1], v35, v35, 1.0
	v_rcp_f32_e32 v38, v27
	v_cvt_f32_f16_e32 v28, v39
	v_cvt_f32_f16_sdwa v29, v39 dst_sel:DWORD dst_unused:UNUSED_PAD src0_sel:WORD_1
	v_fma_f32 v39, -v27, v38, 1.0
	v_fmac_f32_e32 v38, v39, v38
	v_div_scale_f32 v39, vcc, 1.0, v35, 1.0
	v_mul_f32_e32 v46, v39, v38
	v_fma_f32 v47, -v27, v46, v39
	v_fmac_f32_e32 v46, v47, v38
	v_fma_f32 v27, -v27, v46, v39
	v_div_fmas_f32 v27, v27, v38, v46
	v_div_fixup_f32 v35, v27, v35, 1.0
	v_div_scale_f32 v27, s[0:1], v34, v34, 1.0
	v_rcp_f32_e32 v38, v27
	v_pk_add_f32 v[32:33], v[32:33], v[28:29] neg_lo:[0,1] neg_hi:[0,1]
	v_fma_f32 v39, -v27, v38, 1.0
	v_fmac_f32_e32 v38, v39, v38
	v_div_scale_f32 v39, vcc, 1.0, v34, 1.0
	v_mul_f32_e32 v46, v39, v38
	v_fma_f32 v47, -v27, v46, v39
	v_fmac_f32_e32 v46, v47, v38
	v_fma_f32 v27, -v27, v46, v39
	v_div_fmas_f32 v27, v27, v38, v46
	v_div_fixup_f32 v34, v27, v34, 1.0
	v_pk_fma_f32 v[28:29], v[34:35], v[32:33], v[28:29]
	v_pk_add_f32 v[34:35], v[44:45], 1.0 op_sel_hi:[1,0]
	v_cvt_f32_f16_e32 v32, v36
	v_cvt_f32_f16_sdwa v33, v36 dst_sel:DWORD dst_unused:UNUSED_PAD src0_sel:WORD_1
	v_div_scale_f32 v36, s[0:1], v35, v35, 1.0
	v_rcp_f32_e32 v38, v36
	v_cvt_pk_f16_f32 v27, v28, v29
	v_cvt_f32_f16_e32 v28, v40
	v_cvt_f32_f16_sdwa v29, v40 dst_sel:DWORD dst_unused:UNUSED_PAD src0_sel:WORD_1
	v_fma_f32 v39, -v36, v38, 1.0
	v_fmac_f32_e32 v38, v39, v38
	v_div_scale_f32 v39, vcc, 1.0, v35, 1.0
	v_mul_f32_e32 v40, v39, v38
	v_fma_f32 v44, -v36, v40, v39
	v_fmac_f32_e32 v40, v44, v38
	v_fma_f32 v36, -v36, v40, v39
	v_div_fmas_f32 v36, v36, v38, v40
	v_div_fixup_f32 v35, v36, v35, 1.0
	v_div_scale_f32 v36, s[0:1], v34, v34, 1.0
	v_rcp_f32_e32 v38, v36
	v_pk_add_f32 v[32:33], v[32:33], v[28:29] neg_lo:[0,1] neg_hi:[0,1]
	v_fma_f32 v39, -v36, v38, 1.0
	v_fmac_f32_e32 v38, v39, v38
	v_div_scale_f32 v39, vcc, 1.0, v34, 1.0
	v_mul_f32_e32 v40, v39, v38
	v_fma_f32 v44, -v36, v40, v39
	v_fmac_f32_e32 v40, v44, v38
	v_fma_f32 v36, -v36, v40, v39
	v_div_fmas_f32 v36, v36, v38, v40
	v_div_fixup_f32 v34, v36, v34, 1.0
	v_pk_fma_f32 v[28:29], v[34:35], v[32:33], v[28:29]
	v_cvt_f32_f16_e32 v34, v37
	v_cvt_pk_f16_f32 v28, v28, v29
	v_div_scale_f32 v29, s[0:1], v31, v31, 1.0
	v_rcp_f32_e32 v36, v29
	v_cvt_f32_f16_sdwa v35, v37 dst_sel:DWORD dst_unused:UNUSED_PAD src0_sel:WORD_1
	v_cvt_f32_f16_e32 v32, v41
	v_cvt_f32_f16_sdwa v33, v41 dst_sel:DWORD dst_unused:UNUSED_PAD src0_sel:WORD_1
	v_fma_f32 v37, -v29, v36, 1.0
	v_fmac_f32_e32 v36, v37, v36
	v_div_scale_f32 v37, vcc, 1.0, v31, 1.0
	v_mul_f32_e32 v38, v37, v36
	v_fma_f32 v39, -v29, v38, v37
	v_fmac_f32_e32 v38, v39, v36
	v_fma_f32 v29, -v29, v38, v37
	v_div_fmas_f32 v29, v29, v36, v38
	v_div_fixup_f32 v31, v29, v31, 1.0
	v_div_scale_f32 v29, s[0:1], v30, v30, 1.0
	v_rcp_f32_e32 v36, v29
	v_pk_add_f32 v[34:35], v[34:35], v[32:33] neg_lo:[0,1] neg_hi:[0,1]
	v_fma_f32 v37, -v29, v36, 1.0
	v_fmac_f32_e32 v36, v37, v36
	v_div_scale_f32 v37, vcc, 1.0, v30, 1.0
	v_mul_f32_e32 v38, v37, v36
	v_fma_f32 v39, -v29, v38, v37
	v_fmac_f32_e32 v38, v39, v36
	v_fma_f32 v29, -v29, v38, v37
	v_div_fmas_f32 v29, v29, v36, v38
	v_div_fixup_f32 v30, v29, v30, 1.0
	v_pk_fma_f32 v[30:31], v[30:31], v[34:35], v[32:33]
	s_nop 0
	v_cvt_pk_f16_f32 v29, v30, v31
	global_store_dwordx4 v[42:43], v[26:29], off
	v_lshl_add_u64 v[34:35], v[106:107], 0, v[82:83]
	global_load_dwordx4 v[30:33], v[34:35], off
	global_load_dwordx4 v[26:29], v[108:109], off offset:256
	v_add_f32_e32 v18, v18, v66
	v_mul_f32_e32 v18, 0xbfb8aa3b, v18
	v_exp_f32_e32 v36, v18
	v_add_f32_e32 v18, v23, v71
	v_mul_f32_e32 v18, 0xbfb8aa3b, v18
	v_exp_f32_e32 v41, v18
	v_add_f32_e32 v18, v19, v67
	v_mul_f32_e32 v18, 0xbfb8aa3b, v18
	v_add_f32_e32 v22, v22, v70
	v_exp_f32_e32 v37, v18
	v_add_f32_e32 v18, v24, v72
	v_mul_f32_e32 v22, 0xbfb8aa3b, v22
	v_mul_f32_e32 v18, 0xbfb8aa3b, v18
	v_exp_f32_e32 v40, v22
	v_exp_f32_e32 v38, v18
	v_add_f32_e32 v18, v20, v68
	v_mul_f32_e32 v18, 0xbfb8aa3b, v18
	v_exp_f32_e32 v22, v18
	v_add_f32_e32 v18, v25, v73
	v_mul_f32_e32 v18, 0xbfb8aa3b, v18
	v_exp_f32_e32 v39, v18
	v_add_f32_e32 v18, v21, v69
	v_pk_add_f32 v[24:25], v[40:41], 1.0 op_sel_hi:[1,0]
	v_mul_f32_e32 v18, 0xbfb8aa3b, v18
	v_exp_f32_e32 v23, v18
	s_waitcnt vmcnt(0)
; __device__ __forceinline__ float sigmoidf_(float x) { return 1.0f / (1.0f + __expf(-x)); }
;     template <int GI>
;     __device__ __forceinline__ void body(const f32x4 (&acc)[2][2][4][2], int row0, int colt) const {
;     ...
;                     const size_t row = (size_t)(row0 + ai * 128 + m * 16);
;                     f32x4 x0 = acc[ai][bj][m][0] + b0, x1 = acc[ai][bj][m][1] + b1;
;                     if (GI == 0) {
; #pragma unroll
;                         for (int j = 0; j < 4; ++j) {
;                             x0[j] = 0.6065306597126334f * sigmoidf_(x0[j]); x1[j] = 0.6065306597126334f * sigmoidf_(x1[j]); }
;                         *(u32x4*)(DEC + row * DM + c) = pack8(x0, x1);
;                     } else if (GI == 1) {
; #pragma unroll
;                         for (int j = 0; j < 4; ++j) { x0[j] = sigmoidf_(x0[j]); x1[j] = sigmoidf_(x1[j]); }
;                         *(u32x4*)(Ab + row * DM + c) = pack8(x0, x1);
;                     } else if (GI == 2) {
;                         *(u32x4*)(Gb + row * DM + c) = pack8(x0, x1);
;                     } else {
;                         h16* vp = C1 + row * LDC1 + 4096 + c;
;                         const h16x8 vv = *(const h16x8*)vp; const h16x8 vf = *(const h16x8*)(VF + row * DM + c);
;                         f32x4 o0, o1;
; #pragma unroll
;                         for (int j = 0; j < 4; ++j) { float v = (float)vv[j], f = (float)vf[j]; o0[j] = v + (f - v) * sigmoidf_(x0[j]); v = (float)vv[4 + j]; f = (float)vf[4 + j]; o1[j] = v + (f - v) * sigmoidf_(x1[j]); }
;                         *(u32x4*)vp = pack8(o0, o1);
	v_cvt_f32_f16_e32 v18, v30
	v_cvt_f32_f16_e32 v20, v26
	v_cvt_f32_f16_sdwa v21, v26 dst_sel:DWORD dst_unused:UNUSED_PAD src0_sel:WORD_1
	v_div_scale_f32 v26, s[0:1], v25, v25, 1.0
	v_cvt_f32_f16_sdwa v19, v30 dst_sel:DWORD dst_unused:UNUSED_PAD src0_sel:WORD_1
	v_rcp_f32_e32 v30, v26
	v_pk_add_f32 v[22:23], v[22:23], 1.0 op_sel_hi:[1,0]
	v_pk_add_f32 v[20:21], v[20:21], v[18:19] neg_lo:[0,1] neg_hi:[0,1]
	v_fma_f32 v40, -v26, v30, 1.0
	v_fmac_f32_e32 v30, v40, v30
	v_div_scale_f32 v40, vcc, 1.0, v25, 1.0
	v_mul_f32_e32 v41, v40, v30
	v_fma_f32 v42, -v26, v41, v40
	v_fmac_f32_e32 v41, v42, v30
	v_fma_f32 v26, -v26, v41, v40
	v_div_fmas_f32 v26, v26, v30, v41
	v_div_fixup_f32 v25, v26, v25, 1.0
	v_div_scale_f32 v26, s[0:1], v24, v24, 1.0
	v_rcp_f32_e32 v30, v26
	s_nop 0
	v_fma_f32 v40, -v26, v30, 1.0
	v_fmac_f32_e32 v30, v40, v30
	v_div_scale_f32 v40, vcc, 1.0, v24, 1.0
	v_mul_f32_e32 v41, v40, v30
	v_fma_f32 v42, -v26, v41, v40
	v_fmac_f32_e32 v41, v42, v30
	v_fma_f32 v26, -v26, v41, v40
	v_div_fmas_f32 v26, v26, v30, v41
	v_div_fixup_f32 v24, v26, v24, 1.0
	v_pk_fma_f32 v[18:19], v[24:25], v[20:21], v[18:19]
	v_cvt_f32_f16_e32 v24, v27
	v_cvt_f32_f16_sdwa v25, v27 dst_sel:DWORD dst_unused:UNUSED_PAD src0_sel:WORD_1
	v_pk_add_f32 v[26:27], v[38:39], 1.0 op_sel_hi:[1,0]
	v_cvt_pk_f16_f32 v18, v18, v19
	v_div_scale_f32 v19, s[0:1], v27, v27, 1.0
	v_rcp_f32_e32 v30, v19
	v_cvt_f32_f16_e32 v20, v31
	v_cvt_f32_f16_sdwa v21, v31 dst_sel:DWORD dst_unused:UNUSED_PAD src0_sel:WORD_1
	v_fma_f32 v31, -v19, v30, 1.0
	v_fmac_f32_e32 v30, v31, v30
	v_div_scale_f32 v31, vcc, 1.0, v27, 1.0
	v_mul_f32_e32 v38, v31, v30
	v_fma_f32 v39, -v19, v38, v31
	v_fmac_f32_e32 v38, v39, v30
	v_fma_f32 v19, -v19, v38, v31
	v_div_fmas_f32 v19, v19, v30, v38
	v_div_fixup_f32 v27, v19, v27, 1.0
	v_div_scale_f32 v19, s[0:1], v26, v26, 1.0
	v_rcp_f32_e32 v30, v19
	v_pk_add_f32 v[24:25], v[24:25], v[20:21] neg_lo:[0,1] neg_hi:[0,1]
	v_fma_f32 v31, -v19, v30, 1.0
	v_fmac_f32_e32 v30, v31, v30
	v_div_scale_f32 v31, vcc, 1.0, v26, 1.0
	v_mul_f32_e32 v38, v31, v30
	v_fma_f32 v39, -v19, v38, v31
	v_fmac_f32_e32 v38, v39, v30
	v_fma_f32 v19, -v19, v38, v31
	v_div_fmas_f32 v19, v19, v30, v38
	v_div_fixup_f32 v26, v19, v26, 1.0
	v_pk_fma_f32 v[20:21], v[26:27], v[24:25], v[20:21]
	v_pk_add_f32 v[26:27], v[36:37], 1.0 op_sel_hi:[1,0]
	v_cvt_f32_f16_e32 v24, v28
	v_cvt_f32_f16_sdwa v25, v28 dst_sel:DWORD dst_unused:UNUSED_PAD src0_sel:WORD_1
	v_div_scale_f32 v28, s[0:1], v27, v27, 1.0
	v_rcp_f32_e32 v30, v28
	v_cvt_pk_f16_f32 v19, v20, v21
	v_cvt_f32_f16_e32 v20, v32
	v_cvt_f32_f16_sdwa v21, v32 dst_sel:DWORD dst_unused:UNUSED_PAD src0_sel:WORD_1
	v_fma_f32 v31, -v28, v30, 1.0
	v_fmac_f32_e32 v30, v31, v30
	v_div_scale_f32 v31, vcc, 1.0, v27, 1.0
	v_mul_f32_e32 v32, v31, v30
	v_fma_f32 v36, -v28, v32, v31
	v_fmac_f32_e32 v32, v36, v30
	v_fma_f32 v28, -v28, v32, v31
	v_div_fmas_f32 v28, v28, v30, v32
	v_div_fixup_f32 v27, v28, v27, 1.0
	v_div_scale_f32 v28, s[0:1], v26, v26, 1.0
	v_rcp_f32_e32 v30, v28
	v_pk_add_f32 v[24:25], v[24:25], v[20:21] neg_lo:[0,1] neg_hi:[0,1]
	v_fma_f32 v31, -v28, v30, 1.0
	v_fmac_f32_e32 v30, v31, v30
	v_div_scale_f32 v31, vcc, 1.0, v26, 1.0
	v_mul_f32_e32 v32, v31, v30
	v_fma_f32 v36, -v28, v32, v31
	v_fmac_f32_e32 v32, v36, v30
	v_fma_f32 v28, -v28, v32, v31
	v_div_fmas_f32 v28, v28, v30, v32
	v_div_fixup_f32 v26, v28, v26, 1.0
	v_pk_fma_f32 v[20:21], v[26:27], v[24:25], v[20:21]
	v_cvt_f32_f16_e32 v26, v29
	v_cvt_pk_f16_f32 v20, v20, v21
	v_div_scale_f32 v21, s[0:1], v23, v23, 1.0
	v_rcp_f32_e32 v28, v21
	v_cvt_f32_f16_sdwa v27, v29 dst_sel:DWORD dst_unused:UNUSED_PAD src0_sel:WORD_1
	v_cvt_f32_f16_e32 v24, v33
	v_cvt_f32_f16_sdwa v25, v33 dst_sel:DWORD dst_unused:UNUSED_PAD src0_sel:WORD_1
	v_fma_f32 v29, -v21, v28, 1.0
	v_fmac_f32_e32 v28, v29, v28
	v_div_scale_f32 v29, vcc, 1.0, v23, 1.0
	v_mul_f32_e32 v30, v29, v28
	v_fma_f32 v31, -v21, v30, v29
	v_fmac_f32_e32 v30, v31, v28
	v_fma_f32 v21, -v21, v30, v29
	v_div_fmas_f32 v21, v21, v28, v30
	v_div_fixup_f32 v23, v21, v23, 1.0
	v_div_scale_f32 v21, s[0:1], v22, v22, 1.0
	v_rcp_f32_e32 v28, v21
	v_pk_add_f32 v[26:27], v[26:27], v[24:25] neg_lo:[0,1] neg_hi:[0,1]
	v_fma_f32 v29, -v21, v28, 1.0
	v_fmac_f32_e32 v28, v29, v28
	v_div_scale_f32 v29, vcc, 1.0, v22, 1.0
	v_mul_f32_e32 v30, v29, v28
	v_fma_f32 v31, -v21, v30, v29
	v_fmac_f32_e32 v30, v31, v28
	v_fma_f32 v21, -v21, v30, v29
	v_div_fmas_f32 v21, v21, v28, v30
	v_div_fixup_f32 v22, v21, v22, 1.0
	v_pk_fma_f32 v[22:23], v[22:23], v[26:27], v[24:25]
	s_nop 0
	v_cvt_pk_f16_f32 v21, v22, v23
	global_store_dwordx4 v[34:35], v[18:21], off
	v_lshl_add_u64 v[26:27], v[98:99], 0, v[82:83]
	global_load_dwordx4 v[22:25], v[26:27], off
	global_load_dwordx4 v[18:21], v[100:101], off offset:256
	v_add_f32_e32 v10, v10, v66
	v_mul_f32_e32 v10, 0xbfb8aa3b, v10
	v_exp_f32_e32 v28, v10
	v_add_f32_e32 v10, v15, v71
	v_mul_f32_e32 v10, 0xbfb8aa3b, v10
	v_exp_f32_e32 v33, v10
	v_add_f32_e32 v10, v11, v67
	v_mul_f32_e32 v10, 0xbfb8aa3b, v10
	v_add_f32_e32 v14, v14, v70
	v_exp_f32_e32 v29, v10
	v_add_f32_e32 v10, v16, v72
	v_mul_f32_e32 v14, 0xbfb8aa3b, v14
	v_mul_f32_e32 v10, 0xbfb8aa3b, v10
	v_exp_f32_e32 v32, v14
	v_exp_f32_e32 v30, v10
	v_add_f32_e32 v10, v12, v68
	v_mul_f32_e32 v10, 0xbfb8aa3b, v10
	v_exp_f32_e32 v14, v10
	v_add_f32_e32 v10, v17, v73
	v_mul_f32_e32 v10, 0xbfb8aa3b, v10
	v_exp_f32_e32 v31, v10
	v_add_f32_e32 v10, v13, v69
	v_pk_add_f32 v[16:17], v[32:33], 1.0 op_sel_hi:[1,0]
	v_mul_f32_e32 v10, 0xbfb8aa3b, v10
	v_exp_f32_e32 v15, v10
	s_waitcnt vmcnt(0)
; __device__ __forceinline__ float sigmoidf_(float x) { return 1.0f / (1.0f + __expf(-x)); }
;     template <int GI>
;     __device__ __forceinline__ void body(const f32x4 (&acc)[2][2][4][2], int row0, int colt) const {
;     ...
;                     const size_t row = (size_t)(row0 + ai * 128 + m * 16);
;                     f32x4 x0 = acc[ai][bj][m][0] + b0, x1 = acc[ai][bj][m][1] + b1;
;                     if (GI == 0) {
; #pragma unroll
;                         for (int j = 0; j < 4; ++j) {
;                             x0[j] = 0.6065306597126334f * sigmoidf_(x0[j]); x1[j] = 0.6065306597126334f * sigmoidf_(x1[j]); }
;                         *(u32x4*)(DEC + row * DM + c) = pack8(x0, x1);
;                     } else if (GI == 1) {
; #pragma unroll
;                         for (int j = 0; j < 4; ++j) { x0[j] = sigmoidf_(x0[j]); x1[j] = sigmoidf_(x1[j]); }
;                         *(u32x4*)(Ab + row * DM + c) = pack8(x0, x1);
;                     } else if (GI == 2) {
;                         *(u32x4*)(Gb + row * DM + c) = pack8(x0, x1);
;                     } else {
;                         h16* vp = C1 + row * LDC1 + 4096 + c;
;                         const h16x8 vv = *(const h16x8*)vp; const h16x8 vf = *(const h16x8*)(VF + row * DM + c);
;                         f32x4 o0, o1;
; #pragma unroll
;                         for (int j = 0; j < 4; ++j) { float v = (float)vv[j], f = (float)vf[j]; o0[j] = v + (f - v) * sigmoidf_(x0[j]); v = (float)vv[4 + j]; f = (float)vf[4 + j]; o1[j] = v + (f - v) * sigmoidf_(x1[j]); }
;                         *(u32x4*)vp = pack8(o0, o1);
	v_cvt_f32_f16_e32 v10, v22
	v_cvt_f32_f16_e32 v12, v18
	v_cvt_f32_f16_sdwa v13, v18 dst_sel:DWORD dst_unused:UNUSED_PAD src0_sel:WORD_1
	v_div_scale_f32 v18, s[0:1], v17, v17, 1.0
	v_cvt_f32_f16_sdwa v11, v22 dst_sel:DWORD dst_unused:UNUSED_PAD src0_sel:WORD_1
	v_rcp_f32_e32 v22, v18
	v_pk_add_f32 v[14:15], v[14:15], 1.0 op_sel_hi:[1,0]
	v_pk_add_f32 v[12:13], v[12:13], v[10:11] neg_lo:[0,1] neg_hi:[0,1]
	v_fma_f32 v32, -v18, v22, 1.0
	v_fmac_f32_e32 v22, v32, v22
	v_div_scale_f32 v32, vcc, 1.0, v17, 1.0
	v_mul_f32_e32 v33, v32, v22
	v_fma_f32 v34, -v18, v33, v32
	v_fmac_f32_e32 v33, v34, v22
	v_fma_f32 v18, -v18, v33, v32
	v_div_fmas_f32 v18, v18, v22, v33
	v_div_fixup_f32 v17, v18, v17, 1.0
	v_div_scale_f32 v18, s[0:1], v16, v16, 1.0
	v_rcp_f32_e32 v22, v18
	s_nop 0
	v_fma_f32 v32, -v18, v22, 1.0
	v_fmac_f32_e32 v22, v32, v22
	v_div_scale_f32 v32, vcc, 1.0, v16, 1.0
	v_mul_f32_e32 v33, v32, v22
	v_fma_f32 v34, -v18, v33, v32
	v_fmac_f32_e32 v33, v34, v22
	v_fma_f32 v18, -v18, v33, v32
	v_div_fmas_f32 v18, v18, v22, v33
	v_div_fixup_f32 v16, v18, v16, 1.0
	v_pk_fma_f32 v[10:11], v[16:17], v[12:13], v[10:11]
	v_cvt_f32_f16_e32 v16, v19
	v_cvt_f32_f16_sdwa v17, v19 dst_sel:DWORD dst_unused:UNUSED_PAD src0_sel:WORD_1
	v_pk_add_f32 v[18:19], v[30:31], 1.0 op_sel_hi:[1,0]
	v_cvt_pk_f16_f32 v10, v10, v11
	v_div_scale_f32 v11, s[0:1], v19, v19, 1.0
	v_rcp_f32_e32 v22, v11
	v_cvt_f32_f16_e32 v12, v23
	v_cvt_f32_f16_sdwa v13, v23 dst_sel:DWORD dst_unused:UNUSED_PAD src0_sel:WORD_1
	v_fma_f32 v23, -v11, v22, 1.0
	v_fmac_f32_e32 v22, v23, v22
	v_div_scale_f32 v23, vcc, 1.0, v19, 1.0
	v_mul_f32_e32 v30, v23, v22
	v_fma_f32 v31, -v11, v30, v23
	v_fmac_f32_e32 v30, v31, v22
	v_fma_f32 v11, -v11, v30, v23
	v_div_fmas_f32 v11, v11, v22, v30
	v_div_fixup_f32 v19, v11, v19, 1.0
	v_div_scale_f32 v11, s[0:1], v18, v18, 1.0
	v_rcp_f32_e32 v22, v11
	v_pk_add_f32 v[16:17], v[16:17], v[12:13] neg_lo:[0,1] neg_hi:[0,1]
	v_fma_f32 v23, -v11, v22, 1.0
	v_fmac_f32_e32 v22, v23, v22
	v_div_scale_f32 v23, vcc, 1.0, v18, 1.0
	v_mul_f32_e32 v30, v23, v22
	v_fma_f32 v31, -v11, v30, v23
	v_fmac_f32_e32 v30, v31, v22
	v_fma_f32 v11, -v11, v30, v23
	v_div_fmas_f32 v11, v11, v22, v30
	v_div_fixup_f32 v18, v11, v18, 1.0
	v_pk_fma_f32 v[12:13], v[18:19], v[16:17], v[12:13]
	v_pk_add_f32 v[18:19], v[28:29], 1.0 op_sel_hi:[1,0]
	v_cvt_f32_f16_e32 v16, v20
	v_cvt_f32_f16_sdwa v17, v20 dst_sel:DWORD dst_unused:UNUSED_PAD src0_sel:WORD_1
	v_div_scale_f32 v20, s[0:1], v19, v19, 1.0
	v_rcp_f32_e32 v22, v20
	v_cvt_pk_f16_f32 v11, v12, v13
	v_cvt_f32_f16_e32 v12, v24
	v_cvt_f32_f16_sdwa v13, v24 dst_sel:DWORD dst_unused:UNUSED_PAD src0_sel:WORD_1
	v_fma_f32 v23, -v20, v22, 1.0
	v_fmac_f32_e32 v22, v23, v22
	v_div_scale_f32 v23, vcc, 1.0, v19, 1.0
	v_mul_f32_e32 v24, v23, v22
	v_fma_f32 v28, -v20, v24, v23
	v_fmac_f32_e32 v24, v28, v22
	v_fma_f32 v20, -v20, v24, v23
	v_div_fmas_f32 v20, v20, v22, v24
	v_div_fixup_f32 v19, v20, v19, 1.0
	v_div_scale_f32 v20, s[0:1], v18, v18, 1.0
	v_rcp_f32_e32 v22, v20
	v_pk_add_f32 v[16:17], v[16:17], v[12:13] neg_lo:[0,1] neg_hi:[0,1]
	v_fma_f32 v23, -v20, v22, 1.0
	v_fmac_f32_e32 v22, v23, v22
	v_div_scale_f32 v23, vcc, 1.0, v18, 1.0
	v_mul_f32_e32 v24, v23, v22
	v_fma_f32 v28, -v20, v24, v23
	v_fmac_f32_e32 v24, v28, v22
	v_fma_f32 v20, -v20, v24, v23
	v_div_fmas_f32 v20, v20, v22, v24
	v_div_fixup_f32 v18, v20, v18, 1.0
	v_pk_fma_f32 v[12:13], v[18:19], v[16:17], v[12:13]
	v_cvt_f32_f16_e32 v18, v21
	v_cvt_pk_f16_f32 v12, v12, v13
	v_div_scale_f32 v13, s[0:1], v15, v15, 1.0
	v_rcp_f32_e32 v20, v13
	v_cvt_f32_f16_sdwa v19, v21 dst_sel:DWORD dst_unused:UNUSED_PAD src0_sel:WORD_1
	v_cvt_f32_f16_e32 v16, v25
	v_cvt_f32_f16_sdwa v17, v25 dst_sel:DWORD dst_unused:UNUSED_PAD src0_sel:WORD_1
	v_fma_f32 v21, -v13, v20, 1.0
	v_fmac_f32_e32 v20, v21, v20
	v_div_scale_f32 v21, vcc, 1.0, v15, 1.0
	v_mul_f32_e32 v22, v21, v20
	v_fma_f32 v23, -v13, v22, v21
	v_fmac_f32_e32 v22, v23, v20
	v_fma_f32 v13, -v13, v22, v21
	v_div_fmas_f32 v13, v13, v20, v22
	v_div_fixup_f32 v15, v13, v15, 1.0
	v_div_scale_f32 v13, s[0:1], v14, v14, 1.0
	v_rcp_f32_e32 v20, v13
	v_pk_add_f32 v[18:19], v[18:19], v[16:17] neg_lo:[0,1] neg_hi:[0,1]
	v_fma_f32 v21, -v13, v20, 1.0
	v_fmac_f32_e32 v20, v21, v20
	v_div_scale_f32 v21, vcc, 1.0, v14, 1.0
	v_mul_f32_e32 v22, v21, v20
	v_fma_f32 v23, -v13, v22, v21
	v_fmac_f32_e32 v22, v23, v20
	v_fma_f32 v13, -v13, v22, v21
	v_div_fmas_f32 v13, v13, v20, v22
	v_div_fixup_f32 v14, v13, v14, 1.0
	v_pk_fma_f32 v[14:15], v[14:15], v[18:19], v[16:17]
	s_nop 0
	v_cvt_pk_f16_f32 v13, v14, v15
	global_store_dwordx4 v[26:27], v[10:13], off
	v_lshl_add_u64 v[18:19], v[90:91], 0, v[82:83]
	global_load_dwordx4 v[14:17], v[18:19], off
	global_load_dwordx4 v[10:13], v[92:93], off offset:256
	v_add_f32_e32 v2, v2, v66
	v_mul_f32_e32 v2, 0xbfb8aa3b, v2
	v_exp_f32_e32 v20, v2
	v_add_f32_e32 v2, v7, v71
	v_mul_f32_e32 v2, 0xbfb8aa3b, v2
	v_exp_f32_e32 v25, v2
	v_add_f32_e32 v2, v3, v67
	v_mul_f32_e32 v2, 0xbfb8aa3b, v2
	v_add_f32_e32 v6, v6, v70
	v_exp_f32_e32 v21, v2
	v_add_f32_e32 v2, v8, v72
	v_mul_f32_e32 v6, 0xbfb8aa3b, v6
	v_mul_f32_e32 v2, 0xbfb8aa3b, v2
	v_exp_f32_e32 v24, v6
	v_exp_f32_e32 v22, v2
	v_add_f32_e32 v2, v4, v68
	v_mul_f32_e32 v2, 0xbfb8aa3b, v2
	v_exp_f32_e32 v6, v2
	v_add_f32_e32 v2, v9, v73
	v_mul_f32_e32 v2, 0xbfb8aa3b, v2
	v_exp_f32_e32 v23, v2
	v_add_f32_e32 v2, v5, v69
	v_pk_add_f32 v[8:9], v[24:25], 1.0 op_sel_hi:[1,0]
	v_mul_f32_e32 v2, 0xbfb8aa3b, v2
	v_exp_f32_e32 v7, v2
	s_waitcnt vmcnt(0)
; __device__ __forceinline__ float sigmoidf_(float x) { return 1.0f / (1.0f + __expf(-x)); }
; template <class Epi, class AMap>
; __device__ __forceinline__ void gemm_phase(LAS unsigned char* lds, const AMap am, const int lda, const h16* Bt, const int ldb, const int M, const int N, const int K, const Epi& E) {
;     ...
;         if (!has_next) break;
; #pragma unroll
;         for (int a = 0; a < 2; ++a)
; #pragma unroll
;             for (int b = 0; b < 2; ++b)
; #pragma unroll
;                 for (int m = 0; m < 4; ++m)
; #pragma unroll
;                     for (int n = 0; n < 2; ++n) acc[a][b][m][n] = (f32x4){0.f, 0.f, 0.f, 0.f};
;         cur = nxt; cA = nA; cB = nB; ++ui;
;     template <int GI>
;     __device__ __forceinline__ void body(const f32x4 (&acc)[2][2][4][2], int row0, int colt) const {
;     ...
;                         const h16x8 vv = *(const h16x8*)vp; const h16x8 vf = *(const h16x8*)(VF + row * DM + c);
;                         f32x4 o0, o1;
; #pragma unroll
;                         for (int j = 0; j < 4; ++j) { float v = (float)vv[j], f = (float)vf[j]; o0[j] = v + (f - v) * sigmoidf_(x0[j]); v = (float)vv[4 + j]; f = (float)vf[4 + j]; o1[j] = v + (f - v) * sigmoidf_(x1[j]); }
;                         *(u32x4*)vp = pack8(o0, o1);
	v_cvt_f32_f16_e32 v2, v14
	v_cvt_f32_f16_e32 v4, v10
	v_cvt_f32_f16_sdwa v5, v10 dst_sel:DWORD dst_unused:UNUSED_PAD src0_sel:WORD_1
	v_div_scale_f32 v10, s[0:1], v9, v9, 1.0
	v_cvt_f32_f16_sdwa v3, v14 dst_sel:DWORD dst_unused:UNUSED_PAD src0_sel:WORD_1
	v_rcp_f32_e32 v14, v10
	v_pk_add_f32 v[6:7], v[6:7], 1.0 op_sel_hi:[1,0]
	v_pk_add_f32 v[4:5], v[4:5], v[2:3] neg_lo:[0,1] neg_hi:[0,1]
	v_fma_f32 v24, -v10, v14, 1.0
	v_fmac_f32_e32 v14, v24, v14
	v_div_scale_f32 v24, vcc, 1.0, v9, 1.0
	v_mul_f32_e32 v25, v24, v14
	v_fma_f32 v26, -v10, v25, v24
	v_fmac_f32_e32 v25, v26, v14
	v_fma_f32 v10, -v10, v25, v24
	v_div_fmas_f32 v10, v10, v14, v25
	v_div_fixup_f32 v9, v10, v9, 1.0
	v_div_scale_f32 v10, s[0:1], v8, v8, 1.0
	v_rcp_f32_e32 v14, v10
	s_nop 0
	v_fma_f32 v24, -v10, v14, 1.0
	v_fmac_f32_e32 v14, v24, v14
	v_div_scale_f32 v24, vcc, 1.0, v8, 1.0
	v_mul_f32_e32 v25, v24, v14
	v_fma_f32 v26, -v10, v25, v24
	v_fmac_f32_e32 v25, v26, v14
	v_fma_f32 v10, -v10, v25, v24
	v_div_fmas_f32 v10, v10, v14, v25
	v_div_fixup_f32 v8, v10, v8, 1.0
	v_pk_fma_f32 v[2:3], v[8:9], v[4:5], v[2:3]
	v_cvt_f32_f16_e32 v8, v11
	v_cvt_f32_f16_sdwa v9, v11 dst_sel:DWORD dst_unused:UNUSED_PAD src0_sel:WORD_1
	v_pk_add_f32 v[10:11], v[22:23], 1.0 op_sel_hi:[1,0]
	v_cvt_pk_f16_f32 v2, v2, v3
	v_div_scale_f32 v3, s[0:1], v11, v11, 1.0
	v_rcp_f32_e32 v14, v3
	v_cvt_f32_f16_e32 v4, v15
	v_cvt_f32_f16_sdwa v5, v15 dst_sel:DWORD dst_unused:UNUSED_PAD src0_sel:WORD_1
	v_fma_f32 v15, -v3, v14, 1.0
	v_fmac_f32_e32 v14, v15, v14
	v_div_scale_f32 v15, vcc, 1.0, v11, 1.0
	v_mul_f32_e32 v22, v15, v14
	v_fma_f32 v23, -v3, v22, v15
	v_fmac_f32_e32 v22, v23, v14
	v_fma_f32 v3, -v3, v22, v15
	v_div_fmas_f32 v3, v3, v14, v22
	v_div_fixup_f32 v11, v3, v11, 1.0
	v_div_scale_f32 v3, s[0:1], v10, v10, 1.0
	v_rcp_f32_e32 v14, v3
	v_pk_add_f32 v[8:9], v[8:9], v[4:5] neg_lo:[0,1] neg_hi:[0,1]
	v_fma_f32 v15, -v3, v14, 1.0
	v_fmac_f32_e32 v14, v15, v14
	v_div_scale_f32 v15, vcc, 1.0, v10, 1.0
	v_mul_f32_e32 v22, v15, v14
	v_fma_f32 v23, -v3, v22, v15
	v_fmac_f32_e32 v22, v23, v14
	v_fma_f32 v3, -v3, v22, v15
	v_div_fmas_f32 v3, v3, v14, v22
	v_div_fixup_f32 v10, v3, v10, 1.0
	v_pk_fma_f32 v[4:5], v[10:11], v[8:9], v[4:5]
	v_pk_add_f32 v[10:11], v[20:21], 1.0 op_sel_hi:[1,0]
	v_cvt_f32_f16_e32 v8, v12
	v_cvt_f32_f16_sdwa v9, v12 dst_sel:DWORD dst_unused:UNUSED_PAD src0_sel:WORD_1
	v_div_scale_f32 v12, s[0:1], v11, v11, 1.0
	v_rcp_f32_e32 v14, v12
	v_cvt_pk_f16_f32 v3, v4, v5
	v_cvt_f32_f16_e32 v4, v16
	v_cvt_f32_f16_sdwa v5, v16 dst_sel:DWORD dst_unused:UNUSED_PAD src0_sel:WORD_1
	v_fma_f32 v15, -v12, v14, 1.0
	v_fmac_f32_e32 v14, v15, v14
	v_div_scale_f32 v15, vcc, 1.0, v11, 1.0
	v_mul_f32_e32 v16, v15, v14
	v_fma_f32 v20, -v12, v16, v15
	v_fmac_f32_e32 v16, v20, v14
	v_fma_f32 v12, -v12, v16, v15
	v_div_fmas_f32 v12, v12, v14, v16
	v_div_fixup_f32 v11, v12, v11, 1.0
	v_div_scale_f32 v12, s[0:1], v10, v10, 1.0
	v_rcp_f32_e32 v14, v12
	v_pk_add_f32 v[8:9], v[8:9], v[4:5] neg_lo:[0,1] neg_hi:[0,1]
	v_fma_f32 v15, -v12, v14, 1.0
	v_fmac_f32_e32 v14, v15, v14
	v_div_scale_f32 v15, vcc, 1.0, v10, 1.0
	v_mul_f32_e32 v16, v15, v14
	v_fma_f32 v20, -v12, v16, v15
	v_fmac_f32_e32 v16, v20, v14
	v_fma_f32 v12, -v12, v16, v15
	v_div_fmas_f32 v12, v12, v14, v16
	v_div_fixup_f32 v10, v12, v10, 1.0
	v_pk_fma_f32 v[4:5], v[10:11], v[8:9], v[4:5]
	v_cvt_f32_f16_e32 v10, v13
	v_cvt_pk_f16_f32 v4, v4, v5
	v_div_scale_f32 v5, s[0:1], v7, v7, 1.0
	v_rcp_f32_e32 v12, v5
	v_cvt_f32_f16_sdwa v11, v13 dst_sel:DWORD dst_unused:UNUSED_PAD src0_sel:WORD_1
	v_cvt_f32_f16_e32 v8, v17
	v_cvt_f32_f16_sdwa v9, v17 dst_sel:DWORD dst_unused:UNUSED_PAD src0_sel:WORD_1
	v_fma_f32 v13, -v5, v12, 1.0
	v_fmac_f32_e32 v12, v13, v12
	v_div_scale_f32 v13, vcc, 1.0, v7, 1.0
	v_mul_f32_e32 v14, v13, v12
	v_fma_f32 v15, -v5, v14, v13
	v_fmac_f32_e32 v14, v15, v12
	v_fma_f32 v5, -v5, v14, v13
	v_div_fmas_f32 v5, v5, v12, v14
	v_div_fixup_f32 v7, v5, v7, 1.0
	v_div_scale_f32 v5, s[0:1], v6, v6, 1.0
	v_rcp_f32_e32 v12, v5
	v_pk_add_f32 v[10:11], v[10:11], v[8:9] neg_lo:[0,1] neg_hi:[0,1]
	v_fma_f32 v13, -v5, v12, 1.0
	v_fmac_f32_e32 v12, v13, v12
	v_div_scale_f32 v13, vcc, 1.0, v6, 1.0
	v_mul_f32_e32 v14, v13, v12
	v_fma_f32 v15, -v5, v14, v13
	v_fmac_f32_e32 v14, v15, v12
	v_fma_f32 v5, -v5, v14, v13
	v_div_fmas_f32 v5, v5, v12, v14
	v_div_fixup_f32 v6, v5, v6, 1.0
	v_pk_fma_f32 v[6:7], v[6:7], v[10:11], v[8:9]
	s_nop 0
	v_cvt_pk_f16_f32 v5, v6, v7
	global_store_dwordx4 v[18:19], v[2:5], off
	s_and_b64 vcc, exec, s[38:39]
	s_mov_b32 s50, s44
	s_mov_b32 s35, s81
	s_mov_b64 s[26:27], s[64:65]
	s_mov_b64 s[22:23], s[46:47]
	s_cmpk_lt_u32 s69, 0x100
	s_cbranch_scc1 .Lgy7
	s_barrier

; #define PG8_STAGE(bufoff, gbase, voff) do { _Pragma("unroll") for (int _i = 0; _i < 2; ++_i) \
;         __builtin_amdgcn_global_load_lds((const unsigned*)((const char*)(gbase) + (voff)[_i]), (LAS unsigned*)(lds + (bufoff) + ldsw + _i * 8192), 16, 0, 0); } while (0)
; #define PG8_LDA(dst, b, h) do { _Pragma("unroll") for (int m = 0; m < 4; ++m) _Pragma("unroll") for (int k = 0; k < 2; ++k) dst[m][k] = *(const LAS h16x8*)(lds + PG8_SA(b, h) + aoff + m * 2048 + k * 1024); } while (0)
; #define PG8_LDB(dst, b, h) do { _Pragma("unroll") for (int n = 0; n < 2; ++n) _Pragma("unroll") for (int k = 0; k < 2; ++k) dst[n][k] = *(const LAS h16x8*)(lds + PG8_SB(b, h) + boff + n * 2048 + k * 1024); } while (0)
; #define PG8_MMA(ai, bj, At, Bt_) do { __builtin_amdgcn_s_setprio(1); _Pragma("unroll") for (int m = 0; m < 4; ++m) _Pragma("unroll") for (int n = 0; n < 2; ++n) _Pragma("unroll") for (int k = 0; k < 2; ++k) \
;         acc[ai][bj][m][n] = __builtin_amdgcn_mfma_f32_16x16x32_f16(Bt_[n][k], At[m][k], acc[ai][bj][m][n], 0, 0, 0); __builtin_amdgcn_s_setprio(0); } while (0)
; #define PG8_WAIT_L(n) asm volatile("s_waitcnt lgkmcnt(" #n ")" ::: "memory")
; #define PG8_BAR __builtin_amdgcn_s_barrier()
; #define PG8_SCHED __builtin_amdgcn_sched_barrier(0)
; template <class Epi, class AMap>
; __device__ __forceinline__ void gemm_phase(LAS unsigned char* lds, const AMap am, const int lda, const h16* Bt, const int ldb, const int M, const int N, const int K, const Epi& E) {
;     ...
;             PG8_LDB(B0, 0, 0); PG8_SCHED; PG8_LDA(At, 0, 0); PG8_STAGE(PG8_SA(1, 1), a1 + hstepA, voffA);
;             PG8_WAIT_L(8); PG8_BAR; PG8_WAIT_L(0); PG8_MMA(0, 0, At, B0); PG8_BAR; PG8_SCHED;
;             PG8_LDB(B1, 0, 1); PG8_STAGE(PG8_SB(0, 0), b2, voffB);
;             PG8_BAR; PG8_WAIT_L(0); PG8_MMA(0, 1, At, B1); PG8_BAR;
;             PG8_LDA(At, 0, 1); PG8_STAGE(PG8_SA(0, 0), a2, voffA);
;             PG8_BAR; PG8_WAIT_L(0); PG8_MMA(1, 0, At, B0); PG8_BAR; PG8_SCHED;
.LBB0_692:
	s_add_i32 s51, s26, 2
	s_add_u32 s0, s22, 0x100
	s_addc_u32 s1, s23, 0
	s_add_i32 s60, 0, 0x10000
	v_add_u32_e32 v234, s60, v175
	ds_read_b128 v[82:85], v234
	ds_read_b128 v[86:89], v234 offset:1024
	ds_read_b128 v[138:141], v234 offset:2048
	ds_read_b128 v[142:145], v234 offset:3072
	s_cmp_eq_u32 s61, s26
	s_cselect_b32 s26, s21, s29
	s_cselect_b32 s49, s47, s1
	s_cselect_b32 s48, s46, s0
	s_cselect_b32 s27, s20, s45
	v_lshl_add_u64 v[172:173], s[22:23], 0, v[152:153]
	s_add_i32 m0, s74, 0xc000
	ds_read_b128 v[156:159], v177
	ds_read_b128 v[160:163], v177 offset:1024
	ds_read_b128 v[164:167], v177 offset:2048
	ds_read_b128 v[168:171], v177 offset:3072
	ds_read_b128 v[178:181], v177 offset:4096
	ds_read_b128 v[182:185], v177 offset:5120
	ds_read_b128 v[186:189], v177 offset:6144
	ds_read_b128 v[190:193], v177 offset:7168
	global_load_lds_dwordx4 v[172:173], off
	v_lshl_add_u64 v[172:173], s[22:23], 0, v[154:155]
	s_add_i32 m0, s74, 0xe000
	s_nop 0
	global_load_lds_dwordx4 v[172:173], off
	s_waitcnt lgkmcnt(11)
	s_add_i32 s62, 0, 0x14000
	v_add_u32_e32 v172, s62, v175
	s_add_i32 s22, s60, s71
	ds_read_b128 v[194:197], v172
	ds_read_b128 v[198:201], v172 offset:1024
	ds_read_b128 v[202:205], v172 offset:2048
	ds_read_b128 v[220:223], v172 offset:3072
	s_waitcnt vmcnt(8) lgkmcnt(0)
	s_barrier
	v_mfma_f32_16x16x32_f16 v[134:137], v[82:85], v[156:159], v[134:137]
	v_mfma_f32_16x16x32_f16 v[130:133], v[138:141], v[156:159], v[130:133]
	v_mfma_f32_16x16x32_f16 v[126:129], v[82:85], v[164:167], v[126:129]
	v_mfma_f32_16x16x32_f16 v[122:125], v[138:141], v[164:167], v[122:125]
	v_mfma_f32_16x16x32_f16 v[118:121], v[82:85], v[178:181], v[118:121]
	v_mfma_f32_16x16x32_f16 v[114:117], v[138:141], v[178:181], v[114:117]
	v_mfma_f32_16x16x32_f16 v[110:113], v[82:85], v[186:189], v[110:113]
	v_mfma_f32_16x16x32_f16 v[106:109], v[138:141], v[186:189], v[106:109]
	v_mfma_f32_16x16x32_f16 v[134:137], v[86:89], v[160:163], v[134:137]
	v_mfma_f32_16x16x32_f16 v[130:133], v[142:145], v[160:163], v[130:133]
	v_mfma_f32_16x16x32_f16 v[126:129], v[86:89], v[168:171], v[126:129]
	v_mfma_f32_16x16x32_f16 v[122:125], v[142:145], v[168:171], v[122:125]
	v_mfma_f32_16x16x32_f16 v[118:121], v[86:89], v[182:185], v[118:121]
	v_mfma_f32_16x16x32_f16 v[114:117], v[142:145], v[182:185], v[114:117]
	v_mfma_f32_16x16x32_f16 v[110:113], v[86:89], v[190:193], v[110:113]
	v_mfma_f32_16x16x32_f16 v[106:109], v[142:145], v[190:193], v[106:109]
	v_mfma_f32_16x16x32_f16 v[62:65], v[194:197], v[156:159], v[62:65]
	v_mfma_f32_16x16x32_f16 v[58:61], v[202:205], v[156:159], v[58:61]
	v_mfma_f32_16x16x32_f16 v[54:57], v[194:197], v[164:167], v[54:57]
	v_mfma_f32_16x16x32_f16 v[50:53], v[202:205], v[164:167], v[50:53]
	v_mfma_f32_16x16x32_f16 v[46:49], v[194:197], v[178:181], v[46:49]
	v_mfma_f32_16x16x32_f16 v[42:45], v[202:205], v[178:181], v[42:45]
	v_mfma_f32_16x16x32_f16 v[38:41], v[194:197], v[186:189], v[38:41]
	v_mfma_f32_16x16x32_f16 v[34:37], v[202:205], v[186:189], v[34:37]
	v_mfma_f32_16x16x32_f16 v[62:65], v[198:201], v[160:163], v[62:65]
	v_mfma_f32_16x16x32_f16 v[58:61], v[220:223], v[160:163], v[58:61]
	v_mfma_f32_16x16x32_f16 v[54:57], v[198:201], v[168:171], v[54:57]
	v_mfma_f32_16x16x32_f16 v[50:53], v[220:223], v[168:171], v[50:53]
	v_mfma_f32_16x16x32_f16 v[46:49], v[198:201], v[182:185], v[46:49]
	v_mfma_f32_16x16x32_f16 v[42:45], v[220:223], v[182:185], v[42:45]
	v_mfma_f32_16x16x32_f16 v[38:41], v[198:201], v[190:193], v[38:41]
	v_mfma_f32_16x16x32_f16 v[34:37], v[220:223], v[190:193], v[34:37]
	s_barrier
	v_lshl_add_u64 v[172:173], s[26:27], 0, v[0:1]
	s_mov_b32 m0, s22
	v_lshl_add_u64 v[206:207], s[26:27], 0, v[150:151]
	global_load_lds_dwordx4 v[172:173], off
	s_add_i32 m0, s22, 0x2000
	s_nop 0
	global_load_lds_dwordx4 v[206:207], off
	s_mov_b32 m0, s74
	v_lshl_add_u64 v[212:213], s[48:49], 0, v[146:147]
	ds_read_b128 v[156:159], v177 offset:16384
	ds_read_b128 v[160:163], v177 offset:17408
	ds_read_b128 v[164:167], v177 offset:18432
	ds_read_b128 v[168:171], v177 offset:19456
	ds_read_b128 v[178:181], v177 offset:20480
	ds_read_b128 v[182:185], v177 offset:21504
	ds_read_b128 v[186:189], v177 offset:22528
	ds_read_b128 v[190:193], v177 offset:23552
	global_load_lds_dwordx4 v[212:213], off
	v_lshl_add_u64 v[224:225], s[48:49], 0, v[148:149]
	s_mov_b32 m0, s75
	s_nop 0
	global_load_lds_dwordx4 v[224:225], off
	s_add_u32 s22, s26, 0x10000
	s_addc_u32 s23, s27, 0
	s_add_i32 s60, s62, s71
	v_lshl_add_u64 v[232:233], s[22:23], 0, v[0:1]
	s_mov_b32 m0, s60
	s_nop 0
	global_load_lds_dwordx4 v[232:233], off
	v_lshl_add_u64 v[232:233], s[22:23], 0, v[150:151]
	s_add_i32 m0, s60, 0x2000
	s_nop 0
	global_load_lds_dwordx4 v[232:233], off
	s_waitcnt vmcnt(8) lgkmcnt(0)
	s_barrier
; #define PG8_STAGE(bufoff, gbase, voff) do { _Pragma("unroll") for (int _i = 0; _i < 2; ++_i) \
;         __builtin_amdgcn_global_load_lds((const unsigned*)((const char*)(gbase) + (voff)[_i]), (LAS unsigned*)(lds + (bufoff) + ldsw + _i * 8192), 16, 0, 0); } while (0)
; #define PG8_LDA(dst, b, h) do { _Pragma("unroll") for (int m = 0; m < 4; ++m) _Pragma("unroll") for (int k = 0; k < 2; ++k) dst[m][k] = *(const LAS h16x8*)(lds + PG8_SA(b, h) + aoff + m * 2048 + k * 1024); } while (0)
; #define PG8_LDB(dst, b, h) do { _Pragma("unroll") for (int n = 0; n < 2; ++n) _Pragma("unroll") for (int k = 0; k < 2; ++k) dst[n][k] = *(const LAS h16x8*)(lds + PG8_SB(b, h) + boff + n * 2048 + k * 1024); } while (0)
; #define PG8_MMA(ai, bj, At, Bt_) do { __builtin_amdgcn_s_setprio(1); _Pragma("unroll") for (int m = 0; m < 4; ++m) _Pragma("unroll") for (int n = 0; n < 2; ++n) _Pragma("unroll") for (int k = 0; k < 2; ++k) \
;         acc[ai][bj][m][n] = __builtin_amdgcn_mfma_f32_16x16x32_f16(Bt_[n][k], At[m][k], acc[ai][bj][m][n], 0, 0, 0); __builtin_amdgcn_s_setprio(0); } while (0)
; #define PG8_WAIT_V(n) asm volatile("s_waitcnt vmcnt(" #n ")" ::: "memory")
; #define PG8_WAIT_L(n) asm volatile("s_waitcnt lgkmcnt(" #n ")" ::: "memory")
; #define PG8_BAR __builtin_amdgcn_s_barrier()
; #define PG8_SCHED __builtin_amdgcn_sched_barrier(0)
; template <class Epi, class AMap>
; __device__ __forceinline__ void gemm_phase(LAS unsigned char* lds, const AMap am, const int lda, const h16* Bt, const int ldb, const int M, const int N, const int K, const Epi& E) {
;     ...
;             PG8_BAR; PG8_WAIT_L(0); PG8_MMA(1, 0, At, B0); PG8_BAR; PG8_SCHED;
;             PG8_STAGE(PG8_SB(0, 1), b2 + hstepB, voffB);
;             PG8_WAIT_V(6); PG8_BAR; PG8_MMA(1, 1, At, B1); PG8_BAR;
;             PG8_LDB(B0, 1, 0); PG8_SCHED; PG8_LDA(At, 1, 0); PG8_STAGE(PG8_SA(0, 1), a2 + hstepA, voffA);
;             PG8_WAIT_L(8); PG8_BAR; PG8_WAIT_L(0); PG8_MMA(0, 0, At, B0); PG8_BAR; PG8_SCHED;
;             PG8_LDB(B1, 1, 1); PG8_STAGE(PG8_SB(1, 0), b3, voffB);
;             PG8_BAR; PG8_WAIT_L(0); PG8_MMA(0, 1, At, B1); PG8_BAR;
	v_mfma_f32_16x16x32_f16 v[102:105], v[82:85], v[156:159], v[102:105]
	v_mfma_f32_16x16x32_f16 v[98:101], v[138:141], v[156:159], v[98:101]
	v_mfma_f32_16x16x32_f16 v[94:97], v[82:85], v[164:167], v[94:97]
	v_mfma_f32_16x16x32_f16 v[90:93], v[138:141], v[164:167], v[90:93]
	v_mfma_f32_16x16x32_f16 v[78:81], v[82:85], v[178:181], v[78:81]
	v_mfma_f32_16x16x32_f16 v[74:77], v[138:141], v[178:181], v[74:77]
	v_mfma_f32_16x16x32_f16 v[70:73], v[82:85], v[186:189], v[70:73]
	v_mfma_f32_16x16x32_f16 v[66:69], v[138:141], v[186:189], v[66:69]
	v_mfma_f32_16x16x32_f16 v[102:105], v[86:89], v[160:163], v[102:105]
	v_mfma_f32_16x16x32_f16 v[98:101], v[142:145], v[160:163], v[98:101]
	v_mfma_f32_16x16x32_f16 v[94:97], v[86:89], v[168:171], v[94:97]
	v_mfma_f32_16x16x32_f16 v[90:93], v[142:145], v[168:171], v[90:93]
	v_mfma_f32_16x16x32_f16 v[78:81], v[86:89], v[182:185], v[78:81]
	v_mfma_f32_16x16x32_f16 v[74:77], v[142:145], v[182:185], v[74:77]
	v_mfma_f32_16x16x32_f16 v[70:73], v[86:89], v[190:193], v[70:73]
	v_mfma_f32_16x16x32_f16 v[66:69], v[142:145], v[190:193], v[66:69]
	v_mfma_f32_16x16x32_f16 v[30:33], v[194:197], v[156:159], v[30:33]
	v_mfma_f32_16x16x32_f16 v[26:29], v[202:205], v[156:159], v[26:29]
	v_mfma_f32_16x16x32_f16 v[22:25], v[194:197], v[164:167], v[22:25]
	v_mfma_f32_16x16x32_f16 v[18:21], v[202:205], v[164:167], v[18:21]
	v_mfma_f32_16x16x32_f16 v[14:17], v[194:197], v[178:181], v[14:17]
	v_mfma_f32_16x16x32_f16 v[10:13], v[202:205], v[178:181], v[10:13]
	v_mfma_f32_16x16x32_f16 v[6:9], v[194:197], v[186:189], v[6:9]
	v_mfma_f32_16x16x32_f16 v[2:5], v[202:205], v[186:189], v[2:5]
	v_mfma_f32_16x16x32_f16 v[30:33], v[198:201], v[160:163], v[30:33]
	v_mfma_f32_16x16x32_f16 v[26:29], v[220:223], v[160:163], v[26:29]
	v_mfma_f32_16x16x32_f16 v[22:25], v[198:201], v[168:171], v[22:25]
	v_mfma_f32_16x16x32_f16 v[18:21], v[220:223], v[168:171], v[18:21]
	v_mfma_f32_16x16x32_f16 v[14:17], v[198:201], v[182:185], v[14:17]
	v_mfma_f32_16x16x32_f16 v[10:13], v[220:223], v[182:185], v[10:13]
	v_mfma_f32_16x16x32_f16 v[6:9], v[198:201], v[190:193], v[6:9]
	v_mfma_f32_16x16x32_f16 v[2:5], v[220:223], v[190:193], v[2:5]
	s_barrier
	s_add_i32 s60, 0, 0x18000
	v_add_u32_e32 v234, s60, v175
	ds_read_b128 v[82:85], v234
	ds_read_b128 v[86:89], v234 offset:1024
	ds_read_b128 v[138:141], v234 offset:2048
	ds_read_b128 v[142:145], v234 offset:3072
	s_add_u32 s22, s48, 0x1c0000
	s_addc_u32 s23, s49, 0
	s_mov_b32 m0, s76
	v_lshl_add_u64 v[232:233], s[22:23], 0, v[146:147]
	ds_read_b128 v[156:159], v177 offset:32768
	ds_read_b128 v[160:163], v177 offset:33792
	ds_read_b128 v[164:167], v177 offset:34816
	ds_read_b128 v[168:171], v177 offset:35840
	ds_read_b128 v[178:181], v177 offset:36864
	ds_read_b128 v[182:185], v177 offset:37888
	ds_read_b128 v[186:189], v177 offset:38912
	ds_read_b128 v[190:193], v177 offset:39936
	global_load_lds_dwordx4 v[232:233], off
	v_lshl_add_u64 v[232:233], s[22:23], 0, v[148:149]
	s_mov_b32 m0, s77
	s_nop 0
	global_load_lds_dwordx4 v[232:233], off
	s_waitcnt lgkmcnt(11)
	s_add_i32 s48, 0, 0x1c000
	s_add_i32 s22, s60, s71
	v_add_u32_e32 v214, s48, v175
	v_lshl_add_u64 v[172:173], v[172:173], 0, s[92:93]
	s_mov_b32 m0, s22
	ds_read_b128 v[194:197], v214
	ds_read_b128 v[198:201], v214 offset:1024
	ds_read_b128 v[202:205], v214 offset:2048
	ds_read_b128 v[220:223], v214 offset:3072
	s_waitcnt vmcnt(8) lgkmcnt(0)
	s_barrier
	v_mfma_f32_16x16x32_f16 v[134:137], v[82:85], v[156:159], v[134:137]
	v_mfma_f32_16x16x32_f16 v[130:133], v[138:141], v[156:159], v[130:133]
	v_mfma_f32_16x16x32_f16 v[126:129], v[82:85], v[164:167], v[126:129]
	v_mfma_f32_16x16x32_f16 v[122:125], v[138:141], v[164:167], v[122:125]
	v_mfma_f32_16x16x32_f16 v[118:121], v[82:85], v[178:181], v[118:121]
	v_mfma_f32_16x16x32_f16 v[114:117], v[138:141], v[178:181], v[114:117]
	v_mfma_f32_16x16x32_f16 v[110:113], v[82:85], v[186:189], v[110:113]
	v_mfma_f32_16x16x32_f16 v[106:109], v[138:141], v[186:189], v[106:109]
	v_mfma_f32_16x16x32_f16 v[134:137], v[86:89], v[160:163], v[134:137]
	v_mfma_f32_16x16x32_f16 v[130:133], v[142:145], v[160:163], v[130:133]
	v_mfma_f32_16x16x32_f16 v[126:129], v[86:89], v[168:171], v[126:129]
	v_mfma_f32_16x16x32_f16 v[122:125], v[142:145], v[168:171], v[122:125]
	v_mfma_f32_16x16x32_f16 v[118:121], v[86:89], v[182:185], v[118:121]
	v_mfma_f32_16x16x32_f16 v[114:117], v[142:145], v[182:185], v[114:117]
	v_mfma_f32_16x16x32_f16 v[110:113], v[86:89], v[190:193], v[110:113]
	v_mfma_f32_16x16x32_f16 v[106:109], v[142:145], v[190:193], v[106:109]
	v_mfma_f32_16x16x32_f16 v[62:65], v[194:197], v[156:159], v[62:65]
	v_mfma_f32_16x16x32_f16 v[58:61], v[202:205], v[156:159], v[58:61]
	v_mfma_f32_16x16x32_f16 v[54:57], v[194:197], v[164:167], v[54:57]
	v_mfma_f32_16x16x32_f16 v[50:53], v[202:205], v[164:167], v[50:53]
	v_mfma_f32_16x16x32_f16 v[46:49], v[194:197], v[178:181], v[46:49]
	v_mfma_f32_16x16x32_f16 v[42:45], v[202:205], v[178:181], v[42:45]
	v_mfma_f32_16x16x32_f16 v[38:41], v[194:197], v[186:189], v[38:41]
	v_mfma_f32_16x16x32_f16 v[34:37], v[202:205], v[186:189], v[34:37]
	v_mfma_f32_16x16x32_f16 v[62:65], v[198:201], v[160:163], v[62:65]
	v_mfma_f32_16x16x32_f16 v[58:61], v[220:223], v[160:163], v[58:61]
	v_mfma_f32_16x16x32_f16 v[54:57], v[198:201], v[168:171], v[54:57]
	v_mfma_f32_16x16x32_f16 v[50:53], v[220:223], v[168:171], v[50:53]
	v_mfma_f32_16x16x32_f16 v[46:49], v[198:201], v[182:185], v[46:49]
	v_mfma_f32_16x16x32_f16 v[42:45], v[220:223], v[182:185], v[42:45]
	v_mfma_f32_16x16x32_f16 v[38:41], v[198:201], v[190:193], v[38:41]
	v_mfma_f32_16x16x32_f16 v[34:37], v[220:223], v[190:193], v[34:37]
	s_barrier
; #define PG8_STAGE(bufoff, gbase, voff) do { _Pragma("unroll") for (int _i = 0; _i < 2; ++_i) \
;         __builtin_amdgcn_global_load_lds((const unsigned*)((const char*)(gbase) + (voff)[_i]), (LAS unsigned*)(lds + (bufoff) + ldsw + _i * 8192), 16, 0, 0); } while (0)
; #define PG8_LDA(dst, b, h) do { _Pragma("unroll") for (int m = 0; m < 4; ++m) _Pragma("unroll") for (int k = 0; k < 2; ++k) dst[m][k] = *(const LAS h16x8*)(lds + PG8_SA(b, h) + aoff + m * 2048 + k * 1024); } while (0)
; #define PG8_MMA(ai, bj, At, Bt_) do { __builtin_amdgcn_s_setprio(1); _Pragma("unroll") for (int m = 0; m < 4; ++m) _Pragma("unroll") for (int n = 0; n < 2; ++n) _Pragma("unroll") for (int k = 0; k < 2; ++k) \
;         acc[ai][bj][m][n] = __builtin_amdgcn_mfma_f32_16x16x32_f16(Bt_[n][k], At[m][k], acc[ai][bj][m][n], 0, 0, 0); __builtin_amdgcn_s_setprio(0); } while (0)
; #define PG8_WAIT_V(n) asm volatile("s_waitcnt vmcnt(" #n ")" ::: "memory")
; #define PG8_WAIT_L(n) asm volatile("s_waitcnt lgkmcnt(" #n ")" ::: "memory")
; #define PG8_BAR __builtin_amdgcn_s_barrier()
; #define PG8_SCHED __builtin_amdgcn_sched_barrier(0)
; template <class Epi, class AMap>
; __device__ __forceinline__ void gemm_phase(LAS unsigned char* lds, const AMap am, const int lda, const h16* Bt, const int ldb, const int M, const int N, const int K, const Epi& E) {
;     ...
;             PG8_LDA(At, 1, 1); PG8_STAGE(PG8_SA(1, 0), a3, voffA);
;             PG8_BAR; PG8_WAIT_L(0); PG8_MMA(1, 0, At, B0); PG8_BAR; PG8_SCHED;
;             PG8_STAGE(PG8_SB(1, 1), b3 + hstepB, voffB);
;             PG8_WAIT_V(6); PG8_BAR; PG8_MMA(1, 1, At, B1); PG8_BAR;
;         }
;         E(acc, cur, wr, wc, fr, fq);
;         if (!has_next) break;
	global_load_lds_dwordx4 v[172:173], off
	v_lshl_add_u64 v[172:173], v[206:207], 0, s[92:93]
	s_add_i32 m0, s22, 0x2000
	s_nop 0
	global_load_lds_dwordx4 v[172:173], off
	s_mov_b32 m0, s79
	v_lshl_add_u64 v[172:173], v[212:213], 0, s[92:93]
	ds_read_b128 v[156:159], v177 offset:49152
	ds_read_b128 v[160:163], v177 offset:50176
	ds_read_b128 v[164:167], v177 offset:51200
	ds_read_b128 v[168:171], v177 offset:52224
	ds_read_b128 v[178:181], v177 offset:53248
	ds_read_b128 v[182:185], v177 offset:54272
	ds_read_b128 v[186:189], v177 offset:55296
	ds_read_b128 v[190:193], v177 offset:56320
	global_load_lds_dwordx4 v[172:173], off
	v_lshl_add_u64 v[172:173], v[224:225], 0, s[92:93]
	s_mov_b32 m0, s80
	s_nop 0
	global_load_lds_dwordx4 v[172:173], off
	s_add_u32 s22, s26, 0x10080
	s_addc_u32 s23, s27, 0
	s_add_i32 s26, s48, s71
	v_lshl_add_u64 v[232:233], s[22:23], 0, v[0:1]
	s_mov_b32 m0, s26
	s_nop 0
	global_load_lds_dwordx4 v[232:233], off
	v_lshl_add_u64 v[232:233], s[22:23], 0, v[150:151]
	s_add_i32 m0, s26, 0x2000
	s_nop 0
	global_load_lds_dwordx4 v[232:233], off
	s_waitcnt vmcnt(8) lgkmcnt(0)
	s_barrier
	v_mfma_f32_16x16x32_f16 v[102:105], v[82:85], v[156:159], v[102:105]
	v_mfma_f32_16x16x32_f16 v[98:101], v[138:141], v[156:159], v[98:101]
	v_mfma_f32_16x16x32_f16 v[94:97], v[82:85], v[164:167], v[94:97]
	v_mfma_f32_16x16x32_f16 v[90:93], v[138:141], v[164:167], v[90:93]
	v_mfma_f32_16x16x32_f16 v[78:81], v[82:85], v[178:181], v[78:81]
	v_mfma_f32_16x16x32_f16 v[74:77], v[138:141], v[178:181], v[74:77]
	v_mfma_f32_16x16x32_f16 v[70:73], v[82:85], v[186:189], v[70:73]
	v_mfma_f32_16x16x32_f16 v[66:69], v[138:141], v[186:189], v[66:69]
	v_mfma_f32_16x16x32_f16 v[102:105], v[86:89], v[160:163], v[102:105]
	v_mfma_f32_16x16x32_f16 v[98:101], v[142:145], v[160:163], v[98:101]
	v_mfma_f32_16x16x32_f16 v[94:97], v[86:89], v[168:171], v[94:97]
	v_mfma_f32_16x16x32_f16 v[90:93], v[142:145], v[168:171], v[90:93]
	v_mfma_f32_16x16x32_f16 v[78:81], v[86:89], v[182:185], v[78:81]
	v_mfma_f32_16x16x32_f16 v[74:77], v[142:145], v[182:185], v[74:77]
	v_mfma_f32_16x16x32_f16 v[70:73], v[86:89], v[190:193], v[70:73]
	v_mfma_f32_16x16x32_f16 v[66:69], v[142:145], v[190:193], v[66:69]
	v_mfma_f32_16x16x32_f16 v[30:33], v[194:197], v[156:159], v[30:33]
	v_mfma_f32_16x16x32_f16 v[26:29], v[202:205], v[156:159], v[26:29]
	v_mfma_f32_16x16x32_f16 v[22:25], v[194:197], v[164:167], v[22:25]
	v_mfma_f32_16x16x32_f16 v[18:21], v[202:205], v[164:167], v[18:21]
	v_mfma_f32_16x16x32_f16 v[14:17], v[194:197], v[178:181], v[14:17]
	v_mfma_f32_16x16x32_f16 v[10:13], v[202:205], v[178:181], v[10:13]
	v_mfma_f32_16x16x32_f16 v[6:9], v[194:197], v[186:189], v[6:9]
	v_mfma_f32_16x16x32_f16 v[2:5], v[202:205], v[186:189], v[2:5]
	v_mfma_f32_16x16x32_f16 v[30:33], v[198:201], v[160:163], v[30:33]
	v_mfma_f32_16x16x32_f16 v[26:29], v[220:223], v[160:163], v[26:29]
	v_mfma_f32_16x16x32_f16 v[22:25], v[198:201], v[168:171], v[22:25]
	v_mfma_f32_16x16x32_f16 v[18:21], v[220:223], v[168:171], v[18:21]
	v_mfma_f32_16x16x32_f16 v[14:17], v[198:201], v[182:185], v[14:17]
	v_mfma_f32_16x16x32_f16 v[10:13], v[220:223], v[182:185], v[10:13]
	v_mfma_f32_16x16x32_f16 v[6:9], v[198:201], v[190:193], v[6:9]
	v_mfma_f32_16x16x32_f16 v[2:5], v[220:223], v[190:193], v[2:5]
	s_add_u32 s29, s29, 0x100
	s_addc_u32 s45, s45, 0
	s_cmp_ge_i32 s51, s24
	s_mov_b64 s[22:23], s[0:1]
	s_mov_b32 s26, s51
	s_barrier
	s_cbranch_scc0 .LBB0_692
	s_cmpk_gt_u32 s69, 0xff
	s_cbranch_scc1 .Lgx7
	s_barrier

; template <class Epi, class AMap>
; __device__ __forceinline__ void gemm_phase(LAS unsigned char* lds, const AMap am, const int lda, const h16* Bt, const int ldb, const int M, const int N, const int K, const Epi& E) {
;     ...
;         const bool has_next = S.next(ui + 1, nxt);
;         const char* nA = has_next ? am(nxt.pn) + (size_t)nxt.pm * tstepA : cA; const char* nB = has_next ? (const char*)Bt + (size_t)nxt.pn * tstepB : cB;
;     ...
;         if (!has_next) break;
; #pragma unroll
;         for (int a = 0; a < 2; ++a)
; #pragma unroll
;             for (int b = 0; b < 2; ++b)
; #pragma unroll
;                 for (int m = 0; m < 4; ++m)
; #pragma unroll
;                     for (int n = 0; n < 2; ++n) acc[a][b][m][n] = (f32x4){0.f, 0.f, 0.f, 0.f};
;         cur = nxt; cA = nA; cB = nB; ++ui;
;     }
.LBB0_781:
	s_and_b64 vcc, exec, s[38:39]
	s_mov_b32 s22, s42
	s_mov_b32 s26, s44
	s_mov_b64 s[40:41], s[64:65]
	s_mov_b64 s[48:49], s[46:47]
	s_cmpk_lt_u32 s71, 0x100
	s_cbranch_scc1 .Lgy8
	s_barrier

; #define PG8_STAGE(bufoff, gbase, voff) do { _Pragma("unroll") for (int _i = 0; _i < 2; ++_i) \
;         __builtin_amdgcn_global_load_lds((const unsigned*)((const char*)(gbase) + (voff)[_i]), (LAS unsigned*)(lds + (bufoff) + ldsw + _i * 8192), 16, 0, 0); } while (0)
; #define PG8_LDA(dst, b, h) do { _Pragma("unroll") for (int m = 0; m < 4; ++m) _Pragma("unroll") for (int k = 0; k < 2; ++k) dst[m][k] = *(const LAS h16x8*)(lds + PG8_SA(b, h) + aoff + m * 2048 + k * 1024); } while (0)
; #define PG8_LDB(dst, b, h) do { _Pragma("unroll") for (int n = 0; n < 2; ++n) _Pragma("unroll") for (int k = 0; k < 2; ++k) dst[n][k] = *(const LAS h16x8*)(lds + PG8_SB(b, h) + boff + n * 2048 + k * 1024); } while (0)
; #define PG8_MMA(ai, bj, At, Bt_) do { __builtin_amdgcn_s_setprio(1); _Pragma("unroll") for (int m = 0; m < 4; ++m) _Pragma("unroll") for (int n = 0; n < 2; ++n) _Pragma("unroll") for (int k = 0; k < 2; ++k) \
;         acc[ai][bj][m][n] = __builtin_amdgcn_mfma_f32_16x16x32_f16(Bt_[n][k], At[m][k], acc[ai][bj][m][n], 0, 0, 0); __builtin_amdgcn_s_setprio(0); } while (0)
; #define PG8_WAIT_V(n) asm volatile("s_waitcnt vmcnt(" #n ")" ::: "memory")
; template <class Epi, class AMap>
; __device__ __forceinline__ void gemm_phase(LAS unsigned char* lds, const AMap am, const int lda, const h16* Bt, const int ldb, const int M, const int N, const int K, const Epi& E) {
;     ...
;         for (int t = 0; t < nt; t += 2) {
;             const bool last = (t == nt - 2);
;             const char* a1 = cA + (size_t)(t + 1) * kstep;
;             const char* a2 = last ? nA : cA + (size_t)(t + 2) * kstep; const char* b2 = last ? nB : cB + (size_t)(t + 2) * kstep;
;             const char* a3 = a2 + kstep; const char* b3 = b2 + kstep;
;             PG8_LDB(B0, 0, 0); PG8_SCHED; PG8_LDA(At, 0, 0); PG8_STAGE(PG8_SA(1, 1), a1 + hstepA, voffA);
;             PG8_WAIT_L(8); PG8_BAR; PG8_WAIT_L(0); PG8_MMA(0, 0, At, B0); PG8_BAR; PG8_SCHED;
;             PG8_LDB(B1, 0, 1); PG8_STAGE(PG8_SB(0, 0), b2, voffB);
;             PG8_BAR; PG8_WAIT_L(0); PG8_MMA(0, 1, At, B1); PG8_BAR;
;             PG8_LDA(At, 0, 1); PG8_STAGE(PG8_SA(0, 0), a2, voffA);
;             PG8_BAR; PG8_WAIT_L(0); PG8_MMA(1, 0, At, B0); PG8_BAR; PG8_SCHED;
;             PG8_STAGE(PG8_SB(0, 1), b2 + hstepB, voffB);
;             PG8_WAIT_V(6); PG8_BAR; PG8_MMA(1, 1, At, B1); PG8_BAR;
.LBB0_799:
	s_add_u32 s40, s0, 0xfff80080
	s_addc_u32 s41, s1, -1
	s_add_i32 s45, 0, 0x10000
	v_add_u32_e32 v152, s45, v155
	ds_read_b128 v[130:133], v152
	ds_read_b128 v[134:137], v152 offset:1024
	ds_read_b128 v[148:151], v152 offset:2048
	ds_read_b128 v[158:161], v152 offset:3072
	s_cmp_eq_u32 s43, 28
	s_cselect_b32 s49, s47, s41
	s_cselect_b32 s48, s46, s40
	s_cselect_b32 s41, s29, s35
	s_cselect_b32 s40, s20, s21
	v_lshl_add_u64 v[152:153], s[0:1], 0, v[144:145]
	s_add_i32 m0, s23, 0xc000
	ds_read_b128 v[162:165], v157
	ds_read_b128 v[166:169], v157 offset:1024
	ds_read_b128 v[170:173], v157 offset:2048
	ds_read_b128 v[174:177], v157 offset:3072
	ds_read_b128 v[178:181], v157 offset:4096
	ds_read_b128 v[182:185], v157 offset:5120
	ds_read_b128 v[186:189], v157 offset:6144
	ds_read_b128 v[190:193], v157 offset:7168
	global_load_lds_dwordx4 v[152:153], off
	v_lshl_add_u64 v[152:153], s[0:1], 0, v[146:147]
	s_add_i32 m0, s23, 0xe000
	s_nop 0
	global_load_lds_dwordx4 v[152:153], off
	s_waitcnt lgkmcnt(11)
	s_add_i32 s60, 0, 0x14000
	v_add_u32_e32 v152, s60, v155
	s_add_i32 s45, s45, s72
	ds_read_b128 v[194:197], v152
	ds_read_b128 v[198:201], v152 offset:1024
	ds_read_b128 v[202:205], v152 offset:2048
	ds_read_b128 v[220:223], v152 offset:3072
	s_waitcnt vmcnt(8) lgkmcnt(0)
	s_barrier
	v_mfma_f32_16x16x32_f16 v[126:129], v[130:133], v[162:165], v[126:129]
	v_mfma_f32_16x16x32_f16 v[122:125], v[148:151], v[162:165], v[122:125]
	v_mfma_f32_16x16x32_f16 v[110:113], v[130:133], v[170:173], v[110:113]
	v_mfma_f32_16x16x32_f16 v[106:109], v[148:151], v[170:173], v[106:109]
	v_mfma_f32_16x16x32_f16 v[94:97], v[130:133], v[178:181], v[94:97]
	v_mfma_f32_16x16x32_f16 v[90:93], v[148:151], v[178:181], v[90:93]
	v_mfma_f32_16x16x32_f16 v[78:81], v[130:133], v[186:189], v[78:81]
	v_mfma_f32_16x16x32_f16 v[74:77], v[148:151], v[186:189], v[74:77]
	v_mfma_f32_16x16x32_f16 v[126:129], v[134:137], v[166:169], v[126:129]
	v_mfma_f32_16x16x32_f16 v[122:125], v[158:161], v[166:169], v[122:125]
	v_mfma_f32_16x16x32_f16 v[110:113], v[134:137], v[174:177], v[110:113]
	v_mfma_f32_16x16x32_f16 v[106:109], v[158:161], v[174:177], v[106:109]
	v_mfma_f32_16x16x32_f16 v[94:97], v[134:137], v[182:185], v[94:97]
	v_mfma_f32_16x16x32_f16 v[90:93], v[158:161], v[182:185], v[90:93]
	v_mfma_f32_16x16x32_f16 v[78:81], v[134:137], v[190:193], v[78:81]
	v_mfma_f32_16x16x32_f16 v[74:77], v[158:161], v[190:193], v[74:77]
	v_mfma_f32_16x16x32_f16 v[118:121], v[194:197], v[162:165], v[118:121]
	v_mfma_f32_16x16x32_f16 v[114:117], v[202:205], v[162:165], v[114:117]
	v_mfma_f32_16x16x32_f16 v[102:105], v[194:197], v[170:173], v[102:105]
	v_mfma_f32_16x16x32_f16 v[98:101], v[202:205], v[170:173], v[98:101]
	v_mfma_f32_16x16x32_f16 v[86:89], v[194:197], v[178:181], v[86:89]
	v_mfma_f32_16x16x32_f16 v[82:85], v[202:205], v[178:181], v[82:85]
	v_mfma_f32_16x16x32_f16 v[70:73], v[194:197], v[186:189], v[70:73]
	v_mfma_f32_16x16x32_f16 v[66:69], v[202:205], v[186:189], v[66:69]
	v_mfma_f32_16x16x32_f16 v[118:121], v[198:201], v[166:169], v[118:121]
	v_mfma_f32_16x16x32_f16 v[114:117], v[220:223], v[166:169], v[114:117]
	v_mfma_f32_16x16x32_f16 v[102:105], v[198:201], v[174:177], v[102:105]
	v_mfma_f32_16x16x32_f16 v[98:101], v[220:223], v[174:177], v[98:101]
	v_mfma_f32_16x16x32_f16 v[86:89], v[198:201], v[182:185], v[86:89]
	v_mfma_f32_16x16x32_f16 v[82:85], v[220:223], v[182:185], v[82:85]
	v_mfma_f32_16x16x32_f16 v[70:73], v[198:201], v[190:193], v[70:73]
	v_mfma_f32_16x16x32_f16 v[66:69], v[220:223], v[190:193], v[66:69]
	s_barrier
	v_lshl_add_u64 v[152:153], s[40:41], 0, v[0:1]
	s_mov_b32 m0, s45
	v_lshl_add_u64 v[206:207], s[40:41], 0, v[142:143]
	global_load_lds_dwordx4 v[152:153], off
	s_add_i32 m0, s45, 0x2000
	s_nop 0
	global_load_lds_dwordx4 v[206:207], off
	s_mov_b32 m0, s23
	v_lshl_add_u64 v[212:213], s[48:49], 0, v[138:139]
	ds_read_b128 v[162:165], v157 offset:16384
	ds_read_b128 v[166:169], v157 offset:17408
	ds_read_b128 v[170:173], v157 offset:18432
	ds_read_b128 v[174:177], v157 offset:19456
	ds_read_b128 v[178:181], v157 offset:20480
	ds_read_b128 v[182:185], v157 offset:21504
	ds_read_b128 v[186:189], v157 offset:22528
	ds_read_b128 v[190:193], v157 offset:23552
	global_load_lds_dwordx4 v[212:213], off
	v_lshl_add_u64 v[224:225], s[48:49], 0, v[140:141]
	s_mov_b32 m0, s27
	s_nop 0
	global_load_lds_dwordx4 v[224:225], off
	s_add_u32 s50, s40, 0x80000
	s_addc_u32 s51, s41, 0
	s_add_i32 s45, s60, s72
	v_lshl_add_u64 v[232:233], s[50:51], 0, v[0:1]
	s_mov_b32 m0, s45
	s_nop 0
	global_load_lds_dwordx4 v[232:233], off
	v_lshl_add_u64 v[232:233], s[50:51], 0, v[142:143]
	s_add_i32 m0, s45, 0x2000
	s_nop 0
	global_load_lds_dwordx4 v[232:233], off
	s_waitcnt vmcnt(8) lgkmcnt(0)
	s_barrier
; #define PG8_STAGE(bufoff, gbase, voff) do { _Pragma("unroll") for (int _i = 0; _i < 2; ++_i) \
;         __builtin_amdgcn_global_load_lds((const unsigned*)((const char*)(gbase) + (voff)[_i]), (LAS unsigned*)(lds + (bufoff) + ldsw + _i * 8192), 16, 0, 0); } while (0)
; #define PG8_LDA(dst, b, h) do { _Pragma("unroll") for (int m = 0; m < 4; ++m) _Pragma("unroll") for (int k = 0; k < 2; ++k) dst[m][k] = *(const LAS h16x8*)(lds + PG8_SA(b, h) + aoff + m * 2048 + k * 1024); } while (0)
; #define PG8_LDB(dst, b, h) do { _Pragma("unroll") for (int n = 0; n < 2; ++n) _Pragma("unroll") for (int k = 0; k < 2; ++k) dst[n][k] = *(const LAS h16x8*)(lds + PG8_SB(b, h) + boff + n * 2048 + k * 1024); } while (0)
; #define PG8_MMA(ai, bj, At, Bt_) do { __builtin_amdgcn_s_setprio(1); _Pragma("unroll") for (int m = 0; m < 4; ++m) _Pragma("unroll") for (int n = 0; n < 2; ++n) _Pragma("unroll") for (int k = 0; k < 2; ++k) \
;         acc[ai][bj][m][n] = __builtin_amdgcn_mfma_f32_16x16x32_f16(Bt_[n][k], At[m][k], acc[ai][bj][m][n], 0, 0, 0); __builtin_amdgcn_s_setprio(0); } while (0)
; #define PG8_WAIT_V(n) asm volatile("s_waitcnt vmcnt(" #n ")" ::: "memory")
; #define PG8_WAIT_L(n) asm volatile("s_waitcnt lgkmcnt(" #n ")" ::: "memory")
; #define PG8_BAR __builtin_amdgcn_s_barrier()
; #define PG8_SCHED __builtin_amdgcn_sched_barrier(0)
; template <class Epi, class AMap>
; __device__ __forceinline__ void gemm_phase(LAS unsigned char* lds, const AMap am, const int lda, const h16* Bt, const int ldb, const int M, const int N, const int K, const Epi& E) {
;     ...
;             PG8_WAIT_V(6); PG8_BAR; PG8_MMA(1, 1, At, B1); PG8_BAR;
;             PG8_LDB(B0, 1, 0); PG8_SCHED; PG8_LDA(At, 1, 0); PG8_STAGE(PG8_SA(0, 1), a2 + hstepA, voffA);
;             PG8_WAIT_L(8); PG8_BAR; PG8_WAIT_L(0); PG8_MMA(0, 0, At, B0); PG8_BAR; PG8_SCHED;
;             PG8_LDB(B1, 1, 1); PG8_STAGE(PG8_SB(1, 0), b3, voffB);
;             PG8_BAR; PG8_WAIT_L(0); PG8_MMA(0, 1, At, B1); PG8_BAR;
	v_mfma_f32_16x16x32_f16 v[62:65], v[130:133], v[162:165], v[62:65]
	v_mfma_f32_16x16x32_f16 v[58:61], v[148:151], v[162:165], v[58:61]
	v_mfma_f32_16x16x32_f16 v[46:49], v[130:133], v[170:173], v[46:49]
	v_mfma_f32_16x16x32_f16 v[42:45], v[148:151], v[170:173], v[42:45]
	v_mfma_f32_16x16x32_f16 v[30:33], v[130:133], v[178:181], v[30:33]
	v_mfma_f32_16x16x32_f16 v[26:29], v[148:151], v[178:181], v[26:29]
	v_mfma_f32_16x16x32_f16 v[14:17], v[130:133], v[186:189], v[14:17]
	v_mfma_f32_16x16x32_f16 v[10:13], v[148:151], v[186:189], v[10:13]
	v_mfma_f32_16x16x32_f16 v[62:65], v[134:137], v[166:169], v[62:65]
	v_mfma_f32_16x16x32_f16 v[58:61], v[158:161], v[166:169], v[58:61]
	v_mfma_f32_16x16x32_f16 v[46:49], v[134:137], v[174:177], v[46:49]
	v_mfma_f32_16x16x32_f16 v[42:45], v[158:161], v[174:177], v[42:45]
	v_mfma_f32_16x16x32_f16 v[30:33], v[134:137], v[182:185], v[30:33]
	v_mfma_f32_16x16x32_f16 v[26:29], v[158:161], v[182:185], v[26:29]
	v_mfma_f32_16x16x32_f16 v[14:17], v[134:137], v[190:193], v[14:17]
	v_mfma_f32_16x16x32_f16 v[10:13], v[158:161], v[190:193], v[10:13]
	v_mfma_f32_16x16x32_f16 v[54:57], v[194:197], v[162:165], v[54:57]
	v_mfma_f32_16x16x32_f16 v[50:53], v[202:205], v[162:165], v[50:53]
	v_mfma_f32_16x16x32_f16 v[38:41], v[194:197], v[170:173], v[38:41]
	v_mfma_f32_16x16x32_f16 v[34:37], v[202:205], v[170:173], v[34:37]
	v_mfma_f32_16x16x32_f16 v[22:25], v[194:197], v[178:181], v[22:25]
	v_mfma_f32_16x16x32_f16 v[18:21], v[202:205], v[178:181], v[18:21]
	v_mfma_f32_16x16x32_f16 v[6:9], v[194:197], v[186:189], v[6:9]
	v_mfma_f32_16x16x32_f16 v[2:5], v[202:205], v[186:189], v[2:5]
	v_mfma_f32_16x16x32_f16 v[54:57], v[198:201], v[166:169], v[54:57]
	v_mfma_f32_16x16x32_f16 v[50:53], v[220:223], v[166:169], v[50:53]
	v_mfma_f32_16x16x32_f16 v[38:41], v[198:201], v[174:177], v[38:41]
	v_mfma_f32_16x16x32_f16 v[34:37], v[220:223], v[174:177], v[34:37]
	v_mfma_f32_16x16x32_f16 v[22:25], v[198:201], v[182:185], v[22:25]
	v_mfma_f32_16x16x32_f16 v[18:21], v[220:223], v[182:185], v[18:21]
	v_mfma_f32_16x16x32_f16 v[6:9], v[198:201], v[190:193], v[6:9]
	v_mfma_f32_16x16x32_f16 v[2:5], v[220:223], v[190:193], v[2:5]
	s_barrier
	s_add_i32 s45, 0, 0x18000
	v_add_u32_e32 v234, s45, v155
	ds_read_b128 v[130:133], v234
	ds_read_b128 v[134:137], v234 offset:1024
	ds_read_b128 v[148:151], v234 offset:2048
	ds_read_b128 v[158:161], v234 offset:3072
	s_add_u32 s48, s48, 0x80000
	s_addc_u32 s49, s49, 0
	s_mov_b32 m0, s73
	v_lshl_add_u64 v[232:233], s[48:49], 0, v[138:139]
	ds_read_b128 v[162:165], v157 offset:32768
	ds_read_b128 v[166:169], v157 offset:33792
	ds_read_b128 v[170:173], v157 offset:34816
	ds_read_b128 v[174:177], v157 offset:35840
	ds_read_b128 v[178:181], v157 offset:36864
	ds_read_b128 v[182:185], v157 offset:37888
	ds_read_b128 v[186:189], v157 offset:38912
	ds_read_b128 v[190:193], v157 offset:39936
	global_load_lds_dwordx4 v[232:233], off
	v_lshl_add_u64 v[232:233], s[48:49], 0, v[140:141]
	s_mov_b32 m0, s74
	s_nop 0
	global_load_lds_dwordx4 v[232:233], off
	s_waitcnt lgkmcnt(11)
	s_add_i32 s48, 0, 0x1c000
	s_add_i32 s45, s45, s72
	v_add_u32_e32 v214, s48, v155
	v_lshl_add_u64 v[152:153], v[152:153], 0, s[92:93]
	s_mov_b32 m0, s45
	ds_read_b128 v[194:197], v214
	ds_read_b128 v[198:201], v214 offset:1024
	ds_read_b128 v[202:205], v214 offset:2048
	ds_read_b128 v[220:223], v214 offset:3072
	s_waitcnt vmcnt(8) lgkmcnt(0)
	s_barrier
	v_mfma_f32_16x16x32_f16 v[126:129], v[130:133], v[162:165], v[126:129]
	v_mfma_f32_16x16x32_f16 v[122:125], v[148:151], v[162:165], v[122:125]
	v_mfma_f32_16x16x32_f16 v[110:113], v[130:133], v[170:173], v[110:113]
	v_mfma_f32_16x16x32_f16 v[106:109], v[148:151], v[170:173], v[106:109]
	v_mfma_f32_16x16x32_f16 v[94:97], v[130:133], v[178:181], v[94:97]
	v_mfma_f32_16x16x32_f16 v[90:93], v[148:151], v[178:181], v[90:93]
	v_mfma_f32_16x16x32_f16 v[78:81], v[130:133], v[186:189], v[78:81]
	v_mfma_f32_16x16x32_f16 v[74:77], v[148:151], v[186:189], v[74:77]
	v_mfma_f32_16x16x32_f16 v[126:129], v[134:137], v[166:169], v[126:129]
	v_mfma_f32_16x16x32_f16 v[122:125], v[158:161], v[166:169], v[122:125]
	v_mfma_f32_16x16x32_f16 v[110:113], v[134:137], v[174:177], v[110:113]
	v_mfma_f32_16x16x32_f16 v[106:109], v[158:161], v[174:177], v[106:109]
	v_mfma_f32_16x16x32_f16 v[94:97], v[134:137], v[182:185], v[94:97]
	v_mfma_f32_16x16x32_f16 v[90:93], v[158:161], v[182:185], v[90:93]
	v_mfma_f32_16x16x32_f16 v[78:81], v[134:137], v[190:193], v[78:81]
	v_mfma_f32_16x16x32_f16 v[74:77], v[158:161], v[190:193], v[74:77]
	v_mfma_f32_16x16x32_f16 v[118:121], v[194:197], v[162:165], v[118:121]
	v_mfma_f32_16x16x32_f16 v[114:117], v[202:205], v[162:165], v[114:117]
	v_mfma_f32_16x16x32_f16 v[102:105], v[194:197], v[170:173], v[102:105]
	v_mfma_f32_16x16x32_f16 v[98:101], v[202:205], v[170:173], v[98:101]
	v_mfma_f32_16x16x32_f16 v[86:89], v[194:197], v[178:181], v[86:89]
	v_mfma_f32_16x16x32_f16 v[82:85], v[202:205], v[178:181], v[82:85]
	v_mfma_f32_16x16x32_f16 v[70:73], v[194:197], v[186:189], v[70:73]
	v_mfma_f32_16x16x32_f16 v[66:69], v[202:205], v[186:189], v[66:69]
	v_mfma_f32_16x16x32_f16 v[118:121], v[198:201], v[166:169], v[118:121]
	v_mfma_f32_16x16x32_f16 v[114:117], v[220:223], v[166:169], v[114:117]
	v_mfma_f32_16x16x32_f16 v[102:105], v[198:201], v[174:177], v[102:105]
	v_mfma_f32_16x16x32_f16 v[98:101], v[220:223], v[174:177], v[98:101]
	v_mfma_f32_16x16x32_f16 v[86:89], v[198:201], v[182:185], v[86:89]
	v_mfma_f32_16x16x32_f16 v[82:85], v[220:223], v[182:185], v[82:85]
	v_mfma_f32_16x16x32_f16 v[70:73], v[198:201], v[190:193], v[70:73]
	v_mfma_f32_16x16x32_f16 v[66:69], v[220:223], v[190:193], v[66:69]
	s_barrier
; #define PG8_STAGE(bufoff, gbase, voff) do { _Pragma("unroll") for (int _i = 0; _i < 2; ++_i) \
;         __builtin_amdgcn_global_load_lds((const unsigned*)((const char*)(gbase) + (voff)[_i]), (LAS unsigned*)(lds + (bufoff) + ldsw + _i * 8192), 16, 0, 0); } while (0)
; #define PG8_LDA(dst, b, h) do { _Pragma("unroll") for (int m = 0; m < 4; ++m) _Pragma("unroll") for (int k = 0; k < 2; ++k) dst[m][k] = *(const LAS h16x8*)(lds + PG8_SA(b, h) + aoff + m * 2048 + k * 1024); } while (0)
; #define PG8_MMA(ai, bj, At, Bt_) do { __builtin_amdgcn_s_setprio(1); _Pragma("unroll") for (int m = 0; m < 4; ++m) _Pragma("unroll") for (int n = 0; n < 2; ++n) _Pragma("unroll") for (int k = 0; k < 2; ++k) \
;         acc[ai][bj][m][n] = __builtin_amdgcn_mfma_f32_16x16x32_f16(Bt_[n][k], At[m][k], acc[ai][bj][m][n], 0, 0, 0); __builtin_amdgcn_s_setprio(0); } while (0)
; #define PG8_WAIT_V(n) asm volatile("s_waitcnt vmcnt(" #n ")" ::: "memory")
; #define PG8_WAIT_L(n) asm volatile("s_waitcnt lgkmcnt(" #n ")" ::: "memory")
; #define PG8_BAR __builtin_amdgcn_s_barrier()
; #define PG8_SCHED __builtin_amdgcn_sched_barrier(0)
; template <class Epi, class AMap>
; __device__ __forceinline__ void gemm_phase(LAS unsigned char* lds, const AMap am, const int lda, const h16* Bt, const int ldb, const int M, const int N, const int K, const Epi& E) {
;     ...
;             PG8_LDA(At, 1, 1); PG8_STAGE(PG8_SA(1, 0), a3, voffA);
;             PG8_BAR; PG8_WAIT_L(0); PG8_MMA(1, 0, At, B0); PG8_BAR; PG8_SCHED;
;             PG8_STAGE(PG8_SB(1, 1), b3 + hstepB, voffB);
;             PG8_WAIT_V(6); PG8_BAR; PG8_MMA(1, 1, At, B1); PG8_BAR;
;         }
	global_load_lds_dwordx4 v[152:153], off
	v_lshl_add_u64 v[152:153], v[206:207], 0, s[92:93]
	s_add_i32 m0, s45, 0x2000
	s_nop 0
	global_load_lds_dwordx4 v[152:153], off
	s_mov_b32 m0, s75
	v_lshl_add_u64 v[152:153], v[212:213], 0, s[92:93]
	ds_read_b128 v[162:165], v157 offset:49152
	ds_read_b128 v[166:169], v157 offset:50176
	ds_read_b128 v[170:173], v157 offset:51200
	ds_read_b128 v[174:177], v157 offset:52224
	ds_read_b128 v[178:181], v157 offset:53248
	ds_read_b128 v[182:185], v157 offset:54272
	ds_read_b128 v[186:189], v157 offset:55296
	ds_read_b128 v[190:193], v157 offset:56320
	global_load_lds_dwordx4 v[152:153], off
	v_lshl_add_u64 v[152:153], v[224:225], 0, s[92:93]
	s_mov_b32 m0, s76
	s_nop 0
	global_load_lds_dwordx4 v[152:153], off
	s_add_u32 s40, s40, 0x80080
	s_addc_u32 s41, s41, 0
	s_add_i32 s45, s48, s72
	v_lshl_add_u64 v[232:233], s[40:41], 0, v[0:1]
	s_mov_b32 m0, s45
	s_nop 0
	global_load_lds_dwordx4 v[232:233], off
	v_lshl_add_u64 v[232:233], s[40:41], 0, v[142:143]
	s_add_i32 m0, s45, 0x2000
	s_nop 0
	global_load_lds_dwordx4 v[232:233], off
	s_waitcnt vmcnt(8) lgkmcnt(0)
	s_barrier
	v_mfma_f32_16x16x32_f16 v[62:65], v[130:133], v[162:165], v[62:65]
	v_mfma_f32_16x16x32_f16 v[58:61], v[148:151], v[162:165], v[58:61]
	v_mfma_f32_16x16x32_f16 v[46:49], v[130:133], v[170:173], v[46:49]
	v_mfma_f32_16x16x32_f16 v[42:45], v[148:151], v[170:173], v[42:45]
	v_mfma_f32_16x16x32_f16 v[30:33], v[130:133], v[178:181], v[30:33]
	v_mfma_f32_16x16x32_f16 v[26:29], v[148:151], v[178:181], v[26:29]
	v_mfma_f32_16x16x32_f16 v[14:17], v[130:133], v[186:189], v[14:17]
	v_mfma_f32_16x16x32_f16 v[10:13], v[148:151], v[186:189], v[10:13]
	v_mfma_f32_16x16x32_f16 v[62:65], v[134:137], v[166:169], v[62:65]
	v_mfma_f32_16x16x32_f16 v[58:61], v[158:161], v[166:169], v[58:61]
	v_mfma_f32_16x16x32_f16 v[46:49], v[134:137], v[174:177], v[46:49]
	v_mfma_f32_16x16x32_f16 v[42:45], v[158:161], v[174:177], v[42:45]
	v_mfma_f32_16x16x32_f16 v[30:33], v[134:137], v[182:185], v[30:33]
	v_mfma_f32_16x16x32_f16 v[26:29], v[158:161], v[182:185], v[26:29]
	v_mfma_f32_16x16x32_f16 v[14:17], v[134:137], v[190:193], v[14:17]
	v_mfma_f32_16x16x32_f16 v[10:13], v[158:161], v[190:193], v[10:13]
	v_mfma_f32_16x16x32_f16 v[54:57], v[194:197], v[162:165], v[54:57]
	v_mfma_f32_16x16x32_f16 v[50:53], v[202:205], v[162:165], v[50:53]
	v_mfma_f32_16x16x32_f16 v[38:41], v[194:197], v[170:173], v[38:41]
	v_mfma_f32_16x16x32_f16 v[34:37], v[202:205], v[170:173], v[34:37]
	v_mfma_f32_16x16x32_f16 v[22:25], v[194:197], v[178:181], v[22:25]
	v_mfma_f32_16x16x32_f16 v[18:21], v[202:205], v[178:181], v[18:21]
	v_mfma_f32_16x16x32_f16 v[6:9], v[194:197], v[186:189], v[6:9]
	v_mfma_f32_16x16x32_f16 v[2:5], v[202:205], v[186:189], v[2:5]
	v_mfma_f32_16x16x32_f16 v[54:57], v[198:201], v[166:169], v[54:57]
	v_mfma_f32_16x16x32_f16 v[50:53], v[220:223], v[166:169], v[50:53]
	v_mfma_f32_16x16x32_f16 v[38:41], v[198:201], v[174:177], v[38:41]
	v_mfma_f32_16x16x32_f16 v[34:37], v[220:223], v[174:177], v[34:37]
	v_mfma_f32_16x16x32_f16 v[22:25], v[198:201], v[182:185], v[22:25]
	v_mfma_f32_16x16x32_f16 v[18:21], v[220:223], v[182:185], v[18:21]
	v_mfma_f32_16x16x32_f16 v[6:9], v[198:201], v[190:193], v[6:9]
	v_mfma_f32_16x16x32_f16 v[2:5], v[220:223], v[190:193], v[2:5]
	s_add_i32 s43, s43, 2
	s_add_u32 s0, s0, 0x100
	s_addc_u32 s1, s1, 0
	s_add_u32 s21, s21, 0x100
	s_addc_u32 s35, s35, 0
	s_cmp_gt_u32 s43, 29
	s_barrier
	s_cbranch_scc0 .LBB0_799
	s_cmpk_gt_u32 s71, 0xff
	s_cbranch_scc1 .Lgx8
	s_barrier
; __device__ __forceinline__ float sigmoidf_(float x) { return 1.0f / (1.0f + __expf(-x)); }
;     __device__ __forceinline__ void operator()(const f32x4 (&acc)[2][2][4][2], const Unit& u, int wr, int wc, int fr, int fq) const {
;     ...
;         const int mode = u.pn == 24 ? 1 : (u.pn == 26 ? 2 : 0);
;         const bool vtile = VFw != nullptr && u.pn >= 16 && u.pn < 24;
; #pragma unroll
;         for (int ai = 0; ai < 2; ++ai)
; #pragma unroll
;             for (int m = 0; m < 4; ++m) { h16* rowp = O + (size_t)(row0 + ai * 128 + m * 16) * LDC1 + colt;
; #pragma unroll
;                 for (int bj = 0; bj < 2; ++bj) { f32x4 v0 = acc[ai][bj][m][0], v1 = acc[ai][bj][m][1];
;                     if (mode == 1) {
; #pragma unroll
;                         for (int j = 0; j < 4; ++j) { v0[j] = 1.0f - 2.0f / (1.0f + __expf(2.0f * v0[j])); v1[j] = 1.0f - 2.0f / (1.0f + __expf(2.0f * v1[j])); } }
;                     else if (mode == 2) {
; #pragma unroll
;                         for (int j = 0; j < 4; ++j) { v0[j] = sigmoidf_(v0[j]); v1[j] = sigmoidf_(v1[j]); } }
;                     const u32x4 pk = pack8(v0, v1);
;                     *(u32x4*)(rowp + bj * 128) = pk;
;                     if (vtile) *(u32x4*)(VFw + (size_t)(row0 + ai * 128 + m * 16) * DM + (colt - 4096) + bj * 128) = pk; } }
.Lgx8:
	s_cmp_eq_u32 s22, 26
	s_cselect_b32 s0, 2, 0
	s_cmp_lg_u32 s22, 24
	s_cselect_b32 s43, s0, 1
	s_cmp_gt_i32 s43, 1
	s_mov_b64 s[0:1], -1
	s_cbranch_scc0 .LBB0_802
	v_mul_f32_e32 v132, 0xbfb8aa3b, v123
	v_mul_f32_e32 v133, 0xbfb8aa3b, v124
	v_exp_f32_e32 v135, v132
	v_mul_f32_e32 v132, 0xbfb8aa3b, v128
	v_exp_f32_e32 v136, v133
	v_mul_f32_e32 v133, 0xbfb8aa3b, v129
	v_exp_f32_e32 v132, v132
	v_exp_f32_e32 v133, v133
	v_mul_f32_e32 v131, 0xbfb8aa3b, v122
	v_mul_f32_e32 v130, 0xbfb8aa3b, v126
	v_exp_f32_e32 v134, v131
	v_pk_add_f32 v[132:133], v[132:133], 1.0 op_sel_hi:[1,0]
	v_mul_f32_e32 v131, 0xbfb8aa3b, v127
	v_div_scale_f32 v137, s[0:1], v133, v133, 1.0
	v_rcp_f32_e32 v148, v137
	v_exp_f32_e32 v130, v130
	v_exp_f32_e32 v131, v131
	v_pk_add_f32 v[134:135], v[134:135], 1.0 op_sel_hi:[1,0]
	v_fma_f32 v149, -v137, v148, 1.0
	v_fmac_f32_e32 v148, v149, v148
	v_div_scale_f32 v149, vcc, 1.0, v133, 1.0
	v_mul_f32_e32 v150, v149, v148
	v_fma_f32 v151, -v137, v150, v149
	v_fmac_f32_e32 v150, v151, v148
	v_fma_f32 v137, -v137, v150, v149
	v_div_fmas_f32 v137, v137, v148, v150
	v_div_fixup_f32 v133, v137, v133, 1.0
	v_div_scale_f32 v137, s[0:1], v132, v132, 1.0
	v_rcp_f32_e32 v148, v137
	v_pk_add_f32 v[130:131], v[130:131], 1.0 op_sel_hi:[1,0]
	v_fma_f32 v149, -v137, v148, 1.0
	v_fmac_f32_e32 v148, v149, v148
	v_div_scale_f32 v149, vcc, 1.0, v132, 1.0
	v_mul_f32_e32 v150, v149, v148
	v_fma_f32 v151, -v137, v150, v149
	v_fmac_f32_e32 v150, v151, v148
	v_fma_f32 v137, -v137, v150, v149
	v_div_fmas_f32 v137, v137, v148, v150
	v_div_fixup_f32 v132, v137, v132, 1.0
	v_div_scale_f32 v137, s[0:1], v131, v131, 1.0
	v_rcp_f32_e32 v148, v137
	s_nop 0
	v_fma_f32 v149, -v137, v148, 1.0
	v_fmac_f32_e32 v148, v149, v148
	v_div_scale_f32 v149, vcc, 1.0, v131, 1.0
	v_mul_f32_e32 v150, v149, v148
	v_fma_f32 v151, -v137, v150, v149
	v_fmac_f32_e32 v150, v151, v148
	v_fma_f32 v137, -v137, v150, v149
	v_div_fmas_f32 v137, v137, v148, v150
	v_div_fixup_f32 v131, v137, v131, 1.0
	v_div_scale_f32 v137, s[0:1], v130, v130, 1.0
	v_rcp_f32_e32 v148, v137
	s_nop 0
	v_fma_f32 v149, -v137, v148, 1.0
	v_fmac_f32_e32 v148, v149, v148
	v_div_scale_f32 v149, vcc, 1.0, v130, 1.0
	v_mul_f32_e32 v150, v149, v148
	v_fma_f32 v151, -v137, v150, v149
	v_fmac_f32_e32 v150, v151, v148
	v_fma_f32 v137, -v137, v150, v149
	v_div_fmas_f32 v137, v137, v148, v150
	v_div_fixup_f32 v130, v137, v130, 1.0
	v_mul_f32_e32 v137, 0xbfb8aa3b, v125
	v_exp_f32_e32 v137, v137
	s_nop 0
	v_pk_add_f32 v[136:137], v[136:137], 1.0 op_sel_hi:[1,0]
	s_nop 0
	v_div_scale_f32 v148, s[0:1], v137, v137, 1.0
	v_rcp_f32_e32 v149, v148
	s_nop 0
	v_fma_f32 v150, -v148, v149, 1.0
	v_fmac_f32_e32 v149, v150, v149
	v_div_scale_f32 v150, vcc, 1.0, v137, 1.0
	v_mul_f32_e32 v151, v150, v149
	v_fma_f32 v152, -v148, v151, v150
	v_fmac_f32_e32 v151, v152, v149
	v_fma_f32 v148, -v148, v151, v150
	v_div_fmas_f32 v148, v148, v149, v151
	v_div_fixup_f32 v137, v148, v137, 1.0
	v_div_scale_f32 v148, s[0:1], v136, v136, 1.0
	v_rcp_f32_e32 v149, v148
	s_nop 0
	v_fma_f32 v150, -v148, v149, 1.0
	v_fmac_f32_e32 v149, v150, v149
	v_div_scale_f32 v150, vcc, 1.0, v136, 1.0
	v_mul_f32_e32 v151, v150, v149
	v_fma_f32 v152, -v148, v151, v150
	v_fmac_f32_e32 v151, v152, v149
	v_fma_f32 v148, -v148, v151, v150
	v_div_fmas_f32 v148, v148, v149, v151
	v_div_fixup_f32 v136, v148, v136, 1.0
	v_div_scale_f32 v148, s[0:1], v135, v135, 1.0
	v_rcp_f32_e32 v149, v148
	s_nop 0
	v_fma_f32 v150, -v148, v149, 1.0
	v_fmac_f32_e32 v149, v150, v149
	v_div_scale_f32 v150, vcc, 1.0, v135, 1.0
	v_mul_f32_e32 v151, v150, v149
	v_fma_f32 v152, -v148, v151, v150
	v_fmac_f32_e32 v151, v152, v149
	v_fma_f32 v148, -v148, v151, v150
	v_div_fmas_f32 v148, v148, v149, v151
	v_div_fixup_f32 v135, v148, v135, 1.0
	v_div_scale_f32 v148, s[0:1], v134, v134, 1.0
	v_rcp_f32_e32 v149, v148
	s_mov_b64 s[0:1], 0
	v_fma_f32 v150, -v148, v149, 1.0
	v_fmac_f32_e32 v149, v150, v149
	v_div_scale_f32 v150, vcc, 1.0, v134, 1.0
	v_mul_f32_e32 v151, v150, v149
	v_fma_f32 v152, -v148, v151, v150
	v_fmac_f32_e32 v151, v152, v149
	v_fma_f32 v148, -v148, v151, v150
	v_div_fmas_f32 v148, v148, v149, v151
	v_div_fixup_f32 v134, v148, v134, 1.0
